# speedup vs baseline: 1.0119x; 1.0119x over previous
;     DI size_t aoff(const Unit& u, size_t tstep) const { return (size_t)u.pm * tstep; }
;     DI size_t boff(const Unit& u, size_t tstep) const { return (size_t)u.pn * tstep; }
;     DI bool next(int i, Unit& u) const { const long L = (long)i * G + c; if (L >= np) return false; u.pm = pmv; u.pn = (int)(L % nN); u.ks = (int)(L / nN); return true; }
;     DI size_t aoff(const Unit& u, size_t) const { return (size_t)u.ks * kbytes; }
;     DI size_t boff(const Unit& u, size_t tstep) const { return (size_t)u.pn * tstep + (size_t)u.ks * kbytes; }
;     DI bool next(int i, Unit& u) const { Unit t; if (!S.next(i / 3, t)) return false; u.pm = t.pm; u.pn = t.pn; u.ks = i % 3; return true; }
;     DI size_t aoff(const Unit& u, size_t tstep) const { return (u.ks < 2 ? offU : offOA) + (size_t)u.pm * tstep; }
; template <class Epi, class Sched>
; DI void gemm_phase(LAS unsigned char* lds, const Gemm g, const Sched& S, const Epi& E) {
;     ...
;     for (int i = 0; i < 2; ++i) { int Rr, C; stage_rc(tid * 16 + i * 8192, Rr, C); const int Rb = Epi::PERM ? ((Rr & ~31) + perm32(Rr & 31)) : Rr;
;         voffA[i] = (unsigned)(Rr * K + C) * 2u; voffB[i] = (unsigned)(Rb * K + C) * 2u; }
;     const size_t kstep = (size_t)(BK * 2);
;     const size_t hstep = (size_t)HALF * K * 2;
;     const size_t tstep = 2 * hstep;
;     const unsigned ldsw = (unsigned)wid * 1024u;
;     const int aoff = lds_byte(wr * 64 + fr, fq * 8), boff = lds_byte(wc * 32 + fr, fq * 8);
;     ...
;     Unit cur, nxt; int ui = 0;
;     if (!S.next(0, cur)) return;
;     f32x4 acc[2][2][4][2];
; #pragma unroll
;     for (int a = 0; a < 2; ++a)
; #pragma unroll
;         for (int b = 0; b < 2; ++b)
; #pragma unroll
;             for (int m = 0; m < 4; ++m)
; #pragma unroll
;                 for (int n = 0; n < 2; ++n) acc[a][b][m][n] = (f32x4){0.f, 0.f, 0.f, 0.f};
;     bf16x8 At[4][2], B0[2][2], B1[2][2];
;     const char* cA = (const char*)g.A + S.aoff(cur, tstep); const char* cB = (const char*)g.Bt + S.boff(cur, tstep);
;     PG8_STAGE(PG8_SB(0, 0), cB, voffB); PG8_STAGE(PG8_SA(0, 0), cA, voffA); PG8_STAGE(PG8_SB(0, 1), cB + hstep, voffB); PG8_STAGE(PG8_SA(0, 1), cA + hstep, voffA);
;     if (wr == 1) PG8_BAR;
;     PG8_WAIT_V(4); PG8_BAR;
;     PG8_STAGE(PG8_SB(1, 0), cB + kstep, voffB); PG8_STAGE(PG8_SA(1, 0), cA + kstep, voffA); PG8_STAGE(PG8_SB(1, 1), cB + hstep + kstep, voffB);
;     PG8_WAIT_V(6); PG8_BAR;
.LBB0_211:
	s_add_u32 s10, s22, 0x107c3000
	s_addc_u32 s11, s23, 0
	s_lshl_b32 s0, s0, 5
	s_mov_b64 s[12:13], 0x80
	s_and_b32 s58, s0, 0x60
	s_add_i32 m0, s39, 0x18000
	v_lshl_add_u64 v[6:7], v[6:7], 0, s[12:13]
	s_ashr_i32 s56, s26, 31
	s_lshl_b32 s57, s1, 6
	s_lshl_b32 s4, s1, 13
	s_lshl_b32 s5, s58, 7
	s_waitcnt vmcnt(4)
	s_barrier
	global_load_lds_dwordx4 v[6:7], off
	v_lshl_add_u64 v[4:5], v[4:5], 0, s[12:13]
	s_add_i32 m0, s39, 0x1a000
	s_add_i32 s59, s39, 0x8000
	s_add_i32 s60, s39, 0xa000
	global_load_lds_dwordx4 v[4:5], off
	v_lshl_add_u64 v[2:3], v[2:3], 0, s[12:13]
	s_mov_b32 m0, s59
	s_add_u32 s0, s42, 0x80080
	global_load_lds_dwordx4 v[2:3], off
	v_lshl_add_u64 v[0:1], v[0:1], 0, s[12:13]
	s_mov_b32 m0, s60
	s_addc_u32 s1, s43, 0
	global_load_lds_dwordx4 v[0:1], off
	s_add_i32 m0, s39, 0x1c000
	s_nop 0
	global_load_lds_dwordx4 v130, s[0:1]
	s_add_i32 m0, s39, 0x1e000
	v_bfe_u32 v145, v184, 4, 2
	global_load_lds_dwordx4 v134, s[0:1]
	v_lshlrev_b32_e32 v0, 4, v145
	v_lshlrev_b32_e32 v1, 6, v184
	s_movk_i32 s0, 0x3c0
	v_and_b32_e32 v144, 15, v184
	v_and_or_b32 v1, v1, s0, v0
	v_and_b32_e32 v2, 32, v185
	v_lshl_or_b32 v0, v144, 6, v0
	v_bitop3_b32 v146, s5, v1, v2 bitop3:0xf6
	v_lshlrev_b32_e32 v1, 9, v184
	v_bitop3_b32 v0, v0, s4, v2 bitop3:0xde
	v_and_b32_e32 v1, 0x70000, v1
	v_lshlrev_b32_e32 v2, 12, v10
	v_or3_b32 v1, v8, v1, v2
	v_add_u32_e32 v136, v1, v9
	v_lshlrev_b32_e32 v1, 5, v11
	s_waitcnt vmcnt(6)
	v_and_b32_e32 v1, 0xf0000, v1
	v_or3_b32 v1, v8, v1, v2
	s_add_i32 s34, 0, 0x10000
	s_add_i32 s35, 0, 0x14000
	s_sext_i32_i16 s64, s6
	s_mov_b32 s61, s26
	s_mov_b32 s62, 0
	v_mov_b32_e32 v137, v131
	v_add_u32_e32 v138, v1, v9
	v_mov_b32_e32 v139, v131
	v_mov_b64_e32 v[140:141], 0x162c
	v_mov_b64_e32 v[142:143], 0x162b
	v_add_u32_e32 v147, s34, v146
	v_add_u32_e32 v148, 0, v0
	v_add_u32_e32 v149, s35, v146
	s_movk_i32 s63, 0x2c00
	s_barrier

;     DI size_t aoff(const Unit& u, size_t tstep) const { return (size_t)u.pm * tstep; }
;     DI size_t boff(const Unit& u, size_t tstep) const { return (size_t)u.pn * tstep; }
;     DI size_t aoff(const Unit& u, size_t) const { return (size_t)u.ks * kbytes; }
; template <class Epi, class Sched>
; DI void gemm_phase(LAS unsigned char* lds, const Gemm g, const Sched& S, const Epi& E) {
;     ...
;         const bool has_next = S.next(ui + 1, nxt);
;         const char* nA = has_next ? (const char*)g.A + S.aoff(nxt, tstep) : cA; const char* nB = has_next ? (const char*)g.Bt + S.boff(nxt, tstep) : cB;
;         for (int t = 0; t < nt; t += 2) {
;             if constexpr (Epi::HAS_MID) { if (t == E.mid_t(nt)) { int fr3 = fr, fq3 = fq; asm volatile("" : "+v"(fr3), "+v"(fq3)); E.mid(acc, cur, wr, wc, fr3, fq3); } }
;             const bool last = (t == nt - 2);
;             const char* a1 = cA + (size_t)(t + 1) * kstep;
;             const char* a2 = last ? nA : cA + (size_t)(t + 2) * kstep; const char* b2 = last ? nB : cB + (size_t)(t + 2) * kstep;
;             const char* a3 = a2 + kstep; const char* b3 = b2 + kstep;
;             PG8_LDB(B0, 0, 0); PG8_SCHED; PG8_LDA(At, 0, 0); PG8_STAGE(PG8_SA(1, 1), a1 + hstep, voffA);
;             PG8_WAIT_L(8); PG8_BAR; PG8_WAIT_L(0); PG8_MMA(0, 0, At, B0); PG8_BAR; PG8_SCHED;
;             PG8_LDB(B1, 0, 1); PG8_STAGE(PG8_SB(0, 0), b2, voffB);
;             PG8_BAR; PG8_WAIT_L(0); PG8_MMA(0, 1, At, B1); PG8_BAR;
;             PG8_LDA(At, 0, 1); PG8_STAGE(PG8_SA(0, 0), a2, voffA);
;             PG8_BAR; PG8_WAIT_L(0); PG8_MMA(1, 0, At, B0); PG8_BAR; PG8_SCHED;
;             PG8_STAGE(PG8_SB(0, 1), b2 + hstep, voffB);
;             PG8_WAIT_V(6); PG8_BAR; PG8_MMA(1, 1, At, B1); PG8_BAR;
;             PG8_LDB(B0, 1, 0); PG8_SCHED; PG8_LDA(At, 1, 0); PG8_STAGE(PG8_SA(0, 1), a2 + hstep, voffA);
;             PG8_WAIT_L(8); PG8_BAR; PG8_WAIT_L(0); PG8_MMA(0, 0, At, B0); PG8_BAR; PG8_SCHED;
;             PG8_LDB(B1, 1, 1); PG8_STAGE(PG8_SB(1, 0), b3, voffB);
;             PG8_BAR; PG8_WAIT_L(0); PG8_MMA(0, 1, At, B1); PG8_BAR;
;             PG8_LDA(At, 1, 1); PG8_STAGE(PG8_SA(1, 0), a3, voffA);
;             PG8_BAR; PG8_WAIT_L(0); PG8_MMA(1, 0, At, B0); PG8_BAR; PG8_SCHED;
;             PG8_STAGE(PG8_SB(1, 1), b3 + hstep, voffB);
;             PG8_WAIT_V(6); PG8_BAR; PG8_MMA(1, 1, At, B1); PG8_BAR;
.LBB0_218:
	s_ashr_i32 s17, s16, 31
	s_lshl_b64 s[0:1], s[16:17], 20
	v_cmp_lt_i64_e32 vcc, s[18:19], v[140:141]
	s_add_u32 s18, s47, s0
	s_addc_u32 s19, s48, s1
	s_and_b64 s[0:1], vcc, exec
	s_cselect_b32 s17, s19, s41
	s_cselect_b32 s65, s18, s40
	s_ashr_i32 s15, s14, 31
	s_lshl_b64 s[0:1], s[14:15], 20
	s_add_u32 s36, s49, s0
	s_addc_u32 s37, s50, s1
	s_and_b64 s[0:1], vcc, exec
	s_cselect_b32 s15, s37, s43
	s_cselect_b32 s66, s36, s42
	s_add_u32 s40, s40, 0x80080
	s_addc_u32 s41, s41, 0
	s_add_u32 s67, s42, 0x100
	v_mov_b32_e32 v0, 0
	s_addc_u32 s68, s43, 0
	s_mov_b32 s69, -2
	ds_read_b128 v[150:153], v147
	ds_read_b128 v[154:157], v147 offset:1024
	ds_read_b128 v[162:165], v147 offset:2048
	ds_read_b128 v[166:169], v147 offset:3072
	s_add_u32 s0, s40, 0xfff80080
	s_addc_u32 s1, s41, -1
	s_cmp_eq_u32 s69, 28
	s_cselect_b32 s45, s17, s1
	s_cselect_b32 s44, s65, s0
	s_cselect_b32 s43, s15, s68
	s_cselect_b32 s42, s66, s67
	s_add_i32 m0, s39, 0xc000
	ds_read_b128 v[170:173], v148
	ds_read_b128 v[174:177], v148 offset:1024
	ds_read_b128 v[178:181], v148 offset:2048
	ds_read_b128 v[188:191], v148 offset:3072
	ds_read_b128 v[194:197], v148 offset:4096
	ds_read_b128 v[198:201], v148 offset:5120
	ds_read_b128 v[202:205], v148 offset:6144
	ds_read_b128 v[206:209], v148 offset:7168
	global_load_lds_dwordx4 v136, s[40:41]
	s_add_i32 m0, s39, 0xe000
	s_nop 0
	global_load_lds_dwordx4 v138, s[40:41]
	s_waitcnt lgkmcnt(8)
	s_barrier
	s_waitcnt lgkmcnt(0)
	s_setprio 1
	s_waitcnt lgkmcnt(0)
	v_mfma_f32_16x16x32_bf16 v[124:127], v[150:153], v[170:173], 0
	v_mfma_f32_16x16x32_bf16 v[120:123], v[162:165], v[170:173], 0
	v_mfma_f32_16x16x32_bf16 v[108:111], v[150:153], v[178:181], 0
	v_mfma_f32_16x16x32_bf16 v[104:107], v[162:165], v[178:181], 0
	v_mfma_f32_16x16x32_bf16 v[92:95], v[150:153], v[194:197], 0
	v_mfma_f32_16x16x32_bf16 v[88:91], v[162:165], v[194:197], 0
	v_mfma_f32_16x16x32_bf16 v[76:79], v[150:153], v[202:205], 0
	v_mfma_f32_16x16x32_bf16 v[72:75], v[162:165], v[202:205], 0
	v_mfma_f32_16x16x32_bf16 v[124:127], v[154:157], v[174:177], v[124:127]
	v_mfma_f32_16x16x32_bf16 v[120:123], v[166:169], v[174:177], v[120:123]
	v_mfma_f32_16x16x32_bf16 v[108:111], v[154:157], v[188:191], v[108:111]
	v_mfma_f32_16x16x32_bf16 v[104:107], v[166:169], v[188:191], v[104:107]
	v_mfma_f32_16x16x32_bf16 v[92:95], v[154:157], v[198:201], v[92:95]
	v_mfma_f32_16x16x32_bf16 v[88:91], v[166:169], v[198:201], v[88:91]
	v_mfma_f32_16x16x32_bf16 v[76:79], v[154:157], v[206:209], v[76:79]
	v_mfma_f32_16x16x32_bf16 v[72:75], v[166:169], v[206:209], v[72:75]
	s_setprio 0
	s_barrier
	s_add_i32 s0, s34, s52
	s_mov_b32 m0, s0
	ds_read_b128 v[210:213], v149
	ds_read_b128 v[214:217], v149 offset:1024
	ds_read_b128 v[218:221], v149 offset:2048
	ds_read_b128 v[222:225], v149 offset:3072
	global_load_lds_dwordx4 v130, s[42:43]
	v_lshl_add_u64 v[182:183], s[42:43], 0, v[134:135]
	s_add_i32 m0, s0, 0x2000
	s_nop 0
	global_load_lds_dwordx4 v134, s[42:43]
	s_barrier
	s_waitcnt lgkmcnt(0)
	s_setprio 1
	s_waitcnt lgkmcnt(0)
	v_mfma_f32_16x16x32_bf16 v[116:119], v[210:213], v[170:173], 0
	v_mfma_f32_16x16x32_bf16 v[112:115], v[218:221], v[170:173], 0
	v_mfma_f32_16x16x32_bf16 v[100:103], v[210:213], v[178:181], 0
	v_mfma_f32_16x16x32_bf16 v[96:99], v[218:221], v[178:181], 0
	v_mfma_f32_16x16x32_bf16 v[84:87], v[210:213], v[194:197], 0
	v_mfma_f32_16x16x32_bf16 v[80:83], v[218:221], v[194:197], 0
	v_mfma_f32_16x16x32_bf16 v[68:71], v[210:213], v[202:205], 0
	v_mfma_f32_16x16x32_bf16 v[64:67], v[218:221], v[202:205], 0
	v_mfma_f32_16x16x32_bf16 v[116:119], v[214:217], v[174:177], v[116:119]
	v_mfma_f32_16x16x32_bf16 v[112:115], v[222:225], v[174:177], v[112:115]
	v_mfma_f32_16x16x32_bf16 v[100:103], v[214:217], v[188:191], v[100:103]
	v_mfma_f32_16x16x32_bf16 v[96:99], v[222:225], v[188:191], v[96:99]
	v_mfma_f32_16x16x32_bf16 v[84:87], v[214:217], v[198:201], v[84:87]
	v_mfma_f32_16x16x32_bf16 v[80:83], v[222:225], v[198:201], v[80:83]
	v_mfma_f32_16x16x32_bf16 v[68:71], v[214:217], v[206:209], v[68:71]
	v_mfma_f32_16x16x32_bf16 v[64:67], v[222:225], v[206:209], v[64:67]
	s_setprio 0
	s_mov_b32 m0, s39
	v_lshl_add_u64 v[226:227], s[44:45], 0, v[128:129]
	s_barrier
	ds_read_b128 v[170:173], v148 offset:16384
	ds_read_b128 v[174:177], v148 offset:17408
	ds_read_b128 v[178:181], v148 offset:18432
	ds_read_b128 v[188:191], v148 offset:19456
	ds_read_b128 v[194:197], v148 offset:20480
	ds_read_b128 v[198:201], v148 offset:21504
	ds_read_b128 v[202:205], v148 offset:22528
	ds_read_b128 v[206:209], v148 offset:23552
	global_load_lds_dwordx4 v128, s[44:45]
	v_lshl_add_u64 v[228:229], s[44:45], 0, v[132:133]
	s_mov_b32 m0, s53
	s_nop 0
	global_load_lds_dwordx4 v132, s[44:45]
	s_barrier
	s_waitcnt lgkmcnt(0)
	s_setprio 1
	s_waitcnt lgkmcnt(0)
	v_mfma_f32_16x16x32_bf16 v[60:63], v[150:153], v[170:173], 0
	v_mfma_f32_16x16x32_bf16 v[56:59], v[162:165], v[170:173], 0
	v_mfma_f32_16x16x32_bf16 v[44:47], v[150:153], v[178:181], 0
	v_mfma_f32_16x16x32_bf16 v[40:43], v[162:165], v[178:181], 0
	v_mfma_f32_16x16x32_bf16 v[28:31], v[150:153], v[194:197], 0
	v_mfma_f32_16x16x32_bf16 v[24:27], v[162:165], v[194:197], 0
	v_mfma_f32_16x16x32_bf16 v[12:15], v[150:153], v[202:205], 0
	v_mfma_f32_16x16x32_bf16 v[8:11], v[162:165], v[202:205], 0
	v_mfma_f32_16x16x32_bf16 v[60:63], v[154:157], v[174:177], v[60:63]
	v_mfma_f32_16x16x32_bf16 v[56:59], v[166:169], v[174:177], v[56:59]
	v_mfma_f32_16x16x32_bf16 v[44:47], v[154:157], v[188:191], v[44:47]
	v_mfma_f32_16x16x32_bf16 v[40:43], v[166:169], v[188:191], v[40:43]
	v_mfma_f32_16x16x32_bf16 v[28:31], v[154:157], v[198:201], v[28:31]
	v_mfma_f32_16x16x32_bf16 v[24:27], v[166:169], v[198:201], v[24:27]
	v_mfma_f32_16x16x32_bf16 v[12:15], v[154:157], v[206:209], v[12:15]
	v_mfma_f32_16x16x32_bf16 v[8:11], v[166:169], v[206:209], v[8:11]
	s_setprio 0
	s_barrier
; #define PG8_STAGE(bufoff, gbase, voff) do { _Pragma("unroll") for (int _i = 0; _i < 2; ++_i) \
;         __builtin_amdgcn_global_load_lds((const unsigned*)((const char*)(gbase) + (voff)[_i]), (LAS unsigned*)(lds + (bufoff) + ldsw + _i * 8192), 16, 0, 0); } while (0)
; #define PG8_LDA(dst, b, h) do { _Pragma("unroll") for (int m = 0; m < 4; ++m) _Pragma("unroll") for (int k = 0; k < 2; ++k) dst[m][k] = *(const LAS bf16x8*)(lds + PG8_SA(b, h) + aoff + m * 2048 + k * 1024); } while (0)
; #define PG8_LDB(dst, b, h) do { _Pragma("unroll") for (int n = 0; n < 2; ++n) _Pragma("unroll") for (int k = 0; k < 2; ++k) dst[n][k] = *(const LAS bf16x8*)(lds + PG8_SB(b, h) + boff + n * 2048 + k * 1024); } while (0)
; #define PG8_WAIT_V(n) asm volatile("s_waitcnt vmcnt(" #n ")" ::: "memory")
; #define PG8_WAIT_L(n) asm volatile("s_waitcnt lgkmcnt(" #n ")" ::: "memory")
; #define PG8_BAR __builtin_amdgcn_s_barrier()
; #define PG8_SCHED __builtin_amdgcn_sched_barrier(0)
; template <class Epi, class Sched>
; DI void gemm_phase(LAS unsigned char* lds, const Gemm g, const Sched& S, const Epi& E) {
;     ...
;             PG8_LDB(B0, 0, 0); PG8_SCHED; PG8_LDA(At, 0, 0); PG8_STAGE(PG8_SA(1, 1), a1 + hstep, voffA);
;             PG8_WAIT_L(8); PG8_BAR; PG8_WAIT_L(0); PG8_MMA(0, 0, At, B0); PG8_BAR; PG8_SCHED;
;             PG8_LDB(B1, 0, 1); PG8_STAGE(PG8_SB(0, 0), b2, voffB);
;             PG8_BAR; PG8_WAIT_L(0); PG8_MMA(0, 1, At, B1); PG8_BAR;
;             PG8_LDA(At, 0, 1); PG8_STAGE(PG8_SA(0, 0), a2, voffA);
;             PG8_BAR; PG8_WAIT_L(0); PG8_MMA(1, 0, At, B0); PG8_BAR; PG8_SCHED;
;             PG8_STAGE(PG8_SB(0, 1), b2 + hstep, voffB);
;             PG8_WAIT_V(6); PG8_BAR; PG8_MMA(1, 1, At, B1); PG8_BAR;
;             PG8_LDB(B0, 1, 0); PG8_SCHED; PG8_LDA(At, 1, 0); PG8_STAGE(PG8_SA(0, 1), a2 + hstep, voffA);
;             PG8_WAIT_L(8); PG8_BAR; PG8_WAIT_L(0); PG8_MMA(0, 0, At, B0); PG8_BAR; PG8_SCHED;
;             PG8_LDB(B1, 1, 1); PG8_STAGE(PG8_SB(1, 0), b3, voffB);
;             PG8_BAR; PG8_WAIT_L(0); PG8_MMA(0, 1, At, B1); PG8_BAR;
;             PG8_LDA(At, 1, 1); PG8_STAGE(PG8_SA(1, 0), a3, voffA);
;             PG8_BAR; PG8_WAIT_L(0); PG8_MMA(1, 0, At, B0); PG8_BAR; PG8_SCHED;
;             PG8_STAGE(PG8_SB(1, 1), b3 + hstep, voffB);
;             PG8_WAIT_V(6); PG8_BAR; PG8_MMA(1, 1, At, B1); PG8_BAR;
	s_add_u32 s0, s42, 0x80000
	s_addc_u32 s1, s43, 0
	s_add_i32 s4, s35, s52
	s_mov_b32 m0, s4
	s_nop 0
	global_load_lds_dwordx4 v130, s[0:1]
	s_add_i32 m0, s4, 0x2000
	s_nop 0
	global_load_lds_dwordx4 v134, s[0:1]
	s_waitcnt vmcnt(6)
	s_barrier
	s_setprio 1
	v_mfma_f32_16x16x32_bf16 v[52:55], v[210:213], v[170:173], 0
	v_mfma_f32_16x16x32_bf16 v[48:51], v[218:221], v[170:173], 0
	v_mfma_f32_16x16x32_bf16 v[36:39], v[210:213], v[178:181], 0
	v_mfma_f32_16x16x32_bf16 v[32:35], v[218:221], v[178:181], 0
	v_mfma_f32_16x16x32_bf16 v[20:23], v[210:213], v[194:197], 0
	v_mfma_f32_16x16x32_bf16 v[16:19], v[218:221], v[194:197], 0
	v_mfma_f32_16x16x32_bf16 v[4:7], v[210:213], v[202:205], 0
	v_mfma_f32_16x16x32_bf16 v[0:3], v[218:221], v[202:205], 0
	v_mfma_f32_16x16x32_bf16 v[52:55], v[214:217], v[174:177], v[52:55]
	v_mfma_f32_16x16x32_bf16 v[48:51], v[222:225], v[174:177], v[48:51]
	v_mfma_f32_16x16x32_bf16 v[36:39], v[214:217], v[188:191], v[36:39]
	v_mfma_f32_16x16x32_bf16 v[32:35], v[222:225], v[188:191], v[32:35]
	v_mfma_f32_16x16x32_bf16 v[20:23], v[214:217], v[198:201], v[20:23]
	v_mfma_f32_16x16x32_bf16 v[16:19], v[222:225], v[198:201], v[16:19]
	v_mfma_f32_16x16x32_bf16 v[4:7], v[214:217], v[206:209], v[4:7]
	v_mfma_f32_16x16x32_bf16 v[0:3], v[222:225], v[206:209], v[0:3]
	s_setprio 0
	s_add_i32 s4, 0, 0x18000
	v_add_u32_e32 v161, s4, v146
	s_barrier
	ds_read_b128 v[150:153], v161
	ds_read_b128 v[154:157], v161 offset:1024
	ds_read_b128 v[162:165], v161 offset:2048
	ds_read_b128 v[166:169], v161 offset:3072
	s_add_u32 s0, s44, 0x80000
	s_addc_u32 s1, s45, 0
	s_mov_b32 m0, s54
	ds_read_b128 v[170:173], v148 offset:32768
	ds_read_b128 v[174:177], v148 offset:33792
	ds_read_b128 v[178:181], v148 offset:34816
	ds_read_b128 v[188:191], v148 offset:35840
	ds_read_b128 v[194:197], v148 offset:36864
	ds_read_b128 v[198:201], v148 offset:37888
	ds_read_b128 v[202:205], v148 offset:38912
	ds_read_b128 v[206:209], v148 offset:39936
	global_load_lds_dwordx4 v128, s[0:1]
	s_mov_b32 m0, s55
	s_nop 0
	global_load_lds_dwordx4 v132, s[0:1]
	s_waitcnt lgkmcnt(8)
	s_barrier
	s_waitcnt lgkmcnt(0)
	s_setprio 1
	s_waitcnt lgkmcnt(0)
	v_mfma_f32_16x16x32_bf16 v[124:127], v[150:153], v[170:173], v[124:127]
	v_mfma_f32_16x16x32_bf16 v[120:123], v[162:165], v[170:173], v[120:123]
	v_mfma_f32_16x16x32_bf16 v[108:111], v[150:153], v[178:181], v[108:111]
	v_mfma_f32_16x16x32_bf16 v[104:107], v[162:165], v[178:181], v[104:107]
	v_mfma_f32_16x16x32_bf16 v[92:95], v[150:153], v[194:197], v[92:95]
	v_mfma_f32_16x16x32_bf16 v[88:91], v[162:165], v[194:197], v[88:91]
	v_mfma_f32_16x16x32_bf16 v[76:79], v[150:153], v[202:205], v[76:79]
	v_mfma_f32_16x16x32_bf16 v[72:75], v[162:165], v[202:205], v[72:75]
	v_mfma_f32_16x16x32_bf16 v[124:127], v[154:157], v[174:177], v[124:127]
	v_mfma_f32_16x16x32_bf16 v[120:123], v[166:169], v[174:177], v[120:123]
	v_mfma_f32_16x16x32_bf16 v[108:111], v[154:157], v[188:191], v[108:111]
	v_mfma_f32_16x16x32_bf16 v[104:107], v[166:169], v[188:191], v[104:107]
	v_mfma_f32_16x16x32_bf16 v[92:95], v[154:157], v[198:201], v[92:95]
	v_mfma_f32_16x16x32_bf16 v[88:91], v[166:169], v[198:201], v[88:91]
	v_mfma_f32_16x16x32_bf16 v[76:79], v[154:157], v[206:209], v[76:79]
	v_mfma_f32_16x16x32_bf16 v[72:75], v[166:169], v[206:209], v[72:75]
	s_setprio 0
	s_barrier
	s_add_i32 s5, 0, 0x1c000
	s_add_i32 s0, s4, s52
	v_add_u32_e32 v161, s5, v146
	s_add_i32 m0, s0, 0xffffff80
	ds_read_b128 v[210:213], v161
	ds_read_b128 v[214:217], v161 offset:1024
	ds_read_b128 v[218:221], v161 offset:2048
	ds_read_b128 v[222:225], v161 offset:3072
	global_load_lds_dwordx4 v130, s[42:43] offset:128
	s_add_i32 m0, s0, 0x1f80
	s_nop 0
	global_load_lds_dwordx4 v134, s[42:43] offset:128
	s_barrier
	s_waitcnt lgkmcnt(0)
	s_setprio 1
	s_waitcnt lgkmcnt(0)
	v_mfma_f32_16x16x32_bf16 v[116:119], v[210:213], v[170:173], v[116:119]
	v_mfma_f32_16x16x32_bf16 v[112:115], v[218:221], v[170:173], v[112:115]
	v_mfma_f32_16x16x32_bf16 v[100:103], v[210:213], v[178:181], v[100:103]
	v_mfma_f32_16x16x32_bf16 v[96:99], v[218:221], v[178:181], v[96:99]
	v_mfma_f32_16x16x32_bf16 v[84:87], v[210:213], v[194:197], v[84:87]
	v_mfma_f32_16x16x32_bf16 v[80:83], v[218:221], v[194:197], v[80:83]
	v_mfma_f32_16x16x32_bf16 v[68:71], v[210:213], v[202:205], v[68:71]
	v_mfma_f32_16x16x32_bf16 v[64:67], v[218:221], v[202:205], v[64:67]
	v_mfma_f32_16x16x32_bf16 v[116:119], v[214:217], v[174:177], v[116:119]
	v_mfma_f32_16x16x32_bf16 v[112:115], v[222:225], v[174:177], v[112:115]
	v_mfma_f32_16x16x32_bf16 v[100:103], v[214:217], v[188:191], v[100:103]
	v_mfma_f32_16x16x32_bf16 v[96:99], v[222:225], v[188:191], v[96:99]
	v_mfma_f32_16x16x32_bf16 v[84:87], v[214:217], v[198:201], v[84:87]
	v_mfma_f32_16x16x32_bf16 v[80:83], v[222:225], v[198:201], v[80:83]
	v_mfma_f32_16x16x32_bf16 v[68:71], v[214:217], v[206:209], v[68:71]
	v_mfma_f32_16x16x32_bf16 v[64:67], v[222:225], v[206:209], v[64:67]
	s_setprio 0
	s_add_i32 m0, s59, 0xffffff80
	s_barrier
	ds_read_b128 v[170:173], v148 offset:49152
	ds_read_b128 v[174:177], v148 offset:50176
	ds_read_b128 v[178:181], v148 offset:51200
	ds_read_b128 v[188:191], v148 offset:52224
	ds_read_b128 v[194:197], v148 offset:53248
	ds_read_b128 v[198:201], v148 offset:54272
	ds_read_b128 v[202:205], v148 offset:55296
	ds_read_b128 v[206:209], v148 offset:56320
	global_load_lds_dwordx4 v128, s[44:45] offset:128
	v_lshl_add_u64 v[158:159], v[228:229], 0, s[12:13]
	s_add_i32 m0, s60, 0xffffff80
	s_nop 0
	global_load_lds_dwordx4 v132, s[44:45] offset:128
	s_barrier
; #define PG8_STAGE(bufoff, gbase, voff) do { _Pragma("unroll") for (int _i = 0; _i < 2; ++_i) \
;         __builtin_amdgcn_global_load_lds((const unsigned*)((const char*)(gbase) + (voff)[_i]), (LAS unsigned*)(lds + (bufoff) + ldsw + _i * 8192), 16, 0, 0); } while (0)
; #define PG8_LDA(dst, b, h) do { _Pragma("unroll") for (int m = 0; m < 4; ++m) _Pragma("unroll") for (int k = 0; k < 2; ++k) dst[m][k] = *(const LAS bf16x8*)(lds + PG8_SA(b, h) + aoff + m * 2048 + k * 1024); } while (0)
; #define PG8_LDB(dst, b, h) do { _Pragma("unroll") for (int n = 0; n < 2; ++n) _Pragma("unroll") for (int k = 0; k < 2; ++k) dst[n][k] = *(const LAS bf16x8*)(lds + PG8_SB(b, h) + boff + n * 2048 + k * 1024); } while (0)
; #define PG8_WAIT_V(n) asm volatile("s_waitcnt vmcnt(" #n ")" ::: "memory")
; #define PG8_WAIT_L(n) asm volatile("s_waitcnt lgkmcnt(" #n ")" ::: "memory")
; #define PG8_BAR __builtin_amdgcn_s_barrier()
; #define PG8_SCHED __builtin_amdgcn_sched_barrier(0)
; template <class Epi, class Sched>
; DI void gemm_phase(LAS unsigned char* lds, const Gemm g, const Sched& S, const Epi& E) {
;     ...
;             PG8_LDB(B0, 0, 0); PG8_SCHED; PG8_LDA(At, 0, 0); PG8_STAGE(PG8_SA(1, 1), a1 + hstep, voffA);
;             PG8_WAIT_L(8); PG8_BAR; PG8_WAIT_L(0); PG8_MMA(0, 0, At, B0); PG8_BAR; PG8_SCHED;
;             PG8_LDB(B1, 0, 1); PG8_STAGE(PG8_SB(0, 0), b2, voffB);
;             PG8_BAR; PG8_WAIT_L(0); PG8_MMA(0, 1, At, B1); PG8_BAR;
;             PG8_LDA(At, 0, 1); PG8_STAGE(PG8_SA(0, 0), a2, voffA);
;             PG8_BAR; PG8_WAIT_L(0); PG8_MMA(1, 0, At, B0); PG8_BAR; PG8_SCHED;
;             PG8_STAGE(PG8_SB(0, 1), b2 + hstep, voffB);
;             PG8_WAIT_V(6); PG8_BAR; PG8_MMA(1, 1, At, B1); PG8_BAR;
;             PG8_LDB(B0, 1, 0); PG8_SCHED; PG8_LDA(At, 1, 0); PG8_STAGE(PG8_SA(0, 1), a2 + hstep, voffA);
;             PG8_WAIT_L(8); PG8_BAR; PG8_WAIT_L(0); PG8_MMA(0, 0, At, B0); PG8_BAR; PG8_SCHED;
;             PG8_LDB(B1, 1, 1); PG8_STAGE(PG8_SB(1, 0), b3, voffB);
;             PG8_BAR; PG8_WAIT_L(0); PG8_MMA(0, 1, At, B1); PG8_BAR;
;             PG8_LDA(At, 1, 1); PG8_STAGE(PG8_SA(1, 0), a3, voffA);
;             PG8_BAR; PG8_WAIT_L(0); PG8_MMA(1, 0, At, B0); PG8_BAR; PG8_SCHED;
;             PG8_STAGE(PG8_SB(1, 1), b3 + hstep, voffB);
;             PG8_WAIT_V(6); PG8_BAR; PG8_MMA(1, 1, At, B1); PG8_BAR;
	s_waitcnt lgkmcnt(0)
	s_setprio 1
	s_waitcnt lgkmcnt(0)
	v_mfma_f32_16x16x32_bf16 v[60:63], v[150:153], v[170:173], v[60:63]
	v_mfma_f32_16x16x32_bf16 v[56:59], v[162:165], v[170:173], v[56:59]
	v_mfma_f32_16x16x32_bf16 v[44:47], v[150:153], v[178:181], v[44:47]
	v_mfma_f32_16x16x32_bf16 v[40:43], v[162:165], v[178:181], v[40:43]
	v_mfma_f32_16x16x32_bf16 v[28:31], v[150:153], v[194:197], v[28:31]
	v_mfma_f32_16x16x32_bf16 v[24:27], v[162:165], v[194:197], v[24:27]
	v_mfma_f32_16x16x32_bf16 v[12:15], v[150:153], v[202:205], v[12:15]
	v_mfma_f32_16x16x32_bf16 v[8:11], v[162:165], v[202:205], v[8:11]
	v_mfma_f32_16x16x32_bf16 v[60:63], v[154:157], v[174:177], v[60:63]
	v_mfma_f32_16x16x32_bf16 v[56:59], v[166:169], v[174:177], v[56:59]
	v_mfma_f32_16x16x32_bf16 v[44:47], v[154:157], v[188:191], v[44:47]
	v_mfma_f32_16x16x32_bf16 v[40:43], v[166:169], v[188:191], v[40:43]
	v_mfma_f32_16x16x32_bf16 v[28:31], v[154:157], v[198:201], v[28:31]
	v_mfma_f32_16x16x32_bf16 v[24:27], v[166:169], v[198:201], v[24:27]
	v_mfma_f32_16x16x32_bf16 v[12:15], v[154:157], v[206:209], v[12:15]
	v_mfma_f32_16x16x32_bf16 v[8:11], v[166:169], v[206:209], v[8:11]
	s_setprio 0
	s_barrier
	s_add_u32 s0, s42, 0x80080
	s_addc_u32 s1, s43, 0
	s_add_i32 s4, s5, s52
	s_mov_b32 m0, s4
	s_nop 0
	global_load_lds_dwordx4 v130, s[0:1]
	s_add_i32 m0, s4, 0x2000
	s_nop 0
	global_load_lds_dwordx4 v134, s[0:1]
	s_waitcnt vmcnt(6)
	s_barrier
	s_setprio 1
	v_mfma_f32_16x16x32_bf16 v[52:55], v[210:213], v[170:173], v[52:55]
	v_mfma_f32_16x16x32_bf16 v[48:51], v[218:221], v[170:173], v[48:51]
	v_mfma_f32_16x16x32_bf16 v[36:39], v[210:213], v[178:181], v[36:39]
	v_mfma_f32_16x16x32_bf16 v[32:35], v[218:221], v[178:181], v[32:35]
	v_mfma_f32_16x16x32_bf16 v[20:23], v[210:213], v[194:197], v[20:23]
	v_mfma_f32_16x16x32_bf16 v[16:19], v[218:221], v[194:197], v[16:19]
	v_mfma_f32_16x16x32_bf16 v[4:7], v[210:213], v[202:205], v[4:7]
	v_mfma_f32_16x16x32_bf16 v[0:3], v[218:221], v[202:205], v[0:3]
	v_mfma_f32_16x16x32_bf16 v[52:55], v[214:217], v[174:177], v[52:55]
	v_mfma_f32_16x16x32_bf16 v[48:51], v[222:225], v[174:177], v[48:51]
	v_mfma_f32_16x16x32_bf16 v[36:39], v[214:217], v[188:191], v[36:39]
	v_mfma_f32_16x16x32_bf16 v[32:35], v[222:225], v[188:191], v[32:35]
	v_mfma_f32_16x16x32_bf16 v[20:23], v[214:217], v[198:201], v[20:23]
	v_mfma_f32_16x16x32_bf16 v[16:19], v[222:225], v[198:201], v[16:19]
	v_mfma_f32_16x16x32_bf16 v[4:7], v[214:217], v[206:209], v[4:7]
	v_mfma_f32_16x16x32_bf16 v[0:3], v[222:225], v[206:209], v[0:3]
	s_setprio 0
	s_add_i32 s69, s69, 2
	s_add_u32 s40, s40, 0x100
	s_addc_u32 s41, s41, 0
	s_add_u32 s67, s67, 0x100
	s_addc_u32 s68, s68, 0
	s_cmp_gt_u32 s69, 29
	s_barrier
	s_cbranch_scc0 .LBB0_219
	s_branch .Lpeel_done_219
.LBB0_219:
	ds_read_b128 v[150:153], v147
	ds_read_b128 v[154:157], v147 offset:1024
	ds_read_b128 v[162:165], v147 offset:2048
	ds_read_b128 v[166:169], v147 offset:3072
	s_add_u32 s0, s40, 0xfff80080
	s_addc_u32 s1, s41, -1
	s_cmp_eq_u32 s69, 28
	s_cselect_b32 s45, s17, s1
	s_cselect_b32 s44, s65, s0
	s_cselect_b32 s43, s15, s68
	s_cselect_b32 s42, s66, s67
	s_add_i32 m0, s39, 0xc000
	ds_read_b128 v[170:173], v148
	ds_read_b128 v[174:177], v148 offset:1024
	ds_read_b128 v[178:181], v148 offset:2048
	ds_read_b128 v[188:191], v148 offset:3072
	ds_read_b128 v[194:197], v148 offset:4096
	ds_read_b128 v[198:201], v148 offset:5120
	ds_read_b128 v[202:205], v148 offset:6144
	ds_read_b128 v[206:209], v148 offset:7168
	global_load_lds_dwordx4 v136, s[40:41]
	s_add_i32 m0, s39, 0xe000
	s_nop 0
	global_load_lds_dwordx4 v138, s[40:41]
	s_waitcnt lgkmcnt(8)
	s_barrier
	s_waitcnt lgkmcnt(0)
	s_setprio 1
	s_waitcnt lgkmcnt(0)
	v_mfma_f32_16x16x32_bf16 v[124:127], v[150:153], v[170:173], v[124:127]
	v_mfma_f32_16x16x32_bf16 v[120:123], v[162:165], v[170:173], v[120:123]
	v_mfma_f32_16x16x32_bf16 v[108:111], v[150:153], v[178:181], v[108:111]
	v_mfma_f32_16x16x32_bf16 v[104:107], v[162:165], v[178:181], v[104:107]
	v_mfma_f32_16x16x32_bf16 v[92:95], v[150:153], v[194:197], v[92:95]
	v_mfma_f32_16x16x32_bf16 v[88:91], v[162:165], v[194:197], v[88:91]
	v_mfma_f32_16x16x32_bf16 v[76:79], v[150:153], v[202:205], v[76:79]
	v_mfma_f32_16x16x32_bf16 v[72:75], v[162:165], v[202:205], v[72:75]
	v_mfma_f32_16x16x32_bf16 v[124:127], v[154:157], v[174:177], v[124:127]
	v_mfma_f32_16x16x32_bf16 v[120:123], v[166:169], v[174:177], v[120:123]
	v_mfma_f32_16x16x32_bf16 v[108:111], v[154:157], v[188:191], v[108:111]
	v_mfma_f32_16x16x32_bf16 v[104:107], v[166:169], v[188:191], v[104:107]
	v_mfma_f32_16x16x32_bf16 v[92:95], v[154:157], v[198:201], v[92:95]
	v_mfma_f32_16x16x32_bf16 v[88:91], v[166:169], v[198:201], v[88:91]
	v_mfma_f32_16x16x32_bf16 v[76:79], v[154:157], v[206:209], v[76:79]
	v_mfma_f32_16x16x32_bf16 v[72:75], v[166:169], v[206:209], v[72:75]
	s_setprio 0
	s_barrier
	s_add_i32 s0, s34, s52
	s_mov_b32 m0, s0
	ds_read_b128 v[210:213], v149
	ds_read_b128 v[214:217], v149 offset:1024
	ds_read_b128 v[218:221], v149 offset:2048
	ds_read_b128 v[222:225], v149 offset:3072
	global_load_lds_dwordx4 v130, s[42:43]
	v_lshl_add_u64 v[182:183], s[42:43], 0, v[134:135]
	s_add_i32 m0, s0, 0x2000
	s_nop 0
	global_load_lds_dwordx4 v134, s[42:43]
	s_barrier
; #define PG8_STAGE(bufoff, gbase, voff) do { _Pragma("unroll") for (int _i = 0; _i < 2; ++_i) \
;         __builtin_amdgcn_global_load_lds((const unsigned*)((const char*)(gbase) + (voff)[_i]), (LAS unsigned*)(lds + (bufoff) + ldsw + _i * 8192), 16, 0, 0); } while (0)
; #define PG8_LDA(dst, b, h) do { _Pragma("unroll") for (int m = 0; m < 4; ++m) _Pragma("unroll") for (int k = 0; k < 2; ++k) dst[m][k] = *(const LAS bf16x8*)(lds + PG8_SA(b, h) + aoff + m * 2048 + k * 1024); } while (0)
; #define PG8_LDB(dst, b, h) do { _Pragma("unroll") for (int n = 0; n < 2; ++n) _Pragma("unroll") for (int k = 0; k < 2; ++k) dst[n][k] = *(const LAS bf16x8*)(lds + PG8_SB(b, h) + boff + n * 2048 + k * 1024); } while (0)
; #define PG8_WAIT_V(n) asm volatile("s_waitcnt vmcnt(" #n ")" ::: "memory")
; #define PG8_WAIT_L(n) asm volatile("s_waitcnt lgkmcnt(" #n ")" ::: "memory")
; #define PG8_BAR __builtin_amdgcn_s_barrier()
; #define PG8_SCHED __builtin_amdgcn_sched_barrier(0)
; template <class Epi, class Sched>
; DI void gemm_phase(LAS unsigned char* lds, const Gemm g, const Sched& S, const Epi& E) {
;     ...
;             PG8_LDB(B0, 0, 0); PG8_SCHED; PG8_LDA(At, 0, 0); PG8_STAGE(PG8_SA(1, 1), a1 + hstep, voffA);
;             PG8_WAIT_L(8); PG8_BAR; PG8_WAIT_L(0); PG8_MMA(0, 0, At, B0); PG8_BAR; PG8_SCHED;
;             PG8_LDB(B1, 0, 1); PG8_STAGE(PG8_SB(0, 0), b2, voffB);
;             PG8_BAR; PG8_WAIT_L(0); PG8_MMA(0, 1, At, B1); PG8_BAR;
;             PG8_LDA(At, 0, 1); PG8_STAGE(PG8_SA(0, 0), a2, voffA);
;             PG8_BAR; PG8_WAIT_L(0); PG8_MMA(1, 0, At, B0); PG8_BAR; PG8_SCHED;
;             PG8_STAGE(PG8_SB(0, 1), b2 + hstep, voffB);
;             PG8_WAIT_V(6); PG8_BAR; PG8_MMA(1, 1, At, B1); PG8_BAR;
;             PG8_LDB(B0, 1, 0); PG8_SCHED; PG8_LDA(At, 1, 0); PG8_STAGE(PG8_SA(0, 1), a2 + hstep, voffA);
;             PG8_WAIT_L(8); PG8_BAR; PG8_WAIT_L(0); PG8_MMA(0, 0, At, B0); PG8_BAR; PG8_SCHED;
;             PG8_LDB(B1, 1, 1); PG8_STAGE(PG8_SB(1, 0), b3, voffB);
;             PG8_BAR; PG8_WAIT_L(0); PG8_MMA(0, 1, At, B1); PG8_BAR;
;             PG8_LDA(At, 1, 1); PG8_STAGE(PG8_SA(1, 0), a3, voffA);
;             PG8_BAR; PG8_WAIT_L(0); PG8_MMA(1, 0, At, B0); PG8_BAR; PG8_SCHED;
;             PG8_STAGE(PG8_SB(1, 1), b3 + hstep, voffB);
;             PG8_WAIT_V(6); PG8_BAR; PG8_MMA(1, 1, At, B1); PG8_BAR;
	s_waitcnt lgkmcnt(0)
	s_setprio 1
	s_waitcnt lgkmcnt(0)
	v_mfma_f32_16x16x32_bf16 v[116:119], v[210:213], v[170:173], v[116:119]
	v_mfma_f32_16x16x32_bf16 v[112:115], v[218:221], v[170:173], v[112:115]
	v_mfma_f32_16x16x32_bf16 v[100:103], v[210:213], v[178:181], v[100:103]
	v_mfma_f32_16x16x32_bf16 v[96:99], v[218:221], v[178:181], v[96:99]
	v_mfma_f32_16x16x32_bf16 v[84:87], v[210:213], v[194:197], v[84:87]
	v_mfma_f32_16x16x32_bf16 v[80:83], v[218:221], v[194:197], v[80:83]
	v_mfma_f32_16x16x32_bf16 v[68:71], v[210:213], v[202:205], v[68:71]
	v_mfma_f32_16x16x32_bf16 v[64:67], v[218:221], v[202:205], v[64:67]
	v_mfma_f32_16x16x32_bf16 v[116:119], v[214:217], v[174:177], v[116:119]
	v_mfma_f32_16x16x32_bf16 v[112:115], v[222:225], v[174:177], v[112:115]
	v_mfma_f32_16x16x32_bf16 v[100:103], v[214:217], v[188:191], v[100:103]
	v_mfma_f32_16x16x32_bf16 v[96:99], v[222:225], v[188:191], v[96:99]
	v_mfma_f32_16x16x32_bf16 v[84:87], v[214:217], v[198:201], v[84:87]
	v_mfma_f32_16x16x32_bf16 v[80:83], v[222:225], v[198:201], v[80:83]
	v_mfma_f32_16x16x32_bf16 v[68:71], v[214:217], v[206:209], v[68:71]
	v_mfma_f32_16x16x32_bf16 v[64:67], v[222:225], v[206:209], v[64:67]
	s_setprio 0
	s_mov_b32 m0, s39
	v_lshl_add_u64 v[226:227], s[44:45], 0, v[128:129]
	s_barrier
	ds_read_b128 v[170:173], v148 offset:16384
	ds_read_b128 v[174:177], v148 offset:17408
	ds_read_b128 v[178:181], v148 offset:18432
	ds_read_b128 v[188:191], v148 offset:19456
	ds_read_b128 v[194:197], v148 offset:20480
	ds_read_b128 v[198:201], v148 offset:21504
	ds_read_b128 v[202:205], v148 offset:22528
	ds_read_b128 v[206:209], v148 offset:23552
	global_load_lds_dwordx4 v128, s[44:45]
	v_lshl_add_u64 v[228:229], s[44:45], 0, v[132:133]
	s_mov_b32 m0, s53
	s_nop 0
	global_load_lds_dwordx4 v132, s[44:45]
	s_barrier
	s_waitcnt lgkmcnt(0)
	s_setprio 1
	s_waitcnt lgkmcnt(0)
	v_mfma_f32_16x16x32_bf16 v[60:63], v[150:153], v[170:173], v[60:63]
	v_mfma_f32_16x16x32_bf16 v[56:59], v[162:165], v[170:173], v[56:59]
	v_mfma_f32_16x16x32_bf16 v[44:47], v[150:153], v[178:181], v[44:47]
	v_mfma_f32_16x16x32_bf16 v[40:43], v[162:165], v[178:181], v[40:43]
	v_mfma_f32_16x16x32_bf16 v[28:31], v[150:153], v[194:197], v[28:31]
	v_mfma_f32_16x16x32_bf16 v[24:27], v[162:165], v[194:197], v[24:27]
	v_mfma_f32_16x16x32_bf16 v[12:15], v[150:153], v[202:205], v[12:15]
	v_mfma_f32_16x16x32_bf16 v[8:11], v[162:165], v[202:205], v[8:11]
	v_mfma_f32_16x16x32_bf16 v[60:63], v[154:157], v[174:177], v[60:63]
	v_mfma_f32_16x16x32_bf16 v[56:59], v[166:169], v[174:177], v[56:59]
	v_mfma_f32_16x16x32_bf16 v[44:47], v[154:157], v[188:191], v[44:47]
	v_mfma_f32_16x16x32_bf16 v[40:43], v[166:169], v[188:191], v[40:43]
	v_mfma_f32_16x16x32_bf16 v[28:31], v[154:157], v[198:201], v[28:31]
	v_mfma_f32_16x16x32_bf16 v[24:27], v[166:169], v[198:201], v[24:27]
	v_mfma_f32_16x16x32_bf16 v[12:15], v[154:157], v[206:209], v[12:15]
	v_mfma_f32_16x16x32_bf16 v[8:11], v[166:169], v[206:209], v[8:11]
	s_setprio 0
	s_barrier
	s_add_u32 s0, s42, 0x80000
	s_addc_u32 s1, s43, 0
	s_add_i32 s4, s35, s52
	s_mov_b32 m0, s4
	s_nop 0
	global_load_lds_dwordx4 v130, s[0:1]
	s_add_i32 m0, s4, 0x2000
	s_nop 0
	global_load_lds_dwordx4 v134, s[0:1]
	s_waitcnt vmcnt(6)
	s_barrier
	s_setprio 1
	v_mfma_f32_16x16x32_bf16 v[52:55], v[210:213], v[170:173], v[52:55]
	v_mfma_f32_16x16x32_bf16 v[48:51], v[218:221], v[170:173], v[48:51]
	v_mfma_f32_16x16x32_bf16 v[36:39], v[210:213], v[178:181], v[36:39]
	v_mfma_f32_16x16x32_bf16 v[32:35], v[218:221], v[178:181], v[32:35]
	v_mfma_f32_16x16x32_bf16 v[20:23], v[210:213], v[194:197], v[20:23]
	v_mfma_f32_16x16x32_bf16 v[16:19], v[218:221], v[194:197], v[16:19]
	v_mfma_f32_16x16x32_bf16 v[4:7], v[210:213], v[202:205], v[4:7]
	v_mfma_f32_16x16x32_bf16 v[0:3], v[218:221], v[202:205], v[0:3]
	v_mfma_f32_16x16x32_bf16 v[52:55], v[214:217], v[174:177], v[52:55]
	v_mfma_f32_16x16x32_bf16 v[48:51], v[222:225], v[174:177], v[48:51]
	v_mfma_f32_16x16x32_bf16 v[36:39], v[214:217], v[188:191], v[36:39]
	v_mfma_f32_16x16x32_bf16 v[32:35], v[222:225], v[188:191], v[32:35]
	v_mfma_f32_16x16x32_bf16 v[20:23], v[214:217], v[198:201], v[20:23]
	v_mfma_f32_16x16x32_bf16 v[16:19], v[222:225], v[198:201], v[16:19]
	v_mfma_f32_16x16x32_bf16 v[4:7], v[214:217], v[206:209], v[4:7]
	v_mfma_f32_16x16x32_bf16 v[0:3], v[222:225], v[206:209], v[0:3]
	s_setprio 0
	s_add_i32 s4, 0, 0x18000
	v_add_u32_e32 v161, s4, v146
	s_barrier
	ds_read_b128 v[150:153], v161
	ds_read_b128 v[154:157], v161 offset:1024
	ds_read_b128 v[162:165], v161 offset:2048
	ds_read_b128 v[166:169], v161 offset:3072
	s_add_u32 s0, s44, 0x80000
	s_addc_u32 s1, s45, 0
	s_mov_b32 m0, s54
	ds_read_b128 v[170:173], v148 offset:32768
	ds_read_b128 v[174:177], v148 offset:33792
	ds_read_b128 v[178:181], v148 offset:34816
	ds_read_b128 v[188:191], v148 offset:35840
	ds_read_b128 v[194:197], v148 offset:36864
	ds_read_b128 v[198:201], v148 offset:37888
	ds_read_b128 v[202:205], v148 offset:38912
	ds_read_b128 v[206:209], v148 offset:39936
	global_load_lds_dwordx4 v128, s[0:1]
	s_mov_b32 m0, s55
	s_nop 0
	global_load_lds_dwordx4 v132, s[0:1]
	s_waitcnt lgkmcnt(8)
	s_barrier
; #define PG8_STAGE(bufoff, gbase, voff) do { _Pragma("unroll") for (int _i = 0; _i < 2; ++_i) \
;         __builtin_amdgcn_global_load_lds((const unsigned*)((const char*)(gbase) + (voff)[_i]), (LAS unsigned*)(lds + (bufoff) + ldsw + _i * 8192), 16, 0, 0); } while (0)
; #define PG8_LDA(dst, b, h) do { _Pragma("unroll") for (int m = 0; m < 4; ++m) _Pragma("unroll") for (int k = 0; k < 2; ++k) dst[m][k] = *(const LAS bf16x8*)(lds + PG8_SA(b, h) + aoff + m * 2048 + k * 1024); } while (0)
; #define PG8_LDB(dst, b, h) do { _Pragma("unroll") for (int n = 0; n < 2; ++n) _Pragma("unroll") for (int k = 0; k < 2; ++k) dst[n][k] = *(const LAS bf16x8*)(lds + PG8_SB(b, h) + boff + n * 2048 + k * 1024); } while (0)
; #define PG8_MMA(ai, bj, At, Bt) do { __builtin_amdgcn_s_setprio(1); _Pragma("unroll") for (int m = 0; m < 4; ++m) _Pragma("unroll") for (int n = 0; n < 2; ++n) _Pragma("unroll") for (int k = 0; k < 2; ++k) \
;         acc[ai][bj][m][n] = __builtin_amdgcn_mfma_f32_16x16x32_bf16(Bt[n][k], At[m][k], acc[ai][bj][m][n], 0, 0, 0); __builtin_amdgcn_s_setprio(0); } while (0)
; #define PG8_WAIT_V(n) asm volatile("s_waitcnt vmcnt(" #n ")" ::: "memory")
; #define PG8_WAIT_L(n) asm volatile("s_waitcnt lgkmcnt(" #n ")" ::: "memory")
; #define PG8_BAR __builtin_amdgcn_s_barrier()
; #define PG8_SCHED __builtin_amdgcn_sched_barrier(0)
; template <class Epi, class Sched>
; DI void gemm_phase(LAS unsigned char* lds, const Gemm g, const Sched& S, const Epi& E) {
;     ...
;             PG8_LDB(B1, 1, 1); PG8_STAGE(PG8_SB(1, 0), b3, voffB);
;             PG8_BAR; PG8_WAIT_L(0); PG8_MMA(0, 1, At, B1); PG8_BAR;
;             PG8_LDA(At, 1, 1); PG8_STAGE(PG8_SA(1, 0), a3, voffA);
;             PG8_BAR; PG8_WAIT_L(0); PG8_MMA(1, 0, At, B0); PG8_BAR; PG8_SCHED;
;             PG8_STAGE(PG8_SB(1, 1), b3 + hstep, voffB);
;             PG8_WAIT_V(6); PG8_BAR; PG8_MMA(1, 1, At, B1); PG8_BAR;
	s_waitcnt lgkmcnt(0)
	s_setprio 1
	s_waitcnt lgkmcnt(0)
	v_mfma_f32_16x16x32_bf16 v[124:127], v[150:153], v[170:173], v[124:127]
	v_mfma_f32_16x16x32_bf16 v[120:123], v[162:165], v[170:173], v[120:123]
	v_mfma_f32_16x16x32_bf16 v[108:111], v[150:153], v[178:181], v[108:111]
	v_mfma_f32_16x16x32_bf16 v[104:107], v[162:165], v[178:181], v[104:107]
	v_mfma_f32_16x16x32_bf16 v[92:95], v[150:153], v[194:197], v[92:95]
	v_mfma_f32_16x16x32_bf16 v[88:91], v[162:165], v[194:197], v[88:91]
	v_mfma_f32_16x16x32_bf16 v[76:79], v[150:153], v[202:205], v[76:79]
	v_mfma_f32_16x16x32_bf16 v[72:75], v[162:165], v[202:205], v[72:75]
	v_mfma_f32_16x16x32_bf16 v[124:127], v[154:157], v[174:177], v[124:127]
	v_mfma_f32_16x16x32_bf16 v[120:123], v[166:169], v[174:177], v[120:123]
	v_mfma_f32_16x16x32_bf16 v[108:111], v[154:157], v[188:191], v[108:111]
	v_mfma_f32_16x16x32_bf16 v[104:107], v[166:169], v[188:191], v[104:107]
	v_mfma_f32_16x16x32_bf16 v[92:95], v[154:157], v[198:201], v[92:95]
	v_mfma_f32_16x16x32_bf16 v[88:91], v[166:169], v[198:201], v[88:91]
	v_mfma_f32_16x16x32_bf16 v[76:79], v[154:157], v[206:209], v[76:79]
	v_mfma_f32_16x16x32_bf16 v[72:75], v[166:169], v[206:209], v[72:75]
	s_setprio 0
	s_barrier
	s_add_i32 s5, 0, 0x1c000
	s_add_i32 s0, s4, s52
	v_add_u32_e32 v161, s5, v146
	s_add_i32 m0, s0, 0xffffff80
	ds_read_b128 v[210:213], v161
	ds_read_b128 v[214:217], v161 offset:1024
	ds_read_b128 v[218:221], v161 offset:2048
	ds_read_b128 v[222:225], v161 offset:3072
	global_load_lds_dwordx4 v130, s[42:43] offset:128
	s_add_i32 m0, s0, 0x1f80
	s_nop 0
	global_load_lds_dwordx4 v134, s[42:43] offset:128
	s_barrier
	s_waitcnt lgkmcnt(0)
	s_setprio 1
	s_waitcnt lgkmcnt(0)
	v_mfma_f32_16x16x32_bf16 v[116:119], v[210:213], v[170:173], v[116:119]
	v_mfma_f32_16x16x32_bf16 v[112:115], v[218:221], v[170:173], v[112:115]
	v_mfma_f32_16x16x32_bf16 v[100:103], v[210:213], v[178:181], v[100:103]
	v_mfma_f32_16x16x32_bf16 v[96:99], v[218:221], v[178:181], v[96:99]
	v_mfma_f32_16x16x32_bf16 v[84:87], v[210:213], v[194:197], v[84:87]
	v_mfma_f32_16x16x32_bf16 v[80:83], v[218:221], v[194:197], v[80:83]
	v_mfma_f32_16x16x32_bf16 v[68:71], v[210:213], v[202:205], v[68:71]
	v_mfma_f32_16x16x32_bf16 v[64:67], v[218:221], v[202:205], v[64:67]
	v_mfma_f32_16x16x32_bf16 v[116:119], v[214:217], v[174:177], v[116:119]
	v_mfma_f32_16x16x32_bf16 v[112:115], v[222:225], v[174:177], v[112:115]
	v_mfma_f32_16x16x32_bf16 v[100:103], v[214:217], v[188:191], v[100:103]
	v_mfma_f32_16x16x32_bf16 v[96:99], v[222:225], v[188:191], v[96:99]
	v_mfma_f32_16x16x32_bf16 v[84:87], v[214:217], v[198:201], v[84:87]
	v_mfma_f32_16x16x32_bf16 v[80:83], v[222:225], v[198:201], v[80:83]
	v_mfma_f32_16x16x32_bf16 v[68:71], v[214:217], v[206:209], v[68:71]
	v_mfma_f32_16x16x32_bf16 v[64:67], v[222:225], v[206:209], v[64:67]
	s_setprio 0
	s_add_i32 m0, s59, 0xffffff80
	s_barrier
	ds_read_b128 v[170:173], v148 offset:49152
	ds_read_b128 v[174:177], v148 offset:50176
	ds_read_b128 v[178:181], v148 offset:51200
	ds_read_b128 v[188:191], v148 offset:52224
	ds_read_b128 v[194:197], v148 offset:53248
	ds_read_b128 v[198:201], v148 offset:54272
	ds_read_b128 v[202:205], v148 offset:55296
	ds_read_b128 v[206:209], v148 offset:56320
	global_load_lds_dwordx4 v128, s[44:45] offset:128
	v_lshl_add_u64 v[158:159], v[228:229], 0, s[12:13]
	s_add_i32 m0, s60, 0xffffff80
	s_nop 0
	global_load_lds_dwordx4 v132, s[44:45] offset:128
	s_barrier
	s_waitcnt lgkmcnt(0)
	s_setprio 1
	s_waitcnt lgkmcnt(0)
	v_mfma_f32_16x16x32_bf16 v[60:63], v[150:153], v[170:173], v[60:63]
	v_mfma_f32_16x16x32_bf16 v[56:59], v[162:165], v[170:173], v[56:59]
	v_mfma_f32_16x16x32_bf16 v[44:47], v[150:153], v[178:181], v[44:47]
	v_mfma_f32_16x16x32_bf16 v[40:43], v[162:165], v[178:181], v[40:43]
	v_mfma_f32_16x16x32_bf16 v[28:31], v[150:153], v[194:197], v[28:31]
	v_mfma_f32_16x16x32_bf16 v[24:27], v[162:165], v[194:197], v[24:27]
	v_mfma_f32_16x16x32_bf16 v[12:15], v[150:153], v[202:205], v[12:15]
	v_mfma_f32_16x16x32_bf16 v[8:11], v[162:165], v[202:205], v[8:11]
	v_mfma_f32_16x16x32_bf16 v[60:63], v[154:157], v[174:177], v[60:63]
	v_mfma_f32_16x16x32_bf16 v[56:59], v[166:169], v[174:177], v[56:59]
	v_mfma_f32_16x16x32_bf16 v[44:47], v[154:157], v[188:191], v[44:47]
	v_mfma_f32_16x16x32_bf16 v[40:43], v[166:169], v[188:191], v[40:43]
	v_mfma_f32_16x16x32_bf16 v[28:31], v[154:157], v[198:201], v[28:31]
	v_mfma_f32_16x16x32_bf16 v[24:27], v[166:169], v[198:201], v[24:27]
	v_mfma_f32_16x16x32_bf16 v[12:15], v[154:157], v[206:209], v[12:15]
	v_mfma_f32_16x16x32_bf16 v[8:11], v[166:169], v[206:209], v[8:11]
	s_setprio 0
	s_barrier
	s_add_u32 s0, s42, 0x80080
	s_addc_u32 s1, s43, 0
	s_add_i32 s4, s5, s52
	s_mov_b32 m0, s4
	s_nop 0
	global_load_lds_dwordx4 v130, s[0:1]
	s_add_i32 m0, s4, 0x2000
	s_nop 0
	global_load_lds_dwordx4 v134, s[0:1]
	s_waitcnt vmcnt(6)
	s_barrier
	s_setprio 1
	v_mfma_f32_16x16x32_bf16 v[52:55], v[210:213], v[170:173], v[52:55]
	v_mfma_f32_16x16x32_bf16 v[48:51], v[218:221], v[170:173], v[48:51]
	v_mfma_f32_16x16x32_bf16 v[36:39], v[210:213], v[178:181], v[36:39]
	v_mfma_f32_16x16x32_bf16 v[32:35], v[218:221], v[178:181], v[32:35]
	v_mfma_f32_16x16x32_bf16 v[20:23], v[210:213], v[194:197], v[20:23]
	v_mfma_f32_16x16x32_bf16 v[16:19], v[218:221], v[194:197], v[16:19]
	v_mfma_f32_16x16x32_bf16 v[4:7], v[210:213], v[202:205], v[4:7]
	v_mfma_f32_16x16x32_bf16 v[0:3], v[218:221], v[202:205], v[0:3]
	v_mfma_f32_16x16x32_bf16 v[52:55], v[214:217], v[174:177], v[52:55]
	v_mfma_f32_16x16x32_bf16 v[48:51], v[222:225], v[174:177], v[48:51]
	v_mfma_f32_16x16x32_bf16 v[36:39], v[214:217], v[188:191], v[36:39]
	v_mfma_f32_16x16x32_bf16 v[32:35], v[222:225], v[188:191], v[32:35]
	v_mfma_f32_16x16x32_bf16 v[20:23], v[214:217], v[198:201], v[20:23]
	v_mfma_f32_16x16x32_bf16 v[16:19], v[222:225], v[198:201], v[16:19]
	v_mfma_f32_16x16x32_bf16 v[4:7], v[214:217], v[206:209], v[4:7]
	v_mfma_f32_16x16x32_bf16 v[0:3], v[222:225], v[206:209], v[0:3]
	s_setprio 0
	s_add_i32 s69, s69, 2
	s_add_u32 s40, s40, 0x100
	s_addc_u32 s41, s41, 0
	s_add_u32 s67, s67, 0x100
	s_addc_u32 s68, s68, 0
	s_cmp_gt_u32 s69, 29
	s_barrier
	s_cbranch_scc0 .LBB0_219

; #define PG8_STAGE(bufoff, gbase, voff) do { _Pragma("unroll") for (int _i = 0; _i < 2; ++_i) \
;         __builtin_amdgcn_global_load_lds((const unsigned*)((const char*)(gbase) + (voff)[_i]), (LAS unsigned*)(lds + (bufoff) + ldsw + _i * 8192), 16, 0, 0); } while (0)
; #define PG8_WAIT_V(n) asm volatile("s_waitcnt vmcnt(" #n ")" ::: "memory")
; #define PG8_BAR __builtin_amdgcn_s_barrier()
; template <class Epi, class Sched>
; DI void gemm_phase(LAS unsigned char* lds, const Gemm g, const Sched& S, const Epi& E) {
;     ...
;     PG8_STAGE(PG8_SB(0, 0), cB, voffB); PG8_STAGE(PG8_SA(0, 0), cA, voffA); PG8_STAGE(PG8_SB(0, 1), cB + hstep, voffB); PG8_STAGE(PG8_SA(0, 1), cA + hstep, voffA);
;     if (wr == 1) PG8_BAR;
;     PG8_WAIT_V(4); PG8_BAR;
;     PG8_STAGE(PG8_SB(1, 0), cB + kstep, voffB); PG8_STAGE(PG8_SA(1, 0), cA + kstep, voffA); PG8_STAGE(PG8_SB(1, 1), cB + hstep + kstep, voffB);
;     PG8_WAIT_V(6); PG8_BAR;
.LBB0_284:
	s_add_u32 s18, s22, 0x86c3000
	s_addc_u32 s19, s23, 0
	s_add_u32 s36, s22, 0x183000
	s_mov_b64 s[38:39], 0x80
	s_addc_u32 s37, s23, 0
	s_and_b32 s58, s1, 3
	s_add_i32 m0, s54, 0x18000
	v_lshl_add_u64 v[6:7], v[6:7], 0, s[38:39]
	s_lshl_b32 s59, s0, 6
	s_lshl_b32 s4, s0, 13
	s_lshl_b32 s60, s58, 5
	s_waitcnt vmcnt(4)
	s_barrier
	global_load_lds_dwordx4 v[6:7], off
	v_lshl_add_u64 v[4:5], v[4:5], 0, s[38:39]
	s_add_i32 m0, s54, 0x1a000
	s_add_i32 s61, s54, 0x8000
	s_add_i32 s62, s54, 0xa000
	global_load_lds_dwordx4 v[4:5], off
	v_lshl_add_u64 v[2:3], v[2:3], 0, s[38:39]
	s_mov_b32 m0, s61
	s_add_u32 s0, s42, 0x160080
	global_load_lds_dwordx4 v[2:3], off
	v_lshl_add_u64 v[0:1], v[0:1], 0, s[38:39]
	s_mov_b32 m0, s62
	s_addc_u32 s1, s43, 0
	global_load_lds_dwordx4 v[0:1], off
	s_add_i32 m0, s54, 0x1c000
	s_nop 0
	global_load_lds_dwordx4 v130, s[0:1]
	s_add_i32 m0, s54, 0x1e000
	v_lshl_or_b32 v157, s58, 12, v153
	global_load_lds_dwordx4 v134, s[0:1]
	v_lshlrev_b32_e32 v1, 2, v148
	v_lshl_or_b32 v0, v148, 6, v152
	v_and_b32_e32 v1, 32, v1
	v_bitop3_b32 v0, v0, s4, v1 bitop3:0xde
	s_waitcnt vmcnt(6)
	v_add_u16_e32 v1, v150, v151
	v_lshrrev_b16_e32 v1, 1, v1
	s_add_i32 s63, 0, 0x10000
	v_add_u32_e32 v159, 0, v0
	s_add_i32 s64, 0, 0x14000
	v_mbcnt_lo_u32_b32 v0, -1, 0
	v_add_lshl_u32 v136, v8, v1, 1
	v_mov_b32_e32 v137, v131
	v_add_lshl_u32 v138, v9, v1, 1
	v_mov_b32_e32 v139, v131
	v_mov_b64_e32 v[140:141], 0x400
	v_mov_b64_e32 v[142:143], 0x3ff
	v_add_u32_e32 v158, s63, v157
	v_add_u32_e32 v161, s64, v157
	v_mbcnt_hi_u32_b32 v162, -1, v0
	s_mov_b32 s65, 0
	s_barrier
	s_branch .LBB0_286

;     DI size_t aoff(const Unit& u, size_t tstep) const { return (size_t)u.pm * tstep; }
;     DI size_t boff(const Unit& u, size_t tstep) const { return (size_t)u.pn * tstep; }
;     DI size_t aoff(const Unit& u, size_t) const { return (size_t)u.ks * kbytes; }
; template <class Epi, class Sched>
; DI void gemm_phase(LAS unsigned char* lds, const Gemm g, const Sched& S, const Epi& E) {
;     ...
;         const bool has_next = S.next(ui + 1, nxt);
;         const char* nA = has_next ? (const char*)g.A + S.aoff(nxt, tstep) : cA; const char* nB = has_next ? (const char*)g.Bt + S.boff(nxt, tstep) : cB;
;         for (int t = 0; t < nt; t += 2) {
;             if constexpr (Epi::HAS_MID) { if (t == E.mid_t(nt)) { int fr3 = fr, fq3 = fq; asm volatile("" : "+v"(fr3), "+v"(fq3)); E.mid(acc, cur, wr, wc, fr3, fq3); } }
;             const bool last = (t == nt - 2);
;             const char* a1 = cA + (size_t)(t + 1) * kstep;
;             const char* a2 = last ? nA : cA + (size_t)(t + 2) * kstep; const char* b2 = last ? nB : cB + (size_t)(t + 2) * kstep;
;             const char* a3 = a2 + kstep; const char* b3 = b2 + kstep;
;             PG8_LDB(B0, 0, 0); PG8_SCHED; PG8_LDA(At, 0, 0); PG8_STAGE(PG8_SA(1, 1), a1 + hstep, voffA);
;             PG8_WAIT_L(8); PG8_BAR; PG8_WAIT_L(0); PG8_MMA(0, 0, At, B0); PG8_BAR; PG8_SCHED;
;             PG8_LDB(B1, 0, 1); PG8_STAGE(PG8_SB(0, 0), b2, voffB);
;             PG8_BAR; PG8_WAIT_L(0); PG8_MMA(0, 1, At, B1); PG8_BAR;
;             PG8_LDA(At, 0, 1); PG8_STAGE(PG8_SA(0, 0), a2, voffA);
;             PG8_BAR; PG8_WAIT_L(0); PG8_MMA(1, 0, At, B0); PG8_BAR; PG8_SCHED;
;             PG8_STAGE(PG8_SB(0, 1), b2 + hstep, voffB);
;             PG8_WAIT_V(6); PG8_BAR; PG8_MMA(1, 1, At, B1); PG8_BAR;
;             PG8_LDB(B0, 1, 0); PG8_SCHED; PG8_LDA(At, 1, 0); PG8_STAGE(PG8_SA(0, 1), a2 + hstep, voffA);
;             PG8_WAIT_L(8); PG8_BAR; PG8_WAIT_L(0); PG8_MMA(0, 0, At, B0); PG8_BAR; PG8_SCHED;
;             PG8_LDB(B1, 1, 1); PG8_STAGE(PG8_SB(1, 0), b3, voffB);
;             PG8_BAR; PG8_WAIT_L(0); PG8_MMA(0, 1, At, B1); PG8_BAR;
;             PG8_LDA(At, 1, 1); PG8_STAGE(PG8_SA(1, 0), a3, voffA);
;             PG8_BAR; PG8_WAIT_L(0); PG8_MMA(1, 0, At, B0); PG8_BAR; PG8_SCHED;
;             PG8_STAGE(PG8_SB(1, 1), b3 + hstep, voffB);
;             PG8_WAIT_V(6); PG8_BAR; PG8_MMA(1, 1, At, B1); PG8_BAR;
.LBB0_296:
	s_add_u32 s40, s40, 0x160080
	s_addc_u32 s41, s41, 0
	s_add_u32 s35, s42, 0x100
	v_mov_b32_e32 v0, 0
	s_addc_u32 s68, s43, 0
	s_mov_b32 s69, -2
	s_waitcnt lgkmcnt(0)
	ds_read_b128 v[144:147], v158
	ds_read_b128 v[164:167], v158 offset:1024
	ds_read_b128 v[168:171], v158 offset:2048
	ds_read_b128 v[172:175], v158 offset:3072
	s_add_u32 s0, s40, 0xffea0080
	s_addc_u32 s1, s41, -1
	s_cmpk_eq_i32 s69, 0x54
	s_cselect_b32 s45, s9, s1
	s_cselect_b32 s44, s8, s0
	s_cselect_b32 s43, s11, s68
	s_cselect_b32 s42, s10, s35
	s_add_i32 m0, s54, 0xc000
	ds_read_b128 v[176:179], v159
	ds_read_b128 v[180:183], v159 offset:1024
	ds_read_b128 v[188:191], v159 offset:2048
	ds_read_b128 v[194:197], v159 offset:3072
	ds_read_b128 v[198:201], v159 offset:4096
	ds_read_b128 v[202:205], v159 offset:5120
	ds_read_b128 v[206:209], v159 offset:6144
	ds_read_b128 v[210:213], v159 offset:7168
	global_load_lds_dwordx4 v136, s[40:41]
	s_add_i32 m0, s54, 0xe000
	s_nop 0
	global_load_lds_dwordx4 v138, s[40:41]
	s_waitcnt lgkmcnt(8)
	s_barrier
	s_waitcnt lgkmcnt(0)
	s_setprio 1
	s_waitcnt lgkmcnt(0)
	v_mfma_f32_16x16x32_bf16 v[124:127], v[144:147], v[176:179], 0
	v_mfma_f32_16x16x32_bf16 v[120:123], v[168:171], v[176:179], 0
	v_mfma_f32_16x16x32_bf16 v[108:111], v[144:147], v[188:191], 0
	v_mfma_f32_16x16x32_bf16 v[104:107], v[168:171], v[188:191], 0
	v_mfma_f32_16x16x32_bf16 v[92:95], v[144:147], v[198:201], 0
	v_mfma_f32_16x16x32_bf16 v[88:91], v[168:171], v[198:201], 0
	v_mfma_f32_16x16x32_bf16 v[76:79], v[144:147], v[206:209], 0
	v_mfma_f32_16x16x32_bf16 v[72:75], v[168:171], v[206:209], 0
	v_mfma_f32_16x16x32_bf16 v[124:127], v[164:167], v[180:183], v[124:127]
	v_mfma_f32_16x16x32_bf16 v[120:123], v[172:175], v[180:183], v[120:123]
	v_mfma_f32_16x16x32_bf16 v[108:111], v[164:167], v[194:197], v[108:111]
	v_mfma_f32_16x16x32_bf16 v[104:107], v[172:175], v[194:197], v[104:107]
	v_mfma_f32_16x16x32_bf16 v[92:95], v[164:167], v[202:205], v[92:95]
	v_mfma_f32_16x16x32_bf16 v[88:91], v[172:175], v[202:205], v[88:91]
	v_mfma_f32_16x16x32_bf16 v[76:79], v[164:167], v[210:213], v[76:79]
	v_mfma_f32_16x16x32_bf16 v[72:75], v[172:175], v[210:213], v[72:75]
	s_setprio 0
	s_barrier
	s_add_i32 s0, s63, s53
	s_mov_b32 m0, s0
	ds_read_b128 v[214:217], v161
	ds_read_b128 v[218:221], v161 offset:1024
	ds_read_b128 v[222:225], v161 offset:2048
	ds_read_b128 v[226:229], v161 offset:3072
	global_load_lds_dwordx4 v130, s[42:43]
	s_add_i32 m0, s0, 0x2000
	s_nop 0
	global_load_lds_dwordx4 v134, s[42:43]
	s_barrier
	s_waitcnt lgkmcnt(0)
	s_setprio 1
	s_waitcnt lgkmcnt(0)
	v_mfma_f32_16x16x32_bf16 v[116:119], v[214:217], v[176:179], 0
	v_mfma_f32_16x16x32_bf16 v[112:115], v[222:225], v[176:179], 0
	v_mfma_f32_16x16x32_bf16 v[100:103], v[214:217], v[188:191], 0
	v_mfma_f32_16x16x32_bf16 v[96:99], v[222:225], v[188:191], 0
	v_mfma_f32_16x16x32_bf16 v[84:87], v[214:217], v[198:201], 0
	v_mfma_f32_16x16x32_bf16 v[80:83], v[222:225], v[198:201], 0
	v_mfma_f32_16x16x32_bf16 v[68:71], v[214:217], v[206:209], 0
	v_mfma_f32_16x16x32_bf16 v[64:67], v[222:225], v[206:209], 0
	v_mfma_f32_16x16x32_bf16 v[116:119], v[218:221], v[180:183], v[116:119]
	v_mfma_f32_16x16x32_bf16 v[112:115], v[226:229], v[180:183], v[112:115]
	v_mfma_f32_16x16x32_bf16 v[100:103], v[218:221], v[194:197], v[100:103]
	v_mfma_f32_16x16x32_bf16 v[96:99], v[226:229], v[194:197], v[96:99]
	v_mfma_f32_16x16x32_bf16 v[84:87], v[218:221], v[202:205], v[84:87]
	v_mfma_f32_16x16x32_bf16 v[80:83], v[226:229], v[202:205], v[80:83]
	v_mfma_f32_16x16x32_bf16 v[68:71], v[218:221], v[210:213], v[68:71]
	v_mfma_f32_16x16x32_bf16 v[64:67], v[226:229], v[210:213], v[64:67]
	s_setprio 0
	s_mov_b32 m0, s54
	s_barrier
	ds_read_b128 v[176:179], v159 offset:16384
	ds_read_b128 v[180:183], v159 offset:17408
	ds_read_b128 v[188:191], v159 offset:18432
	ds_read_b128 v[194:197], v159 offset:19456
	ds_read_b128 v[198:201], v159 offset:20480
	ds_read_b128 v[202:205], v159 offset:21504
	ds_read_b128 v[206:209], v159 offset:22528
	ds_read_b128 v[210:213], v159 offset:23552
	global_load_lds_dwordx4 v128, s[44:45]
	s_mov_b32 m0, s55
	s_nop 0
	global_load_lds_dwordx4 v132, s[44:45]
	s_barrier
	s_waitcnt lgkmcnt(0)
	s_setprio 1
	s_waitcnt lgkmcnt(0)
	v_mfma_f32_16x16x32_bf16 v[60:63], v[144:147], v[176:179], 0
	v_mfma_f32_16x16x32_bf16 v[56:59], v[168:171], v[176:179], 0
	v_mfma_f32_16x16x32_bf16 v[44:47], v[144:147], v[188:191], 0
	v_mfma_f32_16x16x32_bf16 v[40:43], v[168:171], v[188:191], 0
	v_mfma_f32_16x16x32_bf16 v[28:31], v[144:147], v[198:201], 0
	v_mfma_f32_16x16x32_bf16 v[24:27], v[168:171], v[198:201], 0
	v_mfma_f32_16x16x32_bf16 v[12:15], v[144:147], v[206:209], 0
	v_mfma_f32_16x16x32_bf16 v[8:11], v[168:171], v[206:209], 0
	v_mfma_f32_16x16x32_bf16 v[60:63], v[164:167], v[180:183], v[60:63]
	v_mfma_f32_16x16x32_bf16 v[56:59], v[172:175], v[180:183], v[56:59]
	v_mfma_f32_16x16x32_bf16 v[44:47], v[164:167], v[194:197], v[44:47]
	v_mfma_f32_16x16x32_bf16 v[40:43], v[172:175], v[194:197], v[40:43]
	v_mfma_f32_16x16x32_bf16 v[28:31], v[164:167], v[202:205], v[28:31]
	v_mfma_f32_16x16x32_bf16 v[24:27], v[172:175], v[202:205], v[24:27]
	v_mfma_f32_16x16x32_bf16 v[12:15], v[164:167], v[210:213], v[12:15]
	v_mfma_f32_16x16x32_bf16 v[8:11], v[172:175], v[210:213], v[8:11]
	s_setprio 0
	s_barrier
	s_add_u32 s0, s42, 0x160000
	s_addc_u32 s1, s43, 0
	s_add_i32 s4, s64, s53
	s_mov_b32 m0, s4
	s_nop 0
	global_load_lds_dwordx4 v130, s[0:1]
	s_add_i32 m0, s4, 0x2000
	s_nop 0
	global_load_lds_dwordx4 v134, s[0:1]
	s_waitcnt vmcnt(6)
	s_barrier
; #define PG8_STAGE(bufoff, gbase, voff) do { _Pragma("unroll") for (int _i = 0; _i < 2; ++_i) \
;         __builtin_amdgcn_global_load_lds((const unsigned*)((const char*)(gbase) + (voff)[_i]), (LAS unsigned*)(lds + (bufoff) + ldsw + _i * 8192), 16, 0, 0); } while (0)
; #define PG8_LDA(dst, b, h) do { _Pragma("unroll") for (int m = 0; m < 4; ++m) _Pragma("unroll") for (int k = 0; k < 2; ++k) dst[m][k] = *(const LAS bf16x8*)(lds + PG8_SA(b, h) + aoff + m * 2048 + k * 1024); } while (0)
; #define PG8_LDB(dst, b, h) do { _Pragma("unroll") for (int n = 0; n < 2; ++n) _Pragma("unroll") for (int k = 0; k < 2; ++k) dst[n][k] = *(const LAS bf16x8*)(lds + PG8_SB(b, h) + boff + n * 2048 + k * 1024); } while (0)
; #define PG8_WAIT_V(n) asm volatile("s_waitcnt vmcnt(" #n ")" ::: "memory")
; #define PG8_WAIT_L(n) asm volatile("s_waitcnt lgkmcnt(" #n ")" ::: "memory")
; #define PG8_BAR __builtin_amdgcn_s_barrier()
; #define PG8_SCHED __builtin_amdgcn_sched_barrier(0)
; template <class Epi, class Sched>
; DI void gemm_phase(LAS unsigned char* lds, const Gemm g, const Sched& S, const Epi& E) {
;     ...
;             PG8_LDB(B0, 0, 0); PG8_SCHED; PG8_LDA(At, 0, 0); PG8_STAGE(PG8_SA(1, 1), a1 + hstep, voffA);
;             PG8_WAIT_L(8); PG8_BAR; PG8_WAIT_L(0); PG8_MMA(0, 0, At, B0); PG8_BAR; PG8_SCHED;
;             PG8_LDB(B1, 0, 1); PG8_STAGE(PG8_SB(0, 0), b2, voffB);
;             PG8_BAR; PG8_WAIT_L(0); PG8_MMA(0, 1, At, B1); PG8_BAR;
;             PG8_LDA(At, 0, 1); PG8_STAGE(PG8_SA(0, 0), a2, voffA);
;             PG8_BAR; PG8_WAIT_L(0); PG8_MMA(1, 0, At, B0); PG8_BAR; PG8_SCHED;
;             PG8_STAGE(PG8_SB(0, 1), b2 + hstep, voffB);
;             PG8_WAIT_V(6); PG8_BAR; PG8_MMA(1, 1, At, B1); PG8_BAR;
;             PG8_LDB(B0, 1, 0); PG8_SCHED; PG8_LDA(At, 1, 0); PG8_STAGE(PG8_SA(0, 1), a2 + hstep, voffA);
;             PG8_WAIT_L(8); PG8_BAR; PG8_WAIT_L(0); PG8_MMA(0, 0, At, B0); PG8_BAR; PG8_SCHED;
;             PG8_LDB(B1, 1, 1); PG8_STAGE(PG8_SB(1, 0), b3, voffB);
;             PG8_BAR; PG8_WAIT_L(0); PG8_MMA(0, 1, At, B1); PG8_BAR;
;             PG8_LDA(At, 1, 1); PG8_STAGE(PG8_SA(1, 0), a3, voffA);
;             PG8_BAR; PG8_WAIT_L(0); PG8_MMA(1, 0, At, B0); PG8_BAR; PG8_SCHED;
;             PG8_STAGE(PG8_SB(1, 1), b3 + hstep, voffB);
;             PG8_WAIT_V(6); PG8_BAR; PG8_MMA(1, 1, At, B1); PG8_BAR;
	s_setprio 1
	v_mfma_f32_16x16x32_bf16 v[52:55], v[214:217], v[176:179], 0
	v_mfma_f32_16x16x32_bf16 v[48:51], v[222:225], v[176:179], 0
	v_mfma_f32_16x16x32_bf16 v[36:39], v[214:217], v[188:191], 0
	v_mfma_f32_16x16x32_bf16 v[32:35], v[222:225], v[188:191], 0
	v_mfma_f32_16x16x32_bf16 v[20:23], v[214:217], v[198:201], 0
	v_mfma_f32_16x16x32_bf16 v[16:19], v[222:225], v[198:201], 0
	v_mfma_f32_16x16x32_bf16 v[4:7], v[214:217], v[206:209], 0
	v_mfma_f32_16x16x32_bf16 v[0:3], v[222:225], v[206:209], 0
	v_mfma_f32_16x16x32_bf16 v[52:55], v[218:221], v[180:183], v[52:55]
	v_mfma_f32_16x16x32_bf16 v[48:51], v[226:229], v[180:183], v[48:51]
	v_mfma_f32_16x16x32_bf16 v[36:39], v[218:221], v[194:197], v[36:39]
	v_mfma_f32_16x16x32_bf16 v[32:35], v[226:229], v[194:197], v[32:35]
	v_mfma_f32_16x16x32_bf16 v[20:23], v[218:221], v[202:205], v[20:23]
	v_mfma_f32_16x16x32_bf16 v[16:19], v[226:229], v[202:205], v[16:19]
	v_mfma_f32_16x16x32_bf16 v[4:7], v[218:221], v[210:213], v[4:7]
	v_mfma_f32_16x16x32_bf16 v[0:3], v[226:229], v[210:213], v[0:3]
	s_setprio 0
	s_add_i32 s4, 0, 0x18000
	v_add_u32_e32 v163, s4, v157
	s_barrier
	ds_read_b128 v[144:147], v163
	ds_read_b128 v[164:167], v163 offset:1024
	ds_read_b128 v[168:171], v163 offset:2048
	ds_read_b128 v[172:175], v163 offset:3072
	s_add_u32 s0, s44, 0x160000
	s_addc_u32 s1, s45, 0
	s_mov_b32 m0, s56
	ds_read_b128 v[176:179], v159 offset:32768
	ds_read_b128 v[180:183], v159 offset:33792
	ds_read_b128 v[188:191], v159 offset:34816
	ds_read_b128 v[194:197], v159 offset:35840
	ds_read_b128 v[198:201], v159 offset:36864
	ds_read_b128 v[202:205], v159 offset:37888
	ds_read_b128 v[206:209], v159 offset:38912
	ds_read_b128 v[210:213], v159 offset:39936
	global_load_lds_dwordx4 v128, s[0:1]
	s_mov_b32 m0, s57
	s_nop 0
	global_load_lds_dwordx4 v132, s[0:1]
	s_waitcnt lgkmcnt(8)
	s_barrier
	s_waitcnt lgkmcnt(0)
	s_setprio 1
	s_waitcnt lgkmcnt(0)
	v_mfma_f32_16x16x32_bf16 v[124:127], v[144:147], v[176:179], v[124:127]
	v_mfma_f32_16x16x32_bf16 v[120:123], v[168:171], v[176:179], v[120:123]
	v_mfma_f32_16x16x32_bf16 v[108:111], v[144:147], v[188:191], v[108:111]
	v_mfma_f32_16x16x32_bf16 v[104:107], v[168:171], v[188:191], v[104:107]
	v_mfma_f32_16x16x32_bf16 v[92:95], v[144:147], v[198:201], v[92:95]
	v_mfma_f32_16x16x32_bf16 v[88:91], v[168:171], v[198:201], v[88:91]
	v_mfma_f32_16x16x32_bf16 v[76:79], v[144:147], v[206:209], v[76:79]
	v_mfma_f32_16x16x32_bf16 v[72:75], v[168:171], v[206:209], v[72:75]
	v_mfma_f32_16x16x32_bf16 v[124:127], v[164:167], v[180:183], v[124:127]
	v_mfma_f32_16x16x32_bf16 v[120:123], v[172:175], v[180:183], v[120:123]
	v_mfma_f32_16x16x32_bf16 v[108:111], v[164:167], v[194:197], v[108:111]
	v_mfma_f32_16x16x32_bf16 v[104:107], v[172:175], v[194:197], v[104:107]
	v_mfma_f32_16x16x32_bf16 v[92:95], v[164:167], v[202:205], v[92:95]
	v_mfma_f32_16x16x32_bf16 v[88:91], v[172:175], v[202:205], v[88:91]
	v_mfma_f32_16x16x32_bf16 v[76:79], v[164:167], v[210:213], v[76:79]
	v_mfma_f32_16x16x32_bf16 v[72:75], v[172:175], v[210:213], v[72:75]
	s_setprio 0
	s_barrier
	s_add_i32 s5, 0, 0x1c000
	s_add_i32 s0, s4, s53
	v_add_u32_e32 v163, s5, v157
	s_add_i32 m0, s0, 0xffffff80
	ds_read_b128 v[214:217], v163
	ds_read_b128 v[218:221], v163 offset:1024
	ds_read_b128 v[222:225], v163 offset:2048
	ds_read_b128 v[226:229], v163 offset:3072
	global_load_lds_dwordx4 v130, s[42:43] offset:128
	s_add_i32 m0, s0, 0x1f80
	s_nop 0
	global_load_lds_dwordx4 v134, s[42:43] offset:128
	s_barrier
	s_waitcnt lgkmcnt(0)
	s_setprio 1
	s_waitcnt lgkmcnt(0)
	v_mfma_f32_16x16x32_bf16 v[116:119], v[214:217], v[176:179], v[116:119]
	v_mfma_f32_16x16x32_bf16 v[112:115], v[222:225], v[176:179], v[112:115]
	v_mfma_f32_16x16x32_bf16 v[100:103], v[214:217], v[188:191], v[100:103]
	v_mfma_f32_16x16x32_bf16 v[96:99], v[222:225], v[188:191], v[96:99]
	v_mfma_f32_16x16x32_bf16 v[84:87], v[214:217], v[198:201], v[84:87]
	v_mfma_f32_16x16x32_bf16 v[80:83], v[222:225], v[198:201], v[80:83]
	v_mfma_f32_16x16x32_bf16 v[68:71], v[214:217], v[206:209], v[68:71]
	v_mfma_f32_16x16x32_bf16 v[64:67], v[222:225], v[206:209], v[64:67]
	v_mfma_f32_16x16x32_bf16 v[116:119], v[218:221], v[180:183], v[116:119]
	v_mfma_f32_16x16x32_bf16 v[112:115], v[226:229], v[180:183], v[112:115]
	v_mfma_f32_16x16x32_bf16 v[100:103], v[218:221], v[194:197], v[100:103]
	v_mfma_f32_16x16x32_bf16 v[96:99], v[226:229], v[194:197], v[96:99]
	v_mfma_f32_16x16x32_bf16 v[84:87], v[218:221], v[202:205], v[84:87]
	v_mfma_f32_16x16x32_bf16 v[80:83], v[226:229], v[202:205], v[80:83]
	v_mfma_f32_16x16x32_bf16 v[68:71], v[218:221], v[210:213], v[68:71]
	v_mfma_f32_16x16x32_bf16 v[64:67], v[226:229], v[210:213], v[64:67]
	s_setprio 0
	s_add_i32 m0, s61, 0xffffff80
	s_barrier
	ds_read_b128 v[176:179], v159 offset:49152
	ds_read_b128 v[180:183], v159 offset:50176
	ds_read_b128 v[188:191], v159 offset:51200
	ds_read_b128 v[194:197], v159 offset:52224
	ds_read_b128 v[198:201], v159 offset:53248
	ds_read_b128 v[202:205], v159 offset:54272
	ds_read_b128 v[206:209], v159 offset:55296
	ds_read_b128 v[210:213], v159 offset:56320
	global_load_lds_dwordx4 v128, s[44:45] offset:128
	s_add_i32 m0, s62, 0xffffff80
	s_nop 0
	global_load_lds_dwordx4 v132, s[44:45] offset:128
	s_barrier
; #define PG8_STAGE(bufoff, gbase, voff) do { _Pragma("unroll") for (int _i = 0; _i < 2; ++_i) \
;         __builtin_amdgcn_global_load_lds((const unsigned*)((const char*)(gbase) + (voff)[_i]), (LAS unsigned*)(lds + (bufoff) + ldsw + _i * 8192), 16, 0, 0); } while (0)
; #define PG8_LDA(dst, b, h) do { _Pragma("unroll") for (int m = 0; m < 4; ++m) _Pragma("unroll") for (int k = 0; k < 2; ++k) dst[m][k] = *(const LAS bf16x8*)(lds + PG8_SA(b, h) + aoff + m * 2048 + k * 1024); } while (0)
; #define PG8_LDB(dst, b, h) do { _Pragma("unroll") for (int n = 0; n < 2; ++n) _Pragma("unroll") for (int k = 0; k < 2; ++k) dst[n][k] = *(const LAS bf16x8*)(lds + PG8_SB(b, h) + boff + n * 2048 + k * 1024); } while (0)
; #define PG8_WAIT_V(n) asm volatile("s_waitcnt vmcnt(" #n ")" ::: "memory")
; #define PG8_WAIT_L(n) asm volatile("s_waitcnt lgkmcnt(" #n ")" ::: "memory")
; #define PG8_BAR __builtin_amdgcn_s_barrier()
; #define PG8_SCHED __builtin_amdgcn_sched_barrier(0)
; template <class Epi, class Sched>
; DI void gemm_phase(LAS unsigned char* lds, const Gemm g, const Sched& S, const Epi& E) {
;     ...
;             PG8_LDB(B0, 0, 0); PG8_SCHED; PG8_LDA(At, 0, 0); PG8_STAGE(PG8_SA(1, 1), a1 + hstep, voffA);
;             PG8_WAIT_L(8); PG8_BAR; PG8_WAIT_L(0); PG8_MMA(0, 0, At, B0); PG8_BAR; PG8_SCHED;
;             PG8_LDB(B1, 0, 1); PG8_STAGE(PG8_SB(0, 0), b2, voffB);
;             PG8_BAR; PG8_WAIT_L(0); PG8_MMA(0, 1, At, B1); PG8_BAR;
;             PG8_LDA(At, 0, 1); PG8_STAGE(PG8_SA(0, 0), a2, voffA);
;             PG8_BAR; PG8_WAIT_L(0); PG8_MMA(1, 0, At, B0); PG8_BAR; PG8_SCHED;
;             PG8_STAGE(PG8_SB(0, 1), b2 + hstep, voffB);
;             PG8_WAIT_V(6); PG8_BAR; PG8_MMA(1, 1, At, B1); PG8_BAR;
;             PG8_LDB(B0, 1, 0); PG8_SCHED; PG8_LDA(At, 1, 0); PG8_STAGE(PG8_SA(0, 1), a2 + hstep, voffA);
;             PG8_WAIT_L(8); PG8_BAR; PG8_WAIT_L(0); PG8_MMA(0, 0, At, B0); PG8_BAR; PG8_SCHED;
;             PG8_LDB(B1, 1, 1); PG8_STAGE(PG8_SB(1, 0), b3, voffB);
;             PG8_BAR; PG8_WAIT_L(0); PG8_MMA(0, 1, At, B1); PG8_BAR;
;             PG8_LDA(At, 1, 1); PG8_STAGE(PG8_SA(1, 0), a3, voffA);
;             PG8_BAR; PG8_WAIT_L(0); PG8_MMA(1, 0, At, B0); PG8_BAR; PG8_SCHED;
;             PG8_STAGE(PG8_SB(1, 1), b3 + hstep, voffB);
;             PG8_WAIT_V(6); PG8_BAR; PG8_MMA(1, 1, At, B1); PG8_BAR;
	s_waitcnt lgkmcnt(0)
	s_setprio 1
	s_waitcnt lgkmcnt(0)
	v_mfma_f32_16x16x32_bf16 v[60:63], v[144:147], v[176:179], v[60:63]
	v_mfma_f32_16x16x32_bf16 v[56:59], v[168:171], v[176:179], v[56:59]
	v_mfma_f32_16x16x32_bf16 v[44:47], v[144:147], v[188:191], v[44:47]
	v_mfma_f32_16x16x32_bf16 v[40:43], v[168:171], v[188:191], v[40:43]
	v_mfma_f32_16x16x32_bf16 v[28:31], v[144:147], v[198:201], v[28:31]
	v_mfma_f32_16x16x32_bf16 v[24:27], v[168:171], v[198:201], v[24:27]
	v_mfma_f32_16x16x32_bf16 v[12:15], v[144:147], v[206:209], v[12:15]
	v_mfma_f32_16x16x32_bf16 v[8:11], v[168:171], v[206:209], v[8:11]
	v_mfma_f32_16x16x32_bf16 v[60:63], v[164:167], v[180:183], v[60:63]
	v_mfma_f32_16x16x32_bf16 v[56:59], v[172:175], v[180:183], v[56:59]
	v_mfma_f32_16x16x32_bf16 v[44:47], v[164:167], v[194:197], v[44:47]
	v_mfma_f32_16x16x32_bf16 v[40:43], v[172:175], v[194:197], v[40:43]
	v_mfma_f32_16x16x32_bf16 v[28:31], v[164:167], v[202:205], v[28:31]
	v_mfma_f32_16x16x32_bf16 v[24:27], v[172:175], v[202:205], v[24:27]
	v_mfma_f32_16x16x32_bf16 v[12:15], v[164:167], v[210:213], v[12:15]
	v_mfma_f32_16x16x32_bf16 v[8:11], v[172:175], v[210:213], v[8:11]
	s_setprio 0
	s_barrier
	s_add_u32 s0, s42, 0x160080
	s_addc_u32 s1, s43, 0
	s_add_i32 s4, s5, s53
	s_mov_b32 m0, s4
	s_nop 0
	global_load_lds_dwordx4 v130, s[0:1]
	s_add_i32 m0, s4, 0x2000
	s_nop 0
	global_load_lds_dwordx4 v134, s[0:1]
	s_waitcnt vmcnt(6)
	s_barrier
	s_setprio 1
	v_mfma_f32_16x16x32_bf16 v[52:55], v[214:217], v[176:179], v[52:55]
	v_mfma_f32_16x16x32_bf16 v[48:51], v[222:225], v[176:179], v[48:51]
	v_mfma_f32_16x16x32_bf16 v[36:39], v[214:217], v[188:191], v[36:39]
	v_mfma_f32_16x16x32_bf16 v[32:35], v[222:225], v[188:191], v[32:35]
	v_mfma_f32_16x16x32_bf16 v[20:23], v[214:217], v[198:201], v[20:23]
	v_mfma_f32_16x16x32_bf16 v[16:19], v[222:225], v[198:201], v[16:19]
	v_mfma_f32_16x16x32_bf16 v[4:7], v[214:217], v[206:209], v[4:7]
	v_mfma_f32_16x16x32_bf16 v[0:3], v[222:225], v[206:209], v[0:3]
	v_mfma_f32_16x16x32_bf16 v[52:55], v[218:221], v[180:183], v[52:55]
	v_mfma_f32_16x16x32_bf16 v[48:51], v[226:229], v[180:183], v[48:51]
	v_mfma_f32_16x16x32_bf16 v[36:39], v[218:221], v[194:197], v[36:39]
	v_mfma_f32_16x16x32_bf16 v[32:35], v[226:229], v[194:197], v[32:35]
	v_mfma_f32_16x16x32_bf16 v[20:23], v[218:221], v[202:205], v[20:23]
	v_mfma_f32_16x16x32_bf16 v[16:19], v[226:229], v[202:205], v[16:19]
	v_mfma_f32_16x16x32_bf16 v[4:7], v[218:221], v[210:213], v[4:7]
	v_mfma_f32_16x16x32_bf16 v[0:3], v[226:229], v[210:213], v[0:3]
	s_setprio 0
	s_add_i32 s69, s69, 2
	s_add_u32 s40, s40, 0x100
	s_addc_u32 s41, s41, 0
	s_add_u32 s35, s35, 0x100
	s_addc_u32 s68, s68, 0
	s_cmpk_gt_u32 s69, 0x55
	s_barrier
	s_cbranch_scc0 .LBB0_297
	s_branch .Lpeel_done_297
.LBB0_297:
	ds_read_b128 v[144:147], v158
	ds_read_b128 v[164:167], v158 offset:1024
	ds_read_b128 v[168:171], v158 offset:2048
	ds_read_b128 v[172:175], v158 offset:3072
	s_add_u32 s0, s40, 0xffea0080
	s_addc_u32 s1, s41, -1
	s_cmpk_eq_i32 s69, 0x54
	s_cselect_b32 s45, s9, s1
	s_cselect_b32 s44, s8, s0
	s_cselect_b32 s43, s11, s68
	s_cselect_b32 s42, s10, s35
	s_add_i32 m0, s54, 0xc000
	ds_read_b128 v[176:179], v159
	ds_read_b128 v[180:183], v159 offset:1024
	ds_read_b128 v[188:191], v159 offset:2048
	ds_read_b128 v[194:197], v159 offset:3072
	ds_read_b128 v[198:201], v159 offset:4096
	ds_read_b128 v[202:205], v159 offset:5120
	ds_read_b128 v[206:209], v159 offset:6144
	ds_read_b128 v[210:213], v159 offset:7168
	global_load_lds_dwordx4 v136, s[40:41]
	s_add_i32 m0, s54, 0xe000
	s_nop 0
	global_load_lds_dwordx4 v138, s[40:41]
	s_waitcnt lgkmcnt(8)
	s_barrier
	s_waitcnt lgkmcnt(0)
	s_setprio 1
	s_waitcnt lgkmcnt(0)
	v_mfma_f32_16x16x32_bf16 v[124:127], v[144:147], v[176:179], v[124:127]
	v_mfma_f32_16x16x32_bf16 v[120:123], v[168:171], v[176:179], v[120:123]
	v_mfma_f32_16x16x32_bf16 v[108:111], v[144:147], v[188:191], v[108:111]
	v_mfma_f32_16x16x32_bf16 v[104:107], v[168:171], v[188:191], v[104:107]
	v_mfma_f32_16x16x32_bf16 v[92:95], v[144:147], v[198:201], v[92:95]
	v_mfma_f32_16x16x32_bf16 v[88:91], v[168:171], v[198:201], v[88:91]
	v_mfma_f32_16x16x32_bf16 v[76:79], v[144:147], v[206:209], v[76:79]
	v_mfma_f32_16x16x32_bf16 v[72:75], v[168:171], v[206:209], v[72:75]
	v_mfma_f32_16x16x32_bf16 v[124:127], v[164:167], v[180:183], v[124:127]
	v_mfma_f32_16x16x32_bf16 v[120:123], v[172:175], v[180:183], v[120:123]
	v_mfma_f32_16x16x32_bf16 v[108:111], v[164:167], v[194:197], v[108:111]
	v_mfma_f32_16x16x32_bf16 v[104:107], v[172:175], v[194:197], v[104:107]
	v_mfma_f32_16x16x32_bf16 v[92:95], v[164:167], v[202:205], v[92:95]
	v_mfma_f32_16x16x32_bf16 v[88:91], v[172:175], v[202:205], v[88:91]
	v_mfma_f32_16x16x32_bf16 v[76:79], v[164:167], v[210:213], v[76:79]
	v_mfma_f32_16x16x32_bf16 v[72:75], v[172:175], v[210:213], v[72:75]
	s_setprio 0
	s_barrier
	s_add_i32 s0, s63, s53
	s_mov_b32 m0, s0
	ds_read_b128 v[214:217], v161
	ds_read_b128 v[218:221], v161 offset:1024
	ds_read_b128 v[222:225], v161 offset:2048
	ds_read_b128 v[226:229], v161 offset:3072
	global_load_lds_dwordx4 v130, s[42:43]
	s_add_i32 m0, s0, 0x2000
	s_nop 0
	global_load_lds_dwordx4 v134, s[42:43]
	s_barrier
; #define PG8_STAGE(bufoff, gbase, voff) do { _Pragma("unroll") for (int _i = 0; _i < 2; ++_i) \
;         __builtin_amdgcn_global_load_lds((const unsigned*)((const char*)(gbase) + (voff)[_i]), (LAS unsigned*)(lds + (bufoff) + ldsw + _i * 8192), 16, 0, 0); } while (0)
; #define PG8_LDA(dst, b, h) do { _Pragma("unroll") for (int m = 0; m < 4; ++m) _Pragma("unroll") for (int k = 0; k < 2; ++k) dst[m][k] = *(const LAS bf16x8*)(lds + PG8_SA(b, h) + aoff + m * 2048 + k * 1024); } while (0)
; #define PG8_LDB(dst, b, h) do { _Pragma("unroll") for (int n = 0; n < 2; ++n) _Pragma("unroll") for (int k = 0; k < 2; ++k) dst[n][k] = *(const LAS bf16x8*)(lds + PG8_SB(b, h) + boff + n * 2048 + k * 1024); } while (0)
; #define PG8_WAIT_V(n) asm volatile("s_waitcnt vmcnt(" #n ")" ::: "memory")
; #define PG8_WAIT_L(n) asm volatile("s_waitcnt lgkmcnt(" #n ")" ::: "memory")
; #define PG8_BAR __builtin_amdgcn_s_barrier()
; #define PG8_SCHED __builtin_amdgcn_sched_barrier(0)
; template <class Epi, class Sched>
; DI void gemm_phase(LAS unsigned char* lds, const Gemm g, const Sched& S, const Epi& E) {
;     ...
;             PG8_LDB(B0, 0, 0); PG8_SCHED; PG8_LDA(At, 0, 0); PG8_STAGE(PG8_SA(1, 1), a1 + hstep, voffA);
;             PG8_WAIT_L(8); PG8_BAR; PG8_WAIT_L(0); PG8_MMA(0, 0, At, B0); PG8_BAR; PG8_SCHED;
;             PG8_LDB(B1, 0, 1); PG8_STAGE(PG8_SB(0, 0), b2, voffB);
;             PG8_BAR; PG8_WAIT_L(0); PG8_MMA(0, 1, At, B1); PG8_BAR;
;             PG8_LDA(At, 0, 1); PG8_STAGE(PG8_SA(0, 0), a2, voffA);
;             PG8_BAR; PG8_WAIT_L(0); PG8_MMA(1, 0, At, B0); PG8_BAR; PG8_SCHED;
;             PG8_STAGE(PG8_SB(0, 1), b2 + hstep, voffB);
;             PG8_WAIT_V(6); PG8_BAR; PG8_MMA(1, 1, At, B1); PG8_BAR;
;             PG8_LDB(B0, 1, 0); PG8_SCHED; PG8_LDA(At, 1, 0); PG8_STAGE(PG8_SA(0, 1), a2 + hstep, voffA);
;             PG8_WAIT_L(8); PG8_BAR; PG8_WAIT_L(0); PG8_MMA(0, 0, At, B0); PG8_BAR; PG8_SCHED;
;             PG8_LDB(B1, 1, 1); PG8_STAGE(PG8_SB(1, 0), b3, voffB);
;             PG8_BAR; PG8_WAIT_L(0); PG8_MMA(0, 1, At, B1); PG8_BAR;
;             PG8_LDA(At, 1, 1); PG8_STAGE(PG8_SA(1, 0), a3, voffA);
;             PG8_BAR; PG8_WAIT_L(0); PG8_MMA(1, 0, At, B0); PG8_BAR; PG8_SCHED;
;             PG8_STAGE(PG8_SB(1, 1), b3 + hstep, voffB);
;             PG8_WAIT_V(6); PG8_BAR; PG8_MMA(1, 1, At, B1); PG8_BAR;
	s_waitcnt lgkmcnt(0)
	s_setprio 1
	s_waitcnt lgkmcnt(0)
	v_mfma_f32_16x16x32_bf16 v[116:119], v[214:217], v[176:179], v[116:119]
	v_mfma_f32_16x16x32_bf16 v[112:115], v[222:225], v[176:179], v[112:115]
	v_mfma_f32_16x16x32_bf16 v[100:103], v[214:217], v[188:191], v[100:103]
	v_mfma_f32_16x16x32_bf16 v[96:99], v[222:225], v[188:191], v[96:99]
	v_mfma_f32_16x16x32_bf16 v[84:87], v[214:217], v[198:201], v[84:87]
	v_mfma_f32_16x16x32_bf16 v[80:83], v[222:225], v[198:201], v[80:83]
	v_mfma_f32_16x16x32_bf16 v[68:71], v[214:217], v[206:209], v[68:71]
	v_mfma_f32_16x16x32_bf16 v[64:67], v[222:225], v[206:209], v[64:67]
	v_mfma_f32_16x16x32_bf16 v[116:119], v[218:221], v[180:183], v[116:119]
	v_mfma_f32_16x16x32_bf16 v[112:115], v[226:229], v[180:183], v[112:115]
	v_mfma_f32_16x16x32_bf16 v[100:103], v[218:221], v[194:197], v[100:103]
	v_mfma_f32_16x16x32_bf16 v[96:99], v[226:229], v[194:197], v[96:99]
	v_mfma_f32_16x16x32_bf16 v[84:87], v[218:221], v[202:205], v[84:87]
	v_mfma_f32_16x16x32_bf16 v[80:83], v[226:229], v[202:205], v[80:83]
	v_mfma_f32_16x16x32_bf16 v[68:71], v[218:221], v[210:213], v[68:71]
	v_mfma_f32_16x16x32_bf16 v[64:67], v[226:229], v[210:213], v[64:67]
	s_setprio 0
	s_mov_b32 m0, s54
	s_barrier
	ds_read_b128 v[176:179], v159 offset:16384
	ds_read_b128 v[180:183], v159 offset:17408
	ds_read_b128 v[188:191], v159 offset:18432
	ds_read_b128 v[194:197], v159 offset:19456
	ds_read_b128 v[198:201], v159 offset:20480
	ds_read_b128 v[202:205], v159 offset:21504
	ds_read_b128 v[206:209], v159 offset:22528
	ds_read_b128 v[210:213], v159 offset:23552
	global_load_lds_dwordx4 v128, s[44:45]
	s_mov_b32 m0, s55
	s_nop 0
	global_load_lds_dwordx4 v132, s[44:45]
	s_barrier
	s_waitcnt lgkmcnt(0)
	s_setprio 1
	s_waitcnt lgkmcnt(0)
	v_mfma_f32_16x16x32_bf16 v[60:63], v[144:147], v[176:179], v[60:63]
	v_mfma_f32_16x16x32_bf16 v[56:59], v[168:171], v[176:179], v[56:59]
	v_mfma_f32_16x16x32_bf16 v[44:47], v[144:147], v[188:191], v[44:47]
	v_mfma_f32_16x16x32_bf16 v[40:43], v[168:171], v[188:191], v[40:43]
	v_mfma_f32_16x16x32_bf16 v[28:31], v[144:147], v[198:201], v[28:31]
	v_mfma_f32_16x16x32_bf16 v[24:27], v[168:171], v[198:201], v[24:27]
	v_mfma_f32_16x16x32_bf16 v[12:15], v[144:147], v[206:209], v[12:15]
	v_mfma_f32_16x16x32_bf16 v[8:11], v[168:171], v[206:209], v[8:11]
	v_mfma_f32_16x16x32_bf16 v[60:63], v[164:167], v[180:183], v[60:63]
	v_mfma_f32_16x16x32_bf16 v[56:59], v[172:175], v[180:183], v[56:59]
	v_mfma_f32_16x16x32_bf16 v[44:47], v[164:167], v[194:197], v[44:47]
	v_mfma_f32_16x16x32_bf16 v[40:43], v[172:175], v[194:197], v[40:43]
	v_mfma_f32_16x16x32_bf16 v[28:31], v[164:167], v[202:205], v[28:31]
	v_mfma_f32_16x16x32_bf16 v[24:27], v[172:175], v[202:205], v[24:27]
	v_mfma_f32_16x16x32_bf16 v[12:15], v[164:167], v[210:213], v[12:15]
	v_mfma_f32_16x16x32_bf16 v[8:11], v[172:175], v[210:213], v[8:11]
	s_setprio 0
	s_barrier
	s_add_u32 s0, s42, 0x160000
	s_addc_u32 s1, s43, 0
	s_add_i32 s4, s64, s53
	s_mov_b32 m0, s4
	s_nop 0
	global_load_lds_dwordx4 v130, s[0:1]
	s_add_i32 m0, s4, 0x2000
	s_nop 0
	global_load_lds_dwordx4 v134, s[0:1]
	s_waitcnt vmcnt(6)
	s_barrier
	s_setprio 1
	v_mfma_f32_16x16x32_bf16 v[52:55], v[214:217], v[176:179], v[52:55]
	v_mfma_f32_16x16x32_bf16 v[48:51], v[222:225], v[176:179], v[48:51]
	v_mfma_f32_16x16x32_bf16 v[36:39], v[214:217], v[188:191], v[36:39]
	v_mfma_f32_16x16x32_bf16 v[32:35], v[222:225], v[188:191], v[32:35]
	v_mfma_f32_16x16x32_bf16 v[20:23], v[214:217], v[198:201], v[20:23]
	v_mfma_f32_16x16x32_bf16 v[16:19], v[222:225], v[198:201], v[16:19]
	v_mfma_f32_16x16x32_bf16 v[4:7], v[214:217], v[206:209], v[4:7]
	v_mfma_f32_16x16x32_bf16 v[0:3], v[222:225], v[206:209], v[0:3]
	v_mfma_f32_16x16x32_bf16 v[52:55], v[218:221], v[180:183], v[52:55]
	v_mfma_f32_16x16x32_bf16 v[48:51], v[226:229], v[180:183], v[48:51]
	v_mfma_f32_16x16x32_bf16 v[36:39], v[218:221], v[194:197], v[36:39]
	v_mfma_f32_16x16x32_bf16 v[32:35], v[226:229], v[194:197], v[32:35]
	v_mfma_f32_16x16x32_bf16 v[20:23], v[218:221], v[202:205], v[20:23]
	v_mfma_f32_16x16x32_bf16 v[16:19], v[226:229], v[202:205], v[16:19]
	v_mfma_f32_16x16x32_bf16 v[4:7], v[218:221], v[210:213], v[4:7]
	v_mfma_f32_16x16x32_bf16 v[0:3], v[226:229], v[210:213], v[0:3]
	s_setprio 0
	s_add_i32 s4, 0, 0x18000
	v_add_u32_e32 v163, s4, v157
	s_barrier
	ds_read_b128 v[144:147], v163
	ds_read_b128 v[164:167], v163 offset:1024
	ds_read_b128 v[168:171], v163 offset:2048
	ds_read_b128 v[172:175], v163 offset:3072
	s_add_u32 s0, s44, 0x160000
	s_addc_u32 s1, s45, 0
	s_mov_b32 m0, s56
	ds_read_b128 v[176:179], v159 offset:32768
	ds_read_b128 v[180:183], v159 offset:33792
	ds_read_b128 v[188:191], v159 offset:34816
	ds_read_b128 v[194:197], v159 offset:35840
	ds_read_b128 v[198:201], v159 offset:36864
	ds_read_b128 v[202:205], v159 offset:37888
	ds_read_b128 v[206:209], v159 offset:38912
	ds_read_b128 v[210:213], v159 offset:39936
	global_load_lds_dwordx4 v128, s[0:1]
	s_mov_b32 m0, s57
	s_nop 0
	global_load_lds_dwordx4 v132, s[0:1]
	s_waitcnt lgkmcnt(8)
	s_barrier
; #define PG8_STAGE(bufoff, gbase, voff) do { _Pragma("unroll") for (int _i = 0; _i < 2; ++_i) \
;         __builtin_amdgcn_global_load_lds((const unsigned*)((const char*)(gbase) + (voff)[_i]), (LAS unsigned*)(lds + (bufoff) + ldsw + _i * 8192), 16, 0, 0); } while (0)
; #define PG8_LDA(dst, b, h) do { _Pragma("unroll") for (int m = 0; m < 4; ++m) _Pragma("unroll") for (int k = 0; k < 2; ++k) dst[m][k] = *(const LAS bf16x8*)(lds + PG8_SA(b, h) + aoff + m * 2048 + k * 1024); } while (0)
; #define PG8_LDB(dst, b, h) do { _Pragma("unroll") for (int n = 0; n < 2; ++n) _Pragma("unroll") for (int k = 0; k < 2; ++k) dst[n][k] = *(const LAS bf16x8*)(lds + PG8_SB(b, h) + boff + n * 2048 + k * 1024); } while (0)
; #define PG8_WAIT_V(n) asm volatile("s_waitcnt vmcnt(" #n ")" ::: "memory")
; #define PG8_WAIT_L(n) asm volatile("s_waitcnt lgkmcnt(" #n ")" ::: "memory")
; #define PG8_BAR __builtin_amdgcn_s_barrier()
; #define PG8_SCHED __builtin_amdgcn_sched_barrier(0)
; template <class Epi, class Sched>
; DI void gemm_phase(LAS unsigned char* lds, const Gemm g, const Sched& S, const Epi& E) {
;     ...
;             PG8_LDB(B0, 0, 0); PG8_SCHED; PG8_LDA(At, 0, 0); PG8_STAGE(PG8_SA(1, 1), a1 + hstep, voffA);
;             PG8_WAIT_L(8); PG8_BAR; PG8_WAIT_L(0); PG8_MMA(0, 0, At, B0); PG8_BAR; PG8_SCHED;
;             PG8_LDB(B1, 0, 1); PG8_STAGE(PG8_SB(0, 0), b2, voffB);
;             PG8_BAR; PG8_WAIT_L(0); PG8_MMA(0, 1, At, B1); PG8_BAR;
;             PG8_LDA(At, 0, 1); PG8_STAGE(PG8_SA(0, 0), a2, voffA);
;             PG8_BAR; PG8_WAIT_L(0); PG8_MMA(1, 0, At, B0); PG8_BAR; PG8_SCHED;
;             PG8_STAGE(PG8_SB(0, 1), b2 + hstep, voffB);
;             PG8_WAIT_V(6); PG8_BAR; PG8_MMA(1, 1, At, B1); PG8_BAR;
;             PG8_LDB(B0, 1, 0); PG8_SCHED; PG8_LDA(At, 1, 0); PG8_STAGE(PG8_SA(0, 1), a2 + hstep, voffA);
;             PG8_WAIT_L(8); PG8_BAR; PG8_WAIT_L(0); PG8_MMA(0, 0, At, B0); PG8_BAR; PG8_SCHED;
;             PG8_LDB(B1, 1, 1); PG8_STAGE(PG8_SB(1, 0), b3, voffB);
;             PG8_BAR; PG8_WAIT_L(0); PG8_MMA(0, 1, At, B1); PG8_BAR;
;             PG8_LDA(At, 1, 1); PG8_STAGE(PG8_SA(1, 0), a3, voffA);
;             PG8_BAR; PG8_WAIT_L(0); PG8_MMA(1, 0, At, B0); PG8_BAR; PG8_SCHED;
;             PG8_STAGE(PG8_SB(1, 1), b3 + hstep, voffB);
;             PG8_WAIT_V(6); PG8_BAR; PG8_MMA(1, 1, At, B1); PG8_BAR;
	s_waitcnt lgkmcnt(0)
	s_setprio 1
	s_waitcnt lgkmcnt(0)
	v_mfma_f32_16x16x32_bf16 v[124:127], v[144:147], v[176:179], v[124:127]
	v_mfma_f32_16x16x32_bf16 v[120:123], v[168:171], v[176:179], v[120:123]
	v_mfma_f32_16x16x32_bf16 v[108:111], v[144:147], v[188:191], v[108:111]
	v_mfma_f32_16x16x32_bf16 v[104:107], v[168:171], v[188:191], v[104:107]
	v_mfma_f32_16x16x32_bf16 v[92:95], v[144:147], v[198:201], v[92:95]
	v_mfma_f32_16x16x32_bf16 v[88:91], v[168:171], v[198:201], v[88:91]
	v_mfma_f32_16x16x32_bf16 v[76:79], v[144:147], v[206:209], v[76:79]
	v_mfma_f32_16x16x32_bf16 v[72:75], v[168:171], v[206:209], v[72:75]
	v_mfma_f32_16x16x32_bf16 v[124:127], v[164:167], v[180:183], v[124:127]
	v_mfma_f32_16x16x32_bf16 v[120:123], v[172:175], v[180:183], v[120:123]
	v_mfma_f32_16x16x32_bf16 v[108:111], v[164:167], v[194:197], v[108:111]
	v_mfma_f32_16x16x32_bf16 v[104:107], v[172:175], v[194:197], v[104:107]
	v_mfma_f32_16x16x32_bf16 v[92:95], v[164:167], v[202:205], v[92:95]
	v_mfma_f32_16x16x32_bf16 v[88:91], v[172:175], v[202:205], v[88:91]
	v_mfma_f32_16x16x32_bf16 v[76:79], v[164:167], v[210:213], v[76:79]
	v_mfma_f32_16x16x32_bf16 v[72:75], v[172:175], v[210:213], v[72:75]
	s_setprio 0
	s_barrier
	s_add_i32 s5, 0, 0x1c000
	s_add_i32 s0, s4, s53
	v_add_u32_e32 v163, s5, v157
	s_add_i32 m0, s0, 0xffffff80
	ds_read_b128 v[214:217], v163
	ds_read_b128 v[218:221], v163 offset:1024
	ds_read_b128 v[222:225], v163 offset:2048
	ds_read_b128 v[226:229], v163 offset:3072
	global_load_lds_dwordx4 v130, s[42:43] offset:128
	s_add_i32 m0, s0, 0x1f80
	s_nop 0
	global_load_lds_dwordx4 v134, s[42:43] offset:128
	s_barrier
	s_waitcnt lgkmcnt(0)
	s_setprio 1
	s_waitcnt lgkmcnt(0)
	v_mfma_f32_16x16x32_bf16 v[116:119], v[214:217], v[176:179], v[116:119]
	v_mfma_f32_16x16x32_bf16 v[112:115], v[222:225], v[176:179], v[112:115]
	v_mfma_f32_16x16x32_bf16 v[100:103], v[214:217], v[188:191], v[100:103]
	v_mfma_f32_16x16x32_bf16 v[96:99], v[222:225], v[188:191], v[96:99]
	v_mfma_f32_16x16x32_bf16 v[84:87], v[214:217], v[198:201], v[84:87]
	v_mfma_f32_16x16x32_bf16 v[80:83], v[222:225], v[198:201], v[80:83]
	v_mfma_f32_16x16x32_bf16 v[68:71], v[214:217], v[206:209], v[68:71]
	v_mfma_f32_16x16x32_bf16 v[64:67], v[222:225], v[206:209], v[64:67]
	v_mfma_f32_16x16x32_bf16 v[116:119], v[218:221], v[180:183], v[116:119]
	v_mfma_f32_16x16x32_bf16 v[112:115], v[226:229], v[180:183], v[112:115]
	v_mfma_f32_16x16x32_bf16 v[100:103], v[218:221], v[194:197], v[100:103]
	v_mfma_f32_16x16x32_bf16 v[96:99], v[226:229], v[194:197], v[96:99]
	v_mfma_f32_16x16x32_bf16 v[84:87], v[218:221], v[202:205], v[84:87]
	v_mfma_f32_16x16x32_bf16 v[80:83], v[226:229], v[202:205], v[80:83]
	v_mfma_f32_16x16x32_bf16 v[68:71], v[218:221], v[210:213], v[68:71]
	v_mfma_f32_16x16x32_bf16 v[64:67], v[226:229], v[210:213], v[64:67]
	s_setprio 0
	s_add_i32 m0, s61, 0xffffff80
	s_barrier
	ds_read_b128 v[176:179], v159 offset:49152
	ds_read_b128 v[180:183], v159 offset:50176
	ds_read_b128 v[188:191], v159 offset:51200
	ds_read_b128 v[194:197], v159 offset:52224
	ds_read_b128 v[198:201], v159 offset:53248
	ds_read_b128 v[202:205], v159 offset:54272
	ds_read_b128 v[206:209], v159 offset:55296
	ds_read_b128 v[210:213], v159 offset:56320
	global_load_lds_dwordx4 v128, s[44:45] offset:128
	s_add_i32 m0, s62, 0xffffff80
	s_nop 0
	global_load_lds_dwordx4 v132, s[44:45] offset:128
	s_barrier
	s_waitcnt lgkmcnt(0)
	s_setprio 1
	s_waitcnt lgkmcnt(0)
	v_mfma_f32_16x16x32_bf16 v[60:63], v[144:147], v[176:179], v[60:63]
	v_mfma_f32_16x16x32_bf16 v[56:59], v[168:171], v[176:179], v[56:59]
	v_mfma_f32_16x16x32_bf16 v[44:47], v[144:147], v[188:191], v[44:47]
	v_mfma_f32_16x16x32_bf16 v[40:43], v[168:171], v[188:191], v[40:43]
	v_mfma_f32_16x16x32_bf16 v[28:31], v[144:147], v[198:201], v[28:31]
	v_mfma_f32_16x16x32_bf16 v[24:27], v[168:171], v[198:201], v[24:27]
	v_mfma_f32_16x16x32_bf16 v[12:15], v[144:147], v[206:209], v[12:15]
	v_mfma_f32_16x16x32_bf16 v[8:11], v[168:171], v[206:209], v[8:11]
	v_mfma_f32_16x16x32_bf16 v[60:63], v[164:167], v[180:183], v[60:63]
	v_mfma_f32_16x16x32_bf16 v[56:59], v[172:175], v[180:183], v[56:59]
	v_mfma_f32_16x16x32_bf16 v[44:47], v[164:167], v[194:197], v[44:47]
	v_mfma_f32_16x16x32_bf16 v[40:43], v[172:175], v[194:197], v[40:43]
	v_mfma_f32_16x16x32_bf16 v[28:31], v[164:167], v[202:205], v[28:31]
	v_mfma_f32_16x16x32_bf16 v[24:27], v[172:175], v[202:205], v[24:27]
	v_mfma_f32_16x16x32_bf16 v[12:15], v[164:167], v[210:213], v[12:15]
	v_mfma_f32_16x16x32_bf16 v[8:11], v[172:175], v[210:213], v[8:11]
	s_setprio 0
	s_barrier
	s_add_u32 s0, s42, 0x160080
	s_addc_u32 s1, s43, 0
	s_add_i32 s4, s5, s53
	s_mov_b32 m0, s4
	s_nop 0
	global_load_lds_dwordx4 v130, s[0:1]
	s_add_i32 m0, s4, 0x2000
	s_nop 0
	global_load_lds_dwordx4 v134, s[0:1]
	s_waitcnt vmcnt(6)
	s_barrier
	s_setprio 1
	v_mfma_f32_16x16x32_bf16 v[52:55], v[214:217], v[176:179], v[52:55]
	v_mfma_f32_16x16x32_bf16 v[48:51], v[222:225], v[176:179], v[48:51]
	v_mfma_f32_16x16x32_bf16 v[36:39], v[214:217], v[188:191], v[36:39]
	v_mfma_f32_16x16x32_bf16 v[32:35], v[222:225], v[188:191], v[32:35]
	v_mfma_f32_16x16x32_bf16 v[20:23], v[214:217], v[198:201], v[20:23]
	v_mfma_f32_16x16x32_bf16 v[16:19], v[222:225], v[198:201], v[16:19]
	v_mfma_f32_16x16x32_bf16 v[4:7], v[214:217], v[206:209], v[4:7]
	v_mfma_f32_16x16x32_bf16 v[0:3], v[222:225], v[206:209], v[0:3]
	v_mfma_f32_16x16x32_bf16 v[52:55], v[218:221], v[180:183], v[52:55]
	v_mfma_f32_16x16x32_bf16 v[48:51], v[226:229], v[180:183], v[48:51]
	v_mfma_f32_16x16x32_bf16 v[36:39], v[218:221], v[194:197], v[36:39]
	v_mfma_f32_16x16x32_bf16 v[32:35], v[226:229], v[194:197], v[32:35]
	v_mfma_f32_16x16x32_bf16 v[20:23], v[218:221], v[202:205], v[20:23]
	v_mfma_f32_16x16x32_bf16 v[16:19], v[226:229], v[202:205], v[16:19]
	v_mfma_f32_16x16x32_bf16 v[4:7], v[218:221], v[210:213], v[4:7]
	v_mfma_f32_16x16x32_bf16 v[0:3], v[226:229], v[210:213], v[0:3]
	s_setprio 0
	s_add_i32 s69, s69, 2
	s_add_u32 s40, s40, 0x100
	s_addc_u32 s41, s41, 0
	s_add_u32 s35, s35, 0x100
	s_addc_u32 s68, s68, 0
	s_cmpk_gt_u32 s69, 0x55
	s_barrier
	s_cbranch_scc0 .LBB0_297

;     DI size_t aoff(const Unit& u, size_t tstep) const { return (size_t)u.pm * tstep; }
;     DI size_t boff(const Unit& u, size_t tstep) const { return (size_t)u.pn * tstep; }
;     DI size_t aoff(const Unit& u, size_t) const { return (size_t)u.ks * kbytes; }
;     DI size_t boff(const Unit& u, size_t tstep) const { return (size_t)u.pn * tstep + (size_t)u.ks * kbytes; }
;     DI size_t aoff(const Unit& u, size_t tstep) const { return (u.ks < 2 ? offU : offOA) + (size_t)u.pm * tstep; }
; #define PG8_STAGE(bufoff, gbase, voff) do { _Pragma("unroll") for (int _i = 0; _i < 2; ++_i) \
;         __builtin_amdgcn_global_load_lds((const unsigned*)((const char*)(gbase) + (voff)[_i]), (LAS unsigned*)(lds + (bufoff) + ldsw + _i * 8192), 16, 0, 0); } while (0)
; #define PG8_WAIT_V(n) asm volatile("s_waitcnt vmcnt(" #n ")" ::: "memory")
; #define PG8_BAR __builtin_amdgcn_s_barrier()
; template <class Epi, class Sched>
; DI void gemm_phase(LAS unsigned char* lds, const Gemm g, const Sched& S, const Epi& E) {
;     ...
;     const char* cA = (const char*)g.A + S.aoff(cur, tstep); const char* cB = (const char*)g.Bt + S.boff(cur, tstep);
;     PG8_STAGE(PG8_SB(0, 0), cB, voffB); PG8_STAGE(PG8_SA(0, 0), cA, voffA); PG8_STAGE(PG8_SB(0, 1), cB + hstep, voffB); PG8_STAGE(PG8_SA(0, 1), cA + hstep, voffA);
;     if (wr == 1) PG8_BAR;
;     PG8_WAIT_V(4); PG8_BAR;
;     PG8_STAGE(PG8_SB(1, 0), cB + kstep, voffB); PG8_STAGE(PG8_SA(1, 0), cA + kstep, voffA); PG8_STAGE(PG8_SB(1, 1), cB + hstep + kstep, voffB);
;     PG8_WAIT_V(6); PG8_BAR;
.LBB0_320:
	s_lshl_b32 s0, s0, 5
	s_lshl_b32 s52, s1, 6
	s_lshl_b32 s4, s1, 13
	s_and_b32 s53, s0, 0x60
	s_add_u32 s54, s22, 0x3c40b000
	s_addc_u32 s55, s23, 0
	s_mov_b64 s[10:11], 0x80
	s_add_u32 s0, s36, 0x160080
	v_lshl_add_u64 v[0:1], v[0:1], 0, s[10:11]
	s_addc_u32 s1, s37, 0
	s_add_i32 m0, s42, 0x18000
	v_lshl_add_u64 v[2:3], v[2:3], 0, s[10:11]
	s_waitcnt vmcnt(4)
	s_barrier
	global_load_lds_dwordx4 v[0:1], off
	s_add_i32 m0, s42, 0x1a000
	s_add_i32 s56, s42, 0x8000
	v_lshl_add_u64 v[4:5], v[4:5], 0, s[10:11]
	global_load_lds_dwordx4 v[2:3], off
	s_mov_b32 m0, s56
	s_add_i32 s57, s42, 0xa000
	v_lshl_add_u64 v[6:7], v[6:7], 0, s[10:11]
	global_load_lds_dwordx4 v[4:5], off
	s_mov_b32 m0, s57
	s_nop 0
	global_load_lds_dwordx4 v[6:7], off
	s_add_i32 m0, s42, 0x1c000
	s_nop 0
	global_load_lds_dwordx4 v130, s[0:1]
	s_add_i32 m0, s42, 0x1e000
	v_lshlrev_b32_e32 v1, 2, v148
	global_load_lds_dwordx4 v128, s[0:1]
	v_lshl_or_b32 v0, v148, 6, v152
	v_and_b32_e32 v1, 32, v1
	v_lshl_or_b32 v140, s53, 7, v153
	s_waitcnt vmcnt(6)
	s_add_i32 s60, 0, 0x10000
	s_add_i32 s62, 0, 0x14000
	v_bitop3_b32 v0, v0, s4, v1 bitop3:0xde
	v_add_u32_e32 v141, s60, v140
	v_add_u32_e32 v143, s62, v140
	s_add_i32 s60, s60, s35
	s_add_i32 s62, s62, s35
	s_add_i32 s64, 0, 0x18000
	v_add3_u32 v132, v9, v150, v151
	v_mov_b32_e32 v133, v131
	v_add3_u32 v134, v8, v150, v151
	v_mov_b32_e32 v135, v131
	v_mov_b64_e32 v[136:137], 0x58
	v_mov_b64_e32 v[138:139], 0x57
	v_add_u32_e32 v142, 0, v0
	s_add_i32 s58, s42, 0xc000
	s_add_i32 s59, s42, 0xe000
	s_add_i32 s61, s60, 0x2000
	s_add_i32 s63, s62, 0x2000
	v_add_u32_e32 v144, s64, v140
	s_barrier

;     DI size_t aoff(const Unit& u, size_t tstep) const { return (size_t)u.pm * tstep; }
;     DI size_t boff(const Unit& u, size_t tstep) const { return (size_t)u.pn * tstep; }
;     DI bool next(int i, Unit& u) const { const long L = (long)i * G + c; if (L >= np) return false; u.pm = pmv; u.pn = (int)(L % nN); u.ks = (int)(L / nN); return true; }
;     DI size_t aoff(const Unit& u, size_t) const { return (size_t)u.ks * kbytes; }
;     DI size_t boff(const Unit& u, size_t tstep) const { return (size_t)u.pn * tstep + (size_t)u.ks * kbytes; }
;     DI bool next(int i, Unit& u) const { Unit t; if (!S.next(i / 3, t)) return false; u.pm = t.pm; u.pn = t.pn; u.ks = i % 3; return true; }
; template <class Epi, class Sched>
; DI void gemm_phase(LAS unsigned char* lds, const Gemm g, const Sched& S, const Epi& E) {
;     ...
;         const bool has_next = S.next(ui + 1, nxt);
;         const char* nA = has_next ? (const char*)g.A + S.aoff(nxt, tstep) : cA; const char* nB = has_next ? (const char*)g.Bt + S.boff(nxt, tstep) : cB;
;         for (int t = 0; t < nt; t += 2) {
;             if constexpr (Epi::HAS_MID) { if (t == E.mid_t(nt)) { int fr3 = fr, fq3 = fq; asm volatile("" : "+v"(fr3), "+v"(fq3)); E.mid(acc, cur, wr, wc, fr3, fq3); } }
;             const bool last = (t == nt - 2);
;             const char* a1 = cA + (size_t)(t + 1) * kstep;
;             const char* a2 = last ? nA : cA + (size_t)(t + 2) * kstep; const char* b2 = last ? nB : cB + (size_t)(t + 2) * kstep;
;             const char* a3 = a2 + kstep; const char* b3 = b2 + kstep;
;             PG8_LDB(B0, 0, 0); PG8_SCHED; PG8_LDA(At, 0, 0); PG8_STAGE(PG8_SA(1, 1), a1 + hstep, voffA);
;             PG8_WAIT_L(8); PG8_BAR; PG8_WAIT_L(0); PG8_MMA(0, 0, At, B0); PG8_BAR; PG8_SCHED;
;             PG8_LDB(B1, 0, 1); PG8_STAGE(PG8_SB(0, 0), b2, voffB);
;             PG8_BAR; PG8_WAIT_L(0); PG8_MMA(0, 1, At, B1); PG8_BAR;
;             PG8_LDA(At, 0, 1); PG8_STAGE(PG8_SA(0, 0), a2, voffA);
;             PG8_BAR; PG8_WAIT_L(0); PG8_MMA(1, 0, At, B0); PG8_BAR; PG8_SCHED;
;             PG8_STAGE(PG8_SB(0, 1), b2 + hstep, voffB);
;             PG8_WAIT_V(6); PG8_BAR; PG8_MMA(1, 1, At, B1); PG8_BAR;
;             PG8_LDB(B0, 1, 0); PG8_SCHED; PG8_LDA(At, 1, 0); PG8_STAGE(PG8_SA(0, 1), a2 + hstep, voffA);
;             PG8_WAIT_L(8); PG8_BAR; PG8_WAIT_L(0); PG8_MMA(0, 0, At, B0); PG8_BAR; PG8_SCHED;
.LBB0_325:
	s_add_u32 s28, s40, s28
	s_addc_u32 s29, s41, s29
	s_and_b64 s[0:1], s[8:9], exec
	s_cselect_b32 s15, s29, s39
	s_cselect_b32 s17, s28, s38
	s_add_u32 s8, s38, 0x160080
	s_addc_u32 s9, s39, 0
	s_add_u32 s66, s36, 0x100
	v_mov_b32_e32 v0, 0
	s_addc_u32 s67, s37, 0
	s_mov_b32 s68, -2
	ds_read_b128 v[150:153], v141
	ds_read_b128 v[154:157], v141 offset:1024
	ds_read_b128 v[162:165], v141 offset:2048
	ds_read_b128 v[166:169], v141 offset:3072
	s_add_u32 s0, s8, 0xffea0080
	s_addc_u32 s1, s9, -1
	s_cmp_eq_u32 s68, 4
	s_cselect_b32 s39, s15, s1
	s_cselect_b32 s38, s17, s0
	s_cselect_b32 s37, s19, s67
	s_cselect_b32 s36, s18, s66
	s_mov_b32 m0, s58
	ds_read_b128 v[170:173], v142
	ds_read_b128 v[174:177], v142 offset:1024
	ds_read_b128 v[178:181], v142 offset:2048
	ds_read_b128 v[188:191], v142 offset:3072
	ds_read_b128 v[194:197], v142 offset:4096
	ds_read_b128 v[198:201], v142 offset:5120
	ds_read_b128 v[202:205], v142 offset:6144
	ds_read_b128 v[206:209], v142 offset:7168
	global_load_lds_dwordx4 v132, s[8:9]
	s_mov_b32 m0, s59
	s_nop 0
	global_load_lds_dwordx4 v134, s[8:9]
	s_waitcnt lgkmcnt(8)
	s_barrier
	s_waitcnt lgkmcnt(0)
	s_setprio 1
	s_waitcnt lgkmcnt(0)
	v_mfma_f32_16x16x32_bf16 v[124:127], v[150:153], v[170:173], 0
	v_mfma_f32_16x16x32_bf16 v[120:123], v[162:165], v[170:173], 0
	v_mfma_f32_16x16x32_bf16 v[116:119], v[150:153], v[178:181], 0
	v_mfma_f32_16x16x32_bf16 v[112:115], v[162:165], v[178:181], 0
	v_mfma_f32_16x16x32_bf16 v[104:107], v[150:153], v[194:197], 0
	v_mfma_f32_16x16x32_bf16 v[96:99], v[162:165], v[194:197], 0
	v_mfma_f32_16x16x32_bf16 v[88:91], v[150:153], v[202:205], 0
	v_mfma_f32_16x16x32_bf16 v[80:83], v[162:165], v[202:205], 0
	v_mfma_f32_16x16x32_bf16 v[124:127], v[154:157], v[174:177], v[124:127]
	v_mfma_f32_16x16x32_bf16 v[120:123], v[166:169], v[174:177], v[120:123]
	v_mfma_f32_16x16x32_bf16 v[116:119], v[154:157], v[188:191], v[116:119]
	v_mfma_f32_16x16x32_bf16 v[112:115], v[166:169], v[188:191], v[112:115]
	v_mfma_f32_16x16x32_bf16 v[104:107], v[154:157], v[198:201], v[104:107]
	v_mfma_f32_16x16x32_bf16 v[96:99], v[166:169], v[198:201], v[96:99]
	v_mfma_f32_16x16x32_bf16 v[88:91], v[154:157], v[206:209], v[88:91]
	v_mfma_f32_16x16x32_bf16 v[80:83], v[166:169], v[206:209], v[80:83]
	s_setprio 0
	s_barrier
	s_mov_b32 m0, s60
	ds_read_b128 v[210:213], v143
	ds_read_b128 v[214:217], v143 offset:1024
	ds_read_b128 v[218:221], v143 offset:2048
	ds_read_b128 v[222:225], v143 offset:3072
	global_load_lds_dwordx4 v130, s[36:37]
	v_lshl_add_u64 v[158:159], s[36:37], 0, v[128:129]
	s_mov_b32 m0, s61
	s_nop 0
	global_load_lds_dwordx4 v128, s[36:37]
	s_barrier
	s_waitcnt lgkmcnt(0)
	s_setprio 1
	s_waitcnt lgkmcnt(0)
	v_mfma_f32_16x16x32_bf16 v[108:111], v[210:213], v[170:173], 0
	v_mfma_f32_16x16x32_bf16 v[100:103], v[218:221], v[170:173], 0
	v_mfma_f32_16x16x32_bf16 v[92:95], v[210:213], v[178:181], 0
	v_mfma_f32_16x16x32_bf16 v[84:87], v[218:221], v[178:181], 0
	v_mfma_f32_16x16x32_bf16 v[76:79], v[210:213], v[194:197], 0
	v_mfma_f32_16x16x32_bf16 v[72:75], v[218:221], v[194:197], 0
	v_mfma_f32_16x16x32_bf16 v[68:71], v[210:213], v[202:205], 0
	v_mfma_f32_16x16x32_bf16 v[64:67], v[218:221], v[202:205], 0
	v_mfma_f32_16x16x32_bf16 v[108:111], v[214:217], v[174:177], v[108:111]
	v_mfma_f32_16x16x32_bf16 v[100:103], v[222:225], v[174:177], v[100:103]
	v_mfma_f32_16x16x32_bf16 v[92:95], v[214:217], v[188:191], v[92:95]
	v_mfma_f32_16x16x32_bf16 v[84:87], v[222:225], v[188:191], v[84:87]
	v_mfma_f32_16x16x32_bf16 v[76:79], v[214:217], v[198:201], v[76:79]
	v_mfma_f32_16x16x32_bf16 v[72:75], v[222:225], v[198:201], v[72:75]
	v_mfma_f32_16x16x32_bf16 v[68:71], v[214:217], v[206:209], v[68:71]
	v_mfma_f32_16x16x32_bf16 v[64:67], v[222:225], v[206:209], v[64:67]
	s_setprio 0
	s_mov_b32 m0, s42
	v_lshl_add_u64 v[182:183], s[38:39], 0, v[130:131]
	s_barrier
	ds_read_b128 v[170:173], v142 offset:16384
	ds_read_b128 v[174:177], v142 offset:17408
	ds_read_b128 v[178:181], v142 offset:18432
	ds_read_b128 v[188:191], v142 offset:19456
	ds_read_b128 v[194:197], v142 offset:20480
	ds_read_b128 v[198:201], v142 offset:21504
	ds_read_b128 v[202:205], v142 offset:22528
	ds_read_b128 v[206:209], v142 offset:23552
	global_load_lds_dwordx4 v130, s[38:39]
	v_lshl_add_u64 v[226:227], s[38:39], 0, v[128:129]
	s_mov_b32 m0, s43
	s_nop 0
	global_load_lds_dwordx4 v128, s[38:39]
	s_barrier
	s_waitcnt lgkmcnt(0)
	s_setprio 1
	s_waitcnt lgkmcnt(0)
	v_mfma_f32_16x16x32_bf16 v[60:63], v[150:153], v[170:173], 0
	v_mfma_f32_16x16x32_bf16 v[56:59], v[162:165], v[170:173], 0
	v_mfma_f32_16x16x32_bf16 v[52:55], v[150:153], v[178:181], 0
	v_mfma_f32_16x16x32_bf16 v[48:51], v[162:165], v[178:181], 0
	v_mfma_f32_16x16x32_bf16 v[40:43], v[150:153], v[194:197], 0
	v_mfma_f32_16x16x32_bf16 v[32:35], v[162:165], v[194:197], 0
	v_mfma_f32_16x16x32_bf16 v[24:27], v[150:153], v[202:205], 0
	v_mfma_f32_16x16x32_bf16 v[16:19], v[162:165], v[202:205], 0
	v_mfma_f32_16x16x32_bf16 v[60:63], v[154:157], v[174:177], v[60:63]
	v_mfma_f32_16x16x32_bf16 v[56:59], v[166:169], v[174:177], v[56:59]
	v_mfma_f32_16x16x32_bf16 v[52:55], v[154:157], v[188:191], v[52:55]
	v_mfma_f32_16x16x32_bf16 v[48:51], v[166:169], v[188:191], v[48:51]
	v_mfma_f32_16x16x32_bf16 v[40:43], v[154:157], v[198:201], v[40:43]
	v_mfma_f32_16x16x32_bf16 v[32:35], v[166:169], v[198:201], v[32:35]
	v_mfma_f32_16x16x32_bf16 v[24:27], v[154:157], v[206:209], v[24:27]
	v_mfma_f32_16x16x32_bf16 v[16:19], v[166:169], v[206:209], v[16:19]
	s_setprio 0
	s_barrier
	s_add_u32 s0, s36, 0x160000
	s_addc_u32 s1, s37, 0
	s_mov_b32 m0, s62
	s_nop 0
	global_load_lds_dwordx4 v130, s[0:1]
	s_mov_b32 m0, s63
	s_nop 0
	global_load_lds_dwordx4 v128, s[0:1]
	s_waitcnt vmcnt(6)
	s_barrier
; #define PG8_STAGE(bufoff, gbase, voff) do { _Pragma("unroll") for (int _i = 0; _i < 2; ++_i) \
;         __builtin_amdgcn_global_load_lds((const unsigned*)((const char*)(gbase) + (voff)[_i]), (LAS unsigned*)(lds + (bufoff) + ldsw + _i * 8192), 16, 0, 0); } while (0)
; #define PG8_LDA(dst, b, h) do { _Pragma("unroll") for (int m = 0; m < 4; ++m) _Pragma("unroll") for (int k = 0; k < 2; ++k) dst[m][k] = *(const LAS bf16x8*)(lds + PG8_SA(b, h) + aoff + m * 2048 + k * 1024); } while (0)
; #define PG8_LDB(dst, b, h) do { _Pragma("unroll") for (int n = 0; n < 2; ++n) _Pragma("unroll") for (int k = 0; k < 2; ++k) dst[n][k] = *(const LAS bf16x8*)(lds + PG8_SB(b, h) + boff + n * 2048 + k * 1024); } while (0)
; #define PG8_WAIT_V(n) asm volatile("s_waitcnt vmcnt(" #n ")" ::: "memory")
; #define PG8_WAIT_L(n) asm volatile("s_waitcnt lgkmcnt(" #n ")" ::: "memory")
; #define PG8_BAR __builtin_amdgcn_s_barrier()
; #define PG8_SCHED __builtin_amdgcn_sched_barrier(0)
; template <class Epi, class Sched>
; DI void gemm_phase(LAS unsigned char* lds, const Gemm g, const Sched& S, const Epi& E) {
;     ...
;             PG8_LDB(B0, 0, 0); PG8_SCHED; PG8_LDA(At, 0, 0); PG8_STAGE(PG8_SA(1, 1), a1 + hstep, voffA);
;             PG8_WAIT_L(8); PG8_BAR; PG8_WAIT_L(0); PG8_MMA(0, 0, At, B0); PG8_BAR; PG8_SCHED;
;             PG8_LDB(B1, 0, 1); PG8_STAGE(PG8_SB(0, 0), b2, voffB);
;             PG8_BAR; PG8_WAIT_L(0); PG8_MMA(0, 1, At, B1); PG8_BAR;
;             PG8_LDA(At, 0, 1); PG8_STAGE(PG8_SA(0, 0), a2, voffA);
;             PG8_BAR; PG8_WAIT_L(0); PG8_MMA(1, 0, At, B0); PG8_BAR; PG8_SCHED;
;             PG8_STAGE(PG8_SB(0, 1), b2 + hstep, voffB);
;             PG8_WAIT_V(6); PG8_BAR; PG8_MMA(1, 1, At, B1); PG8_BAR;
;             PG8_LDB(B0, 1, 0); PG8_SCHED; PG8_LDA(At, 1, 0); PG8_STAGE(PG8_SA(0, 1), a2 + hstep, voffA);
;             PG8_WAIT_L(8); PG8_BAR; PG8_WAIT_L(0); PG8_MMA(0, 0, At, B0); PG8_BAR; PG8_SCHED;
;             PG8_LDB(B1, 1, 1); PG8_STAGE(PG8_SB(1, 0), b3, voffB);
;             PG8_BAR; PG8_WAIT_L(0); PG8_MMA(0, 1, At, B1); PG8_BAR;
;             PG8_LDA(At, 1, 1); PG8_STAGE(PG8_SA(1, 0), a3, voffA);
;             PG8_BAR; PG8_WAIT_L(0); PG8_MMA(1, 0, At, B0); PG8_BAR; PG8_SCHED;
;             PG8_STAGE(PG8_SB(1, 1), b3 + hstep, voffB);
;             PG8_WAIT_V(6); PG8_BAR; PG8_MMA(1, 1, At, B1); PG8_BAR;
	s_setprio 1
	v_mfma_f32_16x16x32_bf16 v[44:47], v[210:213], v[170:173], 0
	v_mfma_f32_16x16x32_bf16 v[36:39], v[218:221], v[170:173], 0
	v_mfma_f32_16x16x32_bf16 v[28:31], v[210:213], v[178:181], 0
	v_mfma_f32_16x16x32_bf16 v[20:23], v[218:221], v[178:181], 0
	v_mfma_f32_16x16x32_bf16 v[12:15], v[210:213], v[194:197], 0
	v_mfma_f32_16x16x32_bf16 v[8:11], v[218:221], v[194:197], 0
	v_mfma_f32_16x16x32_bf16 v[4:7], v[210:213], v[202:205], 0
	v_mfma_f32_16x16x32_bf16 v[0:3], v[218:221], v[202:205], 0
	v_mfma_f32_16x16x32_bf16 v[44:47], v[214:217], v[174:177], v[44:47]
	v_mfma_f32_16x16x32_bf16 v[36:39], v[222:225], v[174:177], v[36:39]
	v_mfma_f32_16x16x32_bf16 v[28:31], v[214:217], v[188:191], v[28:31]
	v_mfma_f32_16x16x32_bf16 v[20:23], v[222:225], v[188:191], v[20:23]
	v_mfma_f32_16x16x32_bf16 v[12:15], v[214:217], v[198:201], v[12:15]
	v_mfma_f32_16x16x32_bf16 v[8:11], v[222:225], v[198:201], v[8:11]
	v_mfma_f32_16x16x32_bf16 v[4:7], v[214:217], v[206:209], v[4:7]
	v_mfma_f32_16x16x32_bf16 v[0:3], v[222:225], v[206:209], v[0:3]
	s_setprio 0
	s_barrier
	ds_read_b128 v[150:153], v144
	ds_read_b128 v[154:157], v144 offset:1024
	ds_read_b128 v[162:165], v144 offset:2048
	ds_read_b128 v[166:169], v144 offset:3072
	s_add_u32 s0, s38, 0x160000
	s_addc_u32 s1, s39, 0
	s_mov_b32 m0, s44
	ds_read_b128 v[170:173], v142 offset:32768
	ds_read_b128 v[174:177], v142 offset:33792
	ds_read_b128 v[178:181], v142 offset:34816
	ds_read_b128 v[188:191], v142 offset:35840
	ds_read_b128 v[194:197], v142 offset:36864
	ds_read_b128 v[198:201], v142 offset:37888
	ds_read_b128 v[202:205], v142 offset:38912
	ds_read_b128 v[206:209], v142 offset:39936
	global_load_lds_dwordx4 v130, s[0:1]
	s_mov_b32 m0, s45
	s_nop 0
	global_load_lds_dwordx4 v128, s[0:1]
	s_waitcnt lgkmcnt(8)
	s_barrier
	s_waitcnt lgkmcnt(0)
	s_setprio 1
	s_waitcnt lgkmcnt(0)
	v_mfma_f32_16x16x32_bf16 v[124:127], v[150:153], v[170:173], v[124:127]
	v_mfma_f32_16x16x32_bf16 v[120:123], v[162:165], v[170:173], v[120:123]
	v_mfma_f32_16x16x32_bf16 v[116:119], v[150:153], v[178:181], v[116:119]
	v_mfma_f32_16x16x32_bf16 v[112:115], v[162:165], v[178:181], v[112:115]
	v_mfma_f32_16x16x32_bf16 v[104:107], v[150:153], v[194:197], v[104:107]
	v_mfma_f32_16x16x32_bf16 v[96:99], v[162:165], v[194:197], v[96:99]
	v_mfma_f32_16x16x32_bf16 v[88:91], v[150:153], v[202:205], v[88:91]
	v_mfma_f32_16x16x32_bf16 v[80:83], v[162:165], v[202:205], v[80:83]
	v_mfma_f32_16x16x32_bf16 v[124:127], v[154:157], v[174:177], v[124:127]
	v_mfma_f32_16x16x32_bf16 v[120:123], v[166:169], v[174:177], v[120:123]
	v_mfma_f32_16x16x32_bf16 v[116:119], v[154:157], v[188:191], v[116:119]
	v_mfma_f32_16x16x32_bf16 v[112:115], v[166:169], v[188:191], v[112:115]
	v_mfma_f32_16x16x32_bf16 v[104:107], v[154:157], v[198:201], v[104:107]
	v_mfma_f32_16x16x32_bf16 v[96:99], v[166:169], v[198:201], v[96:99]
	v_mfma_f32_16x16x32_bf16 v[88:91], v[154:157], v[206:209], v[88:91]
	v_mfma_f32_16x16x32_bf16 v[80:83], v[166:169], v[206:209], v[80:83]
	s_setprio 0
	s_barrier
	s_add_i32 s4, 0, 0x1c000
	s_add_i32 s0, s64, s35
	v_add_u32_e32 v145, s4, v140
	s_add_i32 m0, s0, 0xffffff80
	ds_read_b128 v[210:213], v145
	ds_read_b128 v[214:217], v145 offset:1024
	ds_read_b128 v[218:221], v145 offset:2048
	ds_read_b128 v[222:225], v145 offset:3072
	global_load_lds_dwordx4 v130, s[36:37] offset:128
	s_add_i32 m0, s0, 0x1f80
	s_nop 0
	global_load_lds_dwordx4 v128, s[36:37] offset:128
	s_barrier
	s_waitcnt lgkmcnt(0)
	s_setprio 1
	s_waitcnt lgkmcnt(0)
	v_mfma_f32_16x16x32_bf16 v[108:111], v[210:213], v[170:173], v[108:111]
	v_mfma_f32_16x16x32_bf16 v[100:103], v[218:221], v[170:173], v[100:103]
	v_mfma_f32_16x16x32_bf16 v[92:95], v[210:213], v[178:181], v[92:95]
	v_mfma_f32_16x16x32_bf16 v[84:87], v[218:221], v[178:181], v[84:87]
	v_mfma_f32_16x16x32_bf16 v[76:79], v[210:213], v[194:197], v[76:79]
	v_mfma_f32_16x16x32_bf16 v[72:75], v[218:221], v[194:197], v[72:75]
	v_mfma_f32_16x16x32_bf16 v[68:71], v[210:213], v[202:205], v[68:71]
	v_mfma_f32_16x16x32_bf16 v[64:67], v[218:221], v[202:205], v[64:67]
	v_mfma_f32_16x16x32_bf16 v[108:111], v[214:217], v[174:177], v[108:111]
	v_mfma_f32_16x16x32_bf16 v[100:103], v[222:225], v[174:177], v[100:103]
	v_mfma_f32_16x16x32_bf16 v[92:95], v[214:217], v[188:191], v[92:95]
	v_mfma_f32_16x16x32_bf16 v[84:87], v[222:225], v[188:191], v[84:87]
	v_mfma_f32_16x16x32_bf16 v[76:79], v[214:217], v[198:201], v[76:79]
	v_mfma_f32_16x16x32_bf16 v[72:75], v[222:225], v[198:201], v[72:75]
	v_mfma_f32_16x16x32_bf16 v[68:71], v[214:217], v[206:209], v[68:71]
	v_mfma_f32_16x16x32_bf16 v[64:67], v[222:225], v[206:209], v[64:67]
	s_setprio 0
	s_add_i32 m0, s56, 0xffffff80
	s_barrier
	ds_read_b128 v[170:173], v142 offset:49152
	ds_read_b128 v[174:177], v142 offset:50176
	ds_read_b128 v[178:181], v142 offset:51200
	ds_read_b128 v[188:191], v142 offset:52224
	ds_read_b128 v[194:197], v142 offset:53248
	ds_read_b128 v[198:201], v142 offset:54272
	ds_read_b128 v[202:205], v142 offset:55296
	ds_read_b128 v[206:209], v142 offset:56320
	global_load_lds_dwordx4 v130, s[38:39] offset:128
	s_add_i32 m0, s57, 0xffffff80
	s_nop 0
	global_load_lds_dwordx4 v128, s[38:39] offset:128
	s_barrier
; #define PG8_STAGE(bufoff, gbase, voff) do { _Pragma("unroll") for (int _i = 0; _i < 2; ++_i) \
;         __builtin_amdgcn_global_load_lds((const unsigned*)((const char*)(gbase) + (voff)[_i]), (LAS unsigned*)(lds + (bufoff) + ldsw + _i * 8192), 16, 0, 0); } while (0)
; #define PG8_LDA(dst, b, h) do { _Pragma("unroll") for (int m = 0; m < 4; ++m) _Pragma("unroll") for (int k = 0; k < 2; ++k) dst[m][k] = *(const LAS bf16x8*)(lds + PG8_SA(b, h) + aoff + m * 2048 + k * 1024); } while (0)
; #define PG8_LDB(dst, b, h) do { _Pragma("unroll") for (int n = 0; n < 2; ++n) _Pragma("unroll") for (int k = 0; k < 2; ++k) dst[n][k] = *(const LAS bf16x8*)(lds + PG8_SB(b, h) + boff + n * 2048 + k * 1024); } while (0)
; #define PG8_WAIT_V(n) asm volatile("s_waitcnt vmcnt(" #n ")" ::: "memory")
; #define PG8_WAIT_L(n) asm volatile("s_waitcnt lgkmcnt(" #n ")" ::: "memory")
; #define PG8_BAR __builtin_amdgcn_s_barrier()
; #define PG8_SCHED __builtin_amdgcn_sched_barrier(0)
; template <class Epi, class Sched>
; DI void gemm_phase(LAS unsigned char* lds, const Gemm g, const Sched& S, const Epi& E) {
;     ...
;             PG8_LDB(B0, 0, 0); PG8_SCHED; PG8_LDA(At, 0, 0); PG8_STAGE(PG8_SA(1, 1), a1 + hstep, voffA);
;             PG8_WAIT_L(8); PG8_BAR; PG8_WAIT_L(0); PG8_MMA(0, 0, At, B0); PG8_BAR; PG8_SCHED;
;             PG8_LDB(B1, 0, 1); PG8_STAGE(PG8_SB(0, 0), b2, voffB);
;             PG8_BAR; PG8_WAIT_L(0); PG8_MMA(0, 1, At, B1); PG8_BAR;
;             PG8_LDA(At, 0, 1); PG8_STAGE(PG8_SA(0, 0), a2, voffA);
;             PG8_BAR; PG8_WAIT_L(0); PG8_MMA(1, 0, At, B0); PG8_BAR; PG8_SCHED;
;             PG8_STAGE(PG8_SB(0, 1), b2 + hstep, voffB);
;             PG8_WAIT_V(6); PG8_BAR; PG8_MMA(1, 1, At, B1); PG8_BAR;
;             PG8_LDB(B0, 1, 0); PG8_SCHED; PG8_LDA(At, 1, 0); PG8_STAGE(PG8_SA(0, 1), a2 + hstep, voffA);
;             PG8_WAIT_L(8); PG8_BAR; PG8_WAIT_L(0); PG8_MMA(0, 0, At, B0); PG8_BAR; PG8_SCHED;
;             PG8_LDB(B1, 1, 1); PG8_STAGE(PG8_SB(1, 0), b3, voffB);
;             PG8_BAR; PG8_WAIT_L(0); PG8_MMA(0, 1, At, B1); PG8_BAR;
;             PG8_LDA(At, 1, 1); PG8_STAGE(PG8_SA(1, 0), a3, voffA);
;             PG8_BAR; PG8_WAIT_L(0); PG8_MMA(1, 0, At, B0); PG8_BAR; PG8_SCHED;
;             PG8_STAGE(PG8_SB(1, 1), b3 + hstep, voffB);
;             PG8_WAIT_V(6); PG8_BAR; PG8_MMA(1, 1, At, B1); PG8_BAR;
	s_waitcnt lgkmcnt(0)
	s_setprio 1
	s_waitcnt lgkmcnt(0)
	v_mfma_f32_16x16x32_bf16 v[60:63], v[150:153], v[170:173], v[60:63]
	v_mfma_f32_16x16x32_bf16 v[56:59], v[162:165], v[170:173], v[56:59]
	v_mfma_f32_16x16x32_bf16 v[52:55], v[150:153], v[178:181], v[52:55]
	v_mfma_f32_16x16x32_bf16 v[48:51], v[162:165], v[178:181], v[48:51]
	v_mfma_f32_16x16x32_bf16 v[40:43], v[150:153], v[194:197], v[40:43]
	v_mfma_f32_16x16x32_bf16 v[32:35], v[162:165], v[194:197], v[32:35]
	v_mfma_f32_16x16x32_bf16 v[24:27], v[150:153], v[202:205], v[24:27]
	v_mfma_f32_16x16x32_bf16 v[16:19], v[162:165], v[202:205], v[16:19]
	v_mfma_f32_16x16x32_bf16 v[60:63], v[154:157], v[174:177], v[60:63]
	v_mfma_f32_16x16x32_bf16 v[56:59], v[166:169], v[174:177], v[56:59]
	v_mfma_f32_16x16x32_bf16 v[52:55], v[154:157], v[188:191], v[52:55]
	v_mfma_f32_16x16x32_bf16 v[48:51], v[166:169], v[188:191], v[48:51]
	v_mfma_f32_16x16x32_bf16 v[40:43], v[154:157], v[198:201], v[40:43]
	v_mfma_f32_16x16x32_bf16 v[32:35], v[166:169], v[198:201], v[32:35]
	v_mfma_f32_16x16x32_bf16 v[24:27], v[154:157], v[206:209], v[24:27]
	v_mfma_f32_16x16x32_bf16 v[16:19], v[166:169], v[206:209], v[16:19]
	s_setprio 0
	s_barrier
	s_add_u32 s0, s36, 0x160080
	s_addc_u32 s1, s37, 0
	s_add_i32 s4, s4, s35
	s_mov_b32 m0, s4
	s_nop 0
	global_load_lds_dwordx4 v130, s[0:1]
	s_add_i32 m0, s4, 0x2000
	s_nop 0
	global_load_lds_dwordx4 v128, s[0:1]
	s_waitcnt vmcnt(6)
	s_barrier
	s_setprio 1
	v_mfma_f32_16x16x32_bf16 v[44:47], v[210:213], v[170:173], v[44:47]
	v_mfma_f32_16x16x32_bf16 v[36:39], v[218:221], v[170:173], v[36:39]
	v_mfma_f32_16x16x32_bf16 v[28:31], v[210:213], v[178:181], v[28:31]
	v_mfma_f32_16x16x32_bf16 v[20:23], v[218:221], v[178:181], v[20:23]
	v_mfma_f32_16x16x32_bf16 v[12:15], v[210:213], v[194:197], v[12:15]
	v_mfma_f32_16x16x32_bf16 v[8:11], v[218:221], v[194:197], v[8:11]
	v_mfma_f32_16x16x32_bf16 v[4:7], v[210:213], v[202:205], v[4:7]
	v_mfma_f32_16x16x32_bf16 v[0:3], v[218:221], v[202:205], v[0:3]
	v_mfma_f32_16x16x32_bf16 v[44:47], v[214:217], v[174:177], v[44:47]
	v_mfma_f32_16x16x32_bf16 v[36:39], v[222:225], v[174:177], v[36:39]
	v_mfma_f32_16x16x32_bf16 v[28:31], v[214:217], v[188:191], v[28:31]
	v_mfma_f32_16x16x32_bf16 v[20:23], v[222:225], v[188:191], v[20:23]
	v_mfma_f32_16x16x32_bf16 v[12:15], v[214:217], v[198:201], v[12:15]
	v_mfma_f32_16x16x32_bf16 v[8:11], v[222:225], v[198:201], v[8:11]
	v_mfma_f32_16x16x32_bf16 v[4:7], v[214:217], v[206:209], v[4:7]
	v_mfma_f32_16x16x32_bf16 v[0:3], v[222:225], v[206:209], v[0:3]
	s_setprio 0
	s_add_i32 s68, s68, 2
	s_add_u32 s8, s8, 0x100
	s_addc_u32 s9, s9, 0
	s_add_u32 s66, s66, 0x100
	s_addc_u32 s67, s67, 0
	s_cmp_gt_u32 s68, 5
	s_barrier
	s_cbranch_scc0 .LBB0_326
	s_branch .Lpeel_done_326
.LBB0_326:
	ds_read_b128 v[150:153], v141
	ds_read_b128 v[154:157], v141 offset:1024
	ds_read_b128 v[162:165], v141 offset:2048
	ds_read_b128 v[166:169], v141 offset:3072
	s_add_u32 s0, s8, 0xffea0080
	s_addc_u32 s1, s9, -1
	s_cmp_eq_u32 s68, 4
	s_cselect_b32 s39, s15, s1
	s_cselect_b32 s38, s17, s0
	s_cselect_b32 s37, s19, s67
	s_cselect_b32 s36, s18, s66
	s_mov_b32 m0, s58
	ds_read_b128 v[170:173], v142
	ds_read_b128 v[174:177], v142 offset:1024
	ds_read_b128 v[178:181], v142 offset:2048
	ds_read_b128 v[188:191], v142 offset:3072
	ds_read_b128 v[194:197], v142 offset:4096
	ds_read_b128 v[198:201], v142 offset:5120
	ds_read_b128 v[202:205], v142 offset:6144
	ds_read_b128 v[206:209], v142 offset:7168
	global_load_lds_dwordx4 v132, s[8:9]
	s_mov_b32 m0, s59
	s_nop 0
	global_load_lds_dwordx4 v134, s[8:9]
	s_waitcnt lgkmcnt(8)
	s_barrier
	s_waitcnt lgkmcnt(0)
	s_setprio 1
	s_waitcnt lgkmcnt(0)
	v_mfma_f32_16x16x32_bf16 v[124:127], v[150:153], v[170:173], v[124:127]
	v_mfma_f32_16x16x32_bf16 v[120:123], v[162:165], v[170:173], v[120:123]
	v_mfma_f32_16x16x32_bf16 v[116:119], v[150:153], v[178:181], v[116:119]
	v_mfma_f32_16x16x32_bf16 v[112:115], v[162:165], v[178:181], v[112:115]
	v_mfma_f32_16x16x32_bf16 v[104:107], v[150:153], v[194:197], v[104:107]
	v_mfma_f32_16x16x32_bf16 v[96:99], v[162:165], v[194:197], v[96:99]
	v_mfma_f32_16x16x32_bf16 v[88:91], v[150:153], v[202:205], v[88:91]
	v_mfma_f32_16x16x32_bf16 v[80:83], v[162:165], v[202:205], v[80:83]
	v_mfma_f32_16x16x32_bf16 v[124:127], v[154:157], v[174:177], v[124:127]
	v_mfma_f32_16x16x32_bf16 v[120:123], v[166:169], v[174:177], v[120:123]
	v_mfma_f32_16x16x32_bf16 v[116:119], v[154:157], v[188:191], v[116:119]
	v_mfma_f32_16x16x32_bf16 v[112:115], v[166:169], v[188:191], v[112:115]
	v_mfma_f32_16x16x32_bf16 v[104:107], v[154:157], v[198:201], v[104:107]
	v_mfma_f32_16x16x32_bf16 v[96:99], v[166:169], v[198:201], v[96:99]
	v_mfma_f32_16x16x32_bf16 v[88:91], v[154:157], v[206:209], v[88:91]
	v_mfma_f32_16x16x32_bf16 v[80:83], v[166:169], v[206:209], v[80:83]
	s_setprio 0
	s_barrier
	s_mov_b32 m0, s60
	ds_read_b128 v[210:213], v143
	ds_read_b128 v[214:217], v143 offset:1024
	ds_read_b128 v[218:221], v143 offset:2048
	ds_read_b128 v[222:225], v143 offset:3072
	global_load_lds_dwordx4 v130, s[36:37]
	v_lshl_add_u64 v[158:159], s[36:37], 0, v[128:129]
	s_mov_b32 m0, s61
	s_nop 0
	global_load_lds_dwordx4 v128, s[36:37]
	s_barrier
; #define PG8_STAGE(bufoff, gbase, voff) do { _Pragma("unroll") for (int _i = 0; _i < 2; ++_i) \
;         __builtin_amdgcn_global_load_lds((const unsigned*)((const char*)(gbase) + (voff)[_i]), (LAS unsigned*)(lds + (bufoff) + ldsw + _i * 8192), 16, 0, 0); } while (0)
; #define PG8_LDA(dst, b, h) do { _Pragma("unroll") for (int m = 0; m < 4; ++m) _Pragma("unroll") for (int k = 0; k < 2; ++k) dst[m][k] = *(const LAS bf16x8*)(lds + PG8_SA(b, h) + aoff + m * 2048 + k * 1024); } while (0)
; #define PG8_LDB(dst, b, h) do { _Pragma("unroll") for (int n = 0; n < 2; ++n) _Pragma("unroll") for (int k = 0; k < 2; ++k) dst[n][k] = *(const LAS bf16x8*)(lds + PG8_SB(b, h) + boff + n * 2048 + k * 1024); } while (0)
; #define PG8_WAIT_V(n) asm volatile("s_waitcnt vmcnt(" #n ")" ::: "memory")
; #define PG8_WAIT_L(n) asm volatile("s_waitcnt lgkmcnt(" #n ")" ::: "memory")
; #define PG8_BAR __builtin_amdgcn_s_barrier()
; #define PG8_SCHED __builtin_amdgcn_sched_barrier(0)
; template <class Epi, class Sched>
; DI void gemm_phase(LAS unsigned char* lds, const Gemm g, const Sched& S, const Epi& E) {
;     ...
;             PG8_LDB(B0, 0, 0); PG8_SCHED; PG8_LDA(At, 0, 0); PG8_STAGE(PG8_SA(1, 1), a1 + hstep, voffA);
;             PG8_WAIT_L(8); PG8_BAR; PG8_WAIT_L(0); PG8_MMA(0, 0, At, B0); PG8_BAR; PG8_SCHED;
;             PG8_LDB(B1, 0, 1); PG8_STAGE(PG8_SB(0, 0), b2, voffB);
;             PG8_BAR; PG8_WAIT_L(0); PG8_MMA(0, 1, At, B1); PG8_BAR;
;             PG8_LDA(At, 0, 1); PG8_STAGE(PG8_SA(0, 0), a2, voffA);
;             PG8_BAR; PG8_WAIT_L(0); PG8_MMA(1, 0, At, B0); PG8_BAR; PG8_SCHED;
;             PG8_STAGE(PG8_SB(0, 1), b2 + hstep, voffB);
;             PG8_WAIT_V(6); PG8_BAR; PG8_MMA(1, 1, At, B1); PG8_BAR;
;             PG8_LDB(B0, 1, 0); PG8_SCHED; PG8_LDA(At, 1, 0); PG8_STAGE(PG8_SA(0, 1), a2 + hstep, voffA);
;             PG8_WAIT_L(8); PG8_BAR; PG8_WAIT_L(0); PG8_MMA(0, 0, At, B0); PG8_BAR; PG8_SCHED;
;             PG8_LDB(B1, 1, 1); PG8_STAGE(PG8_SB(1, 0), b3, voffB);
;             PG8_BAR; PG8_WAIT_L(0); PG8_MMA(0, 1, At, B1); PG8_BAR;
;             PG8_LDA(At, 1, 1); PG8_STAGE(PG8_SA(1, 0), a3, voffA);
;             PG8_BAR; PG8_WAIT_L(0); PG8_MMA(1, 0, At, B0); PG8_BAR; PG8_SCHED;
;             PG8_STAGE(PG8_SB(1, 1), b3 + hstep, voffB);
;             PG8_WAIT_V(6); PG8_BAR; PG8_MMA(1, 1, At, B1); PG8_BAR;
	s_waitcnt lgkmcnt(0)
	s_setprio 1
	s_waitcnt lgkmcnt(0)
	v_mfma_f32_16x16x32_bf16 v[108:111], v[210:213], v[170:173], v[108:111]
	v_mfma_f32_16x16x32_bf16 v[100:103], v[218:221], v[170:173], v[100:103]
	v_mfma_f32_16x16x32_bf16 v[92:95], v[210:213], v[178:181], v[92:95]
	v_mfma_f32_16x16x32_bf16 v[84:87], v[218:221], v[178:181], v[84:87]
	v_mfma_f32_16x16x32_bf16 v[76:79], v[210:213], v[194:197], v[76:79]
	v_mfma_f32_16x16x32_bf16 v[72:75], v[218:221], v[194:197], v[72:75]
	v_mfma_f32_16x16x32_bf16 v[68:71], v[210:213], v[202:205], v[68:71]
	v_mfma_f32_16x16x32_bf16 v[64:67], v[218:221], v[202:205], v[64:67]
	v_mfma_f32_16x16x32_bf16 v[108:111], v[214:217], v[174:177], v[108:111]
	v_mfma_f32_16x16x32_bf16 v[100:103], v[222:225], v[174:177], v[100:103]
	v_mfma_f32_16x16x32_bf16 v[92:95], v[214:217], v[188:191], v[92:95]
	v_mfma_f32_16x16x32_bf16 v[84:87], v[222:225], v[188:191], v[84:87]
	v_mfma_f32_16x16x32_bf16 v[76:79], v[214:217], v[198:201], v[76:79]
	v_mfma_f32_16x16x32_bf16 v[72:75], v[222:225], v[198:201], v[72:75]
	v_mfma_f32_16x16x32_bf16 v[68:71], v[214:217], v[206:209], v[68:71]
	v_mfma_f32_16x16x32_bf16 v[64:67], v[222:225], v[206:209], v[64:67]
	s_setprio 0
	s_mov_b32 m0, s42
	v_lshl_add_u64 v[182:183], s[38:39], 0, v[130:131]
	s_barrier
	ds_read_b128 v[170:173], v142 offset:16384
	ds_read_b128 v[174:177], v142 offset:17408
	ds_read_b128 v[178:181], v142 offset:18432
	ds_read_b128 v[188:191], v142 offset:19456
	ds_read_b128 v[194:197], v142 offset:20480
	ds_read_b128 v[198:201], v142 offset:21504
	ds_read_b128 v[202:205], v142 offset:22528
	ds_read_b128 v[206:209], v142 offset:23552
	global_load_lds_dwordx4 v130, s[38:39]
	v_lshl_add_u64 v[226:227], s[38:39], 0, v[128:129]
	s_mov_b32 m0, s43
	s_nop 0
	global_load_lds_dwordx4 v128, s[38:39]
	s_barrier
	s_waitcnt lgkmcnt(0)
	s_setprio 1
	s_waitcnt lgkmcnt(0)
	v_mfma_f32_16x16x32_bf16 v[60:63], v[150:153], v[170:173], v[60:63]
	v_mfma_f32_16x16x32_bf16 v[56:59], v[162:165], v[170:173], v[56:59]
	v_mfma_f32_16x16x32_bf16 v[52:55], v[150:153], v[178:181], v[52:55]
	v_mfma_f32_16x16x32_bf16 v[48:51], v[162:165], v[178:181], v[48:51]
	v_mfma_f32_16x16x32_bf16 v[40:43], v[150:153], v[194:197], v[40:43]
	v_mfma_f32_16x16x32_bf16 v[32:35], v[162:165], v[194:197], v[32:35]
	v_mfma_f32_16x16x32_bf16 v[24:27], v[150:153], v[202:205], v[24:27]
	v_mfma_f32_16x16x32_bf16 v[16:19], v[162:165], v[202:205], v[16:19]
	v_mfma_f32_16x16x32_bf16 v[60:63], v[154:157], v[174:177], v[60:63]
	v_mfma_f32_16x16x32_bf16 v[56:59], v[166:169], v[174:177], v[56:59]
	v_mfma_f32_16x16x32_bf16 v[52:55], v[154:157], v[188:191], v[52:55]
	v_mfma_f32_16x16x32_bf16 v[48:51], v[166:169], v[188:191], v[48:51]
	v_mfma_f32_16x16x32_bf16 v[40:43], v[154:157], v[198:201], v[40:43]
	v_mfma_f32_16x16x32_bf16 v[32:35], v[166:169], v[198:201], v[32:35]
	v_mfma_f32_16x16x32_bf16 v[24:27], v[154:157], v[206:209], v[24:27]
	v_mfma_f32_16x16x32_bf16 v[16:19], v[166:169], v[206:209], v[16:19]
	s_setprio 0
	s_barrier
	s_add_u32 s0, s36, 0x160000
	s_addc_u32 s1, s37, 0
	s_mov_b32 m0, s62
	s_nop 0
	global_load_lds_dwordx4 v130, s[0:1]
	s_mov_b32 m0, s63
	s_nop 0
	global_load_lds_dwordx4 v128, s[0:1]
	s_waitcnt vmcnt(6)
	s_barrier
	s_setprio 1
	v_mfma_f32_16x16x32_bf16 v[44:47], v[210:213], v[170:173], v[44:47]
	v_mfma_f32_16x16x32_bf16 v[36:39], v[218:221], v[170:173], v[36:39]
	v_mfma_f32_16x16x32_bf16 v[28:31], v[210:213], v[178:181], v[28:31]
	v_mfma_f32_16x16x32_bf16 v[20:23], v[218:221], v[178:181], v[20:23]
	v_mfma_f32_16x16x32_bf16 v[12:15], v[210:213], v[194:197], v[12:15]
	v_mfma_f32_16x16x32_bf16 v[8:11], v[218:221], v[194:197], v[8:11]
	v_mfma_f32_16x16x32_bf16 v[4:7], v[210:213], v[202:205], v[4:7]
	v_mfma_f32_16x16x32_bf16 v[0:3], v[218:221], v[202:205], v[0:3]
	v_mfma_f32_16x16x32_bf16 v[44:47], v[214:217], v[174:177], v[44:47]
	v_mfma_f32_16x16x32_bf16 v[36:39], v[222:225], v[174:177], v[36:39]
	v_mfma_f32_16x16x32_bf16 v[28:31], v[214:217], v[188:191], v[28:31]
	v_mfma_f32_16x16x32_bf16 v[20:23], v[222:225], v[188:191], v[20:23]
	v_mfma_f32_16x16x32_bf16 v[12:15], v[214:217], v[198:201], v[12:15]
	v_mfma_f32_16x16x32_bf16 v[8:11], v[222:225], v[198:201], v[8:11]
	v_mfma_f32_16x16x32_bf16 v[4:7], v[214:217], v[206:209], v[4:7]
	v_mfma_f32_16x16x32_bf16 v[0:3], v[222:225], v[206:209], v[0:3]
	s_setprio 0
	s_barrier
	ds_read_b128 v[150:153], v144
	ds_read_b128 v[154:157], v144 offset:1024
	ds_read_b128 v[162:165], v144 offset:2048
	ds_read_b128 v[166:169], v144 offset:3072
	s_add_u32 s0, s38, 0x160000
	s_addc_u32 s1, s39, 0
	s_mov_b32 m0, s44
	ds_read_b128 v[170:173], v142 offset:32768
	ds_read_b128 v[174:177], v142 offset:33792
	ds_read_b128 v[178:181], v142 offset:34816
	ds_read_b128 v[188:191], v142 offset:35840
	ds_read_b128 v[194:197], v142 offset:36864
	ds_read_b128 v[198:201], v142 offset:37888
	ds_read_b128 v[202:205], v142 offset:38912
	ds_read_b128 v[206:209], v142 offset:39936
	global_load_lds_dwordx4 v130, s[0:1]
	s_mov_b32 m0, s45
	s_nop 0
	global_load_lds_dwordx4 v128, s[0:1]
	s_waitcnt lgkmcnt(8)
	s_barrier
; #define PG8_STAGE(bufoff, gbase, voff) do { _Pragma("unroll") for (int _i = 0; _i < 2; ++_i) \
;         __builtin_amdgcn_global_load_lds((const unsigned*)((const char*)(gbase) + (voff)[_i]), (LAS unsigned*)(lds + (bufoff) + ldsw + _i * 8192), 16, 0, 0); } while (0)
; #define PG8_LDA(dst, b, h) do { _Pragma("unroll") for (int m = 0; m < 4; ++m) _Pragma("unroll") for (int k = 0; k < 2; ++k) dst[m][k] = *(const LAS bf16x8*)(lds + PG8_SA(b, h) + aoff + m * 2048 + k * 1024); } while (0)
; #define PG8_LDB(dst, b, h) do { _Pragma("unroll") for (int n = 0; n < 2; ++n) _Pragma("unroll") for (int k = 0; k < 2; ++k) dst[n][k] = *(const LAS bf16x8*)(lds + PG8_SB(b, h) + boff + n * 2048 + k * 1024); } while (0)
; #define PG8_WAIT_V(n) asm volatile("s_waitcnt vmcnt(" #n ")" ::: "memory")
; #define PG8_WAIT_L(n) asm volatile("s_waitcnt lgkmcnt(" #n ")" ::: "memory")
; #define PG8_BAR __builtin_amdgcn_s_barrier()
; #define PG8_SCHED __builtin_amdgcn_sched_barrier(0)
; template <class Epi, class Sched>
; DI void gemm_phase(LAS unsigned char* lds, const Gemm g, const Sched& S, const Epi& E) {
;     ...
;             PG8_LDB(B0, 0, 0); PG8_SCHED; PG8_LDA(At, 0, 0); PG8_STAGE(PG8_SA(1, 1), a1 + hstep, voffA);
;             PG8_WAIT_L(8); PG8_BAR; PG8_WAIT_L(0); PG8_MMA(0, 0, At, B0); PG8_BAR; PG8_SCHED;
;             PG8_LDB(B1, 0, 1); PG8_STAGE(PG8_SB(0, 0), b2, voffB);
;             PG8_BAR; PG8_WAIT_L(0); PG8_MMA(0, 1, At, B1); PG8_BAR;
;             PG8_LDA(At, 0, 1); PG8_STAGE(PG8_SA(0, 0), a2, voffA);
;             PG8_BAR; PG8_WAIT_L(0); PG8_MMA(1, 0, At, B0); PG8_BAR; PG8_SCHED;
;             PG8_STAGE(PG8_SB(0, 1), b2 + hstep, voffB);
;             PG8_WAIT_V(6); PG8_BAR; PG8_MMA(1, 1, At, B1); PG8_BAR;
;             PG8_LDB(B0, 1, 0); PG8_SCHED; PG8_LDA(At, 1, 0); PG8_STAGE(PG8_SA(0, 1), a2 + hstep, voffA);
;             PG8_WAIT_L(8); PG8_BAR; PG8_WAIT_L(0); PG8_MMA(0, 0, At, B0); PG8_BAR; PG8_SCHED;
;             PG8_LDB(B1, 1, 1); PG8_STAGE(PG8_SB(1, 0), b3, voffB);
;             PG8_BAR; PG8_WAIT_L(0); PG8_MMA(0, 1, At, B1); PG8_BAR;
;             PG8_LDA(At, 1, 1); PG8_STAGE(PG8_SA(1, 0), a3, voffA);
;             PG8_BAR; PG8_WAIT_L(0); PG8_MMA(1, 0, At, B0); PG8_BAR; PG8_SCHED;
;             PG8_STAGE(PG8_SB(1, 1), b3 + hstep, voffB);
;             PG8_WAIT_V(6); PG8_BAR; PG8_MMA(1, 1, At, B1); PG8_BAR;
	s_waitcnt lgkmcnt(0)
	s_setprio 1
	s_waitcnt lgkmcnt(0)
	v_mfma_f32_16x16x32_bf16 v[124:127], v[150:153], v[170:173], v[124:127]
	v_mfma_f32_16x16x32_bf16 v[120:123], v[162:165], v[170:173], v[120:123]
	v_mfma_f32_16x16x32_bf16 v[116:119], v[150:153], v[178:181], v[116:119]
	v_mfma_f32_16x16x32_bf16 v[112:115], v[162:165], v[178:181], v[112:115]
	v_mfma_f32_16x16x32_bf16 v[104:107], v[150:153], v[194:197], v[104:107]
	v_mfma_f32_16x16x32_bf16 v[96:99], v[162:165], v[194:197], v[96:99]
	v_mfma_f32_16x16x32_bf16 v[88:91], v[150:153], v[202:205], v[88:91]
	v_mfma_f32_16x16x32_bf16 v[80:83], v[162:165], v[202:205], v[80:83]
	v_mfma_f32_16x16x32_bf16 v[124:127], v[154:157], v[174:177], v[124:127]
	v_mfma_f32_16x16x32_bf16 v[120:123], v[166:169], v[174:177], v[120:123]
	v_mfma_f32_16x16x32_bf16 v[116:119], v[154:157], v[188:191], v[116:119]
	v_mfma_f32_16x16x32_bf16 v[112:115], v[166:169], v[188:191], v[112:115]
	v_mfma_f32_16x16x32_bf16 v[104:107], v[154:157], v[198:201], v[104:107]
	v_mfma_f32_16x16x32_bf16 v[96:99], v[166:169], v[198:201], v[96:99]
	v_mfma_f32_16x16x32_bf16 v[88:91], v[154:157], v[206:209], v[88:91]
	v_mfma_f32_16x16x32_bf16 v[80:83], v[166:169], v[206:209], v[80:83]
	s_setprio 0
	s_barrier
	s_add_i32 s4, 0, 0x1c000
	s_add_i32 s0, s64, s35
	v_add_u32_e32 v145, s4, v140
	s_add_i32 m0, s0, 0xffffff80
	ds_read_b128 v[210:213], v145
	ds_read_b128 v[214:217], v145 offset:1024
	ds_read_b128 v[218:221], v145 offset:2048
	ds_read_b128 v[222:225], v145 offset:3072
	global_load_lds_dwordx4 v130, s[36:37] offset:128
	s_add_i32 m0, s0, 0x1f80
	s_nop 0
	global_load_lds_dwordx4 v128, s[36:37] offset:128
	s_barrier
	s_waitcnt lgkmcnt(0)
	s_setprio 1
	s_waitcnt lgkmcnt(0)
	v_mfma_f32_16x16x32_bf16 v[108:111], v[210:213], v[170:173], v[108:111]
	v_mfma_f32_16x16x32_bf16 v[100:103], v[218:221], v[170:173], v[100:103]
	v_mfma_f32_16x16x32_bf16 v[92:95], v[210:213], v[178:181], v[92:95]
	v_mfma_f32_16x16x32_bf16 v[84:87], v[218:221], v[178:181], v[84:87]
	v_mfma_f32_16x16x32_bf16 v[76:79], v[210:213], v[194:197], v[76:79]
	v_mfma_f32_16x16x32_bf16 v[72:75], v[218:221], v[194:197], v[72:75]
	v_mfma_f32_16x16x32_bf16 v[68:71], v[210:213], v[202:205], v[68:71]
	v_mfma_f32_16x16x32_bf16 v[64:67], v[218:221], v[202:205], v[64:67]
	v_mfma_f32_16x16x32_bf16 v[108:111], v[214:217], v[174:177], v[108:111]
	v_mfma_f32_16x16x32_bf16 v[100:103], v[222:225], v[174:177], v[100:103]
	v_mfma_f32_16x16x32_bf16 v[92:95], v[214:217], v[188:191], v[92:95]
	v_mfma_f32_16x16x32_bf16 v[84:87], v[222:225], v[188:191], v[84:87]
	v_mfma_f32_16x16x32_bf16 v[76:79], v[214:217], v[198:201], v[76:79]
	v_mfma_f32_16x16x32_bf16 v[72:75], v[222:225], v[198:201], v[72:75]
	v_mfma_f32_16x16x32_bf16 v[68:71], v[214:217], v[206:209], v[68:71]
	v_mfma_f32_16x16x32_bf16 v[64:67], v[222:225], v[206:209], v[64:67]
	s_setprio 0
	s_add_i32 m0, s56, 0xffffff80
	s_barrier
	ds_read_b128 v[170:173], v142 offset:49152
	ds_read_b128 v[174:177], v142 offset:50176
	ds_read_b128 v[178:181], v142 offset:51200
	ds_read_b128 v[188:191], v142 offset:52224
	ds_read_b128 v[194:197], v142 offset:53248
	ds_read_b128 v[198:201], v142 offset:54272
	ds_read_b128 v[202:205], v142 offset:55296
	ds_read_b128 v[206:209], v142 offset:56320
	global_load_lds_dwordx4 v130, s[38:39] offset:128
	s_add_i32 m0, s57, 0xffffff80
	s_nop 0
	global_load_lds_dwordx4 v128, s[38:39] offset:128
	s_barrier
	s_waitcnt lgkmcnt(0)
	s_setprio 1
	s_waitcnt lgkmcnt(0)
	v_mfma_f32_16x16x32_bf16 v[60:63], v[150:153], v[170:173], v[60:63]
	v_mfma_f32_16x16x32_bf16 v[56:59], v[162:165], v[170:173], v[56:59]
	v_mfma_f32_16x16x32_bf16 v[52:55], v[150:153], v[178:181], v[52:55]
	v_mfma_f32_16x16x32_bf16 v[48:51], v[162:165], v[178:181], v[48:51]
	v_mfma_f32_16x16x32_bf16 v[40:43], v[150:153], v[194:197], v[40:43]
	v_mfma_f32_16x16x32_bf16 v[32:35], v[162:165], v[194:197], v[32:35]
	v_mfma_f32_16x16x32_bf16 v[24:27], v[150:153], v[202:205], v[24:27]
	v_mfma_f32_16x16x32_bf16 v[16:19], v[162:165], v[202:205], v[16:19]
	v_mfma_f32_16x16x32_bf16 v[60:63], v[154:157], v[174:177], v[60:63]
	v_mfma_f32_16x16x32_bf16 v[56:59], v[166:169], v[174:177], v[56:59]
	v_mfma_f32_16x16x32_bf16 v[52:55], v[154:157], v[188:191], v[52:55]
	v_mfma_f32_16x16x32_bf16 v[48:51], v[166:169], v[188:191], v[48:51]
	v_mfma_f32_16x16x32_bf16 v[40:43], v[154:157], v[198:201], v[40:43]
	v_mfma_f32_16x16x32_bf16 v[32:35], v[166:169], v[198:201], v[32:35]
	v_mfma_f32_16x16x32_bf16 v[24:27], v[154:157], v[206:209], v[24:27]
	v_mfma_f32_16x16x32_bf16 v[16:19], v[166:169], v[206:209], v[16:19]
	s_setprio 0
	s_barrier
	s_add_u32 s0, s36, 0x160080
	s_addc_u32 s1, s37, 0
	s_add_i32 s4, s4, s35
	s_mov_b32 m0, s4
	s_nop 0
	global_load_lds_dwordx4 v130, s[0:1]
	s_add_i32 m0, s4, 0x2000
	s_nop 0
	global_load_lds_dwordx4 v128, s[0:1]
	s_waitcnt vmcnt(6)
	s_barrier
	s_setprio 1
	v_mfma_f32_16x16x32_bf16 v[44:47], v[210:213], v[170:173], v[44:47]
	v_mfma_f32_16x16x32_bf16 v[36:39], v[218:221], v[170:173], v[36:39]
	v_mfma_f32_16x16x32_bf16 v[28:31], v[210:213], v[178:181], v[28:31]
	v_mfma_f32_16x16x32_bf16 v[20:23], v[218:221], v[178:181], v[20:23]
	v_mfma_f32_16x16x32_bf16 v[12:15], v[210:213], v[194:197], v[12:15]
	v_mfma_f32_16x16x32_bf16 v[8:11], v[218:221], v[194:197], v[8:11]
	v_mfma_f32_16x16x32_bf16 v[4:7], v[210:213], v[202:205], v[4:7]
	v_mfma_f32_16x16x32_bf16 v[0:3], v[218:221], v[202:205], v[0:3]
	v_mfma_f32_16x16x32_bf16 v[44:47], v[214:217], v[174:177], v[44:47]
	v_mfma_f32_16x16x32_bf16 v[36:39], v[222:225], v[174:177], v[36:39]
	v_mfma_f32_16x16x32_bf16 v[28:31], v[214:217], v[188:191], v[28:31]
	v_mfma_f32_16x16x32_bf16 v[20:23], v[222:225], v[188:191], v[20:23]
	v_mfma_f32_16x16x32_bf16 v[12:15], v[214:217], v[198:201], v[12:15]
	v_mfma_f32_16x16x32_bf16 v[8:11], v[222:225], v[198:201], v[8:11]
	v_mfma_f32_16x16x32_bf16 v[4:7], v[214:217], v[206:209], v[4:7]
	v_mfma_f32_16x16x32_bf16 v[0:3], v[222:225], v[206:209], v[0:3]
	s_setprio 0
	s_add_i32 s68, s68, 2
	s_add_u32 s8, s8, 0x100
	s_addc_u32 s9, s9, 0
	s_add_u32 s66, s66, 0x100
	s_addc_u32 s67, s67, 0
	s_cmp_gt_u32 s68, 5
	s_barrier
	s_cbranch_scc0 .LBB0_326

;     DI size_t aoff(const Unit& u, size_t tstep) const { return (size_t)u.pm * tstep; }
;     DI size_t boff(const Unit& u, size_t tstep) const { return (size_t)u.pn * tstep; }
;     DI size_t aoff(const Unit& u, size_t) const { return (size_t)u.ks * kbytes; }
;     DI size_t boff(const Unit& u, size_t tstep) const { return (size_t)u.pn * tstep + (size_t)u.ks * kbytes; }
;     DI size_t aoff(const Unit& u, size_t tstep) const { return (u.ks < 2 ? offU : offOA) + (size_t)u.pm * tstep; }
; #define PG8_STAGE(bufoff, gbase, voff) do { _Pragma("unroll") for (int _i = 0; _i < 2; ++_i) \
;         __builtin_amdgcn_global_load_lds((const unsigned*)((const char*)(gbase) + (voff)[_i]), (LAS unsigned*)(lds + (bufoff) + ldsw + _i * 8192), 16, 0, 0); } while (0)
; #define PG8_WAIT_V(n) asm volatile("s_waitcnt vmcnt(" #n ")" ::: "memory")
; #define PG8_BAR __builtin_amdgcn_s_barrier()
; template <class Epi, class Sched>
; DI void gemm_phase(LAS unsigned char* lds, const Gemm g, const Sched& S, const Epi& E) {
;     ...
;     const char* cA = (const char*)g.A + S.aoff(cur, tstep); const char* cB = (const char*)g.Bt + S.boff(cur, tstep);
;     PG8_STAGE(PG8_SB(0, 0), cB, voffB); PG8_STAGE(PG8_SA(0, 0), cA, voffA); PG8_STAGE(PG8_SB(0, 1), cB + hstep, voffB); PG8_STAGE(PG8_SA(0, 1), cA + hstep, voffA);
;     if (wr == 1) PG8_BAR;
;     PG8_WAIT_V(4); PG8_BAR;
;     PG8_STAGE(PG8_SB(1, 0), cB + kstep, voffB); PG8_STAGE(PG8_SA(1, 0), cA + kstep, voffA); PG8_STAGE(PG8_SB(1, 1), cB + hstep + kstep, voffB);
;     PG8_WAIT_V(6); PG8_BAR;
.LBB0_518:
	s_add_u32 s78, s22, 0x107c3000
	s_addc_u32 s79, s23, 0
	s_add_u32 s80, s22, 0x14843000
	s_addc_u32 s81, s23, 0
	s_add_u32 s30, s22, 0x1c843000
	s_addc_u32 s31, s23, 0
	s_add_u32 s82, s22, 0x18843000
	s_addc_u32 s83, s23, 0
	s_add_u32 s36, s22, 0x1d0c3000
	s_addc_u32 s37, s23, 0
	s_add_u32 s38, s22, 0x122400
	s_addc_u32 s39, s23, 0
	s_ashr_i32 s86, s26, 31
	s_add_u32 s4, s20, 0x16200000
	v_writelane_b32 v244, s4, 10
	s_addc_u32 s4, s21, 0
	v_writelane_b32 v244, s4, 8
	s_add_u32 s4, s20, 0x16c80000
	v_writelane_b32 v244, s4, 9
	s_addc_u32 s4, s21, 0
	v_writelane_b32 v244, s4, 13
	s_add_u32 s4, s20, 0x12200000
	s_addc_u32 s92, s21, 0
	s_add_u32 s93, s20, 0x16c00000
	s_mov_b64 s[40:41], 0x80
	v_writelane_b32 v244, s4, 11
	s_addc_u32 s94, s21, 0
	s_and_b32 s4, s1, 3
	s_add_i32 m0, s59, 0x18000
	v_lshl_add_u64 v[6:7], v[6:7], 0, s[40:41]
	s_lshl_b32 s95, s0, 6
	s_lshl_b32 s5, s0, 13
	s_lshl_b32 s96, s4, 5
	s_lshl_b32 s6, s4, 12
	s_waitcnt vmcnt(4)
	s_barrier
	global_load_lds_dwordx4 v[6:7], off
	v_lshl_add_u64 v[4:5], v[4:5], 0, s[40:41]
	s_add_i32 m0, s59, 0x1a000
	s_add_i32 s97, s59, 0x8000
	s_add_i32 s84, s59, 0xa000
	global_load_lds_dwordx4 v[4:5], off
	v_lshl_add_u64 v[2:3], v[2:3], 0, s[40:41]
	s_mov_b32 m0, s97
	s_add_u32 s0, s10, 0x80080
	global_load_lds_dwordx4 v[2:3], off
	v_lshl_add_u64 v[0:1], v[0:1], 0, s[40:41]
	s_mov_b32 m0, s84
	s_addc_u32 s1, s11, 0
	global_load_lds_dwordx4 v[0:1], off
	s_add_i32 m0, s59, 0x1c000
	s_nop 0
	global_load_lds_dwordx4 v130, s[0:1]
	s_add_i32 m0, s59, 0x1e000
	v_bfe_u32 v162, v184, 4, 2
	global_load_lds_dwordx4 v134, s[0:1]
	v_lshlrev_b32_e32 v0, 4, v162
	v_lshlrev_b32_e32 v1, 6, v184
	s_movk_i32 s0, 0x3c0
	v_and_b32_e32 v161, 15, v184
	v_and_or_b32 v1, v1, s0, v0
	v_and_b32_e32 v2, 32, v185
	v_lshl_or_b32 v0, v161, 6, v0
	v_bitop3_b32 v163, s6, v1, v2 bitop3:0xf6
	v_lshlrev_b32_e32 v1, 9, v184
	v_bitop3_b32 v0, v0, s5, v2 bitop3:0xde
	v_and_b32_e32 v1, 0x70000, v1
	v_lshlrev_b32_e32 v2, 12, v10
	v_or3_b32 v1, v8, v1, v2
	v_add_u32_e32 v138, v1, v9
	v_lshlrev_b32_e32 v1, 5, v11
	s_waitcnt vmcnt(6)
	s_cmp_lt_u32 s4, 2
	v_and_b32_e32 v1, 0xf0000, v1
	s_cselect_b64 s[42:43], -1, 0
	v_or3_b32 v1, v8, v1, v2
	s_add_i32 s47, 0, 0x10000
	s_add_i32 s87, 0, 0x14000
	s_mov_b32 s46, s26
	v_mov_b32_e32 v139, v136
	v_add_u32_e32 v140, v1, v9
	v_mov_b32_e32 v141, v136
	v_mov_b64_e32 v[142:143], 0x912
	v_mov_b64_e32 v[144:145], 0x911
	v_add_u32_e32 v164, s47, v163
	v_add_u32_e32 v165, 0, v0
	v_add_u32_e32 v166, s87, v163
	v_mov_b32_e32 v167, 0x358637bd
	s_mov_b32 s88, 0xf800000
	v_mov_b32_e32 v168, 0x260
	s_movk_i32 s89, 0x220
	s_mov_b32 s90, 0x110000
	s_mov_b64 s[44:45], 0x400
	s_movk_i32 s69, 0x400
	v_mov_b32_e32 v169, 0x3e0293ee
	s_mov_b32 s91, 0
	s_barrier
	s_branch .LBB0_520

;     DI size_t aoff(const Unit& u, size_t tstep) const { return (size_t)u.pm * tstep; }
;     DI size_t boff(const Unit& u, size_t tstep) const { return (size_t)u.pn * tstep; }
;     DI bool next(int i, Unit& u) const { const long L = (long)i * G + c; if (L >= np) return false; u.pm = pmv; u.pn = (int)(L % nN); u.ks = (int)(L / nN); return true; }
;     DI size_t aoff(const Unit& u, size_t) const { return (size_t)u.ks * kbytes; }
;     DI size_t boff(const Unit& u, size_t tstep) const { return (size_t)u.pn * tstep + (size_t)u.ks * kbytes; }
;     DI bool next(int i, Unit& u) const { Unit t; if (!S.next(i / 3, t)) return false; u.pm = t.pm; u.pn = t.pn; u.ks = i % 3; return true; }
;     DI size_t aoff(const Unit& u, size_t tstep) const { return (u.ks < 2 ? offU : offOA) + (size_t)u.pm * tstep; }
; #define PG8_LDA(dst, b, h) do { _Pragma("unroll") for (int m = 0; m < 4; ++m) _Pragma("unroll") for (int k = 0; k < 2; ++k) dst[m][k] = *(const LAS bf16x8*)(lds + PG8_SA(b, h) + aoff + m * 2048 + k * 1024); } while (0)
; template <class Epi, class Sched>
; DI void gemm_phase(LAS unsigned char* lds, const Gemm g, const Sched& S, const Epi& E) {
;     ...
;         const bool has_next = S.next(ui + 1, nxt);
;         const char* nA = has_next ? (const char*)g.A + S.aoff(nxt, tstep) : cA; const char* nB = has_next ? (const char*)g.Bt + S.boff(nxt, tstep) : cB;
;         for (int t = 0; t < nt; t += 2) {
;             if constexpr (Epi::HAS_MID) { if (t == E.mid_t(nt)) { int fr3 = fr, fq3 = fq; asm volatile("" : "+v"(fr3), "+v"(fq3)); E.mid(acc, cur, wr, wc, fr3, fq3); } }
;             const bool last = (t == nt - 2);
;             const char* a1 = cA + (size_t)(t + 1) * kstep;
;             const char* a2 = last ? nA : cA + (size_t)(t + 2) * kstep; const char* b2 = last ? nB : cB + (size_t)(t + 2) * kstep;
;             const char* a3 = a2 + kstep; const char* b3 = b2 + kstep;
;             PG8_LDB(B0, 0, 0); PG8_SCHED; PG8_LDA(At, 0, 0); PG8_STAGE(PG8_SA(1, 1), a1 + hstep, voffA);
;             PG8_WAIT_L(8); PG8_BAR; PG8_WAIT_L(0); PG8_MMA(0, 0, At, B0); PG8_BAR; PG8_SCHED;
;             PG8_LDB(B1, 0, 1); PG8_STAGE(PG8_SB(0, 0), b2, voffB);
;             PG8_BAR; PG8_WAIT_L(0); PG8_MMA(0, 1, At, B1); PG8_BAR;
;             PG8_LDA(At, 0, 1); PG8_STAGE(PG8_SA(0, 0), a2, voffA);
;             PG8_BAR; PG8_WAIT_L(0); PG8_MMA(1, 0, At, B0); PG8_BAR; PG8_SCHED;
.LBB0_526:
	s_ashr_i32 s51, s50, 31
	s_lshl_b64 s[0:1], s[50:51], 20
	s_add_u32 s52, s70, s0
	v_cmp_lt_i64_e32 vcc, s[12:13], v[142:143]
	s_addc_u32 s53, s71, s1
	s_and_b64 s[0:1], vcc, exec
	s_cselect_b32 s14, s53, s9
	s_cselect_b32 s15, s52, s8
	s_ashr_i32 s49, s48, 31
	s_lshl_b64 s[0:1], s[48:49], 20
	s_add_u32 s54, s72, s0
	s_addc_u32 s55, s73, s1
	s_and_b64 s[0:1], vcc, exec
	s_cselect_b32 s16, s55, s11
	s_cselect_b32 s17, s54, s10
	s_add_u32 s8, s8, 0x80080
	s_addc_u32 s9, s9, 0
	s_add_u32 s28, s10, 0x100
	v_mov_b32_e32 v0, 0
	s_addc_u32 s34, s11, 0
	s_mov_b32 s35, -2
	ds_read_b128 v[146:149], v164
	ds_read_b128 v[150:153], v164 offset:1024
	ds_read_b128 v[154:157], v164 offset:2048
	ds_read_b128 v[170:173], v164 offset:3072
	s_add_u32 s0, s8, 0xfff80080
	s_addc_u32 s1, s9, -1
	s_cmp_eq_u32 s35, 28
	s_cselect_b32 s13, s14, s1
	s_cselect_b32 s12, s15, s0
	s_cselect_b32 s11, s16, s34
	s_cselect_b32 s10, s17, s28
	s_add_i32 m0, s59, 0xc000
	ds_read_b128 v[174:177], v165
	ds_read_b128 v[178:181], v165 offset:1024
	ds_read_b128 v[188:191], v165 offset:2048
	ds_read_b128 v[194:197], v165 offset:3072
	ds_read_b128 v[198:201], v165 offset:4096
	ds_read_b128 v[202:205], v165 offset:5120
	ds_read_b128 v[206:209], v165 offset:6144
	ds_read_b128 v[210:213], v165 offset:7168
	global_load_lds_dwordx4 v138, s[8:9]
	s_add_i32 m0, s59, 0xe000
	s_nop 0
	global_load_lds_dwordx4 v140, s[8:9]
	s_waitcnt lgkmcnt(8)
	s_barrier
	s_waitcnt lgkmcnt(0)
	s_setprio 1
	s_waitcnt lgkmcnt(0)
	v_mfma_f32_16x16x32_bf16 v[124:127], v[146:149], v[174:177], 0
	v_mfma_f32_16x16x32_bf16 v[120:123], v[154:157], v[174:177], 0
	v_mfma_f32_16x16x32_bf16 v[108:111], v[146:149], v[188:191], 0
	v_mfma_f32_16x16x32_bf16 v[104:107], v[154:157], v[188:191], 0
	v_mfma_f32_16x16x32_bf16 v[92:95], v[146:149], v[198:201], 0
	v_mfma_f32_16x16x32_bf16 v[88:91], v[154:157], v[198:201], 0
	v_mfma_f32_16x16x32_bf16 v[76:79], v[146:149], v[206:209], 0
	v_mfma_f32_16x16x32_bf16 v[72:75], v[154:157], v[206:209], 0
	v_mfma_f32_16x16x32_bf16 v[124:127], v[150:153], v[178:181], v[124:127]
	v_mfma_f32_16x16x32_bf16 v[120:123], v[170:173], v[178:181], v[120:123]
	v_mfma_f32_16x16x32_bf16 v[108:111], v[150:153], v[194:197], v[108:111]
	v_mfma_f32_16x16x32_bf16 v[104:107], v[170:173], v[194:197], v[104:107]
	v_mfma_f32_16x16x32_bf16 v[92:95], v[150:153], v[202:205], v[92:95]
	v_mfma_f32_16x16x32_bf16 v[88:91], v[170:173], v[202:205], v[88:91]
	v_mfma_f32_16x16x32_bf16 v[76:79], v[150:153], v[210:213], v[76:79]
	v_mfma_f32_16x16x32_bf16 v[72:75], v[170:173], v[210:213], v[72:75]
	s_setprio 0
	s_barrier
	s_add_i32 s0, s47, s74
	s_mov_b32 m0, s0
	ds_read_b128 v[214:217], v166
	ds_read_b128 v[218:221], v166 offset:1024
	ds_read_b128 v[222:225], v166 offset:2048
	ds_read_b128 v[226:229], v166 offset:3072
	global_load_lds_dwordx4 v130, s[10:11]
	v_lshl_add_u64 v[182:183], s[10:11], 0, v[134:135]
	s_add_i32 m0, s0, 0x2000
	s_nop 0
	global_load_lds_dwordx4 v134, s[10:11]
	s_barrier
	s_waitcnt lgkmcnt(0)
	s_setprio 1
	s_waitcnt lgkmcnt(0)
	v_mfma_f32_16x16x32_bf16 v[116:119], v[214:217], v[174:177], 0
	v_mfma_f32_16x16x32_bf16 v[112:115], v[222:225], v[174:177], 0
	v_mfma_f32_16x16x32_bf16 v[100:103], v[214:217], v[188:191], 0
	v_mfma_f32_16x16x32_bf16 v[96:99], v[222:225], v[188:191], 0
	v_mfma_f32_16x16x32_bf16 v[84:87], v[214:217], v[198:201], 0
	v_mfma_f32_16x16x32_bf16 v[80:83], v[222:225], v[198:201], 0
	v_mfma_f32_16x16x32_bf16 v[68:71], v[214:217], v[206:209], 0
	v_mfma_f32_16x16x32_bf16 v[64:67], v[222:225], v[206:209], 0
	v_mfma_f32_16x16x32_bf16 v[116:119], v[218:221], v[178:181], v[116:119]
	v_mfma_f32_16x16x32_bf16 v[112:115], v[226:229], v[178:181], v[112:115]
	v_mfma_f32_16x16x32_bf16 v[100:103], v[218:221], v[194:197], v[100:103]
	v_mfma_f32_16x16x32_bf16 v[96:99], v[226:229], v[194:197], v[96:99]
	v_mfma_f32_16x16x32_bf16 v[84:87], v[218:221], v[202:205], v[84:87]
	v_mfma_f32_16x16x32_bf16 v[80:83], v[226:229], v[202:205], v[80:83]
	v_mfma_f32_16x16x32_bf16 v[68:71], v[218:221], v[210:213], v[68:71]
	v_mfma_f32_16x16x32_bf16 v[64:67], v[226:229], v[210:213], v[64:67]
	s_setprio 0
	s_mov_b32 m0, s59
	s_barrier
	ds_read_b128 v[174:177], v165 offset:16384
	ds_read_b128 v[178:181], v165 offset:17408
	ds_read_b128 v[188:191], v165 offset:18432
	ds_read_b128 v[194:197], v165 offset:19456
	ds_read_b128 v[198:201], v165 offset:20480
	ds_read_b128 v[202:205], v165 offset:21504
	ds_read_b128 v[206:209], v165 offset:22528
	ds_read_b128 v[210:213], v165 offset:23552
	global_load_lds_dwordx4 v128, s[12:13]
	v_lshl_add_u64 v[232:233], s[12:13], 0, v[132:133]
	s_mov_b32 m0, s75
	s_nop 0
	global_load_lds_dwordx4 v132, s[12:13]
	s_barrier
	s_waitcnt lgkmcnt(0)
	s_setprio 1
	s_waitcnt lgkmcnt(0)
	v_mfma_f32_16x16x32_bf16 v[60:63], v[146:149], v[174:177], 0
	v_mfma_f32_16x16x32_bf16 v[56:59], v[154:157], v[174:177], 0
	v_mfma_f32_16x16x32_bf16 v[44:47], v[146:149], v[188:191], 0
	v_mfma_f32_16x16x32_bf16 v[40:43], v[154:157], v[188:191], 0
	v_mfma_f32_16x16x32_bf16 v[28:31], v[146:149], v[198:201], 0
	v_mfma_f32_16x16x32_bf16 v[24:27], v[154:157], v[198:201], 0
	v_mfma_f32_16x16x32_bf16 v[12:15], v[146:149], v[206:209], 0
	v_mfma_f32_16x16x32_bf16 v[8:11], v[154:157], v[206:209], 0
	v_mfma_f32_16x16x32_bf16 v[60:63], v[150:153], v[178:181], v[60:63]
	v_mfma_f32_16x16x32_bf16 v[56:59], v[170:173], v[178:181], v[56:59]
	v_mfma_f32_16x16x32_bf16 v[44:47], v[150:153], v[194:197], v[44:47]
	v_mfma_f32_16x16x32_bf16 v[40:43], v[170:173], v[194:197], v[40:43]
	v_mfma_f32_16x16x32_bf16 v[28:31], v[150:153], v[202:205], v[28:31]
	v_mfma_f32_16x16x32_bf16 v[24:27], v[170:173], v[202:205], v[24:27]
	v_mfma_f32_16x16x32_bf16 v[12:15], v[150:153], v[210:213], v[12:15]
	v_mfma_f32_16x16x32_bf16 v[8:11], v[170:173], v[210:213], v[8:11]
	s_setprio 0
	s_barrier
; #define PG8_STAGE(bufoff, gbase, voff) do { _Pragma("unroll") for (int _i = 0; _i < 2; ++_i) \
;         __builtin_amdgcn_global_load_lds((const unsigned*)((const char*)(gbase) + (voff)[_i]), (LAS unsigned*)(lds + (bufoff) + ldsw + _i * 8192), 16, 0, 0); } while (0)
; #define PG8_LDA(dst, b, h) do { _Pragma("unroll") for (int m = 0; m < 4; ++m) _Pragma("unroll") for (int k = 0; k < 2; ++k) dst[m][k] = *(const LAS bf16x8*)(lds + PG8_SA(b, h) + aoff + m * 2048 + k * 1024); } while (0)
; #define PG8_LDB(dst, b, h) do { _Pragma("unroll") for (int n = 0; n < 2; ++n) _Pragma("unroll") for (int k = 0; k < 2; ++k) dst[n][k] = *(const LAS bf16x8*)(lds + PG8_SB(b, h) + boff + n * 2048 + k * 1024); } while (0)
; #define PG8_WAIT_V(n) asm volatile("s_waitcnt vmcnt(" #n ")" ::: "memory")
; #define PG8_WAIT_L(n) asm volatile("s_waitcnt lgkmcnt(" #n ")" ::: "memory")
; #define PG8_BAR __builtin_amdgcn_s_barrier()
; #define PG8_SCHED __builtin_amdgcn_sched_barrier(0)
; template <class Epi, class Sched>
; DI void gemm_phase(LAS unsigned char* lds, const Gemm g, const Sched& S, const Epi& E) {
;     ...
;             PG8_LDB(B0, 0, 0); PG8_SCHED; PG8_LDA(At, 0, 0); PG8_STAGE(PG8_SA(1, 1), a1 + hstep, voffA);
;             PG8_WAIT_L(8); PG8_BAR; PG8_WAIT_L(0); PG8_MMA(0, 0, At, B0); PG8_BAR; PG8_SCHED;
;             PG8_LDB(B1, 0, 1); PG8_STAGE(PG8_SB(0, 0), b2, voffB);
;             PG8_BAR; PG8_WAIT_L(0); PG8_MMA(0, 1, At, B1); PG8_BAR;
;             PG8_LDA(At, 0, 1); PG8_STAGE(PG8_SA(0, 0), a2, voffA);
;             PG8_BAR; PG8_WAIT_L(0); PG8_MMA(1, 0, At, B0); PG8_BAR; PG8_SCHED;
;             PG8_STAGE(PG8_SB(0, 1), b2 + hstep, voffB);
;             PG8_WAIT_V(6); PG8_BAR; PG8_MMA(1, 1, At, B1); PG8_BAR;
;             PG8_LDB(B0, 1, 0); PG8_SCHED; PG8_LDA(At, 1, 0); PG8_STAGE(PG8_SA(0, 1), a2 + hstep, voffA);
;             PG8_WAIT_L(8); PG8_BAR; PG8_WAIT_L(0); PG8_MMA(0, 0, At, B0); PG8_BAR; PG8_SCHED;
;             PG8_LDB(B1, 1, 1); PG8_STAGE(PG8_SB(1, 0), b3, voffB);
;             PG8_BAR; PG8_WAIT_L(0); PG8_MMA(0, 1, At, B1); PG8_BAR;
;             PG8_LDA(At, 1, 1); PG8_STAGE(PG8_SA(1, 0), a3, voffA);
;             PG8_BAR; PG8_WAIT_L(0); PG8_MMA(1, 0, At, B0); PG8_BAR; PG8_SCHED;
;             PG8_STAGE(PG8_SB(1, 1), b3 + hstep, voffB);
;             PG8_WAIT_V(6); PG8_BAR; PG8_MMA(1, 1, At, B1); PG8_BAR;
	s_add_u32 s0, s10, 0x80000
	s_addc_u32 s1, s11, 0
	s_add_i32 s4, s87, s74
	s_mov_b32 m0, s4
	s_nop 0
	global_load_lds_dwordx4 v130, s[0:1]
	s_add_i32 m0, s4, 0x2000
	s_nop 0
	global_load_lds_dwordx4 v134, s[0:1]
	s_waitcnt vmcnt(6)
	s_barrier
	s_setprio 1
	v_mfma_f32_16x16x32_bf16 v[52:55], v[214:217], v[174:177], 0
	v_mfma_f32_16x16x32_bf16 v[48:51], v[222:225], v[174:177], 0
	v_mfma_f32_16x16x32_bf16 v[36:39], v[214:217], v[188:191], 0
	v_mfma_f32_16x16x32_bf16 v[32:35], v[222:225], v[188:191], 0
	v_mfma_f32_16x16x32_bf16 v[20:23], v[214:217], v[198:201], 0
	v_mfma_f32_16x16x32_bf16 v[16:19], v[222:225], v[198:201], 0
	v_mfma_f32_16x16x32_bf16 v[4:7], v[214:217], v[206:209], 0
	v_mfma_f32_16x16x32_bf16 v[0:3], v[222:225], v[206:209], 0
	v_mfma_f32_16x16x32_bf16 v[52:55], v[218:221], v[178:181], v[52:55]
	v_mfma_f32_16x16x32_bf16 v[48:51], v[226:229], v[178:181], v[48:51]
	v_mfma_f32_16x16x32_bf16 v[36:39], v[218:221], v[194:197], v[36:39]
	v_mfma_f32_16x16x32_bf16 v[32:35], v[226:229], v[194:197], v[32:35]
	v_mfma_f32_16x16x32_bf16 v[20:23], v[218:221], v[202:205], v[20:23]
	v_mfma_f32_16x16x32_bf16 v[16:19], v[226:229], v[202:205], v[16:19]
	v_mfma_f32_16x16x32_bf16 v[4:7], v[218:221], v[210:213], v[4:7]
	v_mfma_f32_16x16x32_bf16 v[0:3], v[226:229], v[210:213], v[0:3]
	s_setprio 0
	s_add_i32 s4, 0, 0x18000
	v_add_u32_e32 v137, s4, v163
	s_barrier
	ds_read_b128 v[146:149], v137
	ds_read_b128 v[150:153], v137 offset:1024
	ds_read_b128 v[154:157], v137 offset:2048
	ds_read_b128 v[170:173], v137 offset:3072
	s_add_u32 s0, s12, 0x80000
	s_addc_u32 s1, s13, 0
	s_mov_b32 m0, s76
	ds_read_b128 v[174:177], v165 offset:32768
	ds_read_b128 v[178:181], v165 offset:33792
	ds_read_b128 v[188:191], v165 offset:34816
	ds_read_b128 v[194:197], v165 offset:35840
	ds_read_b128 v[198:201], v165 offset:36864
	ds_read_b128 v[202:205], v165 offset:37888
	ds_read_b128 v[206:209], v165 offset:38912
	ds_read_b128 v[210:213], v165 offset:39936
	global_load_lds_dwordx4 v128, s[0:1]
	s_mov_b32 m0, s77
	s_nop 0
	global_load_lds_dwordx4 v132, s[0:1]
	s_waitcnt lgkmcnt(8)
	s_barrier
	s_waitcnt lgkmcnt(0)
	s_setprio 1
	s_waitcnt lgkmcnt(0)
	v_mfma_f32_16x16x32_bf16 v[124:127], v[146:149], v[174:177], v[124:127]
	v_mfma_f32_16x16x32_bf16 v[120:123], v[154:157], v[174:177], v[120:123]
	v_mfma_f32_16x16x32_bf16 v[108:111], v[146:149], v[188:191], v[108:111]
	v_mfma_f32_16x16x32_bf16 v[104:107], v[154:157], v[188:191], v[104:107]
	v_mfma_f32_16x16x32_bf16 v[92:95], v[146:149], v[198:201], v[92:95]
	v_mfma_f32_16x16x32_bf16 v[88:91], v[154:157], v[198:201], v[88:91]
	v_mfma_f32_16x16x32_bf16 v[76:79], v[146:149], v[206:209], v[76:79]
	v_mfma_f32_16x16x32_bf16 v[72:75], v[154:157], v[206:209], v[72:75]
	v_mfma_f32_16x16x32_bf16 v[124:127], v[150:153], v[178:181], v[124:127]
	v_mfma_f32_16x16x32_bf16 v[120:123], v[170:173], v[178:181], v[120:123]
	v_mfma_f32_16x16x32_bf16 v[108:111], v[150:153], v[194:197], v[108:111]
	v_mfma_f32_16x16x32_bf16 v[104:107], v[170:173], v[194:197], v[104:107]
	v_mfma_f32_16x16x32_bf16 v[92:95], v[150:153], v[202:205], v[92:95]
	v_mfma_f32_16x16x32_bf16 v[88:91], v[170:173], v[202:205], v[88:91]
	v_mfma_f32_16x16x32_bf16 v[76:79], v[150:153], v[210:213], v[76:79]
	v_mfma_f32_16x16x32_bf16 v[72:75], v[170:173], v[210:213], v[72:75]
	s_setprio 0
	s_barrier
	s_add_i32 s5, 0, 0x1c000
	s_add_i32 s0, s4, s74
	v_add_u32_e32 v137, s5, v163
	s_add_i32 m0, s0, 0xffffff80
	ds_read_b128 v[214:217], v137
	ds_read_b128 v[218:221], v137 offset:1024
	ds_read_b128 v[222:225], v137 offset:2048
	ds_read_b128 v[226:229], v137 offset:3072
	global_load_lds_dwordx4 v130, s[10:11] offset:128
	s_add_i32 m0, s0, 0x1f80
	s_nop 0
	global_load_lds_dwordx4 v134, s[10:11] offset:128
	s_barrier
	s_waitcnt lgkmcnt(0)
	s_setprio 1
	s_waitcnt lgkmcnt(0)
	v_mfma_f32_16x16x32_bf16 v[116:119], v[214:217], v[174:177], v[116:119]
	v_mfma_f32_16x16x32_bf16 v[112:115], v[222:225], v[174:177], v[112:115]
	v_mfma_f32_16x16x32_bf16 v[100:103], v[214:217], v[188:191], v[100:103]
	v_mfma_f32_16x16x32_bf16 v[96:99], v[222:225], v[188:191], v[96:99]
	v_mfma_f32_16x16x32_bf16 v[84:87], v[214:217], v[198:201], v[84:87]
	v_mfma_f32_16x16x32_bf16 v[80:83], v[222:225], v[198:201], v[80:83]
	v_mfma_f32_16x16x32_bf16 v[68:71], v[214:217], v[206:209], v[68:71]
	v_mfma_f32_16x16x32_bf16 v[64:67], v[222:225], v[206:209], v[64:67]
	v_mfma_f32_16x16x32_bf16 v[116:119], v[218:221], v[178:181], v[116:119]
	v_mfma_f32_16x16x32_bf16 v[112:115], v[226:229], v[178:181], v[112:115]
	v_mfma_f32_16x16x32_bf16 v[100:103], v[218:221], v[194:197], v[100:103]
	v_mfma_f32_16x16x32_bf16 v[96:99], v[226:229], v[194:197], v[96:99]
	v_mfma_f32_16x16x32_bf16 v[84:87], v[218:221], v[202:205], v[84:87]
	v_mfma_f32_16x16x32_bf16 v[80:83], v[226:229], v[202:205], v[80:83]
	v_mfma_f32_16x16x32_bf16 v[68:71], v[218:221], v[210:213], v[68:71]
	v_mfma_f32_16x16x32_bf16 v[64:67], v[226:229], v[210:213], v[64:67]
	s_setprio 0
	s_add_i32 m0, s97, 0xffffff80
	s_barrier
	ds_read_b128 v[174:177], v165 offset:49152
	ds_read_b128 v[178:181], v165 offset:50176
	ds_read_b128 v[188:191], v165 offset:51200
	ds_read_b128 v[194:197], v165 offset:52224
	ds_read_b128 v[198:201], v165 offset:53248
	ds_read_b128 v[202:205], v165 offset:54272
	ds_read_b128 v[206:209], v165 offset:55296
	ds_read_b128 v[210:213], v165 offset:56320
	global_load_lds_dwordx4 v128, s[12:13] offset:128
	v_lshl_add_u64 v[158:159], v[232:233], 0, s[40:41]
	s_add_i32 m0, s84, 0xffffff80
	s_nop 0
	global_load_lds_dwordx4 v132, s[12:13] offset:128
	s_barrier
; #define PG8_STAGE(bufoff, gbase, voff) do { _Pragma("unroll") for (int _i = 0; _i < 2; ++_i) \
;         __builtin_amdgcn_global_load_lds((const unsigned*)((const char*)(gbase) + (voff)[_i]), (LAS unsigned*)(lds + (bufoff) + ldsw + _i * 8192), 16, 0, 0); } while (0)
; #define PG8_LDA(dst, b, h) do { _Pragma("unroll") for (int m = 0; m < 4; ++m) _Pragma("unroll") for (int k = 0; k < 2; ++k) dst[m][k] = *(const LAS bf16x8*)(lds + PG8_SA(b, h) + aoff + m * 2048 + k * 1024); } while (0)
; #define PG8_LDB(dst, b, h) do { _Pragma("unroll") for (int n = 0; n < 2; ++n) _Pragma("unroll") for (int k = 0; k < 2; ++k) dst[n][k] = *(const LAS bf16x8*)(lds + PG8_SB(b, h) + boff + n * 2048 + k * 1024); } while (0)
; #define PG8_WAIT_V(n) asm volatile("s_waitcnt vmcnt(" #n ")" ::: "memory")
; #define PG8_WAIT_L(n) asm volatile("s_waitcnt lgkmcnt(" #n ")" ::: "memory")
; #define PG8_BAR __builtin_amdgcn_s_barrier()
; #define PG8_SCHED __builtin_amdgcn_sched_barrier(0)
; template <class Epi, class Sched>
; DI void gemm_phase(LAS unsigned char* lds, const Gemm g, const Sched& S, const Epi& E) {
;     ...
;             PG8_LDB(B0, 0, 0); PG8_SCHED; PG8_LDA(At, 0, 0); PG8_STAGE(PG8_SA(1, 1), a1 + hstep, voffA);
;             PG8_WAIT_L(8); PG8_BAR; PG8_WAIT_L(0); PG8_MMA(0, 0, At, B0); PG8_BAR; PG8_SCHED;
;             PG8_LDB(B1, 0, 1); PG8_STAGE(PG8_SB(0, 0), b2, voffB);
;             PG8_BAR; PG8_WAIT_L(0); PG8_MMA(0, 1, At, B1); PG8_BAR;
;             PG8_LDA(At, 0, 1); PG8_STAGE(PG8_SA(0, 0), a2, voffA);
;             PG8_BAR; PG8_WAIT_L(0); PG8_MMA(1, 0, At, B0); PG8_BAR; PG8_SCHED;
;             PG8_STAGE(PG8_SB(0, 1), b2 + hstep, voffB);
;             PG8_WAIT_V(6); PG8_BAR; PG8_MMA(1, 1, At, B1); PG8_BAR;
;             PG8_LDB(B0, 1, 0); PG8_SCHED; PG8_LDA(At, 1, 0); PG8_STAGE(PG8_SA(0, 1), a2 + hstep, voffA);
;             PG8_WAIT_L(8); PG8_BAR; PG8_WAIT_L(0); PG8_MMA(0, 0, At, B0); PG8_BAR; PG8_SCHED;
;             PG8_LDB(B1, 1, 1); PG8_STAGE(PG8_SB(1, 0), b3, voffB);
;             PG8_BAR; PG8_WAIT_L(0); PG8_MMA(0, 1, At, B1); PG8_BAR;
;             PG8_LDA(At, 1, 1); PG8_STAGE(PG8_SA(1, 0), a3, voffA);
;             PG8_BAR; PG8_WAIT_L(0); PG8_MMA(1, 0, At, B0); PG8_BAR; PG8_SCHED;
;             PG8_STAGE(PG8_SB(1, 1), b3 + hstep, voffB);
;             PG8_WAIT_V(6); PG8_BAR; PG8_MMA(1, 1, At, B1); PG8_BAR;
	s_waitcnt lgkmcnt(0)
	s_setprio 1
	s_waitcnt lgkmcnt(0)
	v_mfma_f32_16x16x32_bf16 v[60:63], v[146:149], v[174:177], v[60:63]
	v_mfma_f32_16x16x32_bf16 v[56:59], v[154:157], v[174:177], v[56:59]
	v_mfma_f32_16x16x32_bf16 v[44:47], v[146:149], v[188:191], v[44:47]
	v_mfma_f32_16x16x32_bf16 v[40:43], v[154:157], v[188:191], v[40:43]
	v_mfma_f32_16x16x32_bf16 v[28:31], v[146:149], v[198:201], v[28:31]
	v_mfma_f32_16x16x32_bf16 v[24:27], v[154:157], v[198:201], v[24:27]
	v_mfma_f32_16x16x32_bf16 v[12:15], v[146:149], v[206:209], v[12:15]
	v_mfma_f32_16x16x32_bf16 v[8:11], v[154:157], v[206:209], v[8:11]
	v_mfma_f32_16x16x32_bf16 v[60:63], v[150:153], v[178:181], v[60:63]
	v_mfma_f32_16x16x32_bf16 v[56:59], v[170:173], v[178:181], v[56:59]
	v_mfma_f32_16x16x32_bf16 v[44:47], v[150:153], v[194:197], v[44:47]
	v_mfma_f32_16x16x32_bf16 v[40:43], v[170:173], v[194:197], v[40:43]
	v_mfma_f32_16x16x32_bf16 v[28:31], v[150:153], v[202:205], v[28:31]
	v_mfma_f32_16x16x32_bf16 v[24:27], v[170:173], v[202:205], v[24:27]
	v_mfma_f32_16x16x32_bf16 v[12:15], v[150:153], v[210:213], v[12:15]
	v_mfma_f32_16x16x32_bf16 v[8:11], v[170:173], v[210:213], v[8:11]
	s_setprio 0
	s_barrier
	s_add_u32 s0, s10, 0x80080
	s_addc_u32 s1, s11, 0
	s_add_i32 s4, s5, s74
	s_mov_b32 m0, s4
	s_nop 0
	global_load_lds_dwordx4 v130, s[0:1]
	v_lshl_add_u64 v[146:147], s[0:1], 0, v[134:135]
	s_add_i32 m0, s4, 0x2000
	s_nop 0
	global_load_lds_dwordx4 v134, s[0:1]
	s_waitcnt vmcnt(6)
	s_barrier
	s_setprio 1
	v_mfma_f32_16x16x32_bf16 v[52:55], v[214:217], v[174:177], v[52:55]
	v_mfma_f32_16x16x32_bf16 v[48:51], v[222:225], v[174:177], v[48:51]
	v_mfma_f32_16x16x32_bf16 v[36:39], v[214:217], v[188:191], v[36:39]
	v_mfma_f32_16x16x32_bf16 v[32:35], v[222:225], v[188:191], v[32:35]
	v_mfma_f32_16x16x32_bf16 v[20:23], v[214:217], v[198:201], v[20:23]
	v_mfma_f32_16x16x32_bf16 v[16:19], v[222:225], v[198:201], v[16:19]
	v_mfma_f32_16x16x32_bf16 v[4:7], v[214:217], v[206:209], v[4:7]
	v_mfma_f32_16x16x32_bf16 v[0:3], v[222:225], v[206:209], v[0:3]
	v_mfma_f32_16x16x32_bf16 v[52:55], v[218:221], v[178:181], v[52:55]
	v_mfma_f32_16x16x32_bf16 v[48:51], v[226:229], v[178:181], v[48:51]
	v_mfma_f32_16x16x32_bf16 v[36:39], v[218:221], v[194:197], v[36:39]
	v_mfma_f32_16x16x32_bf16 v[32:35], v[226:229], v[194:197], v[32:35]
	v_mfma_f32_16x16x32_bf16 v[20:23], v[218:221], v[202:205], v[20:23]
	v_mfma_f32_16x16x32_bf16 v[16:19], v[226:229], v[202:205], v[16:19]
	v_mfma_f32_16x16x32_bf16 v[4:7], v[218:221], v[210:213], v[4:7]
	v_mfma_f32_16x16x32_bf16 v[0:3], v[226:229], v[210:213], v[0:3]
	s_setprio 0
	s_add_i32 s35, s35, 2
	s_add_u32 s8, s8, 0x100
	s_addc_u32 s9, s9, 0
	s_add_u32 s28, s28, 0x100
	s_addc_u32 s34, s34, 0
	s_cmp_gt_u32 s35, 29
	s_barrier
	s_cbranch_scc0 .LBB0_527
	s_branch .Lpeel_done_527
.LBB0_527:
	ds_read_b128 v[146:149], v164
	ds_read_b128 v[150:153], v164 offset:1024
	ds_read_b128 v[154:157], v164 offset:2048
	ds_read_b128 v[170:173], v164 offset:3072
	s_add_u32 s0, s8, 0xfff80080
	s_addc_u32 s1, s9, -1
	s_cmp_eq_u32 s35, 28
	s_cselect_b32 s13, s14, s1
	s_cselect_b32 s12, s15, s0
	s_cselect_b32 s11, s16, s34
	s_cselect_b32 s10, s17, s28
	s_add_i32 m0, s59, 0xc000
	ds_read_b128 v[174:177], v165
	ds_read_b128 v[178:181], v165 offset:1024
	ds_read_b128 v[188:191], v165 offset:2048
	ds_read_b128 v[194:197], v165 offset:3072
	ds_read_b128 v[198:201], v165 offset:4096
	ds_read_b128 v[202:205], v165 offset:5120
	ds_read_b128 v[206:209], v165 offset:6144
	ds_read_b128 v[210:213], v165 offset:7168
	global_load_lds_dwordx4 v138, s[8:9]
	s_add_i32 m0, s59, 0xe000
	s_nop 0
	global_load_lds_dwordx4 v140, s[8:9]
	s_waitcnt lgkmcnt(8)
	s_barrier
	s_waitcnt lgkmcnt(0)
	s_setprio 1
	s_waitcnt lgkmcnt(0)
	v_mfma_f32_16x16x32_bf16 v[124:127], v[146:149], v[174:177], v[124:127]
	v_mfma_f32_16x16x32_bf16 v[120:123], v[154:157], v[174:177], v[120:123]
	v_mfma_f32_16x16x32_bf16 v[108:111], v[146:149], v[188:191], v[108:111]
	v_mfma_f32_16x16x32_bf16 v[104:107], v[154:157], v[188:191], v[104:107]
	v_mfma_f32_16x16x32_bf16 v[92:95], v[146:149], v[198:201], v[92:95]
	v_mfma_f32_16x16x32_bf16 v[88:91], v[154:157], v[198:201], v[88:91]
	v_mfma_f32_16x16x32_bf16 v[76:79], v[146:149], v[206:209], v[76:79]
	v_mfma_f32_16x16x32_bf16 v[72:75], v[154:157], v[206:209], v[72:75]
	v_mfma_f32_16x16x32_bf16 v[124:127], v[150:153], v[178:181], v[124:127]
	v_mfma_f32_16x16x32_bf16 v[120:123], v[170:173], v[178:181], v[120:123]
	v_mfma_f32_16x16x32_bf16 v[108:111], v[150:153], v[194:197], v[108:111]
	v_mfma_f32_16x16x32_bf16 v[104:107], v[170:173], v[194:197], v[104:107]
	v_mfma_f32_16x16x32_bf16 v[92:95], v[150:153], v[202:205], v[92:95]
	v_mfma_f32_16x16x32_bf16 v[88:91], v[170:173], v[202:205], v[88:91]
	v_mfma_f32_16x16x32_bf16 v[76:79], v[150:153], v[210:213], v[76:79]
	v_mfma_f32_16x16x32_bf16 v[72:75], v[170:173], v[210:213], v[72:75]
	s_setprio 0
	s_barrier
	s_add_i32 s0, s47, s74
	s_mov_b32 m0, s0
	ds_read_b128 v[214:217], v166
	ds_read_b128 v[218:221], v166 offset:1024
	ds_read_b128 v[222:225], v166 offset:2048
	ds_read_b128 v[226:229], v166 offset:3072
	global_load_lds_dwordx4 v130, s[10:11]
	v_lshl_add_u64 v[182:183], s[10:11], 0, v[134:135]
	s_add_i32 m0, s0, 0x2000
	s_nop 0
	global_load_lds_dwordx4 v134, s[10:11]
	s_barrier
; #define PG8_STAGE(bufoff, gbase, voff) do { _Pragma("unroll") for (int _i = 0; _i < 2; ++_i) \
;         __builtin_amdgcn_global_load_lds((const unsigned*)((const char*)(gbase) + (voff)[_i]), (LAS unsigned*)(lds + (bufoff) + ldsw + _i * 8192), 16, 0, 0); } while (0)
; #define PG8_LDA(dst, b, h) do { _Pragma("unroll") for (int m = 0; m < 4; ++m) _Pragma("unroll") for (int k = 0; k < 2; ++k) dst[m][k] = *(const LAS bf16x8*)(lds + PG8_SA(b, h) + aoff + m * 2048 + k * 1024); } while (0)
; #define PG8_LDB(dst, b, h) do { _Pragma("unroll") for (int n = 0; n < 2; ++n) _Pragma("unroll") for (int k = 0; k < 2; ++k) dst[n][k] = *(const LAS bf16x8*)(lds + PG8_SB(b, h) + boff + n * 2048 + k * 1024); } while (0)
; #define PG8_WAIT_V(n) asm volatile("s_waitcnt vmcnt(" #n ")" ::: "memory")
; #define PG8_WAIT_L(n) asm volatile("s_waitcnt lgkmcnt(" #n ")" ::: "memory")
; #define PG8_BAR __builtin_amdgcn_s_barrier()
; #define PG8_SCHED __builtin_amdgcn_sched_barrier(0)
; template <class Epi, class Sched>
; DI void gemm_phase(LAS unsigned char* lds, const Gemm g, const Sched& S, const Epi& E) {
;     ...
;             PG8_LDB(B0, 0, 0); PG8_SCHED; PG8_LDA(At, 0, 0); PG8_STAGE(PG8_SA(1, 1), a1 + hstep, voffA);
;             PG8_WAIT_L(8); PG8_BAR; PG8_WAIT_L(0); PG8_MMA(0, 0, At, B0); PG8_BAR; PG8_SCHED;
;             PG8_LDB(B1, 0, 1); PG8_STAGE(PG8_SB(0, 0), b2, voffB);
;             PG8_BAR; PG8_WAIT_L(0); PG8_MMA(0, 1, At, B1); PG8_BAR;
;             PG8_LDA(At, 0, 1); PG8_STAGE(PG8_SA(0, 0), a2, voffA);
;             PG8_BAR; PG8_WAIT_L(0); PG8_MMA(1, 0, At, B0); PG8_BAR; PG8_SCHED;
;             PG8_STAGE(PG8_SB(0, 1), b2 + hstep, voffB);
;             PG8_WAIT_V(6); PG8_BAR; PG8_MMA(1, 1, At, B1); PG8_BAR;
;             PG8_LDB(B0, 1, 0); PG8_SCHED; PG8_LDA(At, 1, 0); PG8_STAGE(PG8_SA(0, 1), a2 + hstep, voffA);
;             PG8_WAIT_L(8); PG8_BAR; PG8_WAIT_L(0); PG8_MMA(0, 0, At, B0); PG8_BAR; PG8_SCHED;
;             PG8_LDB(B1, 1, 1); PG8_STAGE(PG8_SB(1, 0), b3, voffB);
;             PG8_BAR; PG8_WAIT_L(0); PG8_MMA(0, 1, At, B1); PG8_BAR;
;             PG8_LDA(At, 1, 1); PG8_STAGE(PG8_SA(1, 0), a3, voffA);
;             PG8_BAR; PG8_WAIT_L(0); PG8_MMA(1, 0, At, B0); PG8_BAR; PG8_SCHED;
;             PG8_STAGE(PG8_SB(1, 1), b3 + hstep, voffB);
;             PG8_WAIT_V(6); PG8_BAR; PG8_MMA(1, 1, At, B1); PG8_BAR;
	s_waitcnt lgkmcnt(0)
	s_setprio 1
	s_waitcnt lgkmcnt(0)
	v_mfma_f32_16x16x32_bf16 v[116:119], v[214:217], v[174:177], v[116:119]
	v_mfma_f32_16x16x32_bf16 v[112:115], v[222:225], v[174:177], v[112:115]
	v_mfma_f32_16x16x32_bf16 v[100:103], v[214:217], v[188:191], v[100:103]
	v_mfma_f32_16x16x32_bf16 v[96:99], v[222:225], v[188:191], v[96:99]
	v_mfma_f32_16x16x32_bf16 v[84:87], v[214:217], v[198:201], v[84:87]
	v_mfma_f32_16x16x32_bf16 v[80:83], v[222:225], v[198:201], v[80:83]
	v_mfma_f32_16x16x32_bf16 v[68:71], v[214:217], v[206:209], v[68:71]
	v_mfma_f32_16x16x32_bf16 v[64:67], v[222:225], v[206:209], v[64:67]
	v_mfma_f32_16x16x32_bf16 v[116:119], v[218:221], v[178:181], v[116:119]
	v_mfma_f32_16x16x32_bf16 v[112:115], v[226:229], v[178:181], v[112:115]
	v_mfma_f32_16x16x32_bf16 v[100:103], v[218:221], v[194:197], v[100:103]
	v_mfma_f32_16x16x32_bf16 v[96:99], v[226:229], v[194:197], v[96:99]
	v_mfma_f32_16x16x32_bf16 v[84:87], v[218:221], v[202:205], v[84:87]
	v_mfma_f32_16x16x32_bf16 v[80:83], v[226:229], v[202:205], v[80:83]
	v_mfma_f32_16x16x32_bf16 v[68:71], v[218:221], v[210:213], v[68:71]
	v_mfma_f32_16x16x32_bf16 v[64:67], v[226:229], v[210:213], v[64:67]
	s_setprio 0
	s_mov_b32 m0, s59
	s_barrier
	ds_read_b128 v[174:177], v165 offset:16384
	ds_read_b128 v[178:181], v165 offset:17408
	ds_read_b128 v[188:191], v165 offset:18432
	ds_read_b128 v[194:197], v165 offset:19456
	ds_read_b128 v[198:201], v165 offset:20480
	ds_read_b128 v[202:205], v165 offset:21504
	ds_read_b128 v[206:209], v165 offset:22528
	ds_read_b128 v[210:213], v165 offset:23552
	global_load_lds_dwordx4 v128, s[12:13]
	v_lshl_add_u64 v[232:233], s[12:13], 0, v[132:133]
	s_mov_b32 m0, s75
	s_nop 0
	global_load_lds_dwordx4 v132, s[12:13]
	s_barrier
	s_waitcnt lgkmcnt(0)
	s_setprio 1
	s_waitcnt lgkmcnt(0)
	v_mfma_f32_16x16x32_bf16 v[60:63], v[146:149], v[174:177], v[60:63]
	v_mfma_f32_16x16x32_bf16 v[56:59], v[154:157], v[174:177], v[56:59]
	v_mfma_f32_16x16x32_bf16 v[44:47], v[146:149], v[188:191], v[44:47]
	v_mfma_f32_16x16x32_bf16 v[40:43], v[154:157], v[188:191], v[40:43]
	v_mfma_f32_16x16x32_bf16 v[28:31], v[146:149], v[198:201], v[28:31]
	v_mfma_f32_16x16x32_bf16 v[24:27], v[154:157], v[198:201], v[24:27]
	v_mfma_f32_16x16x32_bf16 v[12:15], v[146:149], v[206:209], v[12:15]
	v_mfma_f32_16x16x32_bf16 v[8:11], v[154:157], v[206:209], v[8:11]
	v_mfma_f32_16x16x32_bf16 v[60:63], v[150:153], v[178:181], v[60:63]
	v_mfma_f32_16x16x32_bf16 v[56:59], v[170:173], v[178:181], v[56:59]
	v_mfma_f32_16x16x32_bf16 v[44:47], v[150:153], v[194:197], v[44:47]
	v_mfma_f32_16x16x32_bf16 v[40:43], v[170:173], v[194:197], v[40:43]
	v_mfma_f32_16x16x32_bf16 v[28:31], v[150:153], v[202:205], v[28:31]
	v_mfma_f32_16x16x32_bf16 v[24:27], v[170:173], v[202:205], v[24:27]
	v_mfma_f32_16x16x32_bf16 v[12:15], v[150:153], v[210:213], v[12:15]
	v_mfma_f32_16x16x32_bf16 v[8:11], v[170:173], v[210:213], v[8:11]
	s_setprio 0
	s_barrier
	s_add_u32 s0, s10, 0x80000
	s_addc_u32 s1, s11, 0
	s_add_i32 s4, s87, s74
	s_mov_b32 m0, s4
	s_nop 0
	global_load_lds_dwordx4 v130, s[0:1]
	s_add_i32 m0, s4, 0x2000
	s_nop 0
	global_load_lds_dwordx4 v134, s[0:1]
	s_waitcnt vmcnt(6)
	s_barrier
	s_setprio 1
	v_mfma_f32_16x16x32_bf16 v[52:55], v[214:217], v[174:177], v[52:55]
	v_mfma_f32_16x16x32_bf16 v[48:51], v[222:225], v[174:177], v[48:51]
	v_mfma_f32_16x16x32_bf16 v[36:39], v[214:217], v[188:191], v[36:39]
	v_mfma_f32_16x16x32_bf16 v[32:35], v[222:225], v[188:191], v[32:35]
	v_mfma_f32_16x16x32_bf16 v[20:23], v[214:217], v[198:201], v[20:23]
	v_mfma_f32_16x16x32_bf16 v[16:19], v[222:225], v[198:201], v[16:19]
	v_mfma_f32_16x16x32_bf16 v[4:7], v[214:217], v[206:209], v[4:7]
	v_mfma_f32_16x16x32_bf16 v[0:3], v[222:225], v[206:209], v[0:3]
	v_mfma_f32_16x16x32_bf16 v[52:55], v[218:221], v[178:181], v[52:55]
	v_mfma_f32_16x16x32_bf16 v[48:51], v[226:229], v[178:181], v[48:51]
	v_mfma_f32_16x16x32_bf16 v[36:39], v[218:221], v[194:197], v[36:39]
	v_mfma_f32_16x16x32_bf16 v[32:35], v[226:229], v[194:197], v[32:35]
	v_mfma_f32_16x16x32_bf16 v[20:23], v[218:221], v[202:205], v[20:23]
	v_mfma_f32_16x16x32_bf16 v[16:19], v[226:229], v[202:205], v[16:19]
	v_mfma_f32_16x16x32_bf16 v[4:7], v[218:221], v[210:213], v[4:7]
	v_mfma_f32_16x16x32_bf16 v[0:3], v[226:229], v[210:213], v[0:3]
	s_setprio 0
	s_add_i32 s4, 0, 0x18000
	v_add_u32_e32 v137, s4, v163
	s_barrier
	ds_read_b128 v[146:149], v137
	ds_read_b128 v[150:153], v137 offset:1024
	ds_read_b128 v[154:157], v137 offset:2048
	ds_read_b128 v[170:173], v137 offset:3072
	s_add_u32 s0, s12, 0x80000
	s_addc_u32 s1, s13, 0
	s_mov_b32 m0, s76
	ds_read_b128 v[174:177], v165 offset:32768
	ds_read_b128 v[178:181], v165 offset:33792
	ds_read_b128 v[188:191], v165 offset:34816
	ds_read_b128 v[194:197], v165 offset:35840
	ds_read_b128 v[198:201], v165 offset:36864
	ds_read_b128 v[202:205], v165 offset:37888
	ds_read_b128 v[206:209], v165 offset:38912
	ds_read_b128 v[210:213], v165 offset:39936
	global_load_lds_dwordx4 v128, s[0:1]
	s_mov_b32 m0, s77
	s_nop 0
	global_load_lds_dwordx4 v132, s[0:1]
	s_waitcnt lgkmcnt(8)
	s_barrier
; #define PG8_STAGE(bufoff, gbase, voff) do { _Pragma("unroll") for (int _i = 0; _i < 2; ++_i) \
;         __builtin_amdgcn_global_load_lds((const unsigned*)((const char*)(gbase) + (voff)[_i]), (LAS unsigned*)(lds + (bufoff) + ldsw + _i * 8192), 16, 0, 0); } while (0)
; #define PG8_LDA(dst, b, h) do { _Pragma("unroll") for (int m = 0; m < 4; ++m) _Pragma("unroll") for (int k = 0; k < 2; ++k) dst[m][k] = *(const LAS bf16x8*)(lds + PG8_SA(b, h) + aoff + m * 2048 + k * 1024); } while (0)
; #define PG8_LDB(dst, b, h) do { _Pragma("unroll") for (int n = 0; n < 2; ++n) _Pragma("unroll") for (int k = 0; k < 2; ++k) dst[n][k] = *(const LAS bf16x8*)(lds + PG8_SB(b, h) + boff + n * 2048 + k * 1024); } while (0)
; #define PG8_WAIT_V(n) asm volatile("s_waitcnt vmcnt(" #n ")" ::: "memory")
; #define PG8_WAIT_L(n) asm volatile("s_waitcnt lgkmcnt(" #n ")" ::: "memory")
; #define PG8_BAR __builtin_amdgcn_s_barrier()
; #define PG8_SCHED __builtin_amdgcn_sched_barrier(0)
; template <class Epi, class Sched>
; DI void gemm_phase(LAS unsigned char* lds, const Gemm g, const Sched& S, const Epi& E) {
;     ...
;             PG8_LDB(B0, 0, 0); PG8_SCHED; PG8_LDA(At, 0, 0); PG8_STAGE(PG8_SA(1, 1), a1 + hstep, voffA);
;             PG8_WAIT_L(8); PG8_BAR; PG8_WAIT_L(0); PG8_MMA(0, 0, At, B0); PG8_BAR; PG8_SCHED;
;             PG8_LDB(B1, 0, 1); PG8_STAGE(PG8_SB(0, 0), b2, voffB);
;             PG8_BAR; PG8_WAIT_L(0); PG8_MMA(0, 1, At, B1); PG8_BAR;
;             PG8_LDA(At, 0, 1); PG8_STAGE(PG8_SA(0, 0), a2, voffA);
;             PG8_BAR; PG8_WAIT_L(0); PG8_MMA(1, 0, At, B0); PG8_BAR; PG8_SCHED;
;             PG8_STAGE(PG8_SB(0, 1), b2 + hstep, voffB);
;             PG8_WAIT_V(6); PG8_BAR; PG8_MMA(1, 1, At, B1); PG8_BAR;
;             PG8_LDB(B0, 1, 0); PG8_SCHED; PG8_LDA(At, 1, 0); PG8_STAGE(PG8_SA(0, 1), a2 + hstep, voffA);
;             PG8_WAIT_L(8); PG8_BAR; PG8_WAIT_L(0); PG8_MMA(0, 0, At, B0); PG8_BAR; PG8_SCHED;
;             PG8_LDB(B1, 1, 1); PG8_STAGE(PG8_SB(1, 0), b3, voffB);
;             PG8_BAR; PG8_WAIT_L(0); PG8_MMA(0, 1, At, B1); PG8_BAR;
;             PG8_LDA(At, 1, 1); PG8_STAGE(PG8_SA(1, 0), a3, voffA);
;             PG8_BAR; PG8_WAIT_L(0); PG8_MMA(1, 0, At, B0); PG8_BAR; PG8_SCHED;
;             PG8_STAGE(PG8_SB(1, 1), b3 + hstep, voffB);
;             PG8_WAIT_V(6); PG8_BAR; PG8_MMA(1, 1, At, B1); PG8_BAR;
	s_waitcnt lgkmcnt(0)
	s_setprio 1
	s_waitcnt lgkmcnt(0)
	v_mfma_f32_16x16x32_bf16 v[124:127], v[146:149], v[174:177], v[124:127]
	v_mfma_f32_16x16x32_bf16 v[120:123], v[154:157], v[174:177], v[120:123]
	v_mfma_f32_16x16x32_bf16 v[108:111], v[146:149], v[188:191], v[108:111]
	v_mfma_f32_16x16x32_bf16 v[104:107], v[154:157], v[188:191], v[104:107]
	v_mfma_f32_16x16x32_bf16 v[92:95], v[146:149], v[198:201], v[92:95]
	v_mfma_f32_16x16x32_bf16 v[88:91], v[154:157], v[198:201], v[88:91]
	v_mfma_f32_16x16x32_bf16 v[76:79], v[146:149], v[206:209], v[76:79]
	v_mfma_f32_16x16x32_bf16 v[72:75], v[154:157], v[206:209], v[72:75]
	v_mfma_f32_16x16x32_bf16 v[124:127], v[150:153], v[178:181], v[124:127]
	v_mfma_f32_16x16x32_bf16 v[120:123], v[170:173], v[178:181], v[120:123]
	v_mfma_f32_16x16x32_bf16 v[108:111], v[150:153], v[194:197], v[108:111]
	v_mfma_f32_16x16x32_bf16 v[104:107], v[170:173], v[194:197], v[104:107]
	v_mfma_f32_16x16x32_bf16 v[92:95], v[150:153], v[202:205], v[92:95]
	v_mfma_f32_16x16x32_bf16 v[88:91], v[170:173], v[202:205], v[88:91]
	v_mfma_f32_16x16x32_bf16 v[76:79], v[150:153], v[210:213], v[76:79]
	v_mfma_f32_16x16x32_bf16 v[72:75], v[170:173], v[210:213], v[72:75]
	s_setprio 0
	s_barrier
	s_add_i32 s5, 0, 0x1c000
	s_add_i32 s0, s4, s74
	v_add_u32_e32 v137, s5, v163
	s_add_i32 m0, s0, 0xffffff80
	ds_read_b128 v[214:217], v137
	ds_read_b128 v[218:221], v137 offset:1024
	ds_read_b128 v[222:225], v137 offset:2048
	ds_read_b128 v[226:229], v137 offset:3072
	global_load_lds_dwordx4 v130, s[10:11] offset:128
	s_add_i32 m0, s0, 0x1f80
	s_nop 0
	global_load_lds_dwordx4 v134, s[10:11] offset:128
	s_barrier
	s_waitcnt lgkmcnt(0)
	s_setprio 1
	s_waitcnt lgkmcnt(0)
	v_mfma_f32_16x16x32_bf16 v[116:119], v[214:217], v[174:177], v[116:119]
	v_mfma_f32_16x16x32_bf16 v[112:115], v[222:225], v[174:177], v[112:115]
	v_mfma_f32_16x16x32_bf16 v[100:103], v[214:217], v[188:191], v[100:103]
	v_mfma_f32_16x16x32_bf16 v[96:99], v[222:225], v[188:191], v[96:99]
	v_mfma_f32_16x16x32_bf16 v[84:87], v[214:217], v[198:201], v[84:87]
	v_mfma_f32_16x16x32_bf16 v[80:83], v[222:225], v[198:201], v[80:83]
	v_mfma_f32_16x16x32_bf16 v[68:71], v[214:217], v[206:209], v[68:71]
	v_mfma_f32_16x16x32_bf16 v[64:67], v[222:225], v[206:209], v[64:67]
	v_mfma_f32_16x16x32_bf16 v[116:119], v[218:221], v[178:181], v[116:119]
	v_mfma_f32_16x16x32_bf16 v[112:115], v[226:229], v[178:181], v[112:115]
	v_mfma_f32_16x16x32_bf16 v[100:103], v[218:221], v[194:197], v[100:103]
	v_mfma_f32_16x16x32_bf16 v[96:99], v[226:229], v[194:197], v[96:99]
	v_mfma_f32_16x16x32_bf16 v[84:87], v[218:221], v[202:205], v[84:87]
	v_mfma_f32_16x16x32_bf16 v[80:83], v[226:229], v[202:205], v[80:83]
	v_mfma_f32_16x16x32_bf16 v[68:71], v[218:221], v[210:213], v[68:71]
	v_mfma_f32_16x16x32_bf16 v[64:67], v[226:229], v[210:213], v[64:67]
	s_setprio 0
	s_add_i32 m0, s97, 0xffffff80
	s_barrier
	ds_read_b128 v[174:177], v165 offset:49152
	ds_read_b128 v[178:181], v165 offset:50176
	ds_read_b128 v[188:191], v165 offset:51200
	ds_read_b128 v[194:197], v165 offset:52224
	ds_read_b128 v[198:201], v165 offset:53248
	ds_read_b128 v[202:205], v165 offset:54272
	ds_read_b128 v[206:209], v165 offset:55296
	ds_read_b128 v[210:213], v165 offset:56320
	global_load_lds_dwordx4 v128, s[12:13] offset:128
	v_lshl_add_u64 v[158:159], v[232:233], 0, s[40:41]
	s_add_i32 m0, s84, 0xffffff80
	s_nop 0
	global_load_lds_dwordx4 v132, s[12:13] offset:128
	s_barrier
	s_waitcnt lgkmcnt(0)
	s_setprio 1
	s_waitcnt lgkmcnt(0)
	v_mfma_f32_16x16x32_bf16 v[60:63], v[146:149], v[174:177], v[60:63]
	v_mfma_f32_16x16x32_bf16 v[56:59], v[154:157], v[174:177], v[56:59]
	v_mfma_f32_16x16x32_bf16 v[44:47], v[146:149], v[188:191], v[44:47]
	v_mfma_f32_16x16x32_bf16 v[40:43], v[154:157], v[188:191], v[40:43]
	v_mfma_f32_16x16x32_bf16 v[28:31], v[146:149], v[198:201], v[28:31]
	v_mfma_f32_16x16x32_bf16 v[24:27], v[154:157], v[198:201], v[24:27]
	v_mfma_f32_16x16x32_bf16 v[12:15], v[146:149], v[206:209], v[12:15]
	v_mfma_f32_16x16x32_bf16 v[8:11], v[154:157], v[206:209], v[8:11]
	v_mfma_f32_16x16x32_bf16 v[60:63], v[150:153], v[178:181], v[60:63]
	v_mfma_f32_16x16x32_bf16 v[56:59], v[170:173], v[178:181], v[56:59]
	v_mfma_f32_16x16x32_bf16 v[44:47], v[150:153], v[194:197], v[44:47]
	v_mfma_f32_16x16x32_bf16 v[40:43], v[170:173], v[194:197], v[40:43]
	v_mfma_f32_16x16x32_bf16 v[28:31], v[150:153], v[202:205], v[28:31]
	v_mfma_f32_16x16x32_bf16 v[24:27], v[170:173], v[202:205], v[24:27]
	v_mfma_f32_16x16x32_bf16 v[12:15], v[150:153], v[210:213], v[12:15]
	v_mfma_f32_16x16x32_bf16 v[8:11], v[170:173], v[210:213], v[8:11]
	s_setprio 0
	s_barrier
	s_add_u32 s0, s10, 0x80080
	s_addc_u32 s1, s11, 0
	s_add_i32 s4, s5, s74
	s_mov_b32 m0, s4
	s_nop 0
	global_load_lds_dwordx4 v130, s[0:1]
	v_lshl_add_u64 v[146:147], s[0:1], 0, v[134:135]
	s_add_i32 m0, s4, 0x2000
	s_nop 0
	global_load_lds_dwordx4 v134, s[0:1]
	s_waitcnt vmcnt(6)
	s_barrier
	s_setprio 1
	v_mfma_f32_16x16x32_bf16 v[52:55], v[214:217], v[174:177], v[52:55]
	v_mfma_f32_16x16x32_bf16 v[48:51], v[222:225], v[174:177], v[48:51]
	v_mfma_f32_16x16x32_bf16 v[36:39], v[214:217], v[188:191], v[36:39]
	v_mfma_f32_16x16x32_bf16 v[32:35], v[222:225], v[188:191], v[32:35]
	v_mfma_f32_16x16x32_bf16 v[20:23], v[214:217], v[198:201], v[20:23]
	v_mfma_f32_16x16x32_bf16 v[16:19], v[222:225], v[198:201], v[16:19]
	v_mfma_f32_16x16x32_bf16 v[4:7], v[214:217], v[206:209], v[4:7]
	v_mfma_f32_16x16x32_bf16 v[0:3], v[222:225], v[206:209], v[0:3]
	v_mfma_f32_16x16x32_bf16 v[52:55], v[218:221], v[178:181], v[52:55]
	v_mfma_f32_16x16x32_bf16 v[48:51], v[226:229], v[178:181], v[48:51]
	v_mfma_f32_16x16x32_bf16 v[36:39], v[218:221], v[194:197], v[36:39]
	v_mfma_f32_16x16x32_bf16 v[32:35], v[226:229], v[194:197], v[32:35]
	v_mfma_f32_16x16x32_bf16 v[20:23], v[218:221], v[202:205], v[20:23]
	v_mfma_f32_16x16x32_bf16 v[16:19], v[226:229], v[202:205], v[16:19]
	v_mfma_f32_16x16x32_bf16 v[4:7], v[218:221], v[210:213], v[4:7]
	v_mfma_f32_16x16x32_bf16 v[0:3], v[226:229], v[210:213], v[0:3]
	s_setprio 0
	s_add_i32 s35, s35, 2
	s_add_u32 s8, s8, 0x100
	s_addc_u32 s9, s9, 0
	s_add_u32 s28, s28, 0x100
	s_addc_u32 s34, s34, 0
	s_cmp_gt_u32 s35, 29
	s_barrier
	s_cbranch_scc0 .LBB0_527

;     DI size_t aoff(const Unit& u, size_t tstep) const { return (size_t)u.pm * tstep; }
;     DI size_t boff(const Unit& u, size_t tstep) const { return (size_t)u.pn * tstep; }
;     DI size_t aoff(const Unit& u, size_t) const { return (size_t)u.ks * kbytes; }
;     DI size_t boff(const Unit& u, size_t tstep) const { return (size_t)u.pn * tstep + (size_t)u.ks * kbytes; }
;     DI size_t aoff(const Unit& u, size_t tstep) const { return (u.ks < 2 ? offU : offOA) + (size_t)u.pm * tstep; }
; #define PG8_STAGE(bufoff, gbase, voff) do { _Pragma("unroll") for (int _i = 0; _i < 2; ++_i) \
;         __builtin_amdgcn_global_load_lds((const unsigned*)((const char*)(gbase) + (voff)[_i]), (LAS unsigned*)(lds + (bufoff) + ldsw + _i * 8192), 16, 0, 0); } while (0)
; #define PG8_WAIT_V(n) asm volatile("s_waitcnt vmcnt(" #n ")" ::: "memory")
; #define PG8_BAR __builtin_amdgcn_s_barrier()
; template <class Epi, class Sched>
; DI void gemm_phase(LAS unsigned char* lds, const Gemm g, const Sched& S, const Epi& E) {
;     ...
;     const char* cA = (const char*)g.A + S.aoff(cur, tstep); const char* cB = (const char*)g.Bt + S.boff(cur, tstep);
;     PG8_STAGE(PG8_SB(0, 0), cB, voffB); PG8_STAGE(PG8_SA(0, 0), cA, voffA); PG8_STAGE(PG8_SB(0, 1), cB + hstep, voffB); PG8_STAGE(PG8_SA(0, 1), cA + hstep, voffA);
;     if (wr == 1) PG8_BAR;
;     PG8_WAIT_V(4); PG8_BAR;
;     PG8_STAGE(PG8_SB(1, 0), cB + kstep, voffB); PG8_STAGE(PG8_SA(1, 0), cA + kstep, voffA); PG8_STAGE(PG8_SB(1, 1), cB + hstep + kstep, voffB);
;     PG8_WAIT_V(6); PG8_BAR;
.LBB0_925:
	s_add_u32 s16, s22, 0x1d943000
	s_addc_u32 s17, s23, 0
	s_add_u32 s18, s22, 0x102000
	s_mov_b64 s[28:29], 0x80
	s_addc_u32 s19, s23, 0
	s_and_b32 s4, s1, 3
	s_add_i32 m0, s51, 0x18000
	v_lshl_add_u64 v[6:7], v[6:7], 0, s[28:29]
	s_lshl_b32 s55, s0, 6
	s_lshl_b32 s5, s0, 13
	s_lshl_b32 s56, s4, 5
	s_waitcnt vmcnt(4)
	s_barrier
	global_load_lds_dwordx4 v[6:7], off
	v_lshl_add_u64 v[4:5], v[4:5], 0, s[28:29]
	s_add_i32 m0, s51, 0x1a000
	s_add_i32 s57, s51, 0x8000
	s_add_i32 s58, s51, 0xa000
	global_load_lds_dwordx4 v[4:5], off
	v_lshl_add_u64 v[2:3], v[2:3], 0, s[28:29]
	s_mov_b32 m0, s57
	s_add_u32 s0, s36, 0x30080
	global_load_lds_dwordx4 v[2:3], off
	v_lshl_add_u64 v[0:1], v[0:1], 0, s[28:29]
	s_mov_b32 m0, s58
	s_addc_u32 s1, s37, 0
	global_load_lds_dwordx4 v[0:1], off
	s_add_i32 m0, s51, 0x1c000
	s_nop 0
	global_load_lds_dwordx4 v130, s[0:1]
	s_add_i32 m0, s51, 0x1e000
	v_lshl_or_b32 v164, s4, 12, v158
	global_load_lds_dwordx4 v134, s[0:1]
	v_lshlrev_b32_e32 v1, 2, v154
	v_lshl_or_b32 v0, v154, 6, v157
	v_and_b32_e32 v1, 32, v1
	v_bitop3_b32 v0, v0, s5, v1 bitop3:0xde
	s_waitcnt vmcnt(6)
	v_add_u16_e32 v1, v151, v152
	v_lshrrev_b16_e32 v1, 1, v1
	s_add_i32 s61, 0, 0x10000
	s_add_i32 s62, 0, 0x14000
	s_mov_b32 s59, 0x8000
	s_or_b32 s60, s4, -16
	v_add_lshl_u32 v136, v8, v1, 1
	v_mov_b32_e32 v137, v131
	v_add_lshl_u32 v138, v9, v1, 1
	v_mov_b32_e32 v139, v131
	v_mov_b64_e32 v[140:141], 0x306
	v_mov_b64_e32 v[142:143], 0x305
	v_add_u32_e32 v165, s61, v164
	v_add_u32_e32 v166, 0, v0
	v_add_u32_e32 v167, s62, v164
	s_movk_i32 s63, 0xc00
	s_movk_i32 s64, 0x7ff0
	s_movk_i32 s65, 0x7fe0
	s_movk_i32 s66, 0x7fd0
	s_movk_i32 s67, 0x7f80
	s_movk_i32 s68, 0x7f70
	s_movk_i32 s69, 0x7f60
	s_movk_i32 s70, 0x7f50
	s_mov_b32 s71, 0
	s_barrier
	s_branch .LBB0_927

;     DI size_t aoff(const Unit& u, size_t tstep) const { return (size_t)u.pm * tstep; }
;     DI size_t boff(const Unit& u, size_t tstep) const { return (size_t)u.pn * tstep; }
;     DI bool next(int i, Unit& u) const { const long L = (long)i * G + c; if (L >= np) return false; u.pm = pmv; u.pn = (int)(L % nN); u.ks = (int)(L / nN); return true; }
;     DI size_t aoff(const Unit& u, size_t) const { return (size_t)u.ks * kbytes; }
;     DI size_t boff(const Unit& u, size_t tstep) const { return (size_t)u.pn * tstep + (size_t)u.ks * kbytes; }
;     DI bool next(int i, Unit& u) const { Unit t; if (!S.next(i / 3, t)) return false; u.pm = t.pm; u.pn = t.pn; u.ks = i % 3; return true; }
;     DI size_t aoff(const Unit& u, size_t tstep) const { return (u.ks < 2 ? offU : offOA) + (size_t)u.pm * tstep; }
; #define PG8_WAIT_L(n) asm volatile("s_waitcnt lgkmcnt(" #n ")" ::: "memory")
; #define PG8_BAR __builtin_amdgcn_s_barrier()
; template <class Epi, class Sched>
; DI void gemm_phase(LAS unsigned char* lds, const Gemm g, const Sched& S, const Epi& E) {
;     ...
;         const bool has_next = S.next(ui + 1, nxt);
;         const char* nA = has_next ? (const char*)g.A + S.aoff(nxt, tstep) : cA; const char* nB = has_next ? (const char*)g.Bt + S.boff(nxt, tstep) : cB;
;         for (int t = 0; t < nt; t += 2) {
;             if constexpr (Epi::HAS_MID) { if (t == E.mid_t(nt)) { int fr3 = fr, fq3 = fq; asm volatile("" : "+v"(fr3), "+v"(fq3)); E.mid(acc, cur, wr, wc, fr3, fq3); } }
;             const bool last = (t == nt - 2);
;             const char* a1 = cA + (size_t)(t + 1) * kstep;
;             const char* a2 = last ? nA : cA + (size_t)(t + 2) * kstep; const char* b2 = last ? nB : cB + (size_t)(t + 2) * kstep;
;             const char* a3 = a2 + kstep; const char* b3 = b2 + kstep;
;             PG8_LDB(B0, 0, 0); PG8_SCHED; PG8_LDA(At, 0, 0); PG8_STAGE(PG8_SA(1, 1), a1 + hstep, voffA);
;             PG8_WAIT_L(8); PG8_BAR; PG8_WAIT_L(0); PG8_MMA(0, 0, At, B0); PG8_BAR; PG8_SCHED;
;             PG8_LDB(B1, 0, 1); PG8_STAGE(PG8_SB(0, 0), b2, voffB);
;             PG8_BAR; PG8_WAIT_L(0); PG8_MMA(0, 1, At, B1); PG8_BAR;
;             PG8_LDA(At, 0, 1); PG8_STAGE(PG8_SA(0, 0), a2, voffA);
;             PG8_BAR; PG8_WAIT_L(0); PG8_MMA(1, 0, At, B0); PG8_BAR; PG8_SCHED;
;             PG8_STAGE(PG8_SB(0, 1), b2 + hstep, voffB);
.LBB0_937:
	s_add_u32 s8, s38, 0x30080
	s_addc_u32 s9, s39, 0
	s_add_u32 s35, s36, 0x100
	v_mov_b32_e32 v0, 0
	s_addc_u32 s40, s37, 0
	s_mov_b32 s41, -2
	ds_read_b128 v[144:147], v165
	ds_read_b128 v[168:171], v165 offset:1024
	ds_read_b128 v[172:175], v165 offset:2048
	ds_read_b128 v[176:179], v165 offset:3072
	s_add_u32 s0, s8, 0xfffd0080
	s_addc_u32 s1, s9, -1
	s_cmp_eq_u32 s41, 8
	s_cselect_b32 s39, s31, s1
	s_cselect_b32 s38, s30, s0
	s_cselect_b32 s37, s11, s40
	s_cselect_b32 s36, s10, s35
	s_add_i32 m0, s51, 0xc000
	ds_read_b128 v[180:183], v166
	ds_read_b128 v[188:191], v166 offset:1024
	ds_read_b128 v[194:197], v166 offset:2048
	ds_read_b128 v[198:201], v166 offset:3072
	ds_read_b128 v[202:205], v166 offset:4096
	ds_read_b128 v[206:209], v166 offset:5120
	ds_read_b128 v[210:213], v166 offset:6144
	ds_read_b128 v[214:217], v166 offset:7168
	global_load_lds_dwordx4 v136, s[8:9]
	s_add_i32 m0, s51, 0xe000
	s_nop 0
	global_load_lds_dwordx4 v138, s[8:9]
	s_waitcnt lgkmcnt(8)
	s_barrier
	s_waitcnt lgkmcnt(0)
	s_setprio 1
	s_waitcnt lgkmcnt(0)
	v_mfma_f32_16x16x32_bf16 v[124:127], v[144:147], v[180:183], 0
	v_mfma_f32_16x16x32_bf16 v[120:123], v[172:175], v[180:183], 0
	v_mfma_f32_16x16x32_bf16 v[108:111], v[144:147], v[194:197], 0
	v_mfma_f32_16x16x32_bf16 v[104:107], v[172:175], v[194:197], 0
	v_mfma_f32_16x16x32_bf16 v[92:95], v[144:147], v[202:205], 0
	v_mfma_f32_16x16x32_bf16 v[88:91], v[172:175], v[202:205], 0
	v_mfma_f32_16x16x32_bf16 v[76:79], v[144:147], v[210:213], 0
	v_mfma_f32_16x16x32_bf16 v[72:75], v[172:175], v[210:213], 0
	v_mfma_f32_16x16x32_bf16 v[124:127], v[168:171], v[188:191], v[124:127]
	v_mfma_f32_16x16x32_bf16 v[120:123], v[176:179], v[188:191], v[120:123]
	v_mfma_f32_16x16x32_bf16 v[108:111], v[168:171], v[198:201], v[108:111]
	v_mfma_f32_16x16x32_bf16 v[104:107], v[176:179], v[198:201], v[104:107]
	v_mfma_f32_16x16x32_bf16 v[92:95], v[168:171], v[206:209], v[92:95]
	v_mfma_f32_16x16x32_bf16 v[88:91], v[176:179], v[206:209], v[88:91]
	v_mfma_f32_16x16x32_bf16 v[76:79], v[168:171], v[214:217], v[76:79]
	v_mfma_f32_16x16x32_bf16 v[72:75], v[176:179], v[214:217], v[72:75]
	s_setprio 0
	s_barrier
	s_add_i32 s0, s61, s50
	s_mov_b32 m0, s0
	ds_read_b128 v[218:221], v167
	ds_read_b128 v[222:225], v167 offset:1024
	ds_read_b128 v[226:229], v167 offset:2048
	ds_read_b128 v[230:233], v167 offset:3072
	global_load_lds_dwordx4 v130, s[36:37]
	s_add_i32 m0, s0, 0x2000
	s_nop 0
	global_load_lds_dwordx4 v134, s[36:37]
	s_barrier
	s_waitcnt lgkmcnt(0)
	s_setprio 1
	s_waitcnt lgkmcnt(0)
	v_mfma_f32_16x16x32_bf16 v[116:119], v[218:221], v[180:183], 0
	v_mfma_f32_16x16x32_bf16 v[112:115], v[226:229], v[180:183], 0
	v_mfma_f32_16x16x32_bf16 v[100:103], v[218:221], v[194:197], 0
	v_mfma_f32_16x16x32_bf16 v[96:99], v[226:229], v[194:197], 0
	v_mfma_f32_16x16x32_bf16 v[84:87], v[218:221], v[202:205], 0
	v_mfma_f32_16x16x32_bf16 v[80:83], v[226:229], v[202:205], 0
	v_mfma_f32_16x16x32_bf16 v[68:71], v[218:221], v[210:213], 0
	v_mfma_f32_16x16x32_bf16 v[64:67], v[226:229], v[210:213], 0
	v_mfma_f32_16x16x32_bf16 v[116:119], v[222:225], v[188:191], v[116:119]
	v_mfma_f32_16x16x32_bf16 v[112:115], v[230:233], v[188:191], v[112:115]
	v_mfma_f32_16x16x32_bf16 v[100:103], v[222:225], v[198:201], v[100:103]
	v_mfma_f32_16x16x32_bf16 v[96:99], v[230:233], v[198:201], v[96:99]
	v_mfma_f32_16x16x32_bf16 v[84:87], v[222:225], v[206:209], v[84:87]
	v_mfma_f32_16x16x32_bf16 v[80:83], v[230:233], v[206:209], v[80:83]
	v_mfma_f32_16x16x32_bf16 v[68:71], v[222:225], v[214:217], v[68:71]
	v_mfma_f32_16x16x32_bf16 v[64:67], v[230:233], v[214:217], v[64:67]
	s_setprio 0
	s_mov_b32 m0, s51
	s_barrier
	ds_read_b128 v[180:183], v166 offset:16384
	ds_read_b128 v[188:191], v166 offset:17408
	ds_read_b128 v[194:197], v166 offset:18432
	ds_read_b128 v[198:201], v166 offset:19456
	ds_read_b128 v[202:205], v166 offset:20480
	ds_read_b128 v[206:209], v166 offset:21504
	ds_read_b128 v[210:213], v166 offset:22528
	ds_read_b128 v[214:217], v166 offset:23552
	global_load_lds_dwordx4 v128, s[38:39]
	s_mov_b32 m0, s52
	s_nop 0
	global_load_lds_dwordx4 v132, s[38:39]
	s_barrier
	s_waitcnt lgkmcnt(0)
	s_setprio 1
	s_waitcnt lgkmcnt(0)
	v_mfma_f32_16x16x32_bf16 v[60:63], v[144:147], v[180:183], 0
	v_mfma_f32_16x16x32_bf16 v[56:59], v[172:175], v[180:183], 0
	v_mfma_f32_16x16x32_bf16 v[44:47], v[144:147], v[194:197], 0
	v_mfma_f32_16x16x32_bf16 v[40:43], v[172:175], v[194:197], 0
	v_mfma_f32_16x16x32_bf16 v[28:31], v[144:147], v[202:205], 0
	v_mfma_f32_16x16x32_bf16 v[24:27], v[172:175], v[202:205], 0
	v_mfma_f32_16x16x32_bf16 v[12:15], v[144:147], v[210:213], 0
	v_mfma_f32_16x16x32_bf16 v[8:11], v[172:175], v[210:213], 0
	v_mfma_f32_16x16x32_bf16 v[60:63], v[168:171], v[188:191], v[60:63]
	v_mfma_f32_16x16x32_bf16 v[56:59], v[176:179], v[188:191], v[56:59]
	v_mfma_f32_16x16x32_bf16 v[44:47], v[168:171], v[198:201], v[44:47]
	v_mfma_f32_16x16x32_bf16 v[40:43], v[176:179], v[198:201], v[40:43]
	v_mfma_f32_16x16x32_bf16 v[28:31], v[168:171], v[206:209], v[28:31]
	v_mfma_f32_16x16x32_bf16 v[24:27], v[176:179], v[206:209], v[24:27]
	v_mfma_f32_16x16x32_bf16 v[12:15], v[168:171], v[214:217], v[12:15]
	v_mfma_f32_16x16x32_bf16 v[8:11], v[176:179], v[214:217], v[8:11]
	s_setprio 0
	s_barrier
	s_add_u32 s0, s36, 0x30000
	s_addc_u32 s1, s37, 0
	s_add_i32 s4, s62, s50
	s_mov_b32 m0, s4
	s_nop 0
	global_load_lds_dwordx4 v130, s[0:1]
	s_add_i32 m0, s4, 0x2000
	s_nop 0
	global_load_lds_dwordx4 v134, s[0:1]
	s_waitcnt vmcnt(6)
	s_barrier
; #define PG8_STAGE(bufoff, gbase, voff) do { _Pragma("unroll") for (int _i = 0; _i < 2; ++_i) \
;         __builtin_amdgcn_global_load_lds((const unsigned*)((const char*)(gbase) + (voff)[_i]), (LAS unsigned*)(lds + (bufoff) + ldsw + _i * 8192), 16, 0, 0); } while (0)
; #define PG8_LDA(dst, b, h) do { _Pragma("unroll") for (int m = 0; m < 4; ++m) _Pragma("unroll") for (int k = 0; k < 2; ++k) dst[m][k] = *(const LAS bf16x8*)(lds + PG8_SA(b, h) + aoff + m * 2048 + k * 1024); } while (0)
; #define PG8_LDB(dst, b, h) do { _Pragma("unroll") for (int n = 0; n < 2; ++n) _Pragma("unroll") for (int k = 0; k < 2; ++k) dst[n][k] = *(const LAS bf16x8*)(lds + PG8_SB(b, h) + boff + n * 2048 + k * 1024); } while (0)
; #define PG8_WAIT_V(n) asm volatile("s_waitcnt vmcnt(" #n ")" ::: "memory")
; #define PG8_WAIT_L(n) asm volatile("s_waitcnt lgkmcnt(" #n ")" ::: "memory")
; #define PG8_BAR __builtin_amdgcn_s_barrier()
; #define PG8_SCHED __builtin_amdgcn_sched_barrier(0)
; template <class Epi, class Sched>
; DI void gemm_phase(LAS unsigned char* lds, const Gemm g, const Sched& S, const Epi& E) {
;     ...
;             PG8_LDB(B0, 0, 0); PG8_SCHED; PG8_LDA(At, 0, 0); PG8_STAGE(PG8_SA(1, 1), a1 + hstep, voffA);
;             PG8_WAIT_L(8); PG8_BAR; PG8_WAIT_L(0); PG8_MMA(0, 0, At, B0); PG8_BAR; PG8_SCHED;
;             PG8_LDB(B1, 0, 1); PG8_STAGE(PG8_SB(0, 0), b2, voffB);
;             PG8_BAR; PG8_WAIT_L(0); PG8_MMA(0, 1, At, B1); PG8_BAR;
;             PG8_LDA(At, 0, 1); PG8_STAGE(PG8_SA(0, 0), a2, voffA);
;             PG8_BAR; PG8_WAIT_L(0); PG8_MMA(1, 0, At, B0); PG8_BAR; PG8_SCHED;
;             PG8_STAGE(PG8_SB(0, 1), b2 + hstep, voffB);
;             PG8_WAIT_V(6); PG8_BAR; PG8_MMA(1, 1, At, B1); PG8_BAR;
;             PG8_LDB(B0, 1, 0); PG8_SCHED; PG8_LDA(At, 1, 0); PG8_STAGE(PG8_SA(0, 1), a2 + hstep, voffA);
;             PG8_WAIT_L(8); PG8_BAR; PG8_WAIT_L(0); PG8_MMA(0, 0, At, B0); PG8_BAR; PG8_SCHED;
;             PG8_LDB(B1, 1, 1); PG8_STAGE(PG8_SB(1, 0), b3, voffB);
;             PG8_BAR; PG8_WAIT_L(0); PG8_MMA(0, 1, At, B1); PG8_BAR;
;             PG8_LDA(At, 1, 1); PG8_STAGE(PG8_SA(1, 0), a3, voffA);
;             PG8_BAR; PG8_WAIT_L(0); PG8_MMA(1, 0, At, B0); PG8_BAR; PG8_SCHED;
;             PG8_STAGE(PG8_SB(1, 1), b3 + hstep, voffB);
;             PG8_WAIT_V(6); PG8_BAR; PG8_MMA(1, 1, At, B1); PG8_BAR;
	s_setprio 1
	v_mfma_f32_16x16x32_bf16 v[52:55], v[218:221], v[180:183], 0
	v_mfma_f32_16x16x32_bf16 v[48:51], v[226:229], v[180:183], 0
	v_mfma_f32_16x16x32_bf16 v[36:39], v[218:221], v[194:197], 0
	v_mfma_f32_16x16x32_bf16 v[32:35], v[226:229], v[194:197], 0
	v_mfma_f32_16x16x32_bf16 v[20:23], v[218:221], v[202:205], 0
	v_mfma_f32_16x16x32_bf16 v[16:19], v[226:229], v[202:205], 0
	v_mfma_f32_16x16x32_bf16 v[4:7], v[218:221], v[210:213], 0
	v_mfma_f32_16x16x32_bf16 v[0:3], v[226:229], v[210:213], 0
	v_mfma_f32_16x16x32_bf16 v[52:55], v[222:225], v[188:191], v[52:55]
	v_mfma_f32_16x16x32_bf16 v[48:51], v[230:233], v[188:191], v[48:51]
	v_mfma_f32_16x16x32_bf16 v[36:39], v[222:225], v[198:201], v[36:39]
	v_mfma_f32_16x16x32_bf16 v[32:35], v[230:233], v[198:201], v[32:35]
	v_mfma_f32_16x16x32_bf16 v[20:23], v[222:225], v[206:209], v[20:23]
	v_mfma_f32_16x16x32_bf16 v[16:19], v[230:233], v[206:209], v[16:19]
	v_mfma_f32_16x16x32_bf16 v[4:7], v[222:225], v[214:217], v[4:7]
	v_mfma_f32_16x16x32_bf16 v[0:3], v[230:233], v[214:217], v[0:3]
	s_setprio 0
	s_add_i32 s4, 0, 0x18000
	v_add_u32_e32 v150, s4, v164
	s_barrier
	ds_read_b128 v[144:147], v150
	ds_read_b128 v[168:171], v150 offset:1024
	ds_read_b128 v[172:175], v150 offset:2048
	ds_read_b128 v[176:179], v150 offset:3072
	s_add_u32 s0, s38, 0x30000
	s_addc_u32 s1, s39, 0
	s_mov_b32 m0, s53
	ds_read_b128 v[180:183], v166 offset:32768
	ds_read_b128 v[188:191], v166 offset:33792
	ds_read_b128 v[194:197], v166 offset:34816
	ds_read_b128 v[198:201], v166 offset:35840
	ds_read_b128 v[202:205], v166 offset:36864
	ds_read_b128 v[206:209], v166 offset:37888
	ds_read_b128 v[210:213], v166 offset:38912
	ds_read_b128 v[214:217], v166 offset:39936
	global_load_lds_dwordx4 v128, s[0:1]
	s_mov_b32 m0, s54
	s_nop 0
	global_load_lds_dwordx4 v132, s[0:1]
	s_waitcnt lgkmcnt(8)
	s_barrier
	s_waitcnt lgkmcnt(0)
	s_setprio 1
	s_waitcnt lgkmcnt(0)
	v_mfma_f32_16x16x32_bf16 v[124:127], v[144:147], v[180:183], v[124:127]
	v_mfma_f32_16x16x32_bf16 v[120:123], v[172:175], v[180:183], v[120:123]
	v_mfma_f32_16x16x32_bf16 v[108:111], v[144:147], v[194:197], v[108:111]
	v_mfma_f32_16x16x32_bf16 v[104:107], v[172:175], v[194:197], v[104:107]
	v_mfma_f32_16x16x32_bf16 v[92:95], v[144:147], v[202:205], v[92:95]
	v_mfma_f32_16x16x32_bf16 v[88:91], v[172:175], v[202:205], v[88:91]
	v_mfma_f32_16x16x32_bf16 v[76:79], v[144:147], v[210:213], v[76:79]
	v_mfma_f32_16x16x32_bf16 v[72:75], v[172:175], v[210:213], v[72:75]
	v_mfma_f32_16x16x32_bf16 v[124:127], v[168:171], v[188:191], v[124:127]
	v_mfma_f32_16x16x32_bf16 v[120:123], v[176:179], v[188:191], v[120:123]
	v_mfma_f32_16x16x32_bf16 v[108:111], v[168:171], v[198:201], v[108:111]
	v_mfma_f32_16x16x32_bf16 v[104:107], v[176:179], v[198:201], v[104:107]
	v_mfma_f32_16x16x32_bf16 v[92:95], v[168:171], v[206:209], v[92:95]
	v_mfma_f32_16x16x32_bf16 v[88:91], v[176:179], v[206:209], v[88:91]
	v_mfma_f32_16x16x32_bf16 v[76:79], v[168:171], v[214:217], v[76:79]
	v_mfma_f32_16x16x32_bf16 v[72:75], v[176:179], v[214:217], v[72:75]
	s_setprio 0
	s_barrier
	s_add_i32 s5, 0, 0x1c000
	s_add_i32 s0, s4, s50
	v_add_u32_e32 v150, s5, v164
	s_add_i32 m0, s0, 0xffffff80
	ds_read_b128 v[218:221], v150
	ds_read_b128 v[222:225], v150 offset:1024
	ds_read_b128 v[226:229], v150 offset:2048
	ds_read_b128 v[230:233], v150 offset:3072
	global_load_lds_dwordx4 v130, s[36:37] offset:128
	s_add_i32 m0, s0, 0x1f80
	s_nop 0
	global_load_lds_dwordx4 v134, s[36:37] offset:128
	s_barrier
	s_waitcnt lgkmcnt(0)
	s_setprio 1
	s_waitcnt lgkmcnt(0)
	v_mfma_f32_16x16x32_bf16 v[116:119], v[218:221], v[180:183], v[116:119]
	v_mfma_f32_16x16x32_bf16 v[112:115], v[226:229], v[180:183], v[112:115]
	v_mfma_f32_16x16x32_bf16 v[100:103], v[218:221], v[194:197], v[100:103]
	v_mfma_f32_16x16x32_bf16 v[96:99], v[226:229], v[194:197], v[96:99]
	v_mfma_f32_16x16x32_bf16 v[84:87], v[218:221], v[202:205], v[84:87]
	v_mfma_f32_16x16x32_bf16 v[80:83], v[226:229], v[202:205], v[80:83]
	v_mfma_f32_16x16x32_bf16 v[68:71], v[218:221], v[210:213], v[68:71]
	v_mfma_f32_16x16x32_bf16 v[64:67], v[226:229], v[210:213], v[64:67]
	v_mfma_f32_16x16x32_bf16 v[116:119], v[222:225], v[188:191], v[116:119]
	v_mfma_f32_16x16x32_bf16 v[112:115], v[230:233], v[188:191], v[112:115]
	v_mfma_f32_16x16x32_bf16 v[100:103], v[222:225], v[198:201], v[100:103]
	v_mfma_f32_16x16x32_bf16 v[96:99], v[230:233], v[198:201], v[96:99]
	v_mfma_f32_16x16x32_bf16 v[84:87], v[222:225], v[206:209], v[84:87]
	v_mfma_f32_16x16x32_bf16 v[80:83], v[230:233], v[206:209], v[80:83]
	v_mfma_f32_16x16x32_bf16 v[68:71], v[222:225], v[214:217], v[68:71]
	v_mfma_f32_16x16x32_bf16 v[64:67], v[230:233], v[214:217], v[64:67]
	s_setprio 0
	s_add_i32 m0, s57, 0xffffff80
	s_barrier
	ds_read_b128 v[180:183], v166 offset:49152
	ds_read_b128 v[188:191], v166 offset:50176
	ds_read_b128 v[194:197], v166 offset:51200
	ds_read_b128 v[198:201], v166 offset:52224
	ds_read_b128 v[202:205], v166 offset:53248
	ds_read_b128 v[206:209], v166 offset:54272
	ds_read_b128 v[210:213], v166 offset:55296
	ds_read_b128 v[214:217], v166 offset:56320
	global_load_lds_dwordx4 v128, s[38:39] offset:128
	s_add_i32 m0, s58, 0xffffff80
	s_nop 0
	global_load_lds_dwordx4 v132, s[38:39] offset:128
	s_barrier
; #define PG8_STAGE(bufoff, gbase, voff) do { _Pragma("unroll") for (int _i = 0; _i < 2; ++_i) \
;         __builtin_amdgcn_global_load_lds((const unsigned*)((const char*)(gbase) + (voff)[_i]), (LAS unsigned*)(lds + (bufoff) + ldsw + _i * 8192), 16, 0, 0); } while (0)
; #define PG8_LDA(dst, b, h) do { _Pragma("unroll") for (int m = 0; m < 4; ++m) _Pragma("unroll") for (int k = 0; k < 2; ++k) dst[m][k] = *(const LAS bf16x8*)(lds + PG8_SA(b, h) + aoff + m * 2048 + k * 1024); } while (0)
; #define PG8_LDB(dst, b, h) do { _Pragma("unroll") for (int n = 0; n < 2; ++n) _Pragma("unroll") for (int k = 0; k < 2; ++k) dst[n][k] = *(const LAS bf16x8*)(lds + PG8_SB(b, h) + boff + n * 2048 + k * 1024); } while (0)
; #define PG8_WAIT_V(n) asm volatile("s_waitcnt vmcnt(" #n ")" ::: "memory")
; #define PG8_WAIT_L(n) asm volatile("s_waitcnt lgkmcnt(" #n ")" ::: "memory")
; #define PG8_BAR __builtin_amdgcn_s_barrier()
; #define PG8_SCHED __builtin_amdgcn_sched_barrier(0)
; template <class Epi, class Sched>
; DI void gemm_phase(LAS unsigned char* lds, const Gemm g, const Sched& S, const Epi& E) {
;     ...
;             PG8_LDB(B0, 0, 0); PG8_SCHED; PG8_LDA(At, 0, 0); PG8_STAGE(PG8_SA(1, 1), a1 + hstep, voffA);
;             PG8_WAIT_L(8); PG8_BAR; PG8_WAIT_L(0); PG8_MMA(0, 0, At, B0); PG8_BAR; PG8_SCHED;
;             PG8_LDB(B1, 0, 1); PG8_STAGE(PG8_SB(0, 0), b2, voffB);
;             PG8_BAR; PG8_WAIT_L(0); PG8_MMA(0, 1, At, B1); PG8_BAR;
;             PG8_LDA(At, 0, 1); PG8_STAGE(PG8_SA(0, 0), a2, voffA);
;             PG8_BAR; PG8_WAIT_L(0); PG8_MMA(1, 0, At, B0); PG8_BAR; PG8_SCHED;
;             PG8_STAGE(PG8_SB(0, 1), b2 + hstep, voffB);
;             PG8_WAIT_V(6); PG8_BAR; PG8_MMA(1, 1, At, B1); PG8_BAR;
;             PG8_LDB(B0, 1, 0); PG8_SCHED; PG8_LDA(At, 1, 0); PG8_STAGE(PG8_SA(0, 1), a2 + hstep, voffA);
;             PG8_WAIT_L(8); PG8_BAR; PG8_WAIT_L(0); PG8_MMA(0, 0, At, B0); PG8_BAR; PG8_SCHED;
;             PG8_LDB(B1, 1, 1); PG8_STAGE(PG8_SB(1, 0), b3, voffB);
;             PG8_BAR; PG8_WAIT_L(0); PG8_MMA(0, 1, At, B1); PG8_BAR;
;             PG8_LDA(At, 1, 1); PG8_STAGE(PG8_SA(1, 0), a3, voffA);
;             PG8_BAR; PG8_WAIT_L(0); PG8_MMA(1, 0, At, B0); PG8_BAR; PG8_SCHED;
;             PG8_STAGE(PG8_SB(1, 1), b3 + hstep, voffB);
;             PG8_WAIT_V(6); PG8_BAR; PG8_MMA(1, 1, At, B1); PG8_BAR;
	s_waitcnt lgkmcnt(0)
	s_setprio 1
	s_waitcnt lgkmcnt(0)
	v_mfma_f32_16x16x32_bf16 v[60:63], v[144:147], v[180:183], v[60:63]
	v_mfma_f32_16x16x32_bf16 v[56:59], v[172:175], v[180:183], v[56:59]
	v_mfma_f32_16x16x32_bf16 v[44:47], v[144:147], v[194:197], v[44:47]
	v_mfma_f32_16x16x32_bf16 v[40:43], v[172:175], v[194:197], v[40:43]
	v_mfma_f32_16x16x32_bf16 v[28:31], v[144:147], v[202:205], v[28:31]
	v_mfma_f32_16x16x32_bf16 v[24:27], v[172:175], v[202:205], v[24:27]
	v_mfma_f32_16x16x32_bf16 v[12:15], v[144:147], v[210:213], v[12:15]
	v_mfma_f32_16x16x32_bf16 v[8:11], v[172:175], v[210:213], v[8:11]
	v_mfma_f32_16x16x32_bf16 v[60:63], v[168:171], v[188:191], v[60:63]
	v_mfma_f32_16x16x32_bf16 v[56:59], v[176:179], v[188:191], v[56:59]
	v_mfma_f32_16x16x32_bf16 v[44:47], v[168:171], v[198:201], v[44:47]
	v_mfma_f32_16x16x32_bf16 v[40:43], v[176:179], v[198:201], v[40:43]
	v_mfma_f32_16x16x32_bf16 v[28:31], v[168:171], v[206:209], v[28:31]
	v_mfma_f32_16x16x32_bf16 v[24:27], v[176:179], v[206:209], v[24:27]
	v_mfma_f32_16x16x32_bf16 v[12:15], v[168:171], v[214:217], v[12:15]
	v_mfma_f32_16x16x32_bf16 v[8:11], v[176:179], v[214:217], v[8:11]
	s_setprio 0
	s_barrier
	s_add_u32 s0, s36, 0x30080
	s_addc_u32 s1, s37, 0
	s_add_i32 s4, s5, s50
	s_mov_b32 m0, s4
	s_nop 0
	global_load_lds_dwordx4 v130, s[0:1]
	s_add_i32 m0, s4, 0x2000
	s_nop 0
	global_load_lds_dwordx4 v134, s[0:1]
	s_waitcnt vmcnt(6)
	s_barrier
	s_setprio 1
	v_mfma_f32_16x16x32_bf16 v[52:55], v[218:221], v[180:183], v[52:55]
	v_mfma_f32_16x16x32_bf16 v[48:51], v[226:229], v[180:183], v[48:51]
	v_mfma_f32_16x16x32_bf16 v[36:39], v[218:221], v[194:197], v[36:39]
	v_mfma_f32_16x16x32_bf16 v[32:35], v[226:229], v[194:197], v[32:35]
	v_mfma_f32_16x16x32_bf16 v[20:23], v[218:221], v[202:205], v[20:23]
	v_mfma_f32_16x16x32_bf16 v[16:19], v[226:229], v[202:205], v[16:19]
	v_mfma_f32_16x16x32_bf16 v[4:7], v[218:221], v[210:213], v[4:7]
	v_mfma_f32_16x16x32_bf16 v[0:3], v[226:229], v[210:213], v[0:3]
	v_mfma_f32_16x16x32_bf16 v[52:55], v[222:225], v[188:191], v[52:55]
	v_mfma_f32_16x16x32_bf16 v[48:51], v[230:233], v[188:191], v[48:51]
	v_mfma_f32_16x16x32_bf16 v[36:39], v[222:225], v[198:201], v[36:39]
	v_mfma_f32_16x16x32_bf16 v[32:35], v[230:233], v[198:201], v[32:35]
	v_mfma_f32_16x16x32_bf16 v[20:23], v[222:225], v[206:209], v[20:23]
	v_mfma_f32_16x16x32_bf16 v[16:19], v[230:233], v[206:209], v[16:19]
	v_mfma_f32_16x16x32_bf16 v[4:7], v[222:225], v[214:217], v[4:7]
	v_mfma_f32_16x16x32_bf16 v[0:3], v[230:233], v[214:217], v[0:3]
	s_setprio 0
	s_add_i32 s41, s41, 2
	s_add_u32 s8, s8, 0x100
	s_addc_u32 s9, s9, 0
	s_add_u32 s35, s35, 0x100
	s_addc_u32 s40, s40, 0
	s_cmp_gt_u32 s41, 9
	s_barrier
	s_cbranch_scc0 .LBB0_938
	s_branch .Lpeel_done_938
.LBB0_938:
	ds_read_b128 v[144:147], v165
	ds_read_b128 v[168:171], v165 offset:1024
	ds_read_b128 v[172:175], v165 offset:2048
	ds_read_b128 v[176:179], v165 offset:3072
	s_add_u32 s0, s8, 0xfffd0080
	s_addc_u32 s1, s9, -1
	s_cmp_eq_u32 s41, 8
	s_cselect_b32 s39, s31, s1
	s_cselect_b32 s38, s30, s0
	s_cselect_b32 s37, s11, s40
	s_cselect_b32 s36, s10, s35
	s_add_i32 m0, s51, 0xc000
	ds_read_b128 v[180:183], v166
	ds_read_b128 v[188:191], v166 offset:1024
	ds_read_b128 v[194:197], v166 offset:2048
	ds_read_b128 v[198:201], v166 offset:3072
	ds_read_b128 v[202:205], v166 offset:4096
	ds_read_b128 v[206:209], v166 offset:5120
	ds_read_b128 v[210:213], v166 offset:6144
	ds_read_b128 v[214:217], v166 offset:7168
	global_load_lds_dwordx4 v136, s[8:9]
	s_add_i32 m0, s51, 0xe000
	s_nop 0
	global_load_lds_dwordx4 v138, s[8:9]
	s_waitcnt lgkmcnt(8)
	s_barrier
	s_waitcnt lgkmcnt(0)
	s_setprio 1
	s_waitcnt lgkmcnt(0)
	v_mfma_f32_16x16x32_bf16 v[124:127], v[144:147], v[180:183], v[124:127]
	v_mfma_f32_16x16x32_bf16 v[120:123], v[172:175], v[180:183], v[120:123]
	v_mfma_f32_16x16x32_bf16 v[108:111], v[144:147], v[194:197], v[108:111]
	v_mfma_f32_16x16x32_bf16 v[104:107], v[172:175], v[194:197], v[104:107]
	v_mfma_f32_16x16x32_bf16 v[92:95], v[144:147], v[202:205], v[92:95]
	v_mfma_f32_16x16x32_bf16 v[88:91], v[172:175], v[202:205], v[88:91]
	v_mfma_f32_16x16x32_bf16 v[76:79], v[144:147], v[210:213], v[76:79]
	v_mfma_f32_16x16x32_bf16 v[72:75], v[172:175], v[210:213], v[72:75]
	v_mfma_f32_16x16x32_bf16 v[124:127], v[168:171], v[188:191], v[124:127]
	v_mfma_f32_16x16x32_bf16 v[120:123], v[176:179], v[188:191], v[120:123]
	v_mfma_f32_16x16x32_bf16 v[108:111], v[168:171], v[198:201], v[108:111]
	v_mfma_f32_16x16x32_bf16 v[104:107], v[176:179], v[198:201], v[104:107]
	v_mfma_f32_16x16x32_bf16 v[92:95], v[168:171], v[206:209], v[92:95]
	v_mfma_f32_16x16x32_bf16 v[88:91], v[176:179], v[206:209], v[88:91]
	v_mfma_f32_16x16x32_bf16 v[76:79], v[168:171], v[214:217], v[76:79]
	v_mfma_f32_16x16x32_bf16 v[72:75], v[176:179], v[214:217], v[72:75]
	s_setprio 0
	s_barrier
	s_add_i32 s0, s61, s50
	s_mov_b32 m0, s0
	ds_read_b128 v[218:221], v167
	ds_read_b128 v[222:225], v167 offset:1024
	ds_read_b128 v[226:229], v167 offset:2048
	ds_read_b128 v[230:233], v167 offset:3072
	global_load_lds_dwordx4 v130, s[36:37]
	s_add_i32 m0, s0, 0x2000
	s_nop 0
	global_load_lds_dwordx4 v134, s[36:37]
	s_barrier
; #define PG8_STAGE(bufoff, gbase, voff) do { _Pragma("unroll") for (int _i = 0; _i < 2; ++_i) \
;         __builtin_amdgcn_global_load_lds((const unsigned*)((const char*)(gbase) + (voff)[_i]), (LAS unsigned*)(lds + (bufoff) + ldsw + _i * 8192), 16, 0, 0); } while (0)
; #define PG8_LDA(dst, b, h) do { _Pragma("unroll") for (int m = 0; m < 4; ++m) _Pragma("unroll") for (int k = 0; k < 2; ++k) dst[m][k] = *(const LAS bf16x8*)(lds + PG8_SA(b, h) + aoff + m * 2048 + k * 1024); } while (0)
; #define PG8_LDB(dst, b, h) do { _Pragma("unroll") for (int n = 0; n < 2; ++n) _Pragma("unroll") for (int k = 0; k < 2; ++k) dst[n][k] = *(const LAS bf16x8*)(lds + PG8_SB(b, h) + boff + n * 2048 + k * 1024); } while (0)
; #define PG8_WAIT_V(n) asm volatile("s_waitcnt vmcnt(" #n ")" ::: "memory")
; #define PG8_WAIT_L(n) asm volatile("s_waitcnt lgkmcnt(" #n ")" ::: "memory")
; #define PG8_BAR __builtin_amdgcn_s_barrier()
; #define PG8_SCHED __builtin_amdgcn_sched_barrier(0)
; template <class Epi, class Sched>
; DI void gemm_phase(LAS unsigned char* lds, const Gemm g, const Sched& S, const Epi& E) {
;     ...
;             PG8_LDB(B0, 0, 0); PG8_SCHED; PG8_LDA(At, 0, 0); PG8_STAGE(PG8_SA(1, 1), a1 + hstep, voffA);
;             PG8_WAIT_L(8); PG8_BAR; PG8_WAIT_L(0); PG8_MMA(0, 0, At, B0); PG8_BAR; PG8_SCHED;
;             PG8_LDB(B1, 0, 1); PG8_STAGE(PG8_SB(0, 0), b2, voffB);
;             PG8_BAR; PG8_WAIT_L(0); PG8_MMA(0, 1, At, B1); PG8_BAR;
;             PG8_LDA(At, 0, 1); PG8_STAGE(PG8_SA(0, 0), a2, voffA);
;             PG8_BAR; PG8_WAIT_L(0); PG8_MMA(1, 0, At, B0); PG8_BAR; PG8_SCHED;
;             PG8_STAGE(PG8_SB(0, 1), b2 + hstep, voffB);
;             PG8_WAIT_V(6); PG8_BAR; PG8_MMA(1, 1, At, B1); PG8_BAR;
;             PG8_LDB(B0, 1, 0); PG8_SCHED; PG8_LDA(At, 1, 0); PG8_STAGE(PG8_SA(0, 1), a2 + hstep, voffA);
;             PG8_WAIT_L(8); PG8_BAR; PG8_WAIT_L(0); PG8_MMA(0, 0, At, B0); PG8_BAR; PG8_SCHED;
;             PG8_LDB(B1, 1, 1); PG8_STAGE(PG8_SB(1, 0), b3, voffB);
;             PG8_BAR; PG8_WAIT_L(0); PG8_MMA(0, 1, At, B1); PG8_BAR;
;             PG8_LDA(At, 1, 1); PG8_STAGE(PG8_SA(1, 0), a3, voffA);
;             PG8_BAR; PG8_WAIT_L(0); PG8_MMA(1, 0, At, B0); PG8_BAR; PG8_SCHED;
;             PG8_STAGE(PG8_SB(1, 1), b3 + hstep, voffB);
;             PG8_WAIT_V(6); PG8_BAR; PG8_MMA(1, 1, At, B1); PG8_BAR;
	s_waitcnt lgkmcnt(0)
	s_setprio 1
	s_waitcnt lgkmcnt(0)
	v_mfma_f32_16x16x32_bf16 v[116:119], v[218:221], v[180:183], v[116:119]
	v_mfma_f32_16x16x32_bf16 v[112:115], v[226:229], v[180:183], v[112:115]
	v_mfma_f32_16x16x32_bf16 v[100:103], v[218:221], v[194:197], v[100:103]
	v_mfma_f32_16x16x32_bf16 v[96:99], v[226:229], v[194:197], v[96:99]
	v_mfma_f32_16x16x32_bf16 v[84:87], v[218:221], v[202:205], v[84:87]
	v_mfma_f32_16x16x32_bf16 v[80:83], v[226:229], v[202:205], v[80:83]
	v_mfma_f32_16x16x32_bf16 v[68:71], v[218:221], v[210:213], v[68:71]
	v_mfma_f32_16x16x32_bf16 v[64:67], v[226:229], v[210:213], v[64:67]
	v_mfma_f32_16x16x32_bf16 v[116:119], v[222:225], v[188:191], v[116:119]
	v_mfma_f32_16x16x32_bf16 v[112:115], v[230:233], v[188:191], v[112:115]
	v_mfma_f32_16x16x32_bf16 v[100:103], v[222:225], v[198:201], v[100:103]
	v_mfma_f32_16x16x32_bf16 v[96:99], v[230:233], v[198:201], v[96:99]
	v_mfma_f32_16x16x32_bf16 v[84:87], v[222:225], v[206:209], v[84:87]
	v_mfma_f32_16x16x32_bf16 v[80:83], v[230:233], v[206:209], v[80:83]
	v_mfma_f32_16x16x32_bf16 v[68:71], v[222:225], v[214:217], v[68:71]
	v_mfma_f32_16x16x32_bf16 v[64:67], v[230:233], v[214:217], v[64:67]
	s_setprio 0
	s_mov_b32 m0, s51
	s_barrier
	ds_read_b128 v[180:183], v166 offset:16384
	ds_read_b128 v[188:191], v166 offset:17408
	ds_read_b128 v[194:197], v166 offset:18432
	ds_read_b128 v[198:201], v166 offset:19456
	ds_read_b128 v[202:205], v166 offset:20480
	ds_read_b128 v[206:209], v166 offset:21504
	ds_read_b128 v[210:213], v166 offset:22528
	ds_read_b128 v[214:217], v166 offset:23552
	global_load_lds_dwordx4 v128, s[38:39]
	s_mov_b32 m0, s52
	s_nop 0
	global_load_lds_dwordx4 v132, s[38:39]
	s_barrier
	s_waitcnt lgkmcnt(0)
	s_setprio 1
	s_waitcnt lgkmcnt(0)
	v_mfma_f32_16x16x32_bf16 v[60:63], v[144:147], v[180:183], v[60:63]
	v_mfma_f32_16x16x32_bf16 v[56:59], v[172:175], v[180:183], v[56:59]
	v_mfma_f32_16x16x32_bf16 v[44:47], v[144:147], v[194:197], v[44:47]
	v_mfma_f32_16x16x32_bf16 v[40:43], v[172:175], v[194:197], v[40:43]
	v_mfma_f32_16x16x32_bf16 v[28:31], v[144:147], v[202:205], v[28:31]
	v_mfma_f32_16x16x32_bf16 v[24:27], v[172:175], v[202:205], v[24:27]
	v_mfma_f32_16x16x32_bf16 v[12:15], v[144:147], v[210:213], v[12:15]
	v_mfma_f32_16x16x32_bf16 v[8:11], v[172:175], v[210:213], v[8:11]
	v_mfma_f32_16x16x32_bf16 v[60:63], v[168:171], v[188:191], v[60:63]
	v_mfma_f32_16x16x32_bf16 v[56:59], v[176:179], v[188:191], v[56:59]
	v_mfma_f32_16x16x32_bf16 v[44:47], v[168:171], v[198:201], v[44:47]
	v_mfma_f32_16x16x32_bf16 v[40:43], v[176:179], v[198:201], v[40:43]
	v_mfma_f32_16x16x32_bf16 v[28:31], v[168:171], v[206:209], v[28:31]
	v_mfma_f32_16x16x32_bf16 v[24:27], v[176:179], v[206:209], v[24:27]
	v_mfma_f32_16x16x32_bf16 v[12:15], v[168:171], v[214:217], v[12:15]
	v_mfma_f32_16x16x32_bf16 v[8:11], v[176:179], v[214:217], v[8:11]
	s_setprio 0
	s_barrier
	s_add_u32 s0, s36, 0x30000
	s_addc_u32 s1, s37, 0
	s_add_i32 s4, s62, s50
	s_mov_b32 m0, s4
	s_nop 0
	global_load_lds_dwordx4 v130, s[0:1]
	s_add_i32 m0, s4, 0x2000
	s_nop 0
	global_load_lds_dwordx4 v134, s[0:1]
	s_waitcnt vmcnt(6)
	s_barrier
	s_setprio 1
	v_mfma_f32_16x16x32_bf16 v[52:55], v[218:221], v[180:183], v[52:55]
	v_mfma_f32_16x16x32_bf16 v[48:51], v[226:229], v[180:183], v[48:51]
	v_mfma_f32_16x16x32_bf16 v[36:39], v[218:221], v[194:197], v[36:39]
	v_mfma_f32_16x16x32_bf16 v[32:35], v[226:229], v[194:197], v[32:35]
	v_mfma_f32_16x16x32_bf16 v[20:23], v[218:221], v[202:205], v[20:23]
	v_mfma_f32_16x16x32_bf16 v[16:19], v[226:229], v[202:205], v[16:19]
	v_mfma_f32_16x16x32_bf16 v[4:7], v[218:221], v[210:213], v[4:7]
	v_mfma_f32_16x16x32_bf16 v[0:3], v[226:229], v[210:213], v[0:3]
	v_mfma_f32_16x16x32_bf16 v[52:55], v[222:225], v[188:191], v[52:55]
	v_mfma_f32_16x16x32_bf16 v[48:51], v[230:233], v[188:191], v[48:51]
	v_mfma_f32_16x16x32_bf16 v[36:39], v[222:225], v[198:201], v[36:39]
	v_mfma_f32_16x16x32_bf16 v[32:35], v[230:233], v[198:201], v[32:35]
	v_mfma_f32_16x16x32_bf16 v[20:23], v[222:225], v[206:209], v[20:23]
	v_mfma_f32_16x16x32_bf16 v[16:19], v[230:233], v[206:209], v[16:19]
	v_mfma_f32_16x16x32_bf16 v[4:7], v[222:225], v[214:217], v[4:7]
	v_mfma_f32_16x16x32_bf16 v[0:3], v[230:233], v[214:217], v[0:3]
	s_setprio 0
	s_add_i32 s4, 0, 0x18000
	v_add_u32_e32 v150, s4, v164
	s_barrier
	ds_read_b128 v[144:147], v150
	ds_read_b128 v[168:171], v150 offset:1024
	ds_read_b128 v[172:175], v150 offset:2048
	ds_read_b128 v[176:179], v150 offset:3072
	s_add_u32 s0, s38, 0x30000
	s_addc_u32 s1, s39, 0
	s_mov_b32 m0, s53
	ds_read_b128 v[180:183], v166 offset:32768
	ds_read_b128 v[188:191], v166 offset:33792
	ds_read_b128 v[194:197], v166 offset:34816
	ds_read_b128 v[198:201], v166 offset:35840
	ds_read_b128 v[202:205], v166 offset:36864
	ds_read_b128 v[206:209], v166 offset:37888
	ds_read_b128 v[210:213], v166 offset:38912
	ds_read_b128 v[214:217], v166 offset:39936
	global_load_lds_dwordx4 v128, s[0:1]
	s_mov_b32 m0, s54
	s_nop 0
	global_load_lds_dwordx4 v132, s[0:1]
	s_waitcnt lgkmcnt(8)
	s_barrier
; #define PG8_STAGE(bufoff, gbase, voff) do { _Pragma("unroll") for (int _i = 0; _i < 2; ++_i) \
;         __builtin_amdgcn_global_load_lds((const unsigned*)((const char*)(gbase) + (voff)[_i]), (LAS unsigned*)(lds + (bufoff) + ldsw + _i * 8192), 16, 0, 0); } while (0)
; #define PG8_LDA(dst, b, h) do { _Pragma("unroll") for (int m = 0; m < 4; ++m) _Pragma("unroll") for (int k = 0; k < 2; ++k) dst[m][k] = *(const LAS bf16x8*)(lds + PG8_SA(b, h) + aoff + m * 2048 + k * 1024); } while (0)
; #define PG8_LDB(dst, b, h) do { _Pragma("unroll") for (int n = 0; n < 2; ++n) _Pragma("unroll") for (int k = 0; k < 2; ++k) dst[n][k] = *(const LAS bf16x8*)(lds + PG8_SB(b, h) + boff + n * 2048 + k * 1024); } while (0)
; #define PG8_WAIT_V(n) asm volatile("s_waitcnt vmcnt(" #n ")" ::: "memory")
; #define PG8_WAIT_L(n) asm volatile("s_waitcnt lgkmcnt(" #n ")" ::: "memory")
; #define PG8_BAR __builtin_amdgcn_s_barrier()
; #define PG8_SCHED __builtin_amdgcn_sched_barrier(0)
; template <class Epi, class Sched>
; DI void gemm_phase(LAS unsigned char* lds, const Gemm g, const Sched& S, const Epi& E) {
;     ...
;             PG8_LDB(B0, 0, 0); PG8_SCHED; PG8_LDA(At, 0, 0); PG8_STAGE(PG8_SA(1, 1), a1 + hstep, voffA);
;             PG8_WAIT_L(8); PG8_BAR; PG8_WAIT_L(0); PG8_MMA(0, 0, At, B0); PG8_BAR; PG8_SCHED;
;             PG8_LDB(B1, 0, 1); PG8_STAGE(PG8_SB(0, 0), b2, voffB);
;             PG8_BAR; PG8_WAIT_L(0); PG8_MMA(0, 1, At, B1); PG8_BAR;
;             PG8_LDA(At, 0, 1); PG8_STAGE(PG8_SA(0, 0), a2, voffA);
;             PG8_BAR; PG8_WAIT_L(0); PG8_MMA(1, 0, At, B0); PG8_BAR; PG8_SCHED;
;             PG8_STAGE(PG8_SB(0, 1), b2 + hstep, voffB);
;             PG8_WAIT_V(6); PG8_BAR; PG8_MMA(1, 1, At, B1); PG8_BAR;
;             PG8_LDB(B0, 1, 0); PG8_SCHED; PG8_LDA(At, 1, 0); PG8_STAGE(PG8_SA(0, 1), a2 + hstep, voffA);
;             PG8_WAIT_L(8); PG8_BAR; PG8_WAIT_L(0); PG8_MMA(0, 0, At, B0); PG8_BAR; PG8_SCHED;
;             PG8_LDB(B1, 1, 1); PG8_STAGE(PG8_SB(1, 0), b3, voffB);
;             PG8_BAR; PG8_WAIT_L(0); PG8_MMA(0, 1, At, B1); PG8_BAR;
;             PG8_LDA(At, 1, 1); PG8_STAGE(PG8_SA(1, 0), a3, voffA);
;             PG8_BAR; PG8_WAIT_L(0); PG8_MMA(1, 0, At, B0); PG8_BAR; PG8_SCHED;
;             PG8_STAGE(PG8_SB(1, 1), b3 + hstep, voffB);
;             PG8_WAIT_V(6); PG8_BAR; PG8_MMA(1, 1, At, B1); PG8_BAR;
	s_waitcnt lgkmcnt(0)
	s_setprio 1
	s_waitcnt lgkmcnt(0)
	v_mfma_f32_16x16x32_bf16 v[124:127], v[144:147], v[180:183], v[124:127]
	v_mfma_f32_16x16x32_bf16 v[120:123], v[172:175], v[180:183], v[120:123]
	v_mfma_f32_16x16x32_bf16 v[108:111], v[144:147], v[194:197], v[108:111]
	v_mfma_f32_16x16x32_bf16 v[104:107], v[172:175], v[194:197], v[104:107]
	v_mfma_f32_16x16x32_bf16 v[92:95], v[144:147], v[202:205], v[92:95]
	v_mfma_f32_16x16x32_bf16 v[88:91], v[172:175], v[202:205], v[88:91]
	v_mfma_f32_16x16x32_bf16 v[76:79], v[144:147], v[210:213], v[76:79]
	v_mfma_f32_16x16x32_bf16 v[72:75], v[172:175], v[210:213], v[72:75]
	v_mfma_f32_16x16x32_bf16 v[124:127], v[168:171], v[188:191], v[124:127]
	v_mfma_f32_16x16x32_bf16 v[120:123], v[176:179], v[188:191], v[120:123]
	v_mfma_f32_16x16x32_bf16 v[108:111], v[168:171], v[198:201], v[108:111]
	v_mfma_f32_16x16x32_bf16 v[104:107], v[176:179], v[198:201], v[104:107]
	v_mfma_f32_16x16x32_bf16 v[92:95], v[168:171], v[206:209], v[92:95]
	v_mfma_f32_16x16x32_bf16 v[88:91], v[176:179], v[206:209], v[88:91]
	v_mfma_f32_16x16x32_bf16 v[76:79], v[168:171], v[214:217], v[76:79]
	v_mfma_f32_16x16x32_bf16 v[72:75], v[176:179], v[214:217], v[72:75]
	s_setprio 0
	s_barrier
	s_add_i32 s5, 0, 0x1c000
	s_add_i32 s0, s4, s50
	v_add_u32_e32 v150, s5, v164
	s_add_i32 m0, s0, 0xffffff80
	ds_read_b128 v[218:221], v150
	ds_read_b128 v[222:225], v150 offset:1024
	ds_read_b128 v[226:229], v150 offset:2048
	ds_read_b128 v[230:233], v150 offset:3072
	global_load_lds_dwordx4 v130, s[36:37] offset:128
	s_add_i32 m0, s0, 0x1f80
	s_nop 0
	global_load_lds_dwordx4 v134, s[36:37] offset:128
	s_barrier
	s_waitcnt lgkmcnt(0)
	s_setprio 1
	s_waitcnt lgkmcnt(0)
	v_mfma_f32_16x16x32_bf16 v[116:119], v[218:221], v[180:183], v[116:119]
	v_mfma_f32_16x16x32_bf16 v[112:115], v[226:229], v[180:183], v[112:115]
	v_mfma_f32_16x16x32_bf16 v[100:103], v[218:221], v[194:197], v[100:103]
	v_mfma_f32_16x16x32_bf16 v[96:99], v[226:229], v[194:197], v[96:99]
	v_mfma_f32_16x16x32_bf16 v[84:87], v[218:221], v[202:205], v[84:87]
	v_mfma_f32_16x16x32_bf16 v[80:83], v[226:229], v[202:205], v[80:83]
	v_mfma_f32_16x16x32_bf16 v[68:71], v[218:221], v[210:213], v[68:71]
	v_mfma_f32_16x16x32_bf16 v[64:67], v[226:229], v[210:213], v[64:67]
	v_mfma_f32_16x16x32_bf16 v[116:119], v[222:225], v[188:191], v[116:119]
	v_mfma_f32_16x16x32_bf16 v[112:115], v[230:233], v[188:191], v[112:115]
	v_mfma_f32_16x16x32_bf16 v[100:103], v[222:225], v[198:201], v[100:103]
	v_mfma_f32_16x16x32_bf16 v[96:99], v[230:233], v[198:201], v[96:99]
	v_mfma_f32_16x16x32_bf16 v[84:87], v[222:225], v[206:209], v[84:87]
	v_mfma_f32_16x16x32_bf16 v[80:83], v[230:233], v[206:209], v[80:83]
	v_mfma_f32_16x16x32_bf16 v[68:71], v[222:225], v[214:217], v[68:71]
	v_mfma_f32_16x16x32_bf16 v[64:67], v[230:233], v[214:217], v[64:67]
	s_setprio 0
	s_add_i32 m0, s57, 0xffffff80
	s_barrier
	ds_read_b128 v[180:183], v166 offset:49152
	ds_read_b128 v[188:191], v166 offset:50176
	ds_read_b128 v[194:197], v166 offset:51200
	ds_read_b128 v[198:201], v166 offset:52224
	ds_read_b128 v[202:205], v166 offset:53248
	ds_read_b128 v[206:209], v166 offset:54272
	ds_read_b128 v[210:213], v166 offset:55296
	ds_read_b128 v[214:217], v166 offset:56320
	global_load_lds_dwordx4 v128, s[38:39] offset:128
	s_add_i32 m0, s58, 0xffffff80
	s_nop 0
	global_load_lds_dwordx4 v132, s[38:39] offset:128
	s_barrier
	s_waitcnt lgkmcnt(0)
	s_setprio 1
	s_waitcnt lgkmcnt(0)
	v_mfma_f32_16x16x32_bf16 v[60:63], v[144:147], v[180:183], v[60:63]
	v_mfma_f32_16x16x32_bf16 v[56:59], v[172:175], v[180:183], v[56:59]
	v_mfma_f32_16x16x32_bf16 v[44:47], v[144:147], v[194:197], v[44:47]
	v_mfma_f32_16x16x32_bf16 v[40:43], v[172:175], v[194:197], v[40:43]
	v_mfma_f32_16x16x32_bf16 v[28:31], v[144:147], v[202:205], v[28:31]
	v_mfma_f32_16x16x32_bf16 v[24:27], v[172:175], v[202:205], v[24:27]
	v_mfma_f32_16x16x32_bf16 v[12:15], v[144:147], v[210:213], v[12:15]
	v_mfma_f32_16x16x32_bf16 v[8:11], v[172:175], v[210:213], v[8:11]
	v_mfma_f32_16x16x32_bf16 v[60:63], v[168:171], v[188:191], v[60:63]
	v_mfma_f32_16x16x32_bf16 v[56:59], v[176:179], v[188:191], v[56:59]
	v_mfma_f32_16x16x32_bf16 v[44:47], v[168:171], v[198:201], v[44:47]
	v_mfma_f32_16x16x32_bf16 v[40:43], v[176:179], v[198:201], v[40:43]
	v_mfma_f32_16x16x32_bf16 v[28:31], v[168:171], v[206:209], v[28:31]
	v_mfma_f32_16x16x32_bf16 v[24:27], v[176:179], v[206:209], v[24:27]
	v_mfma_f32_16x16x32_bf16 v[12:15], v[168:171], v[214:217], v[12:15]
	v_mfma_f32_16x16x32_bf16 v[8:11], v[176:179], v[214:217], v[8:11]
	s_setprio 0
	s_barrier
	s_add_u32 s0, s36, 0x30080
	s_addc_u32 s1, s37, 0
	s_add_i32 s4, s5, s50
	s_mov_b32 m0, s4
	s_nop 0
	global_load_lds_dwordx4 v130, s[0:1]
	s_add_i32 m0, s4, 0x2000
	s_nop 0
	global_load_lds_dwordx4 v134, s[0:1]
	s_waitcnt vmcnt(6)
	s_barrier
	s_setprio 1
	v_mfma_f32_16x16x32_bf16 v[52:55], v[218:221], v[180:183], v[52:55]
	v_mfma_f32_16x16x32_bf16 v[48:51], v[226:229], v[180:183], v[48:51]
	v_mfma_f32_16x16x32_bf16 v[36:39], v[218:221], v[194:197], v[36:39]
	v_mfma_f32_16x16x32_bf16 v[32:35], v[226:229], v[194:197], v[32:35]
	v_mfma_f32_16x16x32_bf16 v[20:23], v[218:221], v[202:205], v[20:23]
	v_mfma_f32_16x16x32_bf16 v[16:19], v[226:229], v[202:205], v[16:19]
	v_mfma_f32_16x16x32_bf16 v[4:7], v[218:221], v[210:213], v[4:7]
	v_mfma_f32_16x16x32_bf16 v[0:3], v[226:229], v[210:213], v[0:3]
	v_mfma_f32_16x16x32_bf16 v[52:55], v[222:225], v[188:191], v[52:55]
	v_mfma_f32_16x16x32_bf16 v[48:51], v[230:233], v[188:191], v[48:51]
	v_mfma_f32_16x16x32_bf16 v[36:39], v[222:225], v[198:201], v[36:39]
	v_mfma_f32_16x16x32_bf16 v[32:35], v[230:233], v[198:201], v[32:35]
	v_mfma_f32_16x16x32_bf16 v[20:23], v[222:225], v[206:209], v[20:23]
	v_mfma_f32_16x16x32_bf16 v[16:19], v[230:233], v[206:209], v[16:19]
	v_mfma_f32_16x16x32_bf16 v[4:7], v[222:225], v[214:217], v[4:7]
	v_mfma_f32_16x16x32_bf16 v[0:3], v[230:233], v[214:217], v[0:3]
	s_setprio 0
	s_add_i32 s41, s41, 2
	s_add_u32 s8, s8, 0x100
	s_addc_u32 s9, s9, 0
	s_add_u32 s35, s35, 0x100
	s_addc_u32 s40, s40, 0
	s_cmp_gt_u32 s41, 9
	s_barrier
	s_cbranch_scc0 .LBB0_938

;     DI size_t aoff(const Unit& u, size_t tstep) const { return (size_t)u.pm * tstep; }
;     DI size_t boff(const Unit& u, size_t tstep) const { return (size_t)u.pn * tstep; }
;     DI size_t aoff(const Unit& u, size_t) const { return (size_t)u.ks * kbytes; }
;     DI size_t boff(const Unit& u, size_t tstep) const { return (size_t)u.pn * tstep + (size_t)u.ks * kbytes; }
;     DI size_t aoff(const Unit& u, size_t tstep) const { return (u.ks < 2 ? offU : offOA) + (size_t)u.pm * tstep; }
; #define PG8_STAGE(bufoff, gbase, voff) do { _Pragma("unroll") for (int _i = 0; _i < 2; ++_i) \
;         __builtin_amdgcn_global_load_lds((const unsigned*)((const char*)(gbase) + (voff)[_i]), (LAS unsigned*)(lds + (bufoff) + ldsw + _i * 8192), 16, 0, 0); } while (0)
; #define PG8_WAIT_V(n) asm volatile("s_waitcnt vmcnt(" #n ")" ::: "memory")
; #define PG8_BAR __builtin_amdgcn_s_barrier()
; template <class Epi, class Sched>
; DI void gemm_phase(LAS unsigned char* lds, const Gemm g, const Sched& S, const Epi& E) {
;     ...
;     const char* cA = (const char*)g.A + S.aoff(cur, tstep); const char* cB = (const char*)g.Bt + S.boff(cur, tstep);
;     PG8_STAGE(PG8_SB(0, 0), cB, voffB); PG8_STAGE(PG8_SA(0, 0), cA, voffA); PG8_STAGE(PG8_SB(0, 1), cB + hstep, voffB); PG8_STAGE(PG8_SA(0, 1), cA + hstep, voffA);
;     if (wr == 1) PG8_BAR;
;     PG8_WAIT_V(4); PG8_BAR;
;     PG8_STAGE(PG8_SB(1, 0), cB + kstep, voffB); PG8_STAGE(PG8_SA(1, 0), cA + kstep, voffA); PG8_STAGE(PG8_SB(1, 1), cB + hstep + kstep, voffB);
;     PG8_WAIT_V(6); PG8_BAR;
.LBB0_979:
	s_lshl_b32 s0, s0, 5
	s_lshl_b32 s60, s1, 6
	s_lshl_b32 s4, s1, 13
	s_and_b32 s61, s0, 0x60
	s_add_u32 s10, s22, 0x2c30b000
	s_addc_u32 s11, s23, 0
	s_add_u32 s14, s22, 0x3438b000
	s_addc_u32 s15, s23, 0
	s_add_u32 s16, s22, 0x3838b000
	s_mov_b64 s[18:19], 0x80
	s_addc_u32 s17, s23, 0
	s_add_i32 m0, s55, 0x18000
	v_lshl_add_u64 v[6:7], v[6:7], 0, s[18:19]
	s_waitcnt vmcnt(4)
	s_barrier
	global_load_lds_dwordx4 v[6:7], off
	v_lshl_add_u64 v[4:5], v[4:5], 0, s[18:19]
	s_add_i32 m0, s55, 0x1a000
	s_add_i32 s62, s55, 0x8000
	s_add_i32 s63, s55, 0xa000
	global_load_lds_dwordx4 v[4:5], off
	v_lshl_add_u64 v[2:3], v[2:3], 0, s[18:19]
	s_mov_b32 m0, s62
	s_add_u32 s0, s44, 0x20080
	global_load_lds_dwordx4 v[2:3], off
	v_lshl_add_u64 v[0:1], v[0:1], 0, s[18:19]
	s_mov_b32 m0, s63
	s_addc_u32 s1, s45, 0
	global_load_lds_dwordx4 v[0:1], off
	s_add_i32 m0, s55, 0x1c000
	s_nop 0
	global_load_lds_dwordx4 v130, s[0:1]
	s_add_i32 m0, s55, 0x1e000
	v_lshlrev_b32_e32 v2, 10, v153
	global_load_lds_dwordx4 v134, s[0:1]
	v_lshlrev_b32_e32 v1, 2, v154
	v_lshl_or_b32 v0, v154, 6, v157
	v_and_b32_e32 v1, 32, v1
	v_bitop3_b32 v0, v0, s4, v1 bitop3:0xde
	v_lshlrev_b32_e32 v1, 7, v184
	v_and_b32_e32 v1, 0x1c000, v1
	v_or3_b32 v1, v151, v1, v2
	v_add_u32_e32 v138, v1, v152
	v_lshlrev_b32_e32 v1, 3, v156
	s_waitcnt vmcnt(6)
	v_and_b32_e32 v1, 0x3c000, v1
	v_lshl_or_b32 v157, s61, 7, v158
	v_or3_b32 v1, v151, v1, v2
	s_add_i32 s66, 0, 0x10000
	s_add_i32 s67, 0, 0x14000
	s_ashr_i32 s64, s48, 31
	v_mov_b32_e32 v139, v137
	v_add_u32_e32 v140, v1, v152
	v_mov_b32_e32 v141, v137
	v_mov_b64_e32 v[142:143], 0x808
	v_mov_b64_e32 v[144:145], 0x807
	s_movk_i32 s65, 0x102
	v_add_u32_e32 v156, s66, v157
	v_add_u32_e32 v158, 0, v0
	v_add_u32_e32 v159, s67, v157
	s_movk_i32 s68, 0x7fff
	s_mov_b32 s69, 0xfe03f81
	s_movk_i32 s70, 0xefe0
	s_movk_i32 s71, 0x2040
	s_movk_i32 s72, 0x7fef
	s_movk_i32 s73, 0x7fdf
	s_movk_i32 s74, 0x7fcf
	s_movk_i32 s75, 0x7f7f
	s_movk_i32 s76, 0x7f6f
	s_movk_i32 s77, 0x7f5f
	s_movk_i32 s78, 0x7f4f
	s_barrier
	s_branch .LBB0_981

;     DI size_t aoff(const Unit& u, size_t tstep) const { return (size_t)u.pm * tstep; }
;     DI size_t boff(const Unit& u, size_t tstep) const { return (size_t)u.pn * tstep; }
;     DI bool next(int i, Unit& u) const { const long L = (long)i * G + c; if (L >= np) return false; u.pm = pmv; u.pn = (int)(L % nN); u.ks = (int)(L / nN); return true; }
;     DI size_t aoff(const Unit& u, size_t) const { return (size_t)u.ks * kbytes; }
;     DI size_t boff(const Unit& u, size_t tstep) const { return (size_t)u.pn * tstep + (size_t)u.ks * kbytes; }
;     DI bool next(int i, Unit& u) const { Unit t; if (!S.next(i / 3, t)) return false; u.pm = t.pm; u.pn = t.pn; u.ks = i % 3; return true; }
; template <class Epi, class Sched>
; DI void gemm_phase(LAS unsigned char* lds, const Gemm g, const Sched& S, const Epi& E) {
;     ...
;         const bool has_next = S.next(ui + 1, nxt);
;         const char* nA = has_next ? (const char*)g.A + S.aoff(nxt, tstep) : cA; const char* nB = has_next ? (const char*)g.Bt + S.boff(nxt, tstep) : cB;
;         for (int t = 0; t < nt; t += 2) {
;             if constexpr (Epi::HAS_MID) { if (t == E.mid_t(nt)) { int fr3 = fr, fq3 = fq; asm volatile("" : "+v"(fr3), "+v"(fq3)); E.mid(acc, cur, wr, wc, fr3, fq3); } }
;             const bool last = (t == nt - 2);
;             const char* a1 = cA + (size_t)(t + 1) * kstep;
;             const char* a2 = last ? nA : cA + (size_t)(t + 2) * kstep; const char* b2 = last ? nB : cB + (size_t)(t + 2) * kstep;
;             const char* a3 = a2 + kstep; const char* b3 = b2 + kstep;
;             PG8_LDB(B0, 0, 0); PG8_SCHED; PG8_LDA(At, 0, 0); PG8_STAGE(PG8_SA(1, 1), a1 + hstep, voffA);
;             PG8_WAIT_L(8); PG8_BAR; PG8_WAIT_L(0); PG8_MMA(0, 0, At, B0); PG8_BAR; PG8_SCHED;
;             PG8_LDB(B1, 0, 1); PG8_STAGE(PG8_SB(0, 0), b2, voffB);
;             PG8_BAR; PG8_WAIT_L(0); PG8_MMA(0, 1, At, B1); PG8_BAR;
;             PG8_LDA(At, 0, 1); PG8_STAGE(PG8_SA(0, 0), a2, voffA);
;             PG8_BAR; PG8_WAIT_L(0); PG8_MMA(1, 0, At, B0); PG8_BAR; PG8_SCHED;
;             PG8_STAGE(PG8_SB(0, 1), b2 + hstep, voffB);
;             PG8_WAIT_V(6); PG8_BAR; PG8_MMA(1, 1, At, B1); PG8_BAR;
;             PG8_LDB(B0, 1, 0); PG8_SCHED; PG8_LDA(At, 1, 0); PG8_STAGE(PG8_SA(0, 1), a2 + hstep, voffA);
;             PG8_WAIT_L(8); PG8_BAR; PG8_WAIT_L(0); PG8_MMA(0, 0, At, B0); PG8_BAR; PG8_SCHED;
.LBB0_983:
	s_ashr_i32 s31, s30, 31
	s_lshl_b64 s[0:1], s[30:31], 18
	v_cmp_lt_i64_e32 vcc, s[36:37], v[142:143]
	s_add_u32 s36, s51, s0
	s_addc_u32 s37, s52, s1
	s_and_b64 s[0:1], vcc, exec
	s_cselect_b32 s9, s37, s43
	s_cselect_b32 s31, s36, s42
	s_ashr_i32 s29, s28, 31
	s_lshl_b64 s[0:1], s[28:29], 18
	s_add_u32 s38, s53, s0
	s_addc_u32 s39, s54, s1
	s_and_b64 s[0:1], vcc, exec
	s_cselect_b32 s29, s39, s45
	s_cselect_b32 s34, s38, s44
	s_add_u32 s42, s42, 0x20080
	s_addc_u32 s43, s43, 0
	s_add_u32 s35, s44, 0x100
	v_mov_b32_e32 v0, 0
	s_addc_u32 s41, s45, 0
	s_mov_b32 s79, -2
	ds_read_b128 v[146:149], v156
	ds_read_b128 v[150:153], v156 offset:1024
	ds_read_b128 v[160:163], v156 offset:2048
	ds_read_b128 v[164:167], v156 offset:3072
	s_add_u32 s0, s42, 0xfffe0080
	s_addc_u32 s1, s43, -1
	s_cmp_eq_u32 s79, 4
	s_cselect_b32 s47, s9, s1
	s_cselect_b32 s46, s31, s0
	s_cselect_b32 s45, s29, s41
	s_cselect_b32 s44, s34, s35
	s_add_i32 m0, s55, 0xc000
	ds_read_b128 v[168:171], v158
	ds_read_b128 v[172:175], v158 offset:1024
	ds_read_b128 v[176:179], v158 offset:2048
	ds_read_b128 v[180:183], v158 offset:3072
	ds_read_b128 v[188:191], v158 offset:4096
	ds_read_b128 v[194:197], v158 offset:5120
	ds_read_b128 v[198:201], v158 offset:6144
	ds_read_b128 v[202:205], v158 offset:7168
	global_load_lds_dwordx4 v138, s[42:43]
	s_add_i32 m0, s55, 0xe000
	s_nop 0
	global_load_lds_dwordx4 v140, s[42:43]
	s_waitcnt lgkmcnt(8)
	s_barrier
	s_waitcnt lgkmcnt(0)
	s_setprio 1
	s_waitcnt lgkmcnt(0)
	v_mfma_f32_16x16x32_bf16 v[124:127], v[146:149], v[168:171], 0
	v_mfma_f32_16x16x32_bf16 v[120:123], v[160:163], v[168:171], 0
	v_mfma_f32_16x16x32_bf16 v[108:111], v[146:149], v[176:179], 0
	v_mfma_f32_16x16x32_bf16 v[104:107], v[160:163], v[176:179], 0
	v_mfma_f32_16x16x32_bf16 v[92:95], v[146:149], v[188:191], 0
	v_mfma_f32_16x16x32_bf16 v[88:91], v[160:163], v[188:191], 0
	v_mfma_f32_16x16x32_bf16 v[76:79], v[146:149], v[198:201], 0
	v_mfma_f32_16x16x32_bf16 v[72:75], v[160:163], v[198:201], 0
	v_mfma_f32_16x16x32_bf16 v[124:127], v[150:153], v[172:175], v[124:127]
	v_mfma_f32_16x16x32_bf16 v[120:123], v[164:167], v[172:175], v[120:123]
	v_mfma_f32_16x16x32_bf16 v[108:111], v[150:153], v[180:183], v[108:111]
	v_mfma_f32_16x16x32_bf16 v[104:107], v[164:167], v[180:183], v[104:107]
	v_mfma_f32_16x16x32_bf16 v[92:95], v[150:153], v[194:197], v[92:95]
	v_mfma_f32_16x16x32_bf16 v[88:91], v[164:167], v[194:197], v[88:91]
	v_mfma_f32_16x16x32_bf16 v[76:79], v[150:153], v[202:205], v[76:79]
	v_mfma_f32_16x16x32_bf16 v[72:75], v[164:167], v[202:205], v[72:75]
	s_setprio 0
	s_barrier
	s_add_i32 s0, s66, s50
	s_mov_b32 m0, s0
	ds_read_b128 v[206:209], v159
	ds_read_b128 v[210:213], v159 offset:1024
	ds_read_b128 v[214:217], v159 offset:2048
	ds_read_b128 v[218:221], v159 offset:3072
	global_load_lds_dwordx4 v130, s[44:45]
	s_add_i32 m0, s0, 0x2000
	s_nop 0
	global_load_lds_dwordx4 v134, s[44:45]
	s_barrier
	s_waitcnt lgkmcnt(0)
	s_setprio 1
	s_waitcnt lgkmcnt(0)
	v_mfma_f32_16x16x32_bf16 v[116:119], v[206:209], v[168:171], 0
	v_mfma_f32_16x16x32_bf16 v[112:115], v[214:217], v[168:171], 0
	v_mfma_f32_16x16x32_bf16 v[100:103], v[206:209], v[176:179], 0
	v_mfma_f32_16x16x32_bf16 v[96:99], v[214:217], v[176:179], 0
	v_mfma_f32_16x16x32_bf16 v[84:87], v[206:209], v[188:191], 0
	v_mfma_f32_16x16x32_bf16 v[80:83], v[214:217], v[188:191], 0
	v_mfma_f32_16x16x32_bf16 v[68:71], v[206:209], v[198:201], 0
	v_mfma_f32_16x16x32_bf16 v[64:67], v[214:217], v[198:201], 0
	v_mfma_f32_16x16x32_bf16 v[116:119], v[210:213], v[172:175], v[116:119]
	v_mfma_f32_16x16x32_bf16 v[112:115], v[218:221], v[172:175], v[112:115]
	v_mfma_f32_16x16x32_bf16 v[100:103], v[210:213], v[180:183], v[100:103]
	v_mfma_f32_16x16x32_bf16 v[96:99], v[218:221], v[180:183], v[96:99]
	v_mfma_f32_16x16x32_bf16 v[84:87], v[210:213], v[194:197], v[84:87]
	v_mfma_f32_16x16x32_bf16 v[80:83], v[218:221], v[194:197], v[80:83]
	v_mfma_f32_16x16x32_bf16 v[68:71], v[210:213], v[202:205], v[68:71]
	v_mfma_f32_16x16x32_bf16 v[64:67], v[218:221], v[202:205], v[64:67]
	s_setprio 0
	s_mov_b32 m0, s55
	s_barrier
	ds_read_b128 v[168:171], v158 offset:16384
	ds_read_b128 v[172:175], v158 offset:17408
	ds_read_b128 v[176:179], v158 offset:18432
	ds_read_b128 v[180:183], v158 offset:19456
	ds_read_b128 v[188:191], v158 offset:20480
	ds_read_b128 v[194:197], v158 offset:21504
	ds_read_b128 v[198:201], v158 offset:22528
	ds_read_b128 v[202:205], v158 offset:23552
	global_load_lds_dwordx4 v128, s[46:47]
	s_mov_b32 m0, s56
	s_nop 0
	global_load_lds_dwordx4 v132, s[46:47]
	s_barrier
	s_waitcnt lgkmcnt(0)
	s_setprio 1
	s_waitcnt lgkmcnt(0)
	v_mfma_f32_16x16x32_bf16 v[60:63], v[146:149], v[168:171], 0
	v_mfma_f32_16x16x32_bf16 v[56:59], v[160:163], v[168:171], 0
	v_mfma_f32_16x16x32_bf16 v[44:47], v[146:149], v[176:179], 0
	v_mfma_f32_16x16x32_bf16 v[40:43], v[160:163], v[176:179], 0
	v_mfma_f32_16x16x32_bf16 v[28:31], v[146:149], v[188:191], 0
	v_mfma_f32_16x16x32_bf16 v[24:27], v[160:163], v[188:191], 0
	v_mfma_f32_16x16x32_bf16 v[12:15], v[146:149], v[198:201], 0
	v_mfma_f32_16x16x32_bf16 v[8:11], v[160:163], v[198:201], 0
	v_mfma_f32_16x16x32_bf16 v[60:63], v[150:153], v[172:175], v[60:63]
	v_mfma_f32_16x16x32_bf16 v[56:59], v[164:167], v[172:175], v[56:59]
	v_mfma_f32_16x16x32_bf16 v[44:47], v[150:153], v[180:183], v[44:47]
	v_mfma_f32_16x16x32_bf16 v[40:43], v[164:167], v[180:183], v[40:43]
	v_mfma_f32_16x16x32_bf16 v[28:31], v[150:153], v[194:197], v[28:31]
	v_mfma_f32_16x16x32_bf16 v[24:27], v[164:167], v[194:197], v[24:27]
	v_mfma_f32_16x16x32_bf16 v[12:15], v[150:153], v[202:205], v[12:15]
	v_mfma_f32_16x16x32_bf16 v[8:11], v[164:167], v[202:205], v[8:11]
	s_setprio 0
	s_barrier
; #define PG8_STAGE(bufoff, gbase, voff) do { _Pragma("unroll") for (int _i = 0; _i < 2; ++_i) \
;         __builtin_amdgcn_global_load_lds((const unsigned*)((const char*)(gbase) + (voff)[_i]), (LAS unsigned*)(lds + (bufoff) + ldsw + _i * 8192), 16, 0, 0); } while (0)
; #define PG8_LDA(dst, b, h) do { _Pragma("unroll") for (int m = 0; m < 4; ++m) _Pragma("unroll") for (int k = 0; k < 2; ++k) dst[m][k] = *(const LAS bf16x8*)(lds + PG8_SA(b, h) + aoff + m * 2048 + k * 1024); } while (0)
; #define PG8_LDB(dst, b, h) do { _Pragma("unroll") for (int n = 0; n < 2; ++n) _Pragma("unroll") for (int k = 0; k < 2; ++k) dst[n][k] = *(const LAS bf16x8*)(lds + PG8_SB(b, h) + boff + n * 2048 + k * 1024); } while (0)
; #define PG8_MMA(ai, bj, At, Bt) do { __builtin_amdgcn_s_setprio(1); _Pragma("unroll") for (int m = 0; m < 4; ++m) _Pragma("unroll") for (int n = 0; n < 2; ++n) _Pragma("unroll") for (int k = 0; k < 2; ++k) \
;         acc[ai][bj][m][n] = __builtin_amdgcn_mfma_f32_16x16x32_bf16(Bt[n][k], At[m][k], acc[ai][bj][m][n], 0, 0, 0); __builtin_amdgcn_s_setprio(0); } while (0)
; #define PG8_WAIT_V(n) asm volatile("s_waitcnt vmcnt(" #n ")" ::: "memory")
; #define PG8_WAIT_L(n) asm volatile("s_waitcnt lgkmcnt(" #n ")" ::: "memory")
; #define PG8_BAR __builtin_amdgcn_s_barrier()
; #define PG8_SCHED __builtin_amdgcn_sched_barrier(0)
; template <class Epi, class Sched>
; DI void gemm_phase(LAS unsigned char* lds, const Gemm g, const Sched& S, const Epi& E) {
;     ...
;             PG8_STAGE(PG8_SB(0, 1), b2 + hstep, voffB);
;             PG8_WAIT_V(6); PG8_BAR; PG8_MMA(1, 1, At, B1); PG8_BAR;
;             PG8_LDB(B0, 1, 0); PG8_SCHED; PG8_LDA(At, 1, 0); PG8_STAGE(PG8_SA(0, 1), a2 + hstep, voffA);
;             PG8_WAIT_L(8); PG8_BAR; PG8_WAIT_L(0); PG8_MMA(0, 0, At, B0); PG8_BAR; PG8_SCHED;
;             PG8_LDB(B1, 1, 1); PG8_STAGE(PG8_SB(1, 0), b3, voffB);
;             PG8_BAR; PG8_WAIT_L(0); PG8_MMA(0, 1, At, B1); PG8_BAR;
;             PG8_LDA(At, 1, 1); PG8_STAGE(PG8_SA(1, 0), a3, voffA);
;             PG8_BAR; PG8_WAIT_L(0); PG8_MMA(1, 0, At, B0); PG8_BAR; PG8_SCHED;
;             PG8_STAGE(PG8_SB(1, 1), b3 + hstep, voffB);
;             PG8_WAIT_V(6); PG8_BAR; PG8_MMA(1, 1, At, B1); PG8_BAR;
	s_add_u32 s0, s44, 0x20000
	s_addc_u32 s1, s45, 0
	s_add_i32 s4, s67, s50
	s_mov_b32 m0, s4
	s_nop 0
	global_load_lds_dwordx4 v130, s[0:1]
	s_add_i32 m0, s4, 0x2000
	s_nop 0
	global_load_lds_dwordx4 v134, s[0:1]
	s_waitcnt vmcnt(6)
	s_barrier
	s_setprio 1
	v_mfma_f32_16x16x32_bf16 v[52:55], v[206:209], v[168:171], 0
	v_mfma_f32_16x16x32_bf16 v[48:51], v[214:217], v[168:171], 0
	v_mfma_f32_16x16x32_bf16 v[36:39], v[206:209], v[176:179], 0
	v_mfma_f32_16x16x32_bf16 v[32:35], v[214:217], v[176:179], 0
	v_mfma_f32_16x16x32_bf16 v[20:23], v[206:209], v[188:191], 0
	v_mfma_f32_16x16x32_bf16 v[16:19], v[214:217], v[188:191], 0
	v_mfma_f32_16x16x32_bf16 v[4:7], v[206:209], v[198:201], 0
	v_mfma_f32_16x16x32_bf16 v[0:3], v[214:217], v[198:201], 0
	v_mfma_f32_16x16x32_bf16 v[52:55], v[210:213], v[172:175], v[52:55]
	v_mfma_f32_16x16x32_bf16 v[48:51], v[218:221], v[172:175], v[48:51]
	v_mfma_f32_16x16x32_bf16 v[36:39], v[210:213], v[180:183], v[36:39]
	v_mfma_f32_16x16x32_bf16 v[32:35], v[218:221], v[180:183], v[32:35]
	v_mfma_f32_16x16x32_bf16 v[20:23], v[210:213], v[194:197], v[20:23]
	v_mfma_f32_16x16x32_bf16 v[16:19], v[218:221], v[194:197], v[16:19]
	v_mfma_f32_16x16x32_bf16 v[4:7], v[210:213], v[202:205], v[4:7]
	v_mfma_f32_16x16x32_bf16 v[0:3], v[218:221], v[202:205], v[0:3]
	s_setprio 0
	s_add_i32 s4, 0, 0x18000
	v_add_u32_e32 v136, s4, v157
	s_barrier
	ds_read_b128 v[146:149], v136
	ds_read_b128 v[150:153], v136 offset:1024
	ds_read_b128 v[160:163], v136 offset:2048
	ds_read_b128 v[164:167], v136 offset:3072
	s_add_u32 s0, s46, 0x20000
	s_addc_u32 s1, s47, 0
	s_mov_b32 m0, s57
	ds_read_b128 v[168:171], v158 offset:32768
	ds_read_b128 v[172:175], v158 offset:33792
	ds_read_b128 v[176:179], v158 offset:34816
	ds_read_b128 v[180:183], v158 offset:35840
	ds_read_b128 v[188:191], v158 offset:36864
	ds_read_b128 v[194:197], v158 offset:37888
	ds_read_b128 v[198:201], v158 offset:38912
	ds_read_b128 v[202:205], v158 offset:39936
	global_load_lds_dwordx4 v128, s[0:1]
	s_mov_b32 m0, s58
	s_nop 0
	global_load_lds_dwordx4 v132, s[0:1]
	s_waitcnt lgkmcnt(8)
	s_barrier
	s_waitcnt lgkmcnt(0)
	s_setprio 1
	s_waitcnt lgkmcnt(0)
	v_mfma_f32_16x16x32_bf16 v[124:127], v[146:149], v[168:171], v[124:127]
	v_mfma_f32_16x16x32_bf16 v[120:123], v[160:163], v[168:171], v[120:123]
	v_mfma_f32_16x16x32_bf16 v[108:111], v[146:149], v[176:179], v[108:111]
	v_mfma_f32_16x16x32_bf16 v[104:107], v[160:163], v[176:179], v[104:107]
	v_mfma_f32_16x16x32_bf16 v[92:95], v[146:149], v[188:191], v[92:95]
	v_mfma_f32_16x16x32_bf16 v[88:91], v[160:163], v[188:191], v[88:91]
	v_mfma_f32_16x16x32_bf16 v[76:79], v[146:149], v[198:201], v[76:79]
	v_mfma_f32_16x16x32_bf16 v[72:75], v[160:163], v[198:201], v[72:75]
	v_mfma_f32_16x16x32_bf16 v[124:127], v[150:153], v[172:175], v[124:127]
	v_mfma_f32_16x16x32_bf16 v[120:123], v[164:167], v[172:175], v[120:123]
	v_mfma_f32_16x16x32_bf16 v[108:111], v[150:153], v[180:183], v[108:111]
	v_mfma_f32_16x16x32_bf16 v[104:107], v[164:167], v[180:183], v[104:107]
	v_mfma_f32_16x16x32_bf16 v[92:95], v[150:153], v[194:197], v[92:95]
	v_mfma_f32_16x16x32_bf16 v[88:91], v[164:167], v[194:197], v[88:91]
	v_mfma_f32_16x16x32_bf16 v[76:79], v[150:153], v[202:205], v[76:79]
	v_mfma_f32_16x16x32_bf16 v[72:75], v[164:167], v[202:205], v[72:75]
	s_setprio 0
	s_barrier
	s_add_i32 s5, 0, 0x1c000
	s_add_i32 s0, s4, s50
	v_add_u32_e32 v136, s5, v157
	s_add_i32 m0, s0, 0xffffff80
	ds_read_b128 v[206:209], v136
	ds_read_b128 v[210:213], v136 offset:1024
	ds_read_b128 v[214:217], v136 offset:2048
	ds_read_b128 v[218:221], v136 offset:3072
	global_load_lds_dwordx4 v130, s[44:45] offset:128
	s_add_i32 m0, s0, 0x1f80
	s_nop 0
	global_load_lds_dwordx4 v134, s[44:45] offset:128
	s_barrier
	s_waitcnt lgkmcnt(0)
	s_setprio 1
	s_waitcnt lgkmcnt(0)
	v_mfma_f32_16x16x32_bf16 v[116:119], v[206:209], v[168:171], v[116:119]
	v_mfma_f32_16x16x32_bf16 v[112:115], v[214:217], v[168:171], v[112:115]
	v_mfma_f32_16x16x32_bf16 v[100:103], v[206:209], v[176:179], v[100:103]
	v_mfma_f32_16x16x32_bf16 v[96:99], v[214:217], v[176:179], v[96:99]
	v_mfma_f32_16x16x32_bf16 v[84:87], v[206:209], v[188:191], v[84:87]
	v_mfma_f32_16x16x32_bf16 v[80:83], v[214:217], v[188:191], v[80:83]
	v_mfma_f32_16x16x32_bf16 v[68:71], v[206:209], v[198:201], v[68:71]
	v_mfma_f32_16x16x32_bf16 v[64:67], v[214:217], v[198:201], v[64:67]
	v_mfma_f32_16x16x32_bf16 v[116:119], v[210:213], v[172:175], v[116:119]
	v_mfma_f32_16x16x32_bf16 v[112:115], v[218:221], v[172:175], v[112:115]
	v_mfma_f32_16x16x32_bf16 v[100:103], v[210:213], v[180:183], v[100:103]
	v_mfma_f32_16x16x32_bf16 v[96:99], v[218:221], v[180:183], v[96:99]
	v_mfma_f32_16x16x32_bf16 v[84:87], v[210:213], v[194:197], v[84:87]
	v_mfma_f32_16x16x32_bf16 v[80:83], v[218:221], v[194:197], v[80:83]
	v_mfma_f32_16x16x32_bf16 v[68:71], v[210:213], v[202:205], v[68:71]
	v_mfma_f32_16x16x32_bf16 v[64:67], v[218:221], v[202:205], v[64:67]
	s_setprio 0
	s_add_i32 m0, s62, 0xffffff80
	s_barrier
	ds_read_b128 v[168:171], v158 offset:49152
	ds_read_b128 v[172:175], v158 offset:50176
	ds_read_b128 v[176:179], v158 offset:51200
	ds_read_b128 v[180:183], v158 offset:52224
	ds_read_b128 v[188:191], v158 offset:53248
	ds_read_b128 v[194:197], v158 offset:54272
	ds_read_b128 v[198:201], v158 offset:55296
	ds_read_b128 v[202:205], v158 offset:56320
	global_load_lds_dwordx4 v128, s[46:47] offset:128
	s_add_i32 m0, s63, 0xffffff80
	s_nop 0
	global_load_lds_dwordx4 v132, s[46:47] offset:128
	s_barrier
; #define PG8_STAGE(bufoff, gbase, voff) do { _Pragma("unroll") for (int _i = 0; _i < 2; ++_i) \
;         __builtin_amdgcn_global_load_lds((const unsigned*)((const char*)(gbase) + (voff)[_i]), (LAS unsigned*)(lds + (bufoff) + ldsw + _i * 8192), 16, 0, 0); } while (0)
; #define PG8_LDA(dst, b, h) do { _Pragma("unroll") for (int m = 0; m < 4; ++m) _Pragma("unroll") for (int k = 0; k < 2; ++k) dst[m][k] = *(const LAS bf16x8*)(lds + PG8_SA(b, h) + aoff + m * 2048 + k * 1024); } while (0)
; #define PG8_LDB(dst, b, h) do { _Pragma("unroll") for (int n = 0; n < 2; ++n) _Pragma("unroll") for (int k = 0; k < 2; ++k) dst[n][k] = *(const LAS bf16x8*)(lds + PG8_SB(b, h) + boff + n * 2048 + k * 1024); } while (0)
; #define PG8_MMA(ai, bj, At, Bt) do { __builtin_amdgcn_s_setprio(1); _Pragma("unroll") for (int m = 0; m < 4; ++m) _Pragma("unroll") for (int n = 0; n < 2; ++n) _Pragma("unroll") for (int k = 0; k < 2; ++k) \
;         acc[ai][bj][m][n] = __builtin_amdgcn_mfma_f32_16x16x32_bf16(Bt[n][k], At[m][k], acc[ai][bj][m][n], 0, 0, 0); __builtin_amdgcn_s_setprio(0); } while (0)
; #define PG8_WAIT_V(n) asm volatile("s_waitcnt vmcnt(" #n ")" ::: "memory")
; #define PG8_WAIT_L(n) asm volatile("s_waitcnt lgkmcnt(" #n ")" ::: "memory")
; #define PG8_BAR __builtin_amdgcn_s_barrier()
; template <class Epi, class Sched>
; DI void gemm_phase(LAS unsigned char* lds, const Gemm g, const Sched& S, const Epi& E) {
;     ...
;             PG8_LDB(B0, 0, 0); PG8_SCHED; PG8_LDA(At, 0, 0); PG8_STAGE(PG8_SA(1, 1), a1 + hstep, voffA);
;             PG8_WAIT_L(8); PG8_BAR; PG8_WAIT_L(0); PG8_MMA(0, 0, At, B0); PG8_BAR; PG8_SCHED;
;     ...
;             PG8_STAGE(PG8_SB(0, 1), b2 + hstep, voffB);
;             PG8_WAIT_V(6); PG8_BAR; PG8_MMA(1, 1, At, B1); PG8_BAR;
;             PG8_LDB(B0, 1, 0); PG8_SCHED; PG8_LDA(At, 1, 0); PG8_STAGE(PG8_SA(0, 1), a2 + hstep, voffA);
;             PG8_WAIT_L(8); PG8_BAR; PG8_WAIT_L(0); PG8_MMA(0, 0, At, B0); PG8_BAR; PG8_SCHED;
;             PG8_LDB(B1, 1, 1); PG8_STAGE(PG8_SB(1, 0), b3, voffB);
;             PG8_BAR; PG8_WAIT_L(0); PG8_MMA(0, 1, At, B1); PG8_BAR;
;             PG8_LDA(At, 1, 1); PG8_STAGE(PG8_SA(1, 0), a3, voffA);
;             PG8_BAR; PG8_WAIT_L(0); PG8_MMA(1, 0, At, B0); PG8_BAR; PG8_SCHED;
;             PG8_STAGE(PG8_SB(1, 1), b3 + hstep, voffB);
;             PG8_WAIT_V(6); PG8_BAR; PG8_MMA(1, 1, At, B1); PG8_BAR;
	s_waitcnt lgkmcnt(0)
	s_setprio 1
	s_waitcnt lgkmcnt(0)
	v_mfma_f32_16x16x32_bf16 v[60:63], v[146:149], v[168:171], v[60:63]
	v_mfma_f32_16x16x32_bf16 v[56:59], v[160:163], v[168:171], v[56:59]
	v_mfma_f32_16x16x32_bf16 v[44:47], v[146:149], v[176:179], v[44:47]
	v_mfma_f32_16x16x32_bf16 v[40:43], v[160:163], v[176:179], v[40:43]
	v_mfma_f32_16x16x32_bf16 v[28:31], v[146:149], v[188:191], v[28:31]
	v_mfma_f32_16x16x32_bf16 v[24:27], v[160:163], v[188:191], v[24:27]
	v_mfma_f32_16x16x32_bf16 v[12:15], v[146:149], v[198:201], v[12:15]
	v_mfma_f32_16x16x32_bf16 v[8:11], v[160:163], v[198:201], v[8:11]
	v_mfma_f32_16x16x32_bf16 v[60:63], v[150:153], v[172:175], v[60:63]
	v_mfma_f32_16x16x32_bf16 v[56:59], v[164:167], v[172:175], v[56:59]
	v_mfma_f32_16x16x32_bf16 v[44:47], v[150:153], v[180:183], v[44:47]
	v_mfma_f32_16x16x32_bf16 v[40:43], v[164:167], v[180:183], v[40:43]
	v_mfma_f32_16x16x32_bf16 v[28:31], v[150:153], v[194:197], v[28:31]
	v_mfma_f32_16x16x32_bf16 v[24:27], v[164:167], v[194:197], v[24:27]
	v_mfma_f32_16x16x32_bf16 v[12:15], v[150:153], v[202:205], v[12:15]
	v_mfma_f32_16x16x32_bf16 v[8:11], v[164:167], v[202:205], v[8:11]
	s_setprio 0
	s_barrier
	s_add_u32 s0, s44, 0x20080
	s_addc_u32 s1, s45, 0
	s_add_i32 s4, s5, s50
	s_mov_b32 m0, s4
	s_nop 0
	global_load_lds_dwordx4 v130, s[0:1]
	v_lshl_add_u64 v[146:147], s[0:1], 0, v[134:135]
	s_add_i32 m0, s4, 0x2000
	s_nop 0
	global_load_lds_dwordx4 v134, s[0:1]
	s_waitcnt vmcnt(6)
	s_barrier
	s_setprio 1
	v_mfma_f32_16x16x32_bf16 v[52:55], v[206:209], v[168:171], v[52:55]
	v_mfma_f32_16x16x32_bf16 v[48:51], v[214:217], v[168:171], v[48:51]
	v_mfma_f32_16x16x32_bf16 v[36:39], v[206:209], v[176:179], v[36:39]
	v_mfma_f32_16x16x32_bf16 v[32:35], v[214:217], v[176:179], v[32:35]
	v_mfma_f32_16x16x32_bf16 v[20:23], v[206:209], v[188:191], v[20:23]
	v_mfma_f32_16x16x32_bf16 v[16:19], v[214:217], v[188:191], v[16:19]
	v_mfma_f32_16x16x32_bf16 v[4:7], v[206:209], v[198:201], v[4:7]
	v_mfma_f32_16x16x32_bf16 v[0:3], v[214:217], v[198:201], v[0:3]
	v_mfma_f32_16x16x32_bf16 v[52:55], v[210:213], v[172:175], v[52:55]
	v_mfma_f32_16x16x32_bf16 v[48:51], v[218:221], v[172:175], v[48:51]
	v_mfma_f32_16x16x32_bf16 v[36:39], v[210:213], v[180:183], v[36:39]
	v_mfma_f32_16x16x32_bf16 v[32:35], v[218:221], v[180:183], v[32:35]
	v_mfma_f32_16x16x32_bf16 v[20:23], v[210:213], v[194:197], v[20:23]
	v_mfma_f32_16x16x32_bf16 v[16:19], v[218:221], v[194:197], v[16:19]
	v_mfma_f32_16x16x32_bf16 v[4:7], v[210:213], v[202:205], v[4:7]
	v_mfma_f32_16x16x32_bf16 v[0:3], v[218:221], v[202:205], v[0:3]
	s_setprio 0
	s_add_i32 s79, s79, 2
	s_add_u32 s42, s42, 0x100
	s_addc_u32 s43, s43, 0
	s_add_u32 s35, s35, 0x100
	s_addc_u32 s41, s41, 0
	s_cmp_gt_u32 s79, 5
	s_barrier
	s_cbranch_scc0 .LBB0_984
	s_branch .Lpeel_done_984
.LBB0_984:
	ds_read_b128 v[146:149], v156
	ds_read_b128 v[150:153], v156 offset:1024
	ds_read_b128 v[160:163], v156 offset:2048
	ds_read_b128 v[164:167], v156 offset:3072
	s_add_u32 s0, s42, 0xfffe0080
	s_addc_u32 s1, s43, -1
	s_cmp_eq_u32 s79, 4
	s_cselect_b32 s47, s9, s1
	s_cselect_b32 s46, s31, s0
	s_cselect_b32 s45, s29, s41
	s_cselect_b32 s44, s34, s35
	s_add_i32 m0, s55, 0xc000
	ds_read_b128 v[168:171], v158
	ds_read_b128 v[172:175], v158 offset:1024
	ds_read_b128 v[176:179], v158 offset:2048
	ds_read_b128 v[180:183], v158 offset:3072
	ds_read_b128 v[188:191], v158 offset:4096
	ds_read_b128 v[194:197], v158 offset:5120
	ds_read_b128 v[198:201], v158 offset:6144
	ds_read_b128 v[202:205], v158 offset:7168
	global_load_lds_dwordx4 v138, s[42:43]
	s_add_i32 m0, s55, 0xe000
	s_nop 0
	global_load_lds_dwordx4 v140, s[42:43]
	s_waitcnt lgkmcnt(8)
	s_barrier
	s_waitcnt lgkmcnt(0)
	s_setprio 1
	s_waitcnt lgkmcnt(0)
	v_mfma_f32_16x16x32_bf16 v[124:127], v[146:149], v[168:171], v[124:127]
	v_mfma_f32_16x16x32_bf16 v[120:123], v[160:163], v[168:171], v[120:123]
	v_mfma_f32_16x16x32_bf16 v[108:111], v[146:149], v[176:179], v[108:111]
	v_mfma_f32_16x16x32_bf16 v[104:107], v[160:163], v[176:179], v[104:107]
	v_mfma_f32_16x16x32_bf16 v[92:95], v[146:149], v[188:191], v[92:95]
	v_mfma_f32_16x16x32_bf16 v[88:91], v[160:163], v[188:191], v[88:91]
	v_mfma_f32_16x16x32_bf16 v[76:79], v[146:149], v[198:201], v[76:79]
	v_mfma_f32_16x16x32_bf16 v[72:75], v[160:163], v[198:201], v[72:75]
	v_mfma_f32_16x16x32_bf16 v[124:127], v[150:153], v[172:175], v[124:127]
	v_mfma_f32_16x16x32_bf16 v[120:123], v[164:167], v[172:175], v[120:123]
	v_mfma_f32_16x16x32_bf16 v[108:111], v[150:153], v[180:183], v[108:111]
	v_mfma_f32_16x16x32_bf16 v[104:107], v[164:167], v[180:183], v[104:107]
	v_mfma_f32_16x16x32_bf16 v[92:95], v[150:153], v[194:197], v[92:95]
	v_mfma_f32_16x16x32_bf16 v[88:91], v[164:167], v[194:197], v[88:91]
	v_mfma_f32_16x16x32_bf16 v[76:79], v[150:153], v[202:205], v[76:79]
	v_mfma_f32_16x16x32_bf16 v[72:75], v[164:167], v[202:205], v[72:75]
	s_setprio 0
	s_barrier
	s_add_i32 s0, s66, s50
	s_mov_b32 m0, s0
	ds_read_b128 v[206:209], v159
	ds_read_b128 v[210:213], v159 offset:1024
	ds_read_b128 v[214:217], v159 offset:2048
	ds_read_b128 v[218:221], v159 offset:3072
	global_load_lds_dwordx4 v130, s[44:45]
	s_add_i32 m0, s0, 0x2000
	s_nop 0
	global_load_lds_dwordx4 v134, s[44:45]
	s_barrier
; #define PG8_STAGE(bufoff, gbase, voff) do { _Pragma("unroll") for (int _i = 0; _i < 2; ++_i) \
;         __builtin_amdgcn_global_load_lds((const unsigned*)((const char*)(gbase) + (voff)[_i]), (LAS unsigned*)(lds + (bufoff) + ldsw + _i * 8192), 16, 0, 0); } while (0)
; #define PG8_LDA(dst, b, h) do { _Pragma("unroll") for (int m = 0; m < 4; ++m) _Pragma("unroll") for (int k = 0; k < 2; ++k) dst[m][k] = *(const LAS bf16x8*)(lds + PG8_SA(b, h) + aoff + m * 2048 + k * 1024); } while (0)
; #define PG8_LDB(dst, b, h) do { _Pragma("unroll") for (int n = 0; n < 2; ++n) _Pragma("unroll") for (int k = 0; k < 2; ++k) dst[n][k] = *(const LAS bf16x8*)(lds + PG8_SB(b, h) + boff + n * 2048 + k * 1024); } while (0)
; #define PG8_MMA(ai, bj, At, Bt) do { __builtin_amdgcn_s_setprio(1); _Pragma("unroll") for (int m = 0; m < 4; ++m) _Pragma("unroll") for (int n = 0; n < 2; ++n) _Pragma("unroll") for (int k = 0; k < 2; ++k) \
;         acc[ai][bj][m][n] = __builtin_amdgcn_mfma_f32_16x16x32_bf16(Bt[n][k], At[m][k], acc[ai][bj][m][n], 0, 0, 0); __builtin_amdgcn_s_setprio(0); } while (0)
; #define PG8_WAIT_V(n) asm volatile("s_waitcnt vmcnt(" #n ")" ::: "memory")
; #define PG8_WAIT_L(n) asm volatile("s_waitcnt lgkmcnt(" #n ")" ::: "memory")
; #define PG8_BAR __builtin_amdgcn_s_barrier()
; #define PG8_SCHED __builtin_amdgcn_sched_barrier(0)
; template <class Epi, class Sched>
; DI void gemm_phase(LAS unsigned char* lds, const Gemm g, const Sched& S, const Epi& E) {
;     ...
;             PG8_LDB(B1, 0, 1); PG8_STAGE(PG8_SB(0, 0), b2, voffB);
;             PG8_BAR; PG8_WAIT_L(0); PG8_MMA(0, 1, At, B1); PG8_BAR;
;             PG8_LDA(At, 0, 1); PG8_STAGE(PG8_SA(0, 0), a2, voffA);
;             PG8_BAR; PG8_WAIT_L(0); PG8_MMA(1, 0, At, B0); PG8_BAR; PG8_SCHED;
;             PG8_STAGE(PG8_SB(0, 1), b2 + hstep, voffB);
;             PG8_WAIT_V(6); PG8_BAR; PG8_MMA(1, 1, At, B1); PG8_BAR;
;             PG8_LDB(B0, 1, 0); PG8_SCHED; PG8_LDA(At, 1, 0); PG8_STAGE(PG8_SA(0, 1), a2 + hstep, voffA);
;             PG8_WAIT_L(8); PG8_BAR; PG8_WAIT_L(0); PG8_MMA(0, 0, At, B0); PG8_BAR; PG8_SCHED;
	s_waitcnt lgkmcnt(0)
	s_setprio 1
	s_waitcnt lgkmcnt(0)
	v_mfma_f32_16x16x32_bf16 v[116:119], v[206:209], v[168:171], v[116:119]
	v_mfma_f32_16x16x32_bf16 v[112:115], v[214:217], v[168:171], v[112:115]
	v_mfma_f32_16x16x32_bf16 v[100:103], v[206:209], v[176:179], v[100:103]
	v_mfma_f32_16x16x32_bf16 v[96:99], v[214:217], v[176:179], v[96:99]
	v_mfma_f32_16x16x32_bf16 v[84:87], v[206:209], v[188:191], v[84:87]
	v_mfma_f32_16x16x32_bf16 v[80:83], v[214:217], v[188:191], v[80:83]
	v_mfma_f32_16x16x32_bf16 v[68:71], v[206:209], v[198:201], v[68:71]
	v_mfma_f32_16x16x32_bf16 v[64:67], v[214:217], v[198:201], v[64:67]
	v_mfma_f32_16x16x32_bf16 v[116:119], v[210:213], v[172:175], v[116:119]
	v_mfma_f32_16x16x32_bf16 v[112:115], v[218:221], v[172:175], v[112:115]
	v_mfma_f32_16x16x32_bf16 v[100:103], v[210:213], v[180:183], v[100:103]
	v_mfma_f32_16x16x32_bf16 v[96:99], v[218:221], v[180:183], v[96:99]
	v_mfma_f32_16x16x32_bf16 v[84:87], v[210:213], v[194:197], v[84:87]
	v_mfma_f32_16x16x32_bf16 v[80:83], v[218:221], v[194:197], v[80:83]
	v_mfma_f32_16x16x32_bf16 v[68:71], v[210:213], v[202:205], v[68:71]
	v_mfma_f32_16x16x32_bf16 v[64:67], v[218:221], v[202:205], v[64:67]
	s_setprio 0
	s_mov_b32 m0, s55
	s_barrier
	ds_read_b128 v[168:171], v158 offset:16384
	ds_read_b128 v[172:175], v158 offset:17408
	ds_read_b128 v[176:179], v158 offset:18432
	ds_read_b128 v[180:183], v158 offset:19456
	ds_read_b128 v[188:191], v158 offset:20480
	ds_read_b128 v[194:197], v158 offset:21504
	ds_read_b128 v[198:201], v158 offset:22528
	ds_read_b128 v[202:205], v158 offset:23552
	global_load_lds_dwordx4 v128, s[46:47]
	s_mov_b32 m0, s56
	s_nop 0
	global_load_lds_dwordx4 v132, s[46:47]
	s_barrier
	s_waitcnt lgkmcnt(0)
	s_setprio 1
	s_waitcnt lgkmcnt(0)
	v_mfma_f32_16x16x32_bf16 v[60:63], v[146:149], v[168:171], v[60:63]
	v_mfma_f32_16x16x32_bf16 v[56:59], v[160:163], v[168:171], v[56:59]
	v_mfma_f32_16x16x32_bf16 v[44:47], v[146:149], v[176:179], v[44:47]
	v_mfma_f32_16x16x32_bf16 v[40:43], v[160:163], v[176:179], v[40:43]
	v_mfma_f32_16x16x32_bf16 v[28:31], v[146:149], v[188:191], v[28:31]
	v_mfma_f32_16x16x32_bf16 v[24:27], v[160:163], v[188:191], v[24:27]
	v_mfma_f32_16x16x32_bf16 v[12:15], v[146:149], v[198:201], v[12:15]
	v_mfma_f32_16x16x32_bf16 v[8:11], v[160:163], v[198:201], v[8:11]
	v_mfma_f32_16x16x32_bf16 v[60:63], v[150:153], v[172:175], v[60:63]
	v_mfma_f32_16x16x32_bf16 v[56:59], v[164:167], v[172:175], v[56:59]
	v_mfma_f32_16x16x32_bf16 v[44:47], v[150:153], v[180:183], v[44:47]
	v_mfma_f32_16x16x32_bf16 v[40:43], v[164:167], v[180:183], v[40:43]
	v_mfma_f32_16x16x32_bf16 v[28:31], v[150:153], v[194:197], v[28:31]
	v_mfma_f32_16x16x32_bf16 v[24:27], v[164:167], v[194:197], v[24:27]
	v_mfma_f32_16x16x32_bf16 v[12:15], v[150:153], v[202:205], v[12:15]
	v_mfma_f32_16x16x32_bf16 v[8:11], v[164:167], v[202:205], v[8:11]
	s_setprio 0
	s_barrier
	s_add_u32 s0, s44, 0x20000
	s_addc_u32 s1, s45, 0
	s_add_i32 s4, s67, s50
	s_mov_b32 m0, s4
	s_nop 0
	global_load_lds_dwordx4 v130, s[0:1]
	s_add_i32 m0, s4, 0x2000
	s_nop 0
	global_load_lds_dwordx4 v134, s[0:1]
	s_waitcnt vmcnt(6)
	s_barrier
	s_setprio 1
	v_mfma_f32_16x16x32_bf16 v[52:55], v[206:209], v[168:171], v[52:55]
	v_mfma_f32_16x16x32_bf16 v[48:51], v[214:217], v[168:171], v[48:51]
	v_mfma_f32_16x16x32_bf16 v[36:39], v[206:209], v[176:179], v[36:39]
	v_mfma_f32_16x16x32_bf16 v[32:35], v[214:217], v[176:179], v[32:35]
	v_mfma_f32_16x16x32_bf16 v[20:23], v[206:209], v[188:191], v[20:23]
	v_mfma_f32_16x16x32_bf16 v[16:19], v[214:217], v[188:191], v[16:19]
	v_mfma_f32_16x16x32_bf16 v[4:7], v[206:209], v[198:201], v[4:7]
	v_mfma_f32_16x16x32_bf16 v[0:3], v[214:217], v[198:201], v[0:3]
	v_mfma_f32_16x16x32_bf16 v[52:55], v[210:213], v[172:175], v[52:55]
	v_mfma_f32_16x16x32_bf16 v[48:51], v[218:221], v[172:175], v[48:51]
	v_mfma_f32_16x16x32_bf16 v[36:39], v[210:213], v[180:183], v[36:39]
	v_mfma_f32_16x16x32_bf16 v[32:35], v[218:221], v[180:183], v[32:35]
	v_mfma_f32_16x16x32_bf16 v[20:23], v[210:213], v[194:197], v[20:23]
	v_mfma_f32_16x16x32_bf16 v[16:19], v[218:221], v[194:197], v[16:19]
	v_mfma_f32_16x16x32_bf16 v[4:7], v[210:213], v[202:205], v[4:7]
	v_mfma_f32_16x16x32_bf16 v[0:3], v[218:221], v[202:205], v[0:3]
	s_setprio 0
	s_add_i32 s4, 0, 0x18000
	v_add_u32_e32 v136, s4, v157
	s_barrier
	ds_read_b128 v[146:149], v136
	ds_read_b128 v[150:153], v136 offset:1024
	ds_read_b128 v[160:163], v136 offset:2048
	ds_read_b128 v[164:167], v136 offset:3072
	s_add_u32 s0, s46, 0x20000
	s_addc_u32 s1, s47, 0
	s_mov_b32 m0, s57
	ds_read_b128 v[168:171], v158 offset:32768
	ds_read_b128 v[172:175], v158 offset:33792
	ds_read_b128 v[176:179], v158 offset:34816
	ds_read_b128 v[180:183], v158 offset:35840
	ds_read_b128 v[188:191], v158 offset:36864
	ds_read_b128 v[194:197], v158 offset:37888
	ds_read_b128 v[198:201], v158 offset:38912
	ds_read_b128 v[202:205], v158 offset:39936
	global_load_lds_dwordx4 v128, s[0:1]
	s_mov_b32 m0, s58
	s_nop 0
	global_load_lds_dwordx4 v132, s[0:1]
	s_waitcnt lgkmcnt(8)
	s_barrier
; #define PG8_STAGE(bufoff, gbase, voff) do { _Pragma("unroll") for (int _i = 0; _i < 2; ++_i) \
;         __builtin_amdgcn_global_load_lds((const unsigned*)((const char*)(gbase) + (voff)[_i]), (LAS unsigned*)(lds + (bufoff) + ldsw + _i * 8192), 16, 0, 0); } while (0)
; #define PG8_LDA(dst, b, h) do { _Pragma("unroll") for (int m = 0; m < 4; ++m) _Pragma("unroll") for (int k = 0; k < 2; ++k) dst[m][k] = *(const LAS bf16x8*)(lds + PG8_SA(b, h) + aoff + m * 2048 + k * 1024); } while (0)
; #define PG8_LDB(dst, b, h) do { _Pragma("unroll") for (int n = 0; n < 2; ++n) _Pragma("unroll") for (int k = 0; k < 2; ++k) dst[n][k] = *(const LAS bf16x8*)(lds + PG8_SB(b, h) + boff + n * 2048 + k * 1024); } while (0)
; #define PG8_MMA(ai, bj, At, Bt) do { __builtin_amdgcn_s_setprio(1); _Pragma("unroll") for (int m = 0; m < 4; ++m) _Pragma("unroll") for (int n = 0; n < 2; ++n) _Pragma("unroll") for (int k = 0; k < 2; ++k) \
;         acc[ai][bj][m][n] = __builtin_amdgcn_mfma_f32_16x16x32_bf16(Bt[n][k], At[m][k], acc[ai][bj][m][n], 0, 0, 0); __builtin_amdgcn_s_setprio(0); } while (0)
; #define PG8_WAIT_V(n) asm volatile("s_waitcnt vmcnt(" #n ")" ::: "memory")
; #define PG8_WAIT_L(n) asm volatile("s_waitcnt lgkmcnt(" #n ")" ::: "memory")
; #define PG8_BAR __builtin_amdgcn_s_barrier()
; #define PG8_SCHED __builtin_amdgcn_sched_barrier(0)
; template <class Epi, class Sched>
; DI void gemm_phase(LAS unsigned char* lds, const Gemm g, const Sched& S, const Epi& E) {
;     ...
;             PG8_LDB(B1, 1, 1); PG8_STAGE(PG8_SB(1, 0), b3, voffB);
;             PG8_BAR; PG8_WAIT_L(0); PG8_MMA(0, 1, At, B1); PG8_BAR;
;             PG8_LDA(At, 1, 1); PG8_STAGE(PG8_SA(1, 0), a3, voffA);
;             PG8_BAR; PG8_WAIT_L(0); PG8_MMA(1, 0, At, B0); PG8_BAR; PG8_SCHED;
;             PG8_STAGE(PG8_SB(1, 1), b3 + hstep, voffB);
;             PG8_WAIT_V(6); PG8_BAR; PG8_MMA(1, 1, At, B1); PG8_BAR;
	s_waitcnt lgkmcnt(0)
	s_setprio 1
	s_waitcnt lgkmcnt(0)
	v_mfma_f32_16x16x32_bf16 v[124:127], v[146:149], v[168:171], v[124:127]
	v_mfma_f32_16x16x32_bf16 v[120:123], v[160:163], v[168:171], v[120:123]
	v_mfma_f32_16x16x32_bf16 v[108:111], v[146:149], v[176:179], v[108:111]
	v_mfma_f32_16x16x32_bf16 v[104:107], v[160:163], v[176:179], v[104:107]
	v_mfma_f32_16x16x32_bf16 v[92:95], v[146:149], v[188:191], v[92:95]
	v_mfma_f32_16x16x32_bf16 v[88:91], v[160:163], v[188:191], v[88:91]
	v_mfma_f32_16x16x32_bf16 v[76:79], v[146:149], v[198:201], v[76:79]
	v_mfma_f32_16x16x32_bf16 v[72:75], v[160:163], v[198:201], v[72:75]
	v_mfma_f32_16x16x32_bf16 v[124:127], v[150:153], v[172:175], v[124:127]
	v_mfma_f32_16x16x32_bf16 v[120:123], v[164:167], v[172:175], v[120:123]
	v_mfma_f32_16x16x32_bf16 v[108:111], v[150:153], v[180:183], v[108:111]
	v_mfma_f32_16x16x32_bf16 v[104:107], v[164:167], v[180:183], v[104:107]
	v_mfma_f32_16x16x32_bf16 v[92:95], v[150:153], v[194:197], v[92:95]
	v_mfma_f32_16x16x32_bf16 v[88:91], v[164:167], v[194:197], v[88:91]
	v_mfma_f32_16x16x32_bf16 v[76:79], v[150:153], v[202:205], v[76:79]
	v_mfma_f32_16x16x32_bf16 v[72:75], v[164:167], v[202:205], v[72:75]
	s_setprio 0
	s_barrier
	s_add_i32 s5, 0, 0x1c000
	s_add_i32 s0, s4, s50
	v_add_u32_e32 v136, s5, v157
	s_add_i32 m0, s0, 0xffffff80
	ds_read_b128 v[206:209], v136
	ds_read_b128 v[210:213], v136 offset:1024
	ds_read_b128 v[214:217], v136 offset:2048
	ds_read_b128 v[218:221], v136 offset:3072
	global_load_lds_dwordx4 v130, s[44:45] offset:128
	s_add_i32 m0, s0, 0x1f80
	s_nop 0
	global_load_lds_dwordx4 v134, s[44:45] offset:128
	s_barrier
	s_waitcnt lgkmcnt(0)
	s_setprio 1
	s_waitcnt lgkmcnt(0)
	v_mfma_f32_16x16x32_bf16 v[116:119], v[206:209], v[168:171], v[116:119]
	v_mfma_f32_16x16x32_bf16 v[112:115], v[214:217], v[168:171], v[112:115]
	v_mfma_f32_16x16x32_bf16 v[100:103], v[206:209], v[176:179], v[100:103]
	v_mfma_f32_16x16x32_bf16 v[96:99], v[214:217], v[176:179], v[96:99]
	v_mfma_f32_16x16x32_bf16 v[84:87], v[206:209], v[188:191], v[84:87]
	v_mfma_f32_16x16x32_bf16 v[80:83], v[214:217], v[188:191], v[80:83]
	v_mfma_f32_16x16x32_bf16 v[68:71], v[206:209], v[198:201], v[68:71]
	v_mfma_f32_16x16x32_bf16 v[64:67], v[214:217], v[198:201], v[64:67]
	v_mfma_f32_16x16x32_bf16 v[116:119], v[210:213], v[172:175], v[116:119]
	v_mfma_f32_16x16x32_bf16 v[112:115], v[218:221], v[172:175], v[112:115]
	v_mfma_f32_16x16x32_bf16 v[100:103], v[210:213], v[180:183], v[100:103]
	v_mfma_f32_16x16x32_bf16 v[96:99], v[218:221], v[180:183], v[96:99]
	v_mfma_f32_16x16x32_bf16 v[84:87], v[210:213], v[194:197], v[84:87]
	v_mfma_f32_16x16x32_bf16 v[80:83], v[218:221], v[194:197], v[80:83]
	v_mfma_f32_16x16x32_bf16 v[68:71], v[210:213], v[202:205], v[68:71]
	v_mfma_f32_16x16x32_bf16 v[64:67], v[218:221], v[202:205], v[64:67]
	s_setprio 0
	s_add_i32 m0, s62, 0xffffff80
	s_barrier
	ds_read_b128 v[168:171], v158 offset:49152
	ds_read_b128 v[172:175], v158 offset:50176
	ds_read_b128 v[176:179], v158 offset:51200
	ds_read_b128 v[180:183], v158 offset:52224
	ds_read_b128 v[188:191], v158 offset:53248
	ds_read_b128 v[194:197], v158 offset:54272
	ds_read_b128 v[198:201], v158 offset:55296
	ds_read_b128 v[202:205], v158 offset:56320
	global_load_lds_dwordx4 v128, s[46:47] offset:128
	s_add_i32 m0, s63, 0xffffff80
	s_nop 0
	global_load_lds_dwordx4 v132, s[46:47] offset:128
	s_barrier
	s_waitcnt lgkmcnt(0)
	s_setprio 1
	s_waitcnt lgkmcnt(0)
	v_mfma_f32_16x16x32_bf16 v[60:63], v[146:149], v[168:171], v[60:63]
	v_mfma_f32_16x16x32_bf16 v[56:59], v[160:163], v[168:171], v[56:59]
	v_mfma_f32_16x16x32_bf16 v[44:47], v[146:149], v[176:179], v[44:47]
	v_mfma_f32_16x16x32_bf16 v[40:43], v[160:163], v[176:179], v[40:43]
	v_mfma_f32_16x16x32_bf16 v[28:31], v[146:149], v[188:191], v[28:31]
	v_mfma_f32_16x16x32_bf16 v[24:27], v[160:163], v[188:191], v[24:27]
	v_mfma_f32_16x16x32_bf16 v[12:15], v[146:149], v[198:201], v[12:15]
	v_mfma_f32_16x16x32_bf16 v[8:11], v[160:163], v[198:201], v[8:11]
	v_mfma_f32_16x16x32_bf16 v[60:63], v[150:153], v[172:175], v[60:63]
	v_mfma_f32_16x16x32_bf16 v[56:59], v[164:167], v[172:175], v[56:59]
	v_mfma_f32_16x16x32_bf16 v[44:47], v[150:153], v[180:183], v[44:47]
	v_mfma_f32_16x16x32_bf16 v[40:43], v[164:167], v[180:183], v[40:43]
	v_mfma_f32_16x16x32_bf16 v[28:31], v[150:153], v[194:197], v[28:31]
	v_mfma_f32_16x16x32_bf16 v[24:27], v[164:167], v[194:197], v[24:27]
	v_mfma_f32_16x16x32_bf16 v[12:15], v[150:153], v[202:205], v[12:15]
	v_mfma_f32_16x16x32_bf16 v[8:11], v[164:167], v[202:205], v[8:11]
	s_setprio 0
	s_barrier
	s_add_u32 s0, s44, 0x20080
	s_addc_u32 s1, s45, 0
	s_add_i32 s4, s5, s50
	s_mov_b32 m0, s4
	s_nop 0
	global_load_lds_dwordx4 v130, s[0:1]
	v_lshl_add_u64 v[146:147], s[0:1], 0, v[134:135]
	s_add_i32 m0, s4, 0x2000
	s_nop 0
	global_load_lds_dwordx4 v134, s[0:1]
	s_waitcnt vmcnt(6)
	s_barrier
	s_setprio 1
	v_mfma_f32_16x16x32_bf16 v[52:55], v[206:209], v[168:171], v[52:55]
	v_mfma_f32_16x16x32_bf16 v[48:51], v[214:217], v[168:171], v[48:51]
	v_mfma_f32_16x16x32_bf16 v[36:39], v[206:209], v[176:179], v[36:39]
	v_mfma_f32_16x16x32_bf16 v[32:35], v[214:217], v[176:179], v[32:35]
	v_mfma_f32_16x16x32_bf16 v[20:23], v[206:209], v[188:191], v[20:23]
	v_mfma_f32_16x16x32_bf16 v[16:19], v[214:217], v[188:191], v[16:19]
	v_mfma_f32_16x16x32_bf16 v[4:7], v[206:209], v[198:201], v[4:7]
	v_mfma_f32_16x16x32_bf16 v[0:3], v[214:217], v[198:201], v[0:3]
	v_mfma_f32_16x16x32_bf16 v[52:55], v[210:213], v[172:175], v[52:55]
	v_mfma_f32_16x16x32_bf16 v[48:51], v[218:221], v[172:175], v[48:51]
	v_mfma_f32_16x16x32_bf16 v[36:39], v[210:213], v[180:183], v[36:39]
	v_mfma_f32_16x16x32_bf16 v[32:35], v[218:221], v[180:183], v[32:35]
	v_mfma_f32_16x16x32_bf16 v[20:23], v[210:213], v[194:197], v[20:23]
	v_mfma_f32_16x16x32_bf16 v[16:19], v[218:221], v[194:197], v[16:19]
	v_mfma_f32_16x16x32_bf16 v[4:7], v[210:213], v[202:205], v[4:7]
	v_mfma_f32_16x16x32_bf16 v[0:3], v[218:221], v[202:205], v[0:3]
	s_setprio 0
	s_add_i32 s79, s79, 2
	s_add_u32 s42, s42, 0x100
	s_addc_u32 s43, s43, 0
	s_add_u32 s35, s35, 0x100
	s_addc_u32 s41, s41, 0
	s_cmp_gt_u32 s79, 5
	s_barrier
	s_cbranch_scc0 .LBB0_984

;     DI size_t aoff(const Unit& u, size_t tstep) const { return (size_t)u.pm * tstep; }
;     DI size_t boff(const Unit& u, size_t tstep) const { return (size_t)u.pn * tstep; }
;     DI bool next(int i, Unit& u) const { const long L = (long)i * G + c; if (L >= np) return false; u.pm = pmv; u.pn = (int)(L % nN); u.ks = (int)(L / nN); return true; }
;     DI size_t aoff(const Unit& u, size_t) const { return (size_t)u.ks * kbytes; }
;     DI size_t boff(const Unit& u, size_t tstep) const { return (size_t)u.pn * tstep + (size_t)u.ks * kbytes; }
; template <class Epi, class Sched>
; DI void gemm_phase(LAS unsigned char* lds, const Gemm g, const Sched& S, const Epi& E) {
;     const int tid = threadIdx.x, wid = __builtin_amdgcn_readfirstlane(tid >> 6), lane = tid & 63, wr = wid >> 2, wc = wid & 3, fr = lane & 15, fq = lane >> 4;
;     const int K = g.ldk, nt = g.nt;
;     unsigned voffA[2], voffB[2];
; #pragma unroll
;     for (int i = 0; i < 2; ++i) { int Rr, C; stage_rc(tid * 16 + i * 8192, Rr, C); const int Rb = Epi::PERM ? ((Rr & ~31) + perm32(Rr & 31)) : Rr;
;         voffA[i] = (unsigned)(Rr * K + C) * 2u; voffB[i] = (unsigned)(Rb * K + C) * 2u; }
;     const size_t kstep = (size_t)(BK * 2);
;     const size_t hstep = (size_t)HALF * K * 2;
;     const size_t tstep = 2 * hstep;
;     const unsigned ldsw = (unsigned)wid * 1024u;
;     const int aoff = lds_byte(wr * 64 + fr, fq * 8), boff = lds_byte(wc * 32 + fr, fq * 8);
;     ...
;     Unit cur, nxt; int ui = 0;
;     if (!S.next(0, cur)) return;
;     f32x4 acc[2][2][4][2];
; #pragma unroll
;     for (int a = 0; a < 2; ++a)
; #pragma unroll
;         for (int b = 0; b < 2; ++b)
; #pragma unroll
;             for (int m = 0; m < 4; ++m)
; #pragma unroll
;                 for (int n = 0; n < 2; ++n) acc[a][b][m][n] = (f32x4){0.f, 0.f, 0.f, 0.f};
;     bf16x8 At[4][2], B0[2][2], B1[2][2];
;     const char* cA = (const char*)g.A + S.aoff(cur, tstep); const char* cB = (const char*)g.Bt + S.boff(cur, tstep);
;     PG8_STAGE(PG8_SB(0, 0), cB, voffB); PG8_STAGE(PG8_SA(0, 0), cA, voffA); PG8_STAGE(PG8_SB(0, 1), cB + hstep, voffB); PG8_STAGE(PG8_SA(0, 1), cA + hstep, voffA);
;     if (wr == 1) PG8_BAR;
;     PG8_WAIT_V(4); PG8_BAR;
;     PG8_STAGE(PG8_SB(1, 0), cB + kstep, voffB); PG8_STAGE(PG8_SA(1, 0), cA + kstep, voffA); PG8_STAGE(PG8_SB(1, 1), cB + hstep + kstep, voffB);
;     PG8_WAIT_V(6); PG8_BAR;
.LBB0_1332:
	s_cmp_lt_i32 s24, 9
	s_cselect_b64 s[10:11], -1, 0
	s_and_b64 s[0:1], s[10:11], s[6:7]
	v_bfe_u32 v192, v184, 4, 2
	s_andn2_b64 vcc, exec, s[0:1]
	v_bfe_u32 v197, v184, 2, 4
	v_lshlrev_b32_e32 v198, 4, v184
	v_and_b32_e32 v200, 32, v184
	v_and_b32_e32 v196, 64, v184
	v_and_b32_e32 v194, 15, v184
	v_lshlrev_b32_e32 v195, 4, v192
	v_lshlrev_b32_e32 v199, 6, v184
	s_cbranch_vccnz .LBB0_1439
	v_bitop3_b32 v4, v198, v200, 48 bitop3:0x6c
	s_movk_i32 s0, 0x70
	s_add_u32 s12, s22, 0x107c3000
	v_or_b32_e32 v0, v4, v196
	s_waitcnt lgkmcnt(0)
	v_and_or_b32 v1, v187, s0, v197
	v_add_u32_e32 v5, 0x2000, v198
	s_addc_u32 s13, s23, 0
	s_waitcnt vmcnt(0)
	v_lshl_or_b32 v168, v1, 12, v0
	v_lshrrev_b32_e32 v1, 7, v5
	s_movk_i32 s0, 0xf0
	s_add_u32 s14, s22, 0x122400
	v_and_or_b32 v2, v1, s0, v197
	s_addc_u32 s15, s23, 0
	v_lshl_or_b32 v170, v2, 12, v0
	v_and_b32_e32 v2, 0x3c0, v199
	v_and_b32_e32 v3, 32, v185
	s_ashr_i32 s3, s26, 31
	v_mov_b32_e32 v169, 0
	v_bitop3_b32 v201, v195, v3, v2 bitop3:0x36
	s_cmpk_gt_i32 s2, 0x3ff
	v_mov_b32_e32 v171, v169
	v_readfirstlane_b32 s50, v184
	s_cbranch_scc1 .LBB0_1358
	v_lshrrev_b32_e32 v2, 2, v184
	v_lshlrev_b32_e32 v3, 1, v2
	v_lshrrev_b32_e32 v6, 5, v184
	v_and_b32_e32 v3, 24, v3
	v_and_b32_e32 v6, 4, v6
	v_and_b32_e32 v2, 3, v2
	v_or3_b32 v2, v6, v2, v3
	s_movk_i32 s0, 0x60
	v_and_or_b32 v3, v187, s0, v2
	s_movk_i32 s0, 0xe0
	s_ashr_i32 s52, s2, 31
	v_and_or_b32 v1, v1, s0, v2
	s_lshr_b32 s0, s52, 29
	s_add_i32 s0, s2, s0
	s_ashr_i32 s5, s0, 3
	s_and_b32 s0, s0, -8
	s_lshr_b32 s1, s50, 6
	s_sub_i32 s0, s2, s0
	s_lshr_b32 s4, s50, 8
	s_lshl_b32 s51, s1, 10
	s_lshl_b32 s7, s0, 7
	s_mul_i32 s6, s0, 0x81
	s_cmp_lt_i32 s0, 0
	s_cselect_b32 s0, s6, s7
	s_add_i32 s0, s0, s5
	s_ashr_i32 s5, s0, 31
	s_lshr_b32 s5, s5, 27
	s_add_i32 s5, s0, s5
	s_ashr_i32 s6, s5, 5
	s_and_b32 s5, s5, 0xffe0
	s_sub_i32 s5, s0, s5
	s_bfe_i32 s0, s5, 0x80000
	s_bfe_u32 s0, s0, 0x2000d
	s_add_i32 s7, s5, s0
	s_bfe_i32 s0, s7, 0x80000
	s_and_b32 s7, s7, 0xfc
	s_sext_i32_i16 s0, s0
	s_sub_i32 s5, s5, s7
	s_lshl_b32 s6, s6, 2
	s_ashr_i32 s0, s0, 2
	s_sext_i32_i8 s5, s5
	s_add_i32 s44, s6, s5
	s_lshl_b32 s6, s0, 1
	s_ashr_i32 s7, s6, 31
	s_ashr_i32 s45, s44, 31
	s_lshl_b64 s[6:7], s[6:7], 20
	s_add_u32 s5, s22, s6
	s_addc_u32 s6, s23, s7
	s_add_u32 s46, s5, 0x5983000
	s_addc_u32 s47, s6, 0
	s_add_i32 s53, s51, 0
	v_lshl_or_b32 v172, v3, 12, v0
	s_add_i32 m0, s53, 0x10000
	s_lshl_b64 s[8:9], s[44:45], 20
	global_load_lds_dwordx4 v172, s[46:47]
	s_add_i32 m0, s53, 0x12000
	s_add_u32 s7, s22, s8
	s_addc_u32 s16, s23, s9
	s_add_u32 s40, s7, 0x86c3000
	v_lshl_or_b32 v174, v1, 12, v0
	s_addc_u32 s41, s16, 0
	global_load_lds_dwordx4 v174, s[46:47]
	v_lshl_add_u64 v[2:3], s[40:41], 0, v[168:169]
	s_mov_b32 m0, s53
	s_add_i32 s54, s53, 0x2000
	global_load_lds_dwordx4 v168, s[40:41]
	v_lshl_add_u64 v[0:1], s[40:41], 0, v[170:171]
	s_mov_b32 m0, s54
	s_add_u32 s8, s5, 0x5a03000
	global_load_lds_dwordx4 v170, s[40:41]
	s_addc_u32 s9, s6, 0
	s_add_i32 m0, s53, 0x14000
	v_mov_b32_e32 v173, v169
	global_load_lds_dwordx4 v172, s[8:9]
	s_add_i32 m0, s53, 0x16000
	v_mov_b32_e32 v175, v169
	global_load_lds_dwordx4 v174, s[8:9]
	s_add_u32 s8, s7, 0x8743000
	s_addc_u32 s9, s16, 0
	s_add_i32 s55, s53, 0x4000
	s_mov_b32 m0, s55
	s_add_i32 s56, s53, 0x6000
	global_load_lds_dwordx4 v168, s[8:9]
	s_mov_b32 m0, s56
	s_cmp_lg_u32 s4, 1
	global_load_lds_dwordx4 v170, s[8:9]
	s_mov_b32 s34, 0
	s_cbranch_scc1 .LBB0_1336
	s_barrier
.LBB0_1336:
	s_add_u32 s16, s22, 0x188c3000
	s_addc_u32 s17, s23, 0
	s_add_u32 s18, s22, 0x2c30b000
	s_addc_u32 s19, s23, 0
	s_lshl_b32 s1, s1, 5
	s_lshl_b32 s57, s4, 6
	s_lshl_b32 s7, s4, 13
	s_and_b32 s58, s1, 0x60
	s_add_u32 s8, s5, 0x5983080
	s_addc_u32 s9, s6, 0
	s_add_i32 m0, s53, 0x18000
	s_waitcnt vmcnt(4)
	s_barrier
	global_load_lds_dwordx4 v172, s[8:9]
	s_add_i32 m0, s53, 0x1a000
	s_mov_b64 s[28:29], 0x80
	s_add_i32 s59, s53, 0x8000
	s_add_i32 s60, s53, 0xa000
	global_load_lds_dwordx4 v174, s[8:9]
	v_lshl_add_u64 v[2:3], v[2:3], 0, s[28:29]
	s_mov_b32 m0, s59
	s_add_u32 s4, s5, 0x5a03080
	global_load_lds_dwordx4 v[2:3], off
	v_lshl_add_u64 v[0:1], v[0:1], 0, s[28:29]
	s_mov_b32 m0, s60
	s_addc_u32 s5, s6, 0
	global_load_lds_dwordx4 v[0:1], off
	s_add_i32 m0, s53, 0x1c000
	s_nop 0
	global_load_lds_dwordx4 v172, s[4:5]
	s_add_i32 m0, s53, 0x1e000
	v_lshlrev_b32_e32 v6, 12, v197
	global_load_lds_dwordx4 v174, s[4:5]
	v_lshlrev_b32_e32 v1, 2, v194
	v_lshl_or_b32 v0, v194, 6, v195
	v_and_b32_e32 v1, 32, v1
	v_bitop3_b32 v1, v0, s7, v1 bitop3:0xde
	v_lshlrev_b32_e32 v0, 9, v184
	v_and_b32_e32 v0, 0x70000, v0
	v_or3_b32 v0, v4, v0, v6
	v_add_u32_e32 v2, v0, v196
	v_mov_b32_e32 v0, 0
	v_mov_b32_e32 v3, v0
	s_mov_b64 s[4:5], 0x80080
	v_lshl_add_u64 v[176:177], v[2:3], 0, s[4:5]
	v_lshlrev_b32_e32 v2, 5, v5
	v_and_b32_e32 v2, 0xf0000, v2
	s_waitcnt vmcnt(6)
	v_or3_b32 v2, v4, v2, v6
	v_add_u32_e32 v2, v2, v196
	v_lshl_or_b32 v202, s58, 7, v201
	v_lshl_add_u64 v[178:179], v[2:3], 0, s[4:5]
	v_mov_b64_e32 v[180:181], 0x400
	v_mov_b64_e32 v[182:183], 0x3ff
	s_mov_b32 s61, 0x5983000
	s_mov_b32 s62, 0x86c3000
	s_add_i32 s63, 0, 0x10000
	v_add_u32_e32 v203, 0, v1
	s_add_i32 s64, 0, 0x14000
	v_mov_b32_e32 v205, 0x358637bd
	s_mov_b32 s65, 0xf800000
	v_mov_b32_e32 v206, 0x260
	s_mov_b32 s66, 0
	s_barrier
	s_branch .LBB0_1338

; #define PG8_STAGE(bufoff, gbase, voff) do { _Pragma("unroll") for (int _i = 0; _i < 2; ++_i) \
;         __builtin_amdgcn_global_load_lds((const unsigned*)((const char*)(gbase) + (voff)[_i]), (LAS unsigned*)(lds + (bufoff) + ldsw + _i * 8192), 16, 0, 0); } while (0)
; #define PG8_LDA(dst, b, h) do { _Pragma("unroll") for (int m = 0; m < 4; ++m) _Pragma("unroll") for (int k = 0; k < 2; ++k) dst[m][k] = *(const LAS bf16x8*)(lds + PG8_SA(b, h) + aoff + m * 2048 + k * 1024); } while (0)
; #define PG8_LDB(dst, b, h) do { _Pragma("unroll") for (int n = 0; n < 2; ++n) _Pragma("unroll") for (int k = 0; k < 2; ++k) dst[n][k] = *(const LAS bf16x8*)(lds + PG8_SB(b, h) + boff + n * 2048 + k * 1024); } while (0)
; #define PG8_MMA(ai, bj, At, Bt) do { __builtin_amdgcn_s_setprio(1); _Pragma("unroll") for (int m = 0; m < 4; ++m) _Pragma("unroll") for (int n = 0; n < 2; ++n) _Pragma("unroll") for (int k = 0; k < 2; ++k) \
;         acc[ai][bj][m][n] = __builtin_amdgcn_mfma_f32_16x16x32_bf16(Bt[n][k], At[m][k], acc[ai][bj][m][n], 0, 0, 0); __builtin_amdgcn_s_setprio(0); } while (0)
; #define PG8_WAIT_L(n) asm volatile("s_waitcnt lgkmcnt(" #n ")" ::: "memory")
; #define PG8_BAR __builtin_amdgcn_s_barrier()
; #define PG8_SCHED __builtin_amdgcn_sched_barrier(0)
; template <class Epi, class Sched>
; DI void gemm_phase(LAS unsigned char* lds, const Gemm g, const Sched& S, const Epi& E) {
;     ...
;             PG8_LDB(B0, 0, 0); PG8_SCHED; PG8_LDA(At, 0, 0); PG8_STAGE(PG8_SA(1, 1), a1 + hstep, voffA);
;             PG8_WAIT_L(8); PG8_BAR; PG8_WAIT_L(0); PG8_MMA(0, 0, At, B0); PG8_BAR; PG8_SCHED;
;             PG8_LDB(B1, 0, 1); PG8_STAGE(PG8_SB(0, 0), b2, voffB);
;             PG8_BAR; PG8_WAIT_L(0); PG8_MMA(0, 1, At, B1); PG8_BAR;
;             PG8_LDA(At, 0, 1); PG8_STAGE(PG8_SA(0, 0), a2, voffA);
;             PG8_BAR; PG8_WAIT_L(0); PG8_MMA(1, 0, At, B0); PG8_BAR; PG8_SCHED;
.LBB0_1347:
	v_add_u32_e32 v1, s63, v202
	s_add_u32 s0, s40, s44
	ds_read_b128 v[132:135], v1
	ds_read_b128 v[136:139], v1 offset:1024
	ds_read_b128 v[140:143], v1 offset:2048
	ds_read_b128 v[144:147], v1 offset:3072
	s_addc_u32 s1, s41, s45
	s_add_u32 s0, s0, 0x100
	s_addc_u32 s1, s1, 0
	s_add_u32 s4, s79, s44
	s_addc_u32 s5, s80, s45
	s_cmpk_eq_i32 s44, 0xf00
	s_cselect_b32 s49, s70, s1
	s_cselect_b32 s48, s71, s0
	s_cselect_b32 s47, s37, s5
	s_cselect_b32 s46, s36, s4
	v_lshl_add_u64 v[2:3], v[188:189], 0, s[44:45]
	s_add_i32 m0, s53, 0xc000
	ds_read_b128 v[148:151], v203
	ds_read_b128 v[152:155], v203 offset:1024
	ds_read_b128 v[156:159], v203 offset:2048
	ds_read_b128 v[160:163], v203 offset:3072
	ds_read_b128 v[164:167], v203 offset:4096
	ds_read_b128 v[208:211], v203 offset:5120
	ds_read_b128 v[212:215], v203 offset:6144
	ds_read_b128 v[216:219], v203 offset:7168
	global_load_lds_dwordx4 v[2:3], off
	v_lshl_add_u64 v[2:3], v[190:191], 0, s[44:45]
	s_add_i32 m0, s53, 0xe000
	s_nop 0
	global_load_lds_dwordx4 v[2:3], off
	s_waitcnt lgkmcnt(8)
	s_barrier
	s_waitcnt lgkmcnt(0)
	s_setprio 1
	s_waitcnt lgkmcnt(0)
	v_mfma_f32_16x16x32_bf16 v[128:131], v[132:135], v[148:151], v[128:131]
	v_mfma_f32_16x16x32_bf16 v[124:127], v[140:143], v[148:151], v[124:127]
	v_mfma_f32_16x16x32_bf16 v[112:115], v[132:135], v[156:159], v[112:115]
	v_mfma_f32_16x16x32_bf16 v[108:111], v[140:143], v[156:159], v[108:111]
	v_mfma_f32_16x16x32_bf16 v[96:99], v[132:135], v[164:167], v[96:99]
	v_mfma_f32_16x16x32_bf16 v[92:95], v[140:143], v[164:167], v[92:95]
	v_mfma_f32_16x16x32_bf16 v[80:83], v[132:135], v[212:215], v[80:83]
	v_mfma_f32_16x16x32_bf16 v[76:79], v[140:143], v[212:215], v[76:79]
	v_mfma_f32_16x16x32_bf16 v[128:131], v[136:139], v[152:155], v[128:131]
	v_mfma_f32_16x16x32_bf16 v[124:127], v[144:147], v[152:155], v[124:127]
	v_mfma_f32_16x16x32_bf16 v[112:115], v[136:139], v[160:163], v[112:115]
	v_mfma_f32_16x16x32_bf16 v[108:111], v[144:147], v[160:163], v[108:111]
	v_mfma_f32_16x16x32_bf16 v[96:99], v[136:139], v[208:211], v[96:99]
	v_mfma_f32_16x16x32_bf16 v[92:95], v[144:147], v[208:211], v[92:95]
	v_mfma_f32_16x16x32_bf16 v[80:83], v[136:139], v[216:219], v[80:83]
	v_mfma_f32_16x16x32_bf16 v[76:79], v[144:147], v[216:219], v[76:79]
	s_setprio 0
	s_barrier
	s_add_i32 s0, s63, s51
	v_add_u32_e32 v1, s64, v202
	s_mov_b32 m0, s0
	ds_read_b128 v[220:223], v1
	ds_read_b128 v[224:227], v1 offset:1024
	ds_read_b128 v[228:231], v1 offset:2048
	ds_read_b128 v[232:235], v1 offset:3072
	global_load_lds_dwordx4 v172, s[46:47]
	s_add_i32 m0, s0, 0x2000
	s_nop 0
	global_load_lds_dwordx4 v174, s[46:47]
	s_barrier
	s_waitcnt lgkmcnt(0)
	s_setprio 1
	s_waitcnt lgkmcnt(0)
	v_mfma_f32_16x16x32_bf16 v[120:123], v[220:223], v[148:151], v[120:123]
	v_mfma_f32_16x16x32_bf16 v[116:119], v[228:231], v[148:151], v[116:119]
	v_mfma_f32_16x16x32_bf16 v[104:107], v[220:223], v[156:159], v[104:107]
	v_mfma_f32_16x16x32_bf16 v[100:103], v[228:231], v[156:159], v[100:103]
	v_mfma_f32_16x16x32_bf16 v[88:91], v[220:223], v[164:167], v[88:91]
	v_mfma_f32_16x16x32_bf16 v[84:87], v[228:231], v[164:167], v[84:87]
	v_mfma_f32_16x16x32_bf16 v[72:75], v[220:223], v[212:215], v[72:75]
	v_mfma_f32_16x16x32_bf16 v[68:71], v[228:231], v[212:215], v[68:71]
	v_mfma_f32_16x16x32_bf16 v[120:123], v[224:227], v[152:155], v[120:123]
	v_mfma_f32_16x16x32_bf16 v[116:119], v[232:235], v[152:155], v[116:119]
	v_mfma_f32_16x16x32_bf16 v[104:107], v[224:227], v[160:163], v[104:107]
	v_mfma_f32_16x16x32_bf16 v[100:103], v[232:235], v[160:163], v[100:103]
	v_mfma_f32_16x16x32_bf16 v[88:91], v[224:227], v[208:211], v[88:91]
	v_mfma_f32_16x16x32_bf16 v[84:87], v[232:235], v[208:211], v[84:87]
	v_mfma_f32_16x16x32_bf16 v[72:75], v[224:227], v[216:219], v[72:75]
	v_mfma_f32_16x16x32_bf16 v[68:71], v[232:235], v[216:219], v[68:71]
	s_setprio 0
	s_mov_b32 m0, s53
	s_barrier
	ds_read_b128 v[148:151], v203 offset:16384
	ds_read_b128 v[152:155], v203 offset:17408
	ds_read_b128 v[156:159], v203 offset:18432
	ds_read_b128 v[160:163], v203 offset:19456
	ds_read_b128 v[164:167], v203 offset:20480
	ds_read_b128 v[208:211], v203 offset:21504
	ds_read_b128 v[212:215], v203 offset:22528
	ds_read_b128 v[216:219], v203 offset:23552
	global_load_lds_dwordx4 v168, s[48:49]
	s_mov_b32 m0, s54
	s_nop 0
	global_load_lds_dwordx4 v170, s[48:49]
	s_barrier
	s_waitcnt lgkmcnt(0)
	s_setprio 1
	s_waitcnt lgkmcnt(0)
	v_mfma_f32_16x16x32_bf16 v[64:67], v[132:135], v[148:151], v[64:67]
	v_mfma_f32_16x16x32_bf16 v[60:63], v[140:143], v[148:151], v[60:63]
	v_mfma_f32_16x16x32_bf16 v[48:51], v[132:135], v[156:159], v[48:51]
	v_mfma_f32_16x16x32_bf16 v[44:47], v[140:143], v[156:159], v[44:47]
	v_mfma_f32_16x16x32_bf16 v[32:35], v[132:135], v[164:167], v[32:35]
	v_mfma_f32_16x16x32_bf16 v[28:31], v[140:143], v[164:167], v[28:31]
	v_mfma_f32_16x16x32_bf16 v[16:19], v[132:135], v[212:215], v[16:19]
	v_mfma_f32_16x16x32_bf16 v[12:15], v[140:143], v[212:215], v[12:15]
	v_mfma_f32_16x16x32_bf16 v[64:67], v[136:139], v[152:155], v[64:67]
	v_mfma_f32_16x16x32_bf16 v[60:63], v[144:147], v[152:155], v[60:63]
	v_mfma_f32_16x16x32_bf16 v[48:51], v[136:139], v[160:163], v[48:51]
	v_mfma_f32_16x16x32_bf16 v[44:47], v[144:147], v[160:163], v[44:47]
	v_mfma_f32_16x16x32_bf16 v[32:35], v[136:139], v[208:211], v[32:35]
	v_mfma_f32_16x16x32_bf16 v[28:31], v[144:147], v[208:211], v[28:31]
	v_mfma_f32_16x16x32_bf16 v[16:19], v[136:139], v[216:219], v[16:19]
	v_mfma_f32_16x16x32_bf16 v[12:15], v[144:147], v[216:219], v[12:15]
	s_setprio 0
	s_barrier
; #define PG8_STAGE(bufoff, gbase, voff) do { _Pragma("unroll") for (int _i = 0; _i < 2; ++_i) \
;         __builtin_amdgcn_global_load_lds((const unsigned*)((const char*)(gbase) + (voff)[_i]), (LAS unsigned*)(lds + (bufoff) + ldsw + _i * 8192), 16, 0, 0); } while (0)
; #define PG8_LDA(dst, b, h) do { _Pragma("unroll") for (int m = 0; m < 4; ++m) _Pragma("unroll") for (int k = 0; k < 2; ++k) dst[m][k] = *(const LAS bf16x8*)(lds + PG8_SA(b, h) + aoff + m * 2048 + k * 1024); } while (0)
; #define PG8_LDB(dst, b, h) do { _Pragma("unroll") for (int n = 0; n < 2; ++n) _Pragma("unroll") for (int k = 0; k < 2; ++k) dst[n][k] = *(const LAS bf16x8*)(lds + PG8_SB(b, h) + boff + n * 2048 + k * 1024); } while (0)
; #define PG8_MMA(ai, bj, At, Bt) do { __builtin_amdgcn_s_setprio(1); _Pragma("unroll") for (int m = 0; m < 4; ++m) _Pragma("unroll") for (int n = 0; n < 2; ++n) _Pragma("unroll") for (int k = 0; k < 2; ++k) \
;         acc[ai][bj][m][n] = __builtin_amdgcn_mfma_f32_16x16x32_bf16(Bt[n][k], At[m][k], acc[ai][bj][m][n], 0, 0, 0); __builtin_amdgcn_s_setprio(0); } while (0)
; #define PG8_WAIT_V(n) asm volatile("s_waitcnt vmcnt(" #n ")" ::: "memory")
; #define PG8_WAIT_L(n) asm volatile("s_waitcnt lgkmcnt(" #n ")" ::: "memory")
; #define PG8_BAR __builtin_amdgcn_s_barrier()
; #define PG8_SCHED __builtin_amdgcn_sched_barrier(0)
; template <class Epi, class Sched>
; DI void gemm_phase(LAS unsigned char* lds, const Gemm g, const Sched& S, const Epi& E) {
;     ...
;             PG8_STAGE(PG8_SB(0, 1), b2 + hstep, voffB);
;             PG8_WAIT_V(6); PG8_BAR; PG8_MMA(1, 1, At, B1); PG8_BAR;
;             PG8_LDB(B0, 1, 0); PG8_SCHED; PG8_LDA(At, 1, 0); PG8_STAGE(PG8_SA(0, 1), a2 + hstep, voffA);
;             PG8_WAIT_L(8); PG8_BAR; PG8_WAIT_L(0); PG8_MMA(0, 0, At, B0); PG8_BAR; PG8_SCHED;
;             PG8_LDB(B1, 1, 1); PG8_STAGE(PG8_SB(1, 0), b3, voffB);
;             PG8_BAR; PG8_WAIT_L(0); PG8_MMA(0, 1, At, B1); PG8_BAR;
;             PG8_LDA(At, 1, 1); PG8_STAGE(PG8_SA(1, 0), a3, voffA);
;             PG8_BAR; PG8_WAIT_L(0); PG8_MMA(1, 0, At, B0); PG8_BAR; PG8_SCHED;
	s_add_u32 s0, s46, 0x80000
	s_addc_u32 s1, s47, 0
	s_add_i32 s4, s64, s51
	s_mov_b32 m0, s4
	s_nop 0
	global_load_lds_dwordx4 v172, s[0:1]
	s_add_i32 m0, s4, 0x2000
	s_nop 0
	global_load_lds_dwordx4 v174, s[0:1]
	s_waitcnt vmcnt(6)
	s_barrier
	s_setprio 1
	v_mfma_f32_16x16x32_bf16 v[56:59], v[220:223], v[148:151], v[56:59]
	v_mfma_f32_16x16x32_bf16 v[52:55], v[228:231], v[148:151], v[52:55]
	v_mfma_f32_16x16x32_bf16 v[40:43], v[220:223], v[156:159], v[40:43]
	v_mfma_f32_16x16x32_bf16 v[36:39], v[228:231], v[156:159], v[36:39]
	v_mfma_f32_16x16x32_bf16 v[24:27], v[220:223], v[164:167], v[24:27]
	v_mfma_f32_16x16x32_bf16 v[20:23], v[228:231], v[164:167], v[20:23]
	v_mfma_f32_16x16x32_bf16 v[8:11], v[220:223], v[212:215], v[8:11]
	v_mfma_f32_16x16x32_bf16 v[2:5], v[228:231], v[212:215], v[4:7]
	v_mfma_f32_16x16x32_bf16 v[56:59], v[224:227], v[152:155], v[56:59]
	v_mfma_f32_16x16x32_bf16 v[52:55], v[232:235], v[152:155], v[52:55]
	v_mfma_f32_16x16x32_bf16 v[40:43], v[224:227], v[160:163], v[40:43]
	v_mfma_f32_16x16x32_bf16 v[36:39], v[232:235], v[160:163], v[36:39]
	v_mfma_f32_16x16x32_bf16 v[24:27], v[224:227], v[208:211], v[24:27]
	v_mfma_f32_16x16x32_bf16 v[20:23], v[232:235], v[208:211], v[20:23]
	v_mfma_f32_16x16x32_bf16 v[8:11], v[224:227], v[216:219], v[8:11]
	v_mfma_f32_16x16x32_bf16 v[2:5], v[232:235], v[216:219], v[2:5]
	s_setprio 0
	s_add_i32 s4, 0, 0x18000
	v_add_u32_e32 v1, s4, v202
	s_barrier
	ds_read_b128 v[132:135], v1
	ds_read_b128 v[136:139], v1 offset:1024
	ds_read_b128 v[140:143], v1 offset:2048
	ds_read_b128 v[144:147], v1 offset:3072
	s_add_u32 s0, s48, 0x80000
	s_addc_u32 s1, s49, 0
	s_mov_b32 m0, s55
	ds_read_b128 v[148:151], v203 offset:32768
	ds_read_b128 v[152:155], v203 offset:33792
	ds_read_b128 v[156:159], v203 offset:34816
	ds_read_b128 v[160:163], v203 offset:35840
	ds_read_b128 v[164:167], v203 offset:36864
	ds_read_b128 v[208:211], v203 offset:37888
	ds_read_b128 v[212:215], v203 offset:38912
	ds_read_b128 v[216:219], v203 offset:39936
	global_load_lds_dwordx4 v168, s[0:1]
	s_mov_b32 m0, s56
	s_nop 0
	global_load_lds_dwordx4 v170, s[0:1]
	s_waitcnt lgkmcnt(8)
	s_barrier
	s_waitcnt lgkmcnt(0)
	s_setprio 1
	s_waitcnt lgkmcnt(0)
	v_mfma_f32_16x16x32_bf16 v[128:131], v[132:135], v[148:151], v[128:131]
	v_mfma_f32_16x16x32_bf16 v[124:127], v[140:143], v[148:151], v[124:127]
	v_mfma_f32_16x16x32_bf16 v[112:115], v[132:135], v[156:159], v[112:115]
	v_mfma_f32_16x16x32_bf16 v[108:111], v[140:143], v[156:159], v[108:111]
	v_mfma_f32_16x16x32_bf16 v[96:99], v[132:135], v[164:167], v[96:99]
	v_mfma_f32_16x16x32_bf16 v[92:95], v[140:143], v[164:167], v[92:95]
	v_mfma_f32_16x16x32_bf16 v[80:83], v[132:135], v[212:215], v[80:83]
	v_mfma_f32_16x16x32_bf16 v[76:79], v[140:143], v[212:215], v[76:79]
	v_mfma_f32_16x16x32_bf16 v[128:131], v[136:139], v[152:155], v[128:131]
	v_mfma_f32_16x16x32_bf16 v[124:127], v[144:147], v[152:155], v[124:127]
	v_mfma_f32_16x16x32_bf16 v[112:115], v[136:139], v[160:163], v[112:115]
	v_mfma_f32_16x16x32_bf16 v[108:111], v[144:147], v[160:163], v[108:111]
	v_mfma_f32_16x16x32_bf16 v[96:99], v[136:139], v[208:211], v[96:99]
	v_mfma_f32_16x16x32_bf16 v[92:95], v[144:147], v[208:211], v[92:95]
	v_mfma_f32_16x16x32_bf16 v[80:83], v[136:139], v[216:219], v[80:83]
	v_mfma_f32_16x16x32_bf16 v[76:79], v[144:147], v[216:219], v[76:79]
	s_setprio 0
	s_barrier
	s_add_i32 s5, 0, 0x1c000
	s_add_i32 s0, s4, s51
	v_add_u32_e32 v1, s5, v202
	s_add_i32 m0, s0, 0xffffff80
	ds_read_b128 v[220:223], v1
	ds_read_b128 v[224:227], v1 offset:1024
	ds_read_b128 v[228:231], v1 offset:2048
	ds_read_b128 v[232:235], v1 offset:3072
	global_load_lds_dwordx4 v172, s[46:47] offset:128
	s_add_i32 m0, s0, 0x1f80
	s_nop 0
	global_load_lds_dwordx4 v174, s[46:47] offset:128
	s_barrier
; #define PG8_STAGE(bufoff, gbase, voff) do { _Pragma("unroll") for (int _i = 0; _i < 2; ++_i) \
;         __builtin_amdgcn_global_load_lds((const unsigned*)((const char*)(gbase) + (voff)[_i]), (LAS unsigned*)(lds + (bufoff) + ldsw + _i * 8192), 16, 0, 0); } while (0)
; #define PG8_LDA(dst, b, h) do { _Pragma("unroll") for (int m = 0; m < 4; ++m) _Pragma("unroll") for (int k = 0; k < 2; ++k) dst[m][k] = *(const LAS bf16x8*)(lds + PG8_SA(b, h) + aoff + m * 2048 + k * 1024); } while (0)
; #define PG8_MMA(ai, bj, At, Bt) do { __builtin_amdgcn_s_setprio(1); _Pragma("unroll") for (int m = 0; m < 4; ++m) _Pragma("unroll") for (int n = 0; n < 2; ++n) _Pragma("unroll") for (int k = 0; k < 2; ++k) \
;         acc[ai][bj][m][n] = __builtin_amdgcn_mfma_f32_16x16x32_bf16(Bt[n][k], At[m][k], acc[ai][bj][m][n], 0, 0, 0); __builtin_amdgcn_s_setprio(0); } while (0)
; #define PG8_WAIT_V(n) asm volatile("s_waitcnt vmcnt(" #n ")" ::: "memory")
; #define PG8_WAIT_L(n) asm volatile("s_waitcnt lgkmcnt(" #n ")" ::: "memory")
; #define PG8_BAR __builtin_amdgcn_s_barrier()
; #define PG8_SCHED __builtin_amdgcn_sched_barrier(0)
; template <class Epi, class Sched>
; DI void gemm_phase(LAS unsigned char* lds, const Gemm g, const Sched& S, const Epi& E) {
;     ...
;             PG8_LDA(At, 1, 1); PG8_STAGE(PG8_SA(1, 0), a3, voffA);
;             PG8_BAR; PG8_WAIT_L(0); PG8_MMA(1, 0, At, B0); PG8_BAR; PG8_SCHED;
;             PG8_STAGE(PG8_SB(1, 1), b3 + hstep, voffB);
;             PG8_WAIT_V(6); PG8_BAR; PG8_MMA(1, 1, At, B1); PG8_BAR;
	s_waitcnt lgkmcnt(0)
	s_setprio 1
	s_waitcnt lgkmcnt(0)
	v_mfma_f32_16x16x32_bf16 v[120:123], v[220:223], v[148:151], v[120:123]
	v_mfma_f32_16x16x32_bf16 v[116:119], v[228:231], v[148:151], v[116:119]
	v_mfma_f32_16x16x32_bf16 v[104:107], v[220:223], v[156:159], v[104:107]
	v_mfma_f32_16x16x32_bf16 v[100:103], v[228:231], v[156:159], v[100:103]
	v_mfma_f32_16x16x32_bf16 v[88:91], v[220:223], v[164:167], v[88:91]
	v_mfma_f32_16x16x32_bf16 v[84:87], v[228:231], v[164:167], v[84:87]
	v_mfma_f32_16x16x32_bf16 v[72:75], v[220:223], v[212:215], v[72:75]
	v_mfma_f32_16x16x32_bf16 v[68:71], v[228:231], v[212:215], v[68:71]
	v_mfma_f32_16x16x32_bf16 v[120:123], v[224:227], v[152:155], v[120:123]
	v_mfma_f32_16x16x32_bf16 v[116:119], v[232:235], v[152:155], v[116:119]
	v_mfma_f32_16x16x32_bf16 v[104:107], v[224:227], v[160:163], v[104:107]
	v_mfma_f32_16x16x32_bf16 v[100:103], v[232:235], v[160:163], v[100:103]
	v_mfma_f32_16x16x32_bf16 v[88:91], v[224:227], v[208:211], v[88:91]
	v_mfma_f32_16x16x32_bf16 v[84:87], v[232:235], v[208:211], v[84:87]
	v_mfma_f32_16x16x32_bf16 v[72:75], v[224:227], v[216:219], v[72:75]
	v_mfma_f32_16x16x32_bf16 v[68:71], v[232:235], v[216:219], v[68:71]
	s_setprio 0
	s_add_i32 m0, s59, 0xffffff80
	s_barrier
	ds_read_b128 v[148:151], v203 offset:49152
	ds_read_b128 v[152:155], v203 offset:50176
	ds_read_b128 v[156:159], v203 offset:51200
	ds_read_b128 v[160:163], v203 offset:52224
	ds_read_b128 v[164:167], v203 offset:53248
	ds_read_b128 v[208:211], v203 offset:54272
	ds_read_b128 v[212:215], v203 offset:55296
	ds_read_b128 v[216:219], v203 offset:56320
	global_load_lds_dwordx4 v168, s[48:49] offset:128
	s_add_i32 m0, s60, 0xffffff80
	s_nop 0
	global_load_lds_dwordx4 v170, s[48:49] offset:128
	s_barrier
	s_waitcnt lgkmcnt(0)
	s_setprio 1
	s_waitcnt lgkmcnt(0)
	v_mfma_f32_16x16x32_bf16 v[64:67], v[132:135], v[148:151], v[64:67]
	v_mfma_f32_16x16x32_bf16 v[60:63], v[140:143], v[148:151], v[60:63]
	v_mfma_f32_16x16x32_bf16 v[48:51], v[132:135], v[156:159], v[48:51]
	v_mfma_f32_16x16x32_bf16 v[44:47], v[140:143], v[156:159], v[44:47]
	v_mfma_f32_16x16x32_bf16 v[32:35], v[132:135], v[164:167], v[32:35]
	v_mfma_f32_16x16x32_bf16 v[28:31], v[140:143], v[164:167], v[28:31]
	v_mfma_f32_16x16x32_bf16 v[16:19], v[132:135], v[212:215], v[16:19]
	v_mfma_f32_16x16x32_bf16 v[12:15], v[140:143], v[212:215], v[12:15]
	v_mfma_f32_16x16x32_bf16 v[64:67], v[136:139], v[152:155], v[64:67]
	v_mfma_f32_16x16x32_bf16 v[60:63], v[144:147], v[152:155], v[60:63]
	v_mfma_f32_16x16x32_bf16 v[48:51], v[136:139], v[160:163], v[48:51]
	v_mfma_f32_16x16x32_bf16 v[44:47], v[144:147], v[160:163], v[44:47]
	v_mfma_f32_16x16x32_bf16 v[32:35], v[136:139], v[208:211], v[32:35]
	v_mfma_f32_16x16x32_bf16 v[28:31], v[144:147], v[208:211], v[28:31]
	v_mfma_f32_16x16x32_bf16 v[16:19], v[136:139], v[216:219], v[16:19]
	v_mfma_f32_16x16x32_bf16 v[12:15], v[144:147], v[216:219], v[12:15]
	s_setprio 0
	s_barrier
	s_add_u32 s0, s46, 0x80080
	s_addc_u32 s1, s47, 0
	s_add_i32 s4, s5, s51
	s_mov_b32 m0, s4
	s_nop 0
	global_load_lds_dwordx4 v172, s[0:1]
	s_add_i32 m0, s4, 0x2000
	s_nop 0
	global_load_lds_dwordx4 v174, s[0:1]
	s_waitcnt vmcnt(6)
	s_barrier
	s_setprio 1
	v_mfma_f32_16x16x32_bf16 v[56:59], v[220:223], v[148:151], v[56:59]
	v_mfma_f32_16x16x32_bf16 v[52:55], v[228:231], v[148:151], v[52:55]
	v_mfma_f32_16x16x32_bf16 v[40:43], v[220:223], v[156:159], v[40:43]
	v_mfma_f32_16x16x32_bf16 v[36:39], v[228:231], v[156:159], v[36:39]
	v_mfma_f32_16x16x32_bf16 v[24:27], v[220:223], v[164:167], v[24:27]
	v_mfma_f32_16x16x32_bf16 v[20:23], v[228:231], v[164:167], v[20:23]
	v_mfma_f32_16x16x32_bf16 v[6:9], v[220:223], v[212:215], v[8:11]
	v_mfma_f32_16x16x32_bf16 v[2:5], v[228:231], v[212:215], v[2:5]
	v_mfma_f32_16x16x32_bf16 v[56:59], v[224:227], v[152:155], v[56:59]
	v_mfma_f32_16x16x32_bf16 v[52:55], v[232:235], v[152:155], v[52:55]
	v_mfma_f32_16x16x32_bf16 v[40:43], v[224:227], v[160:163], v[40:43]
	v_mfma_f32_16x16x32_bf16 v[36:39], v[232:235], v[160:163], v[36:39]
	v_mfma_f32_16x16x32_bf16 v[24:27], v[224:227], v[208:211], v[24:27]
	v_mfma_f32_16x16x32_bf16 v[20:23], v[232:235], v[208:211], v[20:23]
	v_mfma_f32_16x16x32_bf16 v[8:11], v[224:227], v[216:219], v[6:9]
	v_mfma_f32_16x16x32_bf16 v[4:7], v[232:235], v[216:219], v[2:5]
	s_setprio 0
	s_add_i32 s81, s81, 2
	s_add_u32 s44, s44, 0x100
	s_addc_u32 s45, s45, 0
	s_cmp_gt_u32 s81, 29
	s_barrier
	s_cbranch_scc1 .LBB0_1351

;     DI size_t aoff(const Unit& u, size_t tstep) const { return (size_t)u.pm * tstep; }
;     DI size_t boff(const Unit& u, size_t tstep) const { return (size_t)u.pn * tstep; }
;     DI size_t aoff(const Unit& u, size_t) const { return (size_t)u.ks * kbytes; }
;     DI size_t boff(const Unit& u, size_t tstep) const { return (size_t)u.pn * tstep + (size_t)u.ks * kbytes; }
;     DI size_t aoff(const Unit& u, size_t tstep) const { return (u.ks < 2 ? offU : offOA) + (size_t)u.pm * tstep; }
; #define PG8_STAGE(bufoff, gbase, voff) do { _Pragma("unroll") for (int _i = 0; _i < 2; ++_i) \
;         __builtin_amdgcn_global_load_lds((const unsigned*)((const char*)(gbase) + (voff)[_i]), (LAS unsigned*)(lds + (bufoff) + ldsw + _i * 8192), 16, 0, 0); } while (0)
; #define PG8_WAIT_V(n) asm volatile("s_waitcnt vmcnt(" #n ")" ::: "memory")
; #define PG8_BAR __builtin_amdgcn_s_barrier()
; template <class Epi, class Sched>
; DI void gemm_phase(LAS unsigned char* lds, const Gemm g, const Sched& S, const Epi& E) {
;     ...
;     const char* cA = (const char*)g.A + S.aoff(cur, tstep); const char* cB = (const char*)g.Bt + S.boff(cur, tstep);
;     PG8_STAGE(PG8_SB(0, 0), cB, voffB); PG8_STAGE(PG8_SA(0, 0), cA, voffA); PG8_STAGE(PG8_SB(0, 1), cB + hstep, voffB); PG8_STAGE(PG8_SA(0, 1), cA + hstep, voffA);
;     if (wr == 1) PG8_BAR;
;     PG8_WAIT_V(4); PG8_BAR;
;     PG8_STAGE(PG8_SB(1, 0), cB + kstep, voffB); PG8_STAGE(PG8_SA(1, 0), cA + kstep, voffA); PG8_STAGE(PG8_SB(1, 1), cB + hstep + kstep, voffB);
;     PG8_WAIT_V(6); PG8_BAR;
;     const int kc = K / S; pg8::Gemm g{A, Bt, K, kc / 64}; pg8::SplitOrder O; O.init(N, S, kc, 128, (int)gridDim.x, (int)((blockIdx.x + rot) % gridDim.x));
;     pg8::gemm_phase<Epi, pg8::SplitOrder>(lds, g, O, E);
.LBB0_1358:
	v_mul_f32_e32 v0, 0x4f7ffffe, v193
	v_cvt_u32_f32_e32 v0, v0
	s_add_u32 s8, s22, 0x3c40b000
	s_addc_u32 s9, s23, 0
	s_sub_i32 s0, 0, s26
	v_readfirstlane_b32 s34, v0
	s_mul_i32 s0, s0, s34
	s_mul_hi_u32 s0, s34, s0
	s_add_i32 s34, s34, s0
	s_mul_hi_u32 s0, s2, s34
	s_mul_i32 s0, s0, s26
	s_sub_i32 s0, s2, s0
	s_sub_i32 s1, s0, s26
	s_cmp_ge_u32 s0, s26
	s_cselect_b32 s0, s1, s0
	s_sub_i32 s1, s0, s26
	s_cmp_ge_u32 s0, s26
	s_cselect_b32 s35, s1, s0
	s_cmp_gt_i32 s35, 63
	v_readfirstlane_b32 s60, v184
	s_cbranch_scc1 .LBB0_1370
	s_lshr_b32 s0, s60, 6
	s_lshr_b32 s1, s60, 8
	s_lshl_b32 s61, s0, 10
	s_add_u32 s62, s22, 0x2ba03000
	s_addc_u32 s63, s23, 0
	s_add_u32 s64, s22, 0x6dc3000
	s_addc_u32 s65, s23, 0
	s_ashr_i32 s66, s35, 31
	s_lshr_b32 s4, s66, 29
	s_add_i32 s4, s35, s4
	s_ashr_i32 s18, s4, 3
	s_and_b32 s4, s4, -8
	s_sub_i32 s16, s35, s4
	s_ashr_i32 s17, s16, 31
	s_ashr_i32 s19, s18, 31
	s_lshl_b64 s[4:5], s[18:19], 9
	s_lshl_b64 s[6:7], s[16:17], 20
	s_add_u32 s6, s64, s6
	s_addc_u32 s7, s65, s7
	s_add_u32 s28, s6, s4
	s_addc_u32 s29, s7, s5
	s_add_i32 s17, s61, 0
	s_add_i32 m0, s17, 0x10000
	v_lshl_add_u64 v[0:1], s[28:29], 0, v[168:169]
	global_load_lds_dwordx4 v168, s[28:29]
	s_add_i32 m0, s17, 0x12000
	s_add_u32 s30, s62, s4
	v_lshl_add_u64 v[2:3], s[28:29], 0, v[170:171]
	s_addc_u32 s31, s63, s5
	s_add_i32 s67, s17, 0x2000
	global_load_lds_dwordx4 v170, s[28:29]
	v_lshl_add_u64 v[6:7], s[30:31], 0, v[168:169]
	s_mov_b32 m0, s17
	s_add_u32 s4, s28, 0x80000
	global_load_lds_dwordx4 v168, s[30:31]
	v_lshl_add_u64 v[4:5], s[30:31], 0, v[170:171]
	s_mov_b32 m0, s67
	s_addc_u32 s5, s29, 0
	global_load_lds_dwordx4 v170, s[30:31]
	s_add_i32 m0, s17, 0x14000
	s_nop 0
	global_load_lds_dwordx4 v168, s[4:5]
	s_add_i32 m0, s17, 0x16000
	v_lshl_add_u64 v[8:9], s[4:5], 0, v[170:171]
	s_add_u32 s4, s30, 0x80000
	s_addc_u32 s5, s31, 0
	s_add_i32 s68, s17, 0x4000
	global_load_lds_dwordx4 v[8:9], off
	s_mov_b32 m0, s68
	s_add_i32 s69, s17, 0x6000
	global_load_lds_dwordx4 v168, s[4:5]
	s_mov_b32 m0, s69
	s_cmp_lg_u32 s1, 1
	global_load_lds_dwordx4 v170, s[4:5]
	s_cbranch_scc1 .LBB0_1361
	s_barrier
.LBB0_1361:
	s_mov_b64 s[6:7], 0x80
	s_lshl_b32 s0, s0, 5
	s_add_i32 m0, s17, 0x18000
	v_lshl_add_u64 v[0:1], v[0:1], 0, s[6:7]
	s_lshl_b32 s70, s1, 6
	s_lshl_b32 s4, s1, 13
	s_and_b32 s71, s0, 0x60
	s_waitcnt vmcnt(4)
	s_barrier
	global_load_lds_dwordx4 v[0:1], off
	v_lshl_add_u64 v[0:1], v[2:3], 0, s[6:7]
	s_add_i32 m0, s17, 0x1a000
	s_add_i32 s72, s17, 0x8000
	s_add_i32 s73, s17, 0xa000
	global_load_lds_dwordx4 v[0:1], off
	v_lshl_add_u64 v[0:1], v[6:7], 0, s[6:7]
	s_mov_b32 m0, s72
	s_add_u32 s0, s28, 0x80080
	global_load_lds_dwordx4 v[0:1], off
	v_lshl_add_u64 v[0:1], v[4:5], 0, s[6:7]
	s_mov_b32 m0, s73
	s_addc_u32 s1, s29, 0
	global_load_lds_dwordx4 v[0:1], off
	s_add_i32 m0, s17, 0x1c000
	s_nop 0
	global_load_lds_dwordx4 v168, s[0:1]
	s_add_i32 m0, s17, 0x1e000
	v_lshl_or_b32 v128, s71, 7, v201
	global_load_lds_dwordx4 v170, s[0:1]
	v_lshlrev_b32_e32 v1, 2, v194
	v_lshl_or_b32 v0, v194, 6, v195
	v_and_b32_e32 v1, 32, v1
	s_waitcnt vmcnt(6)
	v_bitop3_b32 v0, v0, s4, v1 bitop3:0xde
	s_add_i32 s75, 0, 0x10000
	s_add_i32 s76, 0, 0x14000
	s_mov_b32 s74, 0
	v_add_u32_e32 v129, s75, v128
	v_add_u32_e32 v130, 0, v0
	v_add_u32_e32 v131, s76, v128
	s_add_i32 s77, s17, 0xc000
	s_add_i32 s78, s17, 0xe000
	s_barrier

; #define PG8_STAGE(bufoff, gbase, voff) do { _Pragma("unroll") for (int _i = 0; _i < 2; ++_i) \
;         __builtin_amdgcn_global_load_lds((const unsigned*)((const char*)(gbase) + (voff)[_i]), (LAS unsigned*)(lds + (bufoff) + ldsw + _i * 8192), 16, 0, 0); } while (0)
; #define PG8_LDA(dst, b, h) do { _Pragma("unroll") for (int m = 0; m < 4; ++m) _Pragma("unroll") for (int k = 0; k < 2; ++k) dst[m][k] = *(const LAS bf16x8*)(lds + PG8_SA(b, h) + aoff + m * 2048 + k * 1024); } while (0)
; #define PG8_LDB(dst, b, h) do { _Pragma("unroll") for (int n = 0; n < 2; ++n) _Pragma("unroll") for (int k = 0; k < 2; ++k) dst[n][k] = *(const LAS bf16x8*)(lds + PG8_SB(b, h) + boff + n * 2048 + k * 1024); } while (0)
; #define PG8_MMA(ai, bj, At, Bt) do { __builtin_amdgcn_s_setprio(1); _Pragma("unroll") for (int m = 0; m < 4; ++m) _Pragma("unroll") for (int n = 0; n < 2; ++n) _Pragma("unroll") for (int k = 0; k < 2; ++k) \
;         acc[ai][bj][m][n] = __builtin_amdgcn_mfma_f32_16x16x32_bf16(Bt[n][k], At[m][k], acc[ai][bj][m][n], 0, 0, 0); __builtin_amdgcn_s_setprio(0); } while (0)
; #define PG8_WAIT_V(n) asm volatile("s_waitcnt vmcnt(" #n ")" ::: "memory")
; #define PG8_WAIT_L(n) asm volatile("s_waitcnt lgkmcnt(" #n ")" ::: "memory")
; #define PG8_BAR __builtin_amdgcn_s_barrier()
; #define PG8_SCHED __builtin_amdgcn_sched_barrier(0)
; template <class Epi, class Sched>
; DI void gemm_phase(LAS unsigned char* lds, const Gemm g, const Sched& S, const Epi& E) {
;     ...
;             PG8_LDB(B0, 0, 0); PG8_SCHED; PG8_LDA(At, 0, 0); PG8_STAGE(PG8_SA(1, 1), a1 + hstep, voffA);
;             PG8_WAIT_L(8); PG8_BAR; PG8_WAIT_L(0); PG8_MMA(0, 0, At, B0); PG8_BAR; PG8_SCHED;
;             PG8_LDB(B1, 0, 1); PG8_STAGE(PG8_SB(0, 0), b2, voffB);
;             PG8_BAR; PG8_WAIT_L(0); PG8_MMA(0, 1, At, B1); PG8_BAR;
;             PG8_LDA(At, 0, 1); PG8_STAGE(PG8_SA(0, 0), a2, voffA);
;             PG8_BAR; PG8_WAIT_L(0); PG8_MMA(1, 0, At, B0); PG8_BAR; PG8_SCHED;
;             PG8_STAGE(PG8_SB(0, 1), b2 + hstep, voffB);
;             PG8_WAIT_V(6); PG8_BAR; PG8_MMA(1, 1, At, B1); PG8_BAR;
;             PG8_LDB(B0, 1, 0); PG8_SCHED; PG8_LDA(At, 1, 0); PG8_STAGE(PG8_SA(0, 1), a2 + hstep, voffA);
;             PG8_WAIT_L(8); PG8_BAR; PG8_WAIT_L(0); PG8_MMA(0, 0, At, B0); PG8_BAR; PG8_SCHED;
.LBB0_1365:
	s_add_u32 s33, s30, s0
	s_addc_u32 s39, s31, 0
	s_add_u32 s1, s33, 0x100
	s_addc_u32 s50, s39, 0
	s_and_b64 s[4:5], s[48:49], exec
	s_cselect_b32 s55, s19, s50
	s_cselect_b32 s54, s37, s1
	s_add_u32 s0, s28, s0
	s_addc_u32 s1, s29, 0
	s_add_u32 s4, s0, 0x100
	s_addc_u32 s5, s1, 0
	s_and_b64 s[0:1], s[48:49], exec
	s_cselect_b32 s57, s45, s5
	s_cselect_b32 s56, s44, s4
	s_add_u32 s58, s33, 0x80080
	s_addc_u32 s59, s39, 0
	s_add_i32 s82, s75, s61
	s_add_i32 s81, s82, 0x2000
	s_add_u32 s52, s56, 0x80000
	s_addc_u32 s53, s57, 0
	s_add_i32 s39, s76, s61
	ds_read_b128 v[132:135], v129
	ds_read_b128 v[136:139], v129 offset:1024
	ds_read_b128 v[140:143], v129 offset:2048
	ds_read_b128 v[144:147], v129 offset:3072
	s_add_i32 s33, s39, 0x2000
	s_add_i32 s5, 0, 0x18000
	s_add_u32 s50, s54, 0x80000
	s_addc_u32 s51, s55, 0
	s_add_i32 s4, s5, s61
	s_add_i32 s1, 0, 0x1c000
	s_add_i32 s0, s4, 0x2000
	s_add_u32 s48, s56, 0x80080
	s_addc_u32 s49, s57, 0
	s_add_i32 s80, s1, s61
	s_add_i32 s79, s80, 0x2000
	s_mov_b32 m0, s77
	ds_read_b128 v[148:151], v130
	ds_read_b128 v[152:155], v130 offset:1024
	ds_read_b128 v[156:159], v130 offset:2048
	ds_read_b128 v[160:163], v130 offset:3072
	ds_read_b128 v[164:167], v130 offset:4096
	ds_read_b128 v[172:175], v130 offset:5120
	ds_read_b128 v[176:179], v130 offset:6144
	ds_read_b128 v[180:183], v130 offset:7168
	global_load_lds_dwordx4 v168, s[58:59]
	s_mov_b32 m0, s78
	s_nop 0
	global_load_lds_dwordx4 v170, s[58:59]
	s_waitcnt lgkmcnt(8)
	s_barrier
	s_waitcnt lgkmcnt(0)
	s_setprio 1
	s_waitcnt lgkmcnt(0)
	v_mfma_f32_16x16x32_bf16 v[124:127], v[132:135], v[148:151], v[124:127]
	v_mfma_f32_16x16x32_bf16 v[120:123], v[140:143], v[148:151], v[120:123]
	v_mfma_f32_16x16x32_bf16 v[116:119], v[132:135], v[156:159], v[116:119]
	v_mfma_f32_16x16x32_bf16 v[112:115], v[140:143], v[156:159], v[112:115]
	v_mfma_f32_16x16x32_bf16 v[104:107], v[132:135], v[164:167], v[104:107]
	v_mfma_f32_16x16x32_bf16 v[96:99], v[140:143], v[164:167], v[96:99]
	v_mfma_f32_16x16x32_bf16 v[88:91], v[132:135], v[176:179], v[88:91]
	v_mfma_f32_16x16x32_bf16 v[80:83], v[140:143], v[176:179], v[80:83]
	v_mfma_f32_16x16x32_bf16 v[124:127], v[136:139], v[152:155], v[124:127]
	v_mfma_f32_16x16x32_bf16 v[120:123], v[144:147], v[152:155], v[120:123]
	v_mfma_f32_16x16x32_bf16 v[116:119], v[136:139], v[160:163], v[116:119]
	v_mfma_f32_16x16x32_bf16 v[112:115], v[144:147], v[160:163], v[112:115]
	v_mfma_f32_16x16x32_bf16 v[104:107], v[136:139], v[172:175], v[104:107]
	v_mfma_f32_16x16x32_bf16 v[96:99], v[144:147], v[172:175], v[96:99]
	v_mfma_f32_16x16x32_bf16 v[88:91], v[136:139], v[180:183], v[88:91]
	v_mfma_f32_16x16x32_bf16 v[80:83], v[144:147], v[180:183], v[80:83]
	s_setprio 0
	s_barrier
	s_mov_b32 m0, s82
	ds_read_b128 v[188:191], v131
	ds_read_b128 v[206:209], v131 offset:1024
	ds_read_b128 v[210:213], v131 offset:2048
	ds_read_b128 v[214:217], v131 offset:3072
	global_load_lds_dwordx4 v168, s[56:57]
	s_mov_b32 m0, s81
	s_nop 0
	global_load_lds_dwordx4 v170, s[56:57]
	s_barrier
	s_waitcnt lgkmcnt(0)
	s_setprio 1
	s_waitcnt lgkmcnt(0)
	v_mfma_f32_16x16x32_bf16 v[108:111], v[188:191], v[148:151], v[108:111]
	v_mfma_f32_16x16x32_bf16 v[100:103], v[210:213], v[148:151], v[100:103]
	v_mfma_f32_16x16x32_bf16 v[92:95], v[188:191], v[156:159], v[92:95]
	v_mfma_f32_16x16x32_bf16 v[84:87], v[210:213], v[156:159], v[84:87]
	v_mfma_f32_16x16x32_bf16 v[76:79], v[188:191], v[164:167], v[76:79]
	v_mfma_f32_16x16x32_bf16 v[72:75], v[210:213], v[164:167], v[72:75]
	v_mfma_f32_16x16x32_bf16 v[68:71], v[188:191], v[176:179], v[68:71]
	v_mfma_f32_16x16x32_bf16 v[64:67], v[210:213], v[176:179], v[64:67]
	v_mfma_f32_16x16x32_bf16 v[108:111], v[206:209], v[152:155], v[108:111]
	v_mfma_f32_16x16x32_bf16 v[100:103], v[214:217], v[152:155], v[100:103]
	v_mfma_f32_16x16x32_bf16 v[92:95], v[206:209], v[160:163], v[92:95]
	v_mfma_f32_16x16x32_bf16 v[84:87], v[214:217], v[160:163], v[84:87]
	v_mfma_f32_16x16x32_bf16 v[76:79], v[206:209], v[172:175], v[76:79]
	v_mfma_f32_16x16x32_bf16 v[72:75], v[214:217], v[172:175], v[72:75]
	v_mfma_f32_16x16x32_bf16 v[68:71], v[206:209], v[180:183], v[68:71]
	v_mfma_f32_16x16x32_bf16 v[64:67], v[214:217], v[180:183], v[64:67]
	s_setprio 0
	s_mov_b32 m0, s17
	s_barrier
	ds_read_b128 v[148:151], v130 offset:16384
	ds_read_b128 v[152:155], v130 offset:17408
	ds_read_b128 v[156:159], v130 offset:18432
	ds_read_b128 v[160:163], v130 offset:19456
	ds_read_b128 v[164:167], v130 offset:20480
	ds_read_b128 v[172:175], v130 offset:21504
	ds_read_b128 v[176:179], v130 offset:22528
	ds_read_b128 v[180:183], v130 offset:23552
	global_load_lds_dwordx4 v168, s[54:55]
	s_mov_b32 m0, s67
	s_nop 0
	global_load_lds_dwordx4 v170, s[54:55]
	s_barrier
	s_waitcnt lgkmcnt(0)
	s_setprio 1
	s_waitcnt lgkmcnt(0)
	v_mfma_f32_16x16x32_bf16 v[60:63], v[132:135], v[148:151], v[60:63]
	v_mfma_f32_16x16x32_bf16 v[56:59], v[140:143], v[148:151], v[56:59]
	v_mfma_f32_16x16x32_bf16 v[52:55], v[132:135], v[156:159], v[52:55]
	v_mfma_f32_16x16x32_bf16 v[48:51], v[140:143], v[156:159], v[48:51]
	v_mfma_f32_16x16x32_bf16 v[40:43], v[132:135], v[164:167], v[40:43]
	v_mfma_f32_16x16x32_bf16 v[32:35], v[140:143], v[164:167], v[32:35]
	v_mfma_f32_16x16x32_bf16 v[24:27], v[132:135], v[176:179], v[24:27]
	v_mfma_f32_16x16x32_bf16 v[16:19], v[140:143], v[176:179], v[16:19]
	v_mfma_f32_16x16x32_bf16 v[60:63], v[136:139], v[152:155], v[60:63]
	v_mfma_f32_16x16x32_bf16 v[56:59], v[144:147], v[152:155], v[56:59]
	v_mfma_f32_16x16x32_bf16 v[52:55], v[136:139], v[160:163], v[52:55]
	v_mfma_f32_16x16x32_bf16 v[48:51], v[144:147], v[160:163], v[48:51]
	v_mfma_f32_16x16x32_bf16 v[40:43], v[136:139], v[172:175], v[40:43]
	v_mfma_f32_16x16x32_bf16 v[32:35], v[144:147], v[172:175], v[32:35]
	v_mfma_f32_16x16x32_bf16 v[24:27], v[136:139], v[180:183], v[24:27]
	v_mfma_f32_16x16x32_bf16 v[16:19], v[144:147], v[180:183], v[16:19]
	s_setprio 0
	s_barrier
; #define PG8_STAGE(bufoff, gbase, voff) do { _Pragma("unroll") for (int _i = 0; _i < 2; ++_i) \
;         __builtin_amdgcn_global_load_lds((const unsigned*)((const char*)(gbase) + (voff)[_i]), (LAS unsigned*)(lds + (bufoff) + ldsw + _i * 8192), 16, 0, 0); } while (0)
; #define PG8_LDA(dst, b, h) do { _Pragma("unroll") for (int m = 0; m < 4; ++m) _Pragma("unroll") for (int k = 0; k < 2; ++k) dst[m][k] = *(const LAS bf16x8*)(lds + PG8_SA(b, h) + aoff + m * 2048 + k * 1024); } while (0)
; #define PG8_LDB(dst, b, h) do { _Pragma("unroll") for (int n = 0; n < 2; ++n) _Pragma("unroll") for (int k = 0; k < 2; ++k) dst[n][k] = *(const LAS bf16x8*)(lds + PG8_SB(b, h) + boff + n * 2048 + k * 1024); } while (0)
; #define PG8_MMA(ai, bj, At, Bt) do { __builtin_amdgcn_s_setprio(1); _Pragma("unroll") for (int m = 0; m < 4; ++m) _Pragma("unroll") for (int n = 0; n < 2; ++n) _Pragma("unroll") for (int k = 0; k < 2; ++k) \
;         acc[ai][bj][m][n] = __builtin_amdgcn_mfma_f32_16x16x32_bf16(Bt[n][k], At[m][k], acc[ai][bj][m][n], 0, 0, 0); __builtin_amdgcn_s_setprio(0); } while (0)
; #define PG8_WAIT_V(n) asm volatile("s_waitcnt vmcnt(" #n ")" ::: "memory")
; #define PG8_WAIT_L(n) asm volatile("s_waitcnt lgkmcnt(" #n ")" ::: "memory")
; #define PG8_BAR __builtin_amdgcn_s_barrier()
; #define PG8_SCHED __builtin_amdgcn_sched_barrier(0)
; template <class Epi, class Sched>
; DI void gemm_phase(LAS unsigned char* lds, const Gemm g, const Sched& S, const Epi& E) {
;     ...
;             PG8_STAGE(PG8_SB(0, 1), b2 + hstep, voffB);
;             PG8_WAIT_V(6); PG8_BAR; PG8_MMA(1, 1, At, B1); PG8_BAR;
;             PG8_LDB(B0, 1, 0); PG8_SCHED; PG8_LDA(At, 1, 0); PG8_STAGE(PG8_SA(0, 1), a2 + hstep, voffA);
;             PG8_WAIT_L(8); PG8_BAR; PG8_WAIT_L(0); PG8_MMA(0, 0, At, B0); PG8_BAR; PG8_SCHED;
;             PG8_LDB(B1, 1, 1); PG8_STAGE(PG8_SB(1, 0), b3, voffB);
;             PG8_BAR; PG8_WAIT_L(0); PG8_MMA(0, 1, At, B1); PG8_BAR;
;             PG8_LDA(At, 1, 1); PG8_STAGE(PG8_SA(1, 0), a3, voffA);
;             PG8_BAR; PG8_WAIT_L(0); PG8_MMA(1, 0, At, B0); PG8_BAR; PG8_SCHED;
	s_mov_b32 m0, s39
	s_nop 0
	global_load_lds_dwordx4 v168, s[52:53]
	s_mov_b32 m0, s33
	s_nop 0
	global_load_lds_dwordx4 v170, s[52:53]
	s_waitcnt vmcnt(6)
	s_barrier
	s_setprio 1
	v_mfma_f32_16x16x32_bf16 v[44:47], v[188:191], v[148:151], v[44:47]
	v_mfma_f32_16x16x32_bf16 v[36:39], v[210:213], v[148:151], v[36:39]
	v_mfma_f32_16x16x32_bf16 v[28:31], v[188:191], v[156:159], v[28:31]
	v_mfma_f32_16x16x32_bf16 v[20:23], v[210:213], v[156:159], v[20:23]
	v_mfma_f32_16x16x32_bf16 v[12:15], v[188:191], v[164:167], v[12:15]
	v_mfma_f32_16x16x32_bf16 v[8:11], v[210:213], v[164:167], v[8:11]
	v_mfma_f32_16x16x32_bf16 v[4:7], v[188:191], v[176:179], v[4:7]
	v_mfma_f32_16x16x32_bf16 v[0:3], v[210:213], v[176:179], v[0:3]
	v_mfma_f32_16x16x32_bf16 v[44:47], v[206:209], v[152:155], v[44:47]
	v_mfma_f32_16x16x32_bf16 v[36:39], v[214:217], v[152:155], v[36:39]
	v_mfma_f32_16x16x32_bf16 v[28:31], v[206:209], v[160:163], v[28:31]
	v_mfma_f32_16x16x32_bf16 v[20:23], v[214:217], v[160:163], v[20:23]
	v_mfma_f32_16x16x32_bf16 v[12:15], v[206:209], v[172:175], v[12:15]
	v_mfma_f32_16x16x32_bf16 v[8:11], v[214:217], v[172:175], v[8:11]
	v_mfma_f32_16x16x32_bf16 v[4:7], v[206:209], v[180:183], v[4:7]
	v_mfma_f32_16x16x32_bf16 v[0:3], v[214:217], v[180:183], v[0:3]
	s_setprio 0
	v_add_u32_e32 v144, s5, v128
	s_barrier
	ds_read_b128 v[132:135], v144
	ds_read_b128 v[136:139], v144 offset:1024
	ds_read_b128 v[140:143], v144 offset:2048
	ds_read_b128 v[144:147], v144 offset:3072
	s_mov_b32 m0, s68
	ds_read_b128 v[148:151], v130 offset:32768
	ds_read_b128 v[152:155], v130 offset:33792
	ds_read_b128 v[156:159], v130 offset:34816
	ds_read_b128 v[160:163], v130 offset:35840
	ds_read_b128 v[164:167], v130 offset:36864
	ds_read_b128 v[172:175], v130 offset:37888
	ds_read_b128 v[176:179], v130 offset:38912
	ds_read_b128 v[180:183], v130 offset:39936
	global_load_lds_dwordx4 v168, s[50:51]
	s_mov_b32 m0, s69
	s_nop 0
	global_load_lds_dwordx4 v170, s[50:51]
	s_waitcnt lgkmcnt(8)
	s_barrier
	s_waitcnt lgkmcnt(0)
	s_setprio 1
	s_waitcnt lgkmcnt(0)
	v_mfma_f32_16x16x32_bf16 v[124:127], v[132:135], v[148:151], v[124:127]
	v_mfma_f32_16x16x32_bf16 v[120:123], v[140:143], v[148:151], v[120:123]
	v_mfma_f32_16x16x32_bf16 v[116:119], v[132:135], v[156:159], v[116:119]
	v_mfma_f32_16x16x32_bf16 v[112:115], v[140:143], v[156:159], v[112:115]
	v_mfma_f32_16x16x32_bf16 v[104:107], v[132:135], v[164:167], v[104:107]
	v_mfma_f32_16x16x32_bf16 v[96:99], v[140:143], v[164:167], v[96:99]
	v_mfma_f32_16x16x32_bf16 v[88:91], v[132:135], v[176:179], v[88:91]
	v_mfma_f32_16x16x32_bf16 v[80:83], v[140:143], v[176:179], v[80:83]
	v_mfma_f32_16x16x32_bf16 v[124:127], v[136:139], v[152:155], v[124:127]
	v_mfma_f32_16x16x32_bf16 v[120:123], v[144:147], v[152:155], v[120:123]
	v_mfma_f32_16x16x32_bf16 v[116:119], v[136:139], v[160:163], v[116:119]
	v_mfma_f32_16x16x32_bf16 v[112:115], v[144:147], v[160:163], v[112:115]
	v_mfma_f32_16x16x32_bf16 v[104:107], v[136:139], v[172:175], v[104:107]
	v_mfma_f32_16x16x32_bf16 v[96:99], v[144:147], v[172:175], v[96:99]
	v_mfma_f32_16x16x32_bf16 v[88:91], v[136:139], v[180:183], v[88:91]
	v_mfma_f32_16x16x32_bf16 v[80:83], v[144:147], v[180:183], v[80:83]
	s_setprio 0
	s_barrier
	s_add_i32 m0, s4, 0xffffff80
	v_add_u32_e32 v205, s1, v128
	ds_read_b128 v[188:191], v205
	ds_read_b128 v[206:209], v205 offset:1024
	ds_read_b128 v[210:213], v205 offset:2048
	ds_read_b128 v[214:217], v205 offset:3072
	global_load_lds_dwordx4 v168, s[56:57] offset:128
	s_add_i32 m0, s0, 0xffffff80
	s_nop 0
	global_load_lds_dwordx4 v170, s[56:57] offset:128
	s_barrier
	s_waitcnt lgkmcnt(0)
	s_setprio 1
	s_waitcnt lgkmcnt(0)
	v_mfma_f32_16x16x32_bf16 v[108:111], v[188:191], v[148:151], v[108:111]
	v_mfma_f32_16x16x32_bf16 v[100:103], v[210:213], v[148:151], v[100:103]
	v_mfma_f32_16x16x32_bf16 v[92:95], v[188:191], v[156:159], v[92:95]
	v_mfma_f32_16x16x32_bf16 v[84:87], v[210:213], v[156:159], v[84:87]
	v_mfma_f32_16x16x32_bf16 v[76:79], v[188:191], v[164:167], v[76:79]
	v_mfma_f32_16x16x32_bf16 v[72:75], v[210:213], v[164:167], v[72:75]
	v_mfma_f32_16x16x32_bf16 v[68:71], v[188:191], v[176:179], v[68:71]
	v_mfma_f32_16x16x32_bf16 v[64:67], v[210:213], v[176:179], v[64:67]
	v_mfma_f32_16x16x32_bf16 v[108:111], v[206:209], v[152:155], v[108:111]
	v_mfma_f32_16x16x32_bf16 v[100:103], v[214:217], v[152:155], v[100:103]
	v_mfma_f32_16x16x32_bf16 v[92:95], v[206:209], v[160:163], v[92:95]
	v_mfma_f32_16x16x32_bf16 v[84:87], v[214:217], v[160:163], v[84:87]
	v_mfma_f32_16x16x32_bf16 v[76:79], v[206:209], v[172:175], v[76:79]
	v_mfma_f32_16x16x32_bf16 v[72:75], v[214:217], v[172:175], v[72:75]
	v_mfma_f32_16x16x32_bf16 v[68:71], v[206:209], v[180:183], v[68:71]
	v_mfma_f32_16x16x32_bf16 v[64:67], v[214:217], v[180:183], v[64:67]
	s_setprio 0
	s_add_i32 m0, s72, 0xffffff80
	s_barrier
	ds_read_b128 v[148:151], v130 offset:49152
	ds_read_b128 v[152:155], v130 offset:50176
	ds_read_b128 v[156:159], v130 offset:51200
	ds_read_b128 v[160:163], v130 offset:52224
	ds_read_b128 v[164:167], v130 offset:53248
	ds_read_b128 v[172:175], v130 offset:54272
	ds_read_b128 v[176:179], v130 offset:55296
	ds_read_b128 v[180:183], v130 offset:56320
	global_load_lds_dwordx4 v168, s[54:55] offset:128
	s_add_i32 m0, s73, 0xffffff80
	s_nop 0
	global_load_lds_dwordx4 v170, s[54:55] offset:128
	s_barrier
; #define PG8_STAGE(bufoff, gbase, voff) do { _Pragma("unroll") for (int _i = 0; _i < 2; ++_i) \
;         __builtin_amdgcn_global_load_lds((const unsigned*)((const char*)(gbase) + (voff)[_i]), (LAS unsigned*)(lds + (bufoff) + ldsw + _i * 8192), 16, 0, 0); } while (0)
; #define PG8_MMA(ai, bj, At, Bt) do { __builtin_amdgcn_s_setprio(1); _Pragma("unroll") for (int m = 0; m < 4; ++m) _Pragma("unroll") for (int n = 0; n < 2; ++n) _Pragma("unroll") for (int k = 0; k < 2; ++k) \
;         acc[ai][bj][m][n] = __builtin_amdgcn_mfma_f32_16x16x32_bf16(Bt[n][k], At[m][k], acc[ai][bj][m][n], 0, 0, 0); __builtin_amdgcn_s_setprio(0); } while (0)
; #define PG8_WAIT_V(n) asm volatile("s_waitcnt vmcnt(" #n ")" ::: "memory")
; #define PG8_BAR __builtin_amdgcn_s_barrier()
; template <class Epi, class Sched>
; DI void gemm_phase(LAS unsigned char* lds, const Gemm g, const Sched& S, const Epi& E) {
;     ...
;             PG8_STAGE(PG8_SB(1, 1), b3 + hstep, voffB);
;             PG8_WAIT_V(6); PG8_BAR; PG8_MMA(1, 1, At, B1); PG8_BAR;
;         }
;         { int fr2 = fr, fq2 = fq; asm volatile("" : "+v"(fr2), "+v"(fq2)); E(acc, cur, wr, wc, fr2, fq2); }
;         if (!has_next) break;
;     DI void operator()(AccRef acc, const Unit& u, int wr, int wc, int fr, int fq) const {
;         float* base = P + (size_t)slot0 * 256 * DM + (size_t)u.ks * 256 * ld; const int col0 = u.pn * 256 + wc * 32 + 4 * fq;
; #pragma unroll
;         for (int ai = 0; ai < 2; ++ai)
; #pragma unroll
;             for (int m = 0; m < 4; ++m) { const size_t off = (size_t)(ai * 128 + wr * 64 + m * 16 + fr) * ld + col0;
; #pragma unroll
;                 for (int bj = 0; bj < 2; ++bj)
; #pragma unroll
;                     for (int n = 0; n < 2; ++n) *(f32x4*)(base + off + bj * 128 + n * 16) = acc[ai][bj][m][n]; }
;     }
	s_waitcnt lgkmcnt(0)
	s_setprio 1
	s_waitcnt lgkmcnt(0)
	v_mfma_f32_16x16x32_bf16 v[60:63], v[132:135], v[148:151], v[60:63]
	v_mfma_f32_16x16x32_bf16 v[56:59], v[140:143], v[148:151], v[56:59]
	v_mfma_f32_16x16x32_bf16 v[52:55], v[132:135], v[156:159], v[52:55]
	v_mfma_f32_16x16x32_bf16 v[48:51], v[140:143], v[156:159], v[48:51]
	v_mfma_f32_16x16x32_bf16 v[40:43], v[132:135], v[164:167], v[40:43]
	v_mfma_f32_16x16x32_bf16 v[32:35], v[140:143], v[164:167], v[32:35]
	v_mfma_f32_16x16x32_bf16 v[24:27], v[132:135], v[176:179], v[24:27]
	v_mfma_f32_16x16x32_bf16 v[16:19], v[140:143], v[176:179], v[16:19]
	v_mfma_f32_16x16x32_bf16 v[60:63], v[136:139], v[152:155], v[60:63]
	v_mfma_f32_16x16x32_bf16 v[56:59], v[144:147], v[152:155], v[56:59]
	v_mfma_f32_16x16x32_bf16 v[52:55], v[136:139], v[160:163], v[52:55]
	v_mfma_f32_16x16x32_bf16 v[48:51], v[144:147], v[160:163], v[48:51]
	v_mfma_f32_16x16x32_bf16 v[40:43], v[136:139], v[172:175], v[40:43]
	v_mfma_f32_16x16x32_bf16 v[32:35], v[144:147], v[172:175], v[32:35]
	v_mfma_f32_16x16x32_bf16 v[24:27], v[136:139], v[180:183], v[24:27]
	v_mfma_f32_16x16x32_bf16 v[16:19], v[144:147], v[180:183], v[16:19]
	s_setprio 0
	s_barrier
	s_mov_b32 m0, s80
	s_nop 0
	global_load_lds_dwordx4 v168, s[48:49]
	s_mov_b32 m0, s79
	s_nop 0
	global_load_lds_dwordx4 v170, s[48:49]
	s_waitcnt vmcnt(6)
	s_barrier
	s_setprio 1
	v_mfma_f32_16x16x32_bf16 v[44:47], v[188:191], v[148:151], v[44:47]
	v_mfma_f32_16x16x32_bf16 v[36:39], v[210:213], v[148:151], v[36:39]
	v_mfma_f32_16x16x32_bf16 v[28:31], v[188:191], v[156:159], v[28:31]
	v_mfma_f32_16x16x32_bf16 v[20:23], v[210:213], v[156:159], v[20:23]
	v_mfma_f32_16x16x32_bf16 v[12:15], v[188:191], v[164:167], v[12:15]
	v_mfma_f32_16x16x32_bf16 v[8:11], v[210:213], v[164:167], v[8:11]
	v_mfma_f32_16x16x32_bf16 v[4:7], v[188:191], v[176:179], v[4:7]
	v_mfma_f32_16x16x32_bf16 v[0:3], v[210:213], v[176:179], v[0:3]
	v_mfma_f32_16x16x32_bf16 v[44:47], v[206:209], v[152:155], v[44:47]
	v_mfma_f32_16x16x32_bf16 v[36:39], v[214:217], v[152:155], v[36:39]
	v_mfma_f32_16x16x32_bf16 v[28:31], v[206:209], v[160:163], v[28:31]
	v_mfma_f32_16x16x32_bf16 v[20:23], v[214:217], v[160:163], v[20:23]
	v_mfma_f32_16x16x32_bf16 v[12:15], v[206:209], v[172:175], v[12:15]
	v_mfma_f32_16x16x32_bf16 v[8:11], v[214:217], v[172:175], v[8:11]
	v_mfma_f32_16x16x32_bf16 v[4:7], v[206:209], v[180:183], v[4:7]
	v_mfma_f32_16x16x32_bf16 v[0:3], v[214:217], v[180:183], v[0:3]
	s_setprio 0
	s_movk_i32 s0, 0x100
	s_andn2_b64 vcc, exec, s[46:47]
	s_mov_b64 s[48:49], -1
	s_mov_b64 s[46:47], 0
	s_barrier
	s_cbranch_vccz .LBB0_1365
	s_ashr_i32 s19, s18, 31
	s_lshl_b64 s[0:1], s[18:19], 21
	s_add_u32 s0, s8, s0
	v_mov_b32_e32 v133, v194
	v_mov_b32_e32 v132, v192
	s_addc_u32 s1, s9, s1
	s_lshl_b32 s4, s16, 8
	s_or_b32 s4, s4, s71
	v_lshl_add_u32 v132, v132, 2, s4
	v_add_u32_e32 v134, s70, v133
	v_ashrrev_i32_e32 v133, 31, v132
	v_ashrrev_i32_e32 v135, 31, v134
	v_lshl_add_u64 v[132:133], v[132:133], 2, s[0:1]
	v_lshlrev_b64 v[136:137], 13, v[134:135]
	v_lshl_add_u64 v[136:137], v[132:133], 0, v[136:137]
	global_store_dwordx4 v[136:137], v[124:127], off
	global_store_dwordx4 v[136:137], v[120:123], off offset:64
	global_store_dwordx4 v[136:137], v[108:111], off offset:512
	global_store_dwordx4 v[136:137], v[100:103], off offset:576
	s_and_b64 vcc, exec, s[40:41]
	s_mov_b32 s18, s36
	v_add_u32_e32 v100, 16, v134
	v_ashrrev_i32_e32 v101, 31, v100
	v_lshlrev_b64 v[100:101], 13, v[100:101]
	v_lshl_add_u64 v[100:101], v[132:133], 0, v[100:101]
	global_store_dwordx4 v[100:101], v[116:119], off
	global_store_dwordx4 v[100:101], v[112:115], off offset:64
	global_store_dwordx4 v[100:101], v[92:95], off offset:512
	global_store_dwordx4 v[100:101], v[84:87], off offset:576
	s_mov_b32 s16, s38
	s_mov_b64 s[28:29], s[44:45]
	v_add_u32_e32 v84, 32, v134
	v_ashrrev_i32_e32 v85, 31, v84
	v_lshlrev_b64 v[84:85], 13, v[84:85]
	v_lshl_add_u64 v[84:85], v[132:133], 0, v[84:85]
	global_store_dwordx4 v[84:85], v[104:107], off
	global_store_dwordx4 v[84:85], v[96:99], off offset:64
	global_store_dwordx4 v[84:85], v[76:79], off offset:512
	global_store_dwordx4 v[84:85], v[72:75], off offset:576
	s_mov_b64 s[30:31], s[42:43]
	s_nop 0
	v_add_u32_e32 v72, 48, v134
	v_ashrrev_i32_e32 v73, 31, v72
	v_lshlrev_b64 v[72:73], 13, v[72:73]
	v_lshl_add_u64 v[72:73], v[132:133], 0, v[72:73]
	global_store_dwordx4 v[72:73], v[88:91], off
	global_store_dwordx4 v[72:73], v[80:83], off offset:64
	global_store_dwordx4 v[72:73], v[68:71], off offset:512
	global_store_dwordx4 v[72:73], v[64:67], off offset:576
	s_nop 1
	v_add_u32_e32 v64, 0x80, v134
	v_ashrrev_i32_e32 v65, 31, v64
	v_lshlrev_b64 v[64:65], 13, v[64:65]
	v_lshl_add_u64 v[64:65], v[132:133], 0, v[64:65]
	global_store_dwordx4 v[64:65], v[60:63], off
	global_store_dwordx4 v[64:65], v[56:59], off offset:64
	global_store_dwordx4 v[64:65], v[44:47], off offset:512
	global_store_dwordx4 v[64:65], v[36:39], off offset:576
	s_nop 1
	v_add_u32_e32 v36, 0x90, v134
	v_ashrrev_i32_e32 v37, 31, v36
	v_lshlrev_b64 v[36:37], 13, v[36:37]
	v_lshl_add_u64 v[36:37], v[132:133], 0, v[36:37]
	global_store_dwordx4 v[36:37], v[52:55], off
	global_store_dwordx4 v[36:37], v[48:51], off offset:64
	global_store_dwordx4 v[36:37], v[28:31], off offset:512
	global_store_dwordx4 v[36:37], v[20:23], off offset:576
	s_nop 1
	v_add_u32_e32 v20, 0xa0, v134
	v_ashrrev_i32_e32 v21, 31, v20
	v_lshlrev_b64 v[20:21], 13, v[20:21]
	v_lshl_add_u64 v[20:21], v[132:133], 0, v[20:21]
	global_store_dwordx4 v[20:21], v[40:43], off
	global_store_dwordx4 v[20:21], v[32:35], off offset:64
	global_store_dwordx4 v[20:21], v[12:15], off offset:512
	global_store_dwordx4 v[20:21], v[8:11], off offset:576
	s_nop 1
	v_add_u32_e32 v8, 0xb0, v134
	v_ashrrev_i32_e32 v9, 31, v8
	v_lshlrev_b64 v[8:9], 13, v[8:9]
	v_lshl_add_u64 v[8:9], v[132:133], 0, v[8:9]
	global_store_dwordx4 v[8:9], v[24:27], off
	global_store_dwordx4 v[8:9], v[16:19], off offset:64
	global_store_dwordx4 v[8:9], v[4:7], off offset:512
	global_store_dwordx4 v[8:9], v[0:3], off offset:576
	s_cbranch_vccz .LBB0_1362
	s_waitcnt vmcnt(0)
	s_cmpk_gt_u32 s60, 0xff
	s_cbranch_scc1 .LBB0_1369
	s_barrier

;     DI size_t aoff(const Unit& u, size_t tstep) const { return (size_t)u.pm * tstep; }
;     DI size_t boff(const Unit& u, size_t tstep) const { return (size_t)u.pn * tstep; }
;     DI size_t aoff(const Unit& u, size_t) const { return (size_t)u.ks * kbytes; }
;     DI size_t boff(const Unit& u, size_t tstep) const { return (size_t)u.pn * tstep + (size_t)u.ks * kbytes; }
;     DI size_t aoff(const Unit& u, size_t tstep) const { return (u.ks < 2 ? offU : offOA) + (size_t)u.pm * tstep; }
; #define PG8_STAGE(bufoff, gbase, voff) do { _Pragma("unroll") for (int _i = 0; _i < 2; ++_i) \
;         __builtin_amdgcn_global_load_lds((const unsigned*)((const char*)(gbase) + (voff)[_i]), (LAS unsigned*)(lds + (bufoff) + ldsw + _i * 8192), 16, 0, 0); } while (0)
; #define PG8_WAIT_V(n) asm volatile("s_waitcnt vmcnt(" #n ")" ::: "memory")
; #define PG8_BAR __builtin_amdgcn_s_barrier()
; template <class Epi, class Sched>
; DI void gemm_phase(LAS unsigned char* lds, const Gemm g, const Sched& S, const Epi& E) {
;     ...
;     const char* cA = (const char*)g.A + S.aoff(cur, tstep); const char* cB = (const char*)g.Bt + S.boff(cur, tstep);
;     PG8_STAGE(PG8_SB(0, 0), cB, voffB); PG8_STAGE(PG8_SA(0, 0), cA, voffA); PG8_STAGE(PG8_SB(0, 1), cB + hstep, voffB); PG8_STAGE(PG8_SA(0, 1), cA + hstep, voffA);
;     if (wr == 1) PG8_BAR;
;     PG8_WAIT_V(4); PG8_BAR;
;     PG8_STAGE(PG8_SB(1, 0), cB + kstep, voffB); PG8_STAGE(PG8_SA(1, 0), cA + kstep, voffA); PG8_STAGE(PG8_SB(1, 1), cB + hstep + kstep, voffB);
;     PG8_WAIT_V(6); PG8_BAR;
;     const int kc = K / S; pg8::Gemm g{A, Bt, K, kc / 64}; pg8::SplitOrder O; O.init(N, S, kc, 128, (int)gridDim.x, (int)((blockIdx.x + rot) % gridDim.x));
;     pg8::gemm_phase<Epi, pg8::SplitOrder>(lds, g, O, E);
.LBB0_1370:
	s_add_i32 s0, s2, 0x80
	s_mul_hi_u32 s1, s0, s34
	s_add_u32 s18, s22, 0x3d40b000
	s_mul_i32 s1, s1, s26
	s_addc_u32 s19, s23, 0
	s_sub_i32 s0, s0, s1
	s_sub_i32 s1, s0, s26
	s_cmp_ge_u32 s0, s26
	s_cselect_b32 s0, s1, s0
	s_sub_i32 s1, s0, s26
	s_cmp_ge_u32 s0, s26
	s_cselect_b32 s34, s1, s0
	s_cmpk_gt_i32 s34, 0x7f
	v_readfirstlane_b32 s35, v184
	s_cbranch_scc1 .LBB0_1382
	s_lshr_b32 s0, s35, 6
	s_lshr_b32 s1, s35, 8
	s_lshl_b32 s62, s0, 10
	s_add_u32 s63, s22, 0x106c3000
	s_addc_u32 s64, s23, 0
	s_add_u32 s65, s22, 0x5983000
	s_addc_u32 s66, s23, 0
	s_ashr_i32 s67, s34, 31
	s_lshr_b32 s4, s67, 28
	s_add_i32 s4, s34, s4
	s_ashr_i32 s30, s4, 4
	s_and_b32 s4, s4, -16
	s_sub_i32 s28, s34, s4
	s_ashr_i32 s29, s28, 31
	s_ashr_i32 s31, s30, 31
	s_lshl_b64 s[4:5], s[30:31], 9
	s_lshl_b64 s[6:7], s[28:29], 20
	s_add_u32 s6, s65, s6
	s_addc_u32 s7, s66, s7
	s_add_u32 s36, s6, s4
	s_addc_u32 s37, s7, s5
	s_add_i32 s29, s62, 0
	s_add_i32 m0, s29, 0x10000
	v_lshl_add_u64 v[0:1], s[36:37], 0, v[168:169]
	global_load_lds_dwordx4 v168, s[36:37]
	s_add_i32 m0, s29, 0x12000
	s_add_u32 s38, s63, s4
	v_lshl_add_u64 v[2:3], s[36:37], 0, v[170:171]
	s_addc_u32 s39, s64, s5
	s_add_i32 s68, s29, 0x2000
	global_load_lds_dwordx4 v170, s[36:37]
	v_lshl_add_u64 v[6:7], s[38:39], 0, v[168:169]
	s_mov_b32 m0, s29
	s_add_u32 s4, s36, 0x80000
	global_load_lds_dwordx4 v168, s[38:39]
	v_lshl_add_u64 v[4:5], s[38:39], 0, v[170:171]
	s_mov_b32 m0, s68
	s_addc_u32 s5, s37, 0
	global_load_lds_dwordx4 v170, s[38:39]
	s_add_i32 m0, s29, 0x14000
	s_nop 0
	global_load_lds_dwordx4 v168, s[4:5]
	s_add_i32 m0, s29, 0x16000
	v_lshl_add_u64 v[8:9], s[4:5], 0, v[170:171]
	s_add_u32 s4, s38, 0x80000
	s_addc_u32 s5, s39, 0
	s_add_i32 s69, s29, 0x4000
	global_load_lds_dwordx4 v[8:9], off
	s_mov_b32 m0, s69
	s_add_i32 s70, s29, 0x6000
	global_load_lds_dwordx4 v168, s[4:5]
	s_mov_b32 m0, s70
	s_cmp_lg_u32 s1, 1
	global_load_lds_dwordx4 v170, s[4:5]
	s_mov_b32 s71, 0
	s_cbranch_scc1 .LBB0_1373
	s_barrier
.LBB0_1373:
	s_mov_b64 s[16:17], 0x80
	s_lshl_b32 s0, s0, 5
	s_add_i32 m0, s29, 0x18000
	v_lshl_add_u64 v[0:1], v[0:1], 0, s[16:17]
	s_lshl_b32 s72, s1, 6
	s_lshl_b32 s4, s1, 13
	s_and_b32 s73, s0, 0x60
	s_waitcnt vmcnt(4)
	s_barrier
	global_load_lds_dwordx4 v[0:1], off
	v_lshl_add_u64 v[0:1], v[2:3], 0, s[16:17]
	s_add_i32 m0, s29, 0x1a000
	s_add_i32 s74, s29, 0x8000
	s_add_i32 s75, s29, 0xa000
	global_load_lds_dwordx4 v[0:1], off
	v_lshl_add_u64 v[0:1], v[6:7], 0, s[16:17]
	s_mov_b32 m0, s74
	s_add_u32 s0, s36, 0x80080
	global_load_lds_dwordx4 v[0:1], off
	v_lshl_add_u64 v[0:1], v[4:5], 0, s[16:17]
	s_mov_b32 m0, s75
	s_addc_u32 s1, s37, 0
	global_load_lds_dwordx4 v[0:1], off
	s_add_i32 m0, s29, 0x1c000
	s_nop 0
	global_load_lds_dwordx4 v168, s[0:1]
	s_add_i32 m0, s29, 0x1e000
	v_lshl_or_b32 v132, s73, 7, v201
	global_load_lds_dwordx4 v170, s[0:1]
	v_lshlrev_b32_e32 v1, 2, v194
	v_lshl_or_b32 v0, v194, 6, v195
	v_and_b32_e32 v1, 32, v1
	s_waitcnt vmcnt(6)
	s_add_i32 s79, 0, 0x10000
	v_bitop3_b32 v0, v0, s4, v1 bitop3:0xde
	s_add_i32 s76, 0, 0x14000
	v_add_u32_e32 v133, s79, v132
	s_add_i32 s79, s79, s62
	v_mov_b64_e32 v[128:129], 0x80
	v_mov_b64_e32 v[130:131], 0x7f
	v_add_u32_e32 v134, 0, v0
	v_add_u32_e32 v135, s76, v132
	s_add_i32 s77, s29, 0xc000
	s_add_i32 s78, s29, 0xe000
	s_add_i32 s80, s79, 0x2000
	s_barrier

; #define PG8_STAGE(bufoff, gbase, voff) do { _Pragma("unroll") for (int _i = 0; _i < 2; ++_i) \
;         __builtin_amdgcn_global_load_lds((const unsigned*)((const char*)(gbase) + (voff)[_i]), (LAS unsigned*)(lds + (bufoff) + ldsw + _i * 8192), 16, 0, 0); } while (0)
; #define PG8_LDA(dst, b, h) do { _Pragma("unroll") for (int m = 0; m < 4; ++m) _Pragma("unroll") for (int k = 0; k < 2; ++k) dst[m][k] = *(const LAS bf16x8*)(lds + PG8_SA(b, h) + aoff + m * 2048 + k * 1024); } while (0)
; #define PG8_LDB(dst, b, h) do { _Pragma("unroll") for (int n = 0; n < 2; ++n) _Pragma("unroll") for (int k = 0; k < 2; ++k) dst[n][k] = *(const LAS bf16x8*)(lds + PG8_SB(b, h) + boff + n * 2048 + k * 1024); } while (0)
; #define PG8_MMA(ai, bj, At, Bt) do { __builtin_amdgcn_s_setprio(1); _Pragma("unroll") for (int m = 0; m < 4; ++m) _Pragma("unroll") for (int n = 0; n < 2; ++n) _Pragma("unroll") for (int k = 0; k < 2; ++k) \
;         acc[ai][bj][m][n] = __builtin_amdgcn_mfma_f32_16x16x32_bf16(Bt[n][k], At[m][k], acc[ai][bj][m][n], 0, 0, 0); __builtin_amdgcn_s_setprio(0); } while (0)
; #define PG8_WAIT_V(n) asm volatile("s_waitcnt vmcnt(" #n ")" ::: "memory")
; #define PG8_WAIT_L(n) asm volatile("s_waitcnt lgkmcnt(" #n ")" ::: "memory")
; #define PG8_BAR __builtin_amdgcn_s_barrier()
; #define PG8_SCHED __builtin_amdgcn_sched_barrier(0)
; template <class Epi, class Sched>
; DI void gemm_phase(LAS unsigned char* lds, const Gemm g, const Sched& S, const Epi& E) {
;     ...
;             PG8_LDB(B0, 0, 0); PG8_SCHED; PG8_LDA(At, 0, 0); PG8_STAGE(PG8_SA(1, 1), a1 + hstep, voffA);
;             PG8_WAIT_L(8); PG8_BAR; PG8_WAIT_L(0); PG8_MMA(0, 0, At, B0); PG8_BAR; PG8_SCHED;
;             PG8_LDB(B1, 0, 1); PG8_STAGE(PG8_SB(0, 0), b2, voffB);
;             PG8_BAR; PG8_WAIT_L(0); PG8_MMA(0, 1, At, B1); PG8_BAR;
;             PG8_LDA(At, 0, 1); PG8_STAGE(PG8_SA(0, 0), a2, voffA);
;             PG8_BAR; PG8_WAIT_L(0); PG8_MMA(1, 0, At, B0); PG8_BAR; PG8_SCHED;
;             PG8_STAGE(PG8_SB(0, 1), b2 + hstep, voffB);
;             PG8_WAIT_V(6); PG8_BAR; PG8_MMA(1, 1, At, B1); PG8_BAR;
;             PG8_LDB(B0, 1, 0); PG8_SCHED; PG8_LDA(At, 1, 0); PG8_STAGE(PG8_SA(0, 1), a2 + hstep, voffA);
;             PG8_WAIT_L(8); PG8_BAR; PG8_WAIT_L(0); PG8_MMA(0, 0, At, B0); PG8_BAR; PG8_SCHED;
.LBB0_1377:
	s_add_u32 s33, s38, s0
	s_addc_u32 s43, s39, 0
	s_add_u32 s1, s33, 0x100
	s_addc_u32 s52, s43, 0
	s_and_b64 s[4:5], s[50:51], exec
	s_cselect_b32 s57, s31, s52
	s_cselect_b32 s56, s41, s1
	s_add_u32 s0, s36, s0
	s_addc_u32 s1, s37, 0
	s_add_u32 s4, s0, 0x100
	s_addc_u32 s5, s1, 0
	s_and_b64 s[0:1], s[50:51], exec
	s_cselect_b32 s59, s47, s5
	s_cselect_b32 s58, s46, s4
	s_add_u32 s60, s33, 0x80080
	s_addc_u32 s61, s43, 0
	s_add_u32 s54, s58, 0x80000
	s_addc_u32 s55, s59, 0
	s_add_i32 s43, s76, s62
	ds_read_b128 v[136:139], v133
	ds_read_b128 v[140:143], v133 offset:1024
	ds_read_b128 v[144:147], v133 offset:2048
	ds_read_b128 v[148:151], v133 offset:3072
	s_add_i32 s33, s43, 0x2000
	s_add_i32 s5, 0, 0x18000
	s_add_u32 s52, s56, 0x80000
	s_addc_u32 s53, s57, 0
	s_add_i32 s4, s5, s62
	s_add_i32 s1, 0, 0x1c000
	s_add_i32 s0, s4, 0x2000
	s_add_u32 s50, s58, 0x80080
	s_addc_u32 s51, s59, 0
	s_add_i32 s82, s1, s62
	s_add_i32 s81, s82, 0x2000
	s_mov_b32 m0, s77
	ds_read_b128 v[152:155], v134
	ds_read_b128 v[156:159], v134 offset:1024
	ds_read_b128 v[160:163], v134 offset:2048
	ds_read_b128 v[164:167], v134 offset:3072
	ds_read_b128 v[172:175], v134 offset:4096
	ds_read_b128 v[176:179], v134 offset:5120
	ds_read_b128 v[180:183], v134 offset:6144
	ds_read_b128 v[188:191], v134 offset:7168
	global_load_lds_dwordx4 v168, s[60:61]
	s_mov_b32 m0, s78
	s_nop 0
	global_load_lds_dwordx4 v170, s[60:61]
	s_waitcnt lgkmcnt(8)
	s_barrier
	s_waitcnt lgkmcnt(0)
	s_setprio 1
	s_waitcnt lgkmcnt(0)
	v_mfma_f32_16x16x32_bf16 v[124:127], v[136:139], v[152:155], v[124:127]
	v_mfma_f32_16x16x32_bf16 v[120:123], v[144:147], v[152:155], v[120:123]
	v_mfma_f32_16x16x32_bf16 v[116:119], v[136:139], v[160:163], v[116:119]
	v_mfma_f32_16x16x32_bf16 v[112:115], v[144:147], v[160:163], v[112:115]
	v_mfma_f32_16x16x32_bf16 v[104:107], v[136:139], v[172:175], v[104:107]
	v_mfma_f32_16x16x32_bf16 v[96:99], v[144:147], v[172:175], v[96:99]
	v_mfma_f32_16x16x32_bf16 v[88:91], v[136:139], v[180:183], v[88:91]
	v_mfma_f32_16x16x32_bf16 v[80:83], v[144:147], v[180:183], v[80:83]
	v_mfma_f32_16x16x32_bf16 v[124:127], v[140:143], v[156:159], v[124:127]
	v_mfma_f32_16x16x32_bf16 v[120:123], v[148:151], v[156:159], v[120:123]
	v_mfma_f32_16x16x32_bf16 v[116:119], v[140:143], v[164:167], v[116:119]
	v_mfma_f32_16x16x32_bf16 v[112:115], v[148:151], v[164:167], v[112:115]
	v_mfma_f32_16x16x32_bf16 v[104:107], v[140:143], v[176:179], v[104:107]
	v_mfma_f32_16x16x32_bf16 v[96:99], v[148:151], v[176:179], v[96:99]
	v_mfma_f32_16x16x32_bf16 v[88:91], v[140:143], v[188:191], v[88:91]
	v_mfma_f32_16x16x32_bf16 v[80:83], v[148:151], v[188:191], v[80:83]
	s_setprio 0
	s_barrier
	s_mov_b32 m0, s79
	ds_read_b128 v[206:209], v135
	ds_read_b128 v[210:213], v135 offset:1024
	ds_read_b128 v[214:217], v135 offset:2048
	ds_read_b128 v[218:221], v135 offset:3072
	global_load_lds_dwordx4 v168, s[58:59]
	s_mov_b32 m0, s80
	s_nop 0
	global_load_lds_dwordx4 v170, s[58:59]
	s_barrier
	s_waitcnt lgkmcnt(0)
	s_setprio 1
	s_waitcnt lgkmcnt(0)
	v_mfma_f32_16x16x32_bf16 v[108:111], v[206:209], v[152:155], v[108:111]
	v_mfma_f32_16x16x32_bf16 v[100:103], v[214:217], v[152:155], v[100:103]
	v_mfma_f32_16x16x32_bf16 v[92:95], v[206:209], v[160:163], v[92:95]
	v_mfma_f32_16x16x32_bf16 v[84:87], v[214:217], v[160:163], v[84:87]
	v_mfma_f32_16x16x32_bf16 v[76:79], v[206:209], v[172:175], v[76:79]
	v_mfma_f32_16x16x32_bf16 v[72:75], v[214:217], v[172:175], v[72:75]
	v_mfma_f32_16x16x32_bf16 v[68:71], v[206:209], v[180:183], v[68:71]
	v_mfma_f32_16x16x32_bf16 v[64:67], v[214:217], v[180:183], v[64:67]
	v_mfma_f32_16x16x32_bf16 v[108:111], v[210:213], v[156:159], v[108:111]
	v_mfma_f32_16x16x32_bf16 v[100:103], v[218:221], v[156:159], v[100:103]
	v_mfma_f32_16x16x32_bf16 v[92:95], v[210:213], v[164:167], v[92:95]
	v_mfma_f32_16x16x32_bf16 v[84:87], v[218:221], v[164:167], v[84:87]
	v_mfma_f32_16x16x32_bf16 v[76:79], v[210:213], v[176:179], v[76:79]
	v_mfma_f32_16x16x32_bf16 v[72:75], v[218:221], v[176:179], v[72:75]
	v_mfma_f32_16x16x32_bf16 v[68:71], v[210:213], v[188:191], v[68:71]
	v_mfma_f32_16x16x32_bf16 v[64:67], v[218:221], v[188:191], v[64:67]
	s_setprio 0
	s_mov_b32 m0, s29
	s_barrier
	ds_read_b128 v[152:155], v134 offset:16384
	ds_read_b128 v[156:159], v134 offset:17408
	ds_read_b128 v[160:163], v134 offset:18432
	ds_read_b128 v[164:167], v134 offset:19456
	ds_read_b128 v[172:175], v134 offset:20480
	ds_read_b128 v[176:179], v134 offset:21504
	ds_read_b128 v[180:183], v134 offset:22528
	ds_read_b128 v[188:191], v134 offset:23552
	global_load_lds_dwordx4 v168, s[56:57]
	s_mov_b32 m0, s68
	s_nop 0
	global_load_lds_dwordx4 v170, s[56:57]
	s_barrier
	s_waitcnt lgkmcnt(0)
	s_setprio 1
	s_waitcnt lgkmcnt(0)
	v_mfma_f32_16x16x32_bf16 v[60:63], v[136:139], v[152:155], v[60:63]
	v_mfma_f32_16x16x32_bf16 v[56:59], v[144:147], v[152:155], v[56:59]
	v_mfma_f32_16x16x32_bf16 v[52:55], v[136:139], v[160:163], v[52:55]
	v_mfma_f32_16x16x32_bf16 v[48:51], v[144:147], v[160:163], v[48:51]
	v_mfma_f32_16x16x32_bf16 v[40:43], v[136:139], v[172:175], v[40:43]
	v_mfma_f32_16x16x32_bf16 v[32:35], v[144:147], v[172:175], v[32:35]
	v_mfma_f32_16x16x32_bf16 v[24:27], v[136:139], v[180:183], v[24:27]
	v_mfma_f32_16x16x32_bf16 v[16:19], v[144:147], v[180:183], v[16:19]
	v_mfma_f32_16x16x32_bf16 v[60:63], v[140:143], v[156:159], v[60:63]
	v_mfma_f32_16x16x32_bf16 v[56:59], v[148:151], v[156:159], v[56:59]
	v_mfma_f32_16x16x32_bf16 v[52:55], v[140:143], v[164:167], v[52:55]
	v_mfma_f32_16x16x32_bf16 v[48:51], v[148:151], v[164:167], v[48:51]
	v_mfma_f32_16x16x32_bf16 v[40:43], v[140:143], v[176:179], v[40:43]
	v_mfma_f32_16x16x32_bf16 v[32:35], v[148:151], v[176:179], v[32:35]
	v_mfma_f32_16x16x32_bf16 v[24:27], v[140:143], v[188:191], v[24:27]
	v_mfma_f32_16x16x32_bf16 v[16:19], v[148:151], v[188:191], v[16:19]
	s_setprio 0
	s_barrier
; #define PG8_STAGE(bufoff, gbase, voff) do { _Pragma("unroll") for (int _i = 0; _i < 2; ++_i) \
;         __builtin_amdgcn_global_load_lds((const unsigned*)((const char*)(gbase) + (voff)[_i]), (LAS unsigned*)(lds + (bufoff) + ldsw + _i * 8192), 16, 0, 0); } while (0)
; #define PG8_LDA(dst, b, h) do { _Pragma("unroll") for (int m = 0; m < 4; ++m) _Pragma("unroll") for (int k = 0; k < 2; ++k) dst[m][k] = *(const LAS bf16x8*)(lds + PG8_SA(b, h) + aoff + m * 2048 + k * 1024); } while (0)
; #define PG8_LDB(dst, b, h) do { _Pragma("unroll") for (int n = 0; n < 2; ++n) _Pragma("unroll") for (int k = 0; k < 2; ++k) dst[n][k] = *(const LAS bf16x8*)(lds + PG8_SB(b, h) + boff + n * 2048 + k * 1024); } while (0)
; #define PG8_MMA(ai, bj, At, Bt) do { __builtin_amdgcn_s_setprio(1); _Pragma("unroll") for (int m = 0; m < 4; ++m) _Pragma("unroll") for (int n = 0; n < 2; ++n) _Pragma("unroll") for (int k = 0; k < 2; ++k) \
;         acc[ai][bj][m][n] = __builtin_amdgcn_mfma_f32_16x16x32_bf16(Bt[n][k], At[m][k], acc[ai][bj][m][n], 0, 0, 0); __builtin_amdgcn_s_setprio(0); } while (0)
; #define PG8_WAIT_V(n) asm volatile("s_waitcnt vmcnt(" #n ")" ::: "memory")
; #define PG8_WAIT_L(n) asm volatile("s_waitcnt lgkmcnt(" #n ")" ::: "memory")
; #define PG8_BAR __builtin_amdgcn_s_barrier()
; #define PG8_SCHED __builtin_amdgcn_sched_barrier(0)
; template <class Epi, class Sched>
; DI void gemm_phase(LAS unsigned char* lds, const Gemm g, const Sched& S, const Epi& E) {
;     ...
;             PG8_STAGE(PG8_SB(0, 1), b2 + hstep, voffB);
;             PG8_WAIT_V(6); PG8_BAR; PG8_MMA(1, 1, At, B1); PG8_BAR;
;             PG8_LDB(B0, 1, 0); PG8_SCHED; PG8_LDA(At, 1, 0); PG8_STAGE(PG8_SA(0, 1), a2 + hstep, voffA);
;             PG8_WAIT_L(8); PG8_BAR; PG8_WAIT_L(0); PG8_MMA(0, 0, At, B0); PG8_BAR; PG8_SCHED;
;             PG8_LDB(B1, 1, 1); PG8_STAGE(PG8_SB(1, 0), b3, voffB);
;             PG8_BAR; PG8_WAIT_L(0); PG8_MMA(0, 1, At, B1); PG8_BAR;
;             PG8_LDA(At, 1, 1); PG8_STAGE(PG8_SA(1, 0), a3, voffA);
;             PG8_BAR; PG8_WAIT_L(0); PG8_MMA(1, 0, At, B0); PG8_BAR; PG8_SCHED;
	s_mov_b32 m0, s43
	s_nop 0
	global_load_lds_dwordx4 v168, s[54:55]
	s_mov_b32 m0, s33
	s_nop 0
	global_load_lds_dwordx4 v170, s[54:55]
	s_waitcnt vmcnt(6)
	s_barrier
	s_setprio 1
	v_mfma_f32_16x16x32_bf16 v[44:47], v[206:209], v[152:155], v[44:47]
	v_mfma_f32_16x16x32_bf16 v[36:39], v[214:217], v[152:155], v[36:39]
	v_mfma_f32_16x16x32_bf16 v[28:31], v[206:209], v[160:163], v[28:31]
	v_mfma_f32_16x16x32_bf16 v[20:23], v[214:217], v[160:163], v[20:23]
	v_mfma_f32_16x16x32_bf16 v[12:15], v[206:209], v[172:175], v[12:15]
	v_mfma_f32_16x16x32_bf16 v[8:11], v[214:217], v[172:175], v[8:11]
	v_mfma_f32_16x16x32_bf16 v[4:7], v[206:209], v[180:183], v[4:7]
	v_mfma_f32_16x16x32_bf16 v[0:3], v[214:217], v[180:183], v[0:3]
	v_mfma_f32_16x16x32_bf16 v[44:47], v[210:213], v[156:159], v[44:47]
	v_mfma_f32_16x16x32_bf16 v[36:39], v[218:221], v[156:159], v[36:39]
	v_mfma_f32_16x16x32_bf16 v[28:31], v[210:213], v[164:167], v[28:31]
	v_mfma_f32_16x16x32_bf16 v[20:23], v[218:221], v[164:167], v[20:23]
	v_mfma_f32_16x16x32_bf16 v[12:15], v[210:213], v[176:179], v[12:15]
	v_mfma_f32_16x16x32_bf16 v[8:11], v[218:221], v[176:179], v[8:11]
	v_mfma_f32_16x16x32_bf16 v[4:7], v[210:213], v[188:191], v[4:7]
	v_mfma_f32_16x16x32_bf16 v[0:3], v[218:221], v[188:191], v[0:3]
	s_setprio 0
	v_add_u32_e32 v148, s5, v132
	s_barrier
	ds_read_b128 v[136:139], v148
	ds_read_b128 v[140:143], v148 offset:1024
	ds_read_b128 v[144:147], v148 offset:2048
	ds_read_b128 v[148:151], v148 offset:3072
	s_mov_b32 m0, s69
	ds_read_b128 v[152:155], v134 offset:32768
	ds_read_b128 v[156:159], v134 offset:33792
	ds_read_b128 v[160:163], v134 offset:34816
	ds_read_b128 v[164:167], v134 offset:35840
	ds_read_b128 v[172:175], v134 offset:36864
	ds_read_b128 v[176:179], v134 offset:37888
	ds_read_b128 v[180:183], v134 offset:38912
	ds_read_b128 v[188:191], v134 offset:39936
	global_load_lds_dwordx4 v168, s[52:53]
	s_mov_b32 m0, s70
	s_nop 0
	global_load_lds_dwordx4 v170, s[52:53]
	s_waitcnt lgkmcnt(8)
	s_barrier
	s_waitcnt lgkmcnt(0)
	s_setprio 1
	s_waitcnt lgkmcnt(0)
	v_mfma_f32_16x16x32_bf16 v[124:127], v[136:139], v[152:155], v[124:127]
	v_mfma_f32_16x16x32_bf16 v[120:123], v[144:147], v[152:155], v[120:123]
	v_mfma_f32_16x16x32_bf16 v[116:119], v[136:139], v[160:163], v[116:119]
	v_mfma_f32_16x16x32_bf16 v[112:115], v[144:147], v[160:163], v[112:115]
	v_mfma_f32_16x16x32_bf16 v[104:107], v[136:139], v[172:175], v[104:107]
	v_mfma_f32_16x16x32_bf16 v[96:99], v[144:147], v[172:175], v[96:99]
	v_mfma_f32_16x16x32_bf16 v[88:91], v[136:139], v[180:183], v[88:91]
	v_mfma_f32_16x16x32_bf16 v[80:83], v[144:147], v[180:183], v[80:83]
	v_mfma_f32_16x16x32_bf16 v[124:127], v[140:143], v[156:159], v[124:127]
	v_mfma_f32_16x16x32_bf16 v[120:123], v[148:151], v[156:159], v[120:123]
	v_mfma_f32_16x16x32_bf16 v[116:119], v[140:143], v[164:167], v[116:119]
	v_mfma_f32_16x16x32_bf16 v[112:115], v[148:151], v[164:167], v[112:115]
	v_mfma_f32_16x16x32_bf16 v[104:107], v[140:143], v[176:179], v[104:107]
	v_mfma_f32_16x16x32_bf16 v[96:99], v[148:151], v[176:179], v[96:99]
	v_mfma_f32_16x16x32_bf16 v[88:91], v[140:143], v[188:191], v[88:91]
	v_mfma_f32_16x16x32_bf16 v[80:83], v[148:151], v[188:191], v[80:83]
	s_setprio 0
	s_barrier
	s_add_i32 m0, s4, 0xffffff80
	v_add_u32_e32 v201, s1, v132
	ds_read_b128 v[206:209], v201
	ds_read_b128 v[210:213], v201 offset:1024
	ds_read_b128 v[214:217], v201 offset:2048
	ds_read_b128 v[218:221], v201 offset:3072
	global_load_lds_dwordx4 v168, s[58:59] offset:128
	s_add_i32 m0, s0, 0xffffff80
	s_nop 0
	global_load_lds_dwordx4 v170, s[58:59] offset:128
	s_barrier
	s_waitcnt lgkmcnt(0)
	s_setprio 1
	s_waitcnt lgkmcnt(0)
	v_mfma_f32_16x16x32_bf16 v[108:111], v[206:209], v[152:155], v[108:111]
	v_mfma_f32_16x16x32_bf16 v[100:103], v[214:217], v[152:155], v[100:103]
	v_mfma_f32_16x16x32_bf16 v[92:95], v[206:209], v[160:163], v[92:95]
	v_mfma_f32_16x16x32_bf16 v[84:87], v[214:217], v[160:163], v[84:87]
	v_mfma_f32_16x16x32_bf16 v[76:79], v[206:209], v[172:175], v[76:79]
	v_mfma_f32_16x16x32_bf16 v[72:75], v[214:217], v[172:175], v[72:75]
	v_mfma_f32_16x16x32_bf16 v[68:71], v[206:209], v[180:183], v[68:71]
	v_mfma_f32_16x16x32_bf16 v[64:67], v[214:217], v[180:183], v[64:67]
	v_mfma_f32_16x16x32_bf16 v[108:111], v[210:213], v[156:159], v[108:111]
	v_mfma_f32_16x16x32_bf16 v[100:103], v[218:221], v[156:159], v[100:103]
	v_mfma_f32_16x16x32_bf16 v[92:95], v[210:213], v[164:167], v[92:95]
	v_mfma_f32_16x16x32_bf16 v[84:87], v[218:221], v[164:167], v[84:87]
	v_mfma_f32_16x16x32_bf16 v[76:79], v[210:213], v[176:179], v[76:79]
	v_mfma_f32_16x16x32_bf16 v[72:75], v[218:221], v[176:179], v[72:75]
	v_mfma_f32_16x16x32_bf16 v[68:71], v[210:213], v[188:191], v[68:71]
	v_mfma_f32_16x16x32_bf16 v[64:67], v[218:221], v[188:191], v[64:67]
	s_setprio 0
	s_add_i32 m0, s74, 0xffffff80
	s_barrier
	ds_read_b128 v[152:155], v134 offset:49152
	ds_read_b128 v[156:159], v134 offset:50176
	ds_read_b128 v[160:163], v134 offset:51200
	ds_read_b128 v[164:167], v134 offset:52224
	ds_read_b128 v[172:175], v134 offset:53248
	ds_read_b128 v[176:179], v134 offset:54272
	ds_read_b128 v[180:183], v134 offset:55296
	ds_read_b128 v[188:191], v134 offset:56320
	global_load_lds_dwordx4 v168, s[56:57] offset:128
	s_add_i32 m0, s75, 0xffffff80
	s_nop 0
	global_load_lds_dwordx4 v170, s[56:57] offset:128
	s_barrier
; #define PG8_STAGE(bufoff, gbase, voff) do { _Pragma("unroll") for (int _i = 0; _i < 2; ++_i) \
;         __builtin_amdgcn_global_load_lds((const unsigned*)((const char*)(gbase) + (voff)[_i]), (LAS unsigned*)(lds + (bufoff) + ldsw + _i * 8192), 16, 0, 0); } while (0)
; #define PG8_MMA(ai, bj, At, Bt) do { __builtin_amdgcn_s_setprio(1); _Pragma("unroll") for (int m = 0; m < 4; ++m) _Pragma("unroll") for (int n = 0; n < 2; ++n) _Pragma("unroll") for (int k = 0; k < 2; ++k) \
;         acc[ai][bj][m][n] = __builtin_amdgcn_mfma_f32_16x16x32_bf16(Bt[n][k], At[m][k], acc[ai][bj][m][n], 0, 0, 0); __builtin_amdgcn_s_setprio(0); } while (0)
; #define PG8_WAIT_V(n) asm volatile("s_waitcnt vmcnt(" #n ")" ::: "memory")
; #define PG8_BAR __builtin_amdgcn_s_barrier()
; template <class Epi, class Sched>
; DI void gemm_phase(LAS unsigned char* lds, const Gemm g, const Sched& S, const Epi& E) {
;     ...
;             PG8_STAGE(PG8_SB(1, 1), b3 + hstep, voffB);
;             PG8_WAIT_V(6); PG8_BAR; PG8_MMA(1, 1, At, B1); PG8_BAR;
;         }
;         { int fr2 = fr, fq2 = fq; asm volatile("" : "+v"(fr2), "+v"(fq2)); E(acc, cur, wr, wc, fr2, fq2); }
;         if (!has_next) break;
;     DI void operator()(AccRef acc, const Unit& u, int wr, int wc, int fr, int fq) const {
;         float* base = P + (size_t)slot0 * 256 * DM + (size_t)u.ks * 256 * ld; const int col0 = u.pn * 256 + wc * 32 + 4 * fq;
; #pragma unroll
;         for (int ai = 0; ai < 2; ++ai)
; #pragma unroll
;             for (int m = 0; m < 4; ++m) { const size_t off = (size_t)(ai * 128 + wr * 64 + m * 16 + fr) * ld + col0;
; #pragma unroll
;                 for (int bj = 0; bj < 2; ++bj)
; #pragma unroll
;                     for (int n = 0; n < 2; ++n) *(f32x4*)(base + off + bj * 128 + n * 16) = acc[ai][bj][m][n]; }
;     }
	s_waitcnt lgkmcnt(0)
	s_setprio 1
	s_waitcnt lgkmcnt(0)
	v_mfma_f32_16x16x32_bf16 v[60:63], v[136:139], v[152:155], v[60:63]
	v_mfma_f32_16x16x32_bf16 v[56:59], v[144:147], v[152:155], v[56:59]
	v_mfma_f32_16x16x32_bf16 v[52:55], v[136:139], v[160:163], v[52:55]
	v_mfma_f32_16x16x32_bf16 v[48:51], v[144:147], v[160:163], v[48:51]
	v_mfma_f32_16x16x32_bf16 v[40:43], v[136:139], v[172:175], v[40:43]
	v_mfma_f32_16x16x32_bf16 v[32:35], v[144:147], v[172:175], v[32:35]
	v_mfma_f32_16x16x32_bf16 v[24:27], v[136:139], v[180:183], v[24:27]
	v_mfma_f32_16x16x32_bf16 v[16:19], v[144:147], v[180:183], v[16:19]
	v_mfma_f32_16x16x32_bf16 v[60:63], v[140:143], v[156:159], v[60:63]
	v_mfma_f32_16x16x32_bf16 v[56:59], v[148:151], v[156:159], v[56:59]
	v_mfma_f32_16x16x32_bf16 v[52:55], v[140:143], v[164:167], v[52:55]
	v_mfma_f32_16x16x32_bf16 v[48:51], v[148:151], v[164:167], v[48:51]
	v_mfma_f32_16x16x32_bf16 v[40:43], v[140:143], v[176:179], v[40:43]
	v_mfma_f32_16x16x32_bf16 v[32:35], v[148:151], v[176:179], v[32:35]
	v_mfma_f32_16x16x32_bf16 v[24:27], v[140:143], v[188:191], v[24:27]
	v_mfma_f32_16x16x32_bf16 v[16:19], v[148:151], v[188:191], v[16:19]
	s_setprio 0
	s_barrier
	s_mov_b32 m0, s82
	s_nop 0
	global_load_lds_dwordx4 v168, s[50:51]
	s_mov_b32 m0, s81
	s_nop 0
	global_load_lds_dwordx4 v170, s[50:51]
	s_waitcnt vmcnt(6)
	s_barrier
	s_setprio 1
	v_mfma_f32_16x16x32_bf16 v[44:47], v[206:209], v[152:155], v[44:47]
	v_mfma_f32_16x16x32_bf16 v[36:39], v[214:217], v[152:155], v[36:39]
	v_mfma_f32_16x16x32_bf16 v[28:31], v[206:209], v[160:163], v[28:31]
	v_mfma_f32_16x16x32_bf16 v[20:23], v[214:217], v[160:163], v[20:23]
	v_mfma_f32_16x16x32_bf16 v[12:15], v[206:209], v[172:175], v[12:15]
	v_mfma_f32_16x16x32_bf16 v[8:11], v[214:217], v[172:175], v[8:11]
	v_mfma_f32_16x16x32_bf16 v[4:7], v[206:209], v[180:183], v[4:7]
	v_mfma_f32_16x16x32_bf16 v[0:3], v[214:217], v[180:183], v[0:3]
	v_mfma_f32_16x16x32_bf16 v[44:47], v[210:213], v[156:159], v[44:47]
	v_mfma_f32_16x16x32_bf16 v[36:39], v[218:221], v[156:159], v[36:39]
	v_mfma_f32_16x16x32_bf16 v[28:31], v[210:213], v[164:167], v[28:31]
	v_mfma_f32_16x16x32_bf16 v[20:23], v[218:221], v[164:167], v[20:23]
	v_mfma_f32_16x16x32_bf16 v[12:15], v[210:213], v[176:179], v[12:15]
	v_mfma_f32_16x16x32_bf16 v[8:11], v[218:221], v[176:179], v[8:11]
	v_mfma_f32_16x16x32_bf16 v[4:7], v[210:213], v[188:191], v[4:7]
	v_mfma_f32_16x16x32_bf16 v[0:3], v[218:221], v[188:191], v[0:3]
	s_setprio 0
	s_movk_i32 s0, 0x100
	s_andn2_b64 vcc, exec, s[48:49]
	s_mov_b64 s[50:51], -1
	s_mov_b64 s[48:49], 0
	s_barrier
	s_cbranch_vccz .LBB0_1377
	s_ashr_i32 s31, s30, 31
	s_lshl_b64 s[0:1], s[30:31], 22
	s_add_u32 s0, s18, s0
	v_mov_b32_e32 v137, v194
	v_mov_b32_e32 v136, v192
	s_addc_u32 s1, s19, s1
	s_lshl_b32 s4, s28, 8
	s_or_b32 s4, s4, s73
	v_lshl_add_u32 v136, v136, 2, s4
	v_add_u32_e32 v138, s72, v137
	v_ashrrev_i32_e32 v137, 31, v136
	v_ashrrev_i32_e32 v139, 31, v138
	v_lshl_add_u64 v[136:137], v[136:137], 2, s[0:1]
	v_lshlrev_b64 v[140:141], 14, v[138:139]
	v_lshl_add_u64 v[140:141], v[136:137], 0, v[140:141]
	global_store_dwordx4 v[140:141], v[124:127], off
	global_store_dwordx4 v[140:141], v[120:123], off offset:64
	global_store_dwordx4 v[140:141], v[108:111], off offset:512
	global_store_dwordx4 v[140:141], v[100:103], off offset:576
	s_and_b64 vcc, exec, s[6:7]
	s_mov_b32 s30, s40
	v_add_u32_e32 v100, 16, v138
	v_ashrrev_i32_e32 v101, 31, v100
	v_lshlrev_b64 v[100:101], 14, v[100:101]
	v_lshl_add_u64 v[100:101], v[136:137], 0, v[100:101]
	global_store_dwordx4 v[100:101], v[116:119], off
	global_store_dwordx4 v[100:101], v[112:115], off offset:64
	global_store_dwordx4 v[100:101], v[92:95], off offset:512
	global_store_dwordx4 v[100:101], v[84:87], off offset:576
	s_mov_b32 s28, s42
	s_mov_b64 s[36:37], s[46:47]
	v_add_u32_e32 v84, 32, v138
	v_ashrrev_i32_e32 v85, 31, v84
	v_lshlrev_b64 v[84:85], 14, v[84:85]
	v_lshl_add_u64 v[84:85], v[136:137], 0, v[84:85]
	global_store_dwordx4 v[84:85], v[104:107], off
	global_store_dwordx4 v[84:85], v[96:99], off offset:64
	global_store_dwordx4 v[84:85], v[76:79], off offset:512
	global_store_dwordx4 v[84:85], v[72:75], off offset:576
	s_mov_b64 s[38:39], s[44:45]
	s_nop 0
	v_add_u32_e32 v72, 48, v138
	v_ashrrev_i32_e32 v73, 31, v72
	v_lshlrev_b64 v[72:73], 14, v[72:73]
	v_lshl_add_u64 v[72:73], v[136:137], 0, v[72:73]
	global_store_dwordx4 v[72:73], v[88:91], off
	global_store_dwordx4 v[72:73], v[80:83], off offset:64
	global_store_dwordx4 v[72:73], v[68:71], off offset:512
	global_store_dwordx4 v[72:73], v[64:67], off offset:576
	s_nop 1
	v_add_u32_e32 v64, 0x80, v138
	v_ashrrev_i32_e32 v65, 31, v64
	v_lshlrev_b64 v[64:65], 14, v[64:65]
	v_lshl_add_u64 v[64:65], v[136:137], 0, v[64:65]
	global_store_dwordx4 v[64:65], v[60:63], off
	global_store_dwordx4 v[64:65], v[56:59], off offset:64
	global_store_dwordx4 v[64:65], v[44:47], off offset:512
	global_store_dwordx4 v[64:65], v[36:39], off offset:576
	s_nop 1
	v_add_u32_e32 v36, 0x90, v138
	v_ashrrev_i32_e32 v37, 31, v36
	v_lshlrev_b64 v[36:37], 14, v[36:37]
	v_lshl_add_u64 v[36:37], v[136:137], 0, v[36:37]
	global_store_dwordx4 v[36:37], v[52:55], off
	global_store_dwordx4 v[36:37], v[48:51], off offset:64
	global_store_dwordx4 v[36:37], v[28:31], off offset:512
	global_store_dwordx4 v[36:37], v[20:23], off offset:576
	s_nop 1
	v_add_u32_e32 v20, 0xa0, v138
	v_ashrrev_i32_e32 v21, 31, v20
	v_lshlrev_b64 v[20:21], 14, v[20:21]
	v_lshl_add_u64 v[20:21], v[136:137], 0, v[20:21]
	global_store_dwordx4 v[20:21], v[40:43], off
	global_store_dwordx4 v[20:21], v[32:35], off offset:64
	global_store_dwordx4 v[20:21], v[12:15], off offset:512
	global_store_dwordx4 v[20:21], v[8:11], off offset:576
	s_nop 1
	v_add_u32_e32 v8, 0xb0, v138
	v_ashrrev_i32_e32 v9, 31, v8
	v_lshlrev_b64 v[8:9], 14, v[8:9]
	v_lshl_add_u64 v[8:9], v[136:137], 0, v[8:9]
	global_store_dwordx4 v[8:9], v[24:27], off
	global_store_dwordx4 v[8:9], v[16:19], off offset:64
	global_store_dwordx4 v[8:9], v[4:7], off offset:512
	global_store_dwordx4 v[8:9], v[0:3], off offset:576
	s_cbranch_vccz .LBB0_1374
	s_waitcnt vmcnt(0)
	s_cmpk_gt_u32 s35, 0xff
	s_cbranch_scc1 .LBB0_1381
	s_barrier

;     DI size_t aoff(const Unit& u, size_t tstep) const { return (size_t)u.pm * tstep; }
;     DI size_t boff(const Unit& u, size_t tstep) const { return (size_t)u.pn * tstep; }
;     DI size_t aoff(const Unit& u, size_t) const { return (size_t)u.ks * kbytes; }
;     DI size_t boff(const Unit& u, size_t tstep) const { return (size_t)u.pn * tstep + (size_t)u.ks * kbytes; }
;     DI size_t aoff(const Unit& u, size_t tstep) const { return (u.ks < 2 ? offU : offOA) + (size_t)u.pm * tstep; }
; #define PG8_STAGE(bufoff, gbase, voff) do { _Pragma("unroll") for (int _i = 0; _i < 2; ++_i) \
;         __builtin_amdgcn_global_load_lds((const unsigned*)((const char*)(gbase) + (voff)[_i]), (LAS unsigned*)(lds + (bufoff) + ldsw + _i * 8192), 16, 0, 0); } while (0)
; #define PG8_WAIT_V(n) asm volatile("s_waitcnt vmcnt(" #n ")" ::: "memory")
; #define PG8_BAR __builtin_amdgcn_s_barrier()
; template <class Epi, class Sched>
; DI void gemm_phase(LAS unsigned char* lds, const Gemm g, const Sched& S, const Epi& E) {
;     ...
;     const char* cA = (const char*)g.A + S.aoff(cur, tstep); const char* cB = (const char*)g.Bt + S.boff(cur, tstep);
;     PG8_STAGE(PG8_SB(0, 0), cB, voffB); PG8_STAGE(PG8_SA(0, 0), cA, voffA); PG8_STAGE(PG8_SB(0, 1), cB + hstep, voffB); PG8_STAGE(PG8_SA(0, 1), cA + hstep, voffA);
;     if (wr == 1) PG8_BAR;
;     PG8_WAIT_V(4); PG8_BAR;
;     PG8_STAGE(PG8_SB(1, 0), cB + kstep, voffB); PG8_STAGE(PG8_SA(1, 0), cA + kstep, voffA); PG8_STAGE(PG8_SB(1, 1), cB + hstep + kstep, voffB);
;     PG8_WAIT_V(6); PG8_BAR;
.LBB0_1496:
	v_bitop3_b32 v8, v198, v200, 48 bitop3:0x6c
	s_movk_i32 s0, 0x70
	v_or_b32_e32 v0, v8, v196
	s_waitcnt lgkmcnt(0)
	v_and_or_b32 v1, v187, s0, v197
	v_add_u32_e32 v9, 0x2000, v198
	v_lshl_or_b32 v128, v1, 12, v0
	v_lshrrev_b32_e32 v1, 7, v9
	s_movk_i32 s0, 0xf0
	v_and_or_b32 v2, v1, s0, v197
	s_add_u32 s55, s22, 0x75c3000
	v_lshl_or_b32 v130, v2, 12, v0
	v_and_b32_e32 v2, 0x3c0, v199
	v_and_b32_e32 v3, 32, v185
	v_mov_b32_e32 v129, 0
	s_addc_u32 s56, s23, 0
	s_waitcnt vmcnt(0)
	v_bitop3_b32 v148, v195, v3, v2 bitop3:0x36
	v_mov_b32_e32 v131, v129
	s_andn2_b64 vcc, exec, s[6:7]
	s_ashr_i32 s57, s26, 31
	s_cbranch_vccnz .LBB0_1528
	v_lshrrev_b32_e32 v2, 2, v184
	v_lshlrev_b32_e32 v3, 1, v2
	v_lshrrev_b32_e32 v4, 5, v184
	v_and_b32_e32 v3, 24, v3
	v_and_b32_e32 v4, 4, v4
	v_and_b32_e32 v2, 3, v2
	s_add_u32 s13, s22, 0x107c3000
	v_or3_b32 v2, v4, v2, v3
	s_movk_i32 s0, 0x60
	s_addc_u32 s50, s23, 0
	v_and_or_b32 v3, v187, s0, v2
	s_movk_i32 s0, 0xe0
	s_lshr_b32 s1, s11, 6
	s_ashr_i32 s43, s42, 31
	s_ashr_i32 s15, s14, 31
	v_and_or_b32 v1, v1, s0, v2
	s_lshr_b32 s0, s11, 8
	s_lshl_b32 s51, s1, 10
	s_lshl_b64 s[4:5], s[42:43], 20
	s_lshl_b64 s[6:7], s[14:15], 20
	s_add_u32 s46, s55, s6
	s_addc_u32 s47, s56, s7
	s_add_i32 s52, s51, 0
	v_lshl_or_b32 v132, v3, 12, v0
	s_add_i32 m0, s52, 0x10000
	v_lshl_or_b32 v134, v1, 12, v0
	global_load_lds_dwordx4 v132, s[46:47]
	s_add_i32 m0, s52, 0x12000
	s_add_u32 s44, s13, s4
	s_addc_u32 s45, s50, s5
	global_load_lds_dwordx4 v134, s[46:47]
	v_lshl_add_u64 v[2:3], s[44:45], 0, v[128:129]
	s_mov_b32 m0, s52
	s_add_i32 s53, s52, 0x2000
	global_load_lds_dwordx4 v128, s[44:45]
	v_lshl_add_u64 v[0:1], s[44:45], 0, v[130:131]
	s_mov_b32 m0, s53
	s_add_u32 s4, s46, 0x80000
	global_load_lds_dwordx4 v130, s[44:45]
	s_addc_u32 s5, s47, 0
	s_add_i32 m0, s52, 0x14000
	v_mov_b32_e32 v133, v129
	global_load_lds_dwordx4 v132, s[4:5]
	s_add_i32 m0, s52, 0x16000
	v_mov_b32_e32 v135, v129
	global_load_lds_dwordx4 v134, s[4:5]
	s_add_u32 s4, s44, 0x80000
	s_addc_u32 s5, s45, 0
	s_add_i32 s58, s52, 0x4000
	s_mov_b32 m0, s58
	s_add_i32 s59, s52, 0x6000
	global_load_lds_dwordx4 v128, s[4:5]
	s_mov_b32 m0, s59
	s_mov_b32 s15, 0
	global_load_lds_dwordx4 v130, s[4:5]
	v_lshl_add_u64 v[6:7], s[46:47], 0, v[132:133]
	s_cmp_lg_u32 s0, 1
	v_lshl_add_u64 v[4:5], s[46:47], 0, v[134:135]
	s_cbranch_scc1 .LBB0_1499
	s_barrier
.LBB0_1499:
	s_add_u32 s16, s22, 0x86c3000
	s_addc_u32 s17, s23, 0
	s_add_u32 s18, s22, 0x183000
	s_mov_b64 s[28:29], 0x80
	s_addc_u32 s19, s23, 0
	s_and_b32 s60, s1, 3
	s_add_i32 m0, s52, 0x18000
	v_lshl_add_u64 v[6:7], v[6:7], 0, s[28:29]
	s_lshl_b32 s61, s0, 6
	s_lshl_b32 s4, s0, 13
	s_lshl_b32 s62, s60, 5
	s_waitcnt vmcnt(4)
	s_barrier
	global_load_lds_dwordx4 v[6:7], off
	v_lshl_add_u64 v[4:5], v[4:5], 0, s[28:29]
	s_add_i32 m0, s52, 0x1a000
	s_add_i32 s63, s52, 0x8000
	s_add_i32 s64, s52, 0xa000
	global_load_lds_dwordx4 v[4:5], off
	v_lshl_add_u64 v[2:3], v[2:3], 0, s[28:29]
	s_mov_b32 m0, s63
	s_add_u32 s0, s46, 0x80080
	global_load_lds_dwordx4 v[2:3], off
	v_lshl_add_u64 v[0:1], v[0:1], 0, s[28:29]
	s_mov_b32 m0, s64
	s_addc_u32 s1, s47, 0
	global_load_lds_dwordx4 v[0:1], off
	s_add_i32 m0, s52, 0x1c000
	s_nop 0
	global_load_lds_dwordx4 v132, s[0:1]
	s_add_i32 m0, s52, 0x1e000
	v_lshlrev_b32_e32 v2, 12, v197
	global_load_lds_dwordx4 v134, s[0:1]
	v_lshlrev_b32_e32 v1, 2, v194
	v_lshl_or_b32 v0, v194, 6, v195
	v_and_b32_e32 v1, 32, v1
	v_bitop3_b32 v0, v0, s4, v1 bitop3:0xde
	v_lshlrev_b32_e32 v1, 9, v184
	v_and_b32_e32 v1, 0x70000, v1
	v_or3_b32 v1, v8, v1, v2
	v_add_u32_e32 v136, v1, v196
	v_lshlrev_b32_e32 v1, 5, v9
	s_waitcnt vmcnt(6)
	v_and_b32_e32 v1, 0xf0000, v1
	v_lshl_or_b32 v149, s60, 12, v148
	v_mov_b32_e32 v137, 0
	v_or3_b32 v1, v8, v1, v2
	s_add_i32 s65, 0, 0x10000
	s_add_i32 s66, 0, 0x14000
	v_add_u32_e32 v138, v1, v196
	v_mov_b32_e32 v139, v137
	v_mov_b64_e32 v[140:141], 0x400
	v_mov_b64_e32 v[142:143], 0x3ff
	v_add_u32_e32 v150, s65, v149
	v_add_u32_e32 v151, 0, v0
	v_add_u32_e32 v152, s66, v149
	v_mbcnt_hi_u32_b32 v153, -1, v204
	s_mov_b32 s67, 0
	s_barrier
	s_branch .LBB0_1501

;     DI size_t aoff(const Unit& u, size_t tstep) const { return (size_t)u.pm * tstep; }
;     DI size_t boff(const Unit& u, size_t tstep) const { return (size_t)u.pn * tstep; }
;     DI bool next(int i, Unit& u) const { const long L = (long)i * G + c; if (L >= np) return false; u.pm = pmv; u.pn = (int)(L % nN); u.ks = (int)(L / nN); return true; }
;     DI size_t aoff(const Unit& u, size_t) const { return (size_t)u.ks * kbytes; }
;     DI size_t boff(const Unit& u, size_t tstep) const { return (size_t)u.pn * tstep + (size_t)u.ks * kbytes; }
;     DI bool next(int i, Unit& u) const { Unit t; if (!S.next(i / 3, t)) return false; u.pm = t.pm; u.pn = t.pn; u.ks = i % 3; return true; }
; template <class Epi, class Sched>
; DI void gemm_phase(LAS unsigned char* lds, const Gemm g, const Sched& S, const Epi& E) {
;     ...
;         const bool has_next = S.next(ui + 1, nxt);
;         const char* nA = has_next ? (const char*)g.A + S.aoff(nxt, tstep) : cA; const char* nB = has_next ? (const char*)g.Bt + S.boff(nxt, tstep) : cB;
;         for (int t = 0; t < nt; t += 2) {
;             if constexpr (Epi::HAS_MID) { if (t == E.mid_t(nt)) { int fr3 = fr, fq3 = fq; asm volatile("" : "+v"(fr3), "+v"(fq3)); E.mid(acc, cur, wr, wc, fr3, fq3); } }
;             const bool last = (t == nt - 2);
;             const char* a1 = cA + (size_t)(t + 1) * kstep;
;             const char* a2 = last ? nA : cA + (size_t)(t + 2) * kstep; const char* b2 = last ? nB : cB + (size_t)(t + 2) * kstep;
;             const char* a3 = a2 + kstep; const char* b3 = b2 + kstep;
;             PG8_LDB(B0, 0, 0); PG8_SCHED; PG8_LDA(At, 0, 0); PG8_STAGE(PG8_SA(1, 1), a1 + hstep, voffA);
;             PG8_WAIT_L(8); PG8_BAR; PG8_WAIT_L(0); PG8_MMA(0, 0, At, B0); PG8_BAR; PG8_SCHED;
;             PG8_LDB(B1, 0, 1); PG8_STAGE(PG8_SB(0, 0), b2, voffB);
;             PG8_BAR; PG8_WAIT_L(0); PG8_MMA(0, 1, At, B1); PG8_BAR;
;             PG8_LDA(At, 0, 1); PG8_STAGE(PG8_SA(0, 0), a2, voffA);
;             PG8_BAR; PG8_WAIT_L(0); PG8_MMA(1, 0, At, B0); PG8_BAR; PG8_SCHED;
;             PG8_STAGE(PG8_SB(0, 1), b2 + hstep, voffB);
;             PG8_WAIT_V(6); PG8_BAR; PG8_MMA(1, 1, At, B1); PG8_BAR;
;             PG8_LDB(B0, 1, 0); PG8_SCHED; PG8_LDA(At, 1, 0); PG8_STAGE(PG8_SA(0, 1), a2 + hstep, voffA);
;             PG8_WAIT_L(8); PG8_BAR; PG8_WAIT_L(0); PG8_MMA(0, 0, At, B0); PG8_BAR; PG8_SCHED;
.LBB0_1507:
	s_ashr_i32 s37, s36, 31
	s_lshl_b64 s[0:1], s[36:37], 20
	v_cmp_lt_i64_e32 vcc, s[38:39], v[140:141]
	s_add_u32 s38, s13, s0
	s_addc_u32 s39, s50, s1
	s_and_b64 s[0:1], vcc, exec
	s_cselect_b32 s34, s39, s45
	s_cselect_b32 s35, s38, s44
	s_ashr_i32 s31, s30, 31
	s_lshl_b64 s[0:1], s[30:31], 20
	s_add_u32 s40, s55, s0
	s_addc_u32 s41, s56, s1
	s_and_b64 s[0:1], vcc, exec
	s_cselect_b32 s31, s41, s47
	s_cselect_b32 s37, s40, s46
	s_add_u32 s44, s44, 0x80080
	s_addc_u32 s45, s45, 0
	s_add_u32 s43, s46, 0x100
	v_mov_b32_e32 v0, 0
	s_addc_u32 s68, s47, 0
	s_mov_b32 s69, -2
	s_waitcnt lgkmcnt(0)
	ds_read_b128 v[144:147], v150
	ds_read_b128 v[154:157], v150 offset:1024
	ds_read_b128 v[158:161], v150 offset:2048
	ds_read_b128 v[162:165], v150 offset:3072
	s_add_u32 s0, s44, 0xfff80080
	s_addc_u32 s1, s45, -1
	s_cmp_eq_u32 s69, 28
	s_cselect_b32 s49, s34, s1
	s_cselect_b32 s48, s35, s0
	s_cselect_b32 s47, s31, s68
	s_cselect_b32 s46, s37, s43
	s_add_i32 m0, s52, 0xc000
	ds_read_b128 v[166:169], v151
	ds_read_b128 v[170:173], v151 offset:1024
	ds_read_b128 v[174:177], v151 offset:2048
	ds_read_b128 v[178:181], v151 offset:3072
	ds_read_b128 v[188:191], v151 offset:4096
	ds_read_b128 v[206:209], v151 offset:5120
	ds_read_b128 v[210:213], v151 offset:6144
	ds_read_b128 v[214:217], v151 offset:7168
	global_load_lds_dwordx4 v136, s[44:45]
	s_add_i32 m0, s52, 0xe000
	s_nop 0
	global_load_lds_dwordx4 v138, s[44:45]
	s_waitcnt lgkmcnt(8)
	s_barrier
	s_waitcnt lgkmcnt(0)
	s_setprio 1
	s_waitcnt lgkmcnt(0)
	v_mfma_f32_16x16x32_bf16 v[124:127], v[144:147], v[166:169], 0
	v_mfma_f32_16x16x32_bf16 v[120:123], v[158:161], v[166:169], 0
	v_mfma_f32_16x16x32_bf16 v[108:111], v[144:147], v[174:177], 0
	v_mfma_f32_16x16x32_bf16 v[104:107], v[158:161], v[174:177], 0
	v_mfma_f32_16x16x32_bf16 v[92:95], v[144:147], v[188:191], 0
	v_mfma_f32_16x16x32_bf16 v[88:91], v[158:161], v[188:191], 0
	v_mfma_f32_16x16x32_bf16 v[76:79], v[144:147], v[210:213], 0
	v_mfma_f32_16x16x32_bf16 v[72:75], v[158:161], v[210:213], 0
	v_mfma_f32_16x16x32_bf16 v[124:127], v[154:157], v[170:173], v[124:127]
	v_mfma_f32_16x16x32_bf16 v[120:123], v[162:165], v[170:173], v[120:123]
	v_mfma_f32_16x16x32_bf16 v[108:111], v[154:157], v[178:181], v[108:111]
	v_mfma_f32_16x16x32_bf16 v[104:107], v[162:165], v[178:181], v[104:107]
	v_mfma_f32_16x16x32_bf16 v[92:95], v[154:157], v[206:209], v[92:95]
	v_mfma_f32_16x16x32_bf16 v[88:91], v[162:165], v[206:209], v[88:91]
	v_mfma_f32_16x16x32_bf16 v[76:79], v[154:157], v[214:217], v[76:79]
	v_mfma_f32_16x16x32_bf16 v[72:75], v[162:165], v[214:217], v[72:75]
	s_setprio 0
	s_barrier
	s_add_i32 s0, s65, s51
	s_mov_b32 m0, s0
	ds_read_b128 v[218:221], v152
	ds_read_b128 v[222:225], v152 offset:1024
	ds_read_b128 v[226:229], v152 offset:2048
	ds_read_b128 v[230:233], v152 offset:3072
	global_load_lds_dwordx4 v132, s[46:47]
	s_add_i32 m0, s0, 0x2000
	s_nop 0
	global_load_lds_dwordx4 v134, s[46:47]
	s_barrier
	s_waitcnt lgkmcnt(0)
	s_setprio 1
	s_waitcnt lgkmcnt(0)
	v_mfma_f32_16x16x32_bf16 v[116:119], v[218:221], v[166:169], 0
	v_mfma_f32_16x16x32_bf16 v[112:115], v[226:229], v[166:169], 0
	v_mfma_f32_16x16x32_bf16 v[100:103], v[218:221], v[174:177], 0
	v_mfma_f32_16x16x32_bf16 v[96:99], v[226:229], v[174:177], 0
	v_mfma_f32_16x16x32_bf16 v[84:87], v[218:221], v[188:191], 0
	v_mfma_f32_16x16x32_bf16 v[80:83], v[226:229], v[188:191], 0
	v_mfma_f32_16x16x32_bf16 v[68:71], v[218:221], v[210:213], 0
	v_mfma_f32_16x16x32_bf16 v[64:67], v[226:229], v[210:213], 0
	v_mfma_f32_16x16x32_bf16 v[116:119], v[222:225], v[170:173], v[116:119]
	v_mfma_f32_16x16x32_bf16 v[112:115], v[230:233], v[170:173], v[112:115]
	v_mfma_f32_16x16x32_bf16 v[100:103], v[222:225], v[178:181], v[100:103]
	v_mfma_f32_16x16x32_bf16 v[96:99], v[230:233], v[178:181], v[96:99]
	v_mfma_f32_16x16x32_bf16 v[84:87], v[222:225], v[206:209], v[84:87]
	v_mfma_f32_16x16x32_bf16 v[80:83], v[230:233], v[206:209], v[80:83]
	v_mfma_f32_16x16x32_bf16 v[68:71], v[222:225], v[214:217], v[68:71]
	v_mfma_f32_16x16x32_bf16 v[64:67], v[230:233], v[214:217], v[64:67]
	s_setprio 0
	s_mov_b32 m0, s52
	s_barrier
	ds_read_b128 v[166:169], v151 offset:16384
	ds_read_b128 v[170:173], v151 offset:17408
	ds_read_b128 v[174:177], v151 offset:18432
	ds_read_b128 v[178:181], v151 offset:19456
	ds_read_b128 v[188:191], v151 offset:20480
	ds_read_b128 v[206:209], v151 offset:21504
	ds_read_b128 v[210:213], v151 offset:22528
	ds_read_b128 v[214:217], v151 offset:23552
	global_load_lds_dwordx4 v128, s[48:49]
	s_mov_b32 m0, s53
	s_nop 0
	global_load_lds_dwordx4 v130, s[48:49]
	s_barrier
	s_waitcnt lgkmcnt(0)
	s_setprio 1
	s_waitcnt lgkmcnt(0)
	v_mfma_f32_16x16x32_bf16 v[60:63], v[144:147], v[166:169], 0
	v_mfma_f32_16x16x32_bf16 v[56:59], v[158:161], v[166:169], 0
	v_mfma_f32_16x16x32_bf16 v[44:47], v[144:147], v[174:177], 0
	v_mfma_f32_16x16x32_bf16 v[40:43], v[158:161], v[174:177], 0
	v_mfma_f32_16x16x32_bf16 v[28:31], v[144:147], v[188:191], 0
	v_mfma_f32_16x16x32_bf16 v[24:27], v[158:161], v[188:191], 0
	v_mfma_f32_16x16x32_bf16 v[12:15], v[144:147], v[210:213], 0
	v_mfma_f32_16x16x32_bf16 v[8:11], v[158:161], v[210:213], 0
	v_mfma_f32_16x16x32_bf16 v[60:63], v[154:157], v[170:173], v[60:63]
	v_mfma_f32_16x16x32_bf16 v[56:59], v[162:165], v[170:173], v[56:59]
	v_mfma_f32_16x16x32_bf16 v[44:47], v[154:157], v[178:181], v[44:47]
	v_mfma_f32_16x16x32_bf16 v[40:43], v[162:165], v[178:181], v[40:43]
	v_mfma_f32_16x16x32_bf16 v[28:31], v[154:157], v[206:209], v[28:31]
	v_mfma_f32_16x16x32_bf16 v[24:27], v[162:165], v[206:209], v[24:27]
	v_mfma_f32_16x16x32_bf16 v[12:15], v[154:157], v[214:217], v[12:15]
	v_mfma_f32_16x16x32_bf16 v[8:11], v[162:165], v[214:217], v[8:11]
	s_setprio 0
	s_barrier
; #define PG8_STAGE(bufoff, gbase, voff) do { _Pragma("unroll") for (int _i = 0; _i < 2; ++_i) \
;         __builtin_amdgcn_global_load_lds((const unsigned*)((const char*)(gbase) + (voff)[_i]), (LAS unsigned*)(lds + (bufoff) + ldsw + _i * 8192), 16, 0, 0); } while (0)
; #define PG8_LDA(dst, b, h) do { _Pragma("unroll") for (int m = 0; m < 4; ++m) _Pragma("unroll") for (int k = 0; k < 2; ++k) dst[m][k] = *(const LAS bf16x8*)(lds + PG8_SA(b, h) + aoff + m * 2048 + k * 1024); } while (0)
; #define PG8_LDB(dst, b, h) do { _Pragma("unroll") for (int n = 0; n < 2; ++n) _Pragma("unroll") for (int k = 0; k < 2; ++k) dst[n][k] = *(const LAS bf16x8*)(lds + PG8_SB(b, h) + boff + n * 2048 + k * 1024); } while (0)
; #define PG8_MMA(ai, bj, At, Bt) do { __builtin_amdgcn_s_setprio(1); _Pragma("unroll") for (int m = 0; m < 4; ++m) _Pragma("unroll") for (int n = 0; n < 2; ++n) _Pragma("unroll") for (int k = 0; k < 2; ++k) \
;         acc[ai][bj][m][n] = __builtin_amdgcn_mfma_f32_16x16x32_bf16(Bt[n][k], At[m][k], acc[ai][bj][m][n], 0, 0, 0); __builtin_amdgcn_s_setprio(0); } while (0)
; #define PG8_WAIT_V(n) asm volatile("s_waitcnt vmcnt(" #n ")" ::: "memory")
; #define PG8_WAIT_L(n) asm volatile("s_waitcnt lgkmcnt(" #n ")" ::: "memory")
; #define PG8_BAR __builtin_amdgcn_s_barrier()
; #define PG8_SCHED __builtin_amdgcn_sched_barrier(0)
; template <class Epi, class Sched>
; DI void gemm_phase(LAS unsigned char* lds, const Gemm g, const Sched& S, const Epi& E) {
;     ...
;             PG8_STAGE(PG8_SB(0, 1), b2 + hstep, voffB);
;             PG8_WAIT_V(6); PG8_BAR; PG8_MMA(1, 1, At, B1); PG8_BAR;
;             PG8_LDB(B0, 1, 0); PG8_SCHED; PG8_LDA(At, 1, 0); PG8_STAGE(PG8_SA(0, 1), a2 + hstep, voffA);
;             PG8_WAIT_L(8); PG8_BAR; PG8_WAIT_L(0); PG8_MMA(0, 0, At, B0); PG8_BAR; PG8_SCHED;
;             PG8_LDB(B1, 1, 1); PG8_STAGE(PG8_SB(1, 0), b3, voffB);
;             PG8_BAR; PG8_WAIT_L(0); PG8_MMA(0, 1, At, B1); PG8_BAR;
;             PG8_LDA(At, 1, 1); PG8_STAGE(PG8_SA(1, 0), a3, voffA);
;             PG8_BAR; PG8_WAIT_L(0); PG8_MMA(1, 0, At, B0); PG8_BAR; PG8_SCHED;
	s_add_u32 s0, s46, 0x80000
	s_addc_u32 s1, s47, 0
	s_add_i32 s4, s66, s51
	s_mov_b32 m0, s4
	s_nop 0
	global_load_lds_dwordx4 v132, s[0:1]
	s_add_i32 m0, s4, 0x2000
	s_nop 0
	global_load_lds_dwordx4 v134, s[0:1]
	s_waitcnt vmcnt(6)
	s_barrier
	s_setprio 1
	v_mfma_f32_16x16x32_bf16 v[52:55], v[218:221], v[166:169], 0
	v_mfma_f32_16x16x32_bf16 v[48:51], v[226:229], v[166:169], 0
	v_mfma_f32_16x16x32_bf16 v[36:39], v[218:221], v[174:177], 0
	v_mfma_f32_16x16x32_bf16 v[32:35], v[226:229], v[174:177], 0
	v_mfma_f32_16x16x32_bf16 v[20:23], v[218:221], v[188:191], 0
	v_mfma_f32_16x16x32_bf16 v[16:19], v[226:229], v[188:191], 0
	v_mfma_f32_16x16x32_bf16 v[4:7], v[218:221], v[210:213], 0
	v_mfma_f32_16x16x32_bf16 v[0:3], v[226:229], v[210:213], 0
	v_mfma_f32_16x16x32_bf16 v[52:55], v[222:225], v[170:173], v[52:55]
	v_mfma_f32_16x16x32_bf16 v[48:51], v[230:233], v[170:173], v[48:51]
	v_mfma_f32_16x16x32_bf16 v[36:39], v[222:225], v[178:181], v[36:39]
	v_mfma_f32_16x16x32_bf16 v[32:35], v[230:233], v[178:181], v[32:35]
	v_mfma_f32_16x16x32_bf16 v[20:23], v[222:225], v[206:209], v[20:23]
	v_mfma_f32_16x16x32_bf16 v[16:19], v[230:233], v[206:209], v[16:19]
	v_mfma_f32_16x16x32_bf16 v[4:7], v[222:225], v[214:217], v[4:7]
	v_mfma_f32_16x16x32_bf16 v[0:3], v[230:233], v[214:217], v[0:3]
	s_setprio 0
	s_add_i32 s4, 0, 0x18000
	v_add_u32_e32 v162, s4, v149
	s_barrier
	ds_read_b128 v[144:147], v162
	ds_read_b128 v[154:157], v162 offset:1024
	ds_read_b128 v[158:161], v162 offset:2048
	ds_read_b128 v[162:165], v162 offset:3072
	s_add_u32 s0, s48, 0x80000
	s_addc_u32 s1, s49, 0
	s_mov_b32 m0, s58
	ds_read_b128 v[166:169], v151 offset:32768
	ds_read_b128 v[170:173], v151 offset:33792
	ds_read_b128 v[174:177], v151 offset:34816
	ds_read_b128 v[178:181], v151 offset:35840
	ds_read_b128 v[188:191], v151 offset:36864
	ds_read_b128 v[206:209], v151 offset:37888
	ds_read_b128 v[210:213], v151 offset:38912
	ds_read_b128 v[214:217], v151 offset:39936
	global_load_lds_dwordx4 v128, s[0:1]
	s_mov_b32 m0, s59
	s_nop 0
	global_load_lds_dwordx4 v130, s[0:1]
	s_waitcnt lgkmcnt(8)
	s_barrier
	s_waitcnt lgkmcnt(0)
	s_setprio 1
	s_waitcnt lgkmcnt(0)
	v_mfma_f32_16x16x32_bf16 v[124:127], v[144:147], v[166:169], v[124:127]
	v_mfma_f32_16x16x32_bf16 v[120:123], v[158:161], v[166:169], v[120:123]
	v_mfma_f32_16x16x32_bf16 v[108:111], v[144:147], v[174:177], v[108:111]
	v_mfma_f32_16x16x32_bf16 v[104:107], v[158:161], v[174:177], v[104:107]
	v_mfma_f32_16x16x32_bf16 v[92:95], v[144:147], v[188:191], v[92:95]
	v_mfma_f32_16x16x32_bf16 v[88:91], v[158:161], v[188:191], v[88:91]
	v_mfma_f32_16x16x32_bf16 v[76:79], v[144:147], v[210:213], v[76:79]
	v_mfma_f32_16x16x32_bf16 v[72:75], v[158:161], v[210:213], v[72:75]
	v_mfma_f32_16x16x32_bf16 v[124:127], v[154:157], v[170:173], v[124:127]
	v_mfma_f32_16x16x32_bf16 v[120:123], v[162:165], v[170:173], v[120:123]
	v_mfma_f32_16x16x32_bf16 v[108:111], v[154:157], v[178:181], v[108:111]
	v_mfma_f32_16x16x32_bf16 v[104:107], v[162:165], v[178:181], v[104:107]
	v_mfma_f32_16x16x32_bf16 v[92:95], v[154:157], v[206:209], v[92:95]
	v_mfma_f32_16x16x32_bf16 v[88:91], v[162:165], v[206:209], v[88:91]
	v_mfma_f32_16x16x32_bf16 v[76:79], v[154:157], v[214:217], v[76:79]
	v_mfma_f32_16x16x32_bf16 v[72:75], v[162:165], v[214:217], v[72:75]
	s_setprio 0
	s_barrier
	s_add_i32 s5, 0, 0x1c000
	s_add_i32 s0, s4, s51
	v_add_u32_e32 v201, s5, v149
	s_add_i32 m0, s0, 0xffffff80
	ds_read_b128 v[218:221], v201
	ds_read_b128 v[222:225], v201 offset:1024
	ds_read_b128 v[226:229], v201 offset:2048
	ds_read_b128 v[230:233], v201 offset:3072
	global_load_lds_dwordx4 v132, s[46:47] offset:128
	s_add_i32 m0, s0, 0x1f80
	s_nop 0
	global_load_lds_dwordx4 v134, s[46:47] offset:128
	s_barrier
	s_waitcnt lgkmcnt(0)
	s_setprio 1
	s_waitcnt lgkmcnt(0)
	v_mfma_f32_16x16x32_bf16 v[116:119], v[218:221], v[166:169], v[116:119]
	v_mfma_f32_16x16x32_bf16 v[112:115], v[226:229], v[166:169], v[112:115]
	v_mfma_f32_16x16x32_bf16 v[100:103], v[218:221], v[174:177], v[100:103]
	v_mfma_f32_16x16x32_bf16 v[96:99], v[226:229], v[174:177], v[96:99]
	v_mfma_f32_16x16x32_bf16 v[84:87], v[218:221], v[188:191], v[84:87]
	v_mfma_f32_16x16x32_bf16 v[80:83], v[226:229], v[188:191], v[80:83]
	v_mfma_f32_16x16x32_bf16 v[68:71], v[218:221], v[210:213], v[68:71]
	v_mfma_f32_16x16x32_bf16 v[64:67], v[226:229], v[210:213], v[64:67]
	v_mfma_f32_16x16x32_bf16 v[116:119], v[222:225], v[170:173], v[116:119]
	v_mfma_f32_16x16x32_bf16 v[112:115], v[230:233], v[170:173], v[112:115]
	v_mfma_f32_16x16x32_bf16 v[100:103], v[222:225], v[178:181], v[100:103]
	v_mfma_f32_16x16x32_bf16 v[96:99], v[230:233], v[178:181], v[96:99]
	v_mfma_f32_16x16x32_bf16 v[84:87], v[222:225], v[206:209], v[84:87]
	v_mfma_f32_16x16x32_bf16 v[80:83], v[230:233], v[206:209], v[80:83]
	v_mfma_f32_16x16x32_bf16 v[68:71], v[222:225], v[214:217], v[68:71]
	v_mfma_f32_16x16x32_bf16 v[64:67], v[230:233], v[214:217], v[64:67]
	s_setprio 0
	s_add_i32 m0, s63, 0xffffff80
	s_barrier
	ds_read_b128 v[166:169], v151 offset:49152
	ds_read_b128 v[170:173], v151 offset:50176
	ds_read_b128 v[174:177], v151 offset:51200
	ds_read_b128 v[178:181], v151 offset:52224
	ds_read_b128 v[188:191], v151 offset:53248
	ds_read_b128 v[206:209], v151 offset:54272
	ds_read_b128 v[210:213], v151 offset:55296
	ds_read_b128 v[214:217], v151 offset:56320
	global_load_lds_dwordx4 v128, s[48:49] offset:128
	s_add_i32 m0, s64, 0xffffff80
	s_nop 0
	global_load_lds_dwordx4 v130, s[48:49] offset:128
	s_barrier
; #define PG8_STAGE(bufoff, gbase, voff) do { _Pragma("unroll") for (int _i = 0; _i < 2; ++_i) \
;         __builtin_amdgcn_global_load_lds((const unsigned*)((const char*)(gbase) + (voff)[_i]), (LAS unsigned*)(lds + (bufoff) + ldsw + _i * 8192), 16, 0, 0); } while (0)
; #define PG8_LDA(dst, b, h) do { _Pragma("unroll") for (int m = 0; m < 4; ++m) _Pragma("unroll") for (int k = 0; k < 2; ++k) dst[m][k] = *(const LAS bf16x8*)(lds + PG8_SA(b, h) + aoff + m * 2048 + k * 1024); } while (0)
; #define PG8_LDB(dst, b, h) do { _Pragma("unroll") for (int n = 0; n < 2; ++n) _Pragma("unroll") for (int k = 0; k < 2; ++k) dst[n][k] = *(const LAS bf16x8*)(lds + PG8_SB(b, h) + boff + n * 2048 + k * 1024); } while (0)
; #define PG8_MMA(ai, bj, At, Bt) do { __builtin_amdgcn_s_setprio(1); _Pragma("unroll") for (int m = 0; m < 4; ++m) _Pragma("unroll") for (int n = 0; n < 2; ++n) _Pragma("unroll") for (int k = 0; k < 2; ++k) \
;         acc[ai][bj][m][n] = __builtin_amdgcn_mfma_f32_16x16x32_bf16(Bt[n][k], At[m][k], acc[ai][bj][m][n], 0, 0, 0); __builtin_amdgcn_s_setprio(0); } while (0)
; #define PG8_WAIT_V(n) asm volatile("s_waitcnt vmcnt(" #n ")" ::: "memory")
; #define PG8_WAIT_L(n) asm volatile("s_waitcnt lgkmcnt(" #n ")" ::: "memory")
; #define PG8_BAR __builtin_amdgcn_s_barrier()
; #define PG8_SCHED __builtin_amdgcn_sched_barrier(0)
; template <class Epi, class Sched>
; DI void gemm_phase(LAS unsigned char* lds, const Gemm g, const Sched& S, const Epi& E) {
;     ...
;             PG8_LDB(B0, 0, 0); PG8_SCHED; PG8_LDA(At, 0, 0); PG8_STAGE(PG8_SA(1, 1), a1 + hstep, voffA);
;             PG8_WAIT_L(8); PG8_BAR; PG8_WAIT_L(0); PG8_MMA(0, 0, At, B0); PG8_BAR; PG8_SCHED;
;             PG8_LDB(B1, 0, 1); PG8_STAGE(PG8_SB(0, 0), b2, voffB);
;             PG8_BAR; PG8_WAIT_L(0); PG8_MMA(0, 1, At, B1); PG8_BAR;
;     ...
;             PG8_LDA(At, 1, 1); PG8_STAGE(PG8_SA(1, 0), a3, voffA);
;             PG8_BAR; PG8_WAIT_L(0); PG8_MMA(1, 0, At, B0); PG8_BAR; PG8_SCHED;
;             PG8_STAGE(PG8_SB(1, 1), b3 + hstep, voffB);
;             PG8_WAIT_V(6); PG8_BAR; PG8_MMA(1, 1, At, B1); PG8_BAR;
	s_waitcnt lgkmcnt(0)
	s_setprio 1
	s_waitcnt lgkmcnt(0)
	v_mfma_f32_16x16x32_bf16 v[60:63], v[144:147], v[166:169], v[60:63]
	v_mfma_f32_16x16x32_bf16 v[56:59], v[158:161], v[166:169], v[56:59]
	v_mfma_f32_16x16x32_bf16 v[44:47], v[144:147], v[174:177], v[44:47]
	v_mfma_f32_16x16x32_bf16 v[40:43], v[158:161], v[174:177], v[40:43]
	v_mfma_f32_16x16x32_bf16 v[28:31], v[144:147], v[188:191], v[28:31]
	v_mfma_f32_16x16x32_bf16 v[24:27], v[158:161], v[188:191], v[24:27]
	v_mfma_f32_16x16x32_bf16 v[12:15], v[144:147], v[210:213], v[12:15]
	v_mfma_f32_16x16x32_bf16 v[8:11], v[158:161], v[210:213], v[8:11]
	v_mfma_f32_16x16x32_bf16 v[60:63], v[154:157], v[170:173], v[60:63]
	v_mfma_f32_16x16x32_bf16 v[56:59], v[162:165], v[170:173], v[56:59]
	v_mfma_f32_16x16x32_bf16 v[44:47], v[154:157], v[178:181], v[44:47]
	v_mfma_f32_16x16x32_bf16 v[40:43], v[162:165], v[178:181], v[40:43]
	v_mfma_f32_16x16x32_bf16 v[28:31], v[154:157], v[206:209], v[28:31]
	v_mfma_f32_16x16x32_bf16 v[24:27], v[162:165], v[206:209], v[24:27]
	v_mfma_f32_16x16x32_bf16 v[12:15], v[154:157], v[214:217], v[12:15]
	v_mfma_f32_16x16x32_bf16 v[8:11], v[162:165], v[214:217], v[8:11]
	s_setprio 0
	s_barrier
	s_add_u32 s0, s46, 0x80080
	s_addc_u32 s1, s47, 0
	s_add_i32 s4, s5, s51
	s_mov_b32 m0, s4
	s_nop 0
	global_load_lds_dwordx4 v132, s[0:1]
	s_add_i32 m0, s4, 0x2000
	s_nop 0
	global_load_lds_dwordx4 v134, s[0:1]
	s_waitcnt vmcnt(6)
	s_barrier
	s_setprio 1
	v_mfma_f32_16x16x32_bf16 v[52:55], v[218:221], v[166:169], v[52:55]
	v_mfma_f32_16x16x32_bf16 v[48:51], v[226:229], v[166:169], v[48:51]
	v_mfma_f32_16x16x32_bf16 v[36:39], v[218:221], v[174:177], v[36:39]
	v_mfma_f32_16x16x32_bf16 v[32:35], v[226:229], v[174:177], v[32:35]
	v_mfma_f32_16x16x32_bf16 v[20:23], v[218:221], v[188:191], v[20:23]
	v_mfma_f32_16x16x32_bf16 v[16:19], v[226:229], v[188:191], v[16:19]
	v_mfma_f32_16x16x32_bf16 v[4:7], v[218:221], v[210:213], v[4:7]
	v_mfma_f32_16x16x32_bf16 v[0:3], v[226:229], v[210:213], v[0:3]
	v_mfma_f32_16x16x32_bf16 v[52:55], v[222:225], v[170:173], v[52:55]
	v_mfma_f32_16x16x32_bf16 v[48:51], v[230:233], v[170:173], v[48:51]
	v_mfma_f32_16x16x32_bf16 v[36:39], v[222:225], v[178:181], v[36:39]
	v_mfma_f32_16x16x32_bf16 v[32:35], v[230:233], v[178:181], v[32:35]
	v_mfma_f32_16x16x32_bf16 v[20:23], v[222:225], v[206:209], v[20:23]
	v_mfma_f32_16x16x32_bf16 v[16:19], v[230:233], v[206:209], v[16:19]
	v_mfma_f32_16x16x32_bf16 v[4:7], v[222:225], v[214:217], v[4:7]
	v_mfma_f32_16x16x32_bf16 v[0:3], v[230:233], v[214:217], v[0:3]
	s_setprio 0
	s_add_i32 s69, s69, 2
	s_add_u32 s44, s44, 0x100
	s_addc_u32 s45, s45, 0
	s_add_u32 s43, s43, 0x100
	s_addc_u32 s68, s68, 0
	s_cmp_gt_u32 s69, 29
	s_barrier
	s_cbranch_scc0 .LBB0_1508
	s_branch .Lpeel_done_1508
.LBB0_1508:
	ds_read_b128 v[144:147], v150
	ds_read_b128 v[154:157], v150 offset:1024
	ds_read_b128 v[158:161], v150 offset:2048
	ds_read_b128 v[162:165], v150 offset:3072
	s_add_u32 s0, s44, 0xfff80080
	s_addc_u32 s1, s45, -1
	s_cmp_eq_u32 s69, 28
	s_cselect_b32 s49, s34, s1
	s_cselect_b32 s48, s35, s0
	s_cselect_b32 s47, s31, s68
	s_cselect_b32 s46, s37, s43
	s_add_i32 m0, s52, 0xc000
	ds_read_b128 v[166:169], v151
	ds_read_b128 v[170:173], v151 offset:1024
	ds_read_b128 v[174:177], v151 offset:2048
	ds_read_b128 v[178:181], v151 offset:3072
	ds_read_b128 v[188:191], v151 offset:4096
	ds_read_b128 v[206:209], v151 offset:5120
	ds_read_b128 v[210:213], v151 offset:6144
	ds_read_b128 v[214:217], v151 offset:7168
	global_load_lds_dwordx4 v136, s[44:45]
	s_add_i32 m0, s52, 0xe000
	s_nop 0
	global_load_lds_dwordx4 v138, s[44:45]
	s_waitcnt lgkmcnt(8)
	s_barrier
	s_waitcnt lgkmcnt(0)
	s_setprio 1
	s_waitcnt lgkmcnt(0)
	v_mfma_f32_16x16x32_bf16 v[124:127], v[144:147], v[166:169], v[124:127]
	v_mfma_f32_16x16x32_bf16 v[120:123], v[158:161], v[166:169], v[120:123]
	v_mfma_f32_16x16x32_bf16 v[108:111], v[144:147], v[174:177], v[108:111]
	v_mfma_f32_16x16x32_bf16 v[104:107], v[158:161], v[174:177], v[104:107]
	v_mfma_f32_16x16x32_bf16 v[92:95], v[144:147], v[188:191], v[92:95]
	v_mfma_f32_16x16x32_bf16 v[88:91], v[158:161], v[188:191], v[88:91]
	v_mfma_f32_16x16x32_bf16 v[76:79], v[144:147], v[210:213], v[76:79]
	v_mfma_f32_16x16x32_bf16 v[72:75], v[158:161], v[210:213], v[72:75]
	v_mfma_f32_16x16x32_bf16 v[124:127], v[154:157], v[170:173], v[124:127]
	v_mfma_f32_16x16x32_bf16 v[120:123], v[162:165], v[170:173], v[120:123]
	v_mfma_f32_16x16x32_bf16 v[108:111], v[154:157], v[178:181], v[108:111]
	v_mfma_f32_16x16x32_bf16 v[104:107], v[162:165], v[178:181], v[104:107]
	v_mfma_f32_16x16x32_bf16 v[92:95], v[154:157], v[206:209], v[92:95]
	v_mfma_f32_16x16x32_bf16 v[88:91], v[162:165], v[206:209], v[88:91]
	v_mfma_f32_16x16x32_bf16 v[76:79], v[154:157], v[214:217], v[76:79]
	v_mfma_f32_16x16x32_bf16 v[72:75], v[162:165], v[214:217], v[72:75]
	s_setprio 0
	s_barrier
	s_add_i32 s0, s65, s51
	s_mov_b32 m0, s0
	ds_read_b128 v[218:221], v152
	ds_read_b128 v[222:225], v152 offset:1024
	ds_read_b128 v[226:229], v152 offset:2048
	ds_read_b128 v[230:233], v152 offset:3072
	global_load_lds_dwordx4 v132, s[46:47]
	s_add_i32 m0, s0, 0x2000
	s_nop 0
	global_load_lds_dwordx4 v134, s[46:47]
	s_barrier
; #define PG8_STAGE(bufoff, gbase, voff) do { _Pragma("unroll") for (int _i = 0; _i < 2; ++_i) \
;         __builtin_amdgcn_global_load_lds((const unsigned*)((const char*)(gbase) + (voff)[_i]), (LAS unsigned*)(lds + (bufoff) + ldsw + _i * 8192), 16, 0, 0); } while (0)
; #define PG8_LDA(dst, b, h) do { _Pragma("unroll") for (int m = 0; m < 4; ++m) _Pragma("unroll") for (int k = 0; k < 2; ++k) dst[m][k] = *(const LAS bf16x8*)(lds + PG8_SA(b, h) + aoff + m * 2048 + k * 1024); } while (0)
; #define PG8_LDB(dst, b, h) do { _Pragma("unroll") for (int n = 0; n < 2; ++n) _Pragma("unroll") for (int k = 0; k < 2; ++k) dst[n][k] = *(const LAS bf16x8*)(lds + PG8_SB(b, h) + boff + n * 2048 + k * 1024); } while (0)
; #define PG8_WAIT_V(n) asm volatile("s_waitcnt vmcnt(" #n ")" ::: "memory")
; #define PG8_WAIT_L(n) asm volatile("s_waitcnt lgkmcnt(" #n ")" ::: "memory")
; #define PG8_BAR __builtin_amdgcn_s_barrier()
; #define PG8_SCHED __builtin_amdgcn_sched_barrier(0)
; template <class Epi, class Sched>
; DI void gemm_phase(LAS unsigned char* lds, const Gemm g, const Sched& S, const Epi& E) {
;     ...
;             PG8_LDB(B0, 0, 0); PG8_SCHED; PG8_LDA(At, 0, 0); PG8_STAGE(PG8_SA(1, 1), a1 + hstep, voffA);
;             PG8_WAIT_L(8); PG8_BAR; PG8_WAIT_L(0); PG8_MMA(0, 0, At, B0); PG8_BAR; PG8_SCHED;
;             PG8_LDB(B1, 0, 1); PG8_STAGE(PG8_SB(0, 0), b2, voffB);
;             PG8_BAR; PG8_WAIT_L(0); PG8_MMA(0, 1, At, B1); PG8_BAR;
;             PG8_LDA(At, 0, 1); PG8_STAGE(PG8_SA(0, 0), a2, voffA);
;             PG8_BAR; PG8_WAIT_L(0); PG8_MMA(1, 0, At, B0); PG8_BAR; PG8_SCHED;
;             PG8_STAGE(PG8_SB(0, 1), b2 + hstep, voffB);
;             PG8_WAIT_V(6); PG8_BAR; PG8_MMA(1, 1, At, B1); PG8_BAR;
;             PG8_LDB(B0, 1, 0); PG8_SCHED; PG8_LDA(At, 1, 0); PG8_STAGE(PG8_SA(0, 1), a2 + hstep, voffA);
;             PG8_WAIT_L(8); PG8_BAR; PG8_WAIT_L(0); PG8_MMA(0, 0, At, B0); PG8_BAR; PG8_SCHED;
;             PG8_LDB(B1, 1, 1); PG8_STAGE(PG8_SB(1, 0), b3, voffB);
;             PG8_BAR; PG8_WAIT_L(0); PG8_MMA(0, 1, At, B1); PG8_BAR;
;             PG8_LDA(At, 1, 1); PG8_STAGE(PG8_SA(1, 0), a3, voffA);
;             PG8_BAR; PG8_WAIT_L(0); PG8_MMA(1, 0, At, B0); PG8_BAR; PG8_SCHED;
;             PG8_STAGE(PG8_SB(1, 1), b3 + hstep, voffB);
;             PG8_WAIT_V(6); PG8_BAR; PG8_MMA(1, 1, At, B1); PG8_BAR;
	s_waitcnt lgkmcnt(0)
	s_setprio 1
	s_waitcnt lgkmcnt(0)
	v_mfma_f32_16x16x32_bf16 v[116:119], v[218:221], v[166:169], v[116:119]
	v_mfma_f32_16x16x32_bf16 v[112:115], v[226:229], v[166:169], v[112:115]
	v_mfma_f32_16x16x32_bf16 v[100:103], v[218:221], v[174:177], v[100:103]
	v_mfma_f32_16x16x32_bf16 v[96:99], v[226:229], v[174:177], v[96:99]
	v_mfma_f32_16x16x32_bf16 v[84:87], v[218:221], v[188:191], v[84:87]
	v_mfma_f32_16x16x32_bf16 v[80:83], v[226:229], v[188:191], v[80:83]
	v_mfma_f32_16x16x32_bf16 v[68:71], v[218:221], v[210:213], v[68:71]
	v_mfma_f32_16x16x32_bf16 v[64:67], v[226:229], v[210:213], v[64:67]
	v_mfma_f32_16x16x32_bf16 v[116:119], v[222:225], v[170:173], v[116:119]
	v_mfma_f32_16x16x32_bf16 v[112:115], v[230:233], v[170:173], v[112:115]
	v_mfma_f32_16x16x32_bf16 v[100:103], v[222:225], v[178:181], v[100:103]
	v_mfma_f32_16x16x32_bf16 v[96:99], v[230:233], v[178:181], v[96:99]
	v_mfma_f32_16x16x32_bf16 v[84:87], v[222:225], v[206:209], v[84:87]
	v_mfma_f32_16x16x32_bf16 v[80:83], v[230:233], v[206:209], v[80:83]
	v_mfma_f32_16x16x32_bf16 v[68:71], v[222:225], v[214:217], v[68:71]
	v_mfma_f32_16x16x32_bf16 v[64:67], v[230:233], v[214:217], v[64:67]
	s_setprio 0
	s_mov_b32 m0, s52
	s_barrier
	ds_read_b128 v[166:169], v151 offset:16384
	ds_read_b128 v[170:173], v151 offset:17408
	ds_read_b128 v[174:177], v151 offset:18432
	ds_read_b128 v[178:181], v151 offset:19456
	ds_read_b128 v[188:191], v151 offset:20480
	ds_read_b128 v[206:209], v151 offset:21504
	ds_read_b128 v[210:213], v151 offset:22528
	ds_read_b128 v[214:217], v151 offset:23552
	global_load_lds_dwordx4 v128, s[48:49]
	s_mov_b32 m0, s53
	s_nop 0
	global_load_lds_dwordx4 v130, s[48:49]
	s_barrier
	s_waitcnt lgkmcnt(0)
	s_setprio 1
	s_waitcnt lgkmcnt(0)
	v_mfma_f32_16x16x32_bf16 v[60:63], v[144:147], v[166:169], v[60:63]
	v_mfma_f32_16x16x32_bf16 v[56:59], v[158:161], v[166:169], v[56:59]
	v_mfma_f32_16x16x32_bf16 v[44:47], v[144:147], v[174:177], v[44:47]
	v_mfma_f32_16x16x32_bf16 v[40:43], v[158:161], v[174:177], v[40:43]
	v_mfma_f32_16x16x32_bf16 v[28:31], v[144:147], v[188:191], v[28:31]
	v_mfma_f32_16x16x32_bf16 v[24:27], v[158:161], v[188:191], v[24:27]
	v_mfma_f32_16x16x32_bf16 v[12:15], v[144:147], v[210:213], v[12:15]
	v_mfma_f32_16x16x32_bf16 v[8:11], v[158:161], v[210:213], v[8:11]
	v_mfma_f32_16x16x32_bf16 v[60:63], v[154:157], v[170:173], v[60:63]
	v_mfma_f32_16x16x32_bf16 v[56:59], v[162:165], v[170:173], v[56:59]
	v_mfma_f32_16x16x32_bf16 v[44:47], v[154:157], v[178:181], v[44:47]
	v_mfma_f32_16x16x32_bf16 v[40:43], v[162:165], v[178:181], v[40:43]
	v_mfma_f32_16x16x32_bf16 v[28:31], v[154:157], v[206:209], v[28:31]
	v_mfma_f32_16x16x32_bf16 v[24:27], v[162:165], v[206:209], v[24:27]
	v_mfma_f32_16x16x32_bf16 v[12:15], v[154:157], v[214:217], v[12:15]
	v_mfma_f32_16x16x32_bf16 v[8:11], v[162:165], v[214:217], v[8:11]
	s_setprio 0
	s_barrier
	s_add_u32 s0, s46, 0x80000
	s_addc_u32 s1, s47, 0
	s_add_i32 s4, s66, s51
	s_mov_b32 m0, s4
	s_nop 0
	global_load_lds_dwordx4 v132, s[0:1]
	s_add_i32 m0, s4, 0x2000
	s_nop 0
	global_load_lds_dwordx4 v134, s[0:1]
	s_waitcnt vmcnt(6)
	s_barrier
	s_setprio 1
	v_mfma_f32_16x16x32_bf16 v[52:55], v[218:221], v[166:169], v[52:55]
	v_mfma_f32_16x16x32_bf16 v[48:51], v[226:229], v[166:169], v[48:51]
	v_mfma_f32_16x16x32_bf16 v[36:39], v[218:221], v[174:177], v[36:39]
	v_mfma_f32_16x16x32_bf16 v[32:35], v[226:229], v[174:177], v[32:35]
	v_mfma_f32_16x16x32_bf16 v[20:23], v[218:221], v[188:191], v[20:23]
	v_mfma_f32_16x16x32_bf16 v[16:19], v[226:229], v[188:191], v[16:19]
	v_mfma_f32_16x16x32_bf16 v[4:7], v[218:221], v[210:213], v[4:7]
	v_mfma_f32_16x16x32_bf16 v[0:3], v[226:229], v[210:213], v[0:3]
	v_mfma_f32_16x16x32_bf16 v[52:55], v[222:225], v[170:173], v[52:55]
	v_mfma_f32_16x16x32_bf16 v[48:51], v[230:233], v[170:173], v[48:51]
	v_mfma_f32_16x16x32_bf16 v[36:39], v[222:225], v[178:181], v[36:39]
	v_mfma_f32_16x16x32_bf16 v[32:35], v[230:233], v[178:181], v[32:35]
	v_mfma_f32_16x16x32_bf16 v[20:23], v[222:225], v[206:209], v[20:23]
	v_mfma_f32_16x16x32_bf16 v[16:19], v[230:233], v[206:209], v[16:19]
	v_mfma_f32_16x16x32_bf16 v[4:7], v[222:225], v[214:217], v[4:7]
	v_mfma_f32_16x16x32_bf16 v[0:3], v[230:233], v[214:217], v[0:3]
	s_setprio 0
	s_add_i32 s4, 0, 0x18000
	v_add_u32_e32 v162, s4, v149
	s_barrier
	ds_read_b128 v[144:147], v162
	ds_read_b128 v[154:157], v162 offset:1024
	ds_read_b128 v[158:161], v162 offset:2048
	ds_read_b128 v[162:165], v162 offset:3072
	s_add_u32 s0, s48, 0x80000
	s_addc_u32 s1, s49, 0
	s_mov_b32 m0, s58
	ds_read_b128 v[166:169], v151 offset:32768
	ds_read_b128 v[170:173], v151 offset:33792
	ds_read_b128 v[174:177], v151 offset:34816
	ds_read_b128 v[178:181], v151 offset:35840
	ds_read_b128 v[188:191], v151 offset:36864
	ds_read_b128 v[206:209], v151 offset:37888
	ds_read_b128 v[210:213], v151 offset:38912
	ds_read_b128 v[214:217], v151 offset:39936
	global_load_lds_dwordx4 v128, s[0:1]
	s_mov_b32 m0, s59
	s_nop 0
	global_load_lds_dwordx4 v130, s[0:1]
	s_waitcnt lgkmcnt(8)
	s_barrier
; #define PG8_STAGE(bufoff, gbase, voff) do { _Pragma("unroll") for (int _i = 0; _i < 2; ++_i) \
;         __builtin_amdgcn_global_load_lds((const unsigned*)((const char*)(gbase) + (voff)[_i]), (LAS unsigned*)(lds + (bufoff) + ldsw + _i * 8192), 16, 0, 0); } while (0)
; #define PG8_LDA(dst, b, h) do { _Pragma("unroll") for (int m = 0; m < 4; ++m) _Pragma("unroll") for (int k = 0; k < 2; ++k) dst[m][k] = *(const LAS bf16x8*)(lds + PG8_SA(b, h) + aoff + m * 2048 + k * 1024); } while (0)
; #define PG8_LDB(dst, b, h) do { _Pragma("unroll") for (int n = 0; n < 2; ++n) _Pragma("unroll") for (int k = 0; k < 2; ++k) dst[n][k] = *(const LAS bf16x8*)(lds + PG8_SB(b, h) + boff + n * 2048 + k * 1024); } while (0)
; #define PG8_WAIT_V(n) asm volatile("s_waitcnt vmcnt(" #n ")" ::: "memory")
; #define PG8_WAIT_L(n) asm volatile("s_waitcnt lgkmcnt(" #n ")" ::: "memory")
; #define PG8_BAR __builtin_amdgcn_s_barrier()
; #define PG8_SCHED __builtin_amdgcn_sched_barrier(0)
; template <class Epi, class Sched>
; DI void gemm_phase(LAS unsigned char* lds, const Gemm g, const Sched& S, const Epi& E) {
;     ...
;             PG8_LDB(B0, 0, 0); PG8_SCHED; PG8_LDA(At, 0, 0); PG8_STAGE(PG8_SA(1, 1), a1 + hstep, voffA);
;             PG8_WAIT_L(8); PG8_BAR; PG8_WAIT_L(0); PG8_MMA(0, 0, At, B0); PG8_BAR; PG8_SCHED;
;             PG8_LDB(B1, 0, 1); PG8_STAGE(PG8_SB(0, 0), b2, voffB);
;             PG8_BAR; PG8_WAIT_L(0); PG8_MMA(0, 1, At, B1); PG8_BAR;
;             PG8_LDA(At, 0, 1); PG8_STAGE(PG8_SA(0, 0), a2, voffA);
;             PG8_BAR; PG8_WAIT_L(0); PG8_MMA(1, 0, At, B0); PG8_BAR; PG8_SCHED;
;             PG8_STAGE(PG8_SB(0, 1), b2 + hstep, voffB);
;             PG8_WAIT_V(6); PG8_BAR; PG8_MMA(1, 1, At, B1); PG8_BAR;
;             PG8_LDB(B0, 1, 0); PG8_SCHED; PG8_LDA(At, 1, 0); PG8_STAGE(PG8_SA(0, 1), a2 + hstep, voffA);
;             PG8_WAIT_L(8); PG8_BAR; PG8_WAIT_L(0); PG8_MMA(0, 0, At, B0); PG8_BAR; PG8_SCHED;
;             PG8_LDB(B1, 1, 1); PG8_STAGE(PG8_SB(1, 0), b3, voffB);
;             PG8_BAR; PG8_WAIT_L(0); PG8_MMA(0, 1, At, B1); PG8_BAR;
;             PG8_LDA(At, 1, 1); PG8_STAGE(PG8_SA(1, 0), a3, voffA);
;             PG8_BAR; PG8_WAIT_L(0); PG8_MMA(1, 0, At, B0); PG8_BAR; PG8_SCHED;
;             PG8_STAGE(PG8_SB(1, 1), b3 + hstep, voffB);
;             PG8_WAIT_V(6); PG8_BAR; PG8_MMA(1, 1, At, B1); PG8_BAR;
	s_waitcnt lgkmcnt(0)
	s_setprio 1
	s_waitcnt lgkmcnt(0)
	v_mfma_f32_16x16x32_bf16 v[124:127], v[144:147], v[166:169], v[124:127]
	v_mfma_f32_16x16x32_bf16 v[120:123], v[158:161], v[166:169], v[120:123]
	v_mfma_f32_16x16x32_bf16 v[108:111], v[144:147], v[174:177], v[108:111]
	v_mfma_f32_16x16x32_bf16 v[104:107], v[158:161], v[174:177], v[104:107]
	v_mfma_f32_16x16x32_bf16 v[92:95], v[144:147], v[188:191], v[92:95]
	v_mfma_f32_16x16x32_bf16 v[88:91], v[158:161], v[188:191], v[88:91]
	v_mfma_f32_16x16x32_bf16 v[76:79], v[144:147], v[210:213], v[76:79]
	v_mfma_f32_16x16x32_bf16 v[72:75], v[158:161], v[210:213], v[72:75]
	v_mfma_f32_16x16x32_bf16 v[124:127], v[154:157], v[170:173], v[124:127]
	v_mfma_f32_16x16x32_bf16 v[120:123], v[162:165], v[170:173], v[120:123]
	v_mfma_f32_16x16x32_bf16 v[108:111], v[154:157], v[178:181], v[108:111]
	v_mfma_f32_16x16x32_bf16 v[104:107], v[162:165], v[178:181], v[104:107]
	v_mfma_f32_16x16x32_bf16 v[92:95], v[154:157], v[206:209], v[92:95]
	v_mfma_f32_16x16x32_bf16 v[88:91], v[162:165], v[206:209], v[88:91]
	v_mfma_f32_16x16x32_bf16 v[76:79], v[154:157], v[214:217], v[76:79]
	v_mfma_f32_16x16x32_bf16 v[72:75], v[162:165], v[214:217], v[72:75]
	s_setprio 0
	s_barrier
	s_add_i32 s5, 0, 0x1c000
	s_add_i32 s0, s4, s51
	v_add_u32_e32 v201, s5, v149
	s_add_i32 m0, s0, 0xffffff80
	ds_read_b128 v[218:221], v201
	ds_read_b128 v[222:225], v201 offset:1024
	ds_read_b128 v[226:229], v201 offset:2048
	ds_read_b128 v[230:233], v201 offset:3072
	global_load_lds_dwordx4 v132, s[46:47] offset:128
	s_add_i32 m0, s0, 0x1f80
	s_nop 0
	global_load_lds_dwordx4 v134, s[46:47] offset:128
	s_barrier
	s_waitcnt lgkmcnt(0)
	s_setprio 1
	s_waitcnt lgkmcnt(0)
	v_mfma_f32_16x16x32_bf16 v[116:119], v[218:221], v[166:169], v[116:119]
	v_mfma_f32_16x16x32_bf16 v[112:115], v[226:229], v[166:169], v[112:115]
	v_mfma_f32_16x16x32_bf16 v[100:103], v[218:221], v[174:177], v[100:103]
	v_mfma_f32_16x16x32_bf16 v[96:99], v[226:229], v[174:177], v[96:99]
	v_mfma_f32_16x16x32_bf16 v[84:87], v[218:221], v[188:191], v[84:87]
	v_mfma_f32_16x16x32_bf16 v[80:83], v[226:229], v[188:191], v[80:83]
	v_mfma_f32_16x16x32_bf16 v[68:71], v[218:221], v[210:213], v[68:71]
	v_mfma_f32_16x16x32_bf16 v[64:67], v[226:229], v[210:213], v[64:67]
	v_mfma_f32_16x16x32_bf16 v[116:119], v[222:225], v[170:173], v[116:119]
	v_mfma_f32_16x16x32_bf16 v[112:115], v[230:233], v[170:173], v[112:115]
	v_mfma_f32_16x16x32_bf16 v[100:103], v[222:225], v[178:181], v[100:103]
	v_mfma_f32_16x16x32_bf16 v[96:99], v[230:233], v[178:181], v[96:99]
	v_mfma_f32_16x16x32_bf16 v[84:87], v[222:225], v[206:209], v[84:87]
	v_mfma_f32_16x16x32_bf16 v[80:83], v[230:233], v[206:209], v[80:83]
	v_mfma_f32_16x16x32_bf16 v[68:71], v[222:225], v[214:217], v[68:71]
	v_mfma_f32_16x16x32_bf16 v[64:67], v[230:233], v[214:217], v[64:67]
	s_setprio 0
	s_add_i32 m0, s63, 0xffffff80
	s_barrier
	ds_read_b128 v[166:169], v151 offset:49152
	ds_read_b128 v[170:173], v151 offset:50176
	ds_read_b128 v[174:177], v151 offset:51200
	ds_read_b128 v[178:181], v151 offset:52224
	ds_read_b128 v[188:191], v151 offset:53248
	ds_read_b128 v[206:209], v151 offset:54272
	ds_read_b128 v[210:213], v151 offset:55296
	ds_read_b128 v[214:217], v151 offset:56320
	global_load_lds_dwordx4 v128, s[48:49] offset:128
	s_add_i32 m0, s64, 0xffffff80
	s_nop 0
	global_load_lds_dwordx4 v130, s[48:49] offset:128
	s_barrier
	s_waitcnt lgkmcnt(0)
	s_setprio 1
	s_waitcnt lgkmcnt(0)
	v_mfma_f32_16x16x32_bf16 v[60:63], v[144:147], v[166:169], v[60:63]
	v_mfma_f32_16x16x32_bf16 v[56:59], v[158:161], v[166:169], v[56:59]
	v_mfma_f32_16x16x32_bf16 v[44:47], v[144:147], v[174:177], v[44:47]
	v_mfma_f32_16x16x32_bf16 v[40:43], v[158:161], v[174:177], v[40:43]
	v_mfma_f32_16x16x32_bf16 v[28:31], v[144:147], v[188:191], v[28:31]
	v_mfma_f32_16x16x32_bf16 v[24:27], v[158:161], v[188:191], v[24:27]
	v_mfma_f32_16x16x32_bf16 v[12:15], v[144:147], v[210:213], v[12:15]
	v_mfma_f32_16x16x32_bf16 v[8:11], v[158:161], v[210:213], v[8:11]
	v_mfma_f32_16x16x32_bf16 v[60:63], v[154:157], v[170:173], v[60:63]
	v_mfma_f32_16x16x32_bf16 v[56:59], v[162:165], v[170:173], v[56:59]
	v_mfma_f32_16x16x32_bf16 v[44:47], v[154:157], v[178:181], v[44:47]
	v_mfma_f32_16x16x32_bf16 v[40:43], v[162:165], v[178:181], v[40:43]
	v_mfma_f32_16x16x32_bf16 v[28:31], v[154:157], v[206:209], v[28:31]
	v_mfma_f32_16x16x32_bf16 v[24:27], v[162:165], v[206:209], v[24:27]
	v_mfma_f32_16x16x32_bf16 v[12:15], v[154:157], v[214:217], v[12:15]
	v_mfma_f32_16x16x32_bf16 v[8:11], v[162:165], v[214:217], v[8:11]
	s_setprio 0
	s_barrier
	s_add_u32 s0, s46, 0x80080
	s_addc_u32 s1, s47, 0
	s_add_i32 s4, s5, s51
	s_mov_b32 m0, s4
	s_nop 0
	global_load_lds_dwordx4 v132, s[0:1]
	s_add_i32 m0, s4, 0x2000
	s_nop 0
	global_load_lds_dwordx4 v134, s[0:1]
	s_waitcnt vmcnt(6)
	s_barrier
	s_setprio 1
	v_mfma_f32_16x16x32_bf16 v[52:55], v[218:221], v[166:169], v[52:55]
	v_mfma_f32_16x16x32_bf16 v[48:51], v[226:229], v[166:169], v[48:51]
	v_mfma_f32_16x16x32_bf16 v[36:39], v[218:221], v[174:177], v[36:39]
	v_mfma_f32_16x16x32_bf16 v[32:35], v[226:229], v[174:177], v[32:35]
	v_mfma_f32_16x16x32_bf16 v[20:23], v[218:221], v[188:191], v[20:23]
	v_mfma_f32_16x16x32_bf16 v[16:19], v[226:229], v[188:191], v[16:19]
	v_mfma_f32_16x16x32_bf16 v[4:7], v[218:221], v[210:213], v[4:7]
	v_mfma_f32_16x16x32_bf16 v[0:3], v[226:229], v[210:213], v[0:3]
	v_mfma_f32_16x16x32_bf16 v[52:55], v[222:225], v[170:173], v[52:55]
	v_mfma_f32_16x16x32_bf16 v[48:51], v[230:233], v[170:173], v[48:51]
	v_mfma_f32_16x16x32_bf16 v[36:39], v[222:225], v[178:181], v[36:39]
	v_mfma_f32_16x16x32_bf16 v[32:35], v[230:233], v[178:181], v[32:35]
	v_mfma_f32_16x16x32_bf16 v[20:23], v[222:225], v[206:209], v[20:23]
	v_mfma_f32_16x16x32_bf16 v[16:19], v[230:233], v[206:209], v[16:19]
	v_mfma_f32_16x16x32_bf16 v[4:7], v[222:225], v[214:217], v[4:7]
	v_mfma_f32_16x16x32_bf16 v[0:3], v[230:233], v[214:217], v[0:3]
	s_setprio 0
	s_add_i32 s69, s69, 2
	s_add_u32 s44, s44, 0x100
	s_addc_u32 s45, s45, 0
	s_add_u32 s43, s43, 0x100
	s_addc_u32 s68, s68, 0
	s_cmp_gt_u32 s69, 29
	s_barrier
	s_cbranch_scc0 .LBB0_1508

; #define PG8_STAGE(bufoff, gbase, voff) do { _Pragma("unroll") for (int _i = 0; _i < 2; ++_i) \
;         __builtin_amdgcn_global_load_lds((const unsigned*)((const char*)(gbase) + (voff)[_i]), (LAS unsigned*)(lds + (bufoff) + ldsw + _i * 8192), 16, 0, 0); } while (0)
; #define PG8_WAIT_V(n) asm volatile("s_waitcnt vmcnt(" #n ")" ::: "memory")
; #define PG8_BAR __builtin_amdgcn_s_barrier()
; template <class Epi, class Sched>
; DI void gemm_phase(LAS unsigned char* lds, const Gemm g, const Sched& S, const Epi& E) {
;     ...
;     PG8_STAGE(PG8_SB(0, 0), cB, voffB); PG8_STAGE(PG8_SA(0, 0), cA, voffA); PG8_STAGE(PG8_SB(0, 1), cB + hstep, voffB); PG8_STAGE(PG8_SA(0, 1), cA + hstep, voffA);
;     if (wr == 1) PG8_BAR;
;     PG8_WAIT_V(4); PG8_BAR;
;     PG8_STAGE(PG8_SB(1, 0), cB + kstep, voffB); PG8_STAGE(PG8_SA(1, 0), cA + kstep, voffA); PG8_STAGE(PG8_SB(1, 1), cB + hstep + kstep, voffB);
;     PG8_WAIT_V(6); PG8_BAR;
;     const int kc = K / S; pg8::Gemm g{A, Bt, K, kc / 64}; pg8::SplitOrder O; O.init(N, S, kc, 128, (int)gridDim.x, (int)((blockIdx.x + rot) % gridDim.x));
.LBB0_1528:
	s_cmp_gt_i32 s3, 63
	v_readfirstlane_b32 s34, v184
	s_cbranch_scc1 .LBB0_1540
	s_lshr_b32 s0, s34, 6
	s_lshr_b32 s1, s34, 8
	s_lshl_b32 s35, s0, 10
	s_add_u32 s58, s22, 0x187c3000
	s_addc_u32 s59, s23, 0
	s_ashr_i32 s11, s10, 31
	s_ashr_i32 s13, s12, 31
	s_lshl_b64 s[4:5], s[12:13], 9
	s_lshl_b64 s[6:7], s[10:11], 20
	s_add_u32 s6, s55, s6
	s_addc_u32 s7, s56, s7
	s_add_u32 s14, s6, s4
	s_addc_u32 s15, s7, s5
	s_add_u32 s16, s58, s4
	s_addc_u32 s17, s59, s5
	s_add_u32 s4, s14, 0x80000
	s_addc_u32 s5, s15, 0
	v_lshl_add_u64 v[8:9], s[4:5], 0, v[128:129]
	v_lshl_add_u64 v[10:11], s[4:5], 0, v[130:131]
	s_add_u32 s4, s16, 0x80000
	s_addc_u32 s5, s17, 0
	s_add_i32 s11, s35, 0
	s_waitcnt lgkmcnt(0)
	v_lshl_add_u64 v[0:1], s[14:15], 0, v[128:129]
	s_add_i32 m0, s11, 0x10000
	v_lshl_add_u64 v[2:3], s[14:15], 0, v[130:131]
	global_load_lds_dwordx4 v128, s[14:15]
	s_add_i32 m0, s11, 0x12000
	v_lshl_add_u64 v[4:5], s[16:17], 0, v[128:129]
	global_load_lds_dwordx4 v130, s[14:15]
	s_mov_b32 m0, s11
	s_add_i32 s60, s11, 0x2000
	v_lshl_add_u64 v[6:7], s[16:17], 0, v[130:131]
	global_load_lds_dwordx4 v128, s[16:17]
	s_mov_b32 m0, s60
	s_add_i32 s61, s11, 0x4000
	global_load_lds_dwordx4 v130, s[16:17]
	s_add_i32 m0, s11, 0x14000
	s_nop 0
	global_load_lds_dwordx4 v[8:9], off
	s_add_i32 m0, s11, 0x16000
	s_add_i32 s62, s11, 0x6000
	global_load_lds_dwordx4 v[10:11], off
	s_mov_b32 m0, s61
	s_nop 0
	global_load_lds_dwordx4 v128, s[4:5]
	s_mov_b32 m0, s62
	s_cmp_lg_u32 s1, 1
	global_load_lds_dwordx4 v130, s[4:5]
	s_mov_b32 s63, 0
	s_cbranch_scc1 .LBB0_1531
	s_barrier
.LBB0_1531:
	s_lshl_b32 s0, s0, 5
	s_lshl_b32 s64, s1, 6
	s_lshl_b32 s4, s1, 13
	s_and_b32 s65, s0, 0x60
	s_add_u32 s66, s22, 0x3c40b000
	s_addc_u32 s67, s23, 0
	s_mov_b64 s[6:7], 0x80
	s_add_u32 s0, s14, 0x80080
	v_lshl_add_u64 v[0:1], v[0:1], 0, s[6:7]
	s_addc_u32 s1, s15, 0
	s_add_i32 m0, s11, 0x18000
	v_lshl_add_u64 v[2:3], v[2:3], 0, s[6:7]
	s_waitcnt vmcnt(4)
	s_barrier
	global_load_lds_dwordx4 v[0:1], off
	s_add_i32 m0, s11, 0x1a000
	s_add_i32 s68, s11, 0x8000
	v_lshl_add_u64 v[4:5], v[4:5], 0, s[6:7]
	global_load_lds_dwordx4 v[2:3], off
	s_mov_b32 m0, s68
	s_add_i32 s69, s11, 0xa000
	v_lshl_add_u64 v[6:7], v[6:7], 0, s[6:7]
	global_load_lds_dwordx4 v[4:5], off
	s_mov_b32 m0, s69
	s_nop 0
	global_load_lds_dwordx4 v[6:7], off
	s_add_i32 m0, s11, 0x1c000
	s_nop 0
	global_load_lds_dwordx4 v128, s[0:1]
	s_add_i32 m0, s11, 0x1e000
	v_lshlrev_b32_e32 v1, 2, v194
	global_load_lds_dwordx4 v130, s[0:1]
	v_lshl_or_b32 v0, v194, 6, v195
	v_and_b32_e32 v1, 32, v1
	v_lshl_or_b32 v132, s65, 7, v148
	s_waitcnt vmcnt(6)
	s_add_i32 s73, 0, 0x10000
	v_bitop3_b32 v0, v0, s4, v1 bitop3:0xde
	s_add_i32 s70, 0, 0x14000
	v_add_u32_e32 v133, s73, v132
	s_add_i32 s73, s73, s35
	v_add_u32_e32 v134, 0, v0
	v_add_u32_e32 v135, s70, v132
	s_add_i32 s71, s11, 0xc000
	s_add_i32 s72, s11, 0xe000
	s_add_i32 s74, s73, 0x2000
	s_barrier

; #define PG8_STAGE(bufoff, gbase, voff) do { _Pragma("unroll") for (int _i = 0; _i < 2; ++_i) \
;         __builtin_amdgcn_global_load_lds((const unsigned*)((const char*)(gbase) + (voff)[_i]), (LAS unsigned*)(lds + (bufoff) + ldsw + _i * 8192), 16, 0, 0); } while (0)
; #define PG8_LDA(dst, b, h) do { _Pragma("unroll") for (int m = 0; m < 4; ++m) _Pragma("unroll") for (int k = 0; k < 2; ++k) dst[m][k] = *(const LAS bf16x8*)(lds + PG8_SA(b, h) + aoff + m * 2048 + k * 1024); } while (0)
; #define PG8_LDB(dst, b, h) do { _Pragma("unroll") for (int n = 0; n < 2; ++n) _Pragma("unroll") for (int k = 0; k < 2; ++k) dst[n][k] = *(const LAS bf16x8*)(lds + PG8_SB(b, h) + boff + n * 2048 + k * 1024); } while (0)
; #define PG8_MMA(ai, bj, At, Bt) do { __builtin_amdgcn_s_setprio(1); _Pragma("unroll") for (int m = 0; m < 4; ++m) _Pragma("unroll") for (int n = 0; n < 2; ++n) _Pragma("unroll") for (int k = 0; k < 2; ++k) \
;         acc[ai][bj][m][n] = __builtin_amdgcn_mfma_f32_16x16x32_bf16(Bt[n][k], At[m][k], acc[ai][bj][m][n], 0, 0, 0); __builtin_amdgcn_s_setprio(0); } while (0)
; #define PG8_WAIT_V(n) asm volatile("s_waitcnt vmcnt(" #n ")" ::: "memory")
; #define PG8_WAIT_L(n) asm volatile("s_waitcnt lgkmcnt(" #n ")" ::: "memory")
; #define PG8_BAR __builtin_amdgcn_s_barrier()
; template <class Epi, class Sched>
; DI void gemm_phase(LAS unsigned char* lds, const Gemm g, const Sched& S, const Epi& E) {
;     ...
;             PG8_LDB(B0, 0, 0); PG8_SCHED; PG8_LDA(At, 0, 0); PG8_STAGE(PG8_SA(1, 1), a1 + hstep, voffA);
;             PG8_WAIT_L(8); PG8_BAR; PG8_WAIT_L(0); PG8_MMA(0, 0, At, B0); PG8_BAR; PG8_SCHED;
;             PG8_LDB(B1, 0, 1); PG8_STAGE(PG8_SB(0, 0), b2, voffB);
;             PG8_BAR; PG8_WAIT_L(0); PG8_MMA(0, 1, At, B1); PG8_BAR;
;             PG8_LDA(At, 0, 1); PG8_STAGE(PG8_SA(0, 0), a2, voffA);
;             PG8_BAR; PG8_WAIT_L(0); PG8_MMA(1, 0, At, B0); PG8_BAR; PG8_SCHED;
;             PG8_STAGE(PG8_SB(0, 1), b2 + hstep, voffB);
;             PG8_WAIT_V(6); PG8_BAR; PG8_MMA(1, 1, At, B1); PG8_BAR;
;             PG8_LDB(B0, 1, 0); PG8_SCHED; PG8_LDA(At, 1, 0); PG8_STAGE(PG8_SA(0, 1), a2 + hstep, voffA);
;             PG8_WAIT_L(8); PG8_BAR; PG8_WAIT_L(0); PG8_MMA(0, 0, At, B0); PG8_BAR; PG8_SCHED;
;             PG8_LDB(B1, 1, 1); PG8_STAGE(PG8_SB(1, 0), b3, voffB);
;             PG8_BAR; PG8_WAIT_L(0); PG8_MMA(0, 1, At, B1); PG8_BAR;
.LBB0_1535:
	s_add_u32 s29, s16, s0
	s_addc_u32 s33, s17, 0
	s_add_u32 s1, s29, 0x100
	s_addc_u32 s44, s33, 0
	s_and_b64 s[4:5], s[42:43], exec
	s_cselect_b32 s49, s13, s44
	s_cselect_b32 s48, s19, s1
	s_add_u32 s0, s14, s0
	s_addc_u32 s1, s15, 0
	s_add_u32 s4, s0, 0x100
	s_addc_u32 s5, s1, 0
	s_and_b64 s[0:1], s[42:43], exec
	s_cselect_b32 s51, s39, s5
	s_cselect_b32 s50, s38, s4
	s_add_u32 s52, s29, 0x80080
	s_addc_u32 s53, s33, 0
	s_add_u32 s46, s50, 0x80000
	s_addc_u32 s47, s51, 0
	s_add_i32 s33, s70, s35
	ds_read_b128 v[136:139], v133
	ds_read_b128 v[140:143], v133 offset:1024
	ds_read_b128 v[144:147], v133 offset:2048
	ds_read_b128 v[148:151], v133 offset:3072
	s_add_i32 s29, s33, 0x2000
	s_add_i32 s5, 0, 0x18000
	s_add_u32 s44, s48, 0x80000
	s_addc_u32 s45, s49, 0
	s_add_i32 s4, s5, s35
	s_add_i32 s1, 0, 0x1c000
	s_add_i32 s0, s4, 0x2000
	s_add_u32 s42, s50, 0x80080
	s_addc_u32 s43, s51, 0
	s_add_i32 s76, s1, s35
	s_add_i32 s75, s76, 0x2000
	s_mov_b32 m0, s71
	ds_read_b128 v[152:155], v134
	ds_read_b128 v[156:159], v134 offset:1024
	ds_read_b128 v[160:163], v134 offset:2048
	ds_read_b128 v[164:167], v134 offset:3072
	ds_read_b128 v[168:171], v134 offset:4096
	ds_read_b128 v[172:175], v134 offset:5120
	ds_read_b128 v[176:179], v134 offset:6144
	ds_read_b128 v[180:183], v134 offset:7168
	global_load_lds_dwordx4 v128, s[52:53]
	s_mov_b32 m0, s72
	s_nop 0
	global_load_lds_dwordx4 v130, s[52:53]
	s_waitcnt lgkmcnt(8)
	s_barrier
	s_waitcnt lgkmcnt(0)
	s_setprio 1
	s_waitcnt lgkmcnt(0)
	v_mfma_f32_16x16x32_bf16 v[124:127], v[136:139], v[152:155], v[124:127]
	v_mfma_f32_16x16x32_bf16 v[120:123], v[144:147], v[152:155], v[120:123]
	v_mfma_f32_16x16x32_bf16 v[116:119], v[136:139], v[160:163], v[116:119]
	v_mfma_f32_16x16x32_bf16 v[112:115], v[144:147], v[160:163], v[112:115]
	v_mfma_f32_16x16x32_bf16 v[104:107], v[136:139], v[168:171], v[104:107]
	v_mfma_f32_16x16x32_bf16 v[96:99], v[144:147], v[168:171], v[96:99]
	v_mfma_f32_16x16x32_bf16 v[88:91], v[136:139], v[176:179], v[88:91]
	v_mfma_f32_16x16x32_bf16 v[80:83], v[144:147], v[176:179], v[80:83]
	v_mfma_f32_16x16x32_bf16 v[124:127], v[140:143], v[156:159], v[124:127]
	v_mfma_f32_16x16x32_bf16 v[120:123], v[148:151], v[156:159], v[120:123]
	v_mfma_f32_16x16x32_bf16 v[116:119], v[140:143], v[164:167], v[116:119]
	v_mfma_f32_16x16x32_bf16 v[112:115], v[148:151], v[164:167], v[112:115]
	v_mfma_f32_16x16x32_bf16 v[104:107], v[140:143], v[172:175], v[104:107]
	v_mfma_f32_16x16x32_bf16 v[96:99], v[148:151], v[172:175], v[96:99]
	v_mfma_f32_16x16x32_bf16 v[88:91], v[140:143], v[180:183], v[88:91]
	v_mfma_f32_16x16x32_bf16 v[80:83], v[148:151], v[180:183], v[80:83]
	s_setprio 0
	s_barrier
	s_mov_b32 m0, s73
	ds_read_b128 v[188:191], v135
	ds_read_b128 v[206:209], v135 offset:1024
	ds_read_b128 v[210:213], v135 offset:2048
	ds_read_b128 v[214:217], v135 offset:3072
	global_load_lds_dwordx4 v128, s[50:51]
	s_mov_b32 m0, s74
	s_nop 0
	global_load_lds_dwordx4 v130, s[50:51]
	s_barrier
	s_waitcnt lgkmcnt(0)
	s_setprio 1
	s_waitcnt lgkmcnt(0)
	v_mfma_f32_16x16x32_bf16 v[108:111], v[188:191], v[152:155], v[108:111]
	v_mfma_f32_16x16x32_bf16 v[100:103], v[210:213], v[152:155], v[100:103]
	v_mfma_f32_16x16x32_bf16 v[92:95], v[188:191], v[160:163], v[92:95]
	v_mfma_f32_16x16x32_bf16 v[84:87], v[210:213], v[160:163], v[84:87]
	v_mfma_f32_16x16x32_bf16 v[76:79], v[188:191], v[168:171], v[76:79]
	v_mfma_f32_16x16x32_bf16 v[72:75], v[210:213], v[168:171], v[72:75]
	v_mfma_f32_16x16x32_bf16 v[68:71], v[188:191], v[176:179], v[68:71]
	v_mfma_f32_16x16x32_bf16 v[64:67], v[210:213], v[176:179], v[64:67]
	v_mfma_f32_16x16x32_bf16 v[108:111], v[206:209], v[156:159], v[108:111]
	v_mfma_f32_16x16x32_bf16 v[100:103], v[214:217], v[156:159], v[100:103]
	v_mfma_f32_16x16x32_bf16 v[92:95], v[206:209], v[164:167], v[92:95]
	v_mfma_f32_16x16x32_bf16 v[84:87], v[214:217], v[164:167], v[84:87]
	v_mfma_f32_16x16x32_bf16 v[76:79], v[206:209], v[172:175], v[76:79]
	v_mfma_f32_16x16x32_bf16 v[72:75], v[214:217], v[172:175], v[72:75]
	v_mfma_f32_16x16x32_bf16 v[68:71], v[206:209], v[180:183], v[68:71]
	v_mfma_f32_16x16x32_bf16 v[64:67], v[214:217], v[180:183], v[64:67]
	s_setprio 0
	s_mov_b32 m0, s11
	s_barrier
	ds_read_b128 v[152:155], v134 offset:16384
	ds_read_b128 v[156:159], v134 offset:17408
	ds_read_b128 v[160:163], v134 offset:18432
	ds_read_b128 v[164:167], v134 offset:19456
	ds_read_b128 v[168:171], v134 offset:20480
	ds_read_b128 v[172:175], v134 offset:21504
	ds_read_b128 v[176:179], v134 offset:22528
	ds_read_b128 v[180:183], v134 offset:23552
	global_load_lds_dwordx4 v128, s[48:49]
	s_mov_b32 m0, s60
	s_nop 0
	global_load_lds_dwordx4 v130, s[48:49]
	s_barrier
	s_waitcnt lgkmcnt(0)
	s_setprio 1
	s_waitcnt lgkmcnt(0)
	v_mfma_f32_16x16x32_bf16 v[60:63], v[136:139], v[152:155], v[60:63]
	v_mfma_f32_16x16x32_bf16 v[56:59], v[144:147], v[152:155], v[56:59]
	v_mfma_f32_16x16x32_bf16 v[52:55], v[136:139], v[160:163], v[52:55]
	v_mfma_f32_16x16x32_bf16 v[48:51], v[144:147], v[160:163], v[48:51]
	v_mfma_f32_16x16x32_bf16 v[40:43], v[136:139], v[168:171], v[40:43]
	v_mfma_f32_16x16x32_bf16 v[32:35], v[144:147], v[168:171], v[32:35]
	v_mfma_f32_16x16x32_bf16 v[24:27], v[136:139], v[176:179], v[24:27]
	v_mfma_f32_16x16x32_bf16 v[16:19], v[144:147], v[176:179], v[16:19]
	v_mfma_f32_16x16x32_bf16 v[60:63], v[140:143], v[156:159], v[60:63]
	v_mfma_f32_16x16x32_bf16 v[56:59], v[148:151], v[156:159], v[56:59]
	v_mfma_f32_16x16x32_bf16 v[52:55], v[140:143], v[164:167], v[52:55]
	v_mfma_f32_16x16x32_bf16 v[48:51], v[148:151], v[164:167], v[48:51]
	v_mfma_f32_16x16x32_bf16 v[40:43], v[140:143], v[172:175], v[40:43]
	v_mfma_f32_16x16x32_bf16 v[32:35], v[148:151], v[172:175], v[32:35]
	v_mfma_f32_16x16x32_bf16 v[24:27], v[140:143], v[180:183], v[24:27]
	v_mfma_f32_16x16x32_bf16 v[16:19], v[148:151], v[180:183], v[16:19]
	s_setprio 0
	s_barrier
; #define PG8_STAGE(bufoff, gbase, voff) do { _Pragma("unroll") for (int _i = 0; _i < 2; ++_i) \
;         __builtin_amdgcn_global_load_lds((const unsigned*)((const char*)(gbase) + (voff)[_i]), (LAS unsigned*)(lds + (bufoff) + ldsw + _i * 8192), 16, 0, 0); } while (0)
; #define PG8_LDA(dst, b, h) do { _Pragma("unroll") for (int m = 0; m < 4; ++m) _Pragma("unroll") for (int k = 0; k < 2; ++k) dst[m][k] = *(const LAS bf16x8*)(lds + PG8_SA(b, h) + aoff + m * 2048 + k * 1024); } while (0)
; #define PG8_LDB(dst, b, h) do { _Pragma("unroll") for (int n = 0; n < 2; ++n) _Pragma("unroll") for (int k = 0; k < 2; ++k) dst[n][k] = *(const LAS bf16x8*)(lds + PG8_SB(b, h) + boff + n * 2048 + k * 1024); } while (0)
; #define PG8_MMA(ai, bj, At, Bt) do { __builtin_amdgcn_s_setprio(1); _Pragma("unroll") for (int m = 0; m < 4; ++m) _Pragma("unroll") for (int n = 0; n < 2; ++n) _Pragma("unroll") for (int k = 0; k < 2; ++k) \
;         acc[ai][bj][m][n] = __builtin_amdgcn_mfma_f32_16x16x32_bf16(Bt[n][k], At[m][k], acc[ai][bj][m][n], 0, 0, 0); __builtin_amdgcn_s_setprio(0); } while (0)
; #define PG8_WAIT_V(n) asm volatile("s_waitcnt vmcnt(" #n ")" ::: "memory")
; #define PG8_WAIT_L(n) asm volatile("s_waitcnt lgkmcnt(" #n ")" ::: "memory")
; #define PG8_BAR __builtin_amdgcn_s_barrier()
; #define PG8_SCHED __builtin_amdgcn_sched_barrier(0)
; template <class Epi, class Sched>
; DI void gemm_phase(LAS unsigned char* lds, const Gemm g, const Sched& S, const Epi& E) {
;     ...
;             PG8_BAR; PG8_WAIT_L(0); PG8_MMA(1, 0, At, B0); PG8_BAR; PG8_SCHED;
;             PG8_STAGE(PG8_SB(0, 1), b2 + hstep, voffB);
;             PG8_WAIT_V(6); PG8_BAR; PG8_MMA(1, 1, At, B1); PG8_BAR;
;             PG8_LDB(B0, 1, 0); PG8_SCHED; PG8_LDA(At, 1, 0); PG8_STAGE(PG8_SA(0, 1), a2 + hstep, voffA);
;             PG8_WAIT_L(8); PG8_BAR; PG8_WAIT_L(0); PG8_MMA(0, 0, At, B0); PG8_BAR; PG8_SCHED;
;             PG8_LDB(B1, 1, 1); PG8_STAGE(PG8_SB(1, 0), b3, voffB);
;             PG8_BAR; PG8_WAIT_L(0); PG8_MMA(0, 1, At, B1); PG8_BAR;
;             PG8_LDA(At, 1, 1); PG8_STAGE(PG8_SA(1, 0), a3, voffA);
;             PG8_BAR; PG8_WAIT_L(0); PG8_MMA(1, 0, At, B0); PG8_BAR; PG8_SCHED;
;             PG8_STAGE(PG8_SB(1, 1), b3 + hstep, voffB);
;             PG8_WAIT_V(6); PG8_BAR; PG8_MMA(1, 1, At, B1); PG8_BAR;
	s_mov_b32 m0, s33
	s_nop 0
	global_load_lds_dwordx4 v128, s[46:47]
	s_mov_b32 m0, s29
	s_nop 0
	global_load_lds_dwordx4 v130, s[46:47]
	s_waitcnt vmcnt(6)
	s_barrier
	s_setprio 1
	v_mfma_f32_16x16x32_bf16 v[44:47], v[188:191], v[152:155], v[44:47]
	v_mfma_f32_16x16x32_bf16 v[36:39], v[210:213], v[152:155], v[36:39]
	v_mfma_f32_16x16x32_bf16 v[28:31], v[188:191], v[160:163], v[28:31]
	v_mfma_f32_16x16x32_bf16 v[20:23], v[210:213], v[160:163], v[20:23]
	v_mfma_f32_16x16x32_bf16 v[12:15], v[188:191], v[168:171], v[12:15]
	v_mfma_f32_16x16x32_bf16 v[8:11], v[210:213], v[168:171], v[8:11]
	v_mfma_f32_16x16x32_bf16 v[4:7], v[188:191], v[176:179], v[4:7]
	v_mfma_f32_16x16x32_bf16 v[0:3], v[210:213], v[176:179], v[0:3]
	v_mfma_f32_16x16x32_bf16 v[44:47], v[206:209], v[156:159], v[44:47]
	v_mfma_f32_16x16x32_bf16 v[36:39], v[214:217], v[156:159], v[36:39]
	v_mfma_f32_16x16x32_bf16 v[28:31], v[206:209], v[164:167], v[28:31]
	v_mfma_f32_16x16x32_bf16 v[20:23], v[214:217], v[164:167], v[20:23]
	v_mfma_f32_16x16x32_bf16 v[12:15], v[206:209], v[172:175], v[12:15]
	v_mfma_f32_16x16x32_bf16 v[8:11], v[214:217], v[172:175], v[8:11]
	v_mfma_f32_16x16x32_bf16 v[4:7], v[206:209], v[180:183], v[4:7]
	v_mfma_f32_16x16x32_bf16 v[0:3], v[214:217], v[180:183], v[0:3]
	s_setprio 0
	v_add_u32_e32 v148, s5, v132
	s_barrier
	ds_read_b128 v[136:139], v148
	ds_read_b128 v[140:143], v148 offset:1024
	ds_read_b128 v[144:147], v148 offset:2048
	ds_read_b128 v[148:151], v148 offset:3072
	s_mov_b32 m0, s61
	ds_read_b128 v[152:155], v134 offset:32768
	ds_read_b128 v[156:159], v134 offset:33792
	ds_read_b128 v[160:163], v134 offset:34816
	ds_read_b128 v[164:167], v134 offset:35840
	ds_read_b128 v[168:171], v134 offset:36864
	ds_read_b128 v[172:175], v134 offset:37888
	ds_read_b128 v[176:179], v134 offset:38912
	ds_read_b128 v[180:183], v134 offset:39936
	global_load_lds_dwordx4 v128, s[44:45]
	s_mov_b32 m0, s62
	s_nop 0
	global_load_lds_dwordx4 v130, s[44:45]
	s_waitcnt lgkmcnt(8)
	s_barrier
	s_waitcnt lgkmcnt(0)
	s_setprio 1
	s_waitcnt lgkmcnt(0)
	v_mfma_f32_16x16x32_bf16 v[124:127], v[136:139], v[152:155], v[124:127]
	v_mfma_f32_16x16x32_bf16 v[120:123], v[144:147], v[152:155], v[120:123]
	v_mfma_f32_16x16x32_bf16 v[116:119], v[136:139], v[160:163], v[116:119]
	v_mfma_f32_16x16x32_bf16 v[112:115], v[144:147], v[160:163], v[112:115]
	v_mfma_f32_16x16x32_bf16 v[104:107], v[136:139], v[168:171], v[104:107]
	v_mfma_f32_16x16x32_bf16 v[96:99], v[144:147], v[168:171], v[96:99]
	v_mfma_f32_16x16x32_bf16 v[88:91], v[136:139], v[176:179], v[88:91]
	v_mfma_f32_16x16x32_bf16 v[80:83], v[144:147], v[176:179], v[80:83]
	v_mfma_f32_16x16x32_bf16 v[124:127], v[140:143], v[156:159], v[124:127]
	v_mfma_f32_16x16x32_bf16 v[120:123], v[148:151], v[156:159], v[120:123]
	v_mfma_f32_16x16x32_bf16 v[116:119], v[140:143], v[164:167], v[116:119]
	v_mfma_f32_16x16x32_bf16 v[112:115], v[148:151], v[164:167], v[112:115]
	v_mfma_f32_16x16x32_bf16 v[104:107], v[140:143], v[172:175], v[104:107]
	v_mfma_f32_16x16x32_bf16 v[96:99], v[148:151], v[172:175], v[96:99]
	v_mfma_f32_16x16x32_bf16 v[88:91], v[140:143], v[180:183], v[88:91]
	v_mfma_f32_16x16x32_bf16 v[80:83], v[148:151], v[180:183], v[80:83]
	s_setprio 0
	s_barrier
	s_add_i32 m0, s4, 0xffffff80
	v_add_u32_e32 v201, s1, v132
	ds_read_b128 v[188:191], v201
	ds_read_b128 v[206:209], v201 offset:1024
	ds_read_b128 v[210:213], v201 offset:2048
	ds_read_b128 v[214:217], v201 offset:3072
	global_load_lds_dwordx4 v128, s[50:51] offset:128
	s_add_i32 m0, s0, 0xffffff80
	s_nop 0
	global_load_lds_dwordx4 v130, s[50:51] offset:128
	s_barrier
	s_waitcnt lgkmcnt(0)
	s_setprio 1
	s_waitcnt lgkmcnt(0)
	v_mfma_f32_16x16x32_bf16 v[108:111], v[188:191], v[152:155], v[108:111]
	v_mfma_f32_16x16x32_bf16 v[100:103], v[210:213], v[152:155], v[100:103]
	v_mfma_f32_16x16x32_bf16 v[92:95], v[188:191], v[160:163], v[92:95]
	v_mfma_f32_16x16x32_bf16 v[84:87], v[210:213], v[160:163], v[84:87]
	v_mfma_f32_16x16x32_bf16 v[76:79], v[188:191], v[168:171], v[76:79]
	v_mfma_f32_16x16x32_bf16 v[72:75], v[210:213], v[168:171], v[72:75]
	v_mfma_f32_16x16x32_bf16 v[68:71], v[188:191], v[176:179], v[68:71]
	v_mfma_f32_16x16x32_bf16 v[64:67], v[210:213], v[176:179], v[64:67]
	v_mfma_f32_16x16x32_bf16 v[108:111], v[206:209], v[156:159], v[108:111]
	v_mfma_f32_16x16x32_bf16 v[100:103], v[214:217], v[156:159], v[100:103]
	v_mfma_f32_16x16x32_bf16 v[92:95], v[206:209], v[164:167], v[92:95]
	v_mfma_f32_16x16x32_bf16 v[84:87], v[214:217], v[164:167], v[84:87]
	v_mfma_f32_16x16x32_bf16 v[76:79], v[206:209], v[172:175], v[76:79]
	v_mfma_f32_16x16x32_bf16 v[72:75], v[214:217], v[172:175], v[72:75]
	v_mfma_f32_16x16x32_bf16 v[68:71], v[206:209], v[180:183], v[68:71]
	v_mfma_f32_16x16x32_bf16 v[64:67], v[214:217], v[180:183], v[64:67]
	s_setprio 0
	s_add_i32 m0, s68, 0xffffff80
	s_barrier
	ds_read_b128 v[152:155], v134 offset:49152
	ds_read_b128 v[156:159], v134 offset:50176
	ds_read_b128 v[160:163], v134 offset:51200
	ds_read_b128 v[164:167], v134 offset:52224
	ds_read_b128 v[168:171], v134 offset:53248
	ds_read_b128 v[172:175], v134 offset:54272
	ds_read_b128 v[176:179], v134 offset:55296
	ds_read_b128 v[180:183], v134 offset:56320
	global_load_lds_dwordx4 v128, s[48:49] offset:128
	s_add_i32 m0, s69, 0xffffff80
	s_nop 0
	global_load_lds_dwordx4 v130, s[48:49] offset:128
	s_barrier
; #define PG8_STAGE(bufoff, gbase, voff) do { _Pragma("unroll") for (int _i = 0; _i < 2; ++_i) \
;         __builtin_amdgcn_global_load_lds((const unsigned*)((const char*)(gbase) + (voff)[_i]), (LAS unsigned*)(lds + (bufoff) + ldsw + _i * 8192), 16, 0, 0); } while (0)
; #define PG8_MMA(ai, bj, At, Bt) do { __builtin_amdgcn_s_setprio(1); _Pragma("unroll") for (int m = 0; m < 4; ++m) _Pragma("unroll") for (int n = 0; n < 2; ++n) _Pragma("unroll") for (int k = 0; k < 2; ++k) \
;         acc[ai][bj][m][n] = __builtin_amdgcn_mfma_f32_16x16x32_bf16(Bt[n][k], At[m][k], acc[ai][bj][m][n], 0, 0, 0); __builtin_amdgcn_s_setprio(0); } while (0)
; #define PG8_WAIT_V(n) asm volatile("s_waitcnt vmcnt(" #n ")" ::: "memory")
; #define PG8_WAIT_L(n) asm volatile("s_waitcnt lgkmcnt(" #n ")" ::: "memory")
; #define PG8_BAR __builtin_amdgcn_s_barrier()
; #define PG8_SCHED __builtin_amdgcn_sched_barrier(0)
; template <class Epi, class Sched>
; DI void gemm_phase(LAS unsigned char* lds, const Gemm g, const Sched& S, const Epi& E) {
;     ...
;             PG8_BAR; PG8_WAIT_L(0); PG8_MMA(1, 0, At, B0); PG8_BAR; PG8_SCHED;
;             PG8_STAGE(PG8_SB(1, 1), b3 + hstep, voffB);
;             PG8_WAIT_V(6); PG8_BAR; PG8_MMA(1, 1, At, B1); PG8_BAR;
;         }
;         { int fr2 = fr, fq2 = fq; asm volatile("" : "+v"(fr2), "+v"(fq2)); E(acc, cur, wr, wc, fr2, fq2); }
;     DI void operator()(AccRef acc, const Unit& u, int wr, int wc, int fr, int fq) const {
;         float* base = P + (size_t)slot0 * 256 * DM + (size_t)u.ks * 256 * ld; const int col0 = u.pn * 256 + wc * 32 + 4 * fq;
; #pragma unroll
;         for (int ai = 0; ai < 2; ++ai)
; #pragma unroll
;             for (int m = 0; m < 4; ++m) { const size_t off = (size_t)(ai * 128 + wr * 64 + m * 16 + fr) * ld + col0;
; #pragma unroll
;                 for (int bj = 0; bj < 2; ++bj)
; #pragma unroll
;                     for (int n = 0; n < 2; ++n) *(f32x4*)(base + off + bj * 128 + n * 16) = acc[ai][bj][m][n]; }
;     }
	s_waitcnt lgkmcnt(0)
	s_setprio 1
	s_waitcnt lgkmcnt(0)
	v_mfma_f32_16x16x32_bf16 v[60:63], v[136:139], v[152:155], v[60:63]
	v_mfma_f32_16x16x32_bf16 v[56:59], v[144:147], v[152:155], v[56:59]
	v_mfma_f32_16x16x32_bf16 v[52:55], v[136:139], v[160:163], v[52:55]
	v_mfma_f32_16x16x32_bf16 v[48:51], v[144:147], v[160:163], v[48:51]
	v_mfma_f32_16x16x32_bf16 v[40:43], v[136:139], v[168:171], v[40:43]
	v_mfma_f32_16x16x32_bf16 v[32:35], v[144:147], v[168:171], v[32:35]
	v_mfma_f32_16x16x32_bf16 v[24:27], v[136:139], v[176:179], v[24:27]
	v_mfma_f32_16x16x32_bf16 v[16:19], v[144:147], v[176:179], v[16:19]
	v_mfma_f32_16x16x32_bf16 v[60:63], v[140:143], v[156:159], v[60:63]
	v_mfma_f32_16x16x32_bf16 v[56:59], v[148:151], v[156:159], v[56:59]
	v_mfma_f32_16x16x32_bf16 v[52:55], v[140:143], v[164:167], v[52:55]
	v_mfma_f32_16x16x32_bf16 v[48:51], v[148:151], v[164:167], v[48:51]
	v_mfma_f32_16x16x32_bf16 v[40:43], v[140:143], v[172:175], v[40:43]
	v_mfma_f32_16x16x32_bf16 v[32:35], v[148:151], v[172:175], v[32:35]
	v_mfma_f32_16x16x32_bf16 v[24:27], v[140:143], v[180:183], v[24:27]
	v_mfma_f32_16x16x32_bf16 v[16:19], v[148:151], v[180:183], v[16:19]
	s_setprio 0
	s_barrier
	s_mov_b32 m0, s76
	s_nop 0
	global_load_lds_dwordx4 v128, s[42:43]
	s_mov_b32 m0, s75
	s_nop 0
	global_load_lds_dwordx4 v130, s[42:43]
	s_waitcnt vmcnt(6)
	s_barrier
	s_setprio 1
	v_mfma_f32_16x16x32_bf16 v[44:47], v[188:191], v[152:155], v[44:47]
	v_mfma_f32_16x16x32_bf16 v[36:39], v[210:213], v[152:155], v[36:39]
	v_mfma_f32_16x16x32_bf16 v[28:31], v[188:191], v[160:163], v[28:31]
	v_mfma_f32_16x16x32_bf16 v[20:23], v[210:213], v[160:163], v[20:23]
	v_mfma_f32_16x16x32_bf16 v[12:15], v[188:191], v[168:171], v[12:15]
	v_mfma_f32_16x16x32_bf16 v[8:11], v[210:213], v[168:171], v[8:11]
	v_mfma_f32_16x16x32_bf16 v[4:7], v[188:191], v[176:179], v[4:7]
	v_mfma_f32_16x16x32_bf16 v[0:3], v[210:213], v[176:179], v[0:3]
	v_mfma_f32_16x16x32_bf16 v[44:47], v[206:209], v[156:159], v[44:47]
	v_mfma_f32_16x16x32_bf16 v[36:39], v[214:217], v[156:159], v[36:39]
	v_mfma_f32_16x16x32_bf16 v[28:31], v[206:209], v[164:167], v[28:31]
	v_mfma_f32_16x16x32_bf16 v[20:23], v[214:217], v[164:167], v[20:23]
	v_mfma_f32_16x16x32_bf16 v[12:15], v[206:209], v[172:175], v[12:15]
	v_mfma_f32_16x16x32_bf16 v[8:11], v[214:217], v[172:175], v[8:11]
	v_mfma_f32_16x16x32_bf16 v[4:7], v[206:209], v[180:183], v[4:7]
	v_mfma_f32_16x16x32_bf16 v[0:3], v[214:217], v[180:183], v[0:3]
	s_setprio 0
	s_movk_i32 s0, 0x100
	s_andn2_b64 vcc, exec, s[40:41]
	s_mov_b64 s[42:43], -1
	s_mov_b64 s[40:41], 0
	s_barrier
	s_cbranch_vccz .LBB0_1535
	s_ashr_i32 s13, s12, 31
	s_lshl_b64 s[0:1], s[12:13], 21
	s_add_u32 s0, s66, s0
	v_mov_b32_e32 v137, v194
	v_mov_b32_e32 v136, v192
	s_addc_u32 s1, s67, s1
	s_lshl_b32 s4, s10, 8
	s_or_b32 s4, s4, s65
	v_lshl_add_u32 v136, v136, 2, s4
	v_add_u32_e32 v138, s64, v137
	v_ashrrev_i32_e32 v137, 31, v136
	v_ashrrev_i32_e32 v139, 31, v138
	v_lshl_add_u64 v[136:137], v[136:137], 2, s[0:1]
	v_lshlrev_b64 v[140:141], 13, v[138:139]
	v_lshl_add_u64 v[140:141], v[136:137], 0, v[140:141]
	global_store_dwordx4 v[140:141], v[124:127], off
	global_store_dwordx4 v[140:141], v[120:123], off offset:64
	global_store_dwordx4 v[140:141], v[108:111], off offset:512
	global_store_dwordx4 v[140:141], v[100:103], off offset:576
	s_and_b64 vcc, exec, s[30:31]
	s_mov_b32 s12, s18
	v_add_u32_e32 v100, 16, v138
	v_ashrrev_i32_e32 v101, 31, v100
	v_lshlrev_b64 v[100:101], 13, v[100:101]
	v_lshl_add_u64 v[100:101], v[136:137], 0, v[100:101]
	global_store_dwordx4 v[100:101], v[116:119], off
	global_store_dwordx4 v[100:101], v[112:115], off offset:64
	global_store_dwordx4 v[100:101], v[92:95], off offset:512
	global_store_dwordx4 v[100:101], v[84:87], off offset:576
	s_mov_b32 s10, s28
	s_mov_b64 s[14:15], s[38:39]
	v_add_u32_e32 v84, 32, v138
	v_ashrrev_i32_e32 v85, 31, v84
	v_lshlrev_b64 v[84:85], 13, v[84:85]
	v_lshl_add_u64 v[84:85], v[136:137], 0, v[84:85]
	global_store_dwordx4 v[84:85], v[104:107], off
	global_store_dwordx4 v[84:85], v[96:99], off offset:64
	global_store_dwordx4 v[84:85], v[76:79], off offset:512
	global_store_dwordx4 v[84:85], v[72:75], off offset:576
	s_mov_b64 s[16:17], s[36:37]
	s_nop 0
	v_add_u32_e32 v72, 48, v138
	v_ashrrev_i32_e32 v73, 31, v72
	v_lshlrev_b64 v[72:73], 13, v[72:73]
	v_lshl_add_u64 v[72:73], v[136:137], 0, v[72:73]
	global_store_dwordx4 v[72:73], v[88:91], off
	global_store_dwordx4 v[72:73], v[80:83], off offset:64
	global_store_dwordx4 v[72:73], v[68:71], off offset:512
	global_store_dwordx4 v[72:73], v[64:67], off offset:576
	s_nop 1
	v_add_u32_e32 v64, 0x80, v138
	v_ashrrev_i32_e32 v65, 31, v64
	v_lshlrev_b64 v[64:65], 13, v[64:65]
	v_lshl_add_u64 v[64:65], v[136:137], 0, v[64:65]
	global_store_dwordx4 v[64:65], v[60:63], off
	global_store_dwordx4 v[64:65], v[56:59], off offset:64
	global_store_dwordx4 v[64:65], v[44:47], off offset:512
	global_store_dwordx4 v[64:65], v[36:39], off offset:576
	s_nop 1
	v_add_u32_e32 v36, 0x90, v138
	v_ashrrev_i32_e32 v37, 31, v36
	v_lshlrev_b64 v[36:37], 13, v[36:37]
	v_lshl_add_u64 v[36:37], v[136:137], 0, v[36:37]
	global_store_dwordx4 v[36:37], v[52:55], off
	global_store_dwordx4 v[36:37], v[48:51], off offset:64
	global_store_dwordx4 v[36:37], v[28:31], off offset:512
	global_store_dwordx4 v[36:37], v[20:23], off offset:576
	s_nop 1
	v_add_u32_e32 v20, 0xa0, v138
	v_ashrrev_i32_e32 v21, 31, v20
	v_lshlrev_b64 v[20:21], 13, v[20:21]
	v_lshl_add_u64 v[20:21], v[136:137], 0, v[20:21]
	global_store_dwordx4 v[20:21], v[40:43], off
	global_store_dwordx4 v[20:21], v[32:35], off offset:64
	global_store_dwordx4 v[20:21], v[12:15], off offset:512
	global_store_dwordx4 v[20:21], v[8:11], off offset:576
	s_nop 1
	v_add_u32_e32 v8, 0xb0, v138
	v_ashrrev_i32_e32 v9, 31, v8
	v_lshlrev_b64 v[8:9], 13, v[8:9]
	v_lshl_add_u64 v[8:9], v[136:137], 0, v[8:9]
	global_store_dwordx4 v[8:9], v[24:27], off
	global_store_dwordx4 v[8:9], v[16:19], off offset:64
	global_store_dwordx4 v[8:9], v[4:7], off offset:512
	global_store_dwordx4 v[8:9], v[0:3], off offset:576
	s_cbranch_vccz .LBB0_1532
	s_waitcnt vmcnt(0)
	s_cmpk_gt_u32 s34, 0xff
	s_cbranch_scc1 .LBB0_1539
	s_barrier

; #define PG8_STAGE(bufoff, gbase, voff) do { _Pragma("unroll") for (int _i = 0; _i < 2; ++_i) \
;         __builtin_amdgcn_global_load_lds((const unsigned*)((const char*)(gbase) + (voff)[_i]), (LAS unsigned*)(lds + (bufoff) + ldsw + _i * 8192), 16, 0, 0); } while (0)
; #define PG8_WAIT_V(n) asm volatile("s_waitcnt vmcnt(" #n ")" ::: "memory")
; #define PG8_BAR __builtin_amdgcn_s_barrier()
; template <class Epi, class Sched>
; DI void gemm_phase(LAS unsigned char* lds, const Gemm g, const Sched& S, const Epi& E) {
;     ...
;     PG8_STAGE(PG8_SB(0, 0), cB, voffB); PG8_STAGE(PG8_SA(0, 0), cA, voffA); PG8_STAGE(PG8_SB(0, 1), cB + hstep, voffB); PG8_STAGE(PG8_SA(0, 1), cA + hstep, voffA);
;     if (wr == 1) PG8_BAR;
;     PG8_WAIT_V(4); PG8_BAR;
;     PG8_STAGE(PG8_SB(1, 0), cB + kstep, voffB); PG8_STAGE(PG8_SA(1, 0), cA + kstep, voffA); PG8_STAGE(PG8_SB(1, 1), cB + hstep + kstep, voffB);
;     PG8_WAIT_V(6); PG8_BAR;
;     DI void operator()(AccRef acc, const Unit& u, int wr, int wc, int fr, int fq) const {
;         const int row0 = u.pm * 256 + wr * 64 + fr, col0 = u.pn * 128 + wc * 32 + 8 * fq;
.LBB0_1660:
	s_add_u32 s12, s22, 0x107c3000
	s_addc_u32 s13, s23, 0
	s_add_u32 s14, s22, 0x142800
	s_addc_u32 s15, s23, 0
	s_lshl_b32 s0, s0, 5
	s_mov_b64 s[16:17], 0x80
	s_and_b32 s56, s0, 0x60
	s_add_i32 m0, s39, 0x18000
	v_lshl_add_u64 v[6:7], v[6:7], 0, s[16:17]
	s_ashr_i32 s54, s26, 31
	s_lshl_b32 s55, s1, 6
	s_lshl_b32 s4, s1, 13
	s_lshl_b32 s5, s56, 7
	s_waitcnt vmcnt(4)
	s_barrier
	global_load_lds_dwordx4 v[6:7], off
	v_lshl_add_u64 v[4:5], v[4:5], 0, s[16:17]
	s_add_i32 m0, s39, 0x1a000
	s_add_i32 s57, s39, 0x8000
	s_add_i32 s58, s39, 0xa000
	global_load_lds_dwordx4 v[4:5], off
	v_lshl_add_u64 v[2:3], v[2:3], 0, s[16:17]
	s_mov_b32 m0, s57
	s_add_u32 s0, s40, 0x80080
	global_load_lds_dwordx4 v[2:3], off
	v_lshl_add_u64 v[0:1], v[0:1], 0, s[16:17]
	s_mov_b32 m0, s58
	s_addc_u32 s1, s41, 0
	global_load_lds_dwordx4 v[0:1], off
	s_add_i32 m0, s39, 0x1c000
	s_nop 0
	global_load_lds_dwordx4 v130, s[0:1]
	v_lshl_add_u64 v[0:1], s[0:1], 0, v[134:135]
	s_add_i32 m0, s39, 0x1e000
	s_movk_i32 s0, 0x3c0
	global_load_lds_dwordx4 v[0:1], off
	v_and_or_b32 v0, v199, s0, v195
	v_and_b32_e32 v1, 32, v185
	v_lshl_or_b32 v2, v194, 6, v195
	v_bitop3_b32 v148, s5, v0, v1 bitop3:0xf6
	v_lshlrev_b32_e32 v0, 9, v184
	v_bitop3_b32 v2, v2, s4, v1 bitop3:0xde
	v_and_b32_e32 v0, 0x70000, v0
	v_lshlrev_b32_e32 v1, 12, v197
	v_or3_b32 v0, v8, v0, v1
	v_add_u32_e32 v136, v0, v196
	v_lshlrev_b32_e32 v0, 5, v9
	s_waitcnt vmcnt(6)
	v_and_b32_e32 v0, 0xf0000, v0
	v_or3_b32 v0, v8, v0, v1
	s_add_i32 s61, 0, 0x10000
	s_add_i32 s62, 0, 0x14000
	s_sext_i32_i16 s34, s6
	s_mov_b32 s59, s26
	s_mov_b32 s60, 0
	v_mov_b32_e32 v137, v131
	v_add_u32_e32 v138, v0, v196
	v_mov_b32_e32 v139, v131
	v_mov_b64_e32 v[140:141], 0x162c
	v_mov_b64_e32 v[142:143], 0x162b
	v_add_u32_e32 v149, s61, v148
	v_add_u32_e32 v150, 0, v2
	v_add_u32_e32 v151, s62, v148
	v_mov_b32_e32 v153, 0x358637bd
	s_mov_b32 s63, 0xf800000
	v_mov_b32_e32 v154, 0x260
	s_movk_i32 s64, 0x2c00
	s_barrier

; #define PG8_STAGE(bufoff, gbase, voff) do { _Pragma("unroll") for (int _i = 0; _i < 2; ++_i) \
;         __builtin_amdgcn_global_load_lds((const unsigned*)((const char*)(gbase) + (voff)[_i]), (LAS unsigned*)(lds + (bufoff) + ldsw + _i * 8192), 16, 0, 0); } while (0)
; #define PG8_LDA(dst, b, h) do { _Pragma("unroll") for (int m = 0; m < 4; ++m) _Pragma("unroll") for (int k = 0; k < 2; ++k) dst[m][k] = *(const LAS bf16x8*)(lds + PG8_SA(b, h) + aoff + m * 2048 + k * 1024); } while (0)
; #define PG8_LDB(dst, b, h) do { _Pragma("unroll") for (int n = 0; n < 2; ++n) _Pragma("unroll") for (int k = 0; k < 2; ++k) dst[n][k] = *(const LAS bf16x8*)(lds + PG8_SB(b, h) + boff + n * 2048 + k * 1024); } while (0)
; #define PG8_MMA(ai, bj, At, Bt) do { __builtin_amdgcn_s_setprio(1); _Pragma("unroll") for (int m = 0; m < 4; ++m) _Pragma("unroll") for (int n = 0; n < 2; ++n) _Pragma("unroll") for (int k = 0; k < 2; ++k) \
;         acc[ai][bj][m][n] = __builtin_amdgcn_mfma_f32_16x16x32_bf16(Bt[n][k], At[m][k], acc[ai][bj][m][n], 0, 0, 0); __builtin_amdgcn_s_setprio(0); } while (0)
; #define PG8_WAIT_V(n) asm volatile("s_waitcnt vmcnt(" #n ")" ::: "memory")
; #define PG8_WAIT_L(n) asm volatile("s_waitcnt lgkmcnt(" #n ")" ::: "memory")
; #define PG8_BAR __builtin_amdgcn_s_barrier()
; #define PG8_SCHED __builtin_amdgcn_sched_barrier(0)
; template <class Epi, class Sched>
; DI void gemm_phase(LAS unsigned char* lds, const Gemm g, const Sched& S, const Epi& E) {
;     ...
;             PG8_LDB(B0, 0, 0); PG8_SCHED; PG8_LDA(At, 0, 0); PG8_STAGE(PG8_SA(1, 1), a1 + hstep, voffA);
;             PG8_WAIT_L(8); PG8_BAR; PG8_WAIT_L(0); PG8_MMA(0, 0, At, B0); PG8_BAR; PG8_SCHED;
;             PG8_LDB(B1, 0, 1); PG8_STAGE(PG8_SB(0, 0), b2, voffB);
;             PG8_BAR; PG8_WAIT_L(0); PG8_MMA(0, 1, At, B1); PG8_BAR;
;             PG8_LDA(At, 0, 1); PG8_STAGE(PG8_SA(0, 0), a2, voffA);
;             PG8_BAR; PG8_WAIT_L(0); PG8_MMA(1, 0, At, B0); PG8_BAR; PG8_SCHED;
;             PG8_STAGE(PG8_SB(0, 1), b2 + hstep, voffB);
;             PG8_WAIT_V(6); PG8_BAR; PG8_MMA(1, 1, At, B1); PG8_BAR;
;             PG8_LDB(B0, 1, 0); PG8_SCHED; PG8_LDA(At, 1, 0); PG8_STAGE(PG8_SA(0, 1), a2 + hstep, voffA);
;             PG8_WAIT_L(8); PG8_BAR; PG8_WAIT_L(0); PG8_MMA(0, 0, At, B0); PG8_BAR; PG8_SCHED;
.LBB0_1667:
	s_ashr_i32 s29, s28, 31
	s_lshl_b64 s[0:1], s[28:29], 20
	s_add_u32 s30, s45, s0
	v_cmp_lt_i64_e32 vcc, s[8:9], v[140:141]
	s_addc_u32 s31, s46, s1
	s_and_b64 s[0:1], vcc, exec
	s_cselect_b32 s29, s31, s43
	s_cselect_b32 s35, s30, s42
	s_ashr_i32 s19, s18, 31
	s_lshl_b64 s[0:1], s[18:19], 20
	s_add_u32 s36, s47, s0
	s_addc_u32 s37, s48, s1
	s_and_b64 s[0:1], vcc, exec
	s_cselect_b32 s19, s37, s41
	s_cselect_b32 s65, s36, s40
	s_add_u32 s8, s42, 0x80080
	s_addc_u32 s9, s43, 0
	s_add_u32 s66, s40, 0x100
	v_mov_b32_e32 v8, 0
	s_addc_u32 s67, s41, 0
	s_mov_b32 s68, -2
	ds_read_b128 v[144:147], v149
	ds_read_b128 v[156:159], v149 offset:1024
	ds_read_b128 v[160:163], v149 offset:2048
	ds_read_b128 v[164:167], v149 offset:3072
	s_add_u32 s0, s8, 0xfff80080
	s_addc_u32 s1, s9, -1
	s_cmp_eq_u32 s68, 28
	s_cselect_b32 s43, s29, s1
	s_cselect_b32 s42, s35, s0
	s_cselect_b32 s41, s19, s67
	s_cselect_b32 s40, s65, s66
	s_add_i32 m0, s39, 0xc000
	ds_read_b128 v[168:171], v150
	ds_read_b128 v[172:175], v150 offset:1024
	ds_read_b128 v[176:179], v150 offset:2048
	ds_read_b128 v[180:183], v150 offset:3072
	ds_read_b128 v[188:191], v150 offset:4096
	ds_read_b128 v[206:209], v150 offset:5120
	ds_read_b128 v[210:213], v150 offset:6144
	ds_read_b128 v[214:217], v150 offset:7168
	global_load_lds_dwordx4 v136, s[8:9]
	s_add_i32 m0, s39, 0xe000
	s_nop 0
	global_load_lds_dwordx4 v138, s[8:9]
	s_waitcnt lgkmcnt(8)
	s_barrier
	s_waitcnt lgkmcnt(0)
	s_setprio 1
	s_waitcnt lgkmcnt(0)
	v_mfma_f32_16x16x32_bf16 v[116:119], v[144:147], v[168:171], 0
	v_mfma_f32_16x16x32_bf16 v[112:115], v[160:163], v[168:171], 0
	v_mfma_f32_16x16x32_bf16 v[100:103], v[144:147], v[176:179], 0
	v_mfma_f32_16x16x32_bf16 v[96:99], v[160:163], v[176:179], 0
	v_mfma_f32_16x16x32_bf16 v[84:87], v[144:147], v[188:191], 0
	v_mfma_f32_16x16x32_bf16 v[80:83], v[160:163], v[188:191], 0
	v_mfma_f32_16x16x32_bf16 v[68:71], v[144:147], v[210:213], 0
	v_mfma_f32_16x16x32_bf16 v[64:67], v[160:163], v[210:213], 0
	v_mfma_f32_16x16x32_bf16 v[116:119], v[156:159], v[172:175], v[116:119]
	v_mfma_f32_16x16x32_bf16 v[112:115], v[164:167], v[172:175], v[112:115]
	v_mfma_f32_16x16x32_bf16 v[100:103], v[156:159], v[180:183], v[100:103]
	v_mfma_f32_16x16x32_bf16 v[96:99], v[164:167], v[180:183], v[96:99]
	v_mfma_f32_16x16x32_bf16 v[84:87], v[156:159], v[206:209], v[84:87]
	v_mfma_f32_16x16x32_bf16 v[80:83], v[164:167], v[206:209], v[80:83]
	v_mfma_f32_16x16x32_bf16 v[68:71], v[156:159], v[214:217], v[68:71]
	v_mfma_f32_16x16x32_bf16 v[64:67], v[164:167], v[214:217], v[64:67]
	s_setprio 0
	s_barrier
	s_add_i32 s0, s61, s50
	s_mov_b32 m0, s0
	ds_read_b128 v[218:221], v151
	ds_read_b128 v[222:225], v151 offset:1024
	ds_read_b128 v[226:229], v151 offset:2048
	ds_read_b128 v[230:233], v151 offset:3072
	global_load_lds_dwordx4 v130, s[40:41]
	s_add_i32 m0, s0, 0x2000
	s_nop 0
	global_load_lds_dwordx4 v134, s[40:41]
	s_barrier
	s_waitcnt lgkmcnt(0)
	s_setprio 1
	s_waitcnt lgkmcnt(0)
	v_mfma_f32_16x16x32_bf16 v[124:127], v[218:221], v[168:171], 0
	v_mfma_f32_16x16x32_bf16 v[120:123], v[226:229], v[168:171], 0
	v_mfma_f32_16x16x32_bf16 v[108:111], v[218:221], v[176:179], 0
	v_mfma_f32_16x16x32_bf16 v[104:107], v[226:229], v[176:179], 0
	v_mfma_f32_16x16x32_bf16 v[92:95], v[218:221], v[188:191], 0
	v_mfma_f32_16x16x32_bf16 v[88:91], v[226:229], v[188:191], 0
	v_mfma_f32_16x16x32_bf16 v[76:79], v[218:221], v[210:213], 0
	v_mfma_f32_16x16x32_bf16 v[72:75], v[226:229], v[210:213], 0
	v_mfma_f32_16x16x32_bf16 v[124:127], v[222:225], v[172:175], v[124:127]
	v_mfma_f32_16x16x32_bf16 v[120:123], v[230:233], v[172:175], v[120:123]
	v_mfma_f32_16x16x32_bf16 v[108:111], v[222:225], v[180:183], v[108:111]
	v_mfma_f32_16x16x32_bf16 v[104:107], v[230:233], v[180:183], v[104:107]
	v_mfma_f32_16x16x32_bf16 v[92:95], v[222:225], v[206:209], v[92:95]
	v_mfma_f32_16x16x32_bf16 v[88:91], v[230:233], v[206:209], v[88:91]
	v_mfma_f32_16x16x32_bf16 v[76:79], v[222:225], v[214:217], v[76:79]
	v_mfma_f32_16x16x32_bf16 v[72:75], v[230:233], v[214:217], v[72:75]
	s_setprio 0
	s_mov_b32 m0, s39
	s_barrier
	ds_read_b128 v[168:171], v150 offset:16384
	ds_read_b128 v[172:175], v150 offset:17408
	ds_read_b128 v[176:179], v150 offset:18432
	ds_read_b128 v[180:183], v150 offset:19456
	ds_read_b128 v[188:191], v150 offset:20480
	ds_read_b128 v[206:209], v150 offset:21504
	ds_read_b128 v[210:213], v150 offset:22528
	ds_read_b128 v[214:217], v150 offset:23552
	global_load_lds_dwordx4 v128, s[42:43]
	s_mov_b32 m0, s51
	s_nop 0
	global_load_lds_dwordx4 v132, s[42:43]
	s_barrier
	s_waitcnt lgkmcnt(0)
	s_setprio 1
	s_waitcnt lgkmcnt(0)
	v_mfma_f32_16x16x32_bf16 v[52:55], v[144:147], v[168:171], 0
	v_mfma_f32_16x16x32_bf16 v[48:51], v[160:163], v[168:171], 0
	v_mfma_f32_16x16x32_bf16 v[36:39], v[144:147], v[176:179], 0
	v_mfma_f32_16x16x32_bf16 v[32:35], v[160:163], v[176:179], 0
	v_mfma_f32_16x16x32_bf16 v[20:23], v[144:147], v[188:191], 0
	v_mfma_f32_16x16x32_bf16 v[16:19], v[160:163], v[188:191], 0
	v_mfma_f32_16x16x32_bf16 v[4:7], v[144:147], v[210:213], 0
	v_mfma_f32_16x16x32_bf16 v[0:3], v[160:163], v[210:213], 0
	v_mfma_f32_16x16x32_bf16 v[52:55], v[156:159], v[172:175], v[52:55]
	v_mfma_f32_16x16x32_bf16 v[48:51], v[164:167], v[172:175], v[48:51]
	v_mfma_f32_16x16x32_bf16 v[36:39], v[156:159], v[180:183], v[36:39]
	v_mfma_f32_16x16x32_bf16 v[32:35], v[164:167], v[180:183], v[32:35]
	v_mfma_f32_16x16x32_bf16 v[20:23], v[156:159], v[206:209], v[20:23]
	v_mfma_f32_16x16x32_bf16 v[16:19], v[164:167], v[206:209], v[16:19]
	v_mfma_f32_16x16x32_bf16 v[4:7], v[156:159], v[214:217], v[4:7]
	v_mfma_f32_16x16x32_bf16 v[0:3], v[164:167], v[214:217], v[0:3]
	s_setprio 0
	s_barrier
; #define PG8_STAGE(bufoff, gbase, voff) do { _Pragma("unroll") for (int _i = 0; _i < 2; ++_i) \
;         __builtin_amdgcn_global_load_lds((const unsigned*)((const char*)(gbase) + (voff)[_i]), (LAS unsigned*)(lds + (bufoff) + ldsw + _i * 8192), 16, 0, 0); } while (0)
; #define PG8_LDA(dst, b, h) do { _Pragma("unroll") for (int m = 0; m < 4; ++m) _Pragma("unroll") for (int k = 0; k < 2; ++k) dst[m][k] = *(const LAS bf16x8*)(lds + PG8_SA(b, h) + aoff + m * 2048 + k * 1024); } while (0)
; #define PG8_LDB(dst, b, h) do { _Pragma("unroll") for (int n = 0; n < 2; ++n) _Pragma("unroll") for (int k = 0; k < 2; ++k) dst[n][k] = *(const LAS bf16x8*)(lds + PG8_SB(b, h) + boff + n * 2048 + k * 1024); } while (0)
; #define PG8_MMA(ai, bj, At, Bt) do { __builtin_amdgcn_s_setprio(1); _Pragma("unroll") for (int m = 0; m < 4; ++m) _Pragma("unroll") for (int n = 0; n < 2; ++n) _Pragma("unroll") for (int k = 0; k < 2; ++k) \
;         acc[ai][bj][m][n] = __builtin_amdgcn_mfma_f32_16x16x32_bf16(Bt[n][k], At[m][k], acc[ai][bj][m][n], 0, 0, 0); __builtin_amdgcn_s_setprio(0); } while (0)
; #define PG8_WAIT_V(n) asm volatile("s_waitcnt vmcnt(" #n ")" ::: "memory")
; #define PG8_WAIT_L(n) asm volatile("s_waitcnt lgkmcnt(" #n ")" ::: "memory")
; #define PG8_BAR __builtin_amdgcn_s_barrier()
; #define PG8_SCHED __builtin_amdgcn_sched_barrier(0)
; template <class Epi, class Sched>
; DI void gemm_phase(LAS unsigned char* lds, const Gemm g, const Sched& S, const Epi& E) {
;     ...
;             PG8_BAR; PG8_WAIT_L(0); PG8_MMA(1, 0, At, B0); PG8_BAR; PG8_SCHED;
;             PG8_STAGE(PG8_SB(0, 1), b2 + hstep, voffB);
;             PG8_WAIT_V(6); PG8_BAR; PG8_MMA(1, 1, At, B1); PG8_BAR;
;             PG8_LDB(B0, 1, 0); PG8_SCHED; PG8_LDA(At, 1, 0); PG8_STAGE(PG8_SA(0, 1), a2 + hstep, voffA);
;             PG8_WAIT_L(8); PG8_BAR; PG8_WAIT_L(0); PG8_MMA(0, 0, At, B0); PG8_BAR; PG8_SCHED;
;             PG8_LDB(B1, 1, 1); PG8_STAGE(PG8_SB(1, 0), b3, voffB);
;             PG8_BAR; PG8_WAIT_L(0); PG8_MMA(0, 1, At, B1); PG8_BAR;
;             PG8_LDA(At, 1, 1); PG8_STAGE(PG8_SA(1, 0), a3, voffA);
;             PG8_BAR; PG8_WAIT_L(0); PG8_MMA(1, 0, At, B0); PG8_BAR; PG8_SCHED;
;             PG8_STAGE(PG8_SB(1, 1), b3 + hstep, voffB);
;             PG8_WAIT_V(6); PG8_BAR; PG8_MMA(1, 1, At, B1); PG8_BAR;
	s_add_u32 s0, s40, 0x80000
	s_addc_u32 s1, s41, 0
	s_add_i32 s4, s62, s50
	s_mov_b32 m0, s4
	s_nop 0
	global_load_lds_dwordx4 v130, s[0:1]
	s_add_i32 m0, s4, 0x2000
	s_nop 0
	global_load_lds_dwordx4 v134, s[0:1]
	s_waitcnt vmcnt(6)
	s_barrier
	s_setprio 1
	v_mfma_f32_16x16x32_bf16 v[60:63], v[218:221], v[168:171], 0
	v_mfma_f32_16x16x32_bf16 v[56:59], v[226:229], v[168:171], 0
	v_mfma_f32_16x16x32_bf16 v[44:47], v[218:221], v[176:179], 0
	v_mfma_f32_16x16x32_bf16 v[40:43], v[226:229], v[176:179], 0
	v_mfma_f32_16x16x32_bf16 v[28:31], v[218:221], v[188:191], 0
	v_mfma_f32_16x16x32_bf16 v[24:27], v[226:229], v[188:191], 0
	v_mfma_f32_16x16x32_bf16 v[12:15], v[218:221], v[210:213], 0
	v_mfma_f32_16x16x32_bf16 v[8:11], v[226:229], v[210:213], 0
	v_mfma_f32_16x16x32_bf16 v[60:63], v[222:225], v[172:175], v[60:63]
	v_mfma_f32_16x16x32_bf16 v[56:59], v[230:233], v[172:175], v[56:59]
	v_mfma_f32_16x16x32_bf16 v[44:47], v[222:225], v[180:183], v[44:47]
	v_mfma_f32_16x16x32_bf16 v[40:43], v[230:233], v[180:183], v[40:43]
	v_mfma_f32_16x16x32_bf16 v[28:31], v[222:225], v[206:209], v[28:31]
	v_mfma_f32_16x16x32_bf16 v[24:27], v[230:233], v[206:209], v[24:27]
	v_mfma_f32_16x16x32_bf16 v[12:15], v[222:225], v[214:217], v[12:15]
	v_mfma_f32_16x16x32_bf16 v[8:11], v[230:233], v[214:217], v[8:11]
	s_setprio 0
	s_add_i32 s4, 0, 0x18000
	v_add_u32_e32 v155, s4, v148
	s_barrier
	ds_read_b128 v[144:147], v155
	ds_read_b128 v[156:159], v155 offset:1024
	ds_read_b128 v[160:163], v155 offset:2048
	ds_read_b128 v[164:167], v155 offset:3072
	s_add_u32 s0, s42, 0x80000
	s_addc_u32 s1, s43, 0
	s_mov_b32 m0, s52
	ds_read_b128 v[168:171], v150 offset:32768
	ds_read_b128 v[172:175], v150 offset:33792
	ds_read_b128 v[176:179], v150 offset:34816
	ds_read_b128 v[180:183], v150 offset:35840
	ds_read_b128 v[188:191], v150 offset:36864
	ds_read_b128 v[206:209], v150 offset:37888
	ds_read_b128 v[210:213], v150 offset:38912
	ds_read_b128 v[214:217], v150 offset:39936
	global_load_lds_dwordx4 v128, s[0:1]
	s_mov_b32 m0, s53
	s_nop 0
	global_load_lds_dwordx4 v132, s[0:1]
	s_waitcnt lgkmcnt(8)
	s_barrier
	s_waitcnt lgkmcnt(0)
	s_setprio 1
	s_waitcnt lgkmcnt(0)
	v_mfma_f32_16x16x32_bf16 v[116:119], v[144:147], v[168:171], v[116:119]
	v_mfma_f32_16x16x32_bf16 v[112:115], v[160:163], v[168:171], v[112:115]
	v_mfma_f32_16x16x32_bf16 v[100:103], v[144:147], v[176:179], v[100:103]
	v_mfma_f32_16x16x32_bf16 v[96:99], v[160:163], v[176:179], v[96:99]
	v_mfma_f32_16x16x32_bf16 v[84:87], v[144:147], v[188:191], v[84:87]
	v_mfma_f32_16x16x32_bf16 v[80:83], v[160:163], v[188:191], v[80:83]
	v_mfma_f32_16x16x32_bf16 v[68:71], v[144:147], v[210:213], v[68:71]
	v_mfma_f32_16x16x32_bf16 v[64:67], v[160:163], v[210:213], v[64:67]
	v_mfma_f32_16x16x32_bf16 v[116:119], v[156:159], v[172:175], v[116:119]
	v_mfma_f32_16x16x32_bf16 v[112:115], v[164:167], v[172:175], v[112:115]
	v_mfma_f32_16x16x32_bf16 v[100:103], v[156:159], v[180:183], v[100:103]
	v_mfma_f32_16x16x32_bf16 v[96:99], v[164:167], v[180:183], v[96:99]
	v_mfma_f32_16x16x32_bf16 v[84:87], v[156:159], v[206:209], v[84:87]
	v_mfma_f32_16x16x32_bf16 v[80:83], v[164:167], v[206:209], v[80:83]
	v_mfma_f32_16x16x32_bf16 v[68:71], v[156:159], v[214:217], v[68:71]
	v_mfma_f32_16x16x32_bf16 v[64:67], v[164:167], v[214:217], v[64:67]
	s_setprio 0
	s_barrier
	s_add_i32 s5, 0, 0x1c000
	s_add_i32 s0, s4, s50
	v_add_u32_e32 v155, s5, v148
	s_add_i32 m0, s0, 0xffffff80
	ds_read_b128 v[218:221], v155
	ds_read_b128 v[222:225], v155 offset:1024
	ds_read_b128 v[226:229], v155 offset:2048
	ds_read_b128 v[230:233], v155 offset:3072
	global_load_lds_dwordx4 v130, s[40:41] offset:128
	s_add_i32 m0, s0, 0x1f80
	s_nop 0
	global_load_lds_dwordx4 v134, s[40:41] offset:128
	s_barrier
	s_waitcnt lgkmcnt(0)
	s_setprio 1
	s_waitcnt lgkmcnt(0)
	v_mfma_f32_16x16x32_bf16 v[124:127], v[218:221], v[168:171], v[124:127]
	v_mfma_f32_16x16x32_bf16 v[120:123], v[226:229], v[168:171], v[120:123]
	v_mfma_f32_16x16x32_bf16 v[108:111], v[218:221], v[176:179], v[108:111]
	v_mfma_f32_16x16x32_bf16 v[104:107], v[226:229], v[176:179], v[104:107]
	v_mfma_f32_16x16x32_bf16 v[92:95], v[218:221], v[188:191], v[92:95]
	v_mfma_f32_16x16x32_bf16 v[88:91], v[226:229], v[188:191], v[88:91]
	v_mfma_f32_16x16x32_bf16 v[76:79], v[218:221], v[210:213], v[76:79]
	v_mfma_f32_16x16x32_bf16 v[72:75], v[226:229], v[210:213], v[72:75]
	v_mfma_f32_16x16x32_bf16 v[124:127], v[222:225], v[172:175], v[124:127]
	v_mfma_f32_16x16x32_bf16 v[120:123], v[230:233], v[172:175], v[120:123]
	v_mfma_f32_16x16x32_bf16 v[108:111], v[222:225], v[180:183], v[108:111]
	v_mfma_f32_16x16x32_bf16 v[104:107], v[230:233], v[180:183], v[104:107]
	v_mfma_f32_16x16x32_bf16 v[92:95], v[222:225], v[206:209], v[92:95]
	v_mfma_f32_16x16x32_bf16 v[88:91], v[230:233], v[206:209], v[88:91]
	v_mfma_f32_16x16x32_bf16 v[76:79], v[222:225], v[214:217], v[76:79]
	v_mfma_f32_16x16x32_bf16 v[72:75], v[230:233], v[214:217], v[72:75]
	s_setprio 0
	s_add_i32 m0, s57, 0xffffff80
	s_barrier
	ds_read_b128 v[168:171], v150 offset:49152
	ds_read_b128 v[172:175], v150 offset:50176
	ds_read_b128 v[176:179], v150 offset:51200
	ds_read_b128 v[180:183], v150 offset:52224
	ds_read_b128 v[188:191], v150 offset:53248
	ds_read_b128 v[206:209], v150 offset:54272
	ds_read_b128 v[210:213], v150 offset:55296
	ds_read_b128 v[214:217], v150 offset:56320
	global_load_lds_dwordx4 v128, s[42:43] offset:128
	s_add_i32 m0, s58, 0xffffff80
	s_nop 0
	global_load_lds_dwordx4 v132, s[42:43] offset:128
	s_barrier
; #define PG8_STAGE(bufoff, gbase, voff) do { _Pragma("unroll") for (int _i = 0; _i < 2; ++_i) \
;         __builtin_amdgcn_global_load_lds((const unsigned*)((const char*)(gbase) + (voff)[_i]), (LAS unsigned*)(lds + (bufoff) + ldsw + _i * 8192), 16, 0, 0); } while (0)
; #define PG8_LDA(dst, b, h) do { _Pragma("unroll") for (int m = 0; m < 4; ++m) _Pragma("unroll") for (int k = 0; k < 2; ++k) dst[m][k] = *(const LAS bf16x8*)(lds + PG8_SA(b, h) + aoff + m * 2048 + k * 1024); } while (0)
; #define PG8_LDB(dst, b, h) do { _Pragma("unroll") for (int n = 0; n < 2; ++n) _Pragma("unroll") for (int k = 0; k < 2; ++k) dst[n][k] = *(const LAS bf16x8*)(lds + PG8_SB(b, h) + boff + n * 2048 + k * 1024); } while (0)
; #define PG8_MMA(ai, bj, At, Bt) do { __builtin_amdgcn_s_setprio(1); _Pragma("unroll") for (int m = 0; m < 4; ++m) _Pragma("unroll") for (int n = 0; n < 2; ++n) _Pragma("unroll") for (int k = 0; k < 2; ++k) \
;         acc[ai][bj][m][n] = __builtin_amdgcn_mfma_f32_16x16x32_bf16(Bt[n][k], At[m][k], acc[ai][bj][m][n], 0, 0, 0); __builtin_amdgcn_s_setprio(0); } while (0)
; #define PG8_WAIT_V(n) asm volatile("s_waitcnt vmcnt(" #n ")" ::: "memory")
; #define PG8_WAIT_L(n) asm volatile("s_waitcnt lgkmcnt(" #n ")" ::: "memory")
; #define PG8_BAR __builtin_amdgcn_s_barrier()
; #define PG8_SCHED __builtin_amdgcn_sched_barrier(0)
; template <class Epi, class Sched>
; DI void gemm_phase(LAS unsigned char* lds, const Gemm g, const Sched& S, const Epi& E) {
;     ...
;             PG8_LDB(B0, 0, 0); PG8_SCHED; PG8_LDA(At, 0, 0); PG8_STAGE(PG8_SA(1, 1), a1 + hstep, voffA);
;             PG8_WAIT_L(8); PG8_BAR; PG8_WAIT_L(0); PG8_MMA(0, 0, At, B0); PG8_BAR; PG8_SCHED;
;             PG8_LDB(B1, 0, 1); PG8_STAGE(PG8_SB(0, 0), b2, voffB);
;             PG8_BAR; PG8_WAIT_L(0); PG8_MMA(0, 1, At, B1); PG8_BAR;
;             PG8_LDA(At, 0, 1); PG8_STAGE(PG8_SA(0, 0), a2, voffA);
;             PG8_BAR; PG8_WAIT_L(0); PG8_MMA(1, 0, At, B0); PG8_BAR; PG8_SCHED;
;     ...
;             PG8_BAR; PG8_WAIT_L(0); PG8_MMA(1, 0, At, B0); PG8_BAR; PG8_SCHED;
;             PG8_STAGE(PG8_SB(1, 1), b3 + hstep, voffB);
;             PG8_WAIT_V(6); PG8_BAR; PG8_MMA(1, 1, At, B1); PG8_BAR;
	s_waitcnt lgkmcnt(0)
	s_setprio 1
	s_waitcnt lgkmcnt(0)
	v_mfma_f32_16x16x32_bf16 v[52:55], v[144:147], v[168:171], v[52:55]
	v_mfma_f32_16x16x32_bf16 v[48:51], v[160:163], v[168:171], v[48:51]
	v_mfma_f32_16x16x32_bf16 v[36:39], v[144:147], v[176:179], v[36:39]
	v_mfma_f32_16x16x32_bf16 v[32:35], v[160:163], v[176:179], v[32:35]
	v_mfma_f32_16x16x32_bf16 v[20:23], v[144:147], v[188:191], v[20:23]
	v_mfma_f32_16x16x32_bf16 v[16:19], v[160:163], v[188:191], v[16:19]
	v_mfma_f32_16x16x32_bf16 v[4:7], v[144:147], v[210:213], v[4:7]
	v_mfma_f32_16x16x32_bf16 v[0:3], v[160:163], v[210:213], v[0:3]
	v_mfma_f32_16x16x32_bf16 v[52:55], v[156:159], v[172:175], v[52:55]
	v_mfma_f32_16x16x32_bf16 v[48:51], v[164:167], v[172:175], v[48:51]
	v_mfma_f32_16x16x32_bf16 v[36:39], v[156:159], v[180:183], v[36:39]
	v_mfma_f32_16x16x32_bf16 v[32:35], v[164:167], v[180:183], v[32:35]
	v_mfma_f32_16x16x32_bf16 v[20:23], v[156:159], v[206:209], v[20:23]
	v_mfma_f32_16x16x32_bf16 v[16:19], v[164:167], v[206:209], v[16:19]
	v_mfma_f32_16x16x32_bf16 v[4:7], v[156:159], v[214:217], v[4:7]
	v_mfma_f32_16x16x32_bf16 v[0:3], v[164:167], v[214:217], v[0:3]
	s_setprio 0
	s_barrier
	s_add_u32 s0, s40, 0x80080
	s_addc_u32 s1, s41, 0
	s_add_i32 s4, s5, s50
	s_mov_b32 m0, s4
	s_nop 0
	global_load_lds_dwordx4 v130, s[0:1]
	s_add_i32 m0, s4, 0x2000
	s_nop 0
	global_load_lds_dwordx4 v134, s[0:1]
	s_waitcnt vmcnt(6)
	s_barrier
	s_setprio 1
	v_mfma_f32_16x16x32_bf16 v[60:63], v[218:221], v[168:171], v[60:63]
	v_mfma_f32_16x16x32_bf16 v[56:59], v[226:229], v[168:171], v[56:59]
	v_mfma_f32_16x16x32_bf16 v[44:47], v[218:221], v[176:179], v[44:47]
	v_mfma_f32_16x16x32_bf16 v[40:43], v[226:229], v[176:179], v[40:43]
	v_mfma_f32_16x16x32_bf16 v[28:31], v[218:221], v[188:191], v[28:31]
	v_mfma_f32_16x16x32_bf16 v[24:27], v[226:229], v[188:191], v[24:27]
	v_mfma_f32_16x16x32_bf16 v[12:15], v[218:221], v[210:213], v[12:15]
	v_mfma_f32_16x16x32_bf16 v[8:11], v[226:229], v[210:213], v[8:11]
	v_mfma_f32_16x16x32_bf16 v[60:63], v[222:225], v[172:175], v[60:63]
	v_mfma_f32_16x16x32_bf16 v[56:59], v[230:233], v[172:175], v[56:59]
	v_mfma_f32_16x16x32_bf16 v[44:47], v[222:225], v[180:183], v[44:47]
	v_mfma_f32_16x16x32_bf16 v[40:43], v[230:233], v[180:183], v[40:43]
	v_mfma_f32_16x16x32_bf16 v[28:31], v[222:225], v[206:209], v[28:31]
	v_mfma_f32_16x16x32_bf16 v[24:27], v[230:233], v[206:209], v[24:27]
	v_mfma_f32_16x16x32_bf16 v[12:15], v[222:225], v[214:217], v[12:15]
	v_mfma_f32_16x16x32_bf16 v[8:11], v[230:233], v[214:217], v[8:11]
	s_setprio 0
	s_add_i32 s68, s68, 2
	s_add_u32 s8, s8, 0x100
	s_addc_u32 s9, s9, 0
	s_add_u32 s66, s66, 0x100
	s_addc_u32 s67, s67, 0
	s_cmp_gt_u32 s68, 29
	s_barrier
	s_cbranch_scc0 .LBB0_1668
	s_branch .Lpeel_done_1668
.LBB0_1668:
	ds_read_b128 v[144:147], v149
	ds_read_b128 v[156:159], v149 offset:1024
	ds_read_b128 v[160:163], v149 offset:2048
	ds_read_b128 v[164:167], v149 offset:3072
	s_add_u32 s0, s8, 0xfff80080
	s_addc_u32 s1, s9, -1
	s_cmp_eq_u32 s68, 28
	s_cselect_b32 s43, s29, s1
	s_cselect_b32 s42, s35, s0
	s_cselect_b32 s41, s19, s67
	s_cselect_b32 s40, s65, s66
	s_add_i32 m0, s39, 0xc000
	ds_read_b128 v[168:171], v150
	ds_read_b128 v[172:175], v150 offset:1024
	ds_read_b128 v[176:179], v150 offset:2048
	ds_read_b128 v[180:183], v150 offset:3072
	ds_read_b128 v[188:191], v150 offset:4096
	ds_read_b128 v[206:209], v150 offset:5120
	ds_read_b128 v[210:213], v150 offset:6144
	ds_read_b128 v[214:217], v150 offset:7168
	global_load_lds_dwordx4 v136, s[8:9]
	s_add_i32 m0, s39, 0xe000
	s_nop 0
	global_load_lds_dwordx4 v138, s[8:9]
	s_waitcnt lgkmcnt(8)
	s_barrier
	s_waitcnt lgkmcnt(0)
	s_setprio 1
	s_waitcnt lgkmcnt(0)
	v_mfma_f32_16x16x32_bf16 v[116:119], v[144:147], v[168:171], v[116:119]
	v_mfma_f32_16x16x32_bf16 v[112:115], v[160:163], v[168:171], v[112:115]
	v_mfma_f32_16x16x32_bf16 v[100:103], v[144:147], v[176:179], v[100:103]
	v_mfma_f32_16x16x32_bf16 v[96:99], v[160:163], v[176:179], v[96:99]
	v_mfma_f32_16x16x32_bf16 v[84:87], v[144:147], v[188:191], v[84:87]
	v_mfma_f32_16x16x32_bf16 v[80:83], v[160:163], v[188:191], v[80:83]
	v_mfma_f32_16x16x32_bf16 v[68:71], v[144:147], v[210:213], v[68:71]
	v_mfma_f32_16x16x32_bf16 v[64:67], v[160:163], v[210:213], v[64:67]
	v_mfma_f32_16x16x32_bf16 v[116:119], v[156:159], v[172:175], v[116:119]
	v_mfma_f32_16x16x32_bf16 v[112:115], v[164:167], v[172:175], v[112:115]
	v_mfma_f32_16x16x32_bf16 v[100:103], v[156:159], v[180:183], v[100:103]
	v_mfma_f32_16x16x32_bf16 v[96:99], v[164:167], v[180:183], v[96:99]
	v_mfma_f32_16x16x32_bf16 v[84:87], v[156:159], v[206:209], v[84:87]
	v_mfma_f32_16x16x32_bf16 v[80:83], v[164:167], v[206:209], v[80:83]
	v_mfma_f32_16x16x32_bf16 v[68:71], v[156:159], v[214:217], v[68:71]
	v_mfma_f32_16x16x32_bf16 v[64:67], v[164:167], v[214:217], v[64:67]
	s_setprio 0
	s_barrier
	s_add_i32 s0, s61, s50
	s_mov_b32 m0, s0
	ds_read_b128 v[218:221], v151
	ds_read_b128 v[222:225], v151 offset:1024
	ds_read_b128 v[226:229], v151 offset:2048
	ds_read_b128 v[230:233], v151 offset:3072
	global_load_lds_dwordx4 v130, s[40:41]
	s_add_i32 m0, s0, 0x2000
	s_nop 0
	global_load_lds_dwordx4 v134, s[40:41]
	s_barrier
; #define PG8_STAGE(bufoff, gbase, voff) do { _Pragma("unroll") for (int _i = 0; _i < 2; ++_i) \
;         __builtin_amdgcn_global_load_lds((const unsigned*)((const char*)(gbase) + (voff)[_i]), (LAS unsigned*)(lds + (bufoff) + ldsw + _i * 8192), 16, 0, 0); } while (0)
; #define PG8_LDA(dst, b, h) do { _Pragma("unroll") for (int m = 0; m < 4; ++m) _Pragma("unroll") for (int k = 0; k < 2; ++k) dst[m][k] = *(const LAS bf16x8*)(lds + PG8_SA(b, h) + aoff + m * 2048 + k * 1024); } while (0)
; #define PG8_LDB(dst, b, h) do { _Pragma("unroll") for (int n = 0; n < 2; ++n) _Pragma("unroll") for (int k = 0; k < 2; ++k) dst[n][k] = *(const LAS bf16x8*)(lds + PG8_SB(b, h) + boff + n * 2048 + k * 1024); } while (0)
; #define PG8_MMA(ai, bj, At, Bt) do { __builtin_amdgcn_s_setprio(1); _Pragma("unroll") for (int m = 0; m < 4; ++m) _Pragma("unroll") for (int n = 0; n < 2; ++n) _Pragma("unroll") for (int k = 0; k < 2; ++k) \
;         acc[ai][bj][m][n] = __builtin_amdgcn_mfma_f32_16x16x32_bf16(Bt[n][k], At[m][k], acc[ai][bj][m][n], 0, 0, 0); __builtin_amdgcn_s_setprio(0); } while (0)
; #define PG8_WAIT_V(n) asm volatile("s_waitcnt vmcnt(" #n ")" ::: "memory")
; #define PG8_WAIT_L(n) asm volatile("s_waitcnt lgkmcnt(" #n ")" ::: "memory")
; #define PG8_BAR __builtin_amdgcn_s_barrier()
; #define PG8_SCHED __builtin_amdgcn_sched_barrier(0)
; template <class Epi, class Sched>
; DI void gemm_phase(LAS unsigned char* lds, const Gemm g, const Sched& S, const Epi& E) {
;     ...
;             PG8_BAR; PG8_WAIT_L(0); PG8_MMA(1, 0, At, B0); PG8_BAR; PG8_SCHED;
;             PG8_STAGE(PG8_SB(0, 1), b2 + hstep, voffB);
;             PG8_WAIT_V(6); PG8_BAR; PG8_MMA(1, 1, At, B1); PG8_BAR;
;             PG8_LDB(B0, 1, 0); PG8_SCHED; PG8_LDA(At, 1, 0); PG8_STAGE(PG8_SA(0, 1), a2 + hstep, voffA);
;             PG8_WAIT_L(8); PG8_BAR; PG8_WAIT_L(0); PG8_MMA(0, 0, At, B0); PG8_BAR; PG8_SCHED;
	s_waitcnt lgkmcnt(0)
	s_setprio 1
	s_waitcnt lgkmcnt(0)
	v_mfma_f32_16x16x32_bf16 v[124:127], v[218:221], v[168:171], v[124:127]
	v_mfma_f32_16x16x32_bf16 v[120:123], v[226:229], v[168:171], v[120:123]
	v_mfma_f32_16x16x32_bf16 v[108:111], v[218:221], v[176:179], v[108:111]
	v_mfma_f32_16x16x32_bf16 v[104:107], v[226:229], v[176:179], v[104:107]
	v_mfma_f32_16x16x32_bf16 v[92:95], v[218:221], v[188:191], v[92:95]
	v_mfma_f32_16x16x32_bf16 v[88:91], v[226:229], v[188:191], v[88:91]
	v_mfma_f32_16x16x32_bf16 v[76:79], v[218:221], v[210:213], v[76:79]
	v_mfma_f32_16x16x32_bf16 v[72:75], v[226:229], v[210:213], v[72:75]
	v_mfma_f32_16x16x32_bf16 v[124:127], v[222:225], v[172:175], v[124:127]
	v_mfma_f32_16x16x32_bf16 v[120:123], v[230:233], v[172:175], v[120:123]
	v_mfma_f32_16x16x32_bf16 v[108:111], v[222:225], v[180:183], v[108:111]
	v_mfma_f32_16x16x32_bf16 v[104:107], v[230:233], v[180:183], v[104:107]
	v_mfma_f32_16x16x32_bf16 v[92:95], v[222:225], v[206:209], v[92:95]
	v_mfma_f32_16x16x32_bf16 v[88:91], v[230:233], v[206:209], v[88:91]
	v_mfma_f32_16x16x32_bf16 v[76:79], v[222:225], v[214:217], v[76:79]
	v_mfma_f32_16x16x32_bf16 v[72:75], v[230:233], v[214:217], v[72:75]
	s_setprio 0
	s_mov_b32 m0, s39
	s_barrier
	ds_read_b128 v[168:171], v150 offset:16384
	ds_read_b128 v[172:175], v150 offset:17408
	ds_read_b128 v[176:179], v150 offset:18432
	ds_read_b128 v[180:183], v150 offset:19456
	ds_read_b128 v[188:191], v150 offset:20480
	ds_read_b128 v[206:209], v150 offset:21504
	ds_read_b128 v[210:213], v150 offset:22528
	ds_read_b128 v[214:217], v150 offset:23552
	global_load_lds_dwordx4 v128, s[42:43]
	s_mov_b32 m0, s51
	s_nop 0
	global_load_lds_dwordx4 v132, s[42:43]
	s_barrier
	s_waitcnt lgkmcnt(0)
	s_setprio 1
	s_waitcnt lgkmcnt(0)
	v_mfma_f32_16x16x32_bf16 v[52:55], v[144:147], v[168:171], v[52:55]
	v_mfma_f32_16x16x32_bf16 v[48:51], v[160:163], v[168:171], v[48:51]
	v_mfma_f32_16x16x32_bf16 v[36:39], v[144:147], v[176:179], v[36:39]
	v_mfma_f32_16x16x32_bf16 v[32:35], v[160:163], v[176:179], v[32:35]
	v_mfma_f32_16x16x32_bf16 v[20:23], v[144:147], v[188:191], v[20:23]
	v_mfma_f32_16x16x32_bf16 v[16:19], v[160:163], v[188:191], v[16:19]
	v_mfma_f32_16x16x32_bf16 v[4:7], v[144:147], v[210:213], v[4:7]
	v_mfma_f32_16x16x32_bf16 v[0:3], v[160:163], v[210:213], v[0:3]
	v_mfma_f32_16x16x32_bf16 v[52:55], v[156:159], v[172:175], v[52:55]
	v_mfma_f32_16x16x32_bf16 v[48:51], v[164:167], v[172:175], v[48:51]
	v_mfma_f32_16x16x32_bf16 v[36:39], v[156:159], v[180:183], v[36:39]
	v_mfma_f32_16x16x32_bf16 v[32:35], v[164:167], v[180:183], v[32:35]
	v_mfma_f32_16x16x32_bf16 v[20:23], v[156:159], v[206:209], v[20:23]
	v_mfma_f32_16x16x32_bf16 v[16:19], v[164:167], v[206:209], v[16:19]
	v_mfma_f32_16x16x32_bf16 v[4:7], v[156:159], v[214:217], v[4:7]
	v_mfma_f32_16x16x32_bf16 v[0:3], v[164:167], v[214:217], v[0:3]
	s_setprio 0
	s_barrier
	s_add_u32 s0, s40, 0x80000
	s_addc_u32 s1, s41, 0
	s_add_i32 s4, s62, s50
	s_mov_b32 m0, s4
	s_nop 0
	global_load_lds_dwordx4 v130, s[0:1]
	s_add_i32 m0, s4, 0x2000
	s_nop 0
	global_load_lds_dwordx4 v134, s[0:1]
	s_waitcnt vmcnt(6)
	s_barrier
	s_setprio 1
	v_mfma_f32_16x16x32_bf16 v[60:63], v[218:221], v[168:171], v[60:63]
	v_mfma_f32_16x16x32_bf16 v[56:59], v[226:229], v[168:171], v[56:59]
	v_mfma_f32_16x16x32_bf16 v[44:47], v[218:221], v[176:179], v[44:47]
	v_mfma_f32_16x16x32_bf16 v[40:43], v[226:229], v[176:179], v[40:43]
	v_mfma_f32_16x16x32_bf16 v[28:31], v[218:221], v[188:191], v[28:31]
	v_mfma_f32_16x16x32_bf16 v[24:27], v[226:229], v[188:191], v[24:27]
	v_mfma_f32_16x16x32_bf16 v[12:15], v[218:221], v[210:213], v[12:15]
	v_mfma_f32_16x16x32_bf16 v[8:11], v[226:229], v[210:213], v[8:11]
	v_mfma_f32_16x16x32_bf16 v[60:63], v[222:225], v[172:175], v[60:63]
	v_mfma_f32_16x16x32_bf16 v[56:59], v[230:233], v[172:175], v[56:59]
	v_mfma_f32_16x16x32_bf16 v[44:47], v[222:225], v[180:183], v[44:47]
	v_mfma_f32_16x16x32_bf16 v[40:43], v[230:233], v[180:183], v[40:43]
	v_mfma_f32_16x16x32_bf16 v[28:31], v[222:225], v[206:209], v[28:31]
	v_mfma_f32_16x16x32_bf16 v[24:27], v[230:233], v[206:209], v[24:27]
	v_mfma_f32_16x16x32_bf16 v[12:15], v[222:225], v[214:217], v[12:15]
	v_mfma_f32_16x16x32_bf16 v[8:11], v[230:233], v[214:217], v[8:11]
	s_setprio 0
	s_add_i32 s4, 0, 0x18000
	v_add_u32_e32 v155, s4, v148
	s_barrier
	ds_read_b128 v[144:147], v155
	ds_read_b128 v[156:159], v155 offset:1024
	ds_read_b128 v[160:163], v155 offset:2048
	ds_read_b128 v[164:167], v155 offset:3072
	s_add_u32 s0, s42, 0x80000
	s_addc_u32 s1, s43, 0
	s_mov_b32 m0, s52
	ds_read_b128 v[168:171], v150 offset:32768
	ds_read_b128 v[172:175], v150 offset:33792
	ds_read_b128 v[176:179], v150 offset:34816
	ds_read_b128 v[180:183], v150 offset:35840
	ds_read_b128 v[188:191], v150 offset:36864
	ds_read_b128 v[206:209], v150 offset:37888
	ds_read_b128 v[210:213], v150 offset:38912
	ds_read_b128 v[214:217], v150 offset:39936
	global_load_lds_dwordx4 v128, s[0:1]
	s_mov_b32 m0, s53
	s_nop 0
	global_load_lds_dwordx4 v132, s[0:1]
	s_waitcnt lgkmcnt(8)
	s_barrier
; #define PG8_STAGE(bufoff, gbase, voff) do { _Pragma("unroll") for (int _i = 0; _i < 2; ++_i) \
;         __builtin_amdgcn_global_load_lds((const unsigned*)((const char*)(gbase) + (voff)[_i]), (LAS unsigned*)(lds + (bufoff) + ldsw + _i * 8192), 16, 0, 0); } while (0)
; #define PG8_LDA(dst, b, h) do { _Pragma("unroll") for (int m = 0; m < 4; ++m) _Pragma("unroll") for (int k = 0; k < 2; ++k) dst[m][k] = *(const LAS bf16x8*)(lds + PG8_SA(b, h) + aoff + m * 2048 + k * 1024); } while (0)
; #define PG8_MMA(ai, bj, At, Bt) do { __builtin_amdgcn_s_setprio(1); _Pragma("unroll") for (int m = 0; m < 4; ++m) _Pragma("unroll") for (int n = 0; n < 2; ++n) _Pragma("unroll") for (int k = 0; k < 2; ++k) \
;         acc[ai][bj][m][n] = __builtin_amdgcn_mfma_f32_16x16x32_bf16(Bt[n][k], At[m][k], acc[ai][bj][m][n], 0, 0, 0); __builtin_amdgcn_s_setprio(0); } while (0)
; #define PG8_WAIT_V(n) asm volatile("s_waitcnt vmcnt(" #n ")" ::: "memory")
; #define PG8_WAIT_L(n) asm volatile("s_waitcnt lgkmcnt(" #n ")" ::: "memory")
; #define PG8_BAR __builtin_amdgcn_s_barrier()
; #define PG8_SCHED __builtin_amdgcn_sched_barrier(0)
; template <class Epi, class Sched>
; DI void gemm_phase(LAS unsigned char* lds, const Gemm g, const Sched& S, const Epi& E) {
;     ...
;             PG8_BAR; PG8_WAIT_L(0); PG8_MMA(0, 1, At, B1); PG8_BAR;
;             PG8_LDA(At, 1, 1); PG8_STAGE(PG8_SA(1, 0), a3, voffA);
;             PG8_BAR; PG8_WAIT_L(0); PG8_MMA(1, 0, At, B0); PG8_BAR; PG8_SCHED;
;             PG8_STAGE(PG8_SB(1, 1), b3 + hstep, voffB);
;             PG8_WAIT_V(6); PG8_BAR; PG8_MMA(1, 1, At, B1); PG8_BAR;
	s_waitcnt lgkmcnt(0)
	s_setprio 1
	s_waitcnt lgkmcnt(0)
	v_mfma_f32_16x16x32_bf16 v[116:119], v[144:147], v[168:171], v[116:119]
	v_mfma_f32_16x16x32_bf16 v[112:115], v[160:163], v[168:171], v[112:115]
	v_mfma_f32_16x16x32_bf16 v[100:103], v[144:147], v[176:179], v[100:103]
	v_mfma_f32_16x16x32_bf16 v[96:99], v[160:163], v[176:179], v[96:99]
	v_mfma_f32_16x16x32_bf16 v[84:87], v[144:147], v[188:191], v[84:87]
	v_mfma_f32_16x16x32_bf16 v[80:83], v[160:163], v[188:191], v[80:83]
	v_mfma_f32_16x16x32_bf16 v[68:71], v[144:147], v[210:213], v[68:71]
	v_mfma_f32_16x16x32_bf16 v[64:67], v[160:163], v[210:213], v[64:67]
	v_mfma_f32_16x16x32_bf16 v[116:119], v[156:159], v[172:175], v[116:119]
	v_mfma_f32_16x16x32_bf16 v[112:115], v[164:167], v[172:175], v[112:115]
	v_mfma_f32_16x16x32_bf16 v[100:103], v[156:159], v[180:183], v[100:103]
	v_mfma_f32_16x16x32_bf16 v[96:99], v[164:167], v[180:183], v[96:99]
	v_mfma_f32_16x16x32_bf16 v[84:87], v[156:159], v[206:209], v[84:87]
	v_mfma_f32_16x16x32_bf16 v[80:83], v[164:167], v[206:209], v[80:83]
	v_mfma_f32_16x16x32_bf16 v[68:71], v[156:159], v[214:217], v[68:71]
	v_mfma_f32_16x16x32_bf16 v[64:67], v[164:167], v[214:217], v[64:67]
	s_setprio 0
	s_barrier
	s_add_i32 s5, 0, 0x1c000
	s_add_i32 s0, s4, s50
	v_add_u32_e32 v155, s5, v148
	s_add_i32 m0, s0, 0xffffff80
	ds_read_b128 v[218:221], v155
	ds_read_b128 v[222:225], v155 offset:1024
	ds_read_b128 v[226:229], v155 offset:2048
	ds_read_b128 v[230:233], v155 offset:3072
	global_load_lds_dwordx4 v130, s[40:41] offset:128
	s_add_i32 m0, s0, 0x1f80
	s_nop 0
	global_load_lds_dwordx4 v134, s[40:41] offset:128
	s_barrier
	s_waitcnt lgkmcnt(0)
	s_setprio 1
	s_waitcnt lgkmcnt(0)
	v_mfma_f32_16x16x32_bf16 v[124:127], v[218:221], v[168:171], v[124:127]
	v_mfma_f32_16x16x32_bf16 v[120:123], v[226:229], v[168:171], v[120:123]
	v_mfma_f32_16x16x32_bf16 v[108:111], v[218:221], v[176:179], v[108:111]
	v_mfma_f32_16x16x32_bf16 v[104:107], v[226:229], v[176:179], v[104:107]
	v_mfma_f32_16x16x32_bf16 v[92:95], v[218:221], v[188:191], v[92:95]
	v_mfma_f32_16x16x32_bf16 v[88:91], v[226:229], v[188:191], v[88:91]
	v_mfma_f32_16x16x32_bf16 v[76:79], v[218:221], v[210:213], v[76:79]
	v_mfma_f32_16x16x32_bf16 v[72:75], v[226:229], v[210:213], v[72:75]
	v_mfma_f32_16x16x32_bf16 v[124:127], v[222:225], v[172:175], v[124:127]
	v_mfma_f32_16x16x32_bf16 v[120:123], v[230:233], v[172:175], v[120:123]
	v_mfma_f32_16x16x32_bf16 v[108:111], v[222:225], v[180:183], v[108:111]
	v_mfma_f32_16x16x32_bf16 v[104:107], v[230:233], v[180:183], v[104:107]
	v_mfma_f32_16x16x32_bf16 v[92:95], v[222:225], v[206:209], v[92:95]
	v_mfma_f32_16x16x32_bf16 v[88:91], v[230:233], v[206:209], v[88:91]
	v_mfma_f32_16x16x32_bf16 v[76:79], v[222:225], v[214:217], v[76:79]
	v_mfma_f32_16x16x32_bf16 v[72:75], v[230:233], v[214:217], v[72:75]
	s_setprio 0
	s_add_i32 m0, s57, 0xffffff80
	s_barrier
	ds_read_b128 v[168:171], v150 offset:49152
	ds_read_b128 v[172:175], v150 offset:50176
	ds_read_b128 v[176:179], v150 offset:51200
	ds_read_b128 v[180:183], v150 offset:52224
	ds_read_b128 v[188:191], v150 offset:53248
	ds_read_b128 v[206:209], v150 offset:54272
	ds_read_b128 v[210:213], v150 offset:55296
	ds_read_b128 v[214:217], v150 offset:56320
	global_load_lds_dwordx4 v128, s[42:43] offset:128
	s_add_i32 m0, s58, 0xffffff80
	s_nop 0
	global_load_lds_dwordx4 v132, s[42:43] offset:128
	s_barrier
	s_waitcnt lgkmcnt(0)
	s_setprio 1
	s_waitcnt lgkmcnt(0)
	v_mfma_f32_16x16x32_bf16 v[52:55], v[144:147], v[168:171], v[52:55]
	v_mfma_f32_16x16x32_bf16 v[48:51], v[160:163], v[168:171], v[48:51]
	v_mfma_f32_16x16x32_bf16 v[36:39], v[144:147], v[176:179], v[36:39]
	v_mfma_f32_16x16x32_bf16 v[32:35], v[160:163], v[176:179], v[32:35]
	v_mfma_f32_16x16x32_bf16 v[20:23], v[144:147], v[188:191], v[20:23]
	v_mfma_f32_16x16x32_bf16 v[16:19], v[160:163], v[188:191], v[16:19]
	v_mfma_f32_16x16x32_bf16 v[4:7], v[144:147], v[210:213], v[4:7]
	v_mfma_f32_16x16x32_bf16 v[0:3], v[160:163], v[210:213], v[0:3]
	v_mfma_f32_16x16x32_bf16 v[52:55], v[156:159], v[172:175], v[52:55]
	v_mfma_f32_16x16x32_bf16 v[48:51], v[164:167], v[172:175], v[48:51]
	v_mfma_f32_16x16x32_bf16 v[36:39], v[156:159], v[180:183], v[36:39]
	v_mfma_f32_16x16x32_bf16 v[32:35], v[164:167], v[180:183], v[32:35]
	v_mfma_f32_16x16x32_bf16 v[20:23], v[156:159], v[206:209], v[20:23]
	v_mfma_f32_16x16x32_bf16 v[16:19], v[164:167], v[206:209], v[16:19]
	v_mfma_f32_16x16x32_bf16 v[4:7], v[156:159], v[214:217], v[4:7]
	v_mfma_f32_16x16x32_bf16 v[0:3], v[164:167], v[214:217], v[0:3]
	s_setprio 0
	s_barrier
	s_add_u32 s0, s40, 0x80080
	s_addc_u32 s1, s41, 0
	s_add_i32 s4, s5, s50
	s_mov_b32 m0, s4
	s_nop 0
	global_load_lds_dwordx4 v130, s[0:1]
	s_add_i32 m0, s4, 0x2000
	s_nop 0
	global_load_lds_dwordx4 v134, s[0:1]
	s_waitcnt vmcnt(6)
	s_barrier
	s_setprio 1
	v_mfma_f32_16x16x32_bf16 v[60:63], v[218:221], v[168:171], v[60:63]
	v_mfma_f32_16x16x32_bf16 v[56:59], v[226:229], v[168:171], v[56:59]
	v_mfma_f32_16x16x32_bf16 v[44:47], v[218:221], v[176:179], v[44:47]
	v_mfma_f32_16x16x32_bf16 v[40:43], v[226:229], v[176:179], v[40:43]
	v_mfma_f32_16x16x32_bf16 v[28:31], v[218:221], v[188:191], v[28:31]
	v_mfma_f32_16x16x32_bf16 v[24:27], v[226:229], v[188:191], v[24:27]
	v_mfma_f32_16x16x32_bf16 v[12:15], v[218:221], v[210:213], v[12:15]
	v_mfma_f32_16x16x32_bf16 v[8:11], v[226:229], v[210:213], v[8:11]
	v_mfma_f32_16x16x32_bf16 v[60:63], v[222:225], v[172:175], v[60:63]
	v_mfma_f32_16x16x32_bf16 v[56:59], v[230:233], v[172:175], v[56:59]
	v_mfma_f32_16x16x32_bf16 v[44:47], v[222:225], v[180:183], v[44:47]
	v_mfma_f32_16x16x32_bf16 v[40:43], v[230:233], v[180:183], v[40:43]
	v_mfma_f32_16x16x32_bf16 v[28:31], v[222:225], v[206:209], v[28:31]
	v_mfma_f32_16x16x32_bf16 v[24:27], v[230:233], v[206:209], v[24:27]
	v_mfma_f32_16x16x32_bf16 v[12:15], v[222:225], v[214:217], v[12:15]
	v_mfma_f32_16x16x32_bf16 v[8:11], v[230:233], v[214:217], v[8:11]
	s_setprio 0
	s_add_i32 s68, s68, 2
	s_add_u32 s8, s8, 0x100
	s_addc_u32 s9, s9, 0
	s_add_u32 s66, s66, 0x100
	s_addc_u32 s67, s67, 0
	s_cmp_gt_u32 s68, 29
	s_barrier
	s_cbranch_scc0 .LBB0_1668

; #define PG8_STAGE(bufoff, gbase, voff) do { _Pragma("unroll") for (int _i = 0; _i < 2; ++_i) \
;         __builtin_amdgcn_global_load_lds((const unsigned*)((const char*)(gbase) + (voff)[_i]), (LAS unsigned*)(lds + (bufoff) + ldsw + _i * 8192), 16, 0, 0); } while (0)
; #define PG8_WAIT_V(n) asm volatile("s_waitcnt vmcnt(" #n ")" ::: "memory")
; #define PG8_BAR __builtin_amdgcn_s_barrier()
; template <class Epi, class Sched>
; DI void gemm_phase(LAS unsigned char* lds, const Gemm g, const Sched& S, const Epi& E) {
;     ...
;     PG8_STAGE(PG8_SB(0, 0), cB, voffB); PG8_STAGE(PG8_SA(0, 0), cA, voffA); PG8_STAGE(PG8_SB(0, 1), cB + hstep, voffB); PG8_STAGE(PG8_SA(0, 1), cA + hstep, voffA);
;     if (wr == 1) PG8_BAR;
;     PG8_WAIT_V(4); PG8_BAR;
;     PG8_STAGE(PG8_SB(1, 0), cB + kstep, voffB); PG8_STAGE(PG8_SA(1, 0), cA + kstep, voffA); PG8_STAGE(PG8_SB(1, 1), cB + hstep + kstep, voffB);
;     PG8_WAIT_V(6); PG8_BAR;
.LBB0_1733:
	s_add_u32 s18, s22, 0x86c3000
	s_addc_u32 s19, s23, 0
	s_add_u32 s28, s22, 0x2bb03200
	s_addc_u32 s29, s23, 0
	s_add_u32 s30, s22, 0x183000
	s_mov_b64 s[36:37], 0x80
	s_addc_u32 s31, s23, 0
	s_and_b32 s56, s1, 3
	s_add_i32 m0, s52, 0x18000
	v_lshl_add_u64 v[6:7], v[6:7], 0, s[36:37]
	s_lshl_b32 s57, s0, 6
	s_lshl_b32 s4, s0, 13
	s_lshl_b32 s58, s56, 5
	s_waitcnt vmcnt(4)
	s_barrier
	global_load_lds_dwordx4 v[6:7], off
	v_lshl_add_u64 v[4:5], v[4:5], 0, s[36:37]
	s_add_i32 m0, s52, 0x1a000
	s_add_i32 s59, s52, 0x8000
	s_add_i32 s60, s52, 0xa000
	global_load_lds_dwordx4 v[4:5], off
	v_lshl_add_u64 v[2:3], v[2:3], 0, s[36:37]
	s_mov_b32 m0, s59
	s_add_u32 s0, s40, 0x160080
	global_load_lds_dwordx4 v[2:3], off
	v_lshl_add_u64 v[0:1], v[0:1], 0, s[36:37]
	s_mov_b32 m0, s60
	s_addc_u32 s1, s41, 0
	global_load_lds_dwordx4 v[0:1], off
	s_add_i32 m0, s52, 0x1c000
	s_nop 0
	global_load_lds_dwordx4 v130, s[0:1]
	s_add_i32 m0, s52, 0x1e000
	v_lshl_or_b32 v154, s56, 12, v149
	global_load_lds_dwordx4 v134, s[0:1]
	v_lshlrev_b32_e32 v1, 2, v194
	v_lshl_or_b32 v0, v194, 6, v195
	v_and_b32_e32 v1, 32, v1
	v_bitop3_b32 v0, v0, s4, v1 bitop3:0xde
	s_waitcnt vmcnt(6)
	v_add_u16_e32 v1, v148, v196
	v_lshrrev_b16_e32 v1, 1, v1
	s_add_i32 s61, 0, 0x10000
	s_add_i32 s62, 0, 0x14000
	v_add_lshl_u32 v136, v8, v1, 1
	v_mov_b32_e32 v137, v131
	v_add_lshl_u32 v138, v9, v1, 1
	v_mov_b32_e32 v139, v131
	v_mov_b64_e32 v[140:141], 0x400
	v_mov_b64_e32 v[142:143], 0x3ff
	v_add_u32_e32 v155, s61, v154
	v_add_u32_e32 v156, 0, v0
	v_add_u32_e32 v157, s62, v154
	s_movk_i32 s63, 0x1200
	v_mbcnt_hi_u32_b32 v158, -1, v204
	s_mov_b32 s64, 0
	s_barrier
	s_branch .LBB0_1735

; #define PG8_STAGE(bufoff, gbase, voff) do { _Pragma("unroll") for (int _i = 0; _i < 2; ++_i) \
;         __builtin_amdgcn_global_load_lds((const unsigned*)((const char*)(gbase) + (voff)[_i]), (LAS unsigned*)(lds + (bufoff) + ldsw + _i * 8192), 16, 0, 0); } while (0)
; #define PG8_LDA(dst, b, h) do { _Pragma("unroll") for (int m = 0; m < 4; ++m) _Pragma("unroll") for (int k = 0; k < 2; ++k) dst[m][k] = *(const LAS bf16x8*)(lds + PG8_SA(b, h) + aoff + m * 2048 + k * 1024); } while (0)
; #define PG8_LDB(dst, b, h) do { _Pragma("unroll") for (int n = 0; n < 2; ++n) _Pragma("unroll") for (int k = 0; k < 2; ++k) dst[n][k] = *(const LAS bf16x8*)(lds + PG8_SB(b, h) + boff + n * 2048 + k * 1024); } while (0)
; #define PG8_MMA(ai, bj, At, Bt) do { __builtin_amdgcn_s_setprio(1); _Pragma("unroll") for (int m = 0; m < 4; ++m) _Pragma("unroll") for (int n = 0; n < 2; ++n) _Pragma("unroll") for (int k = 0; k < 2; ++k) \
;         acc[ai][bj][m][n] = __builtin_amdgcn_mfma_f32_16x16x32_bf16(Bt[n][k], At[m][k], acc[ai][bj][m][n], 0, 0, 0); __builtin_amdgcn_s_setprio(0); } while (0)
; #define PG8_WAIT_V(n) asm volatile("s_waitcnt vmcnt(" #n ")" ::: "memory")
; #define PG8_WAIT_L(n) asm volatile("s_waitcnt lgkmcnt(" #n ")" ::: "memory")
; #define PG8_BAR __builtin_amdgcn_s_barrier()
; template <class Epi, class Sched>
; DI void gemm_phase(LAS unsigned char* lds, const Gemm g, const Sched& S, const Epi& E) {
;     ...
;             PG8_LDB(B0, 0, 0); PG8_SCHED; PG8_LDA(At, 0, 0); PG8_STAGE(PG8_SA(1, 1), a1 + hstep, voffA);
;             PG8_WAIT_L(8); PG8_BAR; PG8_WAIT_L(0); PG8_MMA(0, 0, At, B0); PG8_BAR; PG8_SCHED;
;             PG8_LDB(B1, 0, 1); PG8_STAGE(PG8_SB(0, 0), b2, voffB);
;             PG8_BAR; PG8_WAIT_L(0); PG8_MMA(0, 1, At, B1); PG8_BAR;
;             PG8_LDA(At, 0, 1); PG8_STAGE(PG8_SA(0, 0), a2, voffA);
;             PG8_BAR; PG8_WAIT_L(0); PG8_MMA(1, 0, At, B0); PG8_BAR; PG8_SCHED;
;             PG8_STAGE(PG8_SB(0, 1), b2 + hstep, voffB);
;             PG8_WAIT_V(6); PG8_BAR; PG8_MMA(1, 1, At, B1); PG8_BAR;
;             PG8_LDB(B0, 1, 0); PG8_SCHED; PG8_LDA(At, 1, 0); PG8_STAGE(PG8_SA(0, 1), a2 + hstep, voffA);
;             PG8_WAIT_L(8); PG8_BAR; PG8_WAIT_L(0); PG8_MMA(0, 0, At, B0); PG8_BAR; PG8_SCHED;
;             PG8_LDB(B1, 1, 1); PG8_STAGE(PG8_SB(1, 0), b3, voffB);
;             PG8_BAR; PG8_WAIT_L(0); PG8_MMA(0, 1, At, B1); PG8_BAR;
.LBB0_1745:
	s_add_u32 s38, s38, 0x160080
	s_addc_u32 s39, s39, 0
	s_add_u32 s35, s40, 0x100
	v_mov_b32_e32 v0, 0
	s_addc_u32 s67, s41, 0
	s_mov_b32 s68, -2
	s_waitcnt lgkmcnt(0)
	ds_read_b128 v[144:147], v155
	ds_read_b128 v[160:163], v155 offset:1024
	ds_read_b128 v[164:167], v155 offset:2048
	ds_read_b128 v[168:171], v155 offset:3072
	s_add_u32 s0, s38, 0xffea0080
	s_addc_u32 s1, s39, -1
	s_cmpk_eq_i32 s68, 0x54
	s_cselect_b32 s43, s9, s1
	s_cselect_b32 s42, s8, s0
	s_cselect_b32 s41, s11, s67
	s_cselect_b32 s40, s10, s35
	s_add_i32 m0, s52, 0xc000
	ds_read_b128 v[172:175], v156
	ds_read_b128 v[176:179], v156 offset:1024
	ds_read_b128 v[180:183], v156 offset:2048
	ds_read_b128 v[188:191], v156 offset:3072
	ds_read_b128 v[206:209], v156 offset:4096
	ds_read_b128 v[210:213], v156 offset:5120
	ds_read_b128 v[214:217], v156 offset:6144
	ds_read_b128 v[218:221], v156 offset:7168
	global_load_lds_dwordx4 v136, s[38:39]
	s_add_i32 m0, s52, 0xe000
	s_nop 0
	global_load_lds_dwordx4 v138, s[38:39]
	s_waitcnt lgkmcnt(8)
	s_barrier
	s_waitcnt lgkmcnt(0)
	s_setprio 1
	s_waitcnt lgkmcnt(0)
	v_mfma_f32_16x16x32_bf16 v[124:127], v[144:147], v[172:175], 0
	v_mfma_f32_16x16x32_bf16 v[120:123], v[164:167], v[172:175], 0
	v_mfma_f32_16x16x32_bf16 v[108:111], v[144:147], v[180:183], 0
	v_mfma_f32_16x16x32_bf16 v[104:107], v[164:167], v[180:183], 0
	v_mfma_f32_16x16x32_bf16 v[92:95], v[144:147], v[206:209], 0
	v_mfma_f32_16x16x32_bf16 v[88:91], v[164:167], v[206:209], 0
	v_mfma_f32_16x16x32_bf16 v[76:79], v[144:147], v[214:217], 0
	v_mfma_f32_16x16x32_bf16 v[72:75], v[164:167], v[214:217], 0
	v_mfma_f32_16x16x32_bf16 v[124:127], v[160:163], v[176:179], v[124:127]
	v_mfma_f32_16x16x32_bf16 v[120:123], v[168:171], v[176:179], v[120:123]
	v_mfma_f32_16x16x32_bf16 v[108:111], v[160:163], v[188:191], v[108:111]
	v_mfma_f32_16x16x32_bf16 v[104:107], v[168:171], v[188:191], v[104:107]
	v_mfma_f32_16x16x32_bf16 v[92:95], v[160:163], v[210:213], v[92:95]
	v_mfma_f32_16x16x32_bf16 v[88:91], v[168:171], v[210:213], v[88:91]
	v_mfma_f32_16x16x32_bf16 v[76:79], v[160:163], v[218:221], v[76:79]
	v_mfma_f32_16x16x32_bf16 v[72:75], v[168:171], v[218:221], v[72:75]
	s_setprio 0
	s_barrier
	s_add_i32 s0, s61, s51
	s_mov_b32 m0, s0
	ds_read_b128 v[222:225], v157
	ds_read_b128 v[226:229], v157 offset:1024
	ds_read_b128 v[230:233], v157 offset:2048
	ds_read_b128 v[234:237], v157 offset:3072
	global_load_lds_dwordx4 v130, s[40:41]
	s_add_i32 m0, s0, 0x2000
	s_nop 0
	global_load_lds_dwordx4 v134, s[40:41]
	s_barrier
	s_waitcnt lgkmcnt(0)
	s_setprio 1
	s_waitcnt lgkmcnt(0)
	v_mfma_f32_16x16x32_bf16 v[116:119], v[222:225], v[172:175], 0
	v_mfma_f32_16x16x32_bf16 v[112:115], v[230:233], v[172:175], 0
	v_mfma_f32_16x16x32_bf16 v[100:103], v[222:225], v[180:183], 0
	v_mfma_f32_16x16x32_bf16 v[96:99], v[230:233], v[180:183], 0
	v_mfma_f32_16x16x32_bf16 v[84:87], v[222:225], v[206:209], 0
	v_mfma_f32_16x16x32_bf16 v[80:83], v[230:233], v[206:209], 0
	v_mfma_f32_16x16x32_bf16 v[68:71], v[222:225], v[214:217], 0
	v_mfma_f32_16x16x32_bf16 v[64:67], v[230:233], v[214:217], 0
	v_mfma_f32_16x16x32_bf16 v[116:119], v[226:229], v[176:179], v[116:119]
	v_mfma_f32_16x16x32_bf16 v[112:115], v[234:237], v[176:179], v[112:115]
	v_mfma_f32_16x16x32_bf16 v[100:103], v[226:229], v[188:191], v[100:103]
	v_mfma_f32_16x16x32_bf16 v[96:99], v[234:237], v[188:191], v[96:99]
	v_mfma_f32_16x16x32_bf16 v[84:87], v[226:229], v[210:213], v[84:87]
	v_mfma_f32_16x16x32_bf16 v[80:83], v[234:237], v[210:213], v[80:83]
	v_mfma_f32_16x16x32_bf16 v[68:71], v[226:229], v[218:221], v[68:71]
	v_mfma_f32_16x16x32_bf16 v[64:67], v[234:237], v[218:221], v[64:67]
	s_setprio 0
	s_mov_b32 m0, s52
	s_barrier
	ds_read_b128 v[172:175], v156 offset:16384
	ds_read_b128 v[176:179], v156 offset:17408
	ds_read_b128 v[180:183], v156 offset:18432
	ds_read_b128 v[188:191], v156 offset:19456
	ds_read_b128 v[206:209], v156 offset:20480
	ds_read_b128 v[210:213], v156 offset:21504
	ds_read_b128 v[214:217], v156 offset:22528
	ds_read_b128 v[218:221], v156 offset:23552
	global_load_lds_dwordx4 v128, s[42:43]
	s_mov_b32 m0, s53
	s_nop 0
	global_load_lds_dwordx4 v132, s[42:43]
	s_barrier
	s_waitcnt lgkmcnt(0)
	s_setprio 1
	s_waitcnt lgkmcnt(0)
	v_mfma_f32_16x16x32_bf16 v[60:63], v[144:147], v[172:175], 0
	v_mfma_f32_16x16x32_bf16 v[56:59], v[164:167], v[172:175], 0
	v_mfma_f32_16x16x32_bf16 v[44:47], v[144:147], v[180:183], 0
	v_mfma_f32_16x16x32_bf16 v[40:43], v[164:167], v[180:183], 0
	v_mfma_f32_16x16x32_bf16 v[28:31], v[144:147], v[206:209], 0
	v_mfma_f32_16x16x32_bf16 v[24:27], v[164:167], v[206:209], 0
	v_mfma_f32_16x16x32_bf16 v[12:15], v[144:147], v[214:217], 0
	v_mfma_f32_16x16x32_bf16 v[8:11], v[164:167], v[214:217], 0
	v_mfma_f32_16x16x32_bf16 v[60:63], v[160:163], v[176:179], v[60:63]
	v_mfma_f32_16x16x32_bf16 v[56:59], v[168:171], v[176:179], v[56:59]
	v_mfma_f32_16x16x32_bf16 v[44:47], v[160:163], v[188:191], v[44:47]
	v_mfma_f32_16x16x32_bf16 v[40:43], v[168:171], v[188:191], v[40:43]
	v_mfma_f32_16x16x32_bf16 v[28:31], v[160:163], v[210:213], v[28:31]
	v_mfma_f32_16x16x32_bf16 v[24:27], v[168:171], v[210:213], v[24:27]
	v_mfma_f32_16x16x32_bf16 v[12:15], v[160:163], v[218:221], v[12:15]
	v_mfma_f32_16x16x32_bf16 v[8:11], v[168:171], v[218:221], v[8:11]
	s_setprio 0
	s_barrier
	s_add_u32 s0, s40, 0x160000
	s_addc_u32 s1, s41, 0
	s_add_i32 s4, s62, s51
	s_mov_b32 m0, s4
	s_nop 0
	global_load_lds_dwordx4 v130, s[0:1]
	s_add_i32 m0, s4, 0x2000
	s_nop 0
	global_load_lds_dwordx4 v134, s[0:1]
	s_waitcnt vmcnt(6)
	s_barrier
; #define PG8_STAGE(bufoff, gbase, voff) do { _Pragma("unroll") for (int _i = 0; _i < 2; ++_i) \
;         __builtin_amdgcn_global_load_lds((const unsigned*)((const char*)(gbase) + (voff)[_i]), (LAS unsigned*)(lds + (bufoff) + ldsw + _i * 8192), 16, 0, 0); } while (0)
; #define PG8_LDA(dst, b, h) do { _Pragma("unroll") for (int m = 0; m < 4; ++m) _Pragma("unroll") for (int k = 0; k < 2; ++k) dst[m][k] = *(const LAS bf16x8*)(lds + PG8_SA(b, h) + aoff + m * 2048 + k * 1024); } while (0)
; #define PG8_LDB(dst, b, h) do { _Pragma("unroll") for (int n = 0; n < 2; ++n) _Pragma("unroll") for (int k = 0; k < 2; ++k) dst[n][k] = *(const LAS bf16x8*)(lds + PG8_SB(b, h) + boff + n * 2048 + k * 1024); } while (0)
; #define PG8_MMA(ai, bj, At, Bt) do { __builtin_amdgcn_s_setprio(1); _Pragma("unroll") for (int m = 0; m < 4; ++m) _Pragma("unroll") for (int n = 0; n < 2; ++n) _Pragma("unroll") for (int k = 0; k < 2; ++k) \
;         acc[ai][bj][m][n] = __builtin_amdgcn_mfma_f32_16x16x32_bf16(Bt[n][k], At[m][k], acc[ai][bj][m][n], 0, 0, 0); __builtin_amdgcn_s_setprio(0); } while (0)
; #define PG8_WAIT_V(n) asm volatile("s_waitcnt vmcnt(" #n ")" ::: "memory")
; #define PG8_WAIT_L(n) asm volatile("s_waitcnt lgkmcnt(" #n ")" ::: "memory")
; #define PG8_BAR __builtin_amdgcn_s_barrier()
; #define PG8_SCHED __builtin_amdgcn_sched_barrier(0)
; template <class Epi, class Sched>
; DI void gemm_phase(LAS unsigned char* lds, const Gemm g, const Sched& S, const Epi& E) {
;     ...
;             PG8_BAR; PG8_WAIT_L(0); PG8_MMA(1, 0, At, B0); PG8_BAR; PG8_SCHED;
;             PG8_STAGE(PG8_SB(0, 1), b2 + hstep, voffB);
;             PG8_WAIT_V(6); PG8_BAR; PG8_MMA(1, 1, At, B1); PG8_BAR;
;             PG8_LDB(B0, 1, 0); PG8_SCHED; PG8_LDA(At, 1, 0); PG8_STAGE(PG8_SA(0, 1), a2 + hstep, voffA);
;             PG8_WAIT_L(8); PG8_BAR; PG8_WAIT_L(0); PG8_MMA(0, 0, At, B0); PG8_BAR; PG8_SCHED;
;             PG8_LDB(B1, 1, 1); PG8_STAGE(PG8_SB(1, 0), b3, voffB);
;             PG8_BAR; PG8_WAIT_L(0); PG8_MMA(0, 1, At, B1); PG8_BAR;
;             PG8_LDA(At, 1, 1); PG8_STAGE(PG8_SA(1, 0), a3, voffA);
;             PG8_BAR; PG8_WAIT_L(0); PG8_MMA(1, 0, At, B0); PG8_BAR; PG8_SCHED;
;             PG8_STAGE(PG8_SB(1, 1), b3 + hstep, voffB);
;             PG8_WAIT_V(6); PG8_BAR; PG8_MMA(1, 1, At, B1); PG8_BAR;
	s_setprio 1
	v_mfma_f32_16x16x32_bf16 v[52:55], v[222:225], v[172:175], 0
	v_mfma_f32_16x16x32_bf16 v[48:51], v[230:233], v[172:175], 0
	v_mfma_f32_16x16x32_bf16 v[36:39], v[222:225], v[180:183], 0
	v_mfma_f32_16x16x32_bf16 v[32:35], v[230:233], v[180:183], 0
	v_mfma_f32_16x16x32_bf16 v[20:23], v[222:225], v[206:209], 0
	v_mfma_f32_16x16x32_bf16 v[16:19], v[230:233], v[206:209], 0
	v_mfma_f32_16x16x32_bf16 v[4:7], v[222:225], v[214:217], 0
	v_mfma_f32_16x16x32_bf16 v[0:3], v[230:233], v[214:217], 0
	v_mfma_f32_16x16x32_bf16 v[52:55], v[226:229], v[176:179], v[52:55]
	v_mfma_f32_16x16x32_bf16 v[48:51], v[234:237], v[176:179], v[48:51]
	v_mfma_f32_16x16x32_bf16 v[36:39], v[226:229], v[188:191], v[36:39]
	v_mfma_f32_16x16x32_bf16 v[32:35], v[234:237], v[188:191], v[32:35]
	v_mfma_f32_16x16x32_bf16 v[20:23], v[226:229], v[210:213], v[20:23]
	v_mfma_f32_16x16x32_bf16 v[16:19], v[234:237], v[210:213], v[16:19]
	v_mfma_f32_16x16x32_bf16 v[4:7], v[226:229], v[218:221], v[4:7]
	v_mfma_f32_16x16x32_bf16 v[0:3], v[234:237], v[218:221], v[0:3]
	s_setprio 0
	s_add_i32 s4, 0, 0x18000
	v_add_u32_e32 v159, s4, v154
	s_barrier
	ds_read_b128 v[144:147], v159
	ds_read_b128 v[160:163], v159 offset:1024
	ds_read_b128 v[164:167], v159 offset:2048
	ds_read_b128 v[168:171], v159 offset:3072
	s_add_u32 s0, s42, 0x160000
	s_addc_u32 s1, s43, 0
	s_mov_b32 m0, s54
	ds_read_b128 v[172:175], v156 offset:32768
	ds_read_b128 v[176:179], v156 offset:33792
	ds_read_b128 v[180:183], v156 offset:34816
	ds_read_b128 v[188:191], v156 offset:35840
	ds_read_b128 v[206:209], v156 offset:36864
	ds_read_b128 v[210:213], v156 offset:37888
	ds_read_b128 v[214:217], v156 offset:38912
	ds_read_b128 v[218:221], v156 offset:39936
	global_load_lds_dwordx4 v128, s[0:1]
	s_mov_b32 m0, s55
	s_nop 0
	global_load_lds_dwordx4 v132, s[0:1]
	s_waitcnt lgkmcnt(8)
	s_barrier
	s_waitcnt lgkmcnt(0)
	s_setprio 1
	s_waitcnt lgkmcnt(0)
	v_mfma_f32_16x16x32_bf16 v[124:127], v[144:147], v[172:175], v[124:127]
	v_mfma_f32_16x16x32_bf16 v[120:123], v[164:167], v[172:175], v[120:123]
	v_mfma_f32_16x16x32_bf16 v[108:111], v[144:147], v[180:183], v[108:111]
	v_mfma_f32_16x16x32_bf16 v[104:107], v[164:167], v[180:183], v[104:107]
	v_mfma_f32_16x16x32_bf16 v[92:95], v[144:147], v[206:209], v[92:95]
	v_mfma_f32_16x16x32_bf16 v[88:91], v[164:167], v[206:209], v[88:91]
	v_mfma_f32_16x16x32_bf16 v[76:79], v[144:147], v[214:217], v[76:79]
	v_mfma_f32_16x16x32_bf16 v[72:75], v[164:167], v[214:217], v[72:75]
	v_mfma_f32_16x16x32_bf16 v[124:127], v[160:163], v[176:179], v[124:127]
	v_mfma_f32_16x16x32_bf16 v[120:123], v[168:171], v[176:179], v[120:123]
	v_mfma_f32_16x16x32_bf16 v[108:111], v[160:163], v[188:191], v[108:111]
	v_mfma_f32_16x16x32_bf16 v[104:107], v[168:171], v[188:191], v[104:107]
	v_mfma_f32_16x16x32_bf16 v[92:95], v[160:163], v[210:213], v[92:95]
	v_mfma_f32_16x16x32_bf16 v[88:91], v[168:171], v[210:213], v[88:91]
	v_mfma_f32_16x16x32_bf16 v[76:79], v[160:163], v[218:221], v[76:79]
	v_mfma_f32_16x16x32_bf16 v[72:75], v[168:171], v[218:221], v[72:75]
	s_setprio 0
	s_barrier
	s_add_i32 s5, 0, 0x1c000
	s_add_i32 s0, s4, s51
	v_add_u32_e32 v159, s5, v154
	s_add_i32 m0, s0, 0xffffff80
	ds_read_b128 v[222:225], v159
	ds_read_b128 v[226:229], v159 offset:1024
	ds_read_b128 v[230:233], v159 offset:2048
	ds_read_b128 v[234:237], v159 offset:3072
	global_load_lds_dwordx4 v130, s[40:41] offset:128
	s_add_i32 m0, s0, 0x1f80
	s_nop 0
	global_load_lds_dwordx4 v134, s[40:41] offset:128
	s_barrier
	s_waitcnt lgkmcnt(0)
	s_setprio 1
	s_waitcnt lgkmcnt(0)
	v_mfma_f32_16x16x32_bf16 v[116:119], v[222:225], v[172:175], v[116:119]
	v_mfma_f32_16x16x32_bf16 v[112:115], v[230:233], v[172:175], v[112:115]
	v_mfma_f32_16x16x32_bf16 v[100:103], v[222:225], v[180:183], v[100:103]
	v_mfma_f32_16x16x32_bf16 v[96:99], v[230:233], v[180:183], v[96:99]
	v_mfma_f32_16x16x32_bf16 v[84:87], v[222:225], v[206:209], v[84:87]
	v_mfma_f32_16x16x32_bf16 v[80:83], v[230:233], v[206:209], v[80:83]
	v_mfma_f32_16x16x32_bf16 v[68:71], v[222:225], v[214:217], v[68:71]
	v_mfma_f32_16x16x32_bf16 v[64:67], v[230:233], v[214:217], v[64:67]
	v_mfma_f32_16x16x32_bf16 v[116:119], v[226:229], v[176:179], v[116:119]
	v_mfma_f32_16x16x32_bf16 v[112:115], v[234:237], v[176:179], v[112:115]
	v_mfma_f32_16x16x32_bf16 v[100:103], v[226:229], v[188:191], v[100:103]
	v_mfma_f32_16x16x32_bf16 v[96:99], v[234:237], v[188:191], v[96:99]
	v_mfma_f32_16x16x32_bf16 v[84:87], v[226:229], v[210:213], v[84:87]
	v_mfma_f32_16x16x32_bf16 v[80:83], v[234:237], v[210:213], v[80:83]
	v_mfma_f32_16x16x32_bf16 v[68:71], v[226:229], v[218:221], v[68:71]
	v_mfma_f32_16x16x32_bf16 v[64:67], v[234:237], v[218:221], v[64:67]
	s_setprio 0
	s_add_i32 m0, s59, 0xffffff80
	s_barrier
	ds_read_b128 v[172:175], v156 offset:49152
	ds_read_b128 v[176:179], v156 offset:50176
	ds_read_b128 v[180:183], v156 offset:51200
	ds_read_b128 v[188:191], v156 offset:52224
	ds_read_b128 v[206:209], v156 offset:53248
	ds_read_b128 v[210:213], v156 offset:54272
	ds_read_b128 v[214:217], v156 offset:55296
	ds_read_b128 v[218:221], v156 offset:56320
	global_load_lds_dwordx4 v128, s[42:43] offset:128
	s_add_i32 m0, s60, 0xffffff80
	s_nop 0
	global_load_lds_dwordx4 v132, s[42:43] offset:128
	s_barrier
; #define PG8_STAGE(bufoff, gbase, voff) do { _Pragma("unroll") for (int _i = 0; _i < 2; ++_i) \
;         __builtin_amdgcn_global_load_lds((const unsigned*)((const char*)(gbase) + (voff)[_i]), (LAS unsigned*)(lds + (bufoff) + ldsw + _i * 8192), 16, 0, 0); } while (0)
; #define PG8_LDA(dst, b, h) do { _Pragma("unroll") for (int m = 0; m < 4; ++m) _Pragma("unroll") for (int k = 0; k < 2; ++k) dst[m][k] = *(const LAS bf16x8*)(lds + PG8_SA(b, h) + aoff + m * 2048 + k * 1024); } while (0)
; #define PG8_LDB(dst, b, h) do { _Pragma("unroll") for (int n = 0; n < 2; ++n) _Pragma("unroll") for (int k = 0; k < 2; ++k) dst[n][k] = *(const LAS bf16x8*)(lds + PG8_SB(b, h) + boff + n * 2048 + k * 1024); } while (0)
; #define PG8_MMA(ai, bj, At, Bt) do { __builtin_amdgcn_s_setprio(1); _Pragma("unroll") for (int m = 0; m < 4; ++m) _Pragma("unroll") for (int n = 0; n < 2; ++n) _Pragma("unroll") for (int k = 0; k < 2; ++k) \
;         acc[ai][bj][m][n] = __builtin_amdgcn_mfma_f32_16x16x32_bf16(Bt[n][k], At[m][k], acc[ai][bj][m][n], 0, 0, 0); __builtin_amdgcn_s_setprio(0); } while (0)
; #define PG8_WAIT_V(n) asm volatile("s_waitcnt vmcnt(" #n ")" ::: "memory")
; #define PG8_WAIT_L(n) asm volatile("s_waitcnt lgkmcnt(" #n ")" ::: "memory")
; #define PG8_BAR __builtin_amdgcn_s_barrier()
; #define PG8_SCHED __builtin_amdgcn_sched_barrier(0)
; template <class Epi, class Sched>
; DI void gemm_phase(LAS unsigned char* lds, const Gemm g, const Sched& S, const Epi& E) {
;     ...
;             PG8_LDB(B0, 0, 0); PG8_SCHED; PG8_LDA(At, 0, 0); PG8_STAGE(PG8_SA(1, 1), a1 + hstep, voffA);
;             PG8_WAIT_L(8); PG8_BAR; PG8_WAIT_L(0); PG8_MMA(0, 0, At, B0); PG8_BAR; PG8_SCHED;
;             PG8_LDB(B1, 0, 1); PG8_STAGE(PG8_SB(0, 0), b2, voffB);
;             PG8_BAR; PG8_WAIT_L(0); PG8_MMA(0, 1, At, B1); PG8_BAR;
;             PG8_LDA(At, 0, 1); PG8_STAGE(PG8_SA(0, 0), a2, voffA);
;             PG8_BAR; PG8_WAIT_L(0); PG8_MMA(1, 0, At, B0); PG8_BAR; PG8_SCHED;
;     ...
;             PG8_BAR; PG8_WAIT_L(0); PG8_MMA(1, 0, At, B0); PG8_BAR; PG8_SCHED;
;             PG8_STAGE(PG8_SB(1, 1), b3 + hstep, voffB);
;             PG8_WAIT_V(6); PG8_BAR; PG8_MMA(1, 1, At, B1); PG8_BAR;
	s_waitcnt lgkmcnt(0)
	s_setprio 1
	s_waitcnt lgkmcnt(0)
	v_mfma_f32_16x16x32_bf16 v[60:63], v[144:147], v[172:175], v[60:63]
	v_mfma_f32_16x16x32_bf16 v[56:59], v[164:167], v[172:175], v[56:59]
	v_mfma_f32_16x16x32_bf16 v[44:47], v[144:147], v[180:183], v[44:47]
	v_mfma_f32_16x16x32_bf16 v[40:43], v[164:167], v[180:183], v[40:43]
	v_mfma_f32_16x16x32_bf16 v[28:31], v[144:147], v[206:209], v[28:31]
	v_mfma_f32_16x16x32_bf16 v[24:27], v[164:167], v[206:209], v[24:27]
	v_mfma_f32_16x16x32_bf16 v[12:15], v[144:147], v[214:217], v[12:15]
	v_mfma_f32_16x16x32_bf16 v[8:11], v[164:167], v[214:217], v[8:11]
	v_mfma_f32_16x16x32_bf16 v[60:63], v[160:163], v[176:179], v[60:63]
	v_mfma_f32_16x16x32_bf16 v[56:59], v[168:171], v[176:179], v[56:59]
	v_mfma_f32_16x16x32_bf16 v[44:47], v[160:163], v[188:191], v[44:47]
	v_mfma_f32_16x16x32_bf16 v[40:43], v[168:171], v[188:191], v[40:43]
	v_mfma_f32_16x16x32_bf16 v[28:31], v[160:163], v[210:213], v[28:31]
	v_mfma_f32_16x16x32_bf16 v[24:27], v[168:171], v[210:213], v[24:27]
	v_mfma_f32_16x16x32_bf16 v[12:15], v[160:163], v[218:221], v[12:15]
	v_mfma_f32_16x16x32_bf16 v[8:11], v[168:171], v[218:221], v[8:11]
	s_setprio 0
	s_barrier
	s_add_u32 s0, s40, 0x160080
	s_addc_u32 s1, s41, 0
	s_add_i32 s4, s5, s51
	s_mov_b32 m0, s4
	s_nop 0
	global_load_lds_dwordx4 v130, s[0:1]
	s_add_i32 m0, s4, 0x2000
	s_nop 0
	global_load_lds_dwordx4 v134, s[0:1]
	s_waitcnt vmcnt(6)
	s_barrier
	s_setprio 1
	v_mfma_f32_16x16x32_bf16 v[52:55], v[222:225], v[172:175], v[52:55]
	v_mfma_f32_16x16x32_bf16 v[48:51], v[230:233], v[172:175], v[48:51]
	v_mfma_f32_16x16x32_bf16 v[36:39], v[222:225], v[180:183], v[36:39]
	v_mfma_f32_16x16x32_bf16 v[32:35], v[230:233], v[180:183], v[32:35]
	v_mfma_f32_16x16x32_bf16 v[20:23], v[222:225], v[206:209], v[20:23]
	v_mfma_f32_16x16x32_bf16 v[16:19], v[230:233], v[206:209], v[16:19]
	v_mfma_f32_16x16x32_bf16 v[4:7], v[222:225], v[214:217], v[4:7]
	v_mfma_f32_16x16x32_bf16 v[0:3], v[230:233], v[214:217], v[0:3]
	v_mfma_f32_16x16x32_bf16 v[52:55], v[226:229], v[176:179], v[52:55]
	v_mfma_f32_16x16x32_bf16 v[48:51], v[234:237], v[176:179], v[48:51]
	v_mfma_f32_16x16x32_bf16 v[36:39], v[226:229], v[188:191], v[36:39]
	v_mfma_f32_16x16x32_bf16 v[32:35], v[234:237], v[188:191], v[32:35]
	v_mfma_f32_16x16x32_bf16 v[20:23], v[226:229], v[210:213], v[20:23]
	v_mfma_f32_16x16x32_bf16 v[16:19], v[234:237], v[210:213], v[16:19]
	v_mfma_f32_16x16x32_bf16 v[4:7], v[226:229], v[218:221], v[4:7]
	v_mfma_f32_16x16x32_bf16 v[0:3], v[234:237], v[218:221], v[0:3]
	s_setprio 0
	s_add_i32 s68, s68, 2
	s_add_u32 s38, s38, 0x100
	s_addc_u32 s39, s39, 0
	s_add_u32 s35, s35, 0x100
	s_addc_u32 s67, s67, 0
	s_cmpk_gt_u32 s68, 0x55
	s_barrier
	s_cbranch_scc0 .LBB0_1746
	s_branch .Lpeel_done_1746
.LBB0_1746:
	ds_read_b128 v[144:147], v155
	ds_read_b128 v[160:163], v155 offset:1024
	ds_read_b128 v[164:167], v155 offset:2048
	ds_read_b128 v[168:171], v155 offset:3072
	s_add_u32 s0, s38, 0xffea0080
	s_addc_u32 s1, s39, -1
	s_cmpk_eq_i32 s68, 0x54
	s_cselect_b32 s43, s9, s1
	s_cselect_b32 s42, s8, s0
	s_cselect_b32 s41, s11, s67
	s_cselect_b32 s40, s10, s35
	s_add_i32 m0, s52, 0xc000
	ds_read_b128 v[172:175], v156
	ds_read_b128 v[176:179], v156 offset:1024
	ds_read_b128 v[180:183], v156 offset:2048
	ds_read_b128 v[188:191], v156 offset:3072
	ds_read_b128 v[206:209], v156 offset:4096
	ds_read_b128 v[210:213], v156 offset:5120
	ds_read_b128 v[214:217], v156 offset:6144
	ds_read_b128 v[218:221], v156 offset:7168
	global_load_lds_dwordx4 v136, s[38:39]
	s_add_i32 m0, s52, 0xe000
	s_nop 0
	global_load_lds_dwordx4 v138, s[38:39]
	s_waitcnt lgkmcnt(8)
	s_barrier
	s_waitcnt lgkmcnt(0)
	s_setprio 1
	s_waitcnt lgkmcnt(0)
	v_mfma_f32_16x16x32_bf16 v[124:127], v[144:147], v[172:175], v[124:127]
	v_mfma_f32_16x16x32_bf16 v[120:123], v[164:167], v[172:175], v[120:123]
	v_mfma_f32_16x16x32_bf16 v[108:111], v[144:147], v[180:183], v[108:111]
	v_mfma_f32_16x16x32_bf16 v[104:107], v[164:167], v[180:183], v[104:107]
	v_mfma_f32_16x16x32_bf16 v[92:95], v[144:147], v[206:209], v[92:95]
	v_mfma_f32_16x16x32_bf16 v[88:91], v[164:167], v[206:209], v[88:91]
	v_mfma_f32_16x16x32_bf16 v[76:79], v[144:147], v[214:217], v[76:79]
	v_mfma_f32_16x16x32_bf16 v[72:75], v[164:167], v[214:217], v[72:75]
	v_mfma_f32_16x16x32_bf16 v[124:127], v[160:163], v[176:179], v[124:127]
	v_mfma_f32_16x16x32_bf16 v[120:123], v[168:171], v[176:179], v[120:123]
	v_mfma_f32_16x16x32_bf16 v[108:111], v[160:163], v[188:191], v[108:111]
	v_mfma_f32_16x16x32_bf16 v[104:107], v[168:171], v[188:191], v[104:107]
	v_mfma_f32_16x16x32_bf16 v[92:95], v[160:163], v[210:213], v[92:95]
	v_mfma_f32_16x16x32_bf16 v[88:91], v[168:171], v[210:213], v[88:91]
	v_mfma_f32_16x16x32_bf16 v[76:79], v[160:163], v[218:221], v[76:79]
	v_mfma_f32_16x16x32_bf16 v[72:75], v[168:171], v[218:221], v[72:75]
	s_setprio 0
	s_barrier
	s_add_i32 s0, s61, s51
	s_mov_b32 m0, s0
	ds_read_b128 v[222:225], v157
	ds_read_b128 v[226:229], v157 offset:1024
	ds_read_b128 v[230:233], v157 offset:2048
	ds_read_b128 v[234:237], v157 offset:3072
	global_load_lds_dwordx4 v130, s[40:41]
	s_add_i32 m0, s0, 0x2000
	s_nop 0
	global_load_lds_dwordx4 v134, s[40:41]
	s_barrier
; #define PG8_STAGE(bufoff, gbase, voff) do { _Pragma("unroll") for (int _i = 0; _i < 2; ++_i) \
;         __builtin_amdgcn_global_load_lds((const unsigned*)((const char*)(gbase) + (voff)[_i]), (LAS unsigned*)(lds + (bufoff) + ldsw + _i * 8192), 16, 0, 0); } while (0)
; #define PG8_LDA(dst, b, h) do { _Pragma("unroll") for (int m = 0; m < 4; ++m) _Pragma("unroll") for (int k = 0; k < 2; ++k) dst[m][k] = *(const LAS bf16x8*)(lds + PG8_SA(b, h) + aoff + m * 2048 + k * 1024); } while (0)
; #define PG8_LDB(dst, b, h) do { _Pragma("unroll") for (int n = 0; n < 2; ++n) _Pragma("unroll") for (int k = 0; k < 2; ++k) dst[n][k] = *(const LAS bf16x8*)(lds + PG8_SB(b, h) + boff + n * 2048 + k * 1024); } while (0)
; #define PG8_MMA(ai, bj, At, Bt) do { __builtin_amdgcn_s_setprio(1); _Pragma("unroll") for (int m = 0; m < 4; ++m) _Pragma("unroll") for (int n = 0; n < 2; ++n) _Pragma("unroll") for (int k = 0; k < 2; ++k) \
;         acc[ai][bj][m][n] = __builtin_amdgcn_mfma_f32_16x16x32_bf16(Bt[n][k], At[m][k], acc[ai][bj][m][n], 0, 0, 0); __builtin_amdgcn_s_setprio(0); } while (0)
; #define PG8_WAIT_V(n) asm volatile("s_waitcnt vmcnt(" #n ")" ::: "memory")
; #define PG8_WAIT_L(n) asm volatile("s_waitcnt lgkmcnt(" #n ")" ::: "memory")
; #define PG8_BAR __builtin_amdgcn_s_barrier()
; #define PG8_SCHED __builtin_amdgcn_sched_barrier(0)
; template <class Epi, class Sched>
; DI void gemm_phase(LAS unsigned char* lds, const Gemm g, const Sched& S, const Epi& E) {
;     ...
;             PG8_BAR; PG8_WAIT_L(0); PG8_MMA(1, 0, At, B0); PG8_BAR; PG8_SCHED;
;             PG8_STAGE(PG8_SB(0, 1), b2 + hstep, voffB);
;             PG8_WAIT_V(6); PG8_BAR; PG8_MMA(1, 1, At, B1); PG8_BAR;
;             PG8_LDB(B0, 1, 0); PG8_SCHED; PG8_LDA(At, 1, 0); PG8_STAGE(PG8_SA(0, 1), a2 + hstep, voffA);
;             PG8_WAIT_L(8); PG8_BAR; PG8_WAIT_L(0); PG8_MMA(0, 0, At, B0); PG8_BAR; PG8_SCHED;
	s_waitcnt lgkmcnt(0)
	s_setprio 1
	s_waitcnt lgkmcnt(0)
	v_mfma_f32_16x16x32_bf16 v[116:119], v[222:225], v[172:175], v[116:119]
	v_mfma_f32_16x16x32_bf16 v[112:115], v[230:233], v[172:175], v[112:115]
	v_mfma_f32_16x16x32_bf16 v[100:103], v[222:225], v[180:183], v[100:103]
	v_mfma_f32_16x16x32_bf16 v[96:99], v[230:233], v[180:183], v[96:99]
	v_mfma_f32_16x16x32_bf16 v[84:87], v[222:225], v[206:209], v[84:87]
	v_mfma_f32_16x16x32_bf16 v[80:83], v[230:233], v[206:209], v[80:83]
	v_mfma_f32_16x16x32_bf16 v[68:71], v[222:225], v[214:217], v[68:71]
	v_mfma_f32_16x16x32_bf16 v[64:67], v[230:233], v[214:217], v[64:67]
	v_mfma_f32_16x16x32_bf16 v[116:119], v[226:229], v[176:179], v[116:119]
	v_mfma_f32_16x16x32_bf16 v[112:115], v[234:237], v[176:179], v[112:115]
	v_mfma_f32_16x16x32_bf16 v[100:103], v[226:229], v[188:191], v[100:103]
	v_mfma_f32_16x16x32_bf16 v[96:99], v[234:237], v[188:191], v[96:99]
	v_mfma_f32_16x16x32_bf16 v[84:87], v[226:229], v[210:213], v[84:87]
	v_mfma_f32_16x16x32_bf16 v[80:83], v[234:237], v[210:213], v[80:83]
	v_mfma_f32_16x16x32_bf16 v[68:71], v[226:229], v[218:221], v[68:71]
	v_mfma_f32_16x16x32_bf16 v[64:67], v[234:237], v[218:221], v[64:67]
	s_setprio 0
	s_mov_b32 m0, s52
	s_barrier
	ds_read_b128 v[172:175], v156 offset:16384
	ds_read_b128 v[176:179], v156 offset:17408
	ds_read_b128 v[180:183], v156 offset:18432
	ds_read_b128 v[188:191], v156 offset:19456
	ds_read_b128 v[206:209], v156 offset:20480
	ds_read_b128 v[210:213], v156 offset:21504
	ds_read_b128 v[214:217], v156 offset:22528
	ds_read_b128 v[218:221], v156 offset:23552
	global_load_lds_dwordx4 v128, s[42:43]
	s_mov_b32 m0, s53
	s_nop 0
	global_load_lds_dwordx4 v132, s[42:43]
	s_barrier
	s_waitcnt lgkmcnt(0)
	s_setprio 1
	s_waitcnt lgkmcnt(0)
	v_mfma_f32_16x16x32_bf16 v[60:63], v[144:147], v[172:175], v[60:63]
	v_mfma_f32_16x16x32_bf16 v[56:59], v[164:167], v[172:175], v[56:59]
	v_mfma_f32_16x16x32_bf16 v[44:47], v[144:147], v[180:183], v[44:47]
	v_mfma_f32_16x16x32_bf16 v[40:43], v[164:167], v[180:183], v[40:43]
	v_mfma_f32_16x16x32_bf16 v[28:31], v[144:147], v[206:209], v[28:31]
	v_mfma_f32_16x16x32_bf16 v[24:27], v[164:167], v[206:209], v[24:27]
	v_mfma_f32_16x16x32_bf16 v[12:15], v[144:147], v[214:217], v[12:15]
	v_mfma_f32_16x16x32_bf16 v[8:11], v[164:167], v[214:217], v[8:11]
	v_mfma_f32_16x16x32_bf16 v[60:63], v[160:163], v[176:179], v[60:63]
	v_mfma_f32_16x16x32_bf16 v[56:59], v[168:171], v[176:179], v[56:59]
	v_mfma_f32_16x16x32_bf16 v[44:47], v[160:163], v[188:191], v[44:47]
	v_mfma_f32_16x16x32_bf16 v[40:43], v[168:171], v[188:191], v[40:43]
	v_mfma_f32_16x16x32_bf16 v[28:31], v[160:163], v[210:213], v[28:31]
	v_mfma_f32_16x16x32_bf16 v[24:27], v[168:171], v[210:213], v[24:27]
	v_mfma_f32_16x16x32_bf16 v[12:15], v[160:163], v[218:221], v[12:15]
	v_mfma_f32_16x16x32_bf16 v[8:11], v[168:171], v[218:221], v[8:11]
	s_setprio 0
	s_barrier
	s_add_u32 s0, s40, 0x160000
	s_addc_u32 s1, s41, 0
	s_add_i32 s4, s62, s51
	s_mov_b32 m0, s4
	s_nop 0
	global_load_lds_dwordx4 v130, s[0:1]
	s_add_i32 m0, s4, 0x2000
	s_nop 0
	global_load_lds_dwordx4 v134, s[0:1]
	s_waitcnt vmcnt(6)
	s_barrier
	s_setprio 1
	v_mfma_f32_16x16x32_bf16 v[52:55], v[222:225], v[172:175], v[52:55]
	v_mfma_f32_16x16x32_bf16 v[48:51], v[230:233], v[172:175], v[48:51]
	v_mfma_f32_16x16x32_bf16 v[36:39], v[222:225], v[180:183], v[36:39]
	v_mfma_f32_16x16x32_bf16 v[32:35], v[230:233], v[180:183], v[32:35]
	v_mfma_f32_16x16x32_bf16 v[20:23], v[222:225], v[206:209], v[20:23]
	v_mfma_f32_16x16x32_bf16 v[16:19], v[230:233], v[206:209], v[16:19]
	v_mfma_f32_16x16x32_bf16 v[4:7], v[222:225], v[214:217], v[4:7]
	v_mfma_f32_16x16x32_bf16 v[0:3], v[230:233], v[214:217], v[0:3]
	v_mfma_f32_16x16x32_bf16 v[52:55], v[226:229], v[176:179], v[52:55]
	v_mfma_f32_16x16x32_bf16 v[48:51], v[234:237], v[176:179], v[48:51]
	v_mfma_f32_16x16x32_bf16 v[36:39], v[226:229], v[188:191], v[36:39]
	v_mfma_f32_16x16x32_bf16 v[32:35], v[234:237], v[188:191], v[32:35]
	v_mfma_f32_16x16x32_bf16 v[20:23], v[226:229], v[210:213], v[20:23]
	v_mfma_f32_16x16x32_bf16 v[16:19], v[234:237], v[210:213], v[16:19]
	v_mfma_f32_16x16x32_bf16 v[4:7], v[226:229], v[218:221], v[4:7]
	v_mfma_f32_16x16x32_bf16 v[0:3], v[234:237], v[218:221], v[0:3]
	s_setprio 0
	s_add_i32 s4, 0, 0x18000
	v_add_u32_e32 v159, s4, v154
	s_barrier
	ds_read_b128 v[144:147], v159
	ds_read_b128 v[160:163], v159 offset:1024
	ds_read_b128 v[164:167], v159 offset:2048
	ds_read_b128 v[168:171], v159 offset:3072
	s_add_u32 s0, s42, 0x160000
	s_addc_u32 s1, s43, 0
	s_mov_b32 m0, s54
	ds_read_b128 v[172:175], v156 offset:32768
	ds_read_b128 v[176:179], v156 offset:33792
	ds_read_b128 v[180:183], v156 offset:34816
	ds_read_b128 v[188:191], v156 offset:35840
	ds_read_b128 v[206:209], v156 offset:36864
	ds_read_b128 v[210:213], v156 offset:37888
	ds_read_b128 v[214:217], v156 offset:38912
	ds_read_b128 v[218:221], v156 offset:39936
	global_load_lds_dwordx4 v128, s[0:1]
	s_mov_b32 m0, s55
	s_nop 0
	global_load_lds_dwordx4 v132, s[0:1]
	s_waitcnt lgkmcnt(8)
	s_barrier
; #define PG8_STAGE(bufoff, gbase, voff) do { _Pragma("unroll") for (int _i = 0; _i < 2; ++_i) \
;         __builtin_amdgcn_global_load_lds((const unsigned*)((const char*)(gbase) + (voff)[_i]), (LAS unsigned*)(lds + (bufoff) + ldsw + _i * 8192), 16, 0, 0); } while (0)
; #define PG8_LDA(dst, b, h) do { _Pragma("unroll") for (int m = 0; m < 4; ++m) _Pragma("unroll") for (int k = 0; k < 2; ++k) dst[m][k] = *(const LAS bf16x8*)(lds + PG8_SA(b, h) + aoff + m * 2048 + k * 1024); } while (0)
; #define PG8_MMA(ai, bj, At, Bt) do { __builtin_amdgcn_s_setprio(1); _Pragma("unroll") for (int m = 0; m < 4; ++m) _Pragma("unroll") for (int n = 0; n < 2; ++n) _Pragma("unroll") for (int k = 0; k < 2; ++k) \
;         acc[ai][bj][m][n] = __builtin_amdgcn_mfma_f32_16x16x32_bf16(Bt[n][k], At[m][k], acc[ai][bj][m][n], 0, 0, 0); __builtin_amdgcn_s_setprio(0); } while (0)
; #define PG8_WAIT_V(n) asm volatile("s_waitcnt vmcnt(" #n ")" ::: "memory")
; #define PG8_WAIT_L(n) asm volatile("s_waitcnt lgkmcnt(" #n ")" ::: "memory")
; #define PG8_BAR __builtin_amdgcn_s_barrier()
; #define PG8_SCHED __builtin_amdgcn_sched_barrier(0)
; template <class Epi, class Sched>
; DI void gemm_phase(LAS unsigned char* lds, const Gemm g, const Sched& S, const Epi& E) {
;     ...
;             PG8_BAR; PG8_WAIT_L(0); PG8_MMA(0, 1, At, B1); PG8_BAR;
;             PG8_LDA(At, 1, 1); PG8_STAGE(PG8_SA(1, 0), a3, voffA);
;             PG8_BAR; PG8_WAIT_L(0); PG8_MMA(1, 0, At, B0); PG8_BAR; PG8_SCHED;
;             PG8_STAGE(PG8_SB(1, 1), b3 + hstep, voffB);
;             PG8_WAIT_V(6); PG8_BAR; PG8_MMA(1, 1, At, B1); PG8_BAR;
	s_waitcnt lgkmcnt(0)
	s_setprio 1
	s_waitcnt lgkmcnt(0)
	v_mfma_f32_16x16x32_bf16 v[124:127], v[144:147], v[172:175], v[124:127]
	v_mfma_f32_16x16x32_bf16 v[120:123], v[164:167], v[172:175], v[120:123]
	v_mfma_f32_16x16x32_bf16 v[108:111], v[144:147], v[180:183], v[108:111]
	v_mfma_f32_16x16x32_bf16 v[104:107], v[164:167], v[180:183], v[104:107]
	v_mfma_f32_16x16x32_bf16 v[92:95], v[144:147], v[206:209], v[92:95]
	v_mfma_f32_16x16x32_bf16 v[88:91], v[164:167], v[206:209], v[88:91]
	v_mfma_f32_16x16x32_bf16 v[76:79], v[144:147], v[214:217], v[76:79]
	v_mfma_f32_16x16x32_bf16 v[72:75], v[164:167], v[214:217], v[72:75]
	v_mfma_f32_16x16x32_bf16 v[124:127], v[160:163], v[176:179], v[124:127]
	v_mfma_f32_16x16x32_bf16 v[120:123], v[168:171], v[176:179], v[120:123]
	v_mfma_f32_16x16x32_bf16 v[108:111], v[160:163], v[188:191], v[108:111]
	v_mfma_f32_16x16x32_bf16 v[104:107], v[168:171], v[188:191], v[104:107]
	v_mfma_f32_16x16x32_bf16 v[92:95], v[160:163], v[210:213], v[92:95]
	v_mfma_f32_16x16x32_bf16 v[88:91], v[168:171], v[210:213], v[88:91]
	v_mfma_f32_16x16x32_bf16 v[76:79], v[160:163], v[218:221], v[76:79]
	v_mfma_f32_16x16x32_bf16 v[72:75], v[168:171], v[218:221], v[72:75]
	s_setprio 0
	s_barrier
	s_add_i32 s5, 0, 0x1c000
	s_add_i32 s0, s4, s51
	v_add_u32_e32 v159, s5, v154
	s_add_i32 m0, s0, 0xffffff80
	ds_read_b128 v[222:225], v159
	ds_read_b128 v[226:229], v159 offset:1024
	ds_read_b128 v[230:233], v159 offset:2048
	ds_read_b128 v[234:237], v159 offset:3072
	global_load_lds_dwordx4 v130, s[40:41] offset:128
	s_add_i32 m0, s0, 0x1f80
	s_nop 0
	global_load_lds_dwordx4 v134, s[40:41] offset:128
	s_barrier
	s_waitcnt lgkmcnt(0)
	s_setprio 1
	s_waitcnt lgkmcnt(0)
	v_mfma_f32_16x16x32_bf16 v[116:119], v[222:225], v[172:175], v[116:119]
	v_mfma_f32_16x16x32_bf16 v[112:115], v[230:233], v[172:175], v[112:115]
	v_mfma_f32_16x16x32_bf16 v[100:103], v[222:225], v[180:183], v[100:103]
	v_mfma_f32_16x16x32_bf16 v[96:99], v[230:233], v[180:183], v[96:99]
	v_mfma_f32_16x16x32_bf16 v[84:87], v[222:225], v[206:209], v[84:87]
	v_mfma_f32_16x16x32_bf16 v[80:83], v[230:233], v[206:209], v[80:83]
	v_mfma_f32_16x16x32_bf16 v[68:71], v[222:225], v[214:217], v[68:71]
	v_mfma_f32_16x16x32_bf16 v[64:67], v[230:233], v[214:217], v[64:67]
	v_mfma_f32_16x16x32_bf16 v[116:119], v[226:229], v[176:179], v[116:119]
	v_mfma_f32_16x16x32_bf16 v[112:115], v[234:237], v[176:179], v[112:115]
	v_mfma_f32_16x16x32_bf16 v[100:103], v[226:229], v[188:191], v[100:103]
	v_mfma_f32_16x16x32_bf16 v[96:99], v[234:237], v[188:191], v[96:99]
	v_mfma_f32_16x16x32_bf16 v[84:87], v[226:229], v[210:213], v[84:87]
	v_mfma_f32_16x16x32_bf16 v[80:83], v[234:237], v[210:213], v[80:83]
	v_mfma_f32_16x16x32_bf16 v[68:71], v[226:229], v[218:221], v[68:71]
	v_mfma_f32_16x16x32_bf16 v[64:67], v[234:237], v[218:221], v[64:67]
	s_setprio 0
	s_add_i32 m0, s59, 0xffffff80
	s_barrier
	ds_read_b128 v[172:175], v156 offset:49152
	ds_read_b128 v[176:179], v156 offset:50176
	ds_read_b128 v[180:183], v156 offset:51200
	ds_read_b128 v[188:191], v156 offset:52224
	ds_read_b128 v[206:209], v156 offset:53248
	ds_read_b128 v[210:213], v156 offset:54272
	ds_read_b128 v[214:217], v156 offset:55296
	ds_read_b128 v[218:221], v156 offset:56320
	global_load_lds_dwordx4 v128, s[42:43] offset:128
	s_add_i32 m0, s60, 0xffffff80
	s_nop 0
	global_load_lds_dwordx4 v132, s[42:43] offset:128
	s_barrier
	s_waitcnt lgkmcnt(0)
	s_setprio 1
	s_waitcnt lgkmcnt(0)
	v_mfma_f32_16x16x32_bf16 v[60:63], v[144:147], v[172:175], v[60:63]
	v_mfma_f32_16x16x32_bf16 v[56:59], v[164:167], v[172:175], v[56:59]
	v_mfma_f32_16x16x32_bf16 v[44:47], v[144:147], v[180:183], v[44:47]
	v_mfma_f32_16x16x32_bf16 v[40:43], v[164:167], v[180:183], v[40:43]
	v_mfma_f32_16x16x32_bf16 v[28:31], v[144:147], v[206:209], v[28:31]
	v_mfma_f32_16x16x32_bf16 v[24:27], v[164:167], v[206:209], v[24:27]
	v_mfma_f32_16x16x32_bf16 v[12:15], v[144:147], v[214:217], v[12:15]
	v_mfma_f32_16x16x32_bf16 v[8:11], v[164:167], v[214:217], v[8:11]
	v_mfma_f32_16x16x32_bf16 v[60:63], v[160:163], v[176:179], v[60:63]
	v_mfma_f32_16x16x32_bf16 v[56:59], v[168:171], v[176:179], v[56:59]
	v_mfma_f32_16x16x32_bf16 v[44:47], v[160:163], v[188:191], v[44:47]
	v_mfma_f32_16x16x32_bf16 v[40:43], v[168:171], v[188:191], v[40:43]
	v_mfma_f32_16x16x32_bf16 v[28:31], v[160:163], v[210:213], v[28:31]
	v_mfma_f32_16x16x32_bf16 v[24:27], v[168:171], v[210:213], v[24:27]
	v_mfma_f32_16x16x32_bf16 v[12:15], v[160:163], v[218:221], v[12:15]
	v_mfma_f32_16x16x32_bf16 v[8:11], v[168:171], v[218:221], v[8:11]
	s_setprio 0
	s_barrier
	s_add_u32 s0, s40, 0x160080
	s_addc_u32 s1, s41, 0
	s_add_i32 s4, s5, s51
	s_mov_b32 m0, s4
	s_nop 0
	global_load_lds_dwordx4 v130, s[0:1]
	s_add_i32 m0, s4, 0x2000
	s_nop 0
	global_load_lds_dwordx4 v134, s[0:1]
	s_waitcnt vmcnt(6)
	s_barrier
	s_setprio 1
	v_mfma_f32_16x16x32_bf16 v[52:55], v[222:225], v[172:175], v[52:55]
	v_mfma_f32_16x16x32_bf16 v[48:51], v[230:233], v[172:175], v[48:51]
	v_mfma_f32_16x16x32_bf16 v[36:39], v[222:225], v[180:183], v[36:39]
	v_mfma_f32_16x16x32_bf16 v[32:35], v[230:233], v[180:183], v[32:35]
	v_mfma_f32_16x16x32_bf16 v[20:23], v[222:225], v[206:209], v[20:23]
	v_mfma_f32_16x16x32_bf16 v[16:19], v[230:233], v[206:209], v[16:19]
	v_mfma_f32_16x16x32_bf16 v[4:7], v[222:225], v[214:217], v[4:7]
	v_mfma_f32_16x16x32_bf16 v[0:3], v[230:233], v[214:217], v[0:3]
	v_mfma_f32_16x16x32_bf16 v[52:55], v[226:229], v[176:179], v[52:55]
	v_mfma_f32_16x16x32_bf16 v[48:51], v[234:237], v[176:179], v[48:51]
	v_mfma_f32_16x16x32_bf16 v[36:39], v[226:229], v[188:191], v[36:39]
	v_mfma_f32_16x16x32_bf16 v[32:35], v[234:237], v[188:191], v[32:35]
	v_mfma_f32_16x16x32_bf16 v[20:23], v[226:229], v[210:213], v[20:23]
	v_mfma_f32_16x16x32_bf16 v[16:19], v[234:237], v[210:213], v[16:19]
	v_mfma_f32_16x16x32_bf16 v[4:7], v[226:229], v[218:221], v[4:7]
	v_mfma_f32_16x16x32_bf16 v[0:3], v[234:237], v[218:221], v[0:3]
	s_setprio 0
	s_add_i32 s68, s68, 2
	s_add_u32 s38, s38, 0x100
	s_addc_u32 s39, s39, 0
	s_add_u32 s35, s35, 0x100
	s_addc_u32 s67, s67, 0
	s_cmpk_gt_u32 s68, 0x55
	s_barrier
	s_cbranch_scc0 .LBB0_1746

; #define PG8_STAGE(bufoff, gbase, voff) do { _Pragma("unroll") for (int _i = 0; _i < 2; ++_i) \
;         __builtin_amdgcn_global_load_lds((const unsigned*)((const char*)(gbase) + (voff)[_i]), (LAS unsigned*)(lds + (bufoff) + ldsw + _i * 8192), 16, 0, 0); } while (0)
; #define PG8_WAIT_V(n) asm volatile("s_waitcnt vmcnt(" #n ")" ::: "memory")
; #define PG8_BAR __builtin_amdgcn_s_barrier()
; template <class Epi, class Sched>
; DI void gemm_phase(LAS unsigned char* lds, const Gemm g, const Sched& S, const Epi& E) {
;     ...
;     PG8_STAGE(PG8_SB(0, 0), cB, voffB); PG8_STAGE(PG8_SA(0, 0), cA, voffA); PG8_STAGE(PG8_SB(0, 1), cB + hstep, voffB); PG8_STAGE(PG8_SA(0, 1), cA + hstep, voffA);
;     if (wr == 1) PG8_BAR;
;     PG8_WAIT_V(4); PG8_BAR;
;     PG8_STAGE(PG8_SB(1, 0), cB + kstep, voffB); PG8_STAGE(PG8_SA(1, 0), cA + kstep, voffA); PG8_STAGE(PG8_SB(1, 1), cB + hstep + kstep, voffB);
;     PG8_WAIT_V(6); PG8_BAR;
;     const int kc = K / S; pg8::Gemm g{A, Bt, K, kc / 64}; pg8::SplitOrder O; O.init(N, S, kc, 128, (int)gridDim.x, (int)((blockIdx.x + rot) % gridDim.x));
.LBB0_1769:
	s_lshl_b32 s0, s0, 5
	s_lshl_b32 s50, s1, 6
	s_lshl_b32 s4, s1, 13
	s_and_b32 s51, s0, 0x60
	s_add_u32 s52, s22, 0x3c40b000
	s_addc_u32 s53, s23, 0
	s_mov_b64 s[10:11], 0x80
	s_add_u32 s0, s30, 0x160080
	v_lshl_add_u64 v[0:1], v[0:1], 0, s[10:11]
	s_addc_u32 s1, s31, 0
	s_add_i32 m0, s40, 0x18000
	v_lshl_add_u64 v[2:3], v[2:3], 0, s[10:11]
	s_waitcnt vmcnt(4)
	s_barrier
	global_load_lds_dwordx4 v[0:1], off
	s_add_i32 m0, s40, 0x1a000
	s_add_i32 s54, s40, 0x8000
	v_lshl_add_u64 v[4:5], v[4:5], 0, s[10:11]
	global_load_lds_dwordx4 v[2:3], off
	s_mov_b32 m0, s54
	s_add_i32 s55, s40, 0xa000
	v_lshl_add_u64 v[6:7], v[6:7], 0, s[10:11]
	global_load_lds_dwordx4 v[4:5], off
	s_mov_b32 m0, s55
	s_nop 0
	global_load_lds_dwordx4 v[6:7], off
	s_add_i32 m0, s40, 0x1c000
	s_nop 0
	global_load_lds_dwordx4 v130, s[0:1]
	s_add_i32 m0, s40, 0x1e000
	v_lshlrev_b32_e32 v1, 2, v194
	global_load_lds_dwordx4 v128, s[0:1]
	v_lshl_or_b32 v0, v194, 6, v195
	v_and_b32_e32 v1, 32, v1
	v_lshl_or_b32 v140, s51, 7, v149
	s_waitcnt vmcnt(6)
	s_add_i32 s58, 0, 0x10000
	s_add_i32 s60, 0, 0x14000
	v_bitop3_b32 v0, v0, s4, v1 bitop3:0xde
	v_add_u32_e32 v141, s58, v140
	v_add_u32_e32 v143, s60, v140
	s_add_i32 s58, s58, s35
	s_add_i32 s60, s60, s35
	s_add_i32 s62, 0, 0x18000
	v_add3_u32 v132, v9, v148, v196
	v_mov_b32_e32 v133, v131
	v_add3_u32 v134, v8, v148, v196
	v_mov_b32_e32 v135, v131
	v_mov_b64_e32 v[136:137], 0x58
	v_mov_b64_e32 v[138:139], 0x57
	v_add_u32_e32 v142, 0, v0
	s_add_i32 s56, s40, 0xc000
	s_add_i32 s57, s40, 0xe000
	s_add_i32 s59, s58, 0x2000
	s_add_i32 s61, s60, 0x2000
	v_add_u32_e32 v144, s62, v140
	s_barrier

; #define PG8_STAGE(bufoff, gbase, voff) do { _Pragma("unroll") for (int _i = 0; _i < 2; ++_i) \
;         __builtin_amdgcn_global_load_lds((const unsigned*)((const char*)(gbase) + (voff)[_i]), (LAS unsigned*)(lds + (bufoff) + ldsw + _i * 8192), 16, 0, 0); } while (0)
; #define PG8_LDA(dst, b, h) do { _Pragma("unroll") for (int m = 0; m < 4; ++m) _Pragma("unroll") for (int k = 0; k < 2; ++k) dst[m][k] = *(const LAS bf16x8*)(lds + PG8_SA(b, h) + aoff + m * 2048 + k * 1024); } while (0)
; #define PG8_LDB(dst, b, h) do { _Pragma("unroll") for (int n = 0; n < 2; ++n) _Pragma("unroll") for (int k = 0; k < 2; ++k) dst[n][k] = *(const LAS bf16x8*)(lds + PG8_SB(b, h) + boff + n * 2048 + k * 1024); } while (0)
; #define PG8_MMA(ai, bj, At, Bt) do { __builtin_amdgcn_s_setprio(1); _Pragma("unroll") for (int m = 0; m < 4; ++m) _Pragma("unroll") for (int n = 0; n < 2; ++n) _Pragma("unroll") for (int k = 0; k < 2; ++k) \
;         acc[ai][bj][m][n] = __builtin_amdgcn_mfma_f32_16x16x32_bf16(Bt[n][k], At[m][k], acc[ai][bj][m][n], 0, 0, 0); __builtin_amdgcn_s_setprio(0); } while (0)
; #define PG8_WAIT_V(n) asm volatile("s_waitcnt vmcnt(" #n ")" ::: "memory")
; #define PG8_WAIT_L(n) asm volatile("s_waitcnt lgkmcnt(" #n ")" ::: "memory")
; #define PG8_BAR __builtin_amdgcn_s_barrier()
; #define PG8_SCHED __builtin_amdgcn_sched_barrier(0)
; template <class Epi, class Sched>
; DI void gemm_phase(LAS unsigned char* lds, const Gemm g, const Sched& S, const Epi& E) {
;     ...
;             PG8_LDB(B0, 0, 0); PG8_SCHED; PG8_LDA(At, 0, 0); PG8_STAGE(PG8_SA(1, 1), a1 + hstep, voffA);
;             PG8_WAIT_L(8); PG8_BAR; PG8_WAIT_L(0); PG8_MMA(0, 0, At, B0); PG8_BAR; PG8_SCHED;
;             PG8_LDB(B1, 0, 1); PG8_STAGE(PG8_SB(0, 0), b2, voffB);
;             PG8_BAR; PG8_WAIT_L(0); PG8_MMA(0, 1, At, B1); PG8_BAR;
;             PG8_LDA(At, 0, 1); PG8_STAGE(PG8_SA(0, 0), a2, voffA);
;             PG8_BAR; PG8_WAIT_L(0); PG8_MMA(1, 0, At, B0); PG8_BAR; PG8_SCHED;
;             PG8_STAGE(PG8_SB(0, 1), b2 + hstep, voffB);
;             PG8_WAIT_V(6); PG8_BAR; PG8_MMA(1, 1, At, B1); PG8_BAR;
.LBB0_1774:
	s_add_u32 s28, s38, s28
	s_addc_u32 s29, s39, s29
	s_and_b64 s[0:1], s[8:9], exec
	s_cselect_b32 s15, s29, s37
	s_cselect_b32 s17, s28, s36
	s_add_u32 s8, s36, 0x160080
	s_addc_u32 s9, s37, 0
	s_add_u32 s64, s30, 0x100
	v_mov_b32_e32 v0, 0
	s_addc_u32 s65, s31, 0
	s_mov_b32 s66, -2
	ds_read_b128 v[146:149], v141
	ds_read_b128 v[154:157], v141 offset:1024
	ds_read_b128 v[158:161], v141 offset:2048
	ds_read_b128 v[162:165], v141 offset:3072
	s_add_u32 s0, s8, 0xffea0080
	s_addc_u32 s1, s9, -1
	s_cmp_eq_u32 s66, 4
	s_cselect_b32 s37, s15, s1
	s_cselect_b32 s36, s17, s0
	s_cselect_b32 s31, s19, s65
	s_cselect_b32 s30, s18, s64
	s_mov_b32 m0, s56
	ds_read_b128 v[166:169], v142
	ds_read_b128 v[170:173], v142 offset:1024
	ds_read_b128 v[174:177], v142 offset:2048
	ds_read_b128 v[178:181], v142 offset:3072
	ds_read_b128 v[188:191], v142 offset:4096
	ds_read_b128 v[206:209], v142 offset:5120
	ds_read_b128 v[210:213], v142 offset:6144
	ds_read_b128 v[214:217], v142 offset:7168
	global_load_lds_dwordx4 v132, s[8:9]
	s_mov_b32 m0, s57
	s_nop 0
	global_load_lds_dwordx4 v134, s[8:9]
	s_waitcnt lgkmcnt(8)
	s_barrier
	s_waitcnt lgkmcnt(0)
	s_setprio 1
	s_waitcnt lgkmcnt(0)
	v_mfma_f32_16x16x32_bf16 v[124:127], v[146:149], v[166:169], 0
	v_mfma_f32_16x16x32_bf16 v[120:123], v[158:161], v[166:169], 0
	v_mfma_f32_16x16x32_bf16 v[116:119], v[146:149], v[174:177], 0
	v_mfma_f32_16x16x32_bf16 v[112:115], v[158:161], v[174:177], 0
	v_mfma_f32_16x16x32_bf16 v[104:107], v[146:149], v[188:191], 0
	v_mfma_f32_16x16x32_bf16 v[96:99], v[158:161], v[188:191], 0
	v_mfma_f32_16x16x32_bf16 v[88:91], v[146:149], v[210:213], 0
	v_mfma_f32_16x16x32_bf16 v[80:83], v[158:161], v[210:213], 0
	v_mfma_f32_16x16x32_bf16 v[124:127], v[154:157], v[170:173], v[124:127]
	v_mfma_f32_16x16x32_bf16 v[120:123], v[162:165], v[170:173], v[120:123]
	v_mfma_f32_16x16x32_bf16 v[116:119], v[154:157], v[178:181], v[116:119]
	v_mfma_f32_16x16x32_bf16 v[112:115], v[162:165], v[178:181], v[112:115]
	v_mfma_f32_16x16x32_bf16 v[104:107], v[154:157], v[206:209], v[104:107]
	v_mfma_f32_16x16x32_bf16 v[96:99], v[162:165], v[206:209], v[96:99]
	v_mfma_f32_16x16x32_bf16 v[88:91], v[154:157], v[214:217], v[88:91]
	v_mfma_f32_16x16x32_bf16 v[80:83], v[162:165], v[214:217], v[80:83]
	s_setprio 0
	s_barrier
	s_mov_b32 m0, s58
	ds_read_b128 v[218:221], v143
	ds_read_b128 v[222:225], v143 offset:1024
	ds_read_b128 v[226:229], v143 offset:2048
	ds_read_b128 v[230:233], v143 offset:3072
	global_load_lds_dwordx4 v130, s[30:31]
	s_mov_b32 m0, s59
	s_nop 0
	global_load_lds_dwordx4 v128, s[30:31]
	s_barrier
	s_waitcnt lgkmcnt(0)
	s_setprio 1
	s_waitcnt lgkmcnt(0)
	v_mfma_f32_16x16x32_bf16 v[108:111], v[218:221], v[166:169], 0
	v_mfma_f32_16x16x32_bf16 v[100:103], v[226:229], v[166:169], 0
	v_mfma_f32_16x16x32_bf16 v[92:95], v[218:221], v[174:177], 0
	v_mfma_f32_16x16x32_bf16 v[84:87], v[226:229], v[174:177], 0
	v_mfma_f32_16x16x32_bf16 v[76:79], v[218:221], v[188:191], 0
	v_mfma_f32_16x16x32_bf16 v[72:75], v[226:229], v[188:191], 0
	v_mfma_f32_16x16x32_bf16 v[68:71], v[218:221], v[210:213], 0
	v_mfma_f32_16x16x32_bf16 v[64:67], v[226:229], v[210:213], 0
	v_mfma_f32_16x16x32_bf16 v[108:111], v[222:225], v[170:173], v[108:111]
	v_mfma_f32_16x16x32_bf16 v[100:103], v[230:233], v[170:173], v[100:103]
	v_mfma_f32_16x16x32_bf16 v[92:95], v[222:225], v[178:181], v[92:95]
	v_mfma_f32_16x16x32_bf16 v[84:87], v[230:233], v[178:181], v[84:87]
	v_mfma_f32_16x16x32_bf16 v[76:79], v[222:225], v[206:209], v[76:79]
	v_mfma_f32_16x16x32_bf16 v[72:75], v[230:233], v[206:209], v[72:75]
	v_mfma_f32_16x16x32_bf16 v[68:71], v[222:225], v[214:217], v[68:71]
	v_mfma_f32_16x16x32_bf16 v[64:67], v[230:233], v[214:217], v[64:67]
	s_setprio 0
	s_mov_b32 m0, s40
	s_barrier
	ds_read_b128 v[166:169], v142 offset:16384
	ds_read_b128 v[170:173], v142 offset:17408
	ds_read_b128 v[174:177], v142 offset:18432
	ds_read_b128 v[178:181], v142 offset:19456
	ds_read_b128 v[188:191], v142 offset:20480
	ds_read_b128 v[206:209], v142 offset:21504
	ds_read_b128 v[210:213], v142 offset:22528
	ds_read_b128 v[214:217], v142 offset:23552
	global_load_lds_dwordx4 v130, s[36:37]
	s_mov_b32 m0, s41
	s_nop 0
	global_load_lds_dwordx4 v128, s[36:37]
	s_barrier
	s_waitcnt lgkmcnt(0)
	s_setprio 1
	s_waitcnt lgkmcnt(0)
	v_mfma_f32_16x16x32_bf16 v[60:63], v[146:149], v[166:169], 0
	v_mfma_f32_16x16x32_bf16 v[56:59], v[158:161], v[166:169], 0
	v_mfma_f32_16x16x32_bf16 v[52:55], v[146:149], v[174:177], 0
	v_mfma_f32_16x16x32_bf16 v[48:51], v[158:161], v[174:177], 0
	v_mfma_f32_16x16x32_bf16 v[40:43], v[146:149], v[188:191], 0
	v_mfma_f32_16x16x32_bf16 v[32:35], v[158:161], v[188:191], 0
	v_mfma_f32_16x16x32_bf16 v[24:27], v[146:149], v[210:213], 0
	v_mfma_f32_16x16x32_bf16 v[16:19], v[158:161], v[210:213], 0
	v_mfma_f32_16x16x32_bf16 v[60:63], v[154:157], v[170:173], v[60:63]
	v_mfma_f32_16x16x32_bf16 v[56:59], v[162:165], v[170:173], v[56:59]
	v_mfma_f32_16x16x32_bf16 v[52:55], v[154:157], v[178:181], v[52:55]
	v_mfma_f32_16x16x32_bf16 v[48:51], v[162:165], v[178:181], v[48:51]
	v_mfma_f32_16x16x32_bf16 v[40:43], v[154:157], v[206:209], v[40:43]
	v_mfma_f32_16x16x32_bf16 v[32:35], v[162:165], v[206:209], v[32:35]
	v_mfma_f32_16x16x32_bf16 v[24:27], v[154:157], v[214:217], v[24:27]
	v_mfma_f32_16x16x32_bf16 v[16:19], v[162:165], v[214:217], v[16:19]
	s_setprio 0
	s_barrier
	s_add_u32 s0, s30, 0x160000
	s_addc_u32 s1, s31, 0
	s_mov_b32 m0, s60
	s_nop 0
	global_load_lds_dwordx4 v130, s[0:1]
	s_mov_b32 m0, s61
	s_nop 0
	global_load_lds_dwordx4 v128, s[0:1]
	s_waitcnt vmcnt(6)
	s_barrier
; #define PG8_STAGE(bufoff, gbase, voff) do { _Pragma("unroll") for (int _i = 0; _i < 2; ++_i) \
;         __builtin_amdgcn_global_load_lds((const unsigned*)((const char*)(gbase) + (voff)[_i]), (LAS unsigned*)(lds + (bufoff) + ldsw + _i * 8192), 16, 0, 0); } while (0)
; #define PG8_LDA(dst, b, h) do { _Pragma("unroll") for (int m = 0; m < 4; ++m) _Pragma("unroll") for (int k = 0; k < 2; ++k) dst[m][k] = *(const LAS bf16x8*)(lds + PG8_SA(b, h) + aoff + m * 2048 + k * 1024); } while (0)
; #define PG8_LDB(dst, b, h) do { _Pragma("unroll") for (int n = 0; n < 2; ++n) _Pragma("unroll") for (int k = 0; k < 2; ++k) dst[n][k] = *(const LAS bf16x8*)(lds + PG8_SB(b, h) + boff + n * 2048 + k * 1024); } while (0)
; #define PG8_MMA(ai, bj, At, Bt) do { __builtin_amdgcn_s_setprio(1); _Pragma("unroll") for (int m = 0; m < 4; ++m) _Pragma("unroll") for (int n = 0; n < 2; ++n) _Pragma("unroll") for (int k = 0; k < 2; ++k) \
;         acc[ai][bj][m][n] = __builtin_amdgcn_mfma_f32_16x16x32_bf16(Bt[n][k], At[m][k], acc[ai][bj][m][n], 0, 0, 0); __builtin_amdgcn_s_setprio(0); } while (0)
; #define PG8_WAIT_V(n) asm volatile("s_waitcnt vmcnt(" #n ")" ::: "memory")
; #define PG8_WAIT_L(n) asm volatile("s_waitcnt lgkmcnt(" #n ")" ::: "memory")
; #define PG8_BAR __builtin_amdgcn_s_barrier()
; #define PG8_SCHED __builtin_amdgcn_sched_barrier(0)
; template <class Epi, class Sched>
; DI void gemm_phase(LAS unsigned char* lds, const Gemm g, const Sched& S, const Epi& E) {
;     ...
;             PG8_BAR; PG8_WAIT_L(0); PG8_MMA(1, 0, At, B0); PG8_BAR; PG8_SCHED;
;             PG8_STAGE(PG8_SB(0, 1), b2 + hstep, voffB);
;             PG8_WAIT_V(6); PG8_BAR; PG8_MMA(1, 1, At, B1); PG8_BAR;
;             PG8_LDB(B0, 1, 0); PG8_SCHED; PG8_LDA(At, 1, 0); PG8_STAGE(PG8_SA(0, 1), a2 + hstep, voffA);
;             PG8_WAIT_L(8); PG8_BAR; PG8_WAIT_L(0); PG8_MMA(0, 0, At, B0); PG8_BAR; PG8_SCHED;
;             PG8_LDB(B1, 1, 1); PG8_STAGE(PG8_SB(1, 0), b3, voffB);
;             PG8_BAR; PG8_WAIT_L(0); PG8_MMA(0, 1, At, B1); PG8_BAR;
;             PG8_LDA(At, 1, 1); PG8_STAGE(PG8_SA(1, 0), a3, voffA);
;             PG8_BAR; PG8_WAIT_L(0); PG8_MMA(1, 0, At, B0); PG8_BAR; PG8_SCHED;
;             PG8_STAGE(PG8_SB(1, 1), b3 + hstep, voffB);
;             PG8_WAIT_V(6); PG8_BAR; PG8_MMA(1, 1, At, B1); PG8_BAR;
	s_setprio 1
	v_mfma_f32_16x16x32_bf16 v[44:47], v[218:221], v[166:169], 0
	v_mfma_f32_16x16x32_bf16 v[36:39], v[226:229], v[166:169], 0
	v_mfma_f32_16x16x32_bf16 v[28:31], v[218:221], v[174:177], 0
	v_mfma_f32_16x16x32_bf16 v[20:23], v[226:229], v[174:177], 0
	v_mfma_f32_16x16x32_bf16 v[12:15], v[218:221], v[188:191], 0
	v_mfma_f32_16x16x32_bf16 v[8:11], v[226:229], v[188:191], 0
	v_mfma_f32_16x16x32_bf16 v[4:7], v[218:221], v[210:213], 0
	v_mfma_f32_16x16x32_bf16 v[0:3], v[226:229], v[210:213], 0
	v_mfma_f32_16x16x32_bf16 v[44:47], v[222:225], v[170:173], v[44:47]
	v_mfma_f32_16x16x32_bf16 v[36:39], v[230:233], v[170:173], v[36:39]
	v_mfma_f32_16x16x32_bf16 v[28:31], v[222:225], v[178:181], v[28:31]
	v_mfma_f32_16x16x32_bf16 v[20:23], v[230:233], v[178:181], v[20:23]
	v_mfma_f32_16x16x32_bf16 v[12:15], v[222:225], v[206:209], v[12:15]
	v_mfma_f32_16x16x32_bf16 v[8:11], v[230:233], v[206:209], v[8:11]
	v_mfma_f32_16x16x32_bf16 v[4:7], v[222:225], v[214:217], v[4:7]
	v_mfma_f32_16x16x32_bf16 v[0:3], v[230:233], v[214:217], v[0:3]
	s_setprio 0
	s_barrier
	ds_read_b128 v[146:149], v144
	ds_read_b128 v[154:157], v144 offset:1024
	ds_read_b128 v[158:161], v144 offset:2048
	ds_read_b128 v[162:165], v144 offset:3072
	s_add_u32 s0, s36, 0x160000
	s_addc_u32 s1, s37, 0
	s_mov_b32 m0, s42
	ds_read_b128 v[166:169], v142 offset:32768
	ds_read_b128 v[170:173], v142 offset:33792
	ds_read_b128 v[174:177], v142 offset:34816
	ds_read_b128 v[178:181], v142 offset:35840
	ds_read_b128 v[188:191], v142 offset:36864
	ds_read_b128 v[206:209], v142 offset:37888
	ds_read_b128 v[210:213], v142 offset:38912
	ds_read_b128 v[214:217], v142 offset:39936
	global_load_lds_dwordx4 v130, s[0:1]
	s_mov_b32 m0, s43
	s_nop 0
	global_load_lds_dwordx4 v128, s[0:1]
	s_waitcnt lgkmcnt(8)
	s_barrier
	s_waitcnt lgkmcnt(0)
	s_setprio 1
	s_waitcnt lgkmcnt(0)
	v_mfma_f32_16x16x32_bf16 v[124:127], v[146:149], v[166:169], v[124:127]
	v_mfma_f32_16x16x32_bf16 v[120:123], v[158:161], v[166:169], v[120:123]
	v_mfma_f32_16x16x32_bf16 v[116:119], v[146:149], v[174:177], v[116:119]
	v_mfma_f32_16x16x32_bf16 v[112:115], v[158:161], v[174:177], v[112:115]
	v_mfma_f32_16x16x32_bf16 v[104:107], v[146:149], v[188:191], v[104:107]
	v_mfma_f32_16x16x32_bf16 v[96:99], v[158:161], v[188:191], v[96:99]
	v_mfma_f32_16x16x32_bf16 v[88:91], v[146:149], v[210:213], v[88:91]
	v_mfma_f32_16x16x32_bf16 v[80:83], v[158:161], v[210:213], v[80:83]
	v_mfma_f32_16x16x32_bf16 v[124:127], v[154:157], v[170:173], v[124:127]
	v_mfma_f32_16x16x32_bf16 v[120:123], v[162:165], v[170:173], v[120:123]
	v_mfma_f32_16x16x32_bf16 v[116:119], v[154:157], v[178:181], v[116:119]
	v_mfma_f32_16x16x32_bf16 v[112:115], v[162:165], v[178:181], v[112:115]
	v_mfma_f32_16x16x32_bf16 v[104:107], v[154:157], v[206:209], v[104:107]
	v_mfma_f32_16x16x32_bf16 v[96:99], v[162:165], v[206:209], v[96:99]
	v_mfma_f32_16x16x32_bf16 v[88:91], v[154:157], v[214:217], v[88:91]
	v_mfma_f32_16x16x32_bf16 v[80:83], v[162:165], v[214:217], v[80:83]
	s_setprio 0
	s_barrier
	s_add_i32 s4, 0, 0x1c000
	s_add_i32 s0, s62, s35
	v_add_u32_e32 v145, s4, v140
	s_add_i32 m0, s0, 0xffffff80
	ds_read_b128 v[218:221], v145
	ds_read_b128 v[222:225], v145 offset:1024
	ds_read_b128 v[226:229], v145 offset:2048
	ds_read_b128 v[230:233], v145 offset:3072
	global_load_lds_dwordx4 v130, s[30:31] offset:128
	s_add_i32 m0, s0, 0x1f80
	s_nop 0
	global_load_lds_dwordx4 v128, s[30:31] offset:128
	s_barrier
	s_waitcnt lgkmcnt(0)
	s_setprio 1
	s_waitcnt lgkmcnt(0)
	v_mfma_f32_16x16x32_bf16 v[108:111], v[218:221], v[166:169], v[108:111]
	v_mfma_f32_16x16x32_bf16 v[100:103], v[226:229], v[166:169], v[100:103]
	v_mfma_f32_16x16x32_bf16 v[92:95], v[218:221], v[174:177], v[92:95]
	v_mfma_f32_16x16x32_bf16 v[84:87], v[226:229], v[174:177], v[84:87]
	v_mfma_f32_16x16x32_bf16 v[76:79], v[218:221], v[188:191], v[76:79]
	v_mfma_f32_16x16x32_bf16 v[72:75], v[226:229], v[188:191], v[72:75]
	v_mfma_f32_16x16x32_bf16 v[68:71], v[218:221], v[210:213], v[68:71]
	v_mfma_f32_16x16x32_bf16 v[64:67], v[226:229], v[210:213], v[64:67]
	v_mfma_f32_16x16x32_bf16 v[108:111], v[222:225], v[170:173], v[108:111]
	v_mfma_f32_16x16x32_bf16 v[100:103], v[230:233], v[170:173], v[100:103]
	v_mfma_f32_16x16x32_bf16 v[92:95], v[222:225], v[178:181], v[92:95]
	v_mfma_f32_16x16x32_bf16 v[84:87], v[230:233], v[178:181], v[84:87]
	v_mfma_f32_16x16x32_bf16 v[76:79], v[222:225], v[206:209], v[76:79]
	v_mfma_f32_16x16x32_bf16 v[72:75], v[230:233], v[206:209], v[72:75]
	v_mfma_f32_16x16x32_bf16 v[68:71], v[222:225], v[214:217], v[68:71]
	v_mfma_f32_16x16x32_bf16 v[64:67], v[230:233], v[214:217], v[64:67]
	s_setprio 0
	s_add_i32 m0, s54, 0xffffff80
	s_barrier
	ds_read_b128 v[166:169], v142 offset:49152
	ds_read_b128 v[170:173], v142 offset:50176
	ds_read_b128 v[174:177], v142 offset:51200
	ds_read_b128 v[178:181], v142 offset:52224
	ds_read_b128 v[188:191], v142 offset:53248
	ds_read_b128 v[206:209], v142 offset:54272
	ds_read_b128 v[210:213], v142 offset:55296
	ds_read_b128 v[214:217], v142 offset:56320
	global_load_lds_dwordx4 v130, s[36:37] offset:128
	s_add_i32 m0, s55, 0xffffff80
	s_nop 0
	global_load_lds_dwordx4 v128, s[36:37] offset:128
	s_barrier
; #define PG8_STAGE(bufoff, gbase, voff) do { _Pragma("unroll") for (int _i = 0; _i < 2; ++_i) \
;         __builtin_amdgcn_global_load_lds((const unsigned*)((const char*)(gbase) + (voff)[_i]), (LAS unsigned*)(lds + (bufoff) + ldsw + _i * 8192), 16, 0, 0); } while (0)
; #define PG8_LDA(dst, b, h) do { _Pragma("unroll") for (int m = 0; m < 4; ++m) _Pragma("unroll") for (int k = 0; k < 2; ++k) dst[m][k] = *(const LAS bf16x8*)(lds + PG8_SA(b, h) + aoff + m * 2048 + k * 1024); } while (0)
; #define PG8_LDB(dst, b, h) do { _Pragma("unroll") for (int n = 0; n < 2; ++n) _Pragma("unroll") for (int k = 0; k < 2; ++k) dst[n][k] = *(const LAS bf16x8*)(lds + PG8_SB(b, h) + boff + n * 2048 + k * 1024); } while (0)
; #define PG8_MMA(ai, bj, At, Bt) do { __builtin_amdgcn_s_setprio(1); _Pragma("unroll") for (int m = 0; m < 4; ++m) _Pragma("unroll") for (int n = 0; n < 2; ++n) _Pragma("unroll") for (int k = 0; k < 2; ++k) \
;         acc[ai][bj][m][n] = __builtin_amdgcn_mfma_f32_16x16x32_bf16(Bt[n][k], At[m][k], acc[ai][bj][m][n], 0, 0, 0); __builtin_amdgcn_s_setprio(0); } while (0)
; #define PG8_WAIT_V(n) asm volatile("s_waitcnt vmcnt(" #n ")" ::: "memory")
; #define PG8_WAIT_L(n) asm volatile("s_waitcnt lgkmcnt(" #n ")" ::: "memory")
; #define PG8_BAR __builtin_amdgcn_s_barrier()
; #define PG8_SCHED __builtin_amdgcn_sched_barrier(0)
; template <class Epi, class Sched>
; DI void gemm_phase(LAS unsigned char* lds, const Gemm g, const Sched& S, const Epi& E) {
;     ...
;             PG8_LDB(B0, 0, 0); PG8_SCHED; PG8_LDA(At, 0, 0); PG8_STAGE(PG8_SA(1, 1), a1 + hstep, voffA);
;             PG8_WAIT_L(8); PG8_BAR; PG8_WAIT_L(0); PG8_MMA(0, 0, At, B0); PG8_BAR; PG8_SCHED;
;             PG8_LDB(B1, 0, 1); PG8_STAGE(PG8_SB(0, 0), b2, voffB);
;             PG8_BAR; PG8_WAIT_L(0); PG8_MMA(0, 1, At, B1); PG8_BAR;
;             PG8_LDA(At, 0, 1); PG8_STAGE(PG8_SA(0, 0), a2, voffA);
;             PG8_BAR; PG8_WAIT_L(0); PG8_MMA(1, 0, At, B0); PG8_BAR; PG8_SCHED;
;     ...
;             PG8_BAR; PG8_WAIT_L(0); PG8_MMA(1, 0, At, B0); PG8_BAR; PG8_SCHED;
;             PG8_STAGE(PG8_SB(1, 1), b3 + hstep, voffB);
;             PG8_WAIT_V(6); PG8_BAR; PG8_MMA(1, 1, At, B1); PG8_BAR;
	s_waitcnt lgkmcnt(0)
	s_setprio 1
	s_waitcnt lgkmcnt(0)
	v_mfma_f32_16x16x32_bf16 v[60:63], v[146:149], v[166:169], v[60:63]
	v_mfma_f32_16x16x32_bf16 v[56:59], v[158:161], v[166:169], v[56:59]
	v_mfma_f32_16x16x32_bf16 v[52:55], v[146:149], v[174:177], v[52:55]
	v_mfma_f32_16x16x32_bf16 v[48:51], v[158:161], v[174:177], v[48:51]
	v_mfma_f32_16x16x32_bf16 v[40:43], v[146:149], v[188:191], v[40:43]
	v_mfma_f32_16x16x32_bf16 v[32:35], v[158:161], v[188:191], v[32:35]
	v_mfma_f32_16x16x32_bf16 v[24:27], v[146:149], v[210:213], v[24:27]
	v_mfma_f32_16x16x32_bf16 v[16:19], v[158:161], v[210:213], v[16:19]
	v_mfma_f32_16x16x32_bf16 v[60:63], v[154:157], v[170:173], v[60:63]
	v_mfma_f32_16x16x32_bf16 v[56:59], v[162:165], v[170:173], v[56:59]
	v_mfma_f32_16x16x32_bf16 v[52:55], v[154:157], v[178:181], v[52:55]
	v_mfma_f32_16x16x32_bf16 v[48:51], v[162:165], v[178:181], v[48:51]
	v_mfma_f32_16x16x32_bf16 v[40:43], v[154:157], v[206:209], v[40:43]
	v_mfma_f32_16x16x32_bf16 v[32:35], v[162:165], v[206:209], v[32:35]
	v_mfma_f32_16x16x32_bf16 v[24:27], v[154:157], v[214:217], v[24:27]
	v_mfma_f32_16x16x32_bf16 v[16:19], v[162:165], v[214:217], v[16:19]
	s_setprio 0
	s_barrier
	s_add_u32 s0, s30, 0x160080
	s_addc_u32 s1, s31, 0
	s_add_i32 s4, s4, s35
	s_mov_b32 m0, s4
	s_nop 0
	global_load_lds_dwordx4 v130, s[0:1]
	s_add_i32 m0, s4, 0x2000
	s_nop 0
	global_load_lds_dwordx4 v128, s[0:1]
	s_waitcnt vmcnt(6)
	s_barrier
	s_setprio 1
	v_mfma_f32_16x16x32_bf16 v[44:47], v[218:221], v[166:169], v[44:47]
	v_mfma_f32_16x16x32_bf16 v[36:39], v[226:229], v[166:169], v[36:39]
	v_mfma_f32_16x16x32_bf16 v[28:31], v[218:221], v[174:177], v[28:31]
	v_mfma_f32_16x16x32_bf16 v[20:23], v[226:229], v[174:177], v[20:23]
	v_mfma_f32_16x16x32_bf16 v[12:15], v[218:221], v[188:191], v[12:15]
	v_mfma_f32_16x16x32_bf16 v[8:11], v[226:229], v[188:191], v[8:11]
	v_mfma_f32_16x16x32_bf16 v[4:7], v[218:221], v[210:213], v[4:7]
	v_mfma_f32_16x16x32_bf16 v[0:3], v[226:229], v[210:213], v[0:3]
	v_mfma_f32_16x16x32_bf16 v[44:47], v[222:225], v[170:173], v[44:47]
	v_mfma_f32_16x16x32_bf16 v[36:39], v[230:233], v[170:173], v[36:39]
	v_mfma_f32_16x16x32_bf16 v[28:31], v[222:225], v[178:181], v[28:31]
	v_mfma_f32_16x16x32_bf16 v[20:23], v[230:233], v[178:181], v[20:23]
	v_mfma_f32_16x16x32_bf16 v[12:15], v[222:225], v[206:209], v[12:15]
	v_mfma_f32_16x16x32_bf16 v[8:11], v[230:233], v[206:209], v[8:11]
	v_mfma_f32_16x16x32_bf16 v[4:7], v[222:225], v[214:217], v[4:7]
	v_mfma_f32_16x16x32_bf16 v[0:3], v[230:233], v[214:217], v[0:3]
	s_setprio 0
	s_add_i32 s66, s66, 2
	s_add_u32 s8, s8, 0x100
	s_addc_u32 s9, s9, 0
	s_add_u32 s64, s64, 0x100
	s_addc_u32 s65, s65, 0
	s_cmp_gt_u32 s66, 5
	s_barrier
	s_cbranch_scc0 .LBB0_1775
	s_branch .Lpeel_done_1775
.LBB0_1775:
	ds_read_b128 v[146:149], v141
	ds_read_b128 v[154:157], v141 offset:1024
	ds_read_b128 v[158:161], v141 offset:2048
	ds_read_b128 v[162:165], v141 offset:3072
	s_add_u32 s0, s8, 0xffea0080
	s_addc_u32 s1, s9, -1
	s_cmp_eq_u32 s66, 4
	s_cselect_b32 s37, s15, s1
	s_cselect_b32 s36, s17, s0
	s_cselect_b32 s31, s19, s65
	s_cselect_b32 s30, s18, s64
	s_mov_b32 m0, s56
	ds_read_b128 v[166:169], v142
	ds_read_b128 v[170:173], v142 offset:1024
	ds_read_b128 v[174:177], v142 offset:2048
	ds_read_b128 v[178:181], v142 offset:3072
	ds_read_b128 v[188:191], v142 offset:4096
	ds_read_b128 v[206:209], v142 offset:5120
	ds_read_b128 v[210:213], v142 offset:6144
	ds_read_b128 v[214:217], v142 offset:7168
	global_load_lds_dwordx4 v132, s[8:9]
	s_mov_b32 m0, s57
	s_nop 0
	global_load_lds_dwordx4 v134, s[8:9]
	s_waitcnt lgkmcnt(8)
	s_barrier
	s_waitcnt lgkmcnt(0)
	s_setprio 1
	s_waitcnt lgkmcnt(0)
	v_mfma_f32_16x16x32_bf16 v[124:127], v[146:149], v[166:169], v[124:127]
	v_mfma_f32_16x16x32_bf16 v[120:123], v[158:161], v[166:169], v[120:123]
	v_mfma_f32_16x16x32_bf16 v[116:119], v[146:149], v[174:177], v[116:119]
	v_mfma_f32_16x16x32_bf16 v[112:115], v[158:161], v[174:177], v[112:115]
	v_mfma_f32_16x16x32_bf16 v[104:107], v[146:149], v[188:191], v[104:107]
	v_mfma_f32_16x16x32_bf16 v[96:99], v[158:161], v[188:191], v[96:99]
	v_mfma_f32_16x16x32_bf16 v[88:91], v[146:149], v[210:213], v[88:91]
	v_mfma_f32_16x16x32_bf16 v[80:83], v[158:161], v[210:213], v[80:83]
	v_mfma_f32_16x16x32_bf16 v[124:127], v[154:157], v[170:173], v[124:127]
	v_mfma_f32_16x16x32_bf16 v[120:123], v[162:165], v[170:173], v[120:123]
	v_mfma_f32_16x16x32_bf16 v[116:119], v[154:157], v[178:181], v[116:119]
	v_mfma_f32_16x16x32_bf16 v[112:115], v[162:165], v[178:181], v[112:115]
	v_mfma_f32_16x16x32_bf16 v[104:107], v[154:157], v[206:209], v[104:107]
	v_mfma_f32_16x16x32_bf16 v[96:99], v[162:165], v[206:209], v[96:99]
	v_mfma_f32_16x16x32_bf16 v[88:91], v[154:157], v[214:217], v[88:91]
	v_mfma_f32_16x16x32_bf16 v[80:83], v[162:165], v[214:217], v[80:83]
	s_setprio 0
	s_barrier
	s_mov_b32 m0, s58
	ds_read_b128 v[218:221], v143
	ds_read_b128 v[222:225], v143 offset:1024
	ds_read_b128 v[226:229], v143 offset:2048
	ds_read_b128 v[230:233], v143 offset:3072
	global_load_lds_dwordx4 v130, s[30:31]
	s_mov_b32 m0, s59
	s_nop 0
	global_load_lds_dwordx4 v128, s[30:31]
	s_barrier
; #define PG8_STAGE(bufoff, gbase, voff) do { _Pragma("unroll") for (int _i = 0; _i < 2; ++_i) \
;         __builtin_amdgcn_global_load_lds((const unsigned*)((const char*)(gbase) + (voff)[_i]), (LAS unsigned*)(lds + (bufoff) + ldsw + _i * 8192), 16, 0, 0); } while (0)
; #define PG8_LDA(dst, b, h) do { _Pragma("unroll") for (int m = 0; m < 4; ++m) _Pragma("unroll") for (int k = 0; k < 2; ++k) dst[m][k] = *(const LAS bf16x8*)(lds + PG8_SA(b, h) + aoff + m * 2048 + k * 1024); } while (0)
; #define PG8_LDB(dst, b, h) do { _Pragma("unroll") for (int n = 0; n < 2; ++n) _Pragma("unroll") for (int k = 0; k < 2; ++k) dst[n][k] = *(const LAS bf16x8*)(lds + PG8_SB(b, h) + boff + n * 2048 + k * 1024); } while (0)
; #define PG8_WAIT_V(n) asm volatile("s_waitcnt vmcnt(" #n ")" ::: "memory")
; #define PG8_WAIT_L(n) asm volatile("s_waitcnt lgkmcnt(" #n ")" ::: "memory")
; #define PG8_BAR __builtin_amdgcn_s_barrier()
; #define PG8_SCHED __builtin_amdgcn_sched_barrier(0)
; template <class Epi, class Sched>
; DI void gemm_phase(LAS unsigned char* lds, const Gemm g, const Sched& S, const Epi& E) {
;     ...
;             PG8_LDB(B0, 0, 0); PG8_SCHED; PG8_LDA(At, 0, 0); PG8_STAGE(PG8_SA(1, 1), a1 + hstep, voffA);
;             PG8_WAIT_L(8); PG8_BAR; PG8_WAIT_L(0); PG8_MMA(0, 0, At, B0); PG8_BAR; PG8_SCHED;
;             PG8_LDB(B1, 0, 1); PG8_STAGE(PG8_SB(0, 0), b2, voffB);
;             PG8_BAR; PG8_WAIT_L(0); PG8_MMA(0, 1, At, B1); PG8_BAR;
;             PG8_LDA(At, 0, 1); PG8_STAGE(PG8_SA(0, 0), a2, voffA);
;             PG8_BAR; PG8_WAIT_L(0); PG8_MMA(1, 0, At, B0); PG8_BAR; PG8_SCHED;
;             PG8_STAGE(PG8_SB(0, 1), b2 + hstep, voffB);
;             PG8_WAIT_V(6); PG8_BAR; PG8_MMA(1, 1, At, B1); PG8_BAR;
;             PG8_LDB(B0, 1, 0); PG8_SCHED; PG8_LDA(At, 1, 0); PG8_STAGE(PG8_SA(0, 1), a2 + hstep, voffA);
;             PG8_WAIT_L(8); PG8_BAR; PG8_WAIT_L(0); PG8_MMA(0, 0, At, B0); PG8_BAR; PG8_SCHED;
;             PG8_LDB(B1, 1, 1); PG8_STAGE(PG8_SB(1, 0), b3, voffB);
;             PG8_BAR; PG8_WAIT_L(0); PG8_MMA(0, 1, At, B1); PG8_BAR;
;             PG8_LDA(At, 1, 1); PG8_STAGE(PG8_SA(1, 0), a3, voffA);
;             PG8_BAR; PG8_WAIT_L(0); PG8_MMA(1, 0, At, B0); PG8_BAR; PG8_SCHED;
;             PG8_STAGE(PG8_SB(1, 1), b3 + hstep, voffB);
;             PG8_WAIT_V(6); PG8_BAR; PG8_MMA(1, 1, At, B1); PG8_BAR;
	s_waitcnt lgkmcnt(0)
	s_setprio 1
	s_waitcnt lgkmcnt(0)
	v_mfma_f32_16x16x32_bf16 v[108:111], v[218:221], v[166:169], v[108:111]
	v_mfma_f32_16x16x32_bf16 v[100:103], v[226:229], v[166:169], v[100:103]
	v_mfma_f32_16x16x32_bf16 v[92:95], v[218:221], v[174:177], v[92:95]
	v_mfma_f32_16x16x32_bf16 v[84:87], v[226:229], v[174:177], v[84:87]
	v_mfma_f32_16x16x32_bf16 v[76:79], v[218:221], v[188:191], v[76:79]
	v_mfma_f32_16x16x32_bf16 v[72:75], v[226:229], v[188:191], v[72:75]
	v_mfma_f32_16x16x32_bf16 v[68:71], v[218:221], v[210:213], v[68:71]
	v_mfma_f32_16x16x32_bf16 v[64:67], v[226:229], v[210:213], v[64:67]
	v_mfma_f32_16x16x32_bf16 v[108:111], v[222:225], v[170:173], v[108:111]
	v_mfma_f32_16x16x32_bf16 v[100:103], v[230:233], v[170:173], v[100:103]
	v_mfma_f32_16x16x32_bf16 v[92:95], v[222:225], v[178:181], v[92:95]
	v_mfma_f32_16x16x32_bf16 v[84:87], v[230:233], v[178:181], v[84:87]
	v_mfma_f32_16x16x32_bf16 v[76:79], v[222:225], v[206:209], v[76:79]
	v_mfma_f32_16x16x32_bf16 v[72:75], v[230:233], v[206:209], v[72:75]
	v_mfma_f32_16x16x32_bf16 v[68:71], v[222:225], v[214:217], v[68:71]
	v_mfma_f32_16x16x32_bf16 v[64:67], v[230:233], v[214:217], v[64:67]
	s_setprio 0
	s_mov_b32 m0, s40
	s_barrier
	ds_read_b128 v[166:169], v142 offset:16384
	ds_read_b128 v[170:173], v142 offset:17408
	ds_read_b128 v[174:177], v142 offset:18432
	ds_read_b128 v[178:181], v142 offset:19456
	ds_read_b128 v[188:191], v142 offset:20480
	ds_read_b128 v[206:209], v142 offset:21504
	ds_read_b128 v[210:213], v142 offset:22528
	ds_read_b128 v[214:217], v142 offset:23552
	global_load_lds_dwordx4 v130, s[36:37]
	s_mov_b32 m0, s41
	s_nop 0
	global_load_lds_dwordx4 v128, s[36:37]
	s_barrier
	s_waitcnt lgkmcnt(0)
	s_setprio 1
	s_waitcnt lgkmcnt(0)
	v_mfma_f32_16x16x32_bf16 v[60:63], v[146:149], v[166:169], v[60:63]
	v_mfma_f32_16x16x32_bf16 v[56:59], v[158:161], v[166:169], v[56:59]
	v_mfma_f32_16x16x32_bf16 v[52:55], v[146:149], v[174:177], v[52:55]
	v_mfma_f32_16x16x32_bf16 v[48:51], v[158:161], v[174:177], v[48:51]
	v_mfma_f32_16x16x32_bf16 v[40:43], v[146:149], v[188:191], v[40:43]
	v_mfma_f32_16x16x32_bf16 v[32:35], v[158:161], v[188:191], v[32:35]
	v_mfma_f32_16x16x32_bf16 v[24:27], v[146:149], v[210:213], v[24:27]
	v_mfma_f32_16x16x32_bf16 v[16:19], v[158:161], v[210:213], v[16:19]
	v_mfma_f32_16x16x32_bf16 v[60:63], v[154:157], v[170:173], v[60:63]
	v_mfma_f32_16x16x32_bf16 v[56:59], v[162:165], v[170:173], v[56:59]
	v_mfma_f32_16x16x32_bf16 v[52:55], v[154:157], v[178:181], v[52:55]
	v_mfma_f32_16x16x32_bf16 v[48:51], v[162:165], v[178:181], v[48:51]
	v_mfma_f32_16x16x32_bf16 v[40:43], v[154:157], v[206:209], v[40:43]
	v_mfma_f32_16x16x32_bf16 v[32:35], v[162:165], v[206:209], v[32:35]
	v_mfma_f32_16x16x32_bf16 v[24:27], v[154:157], v[214:217], v[24:27]
	v_mfma_f32_16x16x32_bf16 v[16:19], v[162:165], v[214:217], v[16:19]
	s_setprio 0
	s_barrier
	s_add_u32 s0, s30, 0x160000
	s_addc_u32 s1, s31, 0
	s_mov_b32 m0, s60
	s_nop 0
	global_load_lds_dwordx4 v130, s[0:1]
	s_mov_b32 m0, s61
	s_nop 0
	global_load_lds_dwordx4 v128, s[0:1]
	s_waitcnt vmcnt(6)
	s_barrier
	s_setprio 1
	v_mfma_f32_16x16x32_bf16 v[44:47], v[218:221], v[166:169], v[44:47]
	v_mfma_f32_16x16x32_bf16 v[36:39], v[226:229], v[166:169], v[36:39]
	v_mfma_f32_16x16x32_bf16 v[28:31], v[218:221], v[174:177], v[28:31]
	v_mfma_f32_16x16x32_bf16 v[20:23], v[226:229], v[174:177], v[20:23]
	v_mfma_f32_16x16x32_bf16 v[12:15], v[218:221], v[188:191], v[12:15]
	v_mfma_f32_16x16x32_bf16 v[8:11], v[226:229], v[188:191], v[8:11]
	v_mfma_f32_16x16x32_bf16 v[4:7], v[218:221], v[210:213], v[4:7]
	v_mfma_f32_16x16x32_bf16 v[0:3], v[226:229], v[210:213], v[0:3]
	v_mfma_f32_16x16x32_bf16 v[44:47], v[222:225], v[170:173], v[44:47]
	v_mfma_f32_16x16x32_bf16 v[36:39], v[230:233], v[170:173], v[36:39]
	v_mfma_f32_16x16x32_bf16 v[28:31], v[222:225], v[178:181], v[28:31]
	v_mfma_f32_16x16x32_bf16 v[20:23], v[230:233], v[178:181], v[20:23]
	v_mfma_f32_16x16x32_bf16 v[12:15], v[222:225], v[206:209], v[12:15]
	v_mfma_f32_16x16x32_bf16 v[8:11], v[230:233], v[206:209], v[8:11]
	v_mfma_f32_16x16x32_bf16 v[4:7], v[222:225], v[214:217], v[4:7]
	v_mfma_f32_16x16x32_bf16 v[0:3], v[230:233], v[214:217], v[0:3]
	s_setprio 0
	s_barrier
	ds_read_b128 v[146:149], v144
	ds_read_b128 v[154:157], v144 offset:1024
	ds_read_b128 v[158:161], v144 offset:2048
	ds_read_b128 v[162:165], v144 offset:3072
	s_add_u32 s0, s36, 0x160000
	s_addc_u32 s1, s37, 0
	s_mov_b32 m0, s42
	ds_read_b128 v[166:169], v142 offset:32768
	ds_read_b128 v[170:173], v142 offset:33792
	ds_read_b128 v[174:177], v142 offset:34816
	ds_read_b128 v[178:181], v142 offset:35840
	ds_read_b128 v[188:191], v142 offset:36864
	ds_read_b128 v[206:209], v142 offset:37888
	ds_read_b128 v[210:213], v142 offset:38912
	ds_read_b128 v[214:217], v142 offset:39936
	global_load_lds_dwordx4 v130, s[0:1]
	s_mov_b32 m0, s43
	s_nop 0
	global_load_lds_dwordx4 v128, s[0:1]
	s_waitcnt lgkmcnt(8)
	s_barrier
; #define PG8_STAGE(bufoff, gbase, voff) do { _Pragma("unroll") for (int _i = 0; _i < 2; ++_i) \
;         __builtin_amdgcn_global_load_lds((const unsigned*)((const char*)(gbase) + (voff)[_i]), (LAS unsigned*)(lds + (bufoff) + ldsw + _i * 8192), 16, 0, 0); } while (0)
; #define PG8_LDA(dst, b, h) do { _Pragma("unroll") for (int m = 0; m < 4; ++m) _Pragma("unroll") for (int k = 0; k < 2; ++k) dst[m][k] = *(const LAS bf16x8*)(lds + PG8_SA(b, h) + aoff + m * 2048 + k * 1024); } while (0)
; #define PG8_LDB(dst, b, h) do { _Pragma("unroll") for (int n = 0; n < 2; ++n) _Pragma("unroll") for (int k = 0; k < 2; ++k) dst[n][k] = *(const LAS bf16x8*)(lds + PG8_SB(b, h) + boff + n * 2048 + k * 1024); } while (0)
; #define PG8_MMA(ai, bj, At, Bt) do { __builtin_amdgcn_s_setprio(1); _Pragma("unroll") for (int m = 0; m < 4; ++m) _Pragma("unroll") for (int n = 0; n < 2; ++n) _Pragma("unroll") for (int k = 0; k < 2; ++k) \
;         acc[ai][bj][m][n] = __builtin_amdgcn_mfma_f32_16x16x32_bf16(Bt[n][k], At[m][k], acc[ai][bj][m][n], 0, 0, 0); __builtin_amdgcn_s_setprio(0); } while (0)
; #define PG8_WAIT_V(n) asm volatile("s_waitcnt vmcnt(" #n ")" ::: "memory")
; #define PG8_WAIT_L(n) asm volatile("s_waitcnt lgkmcnt(" #n ")" ::: "memory")
; #define PG8_BAR __builtin_amdgcn_s_barrier()
; #define PG8_SCHED __builtin_amdgcn_sched_barrier(0)
; template <class Epi, class Sched>
; DI void gemm_phase(LAS unsigned char* lds, const Gemm g, const Sched& S, const Epi& E) {
;     ...
;             PG8_LDB(B0, 1, 0); PG8_SCHED; PG8_LDA(At, 1, 0); PG8_STAGE(PG8_SA(0, 1), a2 + hstep, voffA);
;             PG8_WAIT_L(8); PG8_BAR; PG8_WAIT_L(0); PG8_MMA(0, 0, At, B0); PG8_BAR; PG8_SCHED;
;             PG8_LDB(B1, 1, 1); PG8_STAGE(PG8_SB(1, 0), b3, voffB);
;             PG8_BAR; PG8_WAIT_L(0); PG8_MMA(0, 1, At, B1); PG8_BAR;
;             PG8_LDA(At, 1, 1); PG8_STAGE(PG8_SA(1, 0), a3, voffA);
;             PG8_BAR; PG8_WAIT_L(0); PG8_MMA(1, 0, At, B0); PG8_BAR; PG8_SCHED;
;             PG8_STAGE(PG8_SB(1, 1), b3 + hstep, voffB);
;             PG8_WAIT_V(6); PG8_BAR; PG8_MMA(1, 1, At, B1); PG8_BAR;
	s_waitcnt lgkmcnt(0)
	s_setprio 1
	s_waitcnt lgkmcnt(0)
	v_mfma_f32_16x16x32_bf16 v[124:127], v[146:149], v[166:169], v[124:127]
	v_mfma_f32_16x16x32_bf16 v[120:123], v[158:161], v[166:169], v[120:123]
	v_mfma_f32_16x16x32_bf16 v[116:119], v[146:149], v[174:177], v[116:119]
	v_mfma_f32_16x16x32_bf16 v[112:115], v[158:161], v[174:177], v[112:115]
	v_mfma_f32_16x16x32_bf16 v[104:107], v[146:149], v[188:191], v[104:107]
	v_mfma_f32_16x16x32_bf16 v[96:99], v[158:161], v[188:191], v[96:99]
	v_mfma_f32_16x16x32_bf16 v[88:91], v[146:149], v[210:213], v[88:91]
	v_mfma_f32_16x16x32_bf16 v[80:83], v[158:161], v[210:213], v[80:83]
	v_mfma_f32_16x16x32_bf16 v[124:127], v[154:157], v[170:173], v[124:127]
	v_mfma_f32_16x16x32_bf16 v[120:123], v[162:165], v[170:173], v[120:123]
	v_mfma_f32_16x16x32_bf16 v[116:119], v[154:157], v[178:181], v[116:119]
	v_mfma_f32_16x16x32_bf16 v[112:115], v[162:165], v[178:181], v[112:115]
	v_mfma_f32_16x16x32_bf16 v[104:107], v[154:157], v[206:209], v[104:107]
	v_mfma_f32_16x16x32_bf16 v[96:99], v[162:165], v[206:209], v[96:99]
	v_mfma_f32_16x16x32_bf16 v[88:91], v[154:157], v[214:217], v[88:91]
	v_mfma_f32_16x16x32_bf16 v[80:83], v[162:165], v[214:217], v[80:83]
	s_setprio 0
	s_barrier
	s_add_i32 s4, 0, 0x1c000
	s_add_i32 s0, s62, s35
	v_add_u32_e32 v145, s4, v140
	s_add_i32 m0, s0, 0xffffff80
	ds_read_b128 v[218:221], v145
	ds_read_b128 v[222:225], v145 offset:1024
	ds_read_b128 v[226:229], v145 offset:2048
	ds_read_b128 v[230:233], v145 offset:3072
	global_load_lds_dwordx4 v130, s[30:31] offset:128
	s_add_i32 m0, s0, 0x1f80
	s_nop 0
	global_load_lds_dwordx4 v128, s[30:31] offset:128
	s_barrier
	s_waitcnt lgkmcnt(0)
	s_setprio 1
	s_waitcnt lgkmcnt(0)
	v_mfma_f32_16x16x32_bf16 v[108:111], v[218:221], v[166:169], v[108:111]
	v_mfma_f32_16x16x32_bf16 v[100:103], v[226:229], v[166:169], v[100:103]
	v_mfma_f32_16x16x32_bf16 v[92:95], v[218:221], v[174:177], v[92:95]
	v_mfma_f32_16x16x32_bf16 v[84:87], v[226:229], v[174:177], v[84:87]
	v_mfma_f32_16x16x32_bf16 v[76:79], v[218:221], v[188:191], v[76:79]
	v_mfma_f32_16x16x32_bf16 v[72:75], v[226:229], v[188:191], v[72:75]
	v_mfma_f32_16x16x32_bf16 v[68:71], v[218:221], v[210:213], v[68:71]
	v_mfma_f32_16x16x32_bf16 v[64:67], v[226:229], v[210:213], v[64:67]
	v_mfma_f32_16x16x32_bf16 v[108:111], v[222:225], v[170:173], v[108:111]
	v_mfma_f32_16x16x32_bf16 v[100:103], v[230:233], v[170:173], v[100:103]
	v_mfma_f32_16x16x32_bf16 v[92:95], v[222:225], v[178:181], v[92:95]
	v_mfma_f32_16x16x32_bf16 v[84:87], v[230:233], v[178:181], v[84:87]
	v_mfma_f32_16x16x32_bf16 v[76:79], v[222:225], v[206:209], v[76:79]
	v_mfma_f32_16x16x32_bf16 v[72:75], v[230:233], v[206:209], v[72:75]
	v_mfma_f32_16x16x32_bf16 v[68:71], v[222:225], v[214:217], v[68:71]
	v_mfma_f32_16x16x32_bf16 v[64:67], v[230:233], v[214:217], v[64:67]
	s_setprio 0
	s_add_i32 m0, s54, 0xffffff80
	s_barrier
	ds_read_b128 v[166:169], v142 offset:49152
	ds_read_b128 v[170:173], v142 offset:50176
	ds_read_b128 v[174:177], v142 offset:51200
	ds_read_b128 v[178:181], v142 offset:52224
	ds_read_b128 v[188:191], v142 offset:53248
	ds_read_b128 v[206:209], v142 offset:54272
	ds_read_b128 v[210:213], v142 offset:55296
	ds_read_b128 v[214:217], v142 offset:56320
	global_load_lds_dwordx4 v130, s[36:37] offset:128
	s_add_i32 m0, s55, 0xffffff80
	s_nop 0
	global_load_lds_dwordx4 v128, s[36:37] offset:128
	s_barrier
	s_waitcnt lgkmcnt(0)
	s_setprio 1
	s_waitcnt lgkmcnt(0)
	v_mfma_f32_16x16x32_bf16 v[60:63], v[146:149], v[166:169], v[60:63]
	v_mfma_f32_16x16x32_bf16 v[56:59], v[158:161], v[166:169], v[56:59]
	v_mfma_f32_16x16x32_bf16 v[52:55], v[146:149], v[174:177], v[52:55]
	v_mfma_f32_16x16x32_bf16 v[48:51], v[158:161], v[174:177], v[48:51]
	v_mfma_f32_16x16x32_bf16 v[40:43], v[146:149], v[188:191], v[40:43]
	v_mfma_f32_16x16x32_bf16 v[32:35], v[158:161], v[188:191], v[32:35]
	v_mfma_f32_16x16x32_bf16 v[24:27], v[146:149], v[210:213], v[24:27]
	v_mfma_f32_16x16x32_bf16 v[16:19], v[158:161], v[210:213], v[16:19]
	v_mfma_f32_16x16x32_bf16 v[60:63], v[154:157], v[170:173], v[60:63]
	v_mfma_f32_16x16x32_bf16 v[56:59], v[162:165], v[170:173], v[56:59]
	v_mfma_f32_16x16x32_bf16 v[52:55], v[154:157], v[178:181], v[52:55]
	v_mfma_f32_16x16x32_bf16 v[48:51], v[162:165], v[178:181], v[48:51]
	v_mfma_f32_16x16x32_bf16 v[40:43], v[154:157], v[206:209], v[40:43]
	v_mfma_f32_16x16x32_bf16 v[32:35], v[162:165], v[206:209], v[32:35]
	v_mfma_f32_16x16x32_bf16 v[24:27], v[154:157], v[214:217], v[24:27]
	v_mfma_f32_16x16x32_bf16 v[16:19], v[162:165], v[214:217], v[16:19]
	s_setprio 0
	s_barrier
	s_add_u32 s0, s30, 0x160080
	s_addc_u32 s1, s31, 0
	s_add_i32 s4, s4, s35
	s_mov_b32 m0, s4
	s_nop 0
	global_load_lds_dwordx4 v130, s[0:1]
	s_add_i32 m0, s4, 0x2000
	s_nop 0
	global_load_lds_dwordx4 v128, s[0:1]
	s_waitcnt vmcnt(6)
	s_barrier
	s_setprio 1
	v_mfma_f32_16x16x32_bf16 v[44:47], v[218:221], v[166:169], v[44:47]
	v_mfma_f32_16x16x32_bf16 v[36:39], v[226:229], v[166:169], v[36:39]
	v_mfma_f32_16x16x32_bf16 v[28:31], v[218:221], v[174:177], v[28:31]
	v_mfma_f32_16x16x32_bf16 v[20:23], v[226:229], v[174:177], v[20:23]
	v_mfma_f32_16x16x32_bf16 v[12:15], v[218:221], v[188:191], v[12:15]
	v_mfma_f32_16x16x32_bf16 v[8:11], v[226:229], v[188:191], v[8:11]
	v_mfma_f32_16x16x32_bf16 v[4:7], v[218:221], v[210:213], v[4:7]
	v_mfma_f32_16x16x32_bf16 v[0:3], v[226:229], v[210:213], v[0:3]
	v_mfma_f32_16x16x32_bf16 v[44:47], v[222:225], v[170:173], v[44:47]
	v_mfma_f32_16x16x32_bf16 v[36:39], v[230:233], v[170:173], v[36:39]
	v_mfma_f32_16x16x32_bf16 v[28:31], v[222:225], v[178:181], v[28:31]
	v_mfma_f32_16x16x32_bf16 v[20:23], v[230:233], v[178:181], v[20:23]
	v_mfma_f32_16x16x32_bf16 v[12:15], v[222:225], v[206:209], v[12:15]
	v_mfma_f32_16x16x32_bf16 v[8:11], v[230:233], v[206:209], v[8:11]
	v_mfma_f32_16x16x32_bf16 v[4:7], v[222:225], v[214:217], v[4:7]
	v_mfma_f32_16x16x32_bf16 v[0:3], v[230:233], v[214:217], v[0:3]
	s_setprio 0
	s_add_i32 s66, s66, 2
	s_add_u32 s8, s8, 0x100
	s_addc_u32 s9, s9, 0
	s_add_u32 s64, s64, 0x100
	s_addc_u32 s65, s65, 0
	s_cmp_gt_u32 s66, 5
	s_barrier
	s_cbranch_scc0 .LBB0_1775

; DI float rs_of(const float* ss, int row) { return 1.0f / sqrtf(ss[row] * (1.0f / DM) + EPS); }
; #define PG8_STAGE(bufoff, gbase, voff) do { _Pragma("unroll") for (int _i = 0; _i < 2; ++_i) \
;         __builtin_amdgcn_global_load_lds((const unsigned*)((const char*)(gbase) + (voff)[_i]), (LAS unsigned*)(lds + (bufoff) + ldsw + _i * 8192), 16, 0, 0); } while (0)
; #define PG8_WAIT_V(n) asm volatile("s_waitcnt vmcnt(" #n ")" ::: "memory")
; #define PG8_BAR __builtin_amdgcn_s_barrier()
; template <class Epi, class Sched>
; DI void gemm_phase(LAS unsigned char* lds, const Gemm g, const Sched& S, const Epi& E) {
;     ...
;     PG8_STAGE(PG8_SB(1, 0), cB + kstep, voffB); PG8_STAGE(PG8_SA(1, 0), cA + kstep, voffA); PG8_STAGE(PG8_SB(1, 1), cB + hstep + kstep, voffB);
;     PG8_WAIT_V(6); PG8_BAR;
;     DI void operator()(AccRef acc, const Unit& u, int wr, int wc, int fr, int fq) const {
;         const int col0 = u.pn * 256 + wc * 32 + 8 * fq;
; #pragma unroll
;         for (int ai = 0; ai < 2; ++ai)
; #pragma unroll
;             for (int m = 0; m < 4; ++m) { const int row = u.pm * 256 + ai * 128 + wr * 64 + m * 16 + fr; const size_t off = (size_t)row * DM + col0; const float r = rs_of(ss, row);
; #pragma unroll
;                 for (int bj = 0; bj < 2; ++bj) {
;                     const u32x4 ev = *(const u32x4*)(Eb + off + bj * 128), uv = *(const u32x4*)(UPh + (size_t)row * 2304 + col0 + bj * 128);
.LBB0_1907:
	s_add_u32 s14, s22, 0x107c3000
	s_addc_u32 s15, s23, 0
	s_add_u32 s16, s22, 0x2bb03200
	s_addc_u32 s17, s23, 0
	s_add_u32 s18, s22, 0x188c3000
	s_addc_u32 s19, s23, 0
	s_add_u32 s28, s22, 0x162c00
	s_mov_b64 s[30:31], 0x80
	s_addc_u32 s29, s23, 0
	s_lshl_b32 s4, s4, 5
	s_add_i32 m0, s53, 0x18000
	v_lshl_add_u64 v[6:7], v[6:7], 0, s[30:31]
	s_lshl_b32 s57, s5, 6
	s_lshl_b32 s6, s5, 13
	s_and_b32 s58, s4, 0x60
	s_waitcnt vmcnt(4)
	s_barrier
	global_load_lds_dwordx4 v[6:7], off
	v_lshl_add_u64 v[4:5], v[4:5], 0, s[30:31]
	s_add_i32 m0, s53, 0x1a000
	s_add_i32 s59, s53, 0x8000
	s_add_i32 s60, s53, 0xa000
	global_load_lds_dwordx4 v[4:5], off
	v_lshl_add_u64 v[2:3], v[2:3], 0, s[30:31]
	s_mov_b32 m0, s59
	s_add_u32 s4, s40, 0x90080
	global_load_lds_dwordx4 v[2:3], off
	v_lshl_add_u64 v[0:1], v[0:1], 0, s[30:31]
	s_mov_b32 m0, s60
	s_addc_u32 s5, s41, 0
	global_load_lds_dwordx4 v[0:1], off
	s_add_i32 m0, s53, 0x1c000
	s_nop 0
	global_load_lds_dwordx4 v130, s[4:5]
	v_lshl_add_u64 v[0:1], s[4:5], 0, v[134:135]
	s_add_i32 m0, s53, 0x1e000
	s_mov_b64 s[4:5], 0x90080
	global_load_lds_dwordx4 v[0:1], off
	v_lshlrev_b32_e32 v1, 2, v194
	v_lshl_or_b32 v0, v194, 6, v195
	v_and_b32_e32 v1, 32, v1
	v_bitop3_b32 v2, v0, s6, v1 bitop3:0xde
	v_add_u16_e32 v0, v8, v196
	v_lshrrev_b16_e32 v3, 1, v0
	s_waitcnt vmcnt(6)
	v_add_lshl_u32 v0, v9, v3, 1
	v_mov_b32_e32 v1, v131
	v_lshl_add_u64 v[136:137], v[0:1], 0, s[4:5]
	v_add_lshl_u32 v0, v10, v3, 1
	s_sext_i32_i8 s1, s1
	v_lshl_or_b32 v157, s58, 7, v153
	s_mov_b32 s61, 0
	v_lshl_add_u64 v[138:139], v[0:1], 0, s[4:5]
	v_mov_b64_e32 v[140:141], 0x400
	v_mov_b64_e32 v[142:143], 0x3ff
	s_add_i32 s62, 0, 0x10000
	v_add_u32_e32 v158, 0, v2
	s_add_i32 s63, 0, 0x14000
	v_mov_b32_e32 v159, 0x358637bd
	s_mov_b32 s64, 0xf800000
	v_mov_b32_e32 v160, 0x260
	s_movk_i32 s65, 0x1200
	s_barrier
	s_branch .LBB0_1909
.LBB0_1908:
	v_mov_b32_e32 v144, v194
	v_mov_b32_e32 v145, v192
	s_mov_b64 s[40:41], s[10:11]
	v_add_u32_e32 v150, s34, v144
	v_ashrrev_i32_e32 v151, 31, v150
	v_lshl_add_u32 v148, v145, 3, s35
	v_lshl_add_u64 v[144:145], v[150:151], 2, s[28:29]
	v_mov_b64_e32 v[242:243], v[144:145]
	v_ashrrev_i32_e32 v149, 31, v148
	v_lshlrev_b64 v[166:167], 11, v[150:151]
	v_lshl_add_u64 v[166:167], v[166:167], 0, v[148:149]
	v_lshlrev_b64 v[172:173], 1, v[166:167]
	v_lshl_add_u64 v[174:175], s[14:15], 0, v[172:173]
	v_mov_b64_e32 v[238:239], v[174:175]
	v_mov_b64_e32 v[144:145], s[16:17]
	v_mad_i64_i32 v[162:163], s[0:1], v150, s65, v[144:145]
	v_lshlrev_b64 v[146:147], 1, v[148:149]
	v_lshl_add_u64 v[170:171], v[162:163], 0, v[146:147]
	v_mov_b64_e32 v[240:241], v[170:171]
	s_mov_b32 s5, 0
	global_load_dword v191, v[242:243], off
	global_load_dwordx4 v[196:199], v[238:239], off
	global_load_dwordx4 v[200:203], v[240:241], off
	global_load_dwordx4 v[206:209], v[238:239], off offset:256
	global_load_dwordx4 v[210:213], v[240:241], off offset:256
	s_mov_b32 s4, 0x40
	v_lshl_add_u64 v[242:243], v[242:243], 0, s[4:5]
	global_load_dword v193, v[242:243], off
	s_mov_b32 s4, 0x10000
	v_lshl_add_u64 v[238:239], v[238:239], 0, s[4:5]
	global_load_dwordx4 v[214:217], v[238:239], off
	s_mov_b32 s4, 0x12000
	v_lshl_add_u64 v[240:241], v[240:241], 0, s[4:5]
	global_load_dwordx4 v[218:221], v[240:241], off
	global_load_dwordx4 v[222:225], v[238:239], off offset:256
	global_load_dwordx4 v[226:229], v[240:241], off offset:256
	s_mov_b32 s4, 0x40
	v_lshl_add_u64 v[242:243], v[242:243], 0, s[4:5]
	global_load_dword v205, v[242:243], off
	s_mov_b32 s4, 0x40
	v_lshl_add_u64 v[242:243], v[242:243], 0, s[4:5]
	global_load_dword v234, v[242:243], off
	s_mov_b32 s4, 0x140
	v_lshl_add_u64 v[242:243], v[242:243], 0, s[4:5]
	global_load_dword v235, v[242:243], off
	s_mov_b32 s4, 0x40
	v_lshl_add_u64 v[242:243], v[242:243], 0, s[4:5]
	global_load_dword v236, v[242:243], off
	s_mov_b32 s4, 0x40
	v_lshl_add_u64 v[242:243], v[242:243], 0, s[4:5]
	global_load_dword v237, v[242:243], off
	s_mov_b32 s4, 0x40
	v_lshl_add_u64 v[242:243], v[242:243], 0, s[4:5]
	global_load_dword v230, v[242:243], off
	s_waitcnt vmcnt(15)
	v_mov_b32_e32 v161, v191
	s_waitcnt vmcnt(14)
	v_mov_b64_e32 v[166:167], v[196:197]
	v_mov_b64_e32 v[168:169], v[198:199]
	s_mov_b32 s4, 0x10000
	v_lshl_add_u64 v[238:239], v[238:239], 0, s[4:5]
	global_load_dwordx4 v[196:199], v[238:239], off
	s_waitcnt vmcnt(14)
; DI float bf_lo(unsigned u) { return __uint_as_float(u << 16); }
; DI float bf_hi(unsigned u) { return __uint_as_float(u & 0xffff0000u); }
; DI float sigmoidf_(float x) { return __builtin_amdgcn_rcpf(1.0f + __builtin_amdgcn_exp2f(-x * LOG2E)); }
; DI float rs_of(const float* ss, int row) { return 1.0f / sqrtf(ss[row] * (1.0f / DM) + EPS); }
; DI u32x4 pack8(f32x4 a, f32x4 b) { u32x4 w; w.x = cvt_pk_bf16(a[0], a[1]); w.y = cvt_pk_bf16(a[2], a[3]); w.z = cvt_pk_bf16(b[0], b[1]); w.w = cvt_pk_bf16(b[2], b[3]); return w; }
;     DI void operator()(AccRef acc, const Unit& u, int wr, int wc, int fr, int fq) const {
;         const int col0 = u.pn * 256 + wc * 32 + 8 * fq;
; #pragma unroll
;         for (int ai = 0; ai < 2; ++ai)
; #pragma unroll
;             for (int m = 0; m < 4; ++m) { const int row = u.pm * 256 + ai * 128 + wr * 64 + m * 16 + fr; const size_t off = (size_t)row * DM + col0; const float r = rs_of(ss, row);
; #pragma unroll
;                 for (int bj = 0; bj < 2; ++bj) {
;                     const u32x4 ev = *(const u32x4*)(Eb + off + bj * 128), uv = *(const u32x4*)(UPh + (size_t)row * 2304 + col0 + bj * 128);
;                     const f32x4 e0 = {bf_lo(ev.x), bf_hi(ev.x), bf_lo(ev.y), bf_hi(ev.y)}, e1 = {bf_lo(ev.z), bf_hi(ev.z), bf_lo(ev.w), bf_hi(ev.w)};
;                     f32x4 h0 = {bf_lo(uv.x), bf_hi(uv.x), bf_lo(uv.y), bf_hi(uv.y)}, h1 = {bf_lo(uv.z), bf_hi(uv.z), bf_lo(uv.w), bf_hi(uv.w)};
; #pragma unroll
;                     for (int j = 0; j < 4; ++j) { h0[j] += sigmoidf_(acc[ai][bj][m][0][j] * r) * e0[j]; h1[j] += sigmoidf_(acc[ai][bj][m][1][j] * r) * e1[j]; }
;                     *(u32x4*)(Hf + off + bj * 128) = pack8(h0, h1); } }
;     }
	v_mov_b64_e32 v[162:163], v[200:201]
	v_mov_b64_e32 v[164:165], v[202:203]
	s_mov_b32 s4, 0x12000
	v_lshl_add_u64 v[240:241], v[240:241], 0, s[4:5]
	global_load_dwordx4 v[200:203], v[240:241], off
	s_mov_b64 s[38:39], s[36:37]
	v_fmamk_f32 v151, v161, 0x3a000000, v159
	v_mul_f32_e32 v161, 0x4f800000, v151
	v_cmp_gt_f32_e32 vcc, s64, v151
	v_lshlrev_b32_e32 v180, 16, v166
	s_nop 0
	v_cndmask_b32_e32 v151, v151, v161, vcc
	v_sqrt_f32_e32 v161, v151
	v_and_b32_e32 v166, 0xffff0000, v166
	v_lshlrev_b32_e32 v181, 16, v167
	v_and_b32_e32 v167, 0xffff0000, v167
	v_add_u32_e32 v187, -1, v161
	v_add_u32_e32 v188, 1, v161
	v_fma_f32 v189, -v187, v161, v151
	v_fma_f32 v190, -v188, v161, v151
	v_cmp_ge_f32_e64 s[8:9], 0, v189
	v_lshlrev_b32_e32 v176, 16, v162
	v_and_b32_e32 v162, 0xffff0000, v162
	v_cndmask_b32_e64 v161, v161, v187, s[8:9]
	v_cmp_lt_f32_e64 s[8:9], 0, v190
	v_lshlrev_b32_e32 v177, 16, v163
	v_and_b32_e32 v163, 0xffff0000, v163
	v_cndmask_b32_e64 v161, v161, v188, s[8:9]
	v_mul_f32_e32 v187, 0x37800000, v161
	v_cndmask_b32_e32 v161, v161, v187, vcc
	v_cmp_class_f32_e32 vcc, v151, v160
	v_lshlrev_b32_e32 v178, 16, v164
	v_and_b32_e32 v164, 0xffff0000, v164
	v_cndmask_b32_e32 v151, v161, v151, vcc
	v_div_scale_f32 v161, s[0:1], v151, v151, 1.0
	v_rcp_f32_e32 v187, v161
	v_div_scale_f32 v188, vcc, 1.0, v151, 1.0
	v_lshlrev_b32_e32 v182, 16, v168
	v_fma_f32 v189, -v161, v187, 1.0
	v_fmac_f32_e32 v187, v189, v187
	v_mul_f32_e32 v189, v188, v187
	v_fma_f32 v190, -v161, v189, v188
	v_fmac_f32_e32 v189, v190, v187
	v_fma_f32 v161, -v161, v189, v188
	v_div_fmas_f32 v161, v161, v187, v189
	v_div_fixup_f32 v151, v161, v151, 1.0
	v_mul_f32_e32 v125, v125, v151
	v_mul_f32_e32 v127, v127, v151
	v_mul_f32_e32 v124, v124, v151
	v_mul_f32_e32 v120, v120, v151
	v_mul_f32_e32 v121, v121, v151
	v_mul_f32_e32 v126, v126, v151
	v_mul_f32_e32 v125, 0xbfb8aa3b, v125
	v_mul_f32_e32 v127, 0xbfb8aa3b, v127
	v_mul_f32_e32 v122, v122, v151
	v_mul_f32_e32 v123, v123, v151
	v_mul_f32_e32 v124, 0xbfb8aa3b, v124
	v_mul_f32_e32 v120, 0xbfb8aa3b, v120
	v_mul_f32_e32 v121, 0xbfb8aa3b, v121
	v_mul_f32_e32 v126, 0xbfb8aa3b, v126
	v_exp_f32_e32 v125, v125
	v_exp_f32_e32 v127, v127
	v_mul_f32_e32 v122, 0xbfb8aa3b, v122
	v_mul_f32_e32 v123, 0xbfb8aa3b, v123
	v_exp_f32_e32 v124, v124
	v_exp_f32_e32 v120, v120
	v_exp_f32_e32 v121, v121
	v_exp_f32_e32 v126, v126
	v_exp_f32_e32 v122, v122
	v_exp_f32_e32 v123, v123
	v_add_f32_e32 v125, 1.0, v125
	v_add_f32_e32 v127, 1.0, v127
	v_add_f32_e32 v124, 1.0, v124
	v_add_f32_e32 v120, 1.0, v120
	v_add_f32_e32 v121, 1.0, v121
	v_add_f32_e32 v126, 1.0, v126
	v_rcp_f32_e32 v125, v125
	v_rcp_f32_e32 v127, v127
	v_add_f32_e32 v122, 1.0, v122
	v_add_f32_e32 v123, 1.0, v123
	v_rcp_f32_e32 v124, v124
	v_rcp_f32_e32 v120, v120
	v_rcp_f32_e32 v121, v121
	v_rcp_f32_e32 v126, v126
	v_rcp_f32_e32 v122, v122
	v_rcp_f32_e32 v123, v123
	v_and_b32_e32 v168, 0xffff0000, v168
	v_fmac_f32_e32 v162, v125, v166
	v_fmac_f32_e32 v163, v127, v167
	v_lshlrev_b32_e32 v179, 16, v165
	v_and_b32_e32 v165, 0xffff0000, v165
	v_lshlrev_b32_e32 v183, 16, v169
	v_and_b32_e32 v169, 0xffff0000, v169
	v_fmac_f32_e32 v176, v124, v180
	v_fmac_f32_e32 v178, v120, v182
	v_fmac_f32_e32 v164, v121, v168
	v_fmac_f32_e32 v177, v126, v181
	v_cvt_pk_bf16_f32 v120, v176, v162
	v_cvt_pk_bf16_f32 v121, v177, v163
	v_lshl_add_u64 v[162:163], s[18:19], 0, v[172:173]
	v_fmac_f32_e32 v179, v122, v183
	v_fmac_f32_e32 v165, v123, v169
	v_cvt_pk_bf16_f32 v122, v178, v164
	v_cvt_pk_bf16_f32 v123, v179, v165
	global_store_dwordx4 v[162:163], v[120:123], off
	s_waitcnt vmcnt(15)
	v_mov_b64_e32 v[124:125], v[206:207]
	v_mov_b64_e32 v[126:127], v[208:209]
	global_load_dwordx4 v[206:209], v[238:239], off offset:256
	v_mul_f32_e32 v116, v116, v151
	s_waitcnt vmcnt(15)
	v_mov_b64_e32 v[120:121], v[210:211]
	v_mov_b64_e32 v[122:123], v[212:213]
	global_load_dwordx4 v[210:213], v[240:241], off offset:256
	v_mul_f32_e32 v112, v112, v151
	v_mul_f32_e32 v117, v117, v151
	v_mul_f32_e32 v113, v113, v151
	v_mul_f32_e32 v118, v118, v151
	v_mul_f32_e32 v114, v114, v151
	v_mul_f32_e32 v119, v119, v151
	v_mul_f32_e32 v115, v115, v151
	v_mul_f32_e32 v116, 0xbfb8aa3b, v116
	v_mul_f32_e32 v112, 0xbfb8aa3b, v112
	v_mul_f32_e32 v117, 0xbfb8aa3b, v117
	v_mul_f32_e32 v113, 0xbfb8aa3b, v113
	v_mul_f32_e32 v118, 0xbfb8aa3b, v118
	v_mul_f32_e32 v114, 0xbfb8aa3b, v114
	v_mul_f32_e32 v119, 0xbfb8aa3b, v119
	v_mul_f32_e32 v115, 0xbfb8aa3b, v115
	v_exp_f32_e32 v116, v116
	v_exp_f32_e32 v112, v112
	v_exp_f32_e32 v117, v117
	v_exp_f32_e32 v113, v113
	v_exp_f32_e32 v118, v118
	v_exp_f32_e32 v114, v114
	v_exp_f32_e32 v119, v119
	v_exp_f32_e32 v115, v115
	v_add_f32_e32 v116, 1.0, v116
	v_add_f32_e32 v112, 1.0, v112
	v_add_f32_e32 v117, 1.0, v117
	v_add_f32_e32 v113, 1.0, v113
	v_add_f32_e32 v118, 1.0, v118
	v_add_f32_e32 v114, 1.0, v114
	v_add_f32_e32 v119, 1.0, v119
	v_add_f32_e32 v115, 1.0, v115
	v_add_u32_e32 v164, 16, v150
	v_rcp_f32_e32 v116, v116
	v_rcp_f32_e32 v112, v112
	v_rcp_f32_e32 v117, v117
	v_rcp_f32_e32 v113, v113
	v_rcp_f32_e32 v118, v118
	v_rcp_f32_e32 v114, v114
	v_rcp_f32_e32 v119, v119
	v_rcp_f32_e32 v115, v115
	v_ashrrev_i32_e32 v165, 31, v164
	v_lshlrev_b64 v[166:167], 11, v[164:165]
	v_lshl_add_u64 v[168:169], v[164:165], 2, s[28:29]
	v_lshl_add_u64 v[166:167], v[166:167], 0, v[148:149]
	v_lshlrev_b64 v[166:167], 1, v[166:167]
	v_lshlrev_b32_e32 v151, 16, v124
	v_and_b32_e32 v124, 0xffff0000, v124
	v_lshlrev_b32_e32 v161, 16, v125
	v_and_b32_e32 v125, 0xffff0000, v125
	v_lshlrev_b32_e32 v165, 16, v126
	v_and_b32_e32 v126, 0xffff0000, v126
	v_lshlrev_b32_e32 v172, 16, v127
	v_and_b32_e32 v127, 0xffff0000, v127
	v_lshlrev_b32_e32 v173, 16, v120
	v_and_b32_e32 v120, 0xffff0000, v120
	v_lshlrev_b32_e32 v174, 16, v121
	v_and_b32_e32 v121, 0xffff0000, v121
	v_lshlrev_b32_e32 v175, 16, v122
	v_and_b32_e32 v122, 0xffff0000, v122
	v_lshlrev_b32_e32 v176, 16, v123
	v_and_b32_e32 v123, 0xffff0000, v123
	v_fmac_f32_e32 v173, v116, v151
	v_fmac_f32_e32 v175, v112, v165
	v_fmac_f32_e32 v120, v117, v124
	v_fmac_f32_e32 v122, v113, v126
	v_fmac_f32_e32 v174, v118, v161
	v_fmac_f32_e32 v176, v114, v172
	v_fmac_f32_e32 v121, v119, v125
	v_fmac_f32_e32 v123, v115, v127
	v_cvt_pk_bf16_f32 v112, v173, v120
	v_cvt_pk_bf16_f32 v113, v174, v121
	v_cvt_pk_bf16_f32 v114, v175, v122
	v_cvt_pk_bf16_f32 v115, v176, v123
	global_store_dwordx4 v[162:163], v[112:115], off offset:256
	s_waitcnt vmcnt(16)
; DI float bf_lo(unsigned u) { return __uint_as_float(u << 16); }
; DI float bf_hi(unsigned u) { return __uint_as_float(u & 0xffff0000u); }
; DI float sigmoidf_(float x) { return __builtin_amdgcn_rcpf(1.0f + __builtin_amdgcn_exp2f(-x * LOG2E)); }
; DI float rs_of(const float* ss, int row) { return 1.0f / sqrtf(ss[row] * (1.0f / DM) + EPS); }
; DI u32x4 pack8(f32x4 a, f32x4 b) { u32x4 w; w.x = cvt_pk_bf16(a[0], a[1]); w.y = cvt_pk_bf16(a[2], a[3]); w.z = cvt_pk_bf16(b[0], b[1]); w.w = cvt_pk_bf16(b[2], b[3]); return w; }
;     DI void operator()(AccRef acc, const Unit& u, int wr, int wc, int fr, int fq) const {
;         const int col0 = u.pn * 256 + wc * 32 + 8 * fq;
; #pragma unroll
;         for (int ai = 0; ai < 2; ++ai)
; #pragma unroll
;             for (int m = 0; m < 4; ++m) { const int row = u.pm * 256 + ai * 128 + wr * 64 + m * 16 + fr; const size_t off = (size_t)row * DM + col0; const float r = rs_of(ss, row);
; #pragma unroll
;                 for (int bj = 0; bj < 2; ++bj) {
;                     const u32x4 ev = *(const u32x4*)(Eb + off + bj * 128), uv = *(const u32x4*)(UPh + (size_t)row * 2304 + col0 + bj * 128);
;                     const f32x4 e0 = {bf_lo(ev.x), bf_hi(ev.x), bf_lo(ev.y), bf_hi(ev.y)}, e1 = {bf_lo(ev.z), bf_hi(ev.z), bf_lo(ev.w), bf_hi(ev.w)};
;                     f32x4 h0 = {bf_lo(uv.x), bf_hi(uv.x), bf_lo(uv.y), bf_hi(uv.y)}, h1 = {bf_lo(uv.z), bf_hi(uv.z), bf_lo(uv.w), bf_hi(uv.w)};
; #pragma unroll
;                     for (int j = 0; j < 4; ++j) { h0[j] += sigmoidf_(acc[ai][bj][m][0][j] * r) * e0[j]; h1[j] += sigmoidf_(acc[ai][bj][m][1][j] * r) * e1[j]; }
;                     *(u32x4*)(Hf + off + bj * 128) = pack8(h0, h1); } }
;     }
	v_mov_b32_e32 v122, v193
	s_nop 0
	s_waitcnt vmcnt(15)
	v_mov_b64_e32 v[112:113], v[214:215]
	v_mov_b64_e32 v[114:115], v[216:217]
	s_mov_b32 s4, 0x10000
	v_lshl_add_u64 v[238:239], v[238:239], 0, s[4:5]
	global_load_dwordx4 v[214:217], v[238:239], off
	v_mad_i64_i32 v[116:117], s[0:1], v164, s65, v[144:145]
	v_lshl_add_u64 v[120:121], v[116:117], 0, v[146:147]
	s_waitcnt vmcnt(15)
	v_mov_b64_e32 v[116:117], v[218:219]
	v_mov_b64_e32 v[118:119], v[220:221]
	s_mov_b32 s4, 0x12000
	v_lshl_add_u64 v[240:241], v[240:241], 0, s[4:5]
	global_load_dwordx4 v[218:221], v[240:241], off
	v_fmamk_f32 v122, v122, 0x3a000000, v159
	v_mul_f32_e32 v161, 0x4f800000, v122
	v_cmp_gt_f32_e32 vcc, s64, v122
	v_lshlrev_b32_e32 v123, 16, v112
	v_and_b32_e32 v112, 0xffff0000, v112
	v_cndmask_b32_e32 v122, v122, v161, vcc
	v_sqrt_f32_e32 v161, v122
	v_lshlrev_b32_e32 v124, 16, v113
	v_and_b32_e32 v113, 0xffff0000, v113
	v_lshlrev_b32_e32 v127, 16, v116
	v_add_u32_e32 v164, -1, v161
	v_add_u32_e32 v165, 1, v161
	v_fma_f32 v168, -v164, v161, v122
	v_fma_f32 v169, -v165, v161, v122
	v_cmp_ge_f32_e64 s[8:9], 0, v168
	v_and_b32_e32 v116, 0xffff0000, v116
	v_lshlrev_b32_e32 v151, 16, v117
	v_cndmask_b32_e64 v161, v161, v164, s[8:9]
	v_cmp_lt_f32_e64 s[8:9], 0, v169
	v_and_b32_e32 v117, 0xffff0000, v117
	v_lshlrev_b32_e32 v125, 16, v114
	v_cndmask_b32_e64 v161, v161, v165, s[8:9]
	v_mul_f32_e32 v164, 0x37800000, v161
	v_cndmask_b32_e32 v161, v161, v164, vcc
	v_cmp_class_f32_e32 vcc, v122, v160
	v_and_b32_e32 v114, 0xffff0000, v114
	v_lshlrev_b32_e32 v126, 16, v115
	v_cndmask_b32_e32 v122, v161, v122, vcc
	v_div_scale_f32 v161, s[0:1], v122, v122, 1.0
	v_rcp_f32_e32 v164, v161
	v_div_scale_f32 v165, vcc, 1.0, v122, 1.0
	v_and_b32_e32 v115, 0xffff0000, v115
	v_fma_f32 v168, -v161, v164, 1.0
	v_fmac_f32_e32 v164, v168, v164
	v_mul_f32_e32 v168, v165, v164
	v_fma_f32 v169, -v161, v168, v165
	v_fmac_f32_e32 v168, v169, v164
	v_fma_f32 v161, -v161, v168, v165
	v_div_fmas_f32 v161, v161, v164, v168
	v_div_fixup_f32 v122, v161, v122, 1.0
	v_mul_f32_e32 v109, v109, v122
	v_mul_f32_e32 v111, v111, v122
	v_mul_f32_e32 v108, v108, v122
	v_mul_f32_e32 v104, v104, v122
	v_mul_f32_e32 v105, v105, v122
	v_mul_f32_e32 v110, v110, v122
	v_mul_f32_e32 v106, v106, v122
	v_mul_f32_e32 v107, v107, v122
	v_mul_f32_e32 v109, 0xbfb8aa3b, v109
	v_mul_f32_e32 v111, 0xbfb8aa3b, v111
	v_mul_f32_e32 v108, 0xbfb8aa3b, v108
	v_mul_f32_e32 v104, 0xbfb8aa3b, v104
	v_mul_f32_e32 v105, 0xbfb8aa3b, v105
	v_mul_f32_e32 v110, 0xbfb8aa3b, v110
	v_mul_f32_e32 v106, 0xbfb8aa3b, v106
	v_mul_f32_e32 v107, 0xbfb8aa3b, v107
	v_exp_f32_e32 v109, v109
	v_exp_f32_e32 v111, v111
	v_exp_f32_e32 v108, v108
	v_exp_f32_e32 v104, v104
	v_exp_f32_e32 v105, v105
	v_exp_f32_e32 v110, v110
	v_exp_f32_e32 v106, v106
	v_exp_f32_e32 v107, v107
	v_add_f32_e32 v109, 1.0, v109
	v_add_f32_e32 v111, 1.0, v111
	v_add_f32_e32 v108, 1.0, v108
	v_add_f32_e32 v104, 1.0, v104
	v_add_f32_e32 v105, 1.0, v105
	v_add_f32_e32 v110, 1.0, v110
	v_add_f32_e32 v106, 1.0, v106
	v_add_f32_e32 v107, 1.0, v107
	v_rcp_f32_e32 v109, v109
	v_rcp_f32_e32 v111, v111
	v_rcp_f32_e32 v108, v108
	v_rcp_f32_e32 v104, v104
	v_rcp_f32_e32 v105, v105
	v_rcp_f32_e32 v110, v110
	v_rcp_f32_e32 v106, v106
	v_rcp_f32_e32 v107, v107
	v_lshlrev_b32_e32 v162, 16, v118
	v_and_b32_e32 v118, 0xffff0000, v118
	v_lshlrev_b32_e32 v163, 16, v119
	v_and_b32_e32 v119, 0xffff0000, v119
	v_fmac_f32_e32 v116, v109, v112
	v_fmac_f32_e32 v117, v111, v113
	v_lshl_add_u64 v[112:113], s[18:19], 0, v[166:167]
	v_fmac_f32_e32 v127, v108, v123
	v_fmac_f32_e32 v162, v104, v125
	v_fmac_f32_e32 v118, v105, v114
	v_fmac_f32_e32 v151, v110, v124
	v_fmac_f32_e32 v163, v106, v126
	v_fmac_f32_e32 v119, v107, v115
	v_cvt_pk_bf16_f32 v104, v127, v116
	v_cvt_pk_bf16_f32 v105, v151, v117
	v_cvt_pk_bf16_f32 v106, v162, v118
	v_cvt_pk_bf16_f32 v107, v163, v119
	global_store_dwordx4 v[112:113], v[104:107], off
	s_waitcnt vmcnt(16)
	v_mov_b64_e32 v[108:109], v[222:223]
	v_mov_b64_e32 v[110:111], v[224:225]
	global_load_dwordx4 v[222:225], v[238:239], off offset:256
	v_mul_f32_e32 v100, v100, v122
	s_waitcnt vmcnt(16)
	v_mov_b64_e32 v[104:105], v[226:227]
	v_mov_b64_e32 v[106:107], v[228:229]
	global_load_dwordx4 v[226:229], v[240:241], off offset:256
	v_mul_f32_e32 v96, v96, v122
	v_mul_f32_e32 v101, v101, v122
	v_mul_f32_e32 v97, v97, v122
	v_mul_f32_e32 v102, v102, v122
	v_mul_f32_e32 v98, v98, v122
	v_mul_f32_e32 v103, v103, v122
	v_mul_f32_e32 v99, v99, v122
	v_mul_f32_e32 v100, 0xbfb8aa3b, v100
	v_mul_f32_e32 v96, 0xbfb8aa3b, v96
	v_mul_f32_e32 v101, 0xbfb8aa3b, v101
	v_mul_f32_e32 v97, 0xbfb8aa3b, v97
	v_mul_f32_e32 v102, 0xbfb8aa3b, v102
	v_mul_f32_e32 v98, 0xbfb8aa3b, v98
	v_mul_f32_e32 v103, 0xbfb8aa3b, v103
	v_mul_f32_e32 v99, 0xbfb8aa3b, v99
	v_exp_f32_e32 v100, v100
	v_exp_f32_e32 v96, v96
	v_exp_f32_e32 v101, v101
	v_exp_f32_e32 v97, v97
	v_exp_f32_e32 v102, v102
	v_exp_f32_e32 v98, v98
	v_exp_f32_e32 v103, v103
	v_exp_f32_e32 v99, v99
	v_add_f32_e32 v100, 1.0, v100
	v_add_f32_e32 v96, 1.0, v96
	v_add_f32_e32 v101, 1.0, v101
	v_add_f32_e32 v97, 1.0, v97
	v_add_f32_e32 v102, 1.0, v102
	v_add_f32_e32 v98, 1.0, v98
	v_add_f32_e32 v103, 1.0, v103
	v_add_f32_e32 v99, 1.0, v99
	v_add_u32_e32 v114, 32, v150
	v_rcp_f32_e32 v100, v100
	v_rcp_f32_e32 v96, v96
	v_rcp_f32_e32 v101, v101
	v_rcp_f32_e32 v97, v97
	v_rcp_f32_e32 v102, v102
	v_rcp_f32_e32 v98, v98
	v_rcp_f32_e32 v103, v103
	v_rcp_f32_e32 v99, v99
	v_ashrrev_i32_e32 v115, 31, v114
	v_lshlrev_b64 v[116:117], 11, v[114:115]
	v_lshl_add_u64 v[118:119], v[114:115], 2, s[28:29]
	v_lshl_add_u64 v[116:117], v[116:117], 0, v[148:149]
	v_lshlrev_b64 v[116:117], 1, v[116:117]
	v_lshl_add_u64 v[120:121], s[14:15], 0, v[116:117]
	v_lshlrev_b32_e32 v115, 16, v108
	v_and_b32_e32 v108, 0xffff0000, v108
	v_lshlrev_b32_e32 v122, 16, v109
	v_and_b32_e32 v109, 0xffff0000, v109
	v_lshlrev_b32_e32 v123, 16, v110
	v_and_b32_e32 v110, 0xffff0000, v110
	v_lshlrev_b32_e32 v124, 16, v111
	v_and_b32_e32 v111, 0xffff0000, v111
	v_lshlrev_b32_e32 v125, 16, v104
	v_and_b32_e32 v104, 0xffff0000, v104
	v_lshlrev_b32_e32 v126, 16, v105
	v_and_b32_e32 v105, 0xffff0000, v105
	v_lshlrev_b32_e32 v127, 16, v106
	v_and_b32_e32 v106, 0xffff0000, v106
	v_lshlrev_b32_e32 v151, 16, v107
	v_and_b32_e32 v107, 0xffff0000, v107
	v_fmac_f32_e32 v125, v100, v115
	v_fmac_f32_e32 v127, v96, v123
	v_fmac_f32_e32 v104, v101, v108
	v_fmac_f32_e32 v106, v97, v110
	v_fmac_f32_e32 v126, v102, v122
	v_fmac_f32_e32 v151, v98, v124
	v_fmac_f32_e32 v105, v103, v109
	v_fmac_f32_e32 v107, v99, v111
	v_cvt_pk_bf16_f32 v96, v125, v104
	v_cvt_pk_bf16_f32 v97, v126, v105
	v_cvt_pk_bf16_f32 v98, v127, v106
	v_cvt_pk_bf16_f32 v99, v151, v107
	global_store_dwordx4 v[112:113], v[96:99], off offset:256
	s_waitcnt vmcnt(17)
; DI float bf_lo(unsigned u) { return __uint_as_float(u << 16); }
; DI float bf_hi(unsigned u) { return __uint_as_float(u & 0xffff0000u); }
; DI float sigmoidf_(float x) { return __builtin_amdgcn_rcpf(1.0f + __builtin_amdgcn_exp2f(-x * LOG2E)); }
; DI float rs_of(const float* ss, int row) { return 1.0f / sqrtf(ss[row] * (1.0f / DM) + EPS); }
; DI u32x4 pack8(f32x4 a, f32x4 b) { u32x4 w; w.x = cvt_pk_bf16(a[0], a[1]); w.y = cvt_pk_bf16(a[2], a[3]); w.z = cvt_pk_bf16(b[0], b[1]); w.w = cvt_pk_bf16(b[2], b[3]); return w; }
;     DI void operator()(AccRef acc, const Unit& u, int wr, int wc, int fr, int fq) const {
;         const int col0 = u.pn * 256 + wc * 32 + 8 * fq;
; #pragma unroll
;         for (int ai = 0; ai < 2; ++ai)
; #pragma unroll
;             for (int m = 0; m < 4; ++m) { const int row = u.pm * 256 + ai * 128 + wr * 64 + m * 16 + fr; const size_t off = (size_t)row * DM + col0; const float r = rs_of(ss, row);
; #pragma unroll
;                 for (int bj = 0; bj < 2; ++bj) {
;                     const u32x4 ev = *(const u32x4*)(Eb + off + bj * 128), uv = *(const u32x4*)(UPh + (size_t)row * 2304 + col0 + bj * 128);
;                     const f32x4 e0 = {bf_lo(ev.x), bf_hi(ev.x), bf_lo(ev.y), bf_hi(ev.y)}, e1 = {bf_lo(ev.z), bf_hi(ev.z), bf_lo(ev.w), bf_hi(ev.w)};
;                     f32x4 h0 = {bf_lo(uv.x), bf_hi(uv.x), bf_lo(uv.y), bf_hi(uv.y)}, h1 = {bf_lo(uv.z), bf_hi(uv.z), bf_lo(uv.w), bf_hi(uv.w)};
; #pragma unroll
;                     for (int j = 0; j < 4; ++j) { h0[j] += sigmoidf_(acc[ai][bj][m][0][j] * r) * e0[j]; h1[j] += sigmoidf_(acc[ai][bj][m][1][j] * r) * e1[j]; }
;                     *(u32x4*)(Hf + off + bj * 128) = pack8(h0, h1); } }
;     }
	v_mov_b32_e32 v106, v205
	s_nop 0
	s_waitcnt vmcnt(11)
	v_mov_b64_e32 v[96:97], v[196:197]
	v_mov_b64_e32 v[98:99], v[198:199]
	s_mov_b32 s4, 0x50000
	v_lshl_add_u64 v[238:239], v[238:239], 0, s[4:5]
	global_load_dwordx4 v[196:199], v[238:239], off
	v_mad_i64_i32 v[100:101], s[0:1], v114, s65, v[144:145]
	v_lshl_add_u64 v[104:105], v[100:101], 0, v[146:147]
	s_waitcnt vmcnt(11)
	v_mov_b64_e32 v[100:101], v[200:201]
	v_mov_b64_e32 v[102:103], v[202:203]
	s_mov_b32 s4, 0x5a000
	v_lshl_add_u64 v[240:241], v[240:241], 0, s[4:5]
	global_load_dwordx4 v[200:203], v[240:241], off
	v_fmamk_f32 v106, v106, 0x3a000000, v159
	v_mul_f32_e32 v113, 0x4f800000, v106
	v_cmp_gt_f32_e32 vcc, s64, v106
	v_lshlrev_b32_e32 v107, 16, v96
	v_and_b32_e32 v96, 0xffff0000, v96
	v_cndmask_b32_e32 v106, v106, v113, vcc
	v_sqrt_f32_e32 v113, v106
	v_lshlrev_b32_e32 v108, 16, v97
	v_and_b32_e32 v97, 0xffff0000, v97
	v_lshlrev_b32_e32 v111, 16, v100
	v_add_u32_e32 v118, -1, v113
	v_add_u32_e32 v119, 1, v113
	v_fma_f32 v122, -v118, v113, v106
	v_fma_f32 v123, -v119, v113, v106
	v_cmp_ge_f32_e64 s[8:9], 0, v122
	v_and_b32_e32 v100, 0xffff0000, v100
	v_lshlrev_b32_e32 v112, 16, v101
	v_cndmask_b32_e64 v113, v113, v118, s[8:9]
	v_cmp_lt_f32_e64 s[8:9], 0, v123
	v_and_b32_e32 v101, 0xffff0000, v101
	v_lshlrev_b32_e32 v109, 16, v98
	v_cndmask_b32_e64 v113, v113, v119, s[8:9]
	v_mul_f32_e32 v118, 0x37800000, v113
	v_cndmask_b32_e32 v113, v113, v118, vcc
	v_cmp_class_f32_e32 vcc, v106, v160
	v_and_b32_e32 v98, 0xffff0000, v98
	v_lshlrev_b32_e32 v110, 16, v99
	v_cndmask_b32_e32 v106, v113, v106, vcc
	v_div_scale_f32 v113, s[0:1], v106, v106, 1.0
	v_rcp_f32_e32 v118, v113
	v_div_scale_f32 v119, vcc, 1.0, v106, 1.0
	v_and_b32_e32 v99, 0xffff0000, v99
	v_fma_f32 v122, -v113, v118, 1.0
	v_fmac_f32_e32 v118, v122, v118
	v_mul_f32_e32 v122, v119, v118
	v_fma_f32 v123, -v113, v122, v119
	v_fmac_f32_e32 v122, v123, v118
	v_fma_f32 v113, -v113, v122, v119
	v_div_fmas_f32 v113, v113, v118, v122
	v_div_fixup_f32 v106, v113, v106, 1.0
	v_mul_f32_e32 v93, v93, v106
	v_mul_f32_e32 v95, v95, v106
	v_mul_f32_e32 v92, v92, v106
	v_mul_f32_e32 v88, v88, v106
	v_mul_f32_e32 v89, v89, v106
	v_mul_f32_e32 v94, v94, v106
	v_mul_f32_e32 v90, v90, v106
	v_mul_f32_e32 v91, v91, v106
	v_mul_f32_e32 v93, 0xbfb8aa3b, v93
	v_mul_f32_e32 v95, 0xbfb8aa3b, v95
	v_mul_f32_e32 v92, 0xbfb8aa3b, v92
	v_mul_f32_e32 v88, 0xbfb8aa3b, v88
	v_mul_f32_e32 v89, 0xbfb8aa3b, v89
	v_mul_f32_e32 v94, 0xbfb8aa3b, v94
	v_mul_f32_e32 v90, 0xbfb8aa3b, v90
	v_mul_f32_e32 v91, 0xbfb8aa3b, v91
	v_exp_f32_e32 v93, v93
	v_exp_f32_e32 v95, v95
	v_exp_f32_e32 v92, v92
	v_exp_f32_e32 v88, v88
	v_exp_f32_e32 v89, v89
	v_exp_f32_e32 v94, v94
	v_exp_f32_e32 v90, v90
	v_exp_f32_e32 v91, v91
	v_add_f32_e32 v93, 1.0, v93
	v_add_f32_e32 v95, 1.0, v95
	v_add_f32_e32 v92, 1.0, v92
	v_add_f32_e32 v88, 1.0, v88
	v_add_f32_e32 v89, 1.0, v89
	v_add_f32_e32 v94, 1.0, v94
	v_add_f32_e32 v90, 1.0, v90
	v_add_f32_e32 v91, 1.0, v91
	v_rcp_f32_e32 v93, v93
	v_rcp_f32_e32 v95, v95
	v_rcp_f32_e32 v92, v92
	v_rcp_f32_e32 v88, v88
	v_rcp_f32_e32 v89, v89
	v_rcp_f32_e32 v94, v94
	v_rcp_f32_e32 v90, v90
	v_rcp_f32_e32 v91, v91
	v_lshlrev_b32_e32 v114, 16, v102
	v_and_b32_e32 v102, 0xffff0000, v102
	v_lshlrev_b32_e32 v115, 16, v103
	v_and_b32_e32 v103, 0xffff0000, v103
	v_fmac_f32_e32 v100, v93, v96
	v_fmac_f32_e32 v101, v95, v97
	v_lshl_add_u64 v[96:97], s[18:19], 0, v[116:117]
	v_fmac_f32_e32 v111, v92, v107
	v_fmac_f32_e32 v114, v88, v109
	v_fmac_f32_e32 v102, v89, v98
	v_fmac_f32_e32 v112, v94, v108
	v_fmac_f32_e32 v115, v90, v110
	v_fmac_f32_e32 v103, v91, v99
	v_cvt_pk_bf16_f32 v88, v111, v100
	v_cvt_pk_bf16_f32 v89, v112, v101
	v_cvt_pk_bf16_f32 v90, v114, v102
	v_cvt_pk_bf16_f32 v91, v115, v103
	global_store_dwordx4 v[96:97], v[88:91], off
	s_waitcnt vmcnt(11)
	v_mov_b64_e32 v[92:93], v[206:207]
	v_mov_b64_e32 v[94:95], v[208:209]
	global_load_dwordx4 v[206:209], v[238:239], off offset:256
	v_mul_f32_e32 v84, v84, v106
	s_waitcnt vmcnt(11)
	v_mov_b64_e32 v[88:89], v[210:211]
	v_mov_b64_e32 v[90:91], v[212:213]
	global_load_dwordx4 v[210:213], v[240:241], off offset:256
	v_mul_f32_e32 v80, v80, v106
	v_mul_f32_e32 v85, v85, v106
	v_mul_f32_e32 v81, v81, v106
	v_mul_f32_e32 v86, v86, v106
	v_mul_f32_e32 v82, v82, v106
	v_mul_f32_e32 v87, v87, v106
	v_mul_f32_e32 v83, v83, v106
	v_mul_f32_e32 v84, 0xbfb8aa3b, v84
	v_mul_f32_e32 v80, 0xbfb8aa3b, v80
	v_mul_f32_e32 v85, 0xbfb8aa3b, v85
	v_mul_f32_e32 v81, 0xbfb8aa3b, v81
	v_mul_f32_e32 v86, 0xbfb8aa3b, v86
	v_mul_f32_e32 v82, 0xbfb8aa3b, v82
	v_mul_f32_e32 v87, 0xbfb8aa3b, v87
	v_mul_f32_e32 v83, 0xbfb8aa3b, v83
	v_exp_f32_e32 v84, v84
	v_exp_f32_e32 v80, v80
	v_exp_f32_e32 v85, v85
	v_exp_f32_e32 v81, v81
	v_exp_f32_e32 v86, v86
	v_exp_f32_e32 v82, v82
	v_exp_f32_e32 v87, v87
	v_exp_f32_e32 v83, v83
	v_add_f32_e32 v84, 1.0, v84
	v_add_f32_e32 v80, 1.0, v80
	v_add_f32_e32 v85, 1.0, v85
	v_add_f32_e32 v81, 1.0, v81
	v_add_f32_e32 v86, 1.0, v86
	v_add_f32_e32 v82, 1.0, v82
	v_add_f32_e32 v87, 1.0, v87
	v_add_f32_e32 v83, 1.0, v83
	v_add_u32_e32 v98, 48, v150
	v_rcp_f32_e32 v84, v84
	v_rcp_f32_e32 v80, v80
	v_rcp_f32_e32 v85, v85
	v_rcp_f32_e32 v81, v81
	v_rcp_f32_e32 v86, v86
	v_rcp_f32_e32 v82, v82
	v_rcp_f32_e32 v87, v87
	v_rcp_f32_e32 v83, v83
	v_ashrrev_i32_e32 v99, 31, v98
	v_lshlrev_b64 v[100:101], 11, v[98:99]
	v_lshl_add_u64 v[102:103], v[98:99], 2, s[28:29]
	v_lshl_add_u64 v[100:101], v[100:101], 0, v[148:149]
	v_lshlrev_b64 v[100:101], 1, v[100:101]
	v_lshl_add_u64 v[104:105], s[14:15], 0, v[100:101]
	v_lshlrev_b32_e32 v99, 16, v92
	v_and_b32_e32 v92, 0xffff0000, v92
	v_lshlrev_b32_e32 v106, 16, v93
	v_and_b32_e32 v93, 0xffff0000, v93
	v_lshlrev_b32_e32 v107, 16, v94
	v_and_b32_e32 v94, 0xffff0000, v94
	v_lshlrev_b32_e32 v108, 16, v95
	v_and_b32_e32 v95, 0xffff0000, v95
	v_lshlrev_b32_e32 v109, 16, v88
	v_and_b32_e32 v88, 0xffff0000, v88
	v_lshlrev_b32_e32 v110, 16, v89
	v_and_b32_e32 v89, 0xffff0000, v89
	v_lshlrev_b32_e32 v111, 16, v90
	v_and_b32_e32 v90, 0xffff0000, v90
	v_lshlrev_b32_e32 v112, 16, v91
	v_and_b32_e32 v91, 0xffff0000, v91
	v_fmac_f32_e32 v109, v84, v99
	v_fmac_f32_e32 v111, v80, v107
	v_fmac_f32_e32 v88, v85, v92
	v_fmac_f32_e32 v90, v81, v94
	v_fmac_f32_e32 v110, v86, v106
	v_fmac_f32_e32 v112, v82, v108
	v_fmac_f32_e32 v89, v87, v93
	v_fmac_f32_e32 v91, v83, v95
	v_cvt_pk_bf16_f32 v80, v109, v88
	v_cvt_pk_bf16_f32 v81, v110, v89
	v_cvt_pk_bf16_f32 v82, v111, v90
	v_cvt_pk_bf16_f32 v83, v112, v91
	global_store_dwordx4 v[96:97], v[80:83], off offset:256
	s_waitcnt vmcnt(22)
; DI float bf_lo(unsigned u) { return __uint_as_float(u << 16); }
; DI float bf_hi(unsigned u) { return __uint_as_float(u & 0xffff0000u); }
; DI float sigmoidf_(float x) { return __builtin_amdgcn_rcpf(1.0f + __builtin_amdgcn_exp2f(-x * LOG2E)); }
; DI float rs_of(const float* ss, int row) { return 1.0f / sqrtf(ss[row] * (1.0f / DM) + EPS); }
; DI u32x4 pack8(f32x4 a, f32x4 b) { u32x4 w; w.x = cvt_pk_bf16(a[0], a[1]); w.y = cvt_pk_bf16(a[2], a[3]); w.z = cvt_pk_bf16(b[0], b[1]); w.w = cvt_pk_bf16(b[2], b[3]); return w; }
;     DI void operator()(AccRef acc, const Unit& u, int wr, int wc, int fr, int fq) const {
;         const int col0 = u.pn * 256 + wc * 32 + 8 * fq;
; #pragma unroll
;         for (int ai = 0; ai < 2; ++ai)
; #pragma unroll
;             for (int m = 0; m < 4; ++m) { const int row = u.pm * 256 + ai * 128 + wr * 64 + m * 16 + fr; const size_t off = (size_t)row * DM + col0; const float r = rs_of(ss, row);
; #pragma unroll
;                 for (int bj = 0; bj < 2; ++bj) {
;                     const u32x4 ev = *(const u32x4*)(Eb + off + bj * 128), uv = *(const u32x4*)(UPh + (size_t)row * 2304 + col0 + bj * 128);
;                     const f32x4 e0 = {bf_lo(ev.x), bf_hi(ev.x), bf_lo(ev.y), bf_hi(ev.y)}, e1 = {bf_lo(ev.z), bf_hi(ev.z), bf_lo(ev.w), bf_hi(ev.w)};
;                     f32x4 h0 = {bf_lo(uv.x), bf_hi(uv.x), bf_lo(uv.y), bf_hi(uv.y)}, h1 = {bf_lo(uv.z), bf_hi(uv.z), bf_lo(uv.w), bf_hi(uv.w)};
; #pragma unroll
;                     for (int j = 0; j < 4; ++j) { h0[j] += sigmoidf_(acc[ai][bj][m][0][j] * r) * e0[j]; h1[j] += sigmoidf_(acc[ai][bj][m][1][j] * r) * e1[j]; }
;                     *(u32x4*)(Hf + off + bj * 128) = pack8(h0, h1); } }
;     }
	v_mov_b32_e32 v90, v234
	s_nop 0
	s_waitcnt vmcnt(11)
	v_mov_b64_e32 v[80:81], v[214:215]
	v_mov_b64_e32 v[82:83], v[216:217]
	s_mov_b32 s4, 0x10000
	v_lshl_add_u64 v[238:239], v[238:239], 0, s[4:5]
	global_load_dwordx4 v[214:217], v[238:239], off
	v_mad_i64_i32 v[84:85], s[0:1], v98, s65, v[144:145]
	v_lshl_add_u64 v[88:89], v[84:85], 0, v[146:147]
	s_waitcnt vmcnt(11)
	v_mov_b64_e32 v[84:85], v[218:219]
	v_mov_b64_e32 v[86:87], v[220:221]
	s_mov_b32 s4, 0x12000
	v_lshl_add_u64 v[240:241], v[240:241], 0, s[4:5]
	global_load_dwordx4 v[218:221], v[240:241], off
	v_fmamk_f32 v90, v90, 0x3a000000, v159
	v_mul_f32_e32 v97, 0x4f800000, v90
	v_cmp_gt_f32_e32 vcc, s64, v90
	v_lshlrev_b32_e32 v91, 16, v80
	v_and_b32_e32 v80, 0xffff0000, v80
	v_cndmask_b32_e32 v90, v90, v97, vcc
	v_sqrt_f32_e32 v97, v90
	v_lshlrev_b32_e32 v92, 16, v81
	v_and_b32_e32 v81, 0xffff0000, v81
	v_lshlrev_b32_e32 v95, 16, v84
	v_add_u32_e32 v102, -1, v97
	v_add_u32_e32 v103, 1, v97
	v_fma_f32 v106, -v102, v97, v90
	v_fma_f32 v107, -v103, v97, v90
	v_cmp_ge_f32_e64 s[8:9], 0, v106
	v_and_b32_e32 v84, 0xffff0000, v84
	v_lshlrev_b32_e32 v96, 16, v85
	v_cndmask_b32_e64 v97, v97, v102, s[8:9]
	v_cmp_lt_f32_e64 s[8:9], 0, v107
	v_and_b32_e32 v85, 0xffff0000, v85
	v_lshlrev_b32_e32 v93, 16, v82
	v_cndmask_b32_e64 v97, v97, v103, s[8:9]
	v_mul_f32_e32 v102, 0x37800000, v97
	v_cndmask_b32_e32 v97, v97, v102, vcc
	v_cmp_class_f32_e32 vcc, v90, v160
	v_and_b32_e32 v82, 0xffff0000, v82
	v_lshlrev_b32_e32 v94, 16, v83
	v_cndmask_b32_e32 v90, v97, v90, vcc
	v_div_scale_f32 v97, s[0:1], v90, v90, 1.0
	v_rcp_f32_e32 v102, v97
	v_div_scale_f32 v103, vcc, 1.0, v90, 1.0
	v_and_b32_e32 v83, 0xffff0000, v83
	v_fma_f32 v106, -v97, v102, 1.0
	v_fmac_f32_e32 v102, v106, v102
	v_mul_f32_e32 v106, v103, v102
	v_fma_f32 v107, -v97, v106, v103
	v_fmac_f32_e32 v106, v107, v102
	v_fma_f32 v97, -v97, v106, v103
	v_div_fmas_f32 v97, v97, v102, v106
	v_div_fixup_f32 v90, v97, v90, 1.0
	v_mul_f32_e32 v77, v77, v90
	v_mul_f32_e32 v79, v79, v90
	v_mul_f32_e32 v76, v76, v90
	v_mul_f32_e32 v72, v72, v90
	v_mul_f32_e32 v73, v73, v90
	v_mul_f32_e32 v78, v78, v90
	v_mul_f32_e32 v74, v74, v90
	v_mul_f32_e32 v75, v75, v90
	v_mul_f32_e32 v77, 0xbfb8aa3b, v77
	v_mul_f32_e32 v79, 0xbfb8aa3b, v79
	v_mul_f32_e32 v76, 0xbfb8aa3b, v76
	v_mul_f32_e32 v72, 0xbfb8aa3b, v72
	v_mul_f32_e32 v73, 0xbfb8aa3b, v73
	v_mul_f32_e32 v78, 0xbfb8aa3b, v78
	v_mul_f32_e32 v74, 0xbfb8aa3b, v74
	v_mul_f32_e32 v75, 0xbfb8aa3b, v75
	v_exp_f32_e32 v77, v77
	v_exp_f32_e32 v79, v79
	v_exp_f32_e32 v76, v76
	v_exp_f32_e32 v72, v72
	v_exp_f32_e32 v73, v73
	v_exp_f32_e32 v78, v78
	v_exp_f32_e32 v74, v74
	v_exp_f32_e32 v75, v75
	v_add_f32_e32 v77, 1.0, v77
	v_add_f32_e32 v79, 1.0, v79
	v_add_f32_e32 v76, 1.0, v76
	v_add_f32_e32 v72, 1.0, v72
	v_add_f32_e32 v73, 1.0, v73
	v_add_f32_e32 v78, 1.0, v78
	v_add_f32_e32 v74, 1.0, v74
	v_add_f32_e32 v75, 1.0, v75
	v_rcp_f32_e32 v77, v77
	v_rcp_f32_e32 v79, v79
	v_rcp_f32_e32 v76, v76
	v_rcp_f32_e32 v72, v72
	v_rcp_f32_e32 v73, v73
	v_rcp_f32_e32 v78, v78
	v_rcp_f32_e32 v74, v74
	v_rcp_f32_e32 v75, v75
	v_lshlrev_b32_e32 v98, 16, v86
	v_and_b32_e32 v86, 0xffff0000, v86
	v_lshlrev_b32_e32 v99, 16, v87
	v_and_b32_e32 v87, 0xffff0000, v87
	v_fmac_f32_e32 v84, v77, v80
	v_fmac_f32_e32 v85, v79, v81
	v_lshl_add_u64 v[80:81], s[18:19], 0, v[100:101]
	v_fmac_f32_e32 v95, v76, v91
	v_fmac_f32_e32 v98, v72, v93
	v_fmac_f32_e32 v86, v73, v82
	v_fmac_f32_e32 v96, v78, v92
	v_fmac_f32_e32 v99, v74, v94
	v_fmac_f32_e32 v87, v75, v83
	v_cvt_pk_bf16_f32 v72, v95, v84
	v_cvt_pk_bf16_f32 v73, v96, v85
	v_cvt_pk_bf16_f32 v74, v98, v86
	v_cvt_pk_bf16_f32 v75, v99, v87
	global_store_dwordx4 v[80:81], v[72:75], off
	s_waitcnt vmcnt(11)
	v_mov_b64_e32 v[76:77], v[222:223]
	v_mov_b64_e32 v[78:79], v[224:225]
	global_load_dwordx4 v[222:225], v[238:239], off offset:256
	v_mul_f32_e32 v68, v68, v90
	s_waitcnt vmcnt(11)
	v_mov_b64_e32 v[72:73], v[226:227]
	v_mov_b64_e32 v[74:75], v[228:229]
	global_load_dwordx4 v[226:229], v[240:241], off offset:256
	v_mul_f32_e32 v64, v64, v90
	v_mul_f32_e32 v69, v69, v90
	v_mul_f32_e32 v65, v65, v90
	v_mul_f32_e32 v70, v70, v90
	v_mul_f32_e32 v66, v66, v90
	v_mul_f32_e32 v71, v71, v90
	v_mul_f32_e32 v67, v67, v90
	v_mul_f32_e32 v68, 0xbfb8aa3b, v68
	v_mul_f32_e32 v64, 0xbfb8aa3b, v64
	v_mul_f32_e32 v69, 0xbfb8aa3b, v69
	v_mul_f32_e32 v65, 0xbfb8aa3b, v65
	v_mul_f32_e32 v70, 0xbfb8aa3b, v70
	v_mul_f32_e32 v66, 0xbfb8aa3b, v66
	v_mul_f32_e32 v71, 0xbfb8aa3b, v71
	v_mul_f32_e32 v67, 0xbfb8aa3b, v67
	v_exp_f32_e32 v68, v68
	v_exp_f32_e32 v64, v64
	v_exp_f32_e32 v69, v69
	v_exp_f32_e32 v65, v65
	v_exp_f32_e32 v70, v70
	v_exp_f32_e32 v66, v66
	v_exp_f32_e32 v71, v71
	v_exp_f32_e32 v67, v67
	v_add_f32_e32 v68, 1.0, v68
	v_add_f32_e32 v64, 1.0, v64
	v_add_f32_e32 v69, 1.0, v69
	v_add_f32_e32 v65, 1.0, v65
	v_add_f32_e32 v70, 1.0, v70
	v_add_f32_e32 v66, 1.0, v66
	v_add_f32_e32 v71, 1.0, v71
	v_add_f32_e32 v67, 1.0, v67
	v_add_u32_e32 v82, 0x80, v150
	v_rcp_f32_e32 v68, v68
	v_rcp_f32_e32 v64, v64
	v_rcp_f32_e32 v69, v69
	v_rcp_f32_e32 v65, v65
	v_rcp_f32_e32 v70, v70
	v_rcp_f32_e32 v66, v66
	v_rcp_f32_e32 v71, v71
	v_rcp_f32_e32 v67, v67
	v_ashrrev_i32_e32 v83, 31, v82
	v_lshlrev_b64 v[84:85], 11, v[82:83]
	v_lshl_add_u64 v[86:87], v[82:83], 2, s[28:29]
	v_lshl_add_u64 v[84:85], v[84:85], 0, v[148:149]
	v_lshlrev_b64 v[84:85], 1, v[84:85]
	v_lshl_add_u64 v[88:89], s[14:15], 0, v[84:85]
	v_lshlrev_b32_e32 v83, 16, v76
	v_and_b32_e32 v76, 0xffff0000, v76
	v_lshlrev_b32_e32 v90, 16, v77
	v_and_b32_e32 v77, 0xffff0000, v77
	v_lshlrev_b32_e32 v91, 16, v78
	v_and_b32_e32 v78, 0xffff0000, v78
	v_lshlrev_b32_e32 v92, 16, v79
	v_and_b32_e32 v79, 0xffff0000, v79
	v_lshlrev_b32_e32 v93, 16, v72
	v_and_b32_e32 v72, 0xffff0000, v72
	v_lshlrev_b32_e32 v94, 16, v73
	v_and_b32_e32 v73, 0xffff0000, v73
	v_lshlrev_b32_e32 v95, 16, v74
	v_and_b32_e32 v74, 0xffff0000, v74
	v_lshlrev_b32_e32 v96, 16, v75
	v_and_b32_e32 v75, 0xffff0000, v75
	v_fmac_f32_e32 v93, v68, v83
	v_fmac_f32_e32 v95, v64, v91
	v_fmac_f32_e32 v72, v69, v76
	v_fmac_f32_e32 v74, v65, v78
	v_fmac_f32_e32 v94, v70, v90
	v_fmac_f32_e32 v96, v66, v92
	v_fmac_f32_e32 v73, v71, v77
	v_fmac_f32_e32 v75, v67, v79
	v_cvt_pk_bf16_f32 v64, v93, v72
	v_cvt_pk_bf16_f32 v65, v94, v73
	v_cvt_pk_bf16_f32 v66, v95, v74
	v_cvt_pk_bf16_f32 v67, v96, v75
	global_store_dwordx4 v[80:81], v[64:67], off offset:256
	s_waitcnt vmcnt(27)
; DI float bf_lo(unsigned u) { return __uint_as_float(u << 16); }
; DI float bf_hi(unsigned u) { return __uint_as_float(u & 0xffff0000u); }
; DI float sigmoidf_(float x) { return __builtin_amdgcn_rcpf(1.0f + __builtin_amdgcn_exp2f(-x * LOG2E)); }
; DI float rs_of(const float* ss, int row) { return 1.0f / sqrtf(ss[row] * (1.0f / DM) + EPS); }
; DI u32x4 pack8(f32x4 a, f32x4 b) { u32x4 w; w.x = cvt_pk_bf16(a[0], a[1]); w.y = cvt_pk_bf16(a[2], a[3]); w.z = cvt_pk_bf16(b[0], b[1]); w.w = cvt_pk_bf16(b[2], b[3]); return w; }
;     DI void operator()(AccRef acc, const Unit& u, int wr, int wc, int fr, int fq) const {
;         const int col0 = u.pn * 256 + wc * 32 + 8 * fq;
; #pragma unroll
;         for (int ai = 0; ai < 2; ++ai)
; #pragma unroll
;             for (int m = 0; m < 4; ++m) { const int row = u.pm * 256 + ai * 128 + wr * 64 + m * 16 + fr; const size_t off = (size_t)row * DM + col0; const float r = rs_of(ss, row);
; #pragma unroll
;                 for (int bj = 0; bj < 2; ++bj) {
;                     const u32x4 ev = *(const u32x4*)(Eb + off + bj * 128), uv = *(const u32x4*)(UPh + (size_t)row * 2304 + col0 + bj * 128);
;                     const f32x4 e0 = {bf_lo(ev.x), bf_hi(ev.x), bf_lo(ev.y), bf_hi(ev.y)}, e1 = {bf_lo(ev.z), bf_hi(ev.z), bf_lo(ev.w), bf_hi(ev.w)};
;                     f32x4 h0 = {bf_lo(uv.x), bf_hi(uv.x), bf_lo(uv.y), bf_hi(uv.y)}, h1 = {bf_lo(uv.z), bf_hi(uv.z), bf_lo(uv.w), bf_hi(uv.w)};
; #pragma unroll
;                     for (int j = 0; j < 4; ++j) { h0[j] += sigmoidf_(acc[ai][bj][m][0][j] * r) * e0[j]; h1[j] += sigmoidf_(acc[ai][bj][m][1][j] * r) * e1[j]; }
;                     *(u32x4*)(Hf + off + bj * 128) = pack8(h0, h1); } }
;     }
	v_mov_b32_e32 v74, v235
	s_nop 0
	s_waitcnt vmcnt(11)
	v_mov_b64_e32 v[64:65], v[196:197]
	v_mov_b64_e32 v[66:67], v[198:199]
	s_mov_b32 s4, 0x10000
	v_lshl_add_u64 v[238:239], v[238:239], 0, s[4:5]
	global_load_dwordx4 v[196:199], v[238:239], off
	v_mad_i64_i32 v[68:69], s[0:1], v82, s65, v[144:145]
	v_lshl_add_u64 v[72:73], v[68:69], 0, v[146:147]
	s_waitcnt vmcnt(11)
	v_mov_b64_e32 v[68:69], v[200:201]
	v_mov_b64_e32 v[70:71], v[202:203]
	s_mov_b32 s4, 0x12000
	v_lshl_add_u64 v[240:241], v[240:241], 0, s[4:5]
	global_load_dwordx4 v[200:203], v[240:241], off
	v_fmamk_f32 v74, v74, 0x3a000000, v159
	v_mul_f32_e32 v81, 0x4f800000, v74
	v_cmp_gt_f32_e32 vcc, s64, v74
	v_lshlrev_b32_e32 v75, 16, v64
	v_and_b32_e32 v64, 0xffff0000, v64
	v_cndmask_b32_e32 v74, v74, v81, vcc
	v_sqrt_f32_e32 v81, v74
	v_lshlrev_b32_e32 v76, 16, v65
	v_and_b32_e32 v65, 0xffff0000, v65
	v_lshlrev_b32_e32 v79, 16, v68
	v_add_u32_e32 v86, -1, v81
	v_add_u32_e32 v87, 1, v81
	v_fma_f32 v90, -v86, v81, v74
	v_fma_f32 v91, -v87, v81, v74
	v_cmp_ge_f32_e64 s[8:9], 0, v90
	v_and_b32_e32 v68, 0xffff0000, v68
	v_lshlrev_b32_e32 v80, 16, v69
	v_cndmask_b32_e64 v81, v81, v86, s[8:9]
	v_cmp_lt_f32_e64 s[8:9], 0, v91
	v_and_b32_e32 v69, 0xffff0000, v69
	v_lshlrev_b32_e32 v77, 16, v66
	v_cndmask_b32_e64 v81, v81, v87, s[8:9]
	v_mul_f32_e32 v86, 0x37800000, v81
	v_cndmask_b32_e32 v81, v81, v86, vcc
	v_cmp_class_f32_e32 vcc, v74, v160
	v_and_b32_e32 v66, 0xffff0000, v66
	v_lshlrev_b32_e32 v78, 16, v67
	v_cndmask_b32_e32 v74, v81, v74, vcc
	v_div_scale_f32 v81, s[0:1], v74, v74, 1.0
	v_rcp_f32_e32 v86, v81
	v_div_scale_f32 v87, vcc, 1.0, v74, 1.0
	v_and_b32_e32 v67, 0xffff0000, v67
	v_fma_f32 v90, -v81, v86, 1.0
	v_fmac_f32_e32 v86, v90, v86
	v_mul_f32_e32 v90, v87, v86
	v_fma_f32 v91, -v81, v90, v87
	v_fmac_f32_e32 v90, v91, v86
	v_fma_f32 v81, -v81, v90, v87
	v_div_fmas_f32 v81, v81, v86, v90
	v_div_fixup_f32 v74, v81, v74, 1.0
	v_mul_f32_e32 v61, v61, v74
	v_mul_f32_e32 v63, v63, v74
	v_mul_f32_e32 v60, v60, v74
	v_mul_f32_e32 v56, v56, v74
	v_mul_f32_e32 v57, v57, v74
	v_mul_f32_e32 v62, v62, v74
	v_mul_f32_e32 v58, v58, v74
	v_mul_f32_e32 v59, v59, v74
	v_mul_f32_e32 v61, 0xbfb8aa3b, v61
	v_mul_f32_e32 v63, 0xbfb8aa3b, v63
	v_mul_f32_e32 v60, 0xbfb8aa3b, v60
	v_mul_f32_e32 v56, 0xbfb8aa3b, v56
	v_mul_f32_e32 v57, 0xbfb8aa3b, v57
	v_mul_f32_e32 v62, 0xbfb8aa3b, v62
	v_mul_f32_e32 v58, 0xbfb8aa3b, v58
	v_mul_f32_e32 v59, 0xbfb8aa3b, v59
	v_exp_f32_e32 v61, v61
	v_exp_f32_e32 v63, v63
	v_exp_f32_e32 v60, v60
	v_exp_f32_e32 v56, v56
	v_exp_f32_e32 v57, v57
	v_exp_f32_e32 v62, v62
	v_exp_f32_e32 v58, v58
	v_exp_f32_e32 v59, v59
	v_add_f32_e32 v61, 1.0, v61
	v_add_f32_e32 v63, 1.0, v63
	v_add_f32_e32 v60, 1.0, v60
	v_add_f32_e32 v56, 1.0, v56
	v_add_f32_e32 v57, 1.0, v57
	v_add_f32_e32 v62, 1.0, v62
	v_add_f32_e32 v58, 1.0, v58
	v_add_f32_e32 v59, 1.0, v59
	v_rcp_f32_e32 v61, v61
	v_rcp_f32_e32 v63, v63
	v_rcp_f32_e32 v60, v60
	v_rcp_f32_e32 v56, v56
	v_rcp_f32_e32 v57, v57
	v_rcp_f32_e32 v62, v62
	v_rcp_f32_e32 v58, v58
	v_rcp_f32_e32 v59, v59
	v_lshlrev_b32_e32 v82, 16, v70
	v_and_b32_e32 v70, 0xffff0000, v70
	v_lshlrev_b32_e32 v83, 16, v71
	v_and_b32_e32 v71, 0xffff0000, v71
	v_fmac_f32_e32 v68, v61, v64
	v_fmac_f32_e32 v69, v63, v65
	v_lshl_add_u64 v[64:65], s[18:19], 0, v[84:85]
	v_fmac_f32_e32 v79, v60, v75
	v_fmac_f32_e32 v82, v56, v77
	v_fmac_f32_e32 v70, v57, v66
	v_fmac_f32_e32 v80, v62, v76
	v_fmac_f32_e32 v83, v58, v78
	v_fmac_f32_e32 v71, v59, v67
	v_cvt_pk_bf16_f32 v56, v79, v68
	v_cvt_pk_bf16_f32 v57, v80, v69
	v_cvt_pk_bf16_f32 v58, v82, v70
	v_cvt_pk_bf16_f32 v59, v83, v71
	global_store_dwordx4 v[64:65], v[56:59], off
	s_waitcnt vmcnt(11)
	v_mov_b64_e32 v[60:61], v[206:207]
	v_mov_b64_e32 v[62:63], v[208:209]
	global_load_dwordx4 v[206:209], v[238:239], off offset:256
	v_mul_f32_e32 v52, v52, v74
	s_waitcnt vmcnt(11)
	v_mov_b64_e32 v[56:57], v[210:211]
	v_mov_b64_e32 v[58:59], v[212:213]
	global_load_dwordx4 v[210:213], v[240:241], off offset:256
	v_mul_f32_e32 v48, v48, v74
	v_mul_f32_e32 v53, v53, v74
	v_mul_f32_e32 v49, v49, v74
	v_mul_f32_e32 v54, v54, v74
	v_mul_f32_e32 v50, v50, v74
	v_mul_f32_e32 v55, v55, v74
	v_mul_f32_e32 v51, v51, v74
	v_mul_f32_e32 v52, 0xbfb8aa3b, v52
	v_mul_f32_e32 v48, 0xbfb8aa3b, v48
	v_mul_f32_e32 v53, 0xbfb8aa3b, v53
	v_mul_f32_e32 v49, 0xbfb8aa3b, v49
	v_mul_f32_e32 v54, 0xbfb8aa3b, v54
	v_mul_f32_e32 v50, 0xbfb8aa3b, v50
	v_mul_f32_e32 v55, 0xbfb8aa3b, v55
	v_mul_f32_e32 v51, 0xbfb8aa3b, v51
	v_exp_f32_e32 v52, v52
	v_exp_f32_e32 v48, v48
	v_exp_f32_e32 v53, v53
	v_exp_f32_e32 v49, v49
	v_exp_f32_e32 v54, v54
	v_exp_f32_e32 v50, v50
	v_exp_f32_e32 v55, v55
	v_exp_f32_e32 v51, v51
	v_add_f32_e32 v52, 1.0, v52
	v_add_f32_e32 v48, 1.0, v48
	v_add_f32_e32 v53, 1.0, v53
	v_add_f32_e32 v49, 1.0, v49
	v_add_f32_e32 v54, 1.0, v54
	v_add_f32_e32 v50, 1.0, v50
	v_add_f32_e32 v55, 1.0, v55
	v_add_f32_e32 v51, 1.0, v51
	v_add_u32_e32 v66, 0x90, v150
	v_rcp_f32_e32 v52, v52
	v_rcp_f32_e32 v48, v48
	v_rcp_f32_e32 v53, v53
	v_rcp_f32_e32 v49, v49
	v_rcp_f32_e32 v54, v54
	v_rcp_f32_e32 v50, v50
	v_rcp_f32_e32 v55, v55
	v_rcp_f32_e32 v51, v51
	v_ashrrev_i32_e32 v67, 31, v66
	v_lshlrev_b64 v[68:69], 11, v[66:67]
	v_lshl_add_u64 v[70:71], v[66:67], 2, s[28:29]
	v_lshl_add_u64 v[68:69], v[68:69], 0, v[148:149]
	v_lshlrev_b64 v[68:69], 1, v[68:69]
	v_lshl_add_u64 v[72:73], s[14:15], 0, v[68:69]
	v_lshlrev_b32_e32 v67, 16, v60
	v_and_b32_e32 v60, 0xffff0000, v60
	v_lshlrev_b32_e32 v74, 16, v61
	v_and_b32_e32 v61, 0xffff0000, v61
	v_lshlrev_b32_e32 v75, 16, v62
	v_and_b32_e32 v62, 0xffff0000, v62
	v_lshlrev_b32_e32 v76, 16, v63
	v_and_b32_e32 v63, 0xffff0000, v63
	v_lshlrev_b32_e32 v77, 16, v56
	v_and_b32_e32 v56, 0xffff0000, v56
	v_lshlrev_b32_e32 v78, 16, v57
	v_and_b32_e32 v57, 0xffff0000, v57
	v_lshlrev_b32_e32 v79, 16, v58
	v_and_b32_e32 v58, 0xffff0000, v58
	v_lshlrev_b32_e32 v80, 16, v59
	v_and_b32_e32 v59, 0xffff0000, v59
	v_fmac_f32_e32 v77, v52, v67
	v_fmac_f32_e32 v79, v48, v75
	v_fmac_f32_e32 v56, v53, v60
	v_fmac_f32_e32 v58, v49, v62
	v_fmac_f32_e32 v78, v54, v74
	v_fmac_f32_e32 v80, v50, v76
	v_fmac_f32_e32 v57, v55, v61
	v_fmac_f32_e32 v59, v51, v63
	v_cvt_pk_bf16_f32 v48, v77, v56
	v_cvt_pk_bf16_f32 v49, v78, v57
	v_cvt_pk_bf16_f32 v50, v79, v58
	v_cvt_pk_bf16_f32 v51, v80, v59
	global_store_dwordx4 v[64:65], v[48:51], off offset:256
	s_waitcnt vmcnt(32)
; DI float bf_lo(unsigned u) { return __uint_as_float(u << 16); }
; DI float bf_hi(unsigned u) { return __uint_as_float(u & 0xffff0000u); }
; DI float sigmoidf_(float x) { return __builtin_amdgcn_rcpf(1.0f + __builtin_amdgcn_exp2f(-x * LOG2E)); }
; DI float rs_of(const float* ss, int row) { return 1.0f / sqrtf(ss[row] * (1.0f / DM) + EPS); }
; DI u32x4 pack8(f32x4 a, f32x4 b) { u32x4 w; w.x = cvt_pk_bf16(a[0], a[1]); w.y = cvt_pk_bf16(a[2], a[3]); w.z = cvt_pk_bf16(b[0], b[1]); w.w = cvt_pk_bf16(b[2], b[3]); return w; }
;     DI void operator()(AccRef acc, const Unit& u, int wr, int wc, int fr, int fq) const {
;         const int col0 = u.pn * 256 + wc * 32 + 8 * fq;
; #pragma unroll
;         for (int ai = 0; ai < 2; ++ai)
; #pragma unroll
;             for (int m = 0; m < 4; ++m) { const int row = u.pm * 256 + ai * 128 + wr * 64 + m * 16 + fr; const size_t off = (size_t)row * DM + col0; const float r = rs_of(ss, row);
; #pragma unroll
;                 for (int bj = 0; bj < 2; ++bj) {
;                     const u32x4 ev = *(const u32x4*)(Eb + off + bj * 128), uv = *(const u32x4*)(UPh + (size_t)row * 2304 + col0 + bj * 128);
;                     const f32x4 e0 = {bf_lo(ev.x), bf_hi(ev.x), bf_lo(ev.y), bf_hi(ev.y)}, e1 = {bf_lo(ev.z), bf_hi(ev.z), bf_lo(ev.w), bf_hi(ev.w)};
;                     f32x4 h0 = {bf_lo(uv.x), bf_hi(uv.x), bf_lo(uv.y), bf_hi(uv.y)}, h1 = {bf_lo(uv.z), bf_hi(uv.z), bf_lo(uv.w), bf_hi(uv.w)};
; #pragma unroll
;                     for (int j = 0; j < 4; ++j) { h0[j] += sigmoidf_(acc[ai][bj][m][0][j] * r) * e0[j]; h1[j] += sigmoidf_(acc[ai][bj][m][1][j] * r) * e1[j]; }
;                     *(u32x4*)(Hf + off + bj * 128) = pack8(h0, h1); } }
;     }
	v_mov_b32_e32 v58, v236
	s_nop 0
	s_waitcnt vmcnt(11)
	v_mov_b64_e32 v[48:49], v[214:215]
	v_mov_b64_e32 v[50:51], v[216:217]
	s_mov_b32 s4, 0x10000
	v_lshl_add_u64 v[238:239], v[238:239], 0, s[4:5]
	global_load_dwordx4 v[214:217], v[238:239], off
	v_mad_i64_i32 v[52:53], s[0:1], v66, s65, v[144:145]
	v_lshl_add_u64 v[56:57], v[52:53], 0, v[146:147]
	s_waitcnt vmcnt(11)
	v_mov_b64_e32 v[52:53], v[218:219]
	v_mov_b64_e32 v[54:55], v[220:221]
	s_mov_b32 s4, 0x12000
	v_lshl_add_u64 v[240:241], v[240:241], 0, s[4:5]
	global_load_dwordx4 v[218:221], v[240:241], off
	v_fmamk_f32 v58, v58, 0x3a000000, v159
	v_mul_f32_e32 v65, 0x4f800000, v58
	v_cmp_gt_f32_e32 vcc, s64, v58
	v_lshlrev_b32_e32 v59, 16, v48
	v_and_b32_e32 v48, 0xffff0000, v48
	v_cndmask_b32_e32 v58, v58, v65, vcc
	v_sqrt_f32_e32 v65, v58
	v_lshlrev_b32_e32 v60, 16, v49
	v_and_b32_e32 v49, 0xffff0000, v49
	v_lshlrev_b32_e32 v63, 16, v52
	v_add_u32_e32 v70, -1, v65
	v_add_u32_e32 v71, 1, v65
	v_fma_f32 v74, -v70, v65, v58
	v_fma_f32 v75, -v71, v65, v58
	v_cmp_ge_f32_e64 s[8:9], 0, v74
	v_and_b32_e32 v52, 0xffff0000, v52
	v_lshlrev_b32_e32 v64, 16, v53
	v_cndmask_b32_e64 v65, v65, v70, s[8:9]
	v_cmp_lt_f32_e64 s[8:9], 0, v75
	v_and_b32_e32 v53, 0xffff0000, v53
	v_lshlrev_b32_e32 v61, 16, v50
	v_cndmask_b32_e64 v65, v65, v71, s[8:9]
	v_mul_f32_e32 v70, 0x37800000, v65
	v_cndmask_b32_e32 v65, v65, v70, vcc
	v_cmp_class_f32_e32 vcc, v58, v160
	v_and_b32_e32 v50, 0xffff0000, v50
	v_lshlrev_b32_e32 v62, 16, v51
	v_cndmask_b32_e32 v58, v65, v58, vcc
	v_div_scale_f32 v65, s[0:1], v58, v58, 1.0
	v_rcp_f32_e32 v70, v65
	v_div_scale_f32 v71, vcc, 1.0, v58, 1.0
	v_and_b32_e32 v51, 0xffff0000, v51
	v_fma_f32 v74, -v65, v70, 1.0
	v_fmac_f32_e32 v70, v74, v70
	v_mul_f32_e32 v74, v71, v70
	v_fma_f32 v75, -v65, v74, v71
	v_fmac_f32_e32 v74, v75, v70
	v_fma_f32 v65, -v65, v74, v71
	v_div_fmas_f32 v65, v65, v70, v74
	v_div_fixup_f32 v58, v65, v58, 1.0
	v_mul_f32_e32 v45, v45, v58
	v_mul_f32_e32 v47, v47, v58
	v_mul_f32_e32 v44, v44, v58
	v_mul_f32_e32 v40, v40, v58
	v_mul_f32_e32 v41, v41, v58
	v_mul_f32_e32 v46, v46, v58
	v_mul_f32_e32 v42, v42, v58
	v_mul_f32_e32 v43, v43, v58
	v_mul_f32_e32 v45, 0xbfb8aa3b, v45
	v_mul_f32_e32 v47, 0xbfb8aa3b, v47
	v_mul_f32_e32 v44, 0xbfb8aa3b, v44
	v_mul_f32_e32 v40, 0xbfb8aa3b, v40
	v_mul_f32_e32 v41, 0xbfb8aa3b, v41
	v_mul_f32_e32 v46, 0xbfb8aa3b, v46
	v_mul_f32_e32 v42, 0xbfb8aa3b, v42
	v_mul_f32_e32 v43, 0xbfb8aa3b, v43
	v_exp_f32_e32 v45, v45
	v_exp_f32_e32 v47, v47
	v_exp_f32_e32 v44, v44
	v_exp_f32_e32 v40, v40
	v_exp_f32_e32 v41, v41
	v_exp_f32_e32 v46, v46
	v_exp_f32_e32 v42, v42
	v_exp_f32_e32 v43, v43
	v_add_f32_e32 v45, 1.0, v45
	v_add_f32_e32 v47, 1.0, v47
	v_add_f32_e32 v44, 1.0, v44
	v_add_f32_e32 v40, 1.0, v40
	v_add_f32_e32 v41, 1.0, v41
	v_add_f32_e32 v46, 1.0, v46
	v_add_f32_e32 v42, 1.0, v42
	v_add_f32_e32 v43, 1.0, v43
	v_rcp_f32_e32 v45, v45
	v_rcp_f32_e32 v47, v47
	v_rcp_f32_e32 v44, v44
	v_rcp_f32_e32 v40, v40
	v_rcp_f32_e32 v41, v41
	v_rcp_f32_e32 v46, v46
	v_rcp_f32_e32 v42, v42
	v_rcp_f32_e32 v43, v43
	v_lshlrev_b32_e32 v66, 16, v54
	v_and_b32_e32 v54, 0xffff0000, v54
	v_lshlrev_b32_e32 v67, 16, v55
	v_and_b32_e32 v55, 0xffff0000, v55
	v_fmac_f32_e32 v52, v45, v48
	v_fmac_f32_e32 v53, v47, v49
	v_lshl_add_u64 v[48:49], s[18:19], 0, v[68:69]
	v_fmac_f32_e32 v63, v44, v59
	v_fmac_f32_e32 v66, v40, v61
	v_fmac_f32_e32 v54, v41, v50
	v_fmac_f32_e32 v64, v46, v60
	v_fmac_f32_e32 v67, v42, v62
	v_fmac_f32_e32 v55, v43, v51
	v_cvt_pk_bf16_f32 v40, v63, v52
	v_cvt_pk_bf16_f32 v41, v64, v53
	v_cvt_pk_bf16_f32 v42, v66, v54
	v_cvt_pk_bf16_f32 v43, v67, v55
	global_store_dwordx4 v[48:49], v[40:43], off
	s_waitcnt vmcnt(11)
	v_mov_b64_e32 v[44:45], v[222:223]
	v_mov_b64_e32 v[46:47], v[224:225]
	global_load_dwordx4 v[222:225], v[238:239], off offset:256
	v_mul_f32_e32 v36, v36, v58
	s_waitcnt vmcnt(11)
	v_mov_b64_e32 v[40:41], v[226:227]
	v_mov_b64_e32 v[42:43], v[228:229]
	global_load_dwordx4 v[226:229], v[240:241], off offset:256
	v_mul_f32_e32 v32, v32, v58
	v_mul_f32_e32 v37, v37, v58
	v_mul_f32_e32 v33, v33, v58
	v_mul_f32_e32 v38, v38, v58
	v_mul_f32_e32 v34, v34, v58
	v_mul_f32_e32 v39, v39, v58
	v_mul_f32_e32 v35, v35, v58
	v_mul_f32_e32 v36, 0xbfb8aa3b, v36
	v_mul_f32_e32 v32, 0xbfb8aa3b, v32
	v_mul_f32_e32 v37, 0xbfb8aa3b, v37
	v_mul_f32_e32 v33, 0xbfb8aa3b, v33
	v_mul_f32_e32 v38, 0xbfb8aa3b, v38
	v_mul_f32_e32 v34, 0xbfb8aa3b, v34
	v_mul_f32_e32 v39, 0xbfb8aa3b, v39
	v_mul_f32_e32 v35, 0xbfb8aa3b, v35
	v_exp_f32_e32 v36, v36
	v_exp_f32_e32 v32, v32
	v_exp_f32_e32 v37, v37
	v_exp_f32_e32 v33, v33
	v_exp_f32_e32 v38, v38
	v_exp_f32_e32 v34, v34
	v_exp_f32_e32 v39, v39
	v_exp_f32_e32 v35, v35
	v_add_f32_e32 v36, 1.0, v36
	v_add_f32_e32 v32, 1.0, v32
	v_add_f32_e32 v37, 1.0, v37
	v_add_f32_e32 v33, 1.0, v33
	v_add_f32_e32 v38, 1.0, v38
	v_add_f32_e32 v34, 1.0, v34
	v_add_f32_e32 v39, 1.0, v39
	v_add_f32_e32 v35, 1.0, v35
	v_add_u32_e32 v50, 0xa0, v150
	v_rcp_f32_e32 v36, v36
	v_rcp_f32_e32 v32, v32
	v_rcp_f32_e32 v37, v37
	v_rcp_f32_e32 v33, v33
	v_rcp_f32_e32 v38, v38
	v_rcp_f32_e32 v34, v34
	v_rcp_f32_e32 v39, v39
	v_rcp_f32_e32 v35, v35
	v_ashrrev_i32_e32 v51, 31, v50
	v_lshlrev_b64 v[52:53], 11, v[50:51]
	v_lshl_add_u64 v[54:55], v[50:51], 2, s[28:29]
	v_lshl_add_u64 v[52:53], v[52:53], 0, v[148:149]
	v_lshlrev_b64 v[52:53], 1, v[52:53]
	v_lshl_add_u64 v[56:57], s[14:15], 0, v[52:53]
	v_lshlrev_b32_e32 v51, 16, v44
	v_and_b32_e32 v44, 0xffff0000, v44
	v_lshlrev_b32_e32 v58, 16, v45
	v_and_b32_e32 v45, 0xffff0000, v45
	v_lshlrev_b32_e32 v59, 16, v46
	v_and_b32_e32 v46, 0xffff0000, v46
	v_lshlrev_b32_e32 v60, 16, v47
	v_and_b32_e32 v47, 0xffff0000, v47
	v_lshlrev_b32_e32 v61, 16, v40
	v_and_b32_e32 v40, 0xffff0000, v40
	v_lshlrev_b32_e32 v62, 16, v41
	v_and_b32_e32 v41, 0xffff0000, v41
	v_lshlrev_b32_e32 v63, 16, v42
	v_and_b32_e32 v42, 0xffff0000, v42
	v_lshlrev_b32_e32 v64, 16, v43
	v_and_b32_e32 v43, 0xffff0000, v43
	v_fmac_f32_e32 v61, v36, v51
	v_fmac_f32_e32 v63, v32, v59
	v_fmac_f32_e32 v40, v37, v44
	v_fmac_f32_e32 v42, v33, v46
	v_fmac_f32_e32 v62, v38, v58
	v_fmac_f32_e32 v64, v34, v60
	v_fmac_f32_e32 v41, v39, v45
	v_fmac_f32_e32 v43, v35, v47
	v_cvt_pk_bf16_f32 v32, v61, v40
	v_cvt_pk_bf16_f32 v33, v62, v41
	v_cvt_pk_bf16_f32 v34, v63, v42
	v_cvt_pk_bf16_f32 v35, v64, v43
	global_store_dwordx4 v[48:49], v[32:35], off offset:256
	s_waitcnt vmcnt(37)
; DI float bf_lo(unsigned u) { return __uint_as_float(u << 16); }
; DI float bf_hi(unsigned u) { return __uint_as_float(u & 0xffff0000u); }
; DI float sigmoidf_(float x) { return __builtin_amdgcn_rcpf(1.0f + __builtin_amdgcn_exp2f(-x * LOG2E)); }
; DI float rs_of(const float* ss, int row) { return 1.0f / sqrtf(ss[row] * (1.0f / DM) + EPS); }
; DI u32x4 pack8(f32x4 a, f32x4 b) { u32x4 w; w.x = cvt_pk_bf16(a[0], a[1]); w.y = cvt_pk_bf16(a[2], a[3]); w.z = cvt_pk_bf16(b[0], b[1]); w.w = cvt_pk_bf16(b[2], b[3]); return w; }
;     DI void operator()(AccRef acc, const Unit& u, int wr, int wc, int fr, int fq) const {
;         const int col0 = u.pn * 256 + wc * 32 + 8 * fq;
; #pragma unroll
;         for (int ai = 0; ai < 2; ++ai)
; #pragma unroll
;             for (int m = 0; m < 4; ++m) { const int row = u.pm * 256 + ai * 128 + wr * 64 + m * 16 + fr; const size_t off = (size_t)row * DM + col0; const float r = rs_of(ss, row);
; #pragma unroll
;                 for (int bj = 0; bj < 2; ++bj) {
;                     const u32x4 ev = *(const u32x4*)(Eb + off + bj * 128), uv = *(const u32x4*)(UPh + (size_t)row * 2304 + col0 + bj * 128);
;                     const f32x4 e0 = {bf_lo(ev.x), bf_hi(ev.x), bf_lo(ev.y), bf_hi(ev.y)}, e1 = {bf_lo(ev.z), bf_hi(ev.z), bf_lo(ev.w), bf_hi(ev.w)};
;                     f32x4 h0 = {bf_lo(uv.x), bf_hi(uv.x), bf_lo(uv.y), bf_hi(uv.y)}, h1 = {bf_lo(uv.z), bf_hi(uv.z), bf_lo(uv.w), bf_hi(uv.w)};
; #pragma unroll
;                     for (int j = 0; j < 4; ++j) { h0[j] += sigmoidf_(acc[ai][bj][m][0][j] * r) * e0[j]; h1[j] += sigmoidf_(acc[ai][bj][m][1][j] * r) * e1[j]; }
;                     *(u32x4*)(Hf + off + bj * 128) = pack8(h0, h1); } }
;     }
	v_mov_b32_e32 v42, v237
	s_nop 0
	s_waitcnt vmcnt(11)
	v_mov_b64_e32 v[32:33], v[196:197]
	v_mov_b64_e32 v[34:35], v[198:199]
	v_mad_i64_i32 v[36:37], s[0:1], v50, s65, v[144:145]
	v_lshl_add_u64 v[40:41], v[36:37], 0, v[146:147]
	s_waitcnt vmcnt(10)
	v_mov_b64_e32 v[36:37], v[200:201]
	v_mov_b64_e32 v[38:39], v[202:203]
	v_fmamk_f32 v42, v42, 0x3a000000, v159
	v_mul_f32_e32 v49, 0x4f800000, v42
	v_cmp_gt_f32_e32 vcc, s64, v42
	v_lshlrev_b32_e32 v43, 16, v32
	v_and_b32_e32 v32, 0xffff0000, v32
	v_cndmask_b32_e32 v42, v42, v49, vcc
	v_sqrt_f32_e32 v49, v42
	v_lshlrev_b32_e32 v44, 16, v33
	v_and_b32_e32 v33, 0xffff0000, v33
	v_lshlrev_b32_e32 v47, 16, v36
	v_add_u32_e32 v54, -1, v49
	v_add_u32_e32 v55, 1, v49
	v_fma_f32 v58, -v54, v49, v42
	v_fma_f32 v59, -v55, v49, v42
	v_cmp_ge_f32_e64 s[8:9], 0, v58
	v_and_b32_e32 v36, 0xffff0000, v36
	v_lshlrev_b32_e32 v48, 16, v37
	v_cndmask_b32_e64 v49, v49, v54, s[8:9]
	v_cmp_lt_f32_e64 s[8:9], 0, v59
	v_and_b32_e32 v37, 0xffff0000, v37
	v_lshlrev_b32_e32 v45, 16, v34
	v_cndmask_b32_e64 v49, v49, v55, s[8:9]
	v_mul_f32_e32 v54, 0x37800000, v49
	v_cndmask_b32_e32 v49, v49, v54, vcc
	v_cmp_class_f32_e32 vcc, v42, v160
	v_and_b32_e32 v34, 0xffff0000, v34
	v_lshlrev_b32_e32 v46, 16, v35
	v_cndmask_b32_e32 v42, v49, v42, vcc
	v_div_scale_f32 v49, s[0:1], v42, v42, 1.0
	v_rcp_f32_e32 v54, v49
	v_div_scale_f32 v55, vcc, 1.0, v42, 1.0
	v_and_b32_e32 v35, 0xffff0000, v35
	v_fma_f32 v58, -v49, v54, 1.0
	v_fmac_f32_e32 v54, v58, v54
	v_mul_f32_e32 v58, v55, v54
	v_fma_f32 v59, -v49, v58, v55
	v_fmac_f32_e32 v58, v59, v54
	v_fma_f32 v49, -v49, v58, v55
	v_div_fmas_f32 v49, v49, v54, v58
	v_div_fixup_f32 v42, v49, v42, 1.0
	v_mul_f32_e32 v29, v29, v42
	v_mul_f32_e32 v31, v31, v42
	v_mul_f32_e32 v28, v28, v42
	v_mul_f32_e32 v24, v24, v42
	v_mul_f32_e32 v25, v25, v42
	v_mul_f32_e32 v30, v30, v42
	v_mul_f32_e32 v26, v26, v42
	v_mul_f32_e32 v27, v27, v42
	v_mul_f32_e32 v29, 0xbfb8aa3b, v29
	v_mul_f32_e32 v31, 0xbfb8aa3b, v31
	v_mul_f32_e32 v28, 0xbfb8aa3b, v28
	v_mul_f32_e32 v24, 0xbfb8aa3b, v24
	v_mul_f32_e32 v25, 0xbfb8aa3b, v25
	v_mul_f32_e32 v30, 0xbfb8aa3b, v30
	v_mul_f32_e32 v26, 0xbfb8aa3b, v26
	v_mul_f32_e32 v27, 0xbfb8aa3b, v27
	v_exp_f32_e32 v29, v29
	v_exp_f32_e32 v31, v31
	v_exp_f32_e32 v28, v28
	v_exp_f32_e32 v24, v24
	v_exp_f32_e32 v25, v25
	v_exp_f32_e32 v30, v30
	v_exp_f32_e32 v26, v26
	v_exp_f32_e32 v27, v27
	v_add_f32_e32 v29, 1.0, v29
	v_add_f32_e32 v31, 1.0, v31
	v_add_f32_e32 v28, 1.0, v28
	v_add_f32_e32 v24, 1.0, v24
	v_add_f32_e32 v25, 1.0, v25
	v_add_f32_e32 v30, 1.0, v30
	v_add_f32_e32 v26, 1.0, v26
	v_add_f32_e32 v27, 1.0, v27
	v_rcp_f32_e32 v29, v29
	v_rcp_f32_e32 v31, v31
	v_rcp_f32_e32 v28, v28
	v_rcp_f32_e32 v24, v24
	v_rcp_f32_e32 v25, v25
	v_rcp_f32_e32 v30, v30
	v_rcp_f32_e32 v26, v26
	v_rcp_f32_e32 v27, v27
	v_lshlrev_b32_e32 v50, 16, v38
	v_and_b32_e32 v38, 0xffff0000, v38
	v_lshlrev_b32_e32 v51, 16, v39
	v_and_b32_e32 v39, 0xffff0000, v39
	v_fmac_f32_e32 v36, v29, v32
	v_fmac_f32_e32 v37, v31, v33
	v_lshl_add_u64 v[32:33], s[18:19], 0, v[52:53]
	v_fmac_f32_e32 v47, v28, v43
	v_fmac_f32_e32 v50, v24, v45
	v_fmac_f32_e32 v38, v25, v34
	v_fmac_f32_e32 v48, v30, v44
	v_fmac_f32_e32 v51, v26, v46
	v_fmac_f32_e32 v39, v27, v35
	v_cvt_pk_bf16_f32 v24, v47, v36
	v_cvt_pk_bf16_f32 v25, v48, v37
	v_cvt_pk_bf16_f32 v26, v50, v38
	v_cvt_pk_bf16_f32 v27, v51, v39
	global_store_dwordx4 v[32:33], v[24:27], off
	s_waitcnt vmcnt(9)
	v_mov_b64_e32 v[28:29], v[206:207]
	v_mov_b64_e32 v[30:31], v[208:209]
	v_mul_f32_e32 v20, v20, v42
	s_waitcnt vmcnt(8)
	v_mov_b64_e32 v[24:25], v[210:211]
	v_mov_b64_e32 v[26:27], v[212:213]
	v_mul_f32_e32 v16, v16, v42
	v_mul_f32_e32 v21, v21, v42
	v_mul_f32_e32 v17, v17, v42
	v_mul_f32_e32 v22, v22, v42
	v_mul_f32_e32 v18, v18, v42
	v_mul_f32_e32 v23, v23, v42
	v_mul_f32_e32 v19, v19, v42
	v_mul_f32_e32 v20, 0xbfb8aa3b, v20
	v_mul_f32_e32 v16, 0xbfb8aa3b, v16
	v_mul_f32_e32 v21, 0xbfb8aa3b, v21
	v_mul_f32_e32 v17, 0xbfb8aa3b, v17
	v_mul_f32_e32 v22, 0xbfb8aa3b, v22
	v_mul_f32_e32 v18, 0xbfb8aa3b, v18
	v_mul_f32_e32 v23, 0xbfb8aa3b, v23
	v_mul_f32_e32 v19, 0xbfb8aa3b, v19
	v_exp_f32_e32 v20, v20
	v_exp_f32_e32 v16, v16
	v_exp_f32_e32 v21, v21
	v_exp_f32_e32 v17, v17
	v_exp_f32_e32 v22, v22
	v_exp_f32_e32 v18, v18
	v_exp_f32_e32 v23, v23
	v_exp_f32_e32 v19, v19
	v_add_f32_e32 v20, 1.0, v20
	v_add_f32_e32 v16, 1.0, v16
	v_add_f32_e32 v21, 1.0, v21
	v_add_f32_e32 v17, 1.0, v17
	v_add_f32_e32 v22, 1.0, v22
	v_add_f32_e32 v18, 1.0, v18
	v_add_f32_e32 v23, 1.0, v23
	v_add_f32_e32 v19, 1.0, v19
	v_add_u32_e32 v34, 0xb0, v150
	v_rcp_f32_e32 v20, v20
	v_rcp_f32_e32 v16, v16
	v_rcp_f32_e32 v21, v21
	v_rcp_f32_e32 v17, v17
	v_rcp_f32_e32 v22, v22
	v_rcp_f32_e32 v18, v18
	v_rcp_f32_e32 v23, v23
	v_rcp_f32_e32 v19, v19
	v_ashrrev_i32_e32 v35, 31, v34
	v_lshlrev_b64 v[36:37], 11, v[34:35]
	v_lshl_add_u64 v[38:39], v[34:35], 2, s[28:29]
	v_lshl_add_u64 v[36:37], v[36:37], 0, v[148:149]
	v_lshlrev_b64 v[36:37], 1, v[36:37]
	v_lshlrev_b32_e32 v35, 16, v28
	v_and_b32_e32 v28, 0xffff0000, v28
	v_lshlrev_b32_e32 v42, 16, v29
	v_and_b32_e32 v29, 0xffff0000, v29
	v_lshlrev_b32_e32 v43, 16, v30
	v_and_b32_e32 v30, 0xffff0000, v30
	v_lshlrev_b32_e32 v44, 16, v31
	v_and_b32_e32 v31, 0xffff0000, v31
	v_lshlrev_b32_e32 v45, 16, v24
	v_and_b32_e32 v24, 0xffff0000, v24
	v_lshlrev_b32_e32 v46, 16, v25
	v_and_b32_e32 v25, 0xffff0000, v25
	v_lshlrev_b32_e32 v47, 16, v26
	v_and_b32_e32 v26, 0xffff0000, v26
	v_lshlrev_b32_e32 v48, 16, v27
	v_and_b32_e32 v27, 0xffff0000, v27
	v_fmac_f32_e32 v45, v20, v35
	v_fmac_f32_e32 v47, v16, v43
	v_fmac_f32_e32 v24, v21, v28
	v_fmac_f32_e32 v26, v17, v30
	v_fmac_f32_e32 v46, v22, v42
	v_fmac_f32_e32 v48, v18, v44
	v_fmac_f32_e32 v25, v23, v29
	v_fmac_f32_e32 v27, v19, v31
	v_cvt_pk_bf16_f32 v16, v45, v24
	v_cvt_pk_bf16_f32 v17, v46, v25
	v_cvt_pk_bf16_f32 v18, v47, v26
	v_cvt_pk_bf16_f32 v19, v48, v27
	global_store_dwordx4 v[32:33], v[16:19], off offset:256
	s_waitcnt vmcnt(38)
; DI float bf_lo(unsigned u) { return __uint_as_float(u << 16); }
; DI float bf_hi(unsigned u) { return __uint_as_float(u & 0xffff0000u); }
; DI float sigmoidf_(float x) { return __builtin_amdgcn_rcpf(1.0f + __builtin_amdgcn_exp2f(-x * LOG2E)); }
; DI float rs_of(const float* ss, int row) { return 1.0f / sqrtf(ss[row] * (1.0f / DM) + EPS); }
; DI u32x4 pack8(f32x4 a, f32x4 b) { u32x4 w; w.x = cvt_pk_bf16(a[0], a[1]); w.y = cvt_pk_bf16(a[2], a[3]); w.z = cvt_pk_bf16(b[0], b[1]); w.w = cvt_pk_bf16(b[2], b[3]); return w; }
;     DI void operator()(AccRef acc, const Unit& u, int wr, int wc, int fr, int fq) const {
;         const int col0 = u.pn * 256 + wc * 32 + 8 * fq;
; #pragma unroll
;         for (int ai = 0; ai < 2; ++ai)
; #pragma unroll
;             for (int m = 0; m < 4; ++m) { const int row = u.pm * 256 + ai * 128 + wr * 64 + m * 16 + fr; const size_t off = (size_t)row * DM + col0; const float r = rs_of(ss, row);
; #pragma unroll
;                 for (int bj = 0; bj < 2; ++bj) {
;                     const u32x4 ev = *(const u32x4*)(Eb + off + bj * 128), uv = *(const u32x4*)(UPh + (size_t)row * 2304 + col0 + bj * 128);
;                     const f32x4 e0 = {bf_lo(ev.x), bf_hi(ev.x), bf_lo(ev.y), bf_hi(ev.y)}, e1 = {bf_lo(ev.z), bf_hi(ev.z), bf_lo(ev.w), bf_hi(ev.w)};
;                     f32x4 h0 = {bf_lo(uv.x), bf_hi(uv.x), bf_lo(uv.y), bf_hi(uv.y)}, h1 = {bf_lo(uv.z), bf_hi(uv.z), bf_lo(uv.w), bf_hi(uv.w)};
; #pragma unroll
;                     for (int j = 0; j < 4; ++j) { h0[j] += sigmoidf_(acc[ai][bj][m][0][j] * r) * e0[j]; h1[j] += sigmoidf_(acc[ai][bj][m][1][j] * r) * e1[j]; }
;                     *(u32x4*)(Hf + off + bj * 128) = pack8(h0, h1); } }
;     }
	v_mov_b32_e32 v26, v230
	s_nop 0
	s_waitcnt vmcnt(7)
	v_mov_b64_e32 v[16:17], v[214:215]
	v_mov_b64_e32 v[18:19], v[216:217]
	v_mad_i64_i32 v[20:21], s[0:1], v34, s65, v[144:145]
	v_lshl_add_u64 v[24:25], v[20:21], 0, v[146:147]
	s_waitcnt vmcnt(6)
	v_mov_b64_e32 v[20:21], v[218:219]
	v_mov_b64_e32 v[22:23], v[220:221]
	v_fmamk_f32 v26, v26, 0x3a000000, v159
	v_mul_f32_e32 v33, 0x4f800000, v26
	v_cmp_gt_f32_e32 vcc, s64, v26
	v_lshlrev_b32_e32 v27, 16, v16
	v_and_b32_e32 v16, 0xffff0000, v16
	v_cndmask_b32_e32 v26, v26, v33, vcc
	v_sqrt_f32_e32 v33, v26
	v_lshlrev_b32_e32 v28, 16, v17
	v_and_b32_e32 v17, 0xffff0000, v17
	v_lshlrev_b32_e32 v31, 16, v20
	v_add_u32_e32 v38, -1, v33
	v_add_u32_e32 v39, 1, v33
	v_fma_f32 v42, -v38, v33, v26
	v_fma_f32 v43, -v39, v33, v26
	v_cmp_ge_f32_e64 s[8:9], 0, v42
	v_and_b32_e32 v20, 0xffff0000, v20
	v_lshlrev_b32_e32 v32, 16, v21
	v_cndmask_b32_e64 v33, v33, v38, s[8:9]
	v_cmp_lt_f32_e64 s[8:9], 0, v43
	v_and_b32_e32 v21, 0xffff0000, v21
	v_lshlrev_b32_e32 v29, 16, v18
	v_cndmask_b32_e64 v33, v33, v39, s[8:9]
	v_mul_f32_e32 v38, 0x37800000, v33
	v_cndmask_b32_e32 v33, v33, v38, vcc
	v_cmp_class_f32_e32 vcc, v26, v160
	v_and_b32_e32 v18, 0xffff0000, v18
	v_lshlrev_b32_e32 v30, 16, v19
	v_cndmask_b32_e32 v26, v33, v26, vcc
	v_div_scale_f32 v33, s[0:1], v26, v26, 1.0
	v_rcp_f32_e32 v38, v33
	v_div_scale_f32 v39, vcc, 1.0, v26, 1.0
	v_and_b32_e32 v19, 0xffff0000, v19
	v_fma_f32 v42, -v33, v38, 1.0
	v_fmac_f32_e32 v38, v42, v38
	v_mul_f32_e32 v42, v39, v38
	v_fma_f32 v43, -v33, v42, v39
	v_fmac_f32_e32 v42, v43, v38
	v_fma_f32 v33, -v33, v42, v39
	v_div_fmas_f32 v33, v33, v38, v42
	v_div_fixup_f32 v26, v33, v26, 1.0
	v_mul_f32_e32 v13, v13, v26
	v_mul_f32_e32 v15, v15, v26
	v_mul_f32_e32 v12, v12, v26
	v_mul_f32_e32 v8, v8, v26
	v_mul_f32_e32 v9, v9, v26
	v_mul_f32_e32 v14, v14, v26
	v_mul_f32_e32 v10, v10, v26
	v_mul_f32_e32 v11, v11, v26
	v_mul_f32_e32 v13, 0xbfb8aa3b, v13
	v_mul_f32_e32 v15, 0xbfb8aa3b, v15
	v_mul_f32_e32 v12, 0xbfb8aa3b, v12
	v_mul_f32_e32 v8, 0xbfb8aa3b, v8
	v_mul_f32_e32 v9, 0xbfb8aa3b, v9
	v_mul_f32_e32 v14, 0xbfb8aa3b, v14
	v_mul_f32_e32 v10, 0xbfb8aa3b, v10
	v_mul_f32_e32 v11, 0xbfb8aa3b, v11
	v_exp_f32_e32 v13, v13
	v_exp_f32_e32 v15, v15
	v_exp_f32_e32 v12, v12
	v_exp_f32_e32 v8, v8
	v_exp_f32_e32 v9, v9
	v_exp_f32_e32 v14, v14
	v_exp_f32_e32 v10, v10
	v_exp_f32_e32 v11, v11
	v_add_f32_e32 v13, 1.0, v13
	v_add_f32_e32 v15, 1.0, v15
	v_add_f32_e32 v12, 1.0, v12
	v_add_f32_e32 v8, 1.0, v8
	v_add_f32_e32 v9, 1.0, v9
	v_add_f32_e32 v14, 1.0, v14
	v_add_f32_e32 v10, 1.0, v10
	v_add_f32_e32 v11, 1.0, v11
	v_rcp_f32_e32 v13, v13
	v_rcp_f32_e32 v15, v15
	v_rcp_f32_e32 v12, v12
	v_rcp_f32_e32 v8, v8
	v_rcp_f32_e32 v9, v9
	v_rcp_f32_e32 v14, v14
	v_rcp_f32_e32 v10, v10
	v_rcp_f32_e32 v11, v11
	v_lshlrev_b32_e32 v34, 16, v22
	v_and_b32_e32 v22, 0xffff0000, v22
	v_lshlrev_b32_e32 v35, 16, v23
	v_and_b32_e32 v23, 0xffff0000, v23
	v_fmac_f32_e32 v20, v13, v16
	v_fmac_f32_e32 v21, v15, v17
	v_lshl_add_u64 v[16:17], s[18:19], 0, v[36:37]
	v_fmac_f32_e32 v31, v12, v27
	v_fmac_f32_e32 v34, v8, v29
	v_fmac_f32_e32 v22, v9, v18
	v_fmac_f32_e32 v32, v14, v28
	v_fmac_f32_e32 v35, v10, v30
	v_fmac_f32_e32 v23, v11, v19
	v_cvt_pk_bf16_f32 v8, v31, v20
	v_cvt_pk_bf16_f32 v9, v32, v21
	v_cvt_pk_bf16_f32 v10, v34, v22
	v_cvt_pk_bf16_f32 v11, v35, v23
	global_store_dwordx4 v[16:17], v[8:11], off
	s_waitcnt vmcnt(5)
	v_mov_b64_e32 v[12:13], v[222:223]
	v_mov_b64_e32 v[14:15], v[224:225]
	v_mul_f32_e32 v4, v4, v26
	s_waitcnt vmcnt(4)
	v_mov_b64_e32 v[8:9], v[226:227]
	v_mov_b64_e32 v[10:11], v[228:229]
	v_mul_f32_e32 v0, v0, v26
	v_mul_f32_e32 v5, v5, v26
	v_mul_f32_e32 v1, v1, v26
	v_mul_f32_e32 v6, v6, v26
	v_mul_f32_e32 v2, v2, v26
	v_mul_f32_e32 v7, v7, v26
	v_mul_f32_e32 v3, v3, v26
	v_mul_f32_e32 v4, 0xbfb8aa3b, v4
	v_mul_f32_e32 v0, 0xbfb8aa3b, v0
	v_mul_f32_e32 v5, 0xbfb8aa3b, v5
	v_mul_f32_e32 v1, 0xbfb8aa3b, v1
	v_mul_f32_e32 v6, 0xbfb8aa3b, v6
	v_mul_f32_e32 v2, 0xbfb8aa3b, v2
	v_mul_f32_e32 v7, 0xbfb8aa3b, v7
	v_mul_f32_e32 v3, 0xbfb8aa3b, v3
	v_exp_f32_e32 v4, v4
	v_exp_f32_e32 v0, v0
	v_exp_f32_e32 v5, v5
	v_exp_f32_e32 v1, v1
	v_exp_f32_e32 v6, v6
	v_exp_f32_e32 v2, v2
	v_exp_f32_e32 v7, v7
	v_exp_f32_e32 v3, v3
	v_add_f32_e32 v4, 1.0, v4
	v_add_f32_e32 v0, 1.0, v0
	v_add_f32_e32 v5, 1.0, v5
	v_add_f32_e32 v1, 1.0, v1
	v_add_f32_e32 v6, 1.0, v6
	v_add_f32_e32 v2, 1.0, v2
	v_add_f32_e32 v7, 1.0, v7
	v_add_f32_e32 v3, 1.0, v3
	v_rcp_f32_e32 v4, v4
	v_rcp_f32_e32 v0, v0
	v_rcp_f32_e32 v5, v5
	v_rcp_f32_e32 v1, v1
	v_rcp_f32_e32 v6, v6
	v_rcp_f32_e32 v2, v2
	v_rcp_f32_e32 v7, v7
	v_rcp_f32_e32 v3, v3
	s_and_b64 vcc, exec, s[6:7]
	s_mov_b32 s1, s66
	s_mov_b32 s0, s67
	v_lshlrev_b32_e32 v18, 16, v12
	v_and_b32_e32 v12, 0xffff0000, v12
	v_lshlrev_b32_e32 v19, 16, v13
	v_and_b32_e32 v13, 0xffff0000, v13
	v_lshlrev_b32_e32 v20, 16, v14
	v_and_b32_e32 v14, 0xffff0000, v14
	v_lshlrev_b32_e32 v21, 16, v15
	v_and_b32_e32 v15, 0xffff0000, v15
	v_lshlrev_b32_e32 v22, 16, v8
	v_and_b32_e32 v8, 0xffff0000, v8
	v_lshlrev_b32_e32 v23, 16, v9
	v_and_b32_e32 v9, 0xffff0000, v9
	v_lshlrev_b32_e32 v24, 16, v10
	v_and_b32_e32 v10, 0xffff0000, v10
	v_lshlrev_b32_e32 v25, 16, v11
	v_and_b32_e32 v11, 0xffff0000, v11
	v_fmac_f32_e32 v22, v4, v18
	v_fmac_f32_e32 v24, v0, v20
	v_fmac_f32_e32 v8, v5, v12
	v_fmac_f32_e32 v10, v1, v14
	v_fmac_f32_e32 v23, v6, v19
	v_fmac_f32_e32 v25, v2, v21
	v_fmac_f32_e32 v9, v7, v13
	v_fmac_f32_e32 v11, v3, v15
	v_cvt_pk_bf16_f32 v0, v22, v8
	v_cvt_pk_bf16_f32 v1, v23, v9
	v_cvt_pk_bf16_f32 v2, v24, v10
	v_cvt_pk_bf16_f32 v3, v25, v11
	global_store_dwordx4 v[16:17], v[0:3], off offset:256
	s_cbranch_vccnz .LBB0_1923

; #define PG8_STAGE(bufoff, gbase, voff) do { _Pragma("unroll") for (int _i = 0; _i < 2; ++_i) \
;         __builtin_amdgcn_global_load_lds((const unsigned*)((const char*)(gbase) + (voff)[_i]), (LAS unsigned*)(lds + (bufoff) + ldsw + _i * 8192), 16, 0, 0); } while (0)
; #define PG8_LDA(dst, b, h) do { _Pragma("unroll") for (int m = 0; m < 4; ++m) _Pragma("unroll") for (int k = 0; k < 2; ++k) dst[m][k] = *(const LAS bf16x8*)(lds + PG8_SA(b, h) + aoff + m * 2048 + k * 1024); } while (0)
; #define PG8_LDB(dst, b, h) do { _Pragma("unroll") for (int n = 0; n < 2; ++n) _Pragma("unroll") for (int k = 0; k < 2; ++k) dst[n][k] = *(const LAS bf16x8*)(lds + PG8_SB(b, h) + boff + n * 2048 + k * 1024); } while (0)
; #define PG8_MMA(ai, bj, At, Bt) do { __builtin_amdgcn_s_setprio(1); _Pragma("unroll") for (int m = 0; m < 4; ++m) _Pragma("unroll") for (int n = 0; n < 2; ++n) _Pragma("unroll") for (int k = 0; k < 2; ++k) \
;         acc[ai][bj][m][n] = __builtin_amdgcn_mfma_f32_16x16x32_bf16(Bt[n][k], At[m][k], acc[ai][bj][m][n], 0, 0, 0); __builtin_amdgcn_s_setprio(0); } while (0)
; #define PG8_WAIT_L(n) asm volatile("s_waitcnt lgkmcnt(" #n ")" ::: "memory")
; #define PG8_BAR __builtin_amdgcn_s_barrier()
; template <class Epi, class Sched>
; DI void gemm_phase(LAS unsigned char* lds, const Gemm g, const Sched& S, const Epi& E) {
;     ...
;         for (int t = 0; t < nt; t += 2) {
;             if constexpr (Epi::HAS_MID) { if (t == E.mid_t(nt)) { int fr3 = fr, fq3 = fq; asm volatile("" : "+v"(fr3), "+v"(fq3)); E.mid(acc, cur, wr, wc, fr3, fq3); } }
;             const bool last = (t == nt - 2);
;             const char* a1 = cA + (size_t)(t + 1) * kstep;
;             const char* a2 = last ? nA : cA + (size_t)(t + 2) * kstep; const char* b2 = last ? nB : cB + (size_t)(t + 2) * kstep;
;             const char* a3 = a2 + kstep; const char* b3 = b2 + kstep;
;             PG8_LDB(B0, 0, 0); PG8_SCHED; PG8_LDA(At, 0, 0); PG8_STAGE(PG8_SA(1, 1), a1 + hstep, voffA);
;             PG8_WAIT_L(8); PG8_BAR; PG8_WAIT_L(0); PG8_MMA(0, 0, At, B0); PG8_BAR; PG8_SCHED;
;             PG8_LDB(B1, 0, 1); PG8_STAGE(PG8_SB(0, 0), b2, voffB);
;             PG8_BAR; PG8_WAIT_L(0); PG8_MMA(0, 1, At, B1); PG8_BAR;
;             PG8_LDA(At, 0, 1); PG8_STAGE(PG8_SA(0, 0), a2, voffA);
;             PG8_BAR; PG8_WAIT_L(0); PG8_MMA(1, 0, At, B0); PG8_BAR; PG8_SCHED;
.LBB0_1920:
	v_add_u32_e32 v161, s62, v157
	s_add_u32 s0, s38, s8
	ds_read_b128 v[148:151], v161
	ds_read_b128 v[162:165], v161 offset:1024
	ds_read_b128 v[166:169], v161 offset:2048
	ds_read_b128 v[170:173], v161 offset:3072
	s_addc_u32 s1, s39, s9
	s_add_u32 s0, s0, 0x100
	s_addc_u32 s1, s1, 0
	s_add_u32 s4, s68, s8
	s_addc_u32 s5, s69, s9
	s_cmpk_eq_i32 s8, 0x1100
	s_cselect_b32 s43, s37, s1
	s_cselect_b32 s42, s36, s0
	s_cselect_b32 s41, s11, s5
	s_cselect_b32 s40, s10, s4
	v_lshl_add_u64 v[182:183], v[144:145], 0, s[8:9]
	s_add_i32 m0, s53, 0xc000
	ds_read_b128 v[174:177], v158
	ds_read_b128 v[178:181], v158 offset:1024
	ds_read_b128 v[188:191], v158 offset:2048
	ds_read_b128 v[196:199], v158 offset:3072
	ds_read_b128 v[200:203], v158 offset:4096
	ds_read_b128 v[206:209], v158 offset:5120
	ds_read_b128 v[210:213], v158 offset:6144
	ds_read_b128 v[214:217], v158 offset:7168
	global_load_lds_dwordx4 v[182:183], off
	v_lshl_add_u64 v[182:183], v[146:147], 0, s[8:9]
	s_add_i32 m0, s53, 0xe000
	s_nop 0
	global_load_lds_dwordx4 v[182:183], off
	s_waitcnt lgkmcnt(8)
	s_barrier
	s_waitcnt lgkmcnt(0)
	s_setprio 1
	s_waitcnt lgkmcnt(0)
	v_mfma_f32_16x16x32_bf16 v[124:127], v[148:151], v[174:177], v[124:127]
	v_mfma_f32_16x16x32_bf16 v[120:123], v[166:169], v[174:177], v[120:123]
	v_mfma_f32_16x16x32_bf16 v[108:111], v[148:151], v[188:191], v[108:111]
	v_mfma_f32_16x16x32_bf16 v[104:107], v[166:169], v[188:191], v[104:107]
	v_mfma_f32_16x16x32_bf16 v[92:95], v[148:151], v[200:203], v[92:95]
	v_mfma_f32_16x16x32_bf16 v[88:91], v[166:169], v[200:203], v[88:91]
	v_mfma_f32_16x16x32_bf16 v[76:79], v[148:151], v[210:213], v[76:79]
	v_mfma_f32_16x16x32_bf16 v[72:75], v[166:169], v[210:213], v[72:75]
	v_mfma_f32_16x16x32_bf16 v[124:127], v[162:165], v[178:181], v[124:127]
	v_mfma_f32_16x16x32_bf16 v[120:123], v[170:173], v[178:181], v[120:123]
	v_mfma_f32_16x16x32_bf16 v[108:111], v[162:165], v[196:199], v[108:111]
	v_mfma_f32_16x16x32_bf16 v[104:107], v[170:173], v[196:199], v[104:107]
	v_mfma_f32_16x16x32_bf16 v[92:95], v[162:165], v[206:209], v[92:95]
	v_mfma_f32_16x16x32_bf16 v[88:91], v[170:173], v[206:209], v[88:91]
	v_mfma_f32_16x16x32_bf16 v[76:79], v[162:165], v[214:217], v[76:79]
	v_mfma_f32_16x16x32_bf16 v[72:75], v[170:173], v[214:217], v[72:75]
	s_setprio 0
	s_barrier
	s_add_i32 s0, s62, s52
	v_add_u32_e32 v161, s63, v157
	s_mov_b32 m0, s0
	ds_read_b128 v[218:221], v161
	ds_read_b128 v[222:225], v161 offset:1024
	ds_read_b128 v[226:229], v161 offset:2048
	ds_read_b128 v[230:233], v161 offset:3072
	global_load_lds_dwordx4 v130, s[40:41]
	s_add_i32 m0, s0, 0x2000
	s_nop 0
	global_load_lds_dwordx4 v134, s[40:41]
	s_barrier
	s_waitcnt lgkmcnt(0)
	s_setprio 1
	s_waitcnt lgkmcnt(0)
	v_mfma_f32_16x16x32_bf16 v[116:119], v[218:221], v[174:177], v[116:119]
	v_mfma_f32_16x16x32_bf16 v[112:115], v[226:229], v[174:177], v[112:115]
	v_mfma_f32_16x16x32_bf16 v[100:103], v[218:221], v[188:191], v[100:103]
	v_mfma_f32_16x16x32_bf16 v[96:99], v[226:229], v[188:191], v[96:99]
	v_mfma_f32_16x16x32_bf16 v[84:87], v[218:221], v[200:203], v[84:87]
	v_mfma_f32_16x16x32_bf16 v[80:83], v[226:229], v[200:203], v[80:83]
	v_mfma_f32_16x16x32_bf16 v[68:71], v[218:221], v[210:213], v[68:71]
	v_mfma_f32_16x16x32_bf16 v[64:67], v[226:229], v[210:213], v[64:67]
	v_mfma_f32_16x16x32_bf16 v[116:119], v[222:225], v[178:181], v[116:119]
	v_mfma_f32_16x16x32_bf16 v[112:115], v[230:233], v[178:181], v[112:115]
	v_mfma_f32_16x16x32_bf16 v[100:103], v[222:225], v[196:199], v[100:103]
	v_mfma_f32_16x16x32_bf16 v[96:99], v[230:233], v[196:199], v[96:99]
	v_mfma_f32_16x16x32_bf16 v[84:87], v[222:225], v[206:209], v[84:87]
	v_mfma_f32_16x16x32_bf16 v[80:83], v[230:233], v[206:209], v[80:83]
	v_mfma_f32_16x16x32_bf16 v[68:71], v[222:225], v[214:217], v[68:71]
	v_mfma_f32_16x16x32_bf16 v[64:67], v[230:233], v[214:217], v[64:67]
	s_setprio 0
	s_mov_b32 m0, s53
	s_barrier
	ds_read_b128 v[174:177], v158 offset:16384
	ds_read_b128 v[178:181], v158 offset:17408
	ds_read_b128 v[188:191], v158 offset:18432
	ds_read_b128 v[196:199], v158 offset:19456
	ds_read_b128 v[200:203], v158 offset:20480
	ds_read_b128 v[206:209], v158 offset:21504
	ds_read_b128 v[210:213], v158 offset:22528
	ds_read_b128 v[214:217], v158 offset:23552
	global_load_lds_dwordx4 v128, s[42:43]
	s_mov_b32 m0, s54
	s_nop 0
	global_load_lds_dwordx4 v132, s[42:43]
	s_barrier
	s_waitcnt lgkmcnt(0)
	s_setprio 1
	s_waitcnt lgkmcnt(0)
	v_mfma_f32_16x16x32_bf16 v[60:63], v[148:151], v[174:177], v[60:63]
	v_mfma_f32_16x16x32_bf16 v[56:59], v[166:169], v[174:177], v[56:59]
	v_mfma_f32_16x16x32_bf16 v[44:47], v[148:151], v[188:191], v[44:47]
	v_mfma_f32_16x16x32_bf16 v[40:43], v[166:169], v[188:191], v[40:43]
	v_mfma_f32_16x16x32_bf16 v[28:31], v[148:151], v[200:203], v[28:31]
	v_mfma_f32_16x16x32_bf16 v[24:27], v[166:169], v[200:203], v[24:27]
	v_mfma_f32_16x16x32_bf16 v[12:15], v[148:151], v[210:213], v[12:15]
	v_mfma_f32_16x16x32_bf16 v[8:11], v[166:169], v[210:213], v[8:11]
	v_mfma_f32_16x16x32_bf16 v[60:63], v[162:165], v[178:181], v[60:63]
	v_mfma_f32_16x16x32_bf16 v[56:59], v[170:173], v[178:181], v[56:59]
	v_mfma_f32_16x16x32_bf16 v[44:47], v[162:165], v[196:199], v[44:47]
	v_mfma_f32_16x16x32_bf16 v[40:43], v[170:173], v[196:199], v[40:43]
	v_mfma_f32_16x16x32_bf16 v[28:31], v[162:165], v[206:209], v[28:31]
	v_mfma_f32_16x16x32_bf16 v[24:27], v[170:173], v[206:209], v[24:27]
	v_mfma_f32_16x16x32_bf16 v[12:15], v[162:165], v[214:217], v[12:15]
	v_mfma_f32_16x16x32_bf16 v[8:11], v[170:173], v[214:217], v[8:11]
	s_setprio 0
	s_barrier
; #define PG8_STAGE(bufoff, gbase, voff) do { _Pragma("unroll") for (int _i = 0; _i < 2; ++_i) \
;         __builtin_amdgcn_global_load_lds((const unsigned*)((const char*)(gbase) + (voff)[_i]), (LAS unsigned*)(lds + (bufoff) + ldsw + _i * 8192), 16, 0, 0); } while (0)
; #define PG8_LDA(dst, b, h) do { _Pragma("unroll") for (int m = 0; m < 4; ++m) _Pragma("unroll") for (int k = 0; k < 2; ++k) dst[m][k] = *(const LAS bf16x8*)(lds + PG8_SA(b, h) + aoff + m * 2048 + k * 1024); } while (0)
; #define PG8_LDB(dst, b, h) do { _Pragma("unroll") for (int n = 0; n < 2; ++n) _Pragma("unroll") for (int k = 0; k < 2; ++k) dst[n][k] = *(const LAS bf16x8*)(lds + PG8_SB(b, h) + boff + n * 2048 + k * 1024); } while (0)
; #define PG8_MMA(ai, bj, At, Bt) do { __builtin_amdgcn_s_setprio(1); _Pragma("unroll") for (int m = 0; m < 4; ++m) _Pragma("unroll") for (int n = 0; n < 2; ++n) _Pragma("unroll") for (int k = 0; k < 2; ++k) \
;         acc[ai][bj][m][n] = __builtin_amdgcn_mfma_f32_16x16x32_bf16(Bt[n][k], At[m][k], acc[ai][bj][m][n], 0, 0, 0); __builtin_amdgcn_s_setprio(0); } while (0)
; #define PG8_WAIT_V(n) asm volatile("s_waitcnt vmcnt(" #n ")" ::: "memory")
; #define PG8_WAIT_L(n) asm volatile("s_waitcnt lgkmcnt(" #n ")" ::: "memory")
; #define PG8_BAR __builtin_amdgcn_s_barrier()
; #define PG8_SCHED __builtin_amdgcn_sched_barrier(0)
; template <class Epi, class Sched>
; DI void gemm_phase(LAS unsigned char* lds, const Gemm g, const Sched& S, const Epi& E) {
;     ...
;             PG8_LDA(At, 0, 1); PG8_STAGE(PG8_SA(0, 0), a2, voffA);
;             PG8_BAR; PG8_WAIT_L(0); PG8_MMA(1, 0, At, B0); PG8_BAR; PG8_SCHED;
;             PG8_STAGE(PG8_SB(0, 1), b2 + hstep, voffB);
;             PG8_WAIT_V(6); PG8_BAR; PG8_MMA(1, 1, At, B1); PG8_BAR;
;             PG8_LDB(B0, 1, 0); PG8_SCHED; PG8_LDA(At, 1, 0); PG8_STAGE(PG8_SA(0, 1), a2 + hstep, voffA);
;             PG8_WAIT_L(8); PG8_BAR; PG8_WAIT_L(0); PG8_MMA(0, 0, At, B0); PG8_BAR; PG8_SCHED;
	s_add_u32 s0, s40, 0x90000
	s_addc_u32 s1, s41, 0
	s_add_i32 s4, s63, s52
	s_mov_b32 m0, s4
	s_nop 0
	global_load_lds_dwordx4 v130, s[0:1]
	s_add_i32 m0, s4, 0x2000
	s_nop 0
	global_load_lds_dwordx4 v134, s[0:1]
	s_waitcnt vmcnt(6)
	s_barrier
	s_setprio 1
	v_mfma_f32_16x16x32_bf16 v[52:55], v[218:221], v[174:177], v[52:55]
	v_mfma_f32_16x16x32_bf16 v[48:51], v[226:229], v[174:177], v[48:51]
	v_mfma_f32_16x16x32_bf16 v[36:39], v[218:221], v[188:191], v[36:39]
	v_mfma_f32_16x16x32_bf16 v[32:35], v[226:229], v[188:191], v[32:35]
	v_mfma_f32_16x16x32_bf16 v[20:23], v[218:221], v[200:203], v[20:23]
	v_mfma_f32_16x16x32_bf16 v[16:19], v[226:229], v[200:203], v[16:19]
	v_mfma_f32_16x16x32_bf16 v[4:7], v[218:221], v[210:213], v[4:7]
	v_mfma_f32_16x16x32_bf16 v[0:3], v[226:229], v[210:213], v[0:3]
	v_mfma_f32_16x16x32_bf16 v[52:55], v[222:225], v[178:181], v[52:55]
	v_mfma_f32_16x16x32_bf16 v[48:51], v[230:233], v[178:181], v[48:51]
	v_mfma_f32_16x16x32_bf16 v[36:39], v[222:225], v[196:199], v[36:39]
	v_mfma_f32_16x16x32_bf16 v[32:35], v[230:233], v[196:199], v[32:35]
	v_mfma_f32_16x16x32_bf16 v[20:23], v[222:225], v[206:209], v[20:23]
	v_mfma_f32_16x16x32_bf16 v[16:19], v[230:233], v[206:209], v[16:19]
	v_mfma_f32_16x16x32_bf16 v[4:7], v[222:225], v[214:217], v[4:7]
	v_mfma_f32_16x16x32_bf16 v[0:3], v[230:233], v[214:217], v[0:3]
	s_setprio 0
	s_add_i32 s4, 0, 0x18000
	v_add_u32_e32 v161, s4, v157
	s_barrier
	ds_read_b128 v[148:151], v161
	ds_read_b128 v[162:165], v161 offset:1024
	ds_read_b128 v[166:169], v161 offset:2048
	ds_read_b128 v[170:173], v161 offset:3072
	s_add_u32 s0, s42, 0x90000
	s_addc_u32 s1, s43, 0
	s_mov_b32 m0, s55
	ds_read_b128 v[174:177], v158 offset:32768
	ds_read_b128 v[178:181], v158 offset:33792
	ds_read_b128 v[188:191], v158 offset:34816
	ds_read_b128 v[196:199], v158 offset:35840
	ds_read_b128 v[200:203], v158 offset:36864
	ds_read_b128 v[206:209], v158 offset:37888
	ds_read_b128 v[210:213], v158 offset:38912
	ds_read_b128 v[214:217], v158 offset:39936
	global_load_lds_dwordx4 v128, s[0:1]
	s_mov_b32 m0, s56
	s_nop 0
	global_load_lds_dwordx4 v132, s[0:1]
	s_waitcnt lgkmcnt(8)
	s_barrier
	s_waitcnt lgkmcnt(0)
	s_setprio 1
	s_waitcnt lgkmcnt(0)
	v_mfma_f32_16x16x32_bf16 v[124:127], v[148:151], v[174:177], v[124:127]
	v_mfma_f32_16x16x32_bf16 v[120:123], v[166:169], v[174:177], v[120:123]
	v_mfma_f32_16x16x32_bf16 v[108:111], v[148:151], v[188:191], v[108:111]
	v_mfma_f32_16x16x32_bf16 v[104:107], v[166:169], v[188:191], v[104:107]
	v_mfma_f32_16x16x32_bf16 v[92:95], v[148:151], v[200:203], v[92:95]
	v_mfma_f32_16x16x32_bf16 v[88:91], v[166:169], v[200:203], v[88:91]
	v_mfma_f32_16x16x32_bf16 v[76:79], v[148:151], v[210:213], v[76:79]
	v_mfma_f32_16x16x32_bf16 v[72:75], v[166:169], v[210:213], v[72:75]
	v_mfma_f32_16x16x32_bf16 v[124:127], v[162:165], v[178:181], v[124:127]
	v_mfma_f32_16x16x32_bf16 v[120:123], v[170:173], v[178:181], v[120:123]
	v_mfma_f32_16x16x32_bf16 v[108:111], v[162:165], v[196:199], v[108:111]
	v_mfma_f32_16x16x32_bf16 v[104:107], v[170:173], v[196:199], v[104:107]
	v_mfma_f32_16x16x32_bf16 v[92:95], v[162:165], v[206:209], v[92:95]
	v_mfma_f32_16x16x32_bf16 v[88:91], v[170:173], v[206:209], v[88:91]
	v_mfma_f32_16x16x32_bf16 v[76:79], v[162:165], v[214:217], v[76:79]
	v_mfma_f32_16x16x32_bf16 v[72:75], v[170:173], v[214:217], v[72:75]
	s_setprio 0
	s_barrier
	s_add_i32 s5, 0, 0x1c000
	s_add_i32 s0, s4, s52
	v_add_u32_e32 v161, s5, v157
	s_add_i32 m0, s0, 0xffffff80
	ds_read_b128 v[218:221], v161
	ds_read_b128 v[222:225], v161 offset:1024
	ds_read_b128 v[226:229], v161 offset:2048
	ds_read_b128 v[230:233], v161 offset:3072
	global_load_lds_dwordx4 v130, s[40:41] offset:128
	s_add_i32 m0, s0, 0x1f80
	s_nop 0
	global_load_lds_dwordx4 v134, s[40:41] offset:128
	s_barrier
; #define PG8_STAGE(bufoff, gbase, voff) do { _Pragma("unroll") for (int _i = 0; _i < 2; ++_i) \
;         __builtin_amdgcn_global_load_lds((const unsigned*)((const char*)(gbase) + (voff)[_i]), (LAS unsigned*)(lds + (bufoff) + ldsw + _i * 8192), 16, 0, 0); } while (0)
; #define PG8_LDA(dst, b, h) do { _Pragma("unroll") for (int m = 0; m < 4; ++m) _Pragma("unroll") for (int k = 0; k < 2; ++k) dst[m][k] = *(const LAS bf16x8*)(lds + PG8_SA(b, h) + aoff + m * 2048 + k * 1024); } while (0)
; #define PG8_LDB(dst, b, h) do { _Pragma("unroll") for (int n = 0; n < 2; ++n) _Pragma("unroll") for (int k = 0; k < 2; ++k) dst[n][k] = *(const LAS bf16x8*)(lds + PG8_SB(b, h) + boff + n * 2048 + k * 1024); } while (0)
; #define PG8_MMA(ai, bj, At, Bt) do { __builtin_amdgcn_s_setprio(1); _Pragma("unroll") for (int m = 0; m < 4; ++m) _Pragma("unroll") for (int n = 0; n < 2; ++n) _Pragma("unroll") for (int k = 0; k < 2; ++k) \
;         acc[ai][bj][m][n] = __builtin_amdgcn_mfma_f32_16x16x32_bf16(Bt[n][k], At[m][k], acc[ai][bj][m][n], 0, 0, 0); __builtin_amdgcn_s_setprio(0); } while (0)
; #define PG8_WAIT_V(n) asm volatile("s_waitcnt vmcnt(" #n ")" ::: "memory")
; #define PG8_WAIT_L(n) asm volatile("s_waitcnt lgkmcnt(" #n ")" ::: "memory")
; #define PG8_BAR __builtin_amdgcn_s_barrier()
; #define PG8_SCHED __builtin_amdgcn_sched_barrier(0)
; template <class Epi, class Sched>
; DI void gemm_phase(LAS unsigned char* lds, const Gemm g, const Sched& S, const Epi& E) {
;     ...
;             PG8_WAIT_L(8); PG8_BAR; PG8_WAIT_L(0); PG8_MMA(0, 0, At, B0); PG8_BAR; PG8_SCHED;
;             PG8_LDB(B1, 1, 1); PG8_STAGE(PG8_SB(1, 0), b3, voffB);
;             PG8_BAR; PG8_WAIT_L(0); PG8_MMA(0, 1, At, B1); PG8_BAR;
;             PG8_LDA(At, 1, 1); PG8_STAGE(PG8_SA(1, 0), a3, voffA);
;             PG8_BAR; PG8_WAIT_L(0); PG8_MMA(1, 0, At, B0); PG8_BAR; PG8_SCHED;
;             PG8_STAGE(PG8_SB(1, 1), b3 + hstep, voffB);
;             PG8_WAIT_V(6); PG8_BAR; PG8_MMA(1, 1, At, B1); PG8_BAR;
	s_waitcnt lgkmcnt(0)
	s_setprio 1
	s_waitcnt lgkmcnt(0)
	v_mfma_f32_16x16x32_bf16 v[116:119], v[218:221], v[174:177], v[116:119]
	v_mfma_f32_16x16x32_bf16 v[112:115], v[226:229], v[174:177], v[112:115]
	v_mfma_f32_16x16x32_bf16 v[100:103], v[218:221], v[188:191], v[100:103]
	v_mfma_f32_16x16x32_bf16 v[96:99], v[226:229], v[188:191], v[96:99]
	v_mfma_f32_16x16x32_bf16 v[84:87], v[218:221], v[200:203], v[84:87]
	v_mfma_f32_16x16x32_bf16 v[80:83], v[226:229], v[200:203], v[80:83]
	v_mfma_f32_16x16x32_bf16 v[68:71], v[218:221], v[210:213], v[68:71]
	v_mfma_f32_16x16x32_bf16 v[64:67], v[226:229], v[210:213], v[64:67]
	v_mfma_f32_16x16x32_bf16 v[116:119], v[222:225], v[178:181], v[116:119]
	v_mfma_f32_16x16x32_bf16 v[112:115], v[230:233], v[178:181], v[112:115]
	v_mfma_f32_16x16x32_bf16 v[100:103], v[222:225], v[196:199], v[100:103]
	v_mfma_f32_16x16x32_bf16 v[96:99], v[230:233], v[196:199], v[96:99]
	v_mfma_f32_16x16x32_bf16 v[84:87], v[222:225], v[206:209], v[84:87]
	v_mfma_f32_16x16x32_bf16 v[80:83], v[230:233], v[206:209], v[80:83]
	v_mfma_f32_16x16x32_bf16 v[68:71], v[222:225], v[214:217], v[68:71]
	v_mfma_f32_16x16x32_bf16 v[64:67], v[230:233], v[214:217], v[64:67]
	s_setprio 0
	s_add_i32 m0, s59, 0xffffff80
	s_barrier
	ds_read_b128 v[174:177], v158 offset:49152
	ds_read_b128 v[178:181], v158 offset:50176
	ds_read_b128 v[188:191], v158 offset:51200
	ds_read_b128 v[196:199], v158 offset:52224
	ds_read_b128 v[200:203], v158 offset:53248
	ds_read_b128 v[206:209], v158 offset:54272
	ds_read_b128 v[210:213], v158 offset:55296
	ds_read_b128 v[214:217], v158 offset:56320
	global_load_lds_dwordx4 v128, s[42:43] offset:128
	s_add_i32 m0, s60, 0xffffff80
	s_nop 0
	global_load_lds_dwordx4 v132, s[42:43] offset:128
	s_barrier
	s_waitcnt lgkmcnt(0)
	s_setprio 1
	s_waitcnt lgkmcnt(0)
	v_mfma_f32_16x16x32_bf16 v[60:63], v[148:151], v[174:177], v[60:63]
	v_mfma_f32_16x16x32_bf16 v[56:59], v[166:169], v[174:177], v[56:59]
	v_mfma_f32_16x16x32_bf16 v[44:47], v[148:151], v[188:191], v[44:47]
	v_mfma_f32_16x16x32_bf16 v[40:43], v[166:169], v[188:191], v[40:43]
	v_mfma_f32_16x16x32_bf16 v[28:31], v[148:151], v[200:203], v[28:31]
	v_mfma_f32_16x16x32_bf16 v[24:27], v[166:169], v[200:203], v[24:27]
	v_mfma_f32_16x16x32_bf16 v[12:15], v[148:151], v[210:213], v[12:15]
	v_mfma_f32_16x16x32_bf16 v[8:11], v[166:169], v[210:213], v[8:11]
	v_mfma_f32_16x16x32_bf16 v[60:63], v[162:165], v[178:181], v[60:63]
	v_mfma_f32_16x16x32_bf16 v[56:59], v[170:173], v[178:181], v[56:59]
	v_mfma_f32_16x16x32_bf16 v[44:47], v[162:165], v[196:199], v[44:47]
	v_mfma_f32_16x16x32_bf16 v[40:43], v[170:173], v[196:199], v[40:43]
	v_mfma_f32_16x16x32_bf16 v[28:31], v[162:165], v[206:209], v[28:31]
	v_mfma_f32_16x16x32_bf16 v[24:27], v[170:173], v[206:209], v[24:27]
	v_mfma_f32_16x16x32_bf16 v[12:15], v[162:165], v[214:217], v[12:15]
	v_mfma_f32_16x16x32_bf16 v[8:11], v[170:173], v[214:217], v[8:11]
	s_setprio 0
	s_barrier
	s_add_u32 s0, s40, 0x90080
	s_addc_u32 s1, s41, 0
	s_add_i32 s4, s5, s52
	s_mov_b32 m0, s4
	s_nop 0
	global_load_lds_dwordx4 v130, s[0:1]
	s_add_i32 m0, s4, 0x2000
	s_nop 0
	global_load_lds_dwordx4 v134, s[0:1]
	s_waitcnt vmcnt(6)
	s_barrier
	s_setprio 1
	v_mfma_f32_16x16x32_bf16 v[52:55], v[218:221], v[174:177], v[52:55]
	v_mfma_f32_16x16x32_bf16 v[48:51], v[226:229], v[174:177], v[48:51]
	v_mfma_f32_16x16x32_bf16 v[36:39], v[218:221], v[188:191], v[36:39]
	v_mfma_f32_16x16x32_bf16 v[32:35], v[226:229], v[188:191], v[32:35]
	v_mfma_f32_16x16x32_bf16 v[20:23], v[218:221], v[200:203], v[20:23]
	v_mfma_f32_16x16x32_bf16 v[16:19], v[226:229], v[200:203], v[16:19]
	v_mfma_f32_16x16x32_bf16 v[4:7], v[218:221], v[210:213], v[4:7]
	v_mfma_f32_16x16x32_bf16 v[0:3], v[226:229], v[210:213], v[0:3]
	v_mfma_f32_16x16x32_bf16 v[52:55], v[222:225], v[178:181], v[52:55]
	v_mfma_f32_16x16x32_bf16 v[48:51], v[230:233], v[178:181], v[48:51]
	v_mfma_f32_16x16x32_bf16 v[36:39], v[222:225], v[196:199], v[36:39]
	v_mfma_f32_16x16x32_bf16 v[32:35], v[230:233], v[196:199], v[32:35]
	v_mfma_f32_16x16x32_bf16 v[20:23], v[222:225], v[206:209], v[20:23]
	v_mfma_f32_16x16x32_bf16 v[16:19], v[230:233], v[206:209], v[16:19]
	v_mfma_f32_16x16x32_bf16 v[4:7], v[222:225], v[214:217], v[4:7]
	v_mfma_f32_16x16x32_bf16 v[0:3], v[230:233], v[214:217], v[0:3]
	s_setprio 0
	s_add_i32 s70, s70, 2
	s_add_u32 s8, s8, 0x100
	s_addc_u32 s9, s9, 0
	s_cmp_gt_u32 s70, 33
	s_barrier
	s_cbranch_scc1 .LBB0_1908

; #define PG8_STAGE(bufoff, gbase, voff) do { _Pragma("unroll") for (int _i = 0; _i < 2; ++_i) \
;         __builtin_amdgcn_global_load_lds((const unsigned*)((const char*)(gbase) + (voff)[_i]), (LAS unsigned*)(lds + (bufoff) + ldsw + _i * 8192), 16, 0, 0); } while (0)
; #define PG8_WAIT_V(n) asm volatile("s_waitcnt vmcnt(" #n ")" ::: "memory")
; #define PG8_BAR __builtin_amdgcn_s_barrier()
; template <class Epi, class Sched>
; DI void gemm_phase(LAS unsigned char* lds, const Gemm g, const Sched& S, const Epi& E) {
;     ...
;     PG8_STAGE(PG8_SB(1, 0), cB + kstep, voffB); PG8_STAGE(PG8_SA(1, 0), cA + kstep, voffA); PG8_STAGE(PG8_SB(1, 1), cB + hstep + kstep, voffB);
;     PG8_WAIT_V(6); PG8_BAR;
.LBB0_1929:
	s_lshl_b32 s0, s0, 5
	s_lshl_b32 s61, s1, 6
	s_lshl_b32 s4, s1, 13
	s_and_b32 s62, s0, 0x60
	s_add_u32 s63, s22, 0x3c40b000
	s_mov_b64 s[10:11], 0x80
	s_addc_u32 s64, s23, 0
	s_add_i32 m0, s56, 0x18000
	v_lshl_add_u64 v[6:7], v[6:7], 0, s[10:11]
	s_waitcnt vmcnt(4)
	s_barrier
	global_load_lds_dwordx4 v[6:7], off
	v_lshl_add_u64 v[4:5], v[4:5], 0, s[10:11]
	s_add_i32 m0, s56, 0x1a000
	s_add_i32 s66, s56, 0x8000
	s_add_i32 s67, s56, 0xa000
	global_load_lds_dwordx4 v[4:5], off
	v_lshl_add_u64 v[2:3], v[2:3], 0, s[10:11]
	s_mov_b32 m0, s66
	s_add_u32 s0, s16, 0x90080
	global_load_lds_dwordx4 v[2:3], off
	v_lshl_add_u64 v[0:1], v[0:1], 0, s[10:11]
	s_mov_b32 m0, s67
	s_addc_u32 s1, s17, 0
	global_load_lds_dwordx4 v[0:1], off
	s_add_i32 m0, s56, 0x1c000
	s_nop 0
	global_load_lds_dwordx4 v130, s[0:1]
	s_add_i32 m0, s56, 0x1e000
	v_lshl_or_b32 v136, s62, 7, v153
	global_load_lds_dwordx4 v128, s[0:1]
	v_lshlrev_b32_e32 v1, 2, v194
	v_lshl_or_b32 v0, v194, 6, v195
	v_and_b32_e32 v1, 32, v1
	s_waitcnt vmcnt(6)
	s_add_i32 s70, 0, 0x10000
	v_bitop3_b32 v0, v0, s4, v1 bitop3:0xde
	s_add_i32 s72, 0, 0x14000
	v_add_u32_e32 v137, s70, v136
	s_add_i32 s70, s70, s52
	v_mov_b64_e32 v[132:133], 0x48
	v_mov_b64_e32 v[134:135], 0x47
	v_add_u32_e32 v138, 0, v0
	v_add_u32_e32 v139, s72, v136
	s_add_i32 s68, s56, 0xc000
	s_add_i32 s69, s56, 0xe000
	s_add_i32 s71, s70, 0x2000
	s_add_i32 s72, s72, s52
	s_barrier

; #define PG8_STAGE(bufoff, gbase, voff) do { _Pragma("unroll") for (int _i = 0; _i < 2; ++_i) \
;         __builtin_amdgcn_global_load_lds((const unsigned*)((const char*)(gbase) + (voff)[_i]), (LAS unsigned*)(lds + (bufoff) + ldsw + _i * 8192), 16, 0, 0); } while (0)
; #define PG8_LDA(dst, b, h) do { _Pragma("unroll") for (int m = 0; m < 4; ++m) _Pragma("unroll") for (int k = 0; k < 2; ++k) dst[m][k] = *(const LAS bf16x8*)(lds + PG8_SA(b, h) + aoff + m * 2048 + k * 1024); } while (0)
; #define PG8_LDB(dst, b, h) do { _Pragma("unroll") for (int n = 0; n < 2; ++n) _Pragma("unroll") for (int k = 0; k < 2; ++k) dst[n][k] = *(const LAS bf16x8*)(lds + PG8_SB(b, h) + boff + n * 2048 + k * 1024); } while (0)
; #define PG8_MMA(ai, bj, At, Bt) do { __builtin_amdgcn_s_setprio(1); _Pragma("unroll") for (int m = 0; m < 4; ++m) _Pragma("unroll") for (int n = 0; n < 2; ++n) _Pragma("unroll") for (int k = 0; k < 2; ++k) \
;         acc[ai][bj][m][n] = __builtin_amdgcn_mfma_f32_16x16x32_bf16(Bt[n][k], At[m][k], acc[ai][bj][m][n], 0, 0, 0); __builtin_amdgcn_s_setprio(0); } while (0)
; #define PG8_WAIT_L(n) asm volatile("s_waitcnt lgkmcnt(" #n ")" ::: "memory")
; #define PG8_BAR __builtin_amdgcn_s_barrier()
; template <class Epi, class Sched>
; DI void gemm_phase(LAS unsigned char* lds, const Gemm g, const Sched& S, const Epi& E) {
;     ...
;         for (int t = 0; t < nt; t += 2) {
;             if constexpr (Epi::HAS_MID) { if (t == E.mid_t(nt)) { int fr3 = fr, fq3 = fq; asm volatile("" : "+v"(fr3), "+v"(fq3)); E.mid(acc, cur, wr, wc, fr3, fq3); } }
;             const bool last = (t == nt - 2);
;             const char* a1 = cA + (size_t)(t + 1) * kstep;
;             const char* a2 = last ? nA : cA + (size_t)(t + 2) * kstep; const char* b2 = last ? nB : cB + (size_t)(t + 2) * kstep;
;             const char* a3 = a2 + kstep; const char* b3 = b2 + kstep;
;             PG8_LDB(B0, 0, 0); PG8_SCHED; PG8_LDA(At, 0, 0); PG8_STAGE(PG8_SA(1, 1), a1 + hstep, voffA);
;             PG8_WAIT_L(8); PG8_BAR; PG8_WAIT_L(0); PG8_MMA(0, 0, At, B0); PG8_BAR; PG8_SCHED;
;             PG8_LDB(B1, 0, 1); PG8_STAGE(PG8_SB(0, 0), b2, voffB);
;             PG8_BAR; PG8_WAIT_L(0); PG8_MMA(0, 1, At, B1); PG8_BAR;
;             PG8_LDA(At, 0, 1); PG8_STAGE(PG8_SA(0, 0), a2, voffA);
;             PG8_BAR; PG8_WAIT_L(0); PG8_MMA(1, 0, At, B0); PG8_BAR; PG8_SCHED;
.LBB0_1935:
	s_add_u32 s33, s18, s0
	s_addc_u32 s40, s19, 0
	s_add_u32 s1, s33, 0x100
	s_addc_u32 s41, s40, 0
	s_and_b64 s[4:5], s[38:39], exec
	s_cselect_b32 s45, s15, s41
	s_cselect_b32 s44, s29, s1
	s_add_u32 s0, s16, s0
	s_addc_u32 s1, s17, 0
	s_add_u32 s4, s0, 0x100
	s_addc_u32 s5, s1, 0
	s_and_b64 s[0:1], s[38:39], exec
	s_cselect_b32 s47, s31, s5
	s_cselect_b32 s46, s30, s4
	s_add_u32 s48, s33, 0x90080
	s_addc_u32 s49, s40, 0
	s_add_u32 s42, s46, 0x90000
	ds_read_b128 v[140:143], v137
	ds_read_b128 v[144:147], v137 offset:1024
	ds_read_b128 v[148:151], v137 offset:2048
	ds_read_b128 v[154:157], v137 offset:3072
	s_addc_u32 s43, s47, 0
	s_add_i32 s33, s72, 0x2000
	s_add_i32 s5, 0, 0x18000
	s_add_u32 s40, s44, 0x90000
	s_addc_u32 s41, s45, 0
	s_add_i32 s4, s5, s52
	s_add_i32 s1, 0, 0x1c000
	s_add_i32 s0, s4, 0x2000
	s_add_u32 s38, s46, 0x90080
	s_addc_u32 s39, s47, 0
	s_add_i32 s75, s1, s52
	s_add_i32 s74, s75, 0x2000
	s_mov_b32 m0, s68
	ds_read_b128 v[158:161], v138
	ds_read_b128 v[162:165], v138 offset:1024
	ds_read_b128 v[166:169], v138 offset:2048
	ds_read_b128 v[170:173], v138 offset:3072
	ds_read_b128 v[174:177], v138 offset:4096
	ds_read_b128 v[178:181], v138 offset:5120
	ds_read_b128 v[188:191], v138 offset:6144
	ds_read_b128 v[196:199], v138 offset:7168
	global_load_lds_dwordx4 v130, s[48:49]
	s_mov_b32 m0, s69
	s_nop 0
	global_load_lds_dwordx4 v128, s[48:49]
	s_waitcnt lgkmcnt(8)
	s_barrier
	s_waitcnt lgkmcnt(0)
	s_setprio 1
	s_waitcnt lgkmcnt(0)
	v_mfma_f32_16x16x32_bf16 v[124:127], v[140:143], v[158:161], v[124:127]
	v_mfma_f32_16x16x32_bf16 v[120:123], v[148:151], v[158:161], v[120:123]
	v_mfma_f32_16x16x32_bf16 v[116:119], v[140:143], v[166:169], v[116:119]
	v_mfma_f32_16x16x32_bf16 v[112:115], v[148:151], v[166:169], v[112:115]
	v_mfma_f32_16x16x32_bf16 v[104:107], v[140:143], v[174:177], v[104:107]
	v_mfma_f32_16x16x32_bf16 v[96:99], v[148:151], v[174:177], v[96:99]
	v_mfma_f32_16x16x32_bf16 v[88:91], v[140:143], v[188:191], v[88:91]
	v_mfma_f32_16x16x32_bf16 v[80:83], v[148:151], v[188:191], v[80:83]
	v_mfma_f32_16x16x32_bf16 v[124:127], v[144:147], v[162:165], v[124:127]
	v_mfma_f32_16x16x32_bf16 v[120:123], v[154:157], v[162:165], v[120:123]
	v_mfma_f32_16x16x32_bf16 v[116:119], v[144:147], v[170:173], v[116:119]
	v_mfma_f32_16x16x32_bf16 v[112:115], v[154:157], v[170:173], v[112:115]
	v_mfma_f32_16x16x32_bf16 v[104:107], v[144:147], v[178:181], v[104:107]
	v_mfma_f32_16x16x32_bf16 v[96:99], v[154:157], v[178:181], v[96:99]
	v_mfma_f32_16x16x32_bf16 v[88:91], v[144:147], v[196:199], v[88:91]
	v_mfma_f32_16x16x32_bf16 v[80:83], v[154:157], v[196:199], v[80:83]
	s_setprio 0
	s_barrier
	s_mov_b32 m0, s70
	ds_read_b128 v[200:203], v139
	ds_read_b128 v[206:209], v139 offset:1024
	ds_read_b128 v[210:213], v139 offset:2048
	ds_read_b128 v[214:217], v139 offset:3072
	global_load_lds_dwordx4 v130, s[46:47]
	s_mov_b32 m0, s71
	s_nop 0
	global_load_lds_dwordx4 v128, s[46:47]
	s_barrier
	s_waitcnt lgkmcnt(0)
	s_setprio 1
	s_waitcnt lgkmcnt(0)
	v_mfma_f32_16x16x32_bf16 v[108:111], v[200:203], v[158:161], v[108:111]
	v_mfma_f32_16x16x32_bf16 v[100:103], v[210:213], v[158:161], v[100:103]
	v_mfma_f32_16x16x32_bf16 v[92:95], v[200:203], v[166:169], v[92:95]
	v_mfma_f32_16x16x32_bf16 v[84:87], v[210:213], v[166:169], v[84:87]
	v_mfma_f32_16x16x32_bf16 v[76:79], v[200:203], v[174:177], v[76:79]
	v_mfma_f32_16x16x32_bf16 v[72:75], v[210:213], v[174:177], v[72:75]
	v_mfma_f32_16x16x32_bf16 v[68:71], v[200:203], v[188:191], v[68:71]
	v_mfma_f32_16x16x32_bf16 v[64:67], v[210:213], v[188:191], v[64:67]
	v_mfma_f32_16x16x32_bf16 v[108:111], v[206:209], v[162:165], v[108:111]
	v_mfma_f32_16x16x32_bf16 v[100:103], v[214:217], v[162:165], v[100:103]
	v_mfma_f32_16x16x32_bf16 v[92:95], v[206:209], v[170:173], v[92:95]
	v_mfma_f32_16x16x32_bf16 v[84:87], v[214:217], v[170:173], v[84:87]
	v_mfma_f32_16x16x32_bf16 v[76:79], v[206:209], v[178:181], v[76:79]
	v_mfma_f32_16x16x32_bf16 v[72:75], v[214:217], v[178:181], v[72:75]
	v_mfma_f32_16x16x32_bf16 v[68:71], v[206:209], v[196:199], v[68:71]
	v_mfma_f32_16x16x32_bf16 v[64:67], v[214:217], v[196:199], v[64:67]
	s_setprio 0
	s_mov_b32 m0, s56
	s_barrier
	ds_read_b128 v[158:161], v138 offset:16384
	ds_read_b128 v[162:165], v138 offset:17408
	ds_read_b128 v[166:169], v138 offset:18432
	ds_read_b128 v[170:173], v138 offset:19456
	ds_read_b128 v[174:177], v138 offset:20480
	ds_read_b128 v[178:181], v138 offset:21504
	ds_read_b128 v[188:191], v138 offset:22528
	ds_read_b128 v[196:199], v138 offset:23552
	global_load_lds_dwordx4 v130, s[44:45]
	s_mov_b32 m0, s57
	s_nop 0
	global_load_lds_dwordx4 v128, s[44:45]
	s_barrier
	s_waitcnt lgkmcnt(0)
	s_setprio 1
	s_waitcnt lgkmcnt(0)
	v_mfma_f32_16x16x32_bf16 v[60:63], v[140:143], v[158:161], v[60:63]
	v_mfma_f32_16x16x32_bf16 v[56:59], v[148:151], v[158:161], v[56:59]
	v_mfma_f32_16x16x32_bf16 v[52:55], v[140:143], v[166:169], v[52:55]
	v_mfma_f32_16x16x32_bf16 v[48:51], v[148:151], v[166:169], v[48:51]
	v_mfma_f32_16x16x32_bf16 v[40:43], v[140:143], v[174:177], v[40:43]
	v_mfma_f32_16x16x32_bf16 v[32:35], v[148:151], v[174:177], v[32:35]
	v_mfma_f32_16x16x32_bf16 v[24:27], v[140:143], v[188:191], v[24:27]
	v_mfma_f32_16x16x32_bf16 v[16:19], v[148:151], v[188:191], v[16:19]
	v_mfma_f32_16x16x32_bf16 v[60:63], v[144:147], v[162:165], v[60:63]
	v_mfma_f32_16x16x32_bf16 v[56:59], v[154:157], v[162:165], v[56:59]
	v_mfma_f32_16x16x32_bf16 v[52:55], v[144:147], v[170:173], v[52:55]
	v_mfma_f32_16x16x32_bf16 v[48:51], v[154:157], v[170:173], v[48:51]
	v_mfma_f32_16x16x32_bf16 v[40:43], v[144:147], v[178:181], v[40:43]
	v_mfma_f32_16x16x32_bf16 v[32:35], v[154:157], v[178:181], v[32:35]
	v_mfma_f32_16x16x32_bf16 v[24:27], v[144:147], v[196:199], v[24:27]
	v_mfma_f32_16x16x32_bf16 v[16:19], v[154:157], v[196:199], v[16:19]
	s_setprio 0
	s_barrier
; #define PG8_STAGE(bufoff, gbase, voff) do { _Pragma("unroll") for (int _i = 0; _i < 2; ++_i) \
;         __builtin_amdgcn_global_load_lds((const unsigned*)((const char*)(gbase) + (voff)[_i]), (LAS unsigned*)(lds + (bufoff) + ldsw + _i * 8192), 16, 0, 0); } while (0)
; #define PG8_LDA(dst, b, h) do { _Pragma("unroll") for (int m = 0; m < 4; ++m) _Pragma("unroll") for (int k = 0; k < 2; ++k) dst[m][k] = *(const LAS bf16x8*)(lds + PG8_SA(b, h) + aoff + m * 2048 + k * 1024); } while (0)
; #define PG8_LDB(dst, b, h) do { _Pragma("unroll") for (int n = 0; n < 2; ++n) _Pragma("unroll") for (int k = 0; k < 2; ++k) dst[n][k] = *(const LAS bf16x8*)(lds + PG8_SB(b, h) + boff + n * 2048 + k * 1024); } while (0)
; #define PG8_MMA(ai, bj, At, Bt) do { __builtin_amdgcn_s_setprio(1); _Pragma("unroll") for (int m = 0; m < 4; ++m) _Pragma("unroll") for (int n = 0; n < 2; ++n) _Pragma("unroll") for (int k = 0; k < 2; ++k) \
;         acc[ai][bj][m][n] = __builtin_amdgcn_mfma_f32_16x16x32_bf16(Bt[n][k], At[m][k], acc[ai][bj][m][n], 0, 0, 0); __builtin_amdgcn_s_setprio(0); } while (0)
; #define PG8_WAIT_V(n) asm volatile("s_waitcnt vmcnt(" #n ")" ::: "memory")
; #define PG8_WAIT_L(n) asm volatile("s_waitcnt lgkmcnt(" #n ")" ::: "memory")
; #define PG8_BAR __builtin_amdgcn_s_barrier()
; #define PG8_SCHED __builtin_amdgcn_sched_barrier(0)
; template <class Epi, class Sched>
; DI void gemm_phase(LAS unsigned char* lds, const Gemm g, const Sched& S, const Epi& E) {
;     ...
;             PG8_STAGE(PG8_SB(0, 1), b2 + hstep, voffB);
;             PG8_WAIT_V(6); PG8_BAR; PG8_MMA(1, 1, At, B1); PG8_BAR;
;             PG8_LDB(B0, 1, 0); PG8_SCHED; PG8_LDA(At, 1, 0); PG8_STAGE(PG8_SA(0, 1), a2 + hstep, voffA);
;             PG8_WAIT_L(8); PG8_BAR; PG8_WAIT_L(0); PG8_MMA(0, 0, At, B0); PG8_BAR; PG8_SCHED;
;             PG8_LDB(B1, 1, 1); PG8_STAGE(PG8_SB(1, 0), b3, voffB);
;             PG8_BAR; PG8_WAIT_L(0); PG8_MMA(0, 1, At, B1); PG8_BAR;
;             PG8_LDA(At, 1, 1); PG8_STAGE(PG8_SA(1, 0), a3, voffA);
;             PG8_BAR; PG8_WAIT_L(0); PG8_MMA(1, 0, At, B0); PG8_BAR; PG8_SCHED;
	s_mov_b32 m0, s72
	s_nop 0
	global_load_lds_dwordx4 v130, s[42:43]
	s_mov_b32 m0, s33
	s_nop 0
	global_load_lds_dwordx4 v128, s[42:43]
	s_waitcnt vmcnt(6)
	s_barrier
	s_setprio 1
	v_mfma_f32_16x16x32_bf16 v[44:47], v[200:203], v[158:161], v[44:47]
	v_mfma_f32_16x16x32_bf16 v[36:39], v[210:213], v[158:161], v[36:39]
	v_mfma_f32_16x16x32_bf16 v[28:31], v[200:203], v[166:169], v[28:31]
	v_mfma_f32_16x16x32_bf16 v[20:23], v[210:213], v[166:169], v[20:23]
	v_mfma_f32_16x16x32_bf16 v[12:15], v[200:203], v[174:177], v[12:15]
	v_mfma_f32_16x16x32_bf16 v[8:11], v[210:213], v[174:177], v[8:11]
	v_mfma_f32_16x16x32_bf16 v[4:7], v[200:203], v[188:191], v[4:7]
	v_mfma_f32_16x16x32_bf16 v[0:3], v[210:213], v[188:191], v[0:3]
	v_mfma_f32_16x16x32_bf16 v[44:47], v[206:209], v[162:165], v[44:47]
	v_mfma_f32_16x16x32_bf16 v[36:39], v[214:217], v[162:165], v[36:39]
	v_mfma_f32_16x16x32_bf16 v[28:31], v[206:209], v[170:173], v[28:31]
	v_mfma_f32_16x16x32_bf16 v[20:23], v[214:217], v[170:173], v[20:23]
	v_mfma_f32_16x16x32_bf16 v[12:15], v[206:209], v[178:181], v[12:15]
	v_mfma_f32_16x16x32_bf16 v[8:11], v[214:217], v[178:181], v[8:11]
	v_mfma_f32_16x16x32_bf16 v[4:7], v[206:209], v[196:199], v[4:7]
	v_mfma_f32_16x16x32_bf16 v[0:3], v[214:217], v[196:199], v[0:3]
	s_setprio 0
	v_add_u32_e32 v153, s5, v136
	s_barrier
	ds_read_b128 v[140:143], v153
	ds_read_b128 v[144:147], v153 offset:1024
	ds_read_b128 v[148:151], v153 offset:2048
	ds_read_b128 v[154:157], v153 offset:3072
	s_mov_b32 m0, s58
	ds_read_b128 v[158:161], v138 offset:32768
	ds_read_b128 v[162:165], v138 offset:33792
	ds_read_b128 v[166:169], v138 offset:34816
	ds_read_b128 v[170:173], v138 offset:35840
	ds_read_b128 v[174:177], v138 offset:36864
	ds_read_b128 v[178:181], v138 offset:37888
	ds_read_b128 v[188:191], v138 offset:38912
	ds_read_b128 v[196:199], v138 offset:39936
	global_load_lds_dwordx4 v130, s[40:41]
	s_mov_b32 m0, s59
	s_nop 0
	global_load_lds_dwordx4 v128, s[40:41]
	s_waitcnt lgkmcnt(8)
	s_barrier
	s_waitcnt lgkmcnt(0)
	s_setprio 1
	s_waitcnt lgkmcnt(0)
	v_mfma_f32_16x16x32_bf16 v[124:127], v[140:143], v[158:161], v[124:127]
	v_mfma_f32_16x16x32_bf16 v[120:123], v[148:151], v[158:161], v[120:123]
	v_mfma_f32_16x16x32_bf16 v[116:119], v[140:143], v[166:169], v[116:119]
	v_mfma_f32_16x16x32_bf16 v[112:115], v[148:151], v[166:169], v[112:115]
	v_mfma_f32_16x16x32_bf16 v[104:107], v[140:143], v[174:177], v[104:107]
	v_mfma_f32_16x16x32_bf16 v[96:99], v[148:151], v[174:177], v[96:99]
	v_mfma_f32_16x16x32_bf16 v[88:91], v[140:143], v[188:191], v[88:91]
	v_mfma_f32_16x16x32_bf16 v[80:83], v[148:151], v[188:191], v[80:83]
	v_mfma_f32_16x16x32_bf16 v[124:127], v[144:147], v[162:165], v[124:127]
	v_mfma_f32_16x16x32_bf16 v[120:123], v[154:157], v[162:165], v[120:123]
	v_mfma_f32_16x16x32_bf16 v[116:119], v[144:147], v[170:173], v[116:119]
	v_mfma_f32_16x16x32_bf16 v[112:115], v[154:157], v[170:173], v[112:115]
	v_mfma_f32_16x16x32_bf16 v[104:107], v[144:147], v[178:181], v[104:107]
	v_mfma_f32_16x16x32_bf16 v[96:99], v[154:157], v[178:181], v[96:99]
	v_mfma_f32_16x16x32_bf16 v[88:91], v[144:147], v[196:199], v[88:91]
	v_mfma_f32_16x16x32_bf16 v[80:83], v[154:157], v[196:199], v[80:83]
	s_setprio 0
	s_barrier
	s_add_i32 m0, s4, 0xffffff80
	v_add_u32_e32 v153, s1, v136
	ds_read_b128 v[200:203], v153
	ds_read_b128 v[206:209], v153 offset:1024
	ds_read_b128 v[210:213], v153 offset:2048
	ds_read_b128 v[214:217], v153 offset:3072
	global_load_lds_dwordx4 v130, s[46:47] offset:128
	s_add_i32 m0, s0, 0xffffff80
	s_nop 0
	global_load_lds_dwordx4 v128, s[46:47] offset:128
	s_barrier
	s_waitcnt lgkmcnt(0)
	s_setprio 1
	s_waitcnt lgkmcnt(0)
	v_mfma_f32_16x16x32_bf16 v[108:111], v[200:203], v[158:161], v[108:111]
	v_mfma_f32_16x16x32_bf16 v[100:103], v[210:213], v[158:161], v[100:103]
	v_mfma_f32_16x16x32_bf16 v[92:95], v[200:203], v[166:169], v[92:95]
	v_mfma_f32_16x16x32_bf16 v[84:87], v[210:213], v[166:169], v[84:87]
	v_mfma_f32_16x16x32_bf16 v[76:79], v[200:203], v[174:177], v[76:79]
	v_mfma_f32_16x16x32_bf16 v[72:75], v[210:213], v[174:177], v[72:75]
	v_mfma_f32_16x16x32_bf16 v[68:71], v[200:203], v[188:191], v[68:71]
	v_mfma_f32_16x16x32_bf16 v[64:67], v[210:213], v[188:191], v[64:67]
	v_mfma_f32_16x16x32_bf16 v[108:111], v[206:209], v[162:165], v[108:111]
	v_mfma_f32_16x16x32_bf16 v[100:103], v[214:217], v[162:165], v[100:103]
	v_mfma_f32_16x16x32_bf16 v[92:95], v[206:209], v[170:173], v[92:95]
	v_mfma_f32_16x16x32_bf16 v[84:87], v[214:217], v[170:173], v[84:87]
	v_mfma_f32_16x16x32_bf16 v[76:79], v[206:209], v[178:181], v[76:79]
	v_mfma_f32_16x16x32_bf16 v[72:75], v[214:217], v[178:181], v[72:75]
	v_mfma_f32_16x16x32_bf16 v[68:71], v[206:209], v[196:199], v[68:71]
	v_mfma_f32_16x16x32_bf16 v[64:67], v[214:217], v[196:199], v[64:67]
	s_setprio 0
	s_add_i32 m0, s66, 0xffffff80
	s_barrier
	ds_read_b128 v[158:161], v138 offset:49152
	ds_read_b128 v[162:165], v138 offset:50176
	ds_read_b128 v[166:169], v138 offset:51200
	ds_read_b128 v[170:173], v138 offset:52224
	ds_read_b128 v[174:177], v138 offset:53248
	ds_read_b128 v[178:181], v138 offset:54272
	ds_read_b128 v[188:191], v138 offset:55296
	ds_read_b128 v[196:199], v138 offset:56320
	global_load_lds_dwordx4 v130, s[44:45] offset:128
	s_add_i32 m0, s67, 0xffffff80
	s_nop 0
	global_load_lds_dwordx4 v128, s[44:45] offset:128
	s_barrier
; #define PG8_STAGE(bufoff, gbase, voff) do { _Pragma("unroll") for (int _i = 0; _i < 2; ++_i) \
;         __builtin_amdgcn_global_load_lds((const unsigned*)((const char*)(gbase) + (voff)[_i]), (LAS unsigned*)(lds + (bufoff) + ldsw + _i * 8192), 16, 0, 0); } while (0)
; #define PG8_MMA(ai, bj, At, Bt) do { __builtin_amdgcn_s_setprio(1); _Pragma("unroll") for (int m = 0; m < 4; ++m) _Pragma("unroll") for (int n = 0; n < 2; ++n) _Pragma("unroll") for (int k = 0; k < 2; ++k) \
;         acc[ai][bj][m][n] = __builtin_amdgcn_mfma_f32_16x16x32_bf16(Bt[n][k], At[m][k], acc[ai][bj][m][n], 0, 0, 0); __builtin_amdgcn_s_setprio(0); } while (0)
; #define PG8_WAIT_V(n) asm volatile("s_waitcnt vmcnt(" #n ")" ::: "memory")
; #define PG8_WAIT_L(n) asm volatile("s_waitcnt lgkmcnt(" #n ")" ::: "memory")
; #define PG8_BAR __builtin_amdgcn_s_barrier()
; #define PG8_SCHED __builtin_amdgcn_sched_barrier(0)
; template <class Epi, class Sched>
; DI void gemm_phase(LAS unsigned char* lds, const Gemm g, const Sched& S, const Epi& E) {
;     ...
;             PG8_BAR; PG8_WAIT_L(0); PG8_MMA(1, 0, At, B0); PG8_BAR; PG8_SCHED;
;             PG8_STAGE(PG8_SB(1, 1), b3 + hstep, voffB);
;             PG8_WAIT_V(6); PG8_BAR; PG8_MMA(1, 1, At, B1); PG8_BAR;
;         }
;         { int fr2 = fr, fq2 = fq; asm volatile("" : "+v"(fr2), "+v"(fq2)); E(acc, cur, wr, wc, fr2, fq2); }
;         if (!has_next) break;
;     DI void operator()(AccRef acc, const Unit& u, int wr, int wc, int fr, int fq) const {
;         float* base = P + (size_t)slot0 * 256 * DM + (size_t)u.ks * 256 * ld; const int col0 = u.pn * 256 + wc * 32 + 4 * fq;
; #pragma unroll
;         for (int ai = 0; ai < 2; ++ai)
; #pragma unroll
;             for (int m = 0; m < 4; ++m) { const size_t off = (size_t)(ai * 128 + wr * 64 + m * 16 + fr) * ld + col0;
; #pragma unroll
;                 for (int bj = 0; bj < 2; ++bj)
; #pragma unroll
;                     for (int n = 0; n < 2; ++n) *(f32x4*)(base + off + bj * 128 + n * 16) = acc[ai][bj][m][n]; }
;     }
	s_waitcnt lgkmcnt(0)
	s_setprio 1
	s_waitcnt lgkmcnt(0)
	v_mfma_f32_16x16x32_bf16 v[60:63], v[140:143], v[158:161], v[60:63]
	v_mfma_f32_16x16x32_bf16 v[56:59], v[148:151], v[158:161], v[56:59]
	v_mfma_f32_16x16x32_bf16 v[52:55], v[140:143], v[166:169], v[52:55]
	v_mfma_f32_16x16x32_bf16 v[48:51], v[148:151], v[166:169], v[48:51]
	v_mfma_f32_16x16x32_bf16 v[40:43], v[140:143], v[174:177], v[40:43]
	v_mfma_f32_16x16x32_bf16 v[32:35], v[148:151], v[174:177], v[32:35]
	v_mfma_f32_16x16x32_bf16 v[24:27], v[140:143], v[188:191], v[24:27]
	v_mfma_f32_16x16x32_bf16 v[16:19], v[148:151], v[188:191], v[16:19]
	v_mfma_f32_16x16x32_bf16 v[60:63], v[144:147], v[162:165], v[60:63]
	v_mfma_f32_16x16x32_bf16 v[56:59], v[154:157], v[162:165], v[56:59]
	v_mfma_f32_16x16x32_bf16 v[52:55], v[144:147], v[170:173], v[52:55]
	v_mfma_f32_16x16x32_bf16 v[48:51], v[154:157], v[170:173], v[48:51]
	v_mfma_f32_16x16x32_bf16 v[40:43], v[144:147], v[178:181], v[40:43]
	v_mfma_f32_16x16x32_bf16 v[32:35], v[154:157], v[178:181], v[32:35]
	v_mfma_f32_16x16x32_bf16 v[24:27], v[144:147], v[196:199], v[24:27]
	v_mfma_f32_16x16x32_bf16 v[16:19], v[154:157], v[196:199], v[16:19]
	s_setprio 0
	s_barrier
	s_mov_b32 m0, s75
	s_nop 0
	global_load_lds_dwordx4 v130, s[38:39]
	s_mov_b32 m0, s74
	s_nop 0
	global_load_lds_dwordx4 v128, s[38:39]
	s_waitcnt vmcnt(6)
	s_barrier
	s_setprio 1
	v_mfma_f32_16x16x32_bf16 v[44:47], v[200:203], v[158:161], v[44:47]
	v_mfma_f32_16x16x32_bf16 v[36:39], v[210:213], v[158:161], v[36:39]
	v_mfma_f32_16x16x32_bf16 v[28:31], v[200:203], v[166:169], v[28:31]
	v_mfma_f32_16x16x32_bf16 v[20:23], v[210:213], v[166:169], v[20:23]
	v_mfma_f32_16x16x32_bf16 v[12:15], v[200:203], v[174:177], v[12:15]
	v_mfma_f32_16x16x32_bf16 v[8:11], v[210:213], v[174:177], v[8:11]
	v_mfma_f32_16x16x32_bf16 v[4:7], v[200:203], v[188:191], v[4:7]
	v_mfma_f32_16x16x32_bf16 v[0:3], v[210:213], v[188:191], v[0:3]
	v_mfma_f32_16x16x32_bf16 v[44:47], v[206:209], v[162:165], v[44:47]
	v_mfma_f32_16x16x32_bf16 v[36:39], v[214:217], v[162:165], v[36:39]
	v_mfma_f32_16x16x32_bf16 v[28:31], v[206:209], v[170:173], v[28:31]
	v_mfma_f32_16x16x32_bf16 v[20:23], v[214:217], v[170:173], v[20:23]
	v_mfma_f32_16x16x32_bf16 v[12:15], v[206:209], v[178:181], v[12:15]
	v_mfma_f32_16x16x32_bf16 v[8:11], v[214:217], v[178:181], v[8:11]
	v_mfma_f32_16x16x32_bf16 v[4:7], v[206:209], v[196:199], v[4:7]
	v_mfma_f32_16x16x32_bf16 v[0:3], v[214:217], v[196:199], v[0:3]
	s_setprio 0
	s_movk_i32 s0, 0x100
	s_andn2_b64 vcc, exec, s[8:9]
	s_mov_b64 s[38:39], -1
	s_mov_b64 s[8:9], 0
	s_barrier
	s_cbranch_vccz .LBB0_1935
	s_ashr_i32 s15, s14, 31
	s_lshl_b64 s[0:1], s[14:15], 21
	s_add_u32 s0, s63, s0
	v_mov_b32_e32 v141, v194
	v_mov_b32_e32 v140, v192
	s_addc_u32 s1, s64, s1
	s_lshl_b32 s4, s65, 8
	s_or_b32 s4, s4, s62
	v_lshl_add_u32 v140, v140, 2, s4
	v_add_u32_e32 v142, s61, v141
	v_ashrrev_i32_e32 v141, 31, v140
	v_ashrrev_i32_e32 v143, 31, v142
	v_lshl_add_u64 v[140:141], v[140:141], 2, s[0:1]
	v_lshlrev_b64 v[144:145], 13, v[142:143]
	v_lshl_add_u64 v[144:145], v[140:141], 0, v[144:145]
	global_store_dwordx4 v[144:145], v[124:127], off
	global_store_dwordx4 v[144:145], v[120:123], off offset:64
	global_store_dwordx4 v[144:145], v[108:111], off offset:512
	global_store_dwordx4 v[144:145], v[100:103], off offset:576
	s_and_b64 vcc, exec, s[6:7]
	s_mov_b32 s14, s28
	v_add_u32_e32 v100, 16, v142
	v_ashrrev_i32_e32 v101, 31, v100
	v_lshlrev_b64 v[100:101], 13, v[100:101]
	v_lshl_add_u64 v[100:101], v[140:141], 0, v[100:101]
	global_store_dwordx4 v[100:101], v[116:119], off
	global_store_dwordx4 v[100:101], v[112:115], off offset:64
	global_store_dwordx4 v[100:101], v[92:95], off offset:512
	global_store_dwordx4 v[100:101], v[84:87], off offset:576
	s_mov_b32 s65, s73
	s_mov_b64 s[16:17], s[30:31]
	v_add_u32_e32 v84, 32, v142
	v_ashrrev_i32_e32 v85, 31, v84
	v_lshlrev_b64 v[84:85], 13, v[84:85]
	v_lshl_add_u64 v[84:85], v[140:141], 0, v[84:85]
	global_store_dwordx4 v[84:85], v[104:107], off
	global_store_dwordx4 v[84:85], v[96:99], off offset:64
	global_store_dwordx4 v[84:85], v[76:79], off offset:512
	global_store_dwordx4 v[84:85], v[72:75], off offset:576
	s_mov_b64 s[18:19], s[36:37]
	s_nop 0
	v_add_u32_e32 v72, 48, v142
	v_ashrrev_i32_e32 v73, 31, v72
	v_lshlrev_b64 v[72:73], 13, v[72:73]
	v_lshl_add_u64 v[72:73], v[140:141], 0, v[72:73]
	global_store_dwordx4 v[72:73], v[88:91], off
	global_store_dwordx4 v[72:73], v[80:83], off offset:64
	global_store_dwordx4 v[72:73], v[68:71], off offset:512
	global_store_dwordx4 v[72:73], v[64:67], off offset:576
	s_nop 1
	v_add_u32_e32 v64, 0x80, v142
	v_ashrrev_i32_e32 v65, 31, v64
	v_lshlrev_b64 v[64:65], 13, v[64:65]
	v_lshl_add_u64 v[64:65], v[140:141], 0, v[64:65]
	global_store_dwordx4 v[64:65], v[60:63], off
	global_store_dwordx4 v[64:65], v[56:59], off offset:64
	global_store_dwordx4 v[64:65], v[44:47], off offset:512
	global_store_dwordx4 v[64:65], v[36:39], off offset:576
	s_nop 1
	v_add_u32_e32 v36, 0x90, v142
	v_ashrrev_i32_e32 v37, 31, v36
	v_lshlrev_b64 v[36:37], 13, v[36:37]
	v_lshl_add_u64 v[36:37], v[140:141], 0, v[36:37]
	global_store_dwordx4 v[36:37], v[52:55], off
	global_store_dwordx4 v[36:37], v[48:51], off offset:64
	global_store_dwordx4 v[36:37], v[28:31], off offset:512
	global_store_dwordx4 v[36:37], v[20:23], off offset:576
	s_nop 1
	v_add_u32_e32 v20, 0xa0, v142
	v_ashrrev_i32_e32 v21, 31, v20
	v_lshlrev_b64 v[20:21], 13, v[20:21]
	v_lshl_add_u64 v[20:21], v[140:141], 0, v[20:21]
	global_store_dwordx4 v[20:21], v[40:43], off
	global_store_dwordx4 v[20:21], v[32:35], off offset:64
	global_store_dwordx4 v[20:21], v[12:15], off offset:512
	global_store_dwordx4 v[20:21], v[8:11], off offset:576
	s_nop 1
	v_add_u32_e32 v8, 0xb0, v142
	v_ashrrev_i32_e32 v9, 31, v8
	v_lshlrev_b64 v[8:9], 13, v[8:9]
	v_lshl_add_u64 v[8:9], v[140:141], 0, v[8:9]
	global_store_dwordx4 v[8:9], v[24:27], off
	global_store_dwordx4 v[8:9], v[16:19], off offset:64
	global_store_dwordx4 v[8:9], v[4:7], off offset:512
	global_store_dwordx4 v[8:9], v[0:3], off offset:576
	s_cbranch_vccz .LBB0_1930
	s_waitcnt vmcnt(0)
	s_cmpk_gt_u32 s35, 0xff
	s_cbranch_scc1 .LBB0_1939
	s_barrier
